# v25 plus peeled last K-iteration: a unit without successor moves only lane 0 in its 14 next-unit prefetch DMAs
# baseline (speedup 1.0000x reference)
; #define PG8_STAGE(bufoff, gbase, voff) do { _Pragma("unroll") for (int _i = 0; _i < 2; ++_i) \
;         __builtin_amdgcn_global_load_lds((const unsigned*)((const char*)(gbase) + (voff)[_i]), (PG8_LAS unsigned*)(lds + (bufoff) + ldsw + _i * 8192), 16, 0, 0); } while (0)
; #define PG8_LDA(dst, b, h) do { _Pragma("unroll") for (int m = 0; m < 4; ++m) _Pragma("unroll") for (int k = 0; k < 2; ++k) dst[m][k] = *(const PG8_LAS bf16x8*)(lds + PG8_SA(b, h) + aoff + m * 2048 + k * 1024); } while (0)
; #define PG8_LDB(dst, b, h) do { _Pragma("unroll") for (int n = 0; n < 2; ++n) _Pragma("unroll") for (int k = 0; k < 2; ++k) dst[n][k] = *(const PG8_LAS bf16x8*)(lds + PG8_SB(b, h) + boff + n * 2048 + k * 1024); } while (0)
; #define PG8_MMA(ai, bj, At, Bt) do { __builtin_amdgcn_s_setprio(1); _Pragma("unroll") for (int m = 0; m < 4; ++m) _Pragma("unroll") for (int n = 0; n < 2; ++n) _Pragma("unroll") for (int k = 0; k < 2; ++k) \
;         acc[ai][bj][m][n] = __builtin_amdgcn_mfma_f32_16x16x32_bf16(Bt[n][k], At[m][k], acc[ai][bj][m][n], 0, 0, 0); __builtin_amdgcn_s_setprio(0); } while (0)
; #define PG8_WAIT_V(n) asm volatile("s_waitcnt vmcnt(" #n ")" ::: "memory")
; #define PG8_WAIT_L(n) asm volatile("s_waitcnt lgkmcnt(" #n ")" ::: "memory")
; #define PG8_BAR __builtin_amdgcn_s_barrier()
; #define PG8_SCHED __builtin_amdgcn_sched_barrier(0)
; template <class Epi, class Sched, bool ALIGN_EPI = false, bool SP2 = false>
; __device__ __forceinline__ void gemm_phase(PG8_LAS unsigned char* lds, const Gemm g, const Sched& S, const Epi& E, int tid_in) {
;     ...
;         for (int t = 0; t < nt; t += 2) {
;             const bool last = (t == nt - 2);
;             const char* a1 = cA + (size_t)(t + 1) * kstep;
;             const char* a2 = last ? nA : cA + (size_t)(t + 2) * kstep; const char* b2 = last ? nB : cB + (size_t)(t + 2) * kstep;
;             const char* a3 = a2 + kstep; const char* b3 = b2 + kstep;
;             if (last && has_next) S.a_ready(nxt);
;             if constexpr (SP2) {
;             PG8_LDB(B0, 0, 0); PG8_LDB(B1, 0, 1); PG8_SCHED; PG8_LDA(At, 0, 0); PG8_STAGE(PG8_SA(1, 1), a1 + hstep, voffA);
;             PG8_WAIT_V(8); PG8_WAIT_L(0); PG8_BAR; PG8_MMA(0, 0, At, B0); PG8_MMA(0, 1, At, B1); PG8_BAR; PG8_SCHED;
;             PG8_LDA(At, 0, 1); PG8_STAGE(PG8_SB(0, 0), b2, voffB); PG8_STAGE(PG8_SB(0, 1), b2 + hstep, voffB); PG8_STAGE(PG8_SA(0, 0), a2, voffA);
.LBB0_120:
	ds_read_b128 v[148:151], v198
	ds_read_b128 v[152:155], v198 offset:1024
	ds_read_b128 v[156:159], v198 offset:2048
	ds_read_b128 v[160:163], v198 offset:3072
	ds_read_b128 v[164:167], v199
	ds_read_b128 v[168:171], v199 offset:1024
	ds_read_b128 v[172:175], v199 offset:2048
	ds_read_b128 v[176:179], v199 offset:3072
	s_add_u32 s34, s26, 0xfffc0080
	s_addc_u32 s35, s27, -1
	s_cmp_eq_u32 s57, 12
	s_cselect_b32 s41, s11, s35
	s_cselect_b32 s40, s37, s34
	s_cselect_b32 s35, s9, s43
	s_cselect_b32 s34, s39, s42
	s_cbranch_scc1 .Lpk1
	v_lshl_add_u64 v[226:227], s[26:27], 0, v[142:143]
	s_add_i32 m0, s31, 0xc000
	ds_read_b128 v[180:183], v200
	ds_read_b128 v[184:187], v200 offset:1024
	ds_read_b128 v[188:191], v200 offset:2048
	ds_read_b128 v[206:209], v200 offset:3072
	ds_read_b128 v[210:213], v200 offset:4096
	ds_read_b128 v[214:217], v200 offset:5120
	ds_read_b128 v[218:221], v200 offset:6144
	ds_read_b128 v[222:225], v200 offset:7168
	global_load_lds_dwordx4 v[226:227], off
	v_lshl_add_u64 v[226:227], s[26:27], 0, v[140:141]
	s_add_i32 m0, s31, 0xe000
	s_nop 0
	global_load_lds_dwordx4 v[226:227], off
	s_waitcnt vmcnt(8)
	s_waitcnt lgkmcnt(0)
	s_barrier
	s_setprio 1
	s_waitcnt lgkmcnt(0)
	v_mfma_f32_16x16x32_bf16 v[124:127], v[148:151], v[180:183], v[124:127]
	v_mfma_f32_16x16x32_bf16 v[120:123], v[156:159], v[180:183], v[120:123]
	v_mfma_f32_16x16x32_bf16 v[108:111], v[148:151], v[188:191], v[108:111]
	v_mfma_f32_16x16x32_bf16 v[104:107], v[156:159], v[188:191], v[104:107]
	v_mfma_f32_16x16x32_bf16 v[92:95], v[148:151], v[210:213], v[92:95]
	v_mfma_f32_16x16x32_bf16 v[88:91], v[156:159], v[210:213], v[88:91]
	v_mfma_f32_16x16x32_bf16 v[76:79], v[148:151], v[218:221], v[76:79]
	v_mfma_f32_16x16x32_bf16 v[72:75], v[156:159], v[218:221], v[72:75]
	v_mfma_f32_16x16x32_bf16 v[124:127], v[152:155], v[184:187], v[124:127]
	v_mfma_f32_16x16x32_bf16 v[120:123], v[160:163], v[184:187], v[120:123]
	v_mfma_f32_16x16x32_bf16 v[108:111], v[152:155], v[206:209], v[108:111]
	v_mfma_f32_16x16x32_bf16 v[104:107], v[160:163], v[206:209], v[104:107]
	v_mfma_f32_16x16x32_bf16 v[92:95], v[152:155], v[214:217], v[92:95]
	v_mfma_f32_16x16x32_bf16 v[88:91], v[160:163], v[214:217], v[88:91]
	v_mfma_f32_16x16x32_bf16 v[76:79], v[152:155], v[222:225], v[76:79]
	v_mfma_f32_16x16x32_bf16 v[72:75], v[160:163], v[222:225], v[72:75]
	s_setprio 0
	s_setprio 1
	v_mfma_f32_16x16x32_bf16 v[116:119], v[164:167], v[180:183], v[116:119]
	v_mfma_f32_16x16x32_bf16 v[112:115], v[172:175], v[180:183], v[112:115]
	v_mfma_f32_16x16x32_bf16 v[100:103], v[164:167], v[188:191], v[100:103]
	v_mfma_f32_16x16x32_bf16 v[96:99], v[172:175], v[188:191], v[96:99]
	v_mfma_f32_16x16x32_bf16 v[84:87], v[164:167], v[210:213], v[84:87]
	v_mfma_f32_16x16x32_bf16 v[80:83], v[172:175], v[210:213], v[80:83]
	v_mfma_f32_16x16x32_bf16 v[68:71], v[164:167], v[218:221], v[68:71]
	v_mfma_f32_16x16x32_bf16 v[64:67], v[172:175], v[218:221], v[64:67]
	v_mfma_f32_16x16x32_bf16 v[116:119], v[168:171], v[184:187], v[116:119]
	v_mfma_f32_16x16x32_bf16 v[112:115], v[176:179], v[184:187], v[112:115]
	v_mfma_f32_16x16x32_bf16 v[100:103], v[168:171], v[206:209], v[100:103]
	v_mfma_f32_16x16x32_bf16 v[96:99], v[176:179], v[206:209], v[96:99]
	v_mfma_f32_16x16x32_bf16 v[84:87], v[168:171], v[214:217], v[84:87]
	v_mfma_f32_16x16x32_bf16 v[80:83], v[176:179], v[214:217], v[80:83]
	v_mfma_f32_16x16x32_bf16 v[68:71], v[168:171], v[222:225], v[68:71]
	v_mfma_f32_16x16x32_bf16 v[64:67], v[176:179], v[222:225], v[64:67]
	s_setprio 0
	s_barrier
	s_add_i32 s58, s54, s30
	v_lshl_add_u64 v[226:227], s[34:35], 0, v[130:131]
	s_mov_b32 m0, s58
	ds_read_b128 v[180:183], v200 offset:16384
	ds_read_b128 v[184:187], v200 offset:17408
	ds_read_b128 v[188:191], v200 offset:18432
	ds_read_b128 v[206:209], v200 offset:19456
	ds_read_b128 v[210:213], v200 offset:20480
	ds_read_b128 v[214:217], v200 offset:21504
	ds_read_b128 v[218:221], v200 offset:22528
	ds_read_b128 v[222:225], v200 offset:23552
	global_load_lds_dwordx4 v[226:227], off
	s_add_i32 m0, s58, 0x2000
	s_add_u32 s58, s34, 0x40000
	v_lshl_add_u64 v[228:229], s[34:35], 0, v[134:135]
	s_addc_u32 s59, s35, 0
	s_add_i32 s60, s55, s30
	global_load_lds_dwordx4 v[228:229], off
	v_lshl_add_u64 v[230:231], s[58:59], 0, v[130:131]
	s_mov_b32 m0, s60
	v_lshl_add_u64 v[232:233], s[40:41], 0, v[132:133]
	global_load_lds_dwordx4 v[230:231], off
	v_lshl_add_u64 v[230:231], s[58:59], 0, v[134:135]
	s_add_i32 m0, s60, 0x2000
	s_nop 0
	global_load_lds_dwordx4 v[230:231], off
	v_lshl_add_u64 v[230:231], s[40:41], 0, v[128:129]
	s_mov_b32 m0, s31
	s_nop 0
	global_load_lds_dwordx4 v[230:231], off
	s_mov_b32 m0, s33
	s_nop 0
	global_load_lds_dwordx4 v[232:233], off
	s_waitcnt vmcnt(8)
	s_waitcnt lgkmcnt(0)
	s_barrier
; #define PG8_STAGE(bufoff, gbase, voff) do { _Pragma("unroll") for (int _i = 0; _i < 2; ++_i) \
;         __builtin_amdgcn_global_load_lds((const unsigned*)((const char*)(gbase) + (voff)[_i]), (PG8_LAS unsigned*)(lds + (bufoff) + ldsw + _i * 8192), 16, 0, 0); } while (0)
; #define PG8_LDA(dst, b, h) do { _Pragma("unroll") for (int m = 0; m < 4; ++m) _Pragma("unroll") for (int k = 0; k < 2; ++k) dst[m][k] = *(const PG8_LAS bf16x8*)(lds + PG8_SA(b, h) + aoff + m * 2048 + k * 1024); } while (0)
; #define PG8_LDB(dst, b, h) do { _Pragma("unroll") for (int n = 0; n < 2; ++n) _Pragma("unroll") for (int k = 0; k < 2; ++k) dst[n][k] = *(const PG8_LAS bf16x8*)(lds + PG8_SB(b, h) + boff + n * 2048 + k * 1024); } while (0)
; #define PG8_MMA(ai, bj, At, Bt) do { __builtin_amdgcn_s_setprio(1); _Pragma("unroll") for (int m = 0; m < 4; ++m) _Pragma("unroll") for (int n = 0; n < 2; ++n) _Pragma("unroll") for (int k = 0; k < 2; ++k) \
;         acc[ai][bj][m][n] = __builtin_amdgcn_mfma_f32_16x16x32_bf16(Bt[n][k], At[m][k], acc[ai][bj][m][n], 0, 0, 0); __builtin_amdgcn_s_setprio(0); } while (0)
; #define PG8_WAIT_V(n) asm volatile("s_waitcnt vmcnt(" #n ")" ::: "memory")
; #define PG8_WAIT_L(n) asm volatile("s_waitcnt lgkmcnt(" #n ")" ::: "memory")
; #define PG8_BAR __builtin_amdgcn_s_barrier()
; #define PG8_SCHED __builtin_amdgcn_sched_barrier(0)
; template <class Epi, class Sched, bool ALIGN_EPI = false, bool SP2 = false>
; __device__ __forceinline__ void gemm_phase(PG8_LAS unsigned char* lds, const Gemm g, const Sched& S, const Epi& E, int tid_in) {
;     ...
;             PG8_WAIT_V(8); PG8_WAIT_L(0); PG8_BAR; PG8_MMA(1, 0, At, B0); PG8_MMA(1, 1, At, B1); PG8_BAR; PG8_SCHED;
;             PG8_LDB(B0, 1, 0); PG8_LDB(B1, 1, 1); PG8_SCHED; PG8_LDA(At, 1, 0); PG8_STAGE(PG8_SA(0, 1), a2 + hstep, voffA);
;             PG8_WAIT_V(8); PG8_WAIT_L(0); PG8_BAR; PG8_MMA(0, 0, At, B0); PG8_MMA(0, 1, At, B1); PG8_BAR; PG8_SCHED;
	s_setprio 1
	s_waitcnt lgkmcnt(0)
	v_mfma_f32_16x16x32_bf16 v[60:63], v[148:151], v[180:183], v[60:63]
	v_mfma_f32_16x16x32_bf16 v[56:59], v[156:159], v[180:183], v[56:59]
	v_mfma_f32_16x16x32_bf16 v[44:47], v[148:151], v[188:191], v[44:47]
	v_mfma_f32_16x16x32_bf16 v[40:43], v[156:159], v[188:191], v[40:43]
	v_mfma_f32_16x16x32_bf16 v[28:31], v[148:151], v[210:213], v[28:31]
	v_mfma_f32_16x16x32_bf16 v[24:27], v[156:159], v[210:213], v[24:27]
	v_mfma_f32_16x16x32_bf16 v[12:15], v[148:151], v[218:221], v[12:15]
	v_mfma_f32_16x16x32_bf16 v[8:11], v[156:159], v[218:221], v[8:11]
	v_mfma_f32_16x16x32_bf16 v[60:63], v[152:155], v[184:187], v[60:63]
	v_mfma_f32_16x16x32_bf16 v[56:59], v[160:163], v[184:187], v[56:59]
	v_mfma_f32_16x16x32_bf16 v[44:47], v[152:155], v[206:209], v[44:47]
	v_mfma_f32_16x16x32_bf16 v[40:43], v[160:163], v[206:209], v[40:43]
	v_mfma_f32_16x16x32_bf16 v[28:31], v[152:155], v[214:217], v[28:31]
	v_mfma_f32_16x16x32_bf16 v[24:27], v[160:163], v[214:217], v[24:27]
	v_mfma_f32_16x16x32_bf16 v[12:15], v[152:155], v[222:225], v[12:15]
	v_mfma_f32_16x16x32_bf16 v[8:11], v[160:163], v[222:225], v[8:11]
	s_setprio 0
	s_setprio 1
	v_mfma_f32_16x16x32_bf16 v[52:55], v[164:167], v[180:183], v[52:55]
	v_mfma_f32_16x16x32_bf16 v[48:51], v[172:175], v[180:183], v[48:51]
	v_mfma_f32_16x16x32_bf16 v[36:39], v[164:167], v[188:191], v[36:39]
	v_mfma_f32_16x16x32_bf16 v[32:35], v[172:175], v[188:191], v[32:35]
	v_mfma_f32_16x16x32_bf16 v[20:23], v[164:167], v[210:213], v[20:23]
	v_mfma_f32_16x16x32_bf16 v[16:19], v[172:175], v[210:213], v[16:19]
	v_mfma_f32_16x16x32_bf16 v[4:7], v[164:167], v[218:221], v[4:7]
	v_mfma_f32_16x16x32_bf16 v[0:3], v[172:175], v[218:221], v[0:3]
	v_mfma_f32_16x16x32_bf16 v[52:55], v[168:171], v[184:187], v[52:55]
	v_mfma_f32_16x16x32_bf16 v[48:51], v[176:179], v[184:187], v[48:51]
	v_mfma_f32_16x16x32_bf16 v[36:39], v[168:171], v[206:209], v[36:39]
	v_mfma_f32_16x16x32_bf16 v[32:35], v[176:179], v[206:209], v[32:35]
	v_mfma_f32_16x16x32_bf16 v[20:23], v[168:171], v[214:217], v[20:23]
	v_mfma_f32_16x16x32_bf16 v[16:19], v[176:179], v[214:217], v[16:19]
	v_mfma_f32_16x16x32_bf16 v[4:7], v[168:171], v[222:225], v[4:7]
	v_mfma_f32_16x16x32_bf16 v[0:3], v[176:179], v[222:225], v[0:3]
	s_setprio 0
	s_barrier
	s_add_i32 s58, 0, 0x18000
	s_add_i32 s59, 0, 0x1c000
	v_add_u32_e32 v160, s58, v193
	v_add_u32_e32 v176, s59, v193
	ds_read_b128 v[148:151], v160
	ds_read_b128 v[152:155], v160 offset:1024
	ds_read_b128 v[156:159], v160 offset:2048
	ds_read_b128 v[160:163], v160 offset:3072
	ds_read_b128 v[164:167], v176
	ds_read_b128 v[168:171], v176 offset:1024
	ds_read_b128 v[172:175], v176 offset:2048
	ds_read_b128 v[176:179], v176 offset:3072
	s_add_u32 s40, s40, 0x40000
	s_addc_u32 s41, s41, 0
	s_mov_b32 m0, s44
	v_lshl_add_u64 v[234:235], s[40:41], 0, v[128:129]
	ds_read_b128 v[180:183], v200 offset:32768
	ds_read_b128 v[184:187], v200 offset:33792
	ds_read_b128 v[188:191], v200 offset:34816
	ds_read_b128 v[206:209], v200 offset:35840
	ds_read_b128 v[210:213], v200 offset:36864
	ds_read_b128 v[214:217], v200 offset:37888
	ds_read_b128 v[218:221], v200 offset:38912
	ds_read_b128 v[222:225], v200 offset:39936
	global_load_lds_dwordx4 v[234:235], off
	v_lshl_add_u64 v[234:235], s[40:41], 0, v[132:133]
	s_mov_b32 m0, s45
	s_nop 0
	global_load_lds_dwordx4 v[234:235], off
	s_waitcnt vmcnt(8)
	s_waitcnt lgkmcnt(0)
	s_barrier
	s_setprio 1
	s_waitcnt lgkmcnt(0)
	v_mfma_f32_16x16x32_bf16 v[124:127], v[148:151], v[180:183], v[124:127]
	v_mfma_f32_16x16x32_bf16 v[120:123], v[156:159], v[180:183], v[120:123]
	v_mfma_f32_16x16x32_bf16 v[108:111], v[148:151], v[188:191], v[108:111]
	v_mfma_f32_16x16x32_bf16 v[104:107], v[156:159], v[188:191], v[104:107]
	v_mfma_f32_16x16x32_bf16 v[92:95], v[148:151], v[210:213], v[92:95]
	v_mfma_f32_16x16x32_bf16 v[88:91], v[156:159], v[210:213], v[88:91]
	v_mfma_f32_16x16x32_bf16 v[76:79], v[148:151], v[218:221], v[76:79]
	v_mfma_f32_16x16x32_bf16 v[72:75], v[156:159], v[218:221], v[72:75]
	v_mfma_f32_16x16x32_bf16 v[124:127], v[152:155], v[184:187], v[124:127]
	v_mfma_f32_16x16x32_bf16 v[120:123], v[160:163], v[184:187], v[120:123]
	v_mfma_f32_16x16x32_bf16 v[108:111], v[152:155], v[206:209], v[108:111]
	v_mfma_f32_16x16x32_bf16 v[104:107], v[160:163], v[206:209], v[104:107]
	v_mfma_f32_16x16x32_bf16 v[92:95], v[152:155], v[214:217], v[92:95]
	v_mfma_f32_16x16x32_bf16 v[88:91], v[160:163], v[214:217], v[88:91]
	v_mfma_f32_16x16x32_bf16 v[76:79], v[152:155], v[222:225], v[76:79]
	v_mfma_f32_16x16x32_bf16 v[72:75], v[160:163], v[222:225], v[72:75]
	s_setprio 0
	s_setprio 1
	v_mfma_f32_16x16x32_bf16 v[116:119], v[164:167], v[180:183], v[116:119]
	v_mfma_f32_16x16x32_bf16 v[112:115], v[172:175], v[180:183], v[112:115]
	v_mfma_f32_16x16x32_bf16 v[100:103], v[164:167], v[188:191], v[100:103]
	v_mfma_f32_16x16x32_bf16 v[96:99], v[172:175], v[188:191], v[96:99]
	v_mfma_f32_16x16x32_bf16 v[84:87], v[164:167], v[210:213], v[84:87]
	v_mfma_f32_16x16x32_bf16 v[80:83], v[172:175], v[210:213], v[80:83]
	v_mfma_f32_16x16x32_bf16 v[68:71], v[164:167], v[218:221], v[68:71]
	v_mfma_f32_16x16x32_bf16 v[64:67], v[172:175], v[218:221], v[64:67]
	v_mfma_f32_16x16x32_bf16 v[116:119], v[168:171], v[184:187], v[116:119]
	v_mfma_f32_16x16x32_bf16 v[112:115], v[176:179], v[184:187], v[112:115]
	v_mfma_f32_16x16x32_bf16 v[100:103], v[168:171], v[206:209], v[100:103]
	v_mfma_f32_16x16x32_bf16 v[96:99], v[176:179], v[206:209], v[96:99]
	v_mfma_f32_16x16x32_bf16 v[84:87], v[168:171], v[214:217], v[84:87]
	v_mfma_f32_16x16x32_bf16 v[80:83], v[176:179], v[214:217], v[80:83]
	v_mfma_f32_16x16x32_bf16 v[68:71], v[168:171], v[222:225], v[68:71]
	v_mfma_f32_16x16x32_bf16 v[64:67], v[176:179], v[222:225], v[64:67]
	s_setprio 0
	s_barrier
; #define PG8_STAGE(bufoff, gbase, voff) do { _Pragma("unroll") for (int _i = 0; _i < 2; ++_i) \
;         __builtin_amdgcn_global_load_lds((const unsigned*)((const char*)(gbase) + (voff)[_i]), (PG8_LAS unsigned*)(lds + (bufoff) + ldsw + _i * 8192), 16, 0, 0); } while (0)
; #define PG8_LDA(dst, b, h) do { _Pragma("unroll") for (int m = 0; m < 4; ++m) _Pragma("unroll") for (int k = 0; k < 2; ++k) dst[m][k] = *(const PG8_LAS bf16x8*)(lds + PG8_SA(b, h) + aoff + m * 2048 + k * 1024); } while (0)
; #define PG8_MMA(ai, bj, At, Bt) do { __builtin_amdgcn_s_setprio(1); _Pragma("unroll") for (int m = 0; m < 4; ++m) _Pragma("unroll") for (int n = 0; n < 2; ++n) _Pragma("unroll") for (int k = 0; k < 2; ++k) \
;         acc[ai][bj][m][n] = __builtin_amdgcn_mfma_f32_16x16x32_bf16(Bt[n][k], At[m][k], acc[ai][bj][m][n], 0, 0, 0); __builtin_amdgcn_s_setprio(0); } while (0)
; #define PG8_WAIT_V(n) asm volatile("s_waitcnt vmcnt(" #n ")" ::: "memory")
; #define PG8_WAIT_L(n) asm volatile("s_waitcnt lgkmcnt(" #n ")" ::: "memory")
; #define PG8_BAR __builtin_amdgcn_s_barrier()
; #define PG8_SCHED __builtin_amdgcn_sched_barrier(0)
; template <class Epi, class Sched, bool ALIGN_EPI = false, bool SP2 = false>
; __device__ __forceinline__ void gemm_phase(PG8_LAS unsigned char* lds, const Gemm g, const Sched& S, const Epi& E, int tid_in) {
;     ...
;             PG8_LDA(At, 1, 1); PG8_STAGE(PG8_SB(1, 0), b3, voffB); PG8_STAGE(PG8_SB(1, 1), b3 + hstep, voffB); PG8_STAGE(PG8_SA(1, 0), a3, voffA);
;             PG8_WAIT_V(8); PG8_WAIT_L(0); PG8_BAR; PG8_MMA(1, 0, At, B0); PG8_MMA(1, 1, At, B1); PG8_BAR; PG8_SCHED;
	s_add_i32 s40, s58, s30
	v_lshl_add_u64 v[226:227], v[226:227], 0, s[16:17]
	s_mov_b32 m0, s40
	ds_read_b128 v[180:183], v200 offset:49152
	ds_read_b128 v[184:187], v200 offset:50176
	ds_read_b128 v[188:191], v200 offset:51200
	ds_read_b128 v[206:209], v200 offset:52224
	ds_read_b128 v[210:213], v200 offset:53248
	ds_read_b128 v[214:217], v200 offset:54272
	ds_read_b128 v[218:221], v200 offset:55296
	ds_read_b128 v[222:225], v200 offset:56320
	global_load_lds_dwordx4 v[226:227], off
	s_add_i32 m0, s40, 0x2000
	s_add_u32 s34, s34, 0x40080
	v_lshl_add_u64 v[226:227], v[228:229], 0, s[16:17]
	s_addc_u32 s35, s35, 0
	s_add_i32 s40, s59, s30
	global_load_lds_dwordx4 v[226:227], off
	v_lshl_add_u64 v[226:227], s[34:35], 0, v[130:131]
	s_mov_b32 m0, s40
	s_nop 0
	global_load_lds_dwordx4 v[226:227], off
	v_lshl_add_u64 v[226:227], s[34:35], 0, v[134:135]
	s_add_i32 m0, s40, 0x2000
	s_nop 0
	global_load_lds_dwordx4 v[226:227], off
	v_lshl_add_u64 v[226:227], v[230:231], 0, s[16:17]
	s_mov_b32 m0, s48
	s_nop 0
	global_load_lds_dwordx4 v[226:227], off
	v_lshl_add_u64 v[226:227], v[232:233], 0, s[16:17]
	s_mov_b32 m0, s49
	s_nop 0
	global_load_lds_dwordx4 v[226:227], off
	s_waitcnt vmcnt(8)
	s_waitcnt lgkmcnt(0)
	s_barrier
	s_setprio 1
	s_waitcnt lgkmcnt(0)
	v_mfma_f32_16x16x32_bf16 v[60:63], v[148:151], v[180:183], v[60:63]
	v_mfma_f32_16x16x32_bf16 v[56:59], v[156:159], v[180:183], v[56:59]
	v_mfma_f32_16x16x32_bf16 v[44:47], v[148:151], v[188:191], v[44:47]
	v_mfma_f32_16x16x32_bf16 v[40:43], v[156:159], v[188:191], v[40:43]
	v_mfma_f32_16x16x32_bf16 v[28:31], v[148:151], v[210:213], v[28:31]
	v_mfma_f32_16x16x32_bf16 v[24:27], v[156:159], v[210:213], v[24:27]
	v_mfma_f32_16x16x32_bf16 v[12:15], v[148:151], v[218:221], v[12:15]
	v_mfma_f32_16x16x32_bf16 v[8:11], v[156:159], v[218:221], v[8:11]
	v_mfma_f32_16x16x32_bf16 v[60:63], v[152:155], v[184:187], v[60:63]
	v_mfma_f32_16x16x32_bf16 v[56:59], v[160:163], v[184:187], v[56:59]
	v_mfma_f32_16x16x32_bf16 v[44:47], v[152:155], v[206:209], v[44:47]
	v_mfma_f32_16x16x32_bf16 v[40:43], v[160:163], v[206:209], v[40:43]
	v_mfma_f32_16x16x32_bf16 v[28:31], v[152:155], v[214:217], v[28:31]
	v_mfma_f32_16x16x32_bf16 v[24:27], v[160:163], v[214:217], v[24:27]
	v_mfma_f32_16x16x32_bf16 v[12:15], v[152:155], v[222:225], v[12:15]
	v_mfma_f32_16x16x32_bf16 v[8:11], v[160:163], v[222:225], v[8:11]
	s_setprio 0
	s_setprio 1
	v_mfma_f32_16x16x32_bf16 v[52:55], v[164:167], v[180:183], v[52:55]
	v_mfma_f32_16x16x32_bf16 v[48:51], v[172:175], v[180:183], v[48:51]
	v_mfma_f32_16x16x32_bf16 v[36:39], v[164:167], v[188:191], v[36:39]
	v_mfma_f32_16x16x32_bf16 v[32:35], v[172:175], v[188:191], v[32:35]
	v_mfma_f32_16x16x32_bf16 v[20:23], v[164:167], v[210:213], v[20:23]
	v_mfma_f32_16x16x32_bf16 v[16:19], v[172:175], v[210:213], v[16:19]
	v_mfma_f32_16x16x32_bf16 v[4:7], v[164:167], v[218:221], v[4:7]
	v_mfma_f32_16x16x32_bf16 v[0:3], v[172:175], v[218:221], v[0:3]
	v_mfma_f32_16x16x32_bf16 v[52:55], v[168:171], v[184:187], v[52:55]
	v_mfma_f32_16x16x32_bf16 v[48:51], v[176:179], v[184:187], v[48:51]
	v_mfma_f32_16x16x32_bf16 v[36:39], v[168:171], v[206:209], v[36:39]
	v_mfma_f32_16x16x32_bf16 v[32:35], v[176:179], v[206:209], v[32:35]
	v_mfma_f32_16x16x32_bf16 v[20:23], v[168:171], v[214:217], v[20:23]
	v_mfma_f32_16x16x32_bf16 v[16:19], v[176:179], v[214:217], v[16:19]
	v_mfma_f32_16x16x32_bf16 v[4:7], v[168:171], v[222:225], v[4:7]
	v_mfma_f32_16x16x32_bf16 v[0:3], v[176:179], v[222:225], v[0:3]
	s_setprio 0
	s_barrier
	s_add_i32 s57, s57, 2
	s_add_u32 s42, s42, 0x100
	s_addc_u32 s43, s43, 0
	s_add_u32 s26, s26, 0x100
	s_addc_u32 s27, s27, 0
	s_cmp_gt_u32 s57, 13
	s_cbranch_scc0 .LBB0_120
.Lpost1:
	s_and_b64 vcc, exec, s[18:19]
	s_cbranch_vccz .LBB0_123
	s_barrier

; #define PG8_STAGE(bufoff, gbase, voff) do { _Pragma("unroll") for (int _i = 0; _i < 2; ++_i) \
;         __builtin_amdgcn_global_load_lds((const unsigned*)((const char*)(gbase) + (voff)[_i]), (PG8_LAS unsigned*)(lds + (bufoff) + ldsw + _i * 8192), 16, 0, 0); } while (0)
; #define PG8_LDA(dst, b, h) do { _Pragma("unroll") for (int m = 0; m < 4; ++m) _Pragma("unroll") for (int k = 0; k < 2; ++k) dst[m][k] = *(const PG8_LAS bf16x8*)(lds + PG8_SA(b, h) + aoff + m * 2048 + k * 1024); } while (0)
; #define PG8_LDB(dst, b, h) do { _Pragma("unroll") for (int n = 0; n < 2; ++n) _Pragma("unroll") for (int k = 0; k < 2; ++k) dst[n][k] = *(const PG8_LAS bf16x8*)(lds + PG8_SB(b, h) + boff + n * 2048 + k * 1024); } while (0)
; #define PG8_MMA(ai, bj, At, Bt) do { __builtin_amdgcn_s_setprio(1); _Pragma("unroll") for (int m = 0; m < 4; ++m) _Pragma("unroll") for (int n = 0; n < 2; ++n) _Pragma("unroll") for (int k = 0; k < 2; ++k) \
;         acc[ai][bj][m][n] = __builtin_amdgcn_mfma_f32_16x16x32_bf16(Bt[n][k], At[m][k], acc[ai][bj][m][n], 0, 0, 0); __builtin_amdgcn_s_setprio(0); } while (0)
; #define PG8_WAIT_V(n) asm volatile("s_waitcnt vmcnt(" #n ")" ::: "memory")
; #define PG8_WAIT_L(n) asm volatile("s_waitcnt lgkmcnt(" #n ")" ::: "memory")
; #define PG8_BAR __builtin_amdgcn_s_barrier()
; #define PG8_SCHED __builtin_amdgcn_sched_barrier(0)
; template <class Epi, class Sched, bool ALIGN_EPI = false, bool SP2 = false>
; __device__ __forceinline__ void gemm_phase(PG8_LAS unsigned char* lds, const Gemm g, const Sched& S, const Epi& E, int tid_in) {
;     ...
;             if (last && has_next) S.a_ready(nxt);
;             if constexpr (SP2) {
;             PG8_LDB(B0, 0, 0); PG8_LDB(B1, 0, 1); PG8_SCHED; PG8_LDA(At, 0, 0); PG8_STAGE(PG8_SA(1, 1), a1 + hstep, voffA);
;             PG8_WAIT_V(8); PG8_WAIT_L(0); PG8_BAR; PG8_MMA(0, 0, At, B0); PG8_MMA(0, 1, At, B1); PG8_BAR; PG8_SCHED;
;             PG8_LDA(At, 0, 1); PG8_STAGE(PG8_SB(0, 0), b2, voffB); PG8_STAGE(PG8_SB(0, 1), b2 + hstep, voffB); PG8_STAGE(PG8_SA(0, 0), a2, voffA);
.Lpk1:
	s_or_b64 s[98:99], s[4:5], 1
	v_lshl_add_u64 v[226:227], s[26:27], 0, v[142:143]
	s_add_i32 m0, s31, 0xc000
	ds_read_b128 v[180:183], v200
	ds_read_b128 v[184:187], v200 offset:1024
	ds_read_b128 v[188:191], v200 offset:2048
	ds_read_b128 v[206:209], v200 offset:3072
	ds_read_b128 v[210:213], v200 offset:4096
	ds_read_b128 v[214:217], v200 offset:5120
	ds_read_b128 v[218:221], v200 offset:6144
	ds_read_b128 v[222:225], v200 offset:7168
	global_load_lds_dwordx4 v[226:227], off
	v_lshl_add_u64 v[226:227], s[26:27], 0, v[140:141]
	s_add_i32 m0, s31, 0xe000
	s_nop 0
	global_load_lds_dwordx4 v[226:227], off
	s_waitcnt vmcnt(8)
	s_waitcnt lgkmcnt(0)
	s_barrier
	s_setprio 1
	s_waitcnt lgkmcnt(0)
	v_mfma_f32_16x16x32_bf16 v[124:127], v[148:151], v[180:183], v[124:127]
	v_mfma_f32_16x16x32_bf16 v[120:123], v[156:159], v[180:183], v[120:123]
	v_mfma_f32_16x16x32_bf16 v[108:111], v[148:151], v[188:191], v[108:111]
	v_mfma_f32_16x16x32_bf16 v[104:107], v[156:159], v[188:191], v[104:107]
	v_mfma_f32_16x16x32_bf16 v[92:95], v[148:151], v[210:213], v[92:95]
	v_mfma_f32_16x16x32_bf16 v[88:91], v[156:159], v[210:213], v[88:91]
	v_mfma_f32_16x16x32_bf16 v[76:79], v[148:151], v[218:221], v[76:79]
	v_mfma_f32_16x16x32_bf16 v[72:75], v[156:159], v[218:221], v[72:75]
	v_mfma_f32_16x16x32_bf16 v[124:127], v[152:155], v[184:187], v[124:127]
	v_mfma_f32_16x16x32_bf16 v[120:123], v[160:163], v[184:187], v[120:123]
	v_mfma_f32_16x16x32_bf16 v[108:111], v[152:155], v[206:209], v[108:111]
	v_mfma_f32_16x16x32_bf16 v[104:107], v[160:163], v[206:209], v[104:107]
	v_mfma_f32_16x16x32_bf16 v[92:95], v[152:155], v[214:217], v[92:95]
	v_mfma_f32_16x16x32_bf16 v[88:91], v[160:163], v[214:217], v[88:91]
	v_mfma_f32_16x16x32_bf16 v[76:79], v[152:155], v[222:225], v[76:79]
	v_mfma_f32_16x16x32_bf16 v[72:75], v[160:163], v[222:225], v[72:75]
	s_setprio 0
	s_setprio 1
	v_mfma_f32_16x16x32_bf16 v[116:119], v[164:167], v[180:183], v[116:119]
	v_mfma_f32_16x16x32_bf16 v[112:115], v[172:175], v[180:183], v[112:115]
	v_mfma_f32_16x16x32_bf16 v[100:103], v[164:167], v[188:191], v[100:103]
	v_mfma_f32_16x16x32_bf16 v[96:99], v[172:175], v[188:191], v[96:99]
	v_mfma_f32_16x16x32_bf16 v[84:87], v[164:167], v[210:213], v[84:87]
	v_mfma_f32_16x16x32_bf16 v[80:83], v[172:175], v[210:213], v[80:83]
	v_mfma_f32_16x16x32_bf16 v[68:71], v[164:167], v[218:221], v[68:71]
	v_mfma_f32_16x16x32_bf16 v[64:67], v[172:175], v[218:221], v[64:67]
	v_mfma_f32_16x16x32_bf16 v[116:119], v[168:171], v[184:187], v[116:119]
	v_mfma_f32_16x16x32_bf16 v[112:115], v[176:179], v[184:187], v[112:115]
	v_mfma_f32_16x16x32_bf16 v[100:103], v[168:171], v[206:209], v[100:103]
	v_mfma_f32_16x16x32_bf16 v[96:99], v[176:179], v[206:209], v[96:99]
	v_mfma_f32_16x16x32_bf16 v[84:87], v[168:171], v[214:217], v[84:87]
	v_mfma_f32_16x16x32_bf16 v[80:83], v[176:179], v[214:217], v[80:83]
	v_mfma_f32_16x16x32_bf16 v[68:71], v[168:171], v[222:225], v[68:71]
	v_mfma_f32_16x16x32_bf16 v[64:67], v[176:179], v[222:225], v[64:67]
	s_setprio 0
	s_barrier
	s_add_i32 s58, s54, s30
	v_lshl_add_u64 v[226:227], s[34:35], 0, v[130:131]
	s_mov_b32 m0, s58
	ds_read_b128 v[180:183], v200 offset:16384
	ds_read_b128 v[184:187], v200 offset:17408
	ds_read_b128 v[188:191], v200 offset:18432
	ds_read_b128 v[206:209], v200 offset:19456
	ds_read_b128 v[210:213], v200 offset:20480
	ds_read_b128 v[214:217], v200 offset:21504
	ds_read_b128 v[218:221], v200 offset:22528
	ds_read_b128 v[222:225], v200 offset:23552
	s_mov_b64 exec, s[98:99]
	global_load_lds_dwordx4 v[226:227], off
	s_mov_b64 exec, -1
	s_add_i32 m0, s58, 0x2000
	s_add_u32 s58, s34, 0x40000
	v_lshl_add_u64 v[228:229], s[34:35], 0, v[134:135]
	s_addc_u32 s59, s35, 0
	s_add_i32 s60, s55, s30
	s_mov_b64 exec, s[98:99]
	global_load_lds_dwordx4 v[228:229], off
	s_mov_b64 exec, -1
	v_lshl_add_u64 v[230:231], s[58:59], 0, v[130:131]
	s_mov_b32 m0, s60
	v_lshl_add_u64 v[232:233], s[40:41], 0, v[132:133]
	s_mov_b64 exec, s[98:99]
	global_load_lds_dwordx4 v[230:231], off
	s_mov_b64 exec, -1
	v_lshl_add_u64 v[230:231], s[58:59], 0, v[134:135]
	s_add_i32 m0, s60, 0x2000
	s_nop 0
	s_mov_b64 exec, s[98:99]
	global_load_lds_dwordx4 v[230:231], off
	s_mov_b64 exec, -1
	v_lshl_add_u64 v[230:231], s[40:41], 0, v[128:129]
	s_mov_b32 m0, s31
	s_nop 0
	s_mov_b64 exec, s[98:99]
	global_load_lds_dwordx4 v[230:231], off
	s_mov_b64 exec, -1
	s_mov_b32 m0, s33
	s_nop 0
	s_mov_b64 exec, s[98:99]
	global_load_lds_dwordx4 v[232:233], off
	s_mov_b64 exec, -1
	s_waitcnt vmcnt(8)
	s_waitcnt lgkmcnt(0)
	s_barrier
; #define PG8_STAGE(bufoff, gbase, voff) do { _Pragma("unroll") for (int _i = 0; _i < 2; ++_i) \
;         __builtin_amdgcn_global_load_lds((const unsigned*)((const char*)(gbase) + (voff)[_i]), (PG8_LAS unsigned*)(lds + (bufoff) + ldsw + _i * 8192), 16, 0, 0); } while (0)
; #define PG8_LDA(dst, b, h) do { _Pragma("unroll") for (int m = 0; m < 4; ++m) _Pragma("unroll") for (int k = 0; k < 2; ++k) dst[m][k] = *(const PG8_LAS bf16x8*)(lds + PG8_SA(b, h) + aoff + m * 2048 + k * 1024); } while (0)
; #define PG8_LDB(dst, b, h) do { _Pragma("unroll") for (int n = 0; n < 2; ++n) _Pragma("unroll") for (int k = 0; k < 2; ++k) dst[n][k] = *(const PG8_LAS bf16x8*)(lds + PG8_SB(b, h) + boff + n * 2048 + k * 1024); } while (0)
; #define PG8_MMA(ai, bj, At, Bt) do { __builtin_amdgcn_s_setprio(1); _Pragma("unroll") for (int m = 0; m < 4; ++m) _Pragma("unroll") for (int n = 0; n < 2; ++n) _Pragma("unroll") for (int k = 0; k < 2; ++k) \
;         acc[ai][bj][m][n] = __builtin_amdgcn_mfma_f32_16x16x32_bf16(Bt[n][k], At[m][k], acc[ai][bj][m][n], 0, 0, 0); __builtin_amdgcn_s_setprio(0); } while (0)
; #define PG8_WAIT_V(n) asm volatile("s_waitcnt vmcnt(" #n ")" ::: "memory")
; #define PG8_WAIT_L(n) asm volatile("s_waitcnt lgkmcnt(" #n ")" ::: "memory")
; #define PG8_BAR __builtin_amdgcn_s_barrier()
; #define PG8_SCHED __builtin_amdgcn_sched_barrier(0)
; template <class Epi, class Sched, bool ALIGN_EPI = false, bool SP2 = false>
; __device__ __forceinline__ void gemm_phase(PG8_LAS unsigned char* lds, const Gemm g, const Sched& S, const Epi& E, int tid_in) {
;     ...
;             PG8_WAIT_V(8); PG8_WAIT_L(0); PG8_BAR; PG8_MMA(1, 0, At, B0); PG8_MMA(1, 1, At, B1); PG8_BAR; PG8_SCHED;
;             PG8_LDB(B0, 1, 0); PG8_LDB(B1, 1, 1); PG8_SCHED; PG8_LDA(At, 1, 0); PG8_STAGE(PG8_SA(0, 1), a2 + hstep, voffA);
;             PG8_WAIT_V(8); PG8_WAIT_L(0); PG8_BAR; PG8_MMA(0, 0, At, B0); PG8_MMA(0, 1, At, B1); PG8_BAR; PG8_SCHED;
	s_setprio 1
	s_waitcnt lgkmcnt(0)
	v_mfma_f32_16x16x32_bf16 v[60:63], v[148:151], v[180:183], v[60:63]
	v_mfma_f32_16x16x32_bf16 v[56:59], v[156:159], v[180:183], v[56:59]
	v_mfma_f32_16x16x32_bf16 v[44:47], v[148:151], v[188:191], v[44:47]
	v_mfma_f32_16x16x32_bf16 v[40:43], v[156:159], v[188:191], v[40:43]
	v_mfma_f32_16x16x32_bf16 v[28:31], v[148:151], v[210:213], v[28:31]
	v_mfma_f32_16x16x32_bf16 v[24:27], v[156:159], v[210:213], v[24:27]
	v_mfma_f32_16x16x32_bf16 v[12:15], v[148:151], v[218:221], v[12:15]
	v_mfma_f32_16x16x32_bf16 v[8:11], v[156:159], v[218:221], v[8:11]
	v_mfma_f32_16x16x32_bf16 v[60:63], v[152:155], v[184:187], v[60:63]
	v_mfma_f32_16x16x32_bf16 v[56:59], v[160:163], v[184:187], v[56:59]
	v_mfma_f32_16x16x32_bf16 v[44:47], v[152:155], v[206:209], v[44:47]
	v_mfma_f32_16x16x32_bf16 v[40:43], v[160:163], v[206:209], v[40:43]
	v_mfma_f32_16x16x32_bf16 v[28:31], v[152:155], v[214:217], v[28:31]
	v_mfma_f32_16x16x32_bf16 v[24:27], v[160:163], v[214:217], v[24:27]
	v_mfma_f32_16x16x32_bf16 v[12:15], v[152:155], v[222:225], v[12:15]
	v_mfma_f32_16x16x32_bf16 v[8:11], v[160:163], v[222:225], v[8:11]
	s_setprio 0
	s_setprio 1
	v_mfma_f32_16x16x32_bf16 v[52:55], v[164:167], v[180:183], v[52:55]
	v_mfma_f32_16x16x32_bf16 v[48:51], v[172:175], v[180:183], v[48:51]
	v_mfma_f32_16x16x32_bf16 v[36:39], v[164:167], v[188:191], v[36:39]
	v_mfma_f32_16x16x32_bf16 v[32:35], v[172:175], v[188:191], v[32:35]
	v_mfma_f32_16x16x32_bf16 v[20:23], v[164:167], v[210:213], v[20:23]
	v_mfma_f32_16x16x32_bf16 v[16:19], v[172:175], v[210:213], v[16:19]
	v_mfma_f32_16x16x32_bf16 v[4:7], v[164:167], v[218:221], v[4:7]
	v_mfma_f32_16x16x32_bf16 v[0:3], v[172:175], v[218:221], v[0:3]
	v_mfma_f32_16x16x32_bf16 v[52:55], v[168:171], v[184:187], v[52:55]
	v_mfma_f32_16x16x32_bf16 v[48:51], v[176:179], v[184:187], v[48:51]
	v_mfma_f32_16x16x32_bf16 v[36:39], v[168:171], v[206:209], v[36:39]
	v_mfma_f32_16x16x32_bf16 v[32:35], v[176:179], v[206:209], v[32:35]
	v_mfma_f32_16x16x32_bf16 v[20:23], v[168:171], v[214:217], v[20:23]
	v_mfma_f32_16x16x32_bf16 v[16:19], v[176:179], v[214:217], v[16:19]
	v_mfma_f32_16x16x32_bf16 v[4:7], v[168:171], v[222:225], v[4:7]
	v_mfma_f32_16x16x32_bf16 v[0:3], v[176:179], v[222:225], v[0:3]
	s_setprio 0
	s_barrier
	s_add_i32 s58, 0, 0x18000
	s_add_i32 s59, 0, 0x1c000
	v_add_u32_e32 v160, s58, v193
	v_add_u32_e32 v176, s59, v193
	ds_read_b128 v[148:151], v160
	ds_read_b128 v[152:155], v160 offset:1024
	ds_read_b128 v[156:159], v160 offset:2048
	ds_read_b128 v[160:163], v160 offset:3072
	ds_read_b128 v[164:167], v176
	ds_read_b128 v[168:171], v176 offset:1024
	ds_read_b128 v[172:175], v176 offset:2048
	ds_read_b128 v[176:179], v176 offset:3072
	s_add_u32 s40, s40, 0x40000
	s_addc_u32 s41, s41, 0
	s_mov_b32 m0, s44
	v_lshl_add_u64 v[234:235], s[40:41], 0, v[128:129]
	ds_read_b128 v[180:183], v200 offset:32768
	ds_read_b128 v[184:187], v200 offset:33792
	ds_read_b128 v[188:191], v200 offset:34816
	ds_read_b128 v[206:209], v200 offset:35840
	ds_read_b128 v[210:213], v200 offset:36864
	ds_read_b128 v[214:217], v200 offset:37888
	ds_read_b128 v[218:221], v200 offset:38912
	ds_read_b128 v[222:225], v200 offset:39936
	s_mov_b64 exec, s[98:99]
	global_load_lds_dwordx4 v[234:235], off
	s_mov_b64 exec, -1
	v_lshl_add_u64 v[234:235], s[40:41], 0, v[132:133]
	s_mov_b32 m0, s45
	s_nop 0
	s_mov_b64 exec, s[98:99]
	global_load_lds_dwordx4 v[234:235], off
	s_mov_b64 exec, -1
	s_waitcnt vmcnt(8)
	s_waitcnt lgkmcnt(0)
	s_barrier
	s_setprio 1
	s_waitcnt lgkmcnt(0)
	v_mfma_f32_16x16x32_bf16 v[124:127], v[148:151], v[180:183], v[124:127]
	v_mfma_f32_16x16x32_bf16 v[120:123], v[156:159], v[180:183], v[120:123]
	v_mfma_f32_16x16x32_bf16 v[108:111], v[148:151], v[188:191], v[108:111]
	v_mfma_f32_16x16x32_bf16 v[104:107], v[156:159], v[188:191], v[104:107]
	v_mfma_f32_16x16x32_bf16 v[92:95], v[148:151], v[210:213], v[92:95]
	v_mfma_f32_16x16x32_bf16 v[88:91], v[156:159], v[210:213], v[88:91]
	v_mfma_f32_16x16x32_bf16 v[76:79], v[148:151], v[218:221], v[76:79]
	v_mfma_f32_16x16x32_bf16 v[72:75], v[156:159], v[218:221], v[72:75]
	v_mfma_f32_16x16x32_bf16 v[124:127], v[152:155], v[184:187], v[124:127]
	v_mfma_f32_16x16x32_bf16 v[120:123], v[160:163], v[184:187], v[120:123]
	v_mfma_f32_16x16x32_bf16 v[108:111], v[152:155], v[206:209], v[108:111]
	v_mfma_f32_16x16x32_bf16 v[104:107], v[160:163], v[206:209], v[104:107]
	v_mfma_f32_16x16x32_bf16 v[92:95], v[152:155], v[214:217], v[92:95]
	v_mfma_f32_16x16x32_bf16 v[88:91], v[160:163], v[214:217], v[88:91]
	v_mfma_f32_16x16x32_bf16 v[76:79], v[152:155], v[222:225], v[76:79]
	v_mfma_f32_16x16x32_bf16 v[72:75], v[160:163], v[222:225], v[72:75]
	s_setprio 0
	s_setprio 1
	v_mfma_f32_16x16x32_bf16 v[116:119], v[164:167], v[180:183], v[116:119]
	v_mfma_f32_16x16x32_bf16 v[112:115], v[172:175], v[180:183], v[112:115]
	v_mfma_f32_16x16x32_bf16 v[100:103], v[164:167], v[188:191], v[100:103]
	v_mfma_f32_16x16x32_bf16 v[96:99], v[172:175], v[188:191], v[96:99]
	v_mfma_f32_16x16x32_bf16 v[84:87], v[164:167], v[210:213], v[84:87]
	v_mfma_f32_16x16x32_bf16 v[80:83], v[172:175], v[210:213], v[80:83]
	v_mfma_f32_16x16x32_bf16 v[68:71], v[164:167], v[218:221], v[68:71]
	v_mfma_f32_16x16x32_bf16 v[64:67], v[172:175], v[218:221], v[64:67]
	v_mfma_f32_16x16x32_bf16 v[116:119], v[168:171], v[184:187], v[116:119]
	v_mfma_f32_16x16x32_bf16 v[112:115], v[176:179], v[184:187], v[112:115]
	v_mfma_f32_16x16x32_bf16 v[100:103], v[168:171], v[206:209], v[100:103]
	v_mfma_f32_16x16x32_bf16 v[96:99], v[176:179], v[206:209], v[96:99]
	v_mfma_f32_16x16x32_bf16 v[84:87], v[168:171], v[214:217], v[84:87]
	v_mfma_f32_16x16x32_bf16 v[80:83], v[176:179], v[214:217], v[80:83]
	v_mfma_f32_16x16x32_bf16 v[68:71], v[168:171], v[222:225], v[68:71]
	v_mfma_f32_16x16x32_bf16 v[64:67], v[176:179], v[222:225], v[64:67]
	s_setprio 0
	s_barrier
; #define PG8_STAGE(bufoff, gbase, voff) do { _Pragma("unroll") for (int _i = 0; _i < 2; ++_i) \
;         __builtin_amdgcn_global_load_lds((const unsigned*)((const char*)(gbase) + (voff)[_i]), (PG8_LAS unsigned*)(lds + (bufoff) + ldsw + _i * 8192), 16, 0, 0); } while (0)
; #define PG8_LDA(dst, b, h) do { _Pragma("unroll") for (int m = 0; m < 4; ++m) _Pragma("unroll") for (int k = 0; k < 2; ++k) dst[m][k] = *(const PG8_LAS bf16x8*)(lds + PG8_SA(b, h) + aoff + m * 2048 + k * 1024); } while (0)
; #define PG8_MMA(ai, bj, At, Bt) do { __builtin_amdgcn_s_setprio(1); _Pragma("unroll") for (int m = 0; m < 4; ++m) _Pragma("unroll") for (int n = 0; n < 2; ++n) _Pragma("unroll") for (int k = 0; k < 2; ++k) \
;         acc[ai][bj][m][n] = __builtin_amdgcn_mfma_f32_16x16x32_bf16(Bt[n][k], At[m][k], acc[ai][bj][m][n], 0, 0, 0); __builtin_amdgcn_s_setprio(0); } while (0)
; #define PG8_WAIT_V(n) asm volatile("s_waitcnt vmcnt(" #n ")" ::: "memory")
; #define PG8_WAIT_L(n) asm volatile("s_waitcnt lgkmcnt(" #n ")" ::: "memory")
; #define PG8_BAR __builtin_amdgcn_s_barrier()
; #define PG8_SCHED __builtin_amdgcn_sched_barrier(0)
; template <class Epi, class Sched, bool ALIGN_EPI = false, bool SP2 = false>
; __device__ __forceinline__ void gemm_phase(PG8_LAS unsigned char* lds, const Gemm g, const Sched& S, const Epi& E, int tid_in) {
;     ...
;             PG8_LDA(At, 1, 1); PG8_STAGE(PG8_SB(1, 0), b3, voffB); PG8_STAGE(PG8_SB(1, 1), b3 + hstep, voffB); PG8_STAGE(PG8_SA(1, 0), a3, voffA);
;             PG8_WAIT_V(8); PG8_WAIT_L(0); PG8_BAR; PG8_MMA(1, 0, At, B0); PG8_MMA(1, 1, At, B1); PG8_BAR; PG8_SCHED;
	s_add_i32 s40, s58, s30
	v_lshl_add_u64 v[226:227], v[226:227], 0, s[16:17]
	s_mov_b32 m0, s40
	ds_read_b128 v[180:183], v200 offset:49152
	ds_read_b128 v[184:187], v200 offset:50176
	ds_read_b128 v[188:191], v200 offset:51200
	ds_read_b128 v[206:209], v200 offset:52224
	ds_read_b128 v[210:213], v200 offset:53248
	ds_read_b128 v[214:217], v200 offset:54272
	ds_read_b128 v[218:221], v200 offset:55296
	ds_read_b128 v[222:225], v200 offset:56320
	s_mov_b64 exec, s[98:99]
	global_load_lds_dwordx4 v[226:227], off
	s_mov_b64 exec, -1
	s_add_i32 m0, s40, 0x2000
	s_add_u32 s34, s34, 0x40080
	v_lshl_add_u64 v[226:227], v[228:229], 0, s[16:17]
	s_addc_u32 s35, s35, 0
	s_add_i32 s40, s59, s30
	s_mov_b64 exec, s[98:99]
	global_load_lds_dwordx4 v[226:227], off
	s_mov_b64 exec, -1
	v_lshl_add_u64 v[226:227], s[34:35], 0, v[130:131]
	s_mov_b32 m0, s40
	s_nop 0
	s_mov_b64 exec, s[98:99]
	global_load_lds_dwordx4 v[226:227], off
	s_mov_b64 exec, -1
	v_lshl_add_u64 v[226:227], s[34:35], 0, v[134:135]
	s_add_i32 m0, s40, 0x2000
	s_nop 0
	s_mov_b64 exec, s[98:99]
	global_load_lds_dwordx4 v[226:227], off
	s_mov_b64 exec, -1
	v_lshl_add_u64 v[226:227], v[230:231], 0, s[16:17]
	s_mov_b32 m0, s48
	s_nop 0
	s_mov_b64 exec, s[98:99]
	global_load_lds_dwordx4 v[226:227], off
	s_mov_b64 exec, -1
	v_lshl_add_u64 v[226:227], v[232:233], 0, s[16:17]
	s_mov_b32 m0, s49
	s_nop 0
	s_mov_b64 exec, s[98:99]
	global_load_lds_dwordx4 v[226:227], off
	s_mov_b64 exec, -1
	s_waitcnt vmcnt(8)
	s_waitcnt lgkmcnt(0)
	s_barrier
	s_setprio 1
	s_waitcnt lgkmcnt(0)
	v_mfma_f32_16x16x32_bf16 v[60:63], v[148:151], v[180:183], v[60:63]
	v_mfma_f32_16x16x32_bf16 v[56:59], v[156:159], v[180:183], v[56:59]
	v_mfma_f32_16x16x32_bf16 v[44:47], v[148:151], v[188:191], v[44:47]
	v_mfma_f32_16x16x32_bf16 v[40:43], v[156:159], v[188:191], v[40:43]
	v_mfma_f32_16x16x32_bf16 v[28:31], v[148:151], v[210:213], v[28:31]
	v_mfma_f32_16x16x32_bf16 v[24:27], v[156:159], v[210:213], v[24:27]
	v_mfma_f32_16x16x32_bf16 v[12:15], v[148:151], v[218:221], v[12:15]
	v_mfma_f32_16x16x32_bf16 v[8:11], v[156:159], v[218:221], v[8:11]
	v_mfma_f32_16x16x32_bf16 v[60:63], v[152:155], v[184:187], v[60:63]
	v_mfma_f32_16x16x32_bf16 v[56:59], v[160:163], v[184:187], v[56:59]
	v_mfma_f32_16x16x32_bf16 v[44:47], v[152:155], v[206:209], v[44:47]
	v_mfma_f32_16x16x32_bf16 v[40:43], v[160:163], v[206:209], v[40:43]
	v_mfma_f32_16x16x32_bf16 v[28:31], v[152:155], v[214:217], v[28:31]
	v_mfma_f32_16x16x32_bf16 v[24:27], v[160:163], v[214:217], v[24:27]
	v_mfma_f32_16x16x32_bf16 v[12:15], v[152:155], v[222:225], v[12:15]
	v_mfma_f32_16x16x32_bf16 v[8:11], v[160:163], v[222:225], v[8:11]
	s_setprio 0
	s_setprio 1
	v_mfma_f32_16x16x32_bf16 v[52:55], v[164:167], v[180:183], v[52:55]
	v_mfma_f32_16x16x32_bf16 v[48:51], v[172:175], v[180:183], v[48:51]
	v_mfma_f32_16x16x32_bf16 v[36:39], v[164:167], v[188:191], v[36:39]
	v_mfma_f32_16x16x32_bf16 v[32:35], v[172:175], v[188:191], v[32:35]
	v_mfma_f32_16x16x32_bf16 v[20:23], v[164:167], v[210:213], v[20:23]
	v_mfma_f32_16x16x32_bf16 v[16:19], v[172:175], v[210:213], v[16:19]
	v_mfma_f32_16x16x32_bf16 v[4:7], v[164:167], v[218:221], v[4:7]
	v_mfma_f32_16x16x32_bf16 v[0:3], v[172:175], v[218:221], v[0:3]
	v_mfma_f32_16x16x32_bf16 v[52:55], v[168:171], v[184:187], v[52:55]
	v_mfma_f32_16x16x32_bf16 v[48:51], v[176:179], v[184:187], v[48:51]
	v_mfma_f32_16x16x32_bf16 v[36:39], v[168:171], v[206:209], v[36:39]
	v_mfma_f32_16x16x32_bf16 v[32:35], v[176:179], v[206:209], v[32:35]
	v_mfma_f32_16x16x32_bf16 v[20:23], v[168:171], v[214:217], v[20:23]
	v_mfma_f32_16x16x32_bf16 v[16:19], v[176:179], v[214:217], v[16:19]
	v_mfma_f32_16x16x32_bf16 v[4:7], v[168:171], v[222:225], v[4:7]
	v_mfma_f32_16x16x32_bf16 v[0:3], v[176:179], v[222:225], v[0:3]
	s_setprio 0
	s_barrier
	s_add_i32 s57, s57, 2
	s_add_u32 s42, s42, 0x100
	s_addc_u32 s43, s43, 0
	s_add_u32 s26, s26, 0x100
	s_addc_u32 s27, s27, 0
	s_cmp_gt_u32 s57, 13
	s_branch .Lpost1

;     __device__ bool next(int i, Unit& u) const { if (i > 0) return false; const int t = c - first; if (t < 0 || t >= nM * nN) return false; u.pm = t % nM; u.pn = t / nM; return true; }
; #define PG8_STAGE(bufoff, gbase, voff) do { _Pragma("unroll") for (int _i = 0; _i < 2; ++_i) \
;         __builtin_amdgcn_global_load_lds((const unsigned*)((const char*)(gbase) + (voff)[_i]), (PG8_LAS unsigned*)(lds + (bufoff) + ldsw + _i * 8192), 16, 0, 0); } while (0)
; #define PG8_LDA(dst, b, h) do { _Pragma("unroll") for (int m = 0; m < 4; ++m) _Pragma("unroll") for (int k = 0; k < 2; ++k) dst[m][k] = *(const PG8_LAS bf16x8*)(lds + PG8_SA(b, h) + aoff + m * 2048 + k * 1024); } while (0)
; #define PG8_LDB(dst, b, h) do { _Pragma("unroll") for (int n = 0; n < 2; ++n) _Pragma("unroll") for (int k = 0; k < 2; ++k) dst[n][k] = *(const PG8_LAS bf16x8*)(lds + PG8_SB(b, h) + boff + n * 2048 + k * 1024); } while (0)
; #define PG8_WAIT_V(n) asm volatile("s_waitcnt vmcnt(" #n ")" ::: "memory")
; #define PG8_WAIT_L(n) asm volatile("s_waitcnt lgkmcnt(" #n ")" ::: "memory")
; #define PG8_BAR __builtin_amdgcn_s_barrier()
; template <class Epi, class Sched, bool ALIGN_EPI = false, bool SP2 = false>
; __device__ __forceinline__ void gemm_phase(PG8_LAS unsigned char* lds, const Gemm g, const Sched& S, const Epi& E, int tid_in) {
;     ...
;         const bool has_next = S.next(ui + 1, nxt);
;         const char* nA = has_next ? (const char*)g.A + (size_t)nxt.pm * tstep : cA; const char* nB = has_next ? (const char*)g.Bt + (size_t)nxt.pn * tstep : cB;
;         for (int t = 0; t < nt; t += 2) {
;             const bool last = (t == nt - 2);
;             const char* a1 = cA + (size_t)(t + 1) * kstep;
;             const char* a2 = last ? nA : cA + (size_t)(t + 2) * kstep; const char* b2 = last ? nB : cB + (size_t)(t + 2) * kstep;
;             const char* a3 = a2 + kstep; const char* b3 = b2 + kstep;
;             if (last && has_next) S.a_ready(nxt);
;             if constexpr (SP2) {
;             PG8_LDB(B0, 0, 0); PG8_LDB(B1, 0, 1); PG8_SCHED; PG8_LDA(At, 0, 0); PG8_STAGE(PG8_SA(1, 1), a1 + hstep, voffA);
;             PG8_WAIT_V(8); PG8_WAIT_L(0); PG8_BAR; PG8_MMA(0, 0, At, B0); PG8_MMA(0, 1, At, B1); PG8_BAR; PG8_SCHED;
;             PG8_LDA(At, 0, 1); PG8_STAGE(PG8_SB(0, 0), b2, voffB); PG8_STAGE(PG8_SB(0, 1), b2 + hstep, voffB); PG8_STAGE(PG8_SA(0, 0), a2, voffA);
.LBB0_436:
	ds_read_b128 v[128:131], v189
	ds_read_b128 v[132:135], v189 offset:1024
	ds_read_b128 v[136:139], v189 offset:2048
	ds_read_b128 v[140:143], v189 offset:3072
	ds_read_b128 v[144:147], v190
	ds_read_b128 v[148:151], v190 offset:1024
	ds_read_b128 v[168:171], v190 offset:2048
	ds_read_b128 v[172:175], v190 offset:3072
	s_add_u32 s46, s44, 0xfffc0080
	s_addc_u32 s47, s45, -1
	s_cmp_eq_u32 s64, 12
	s_cselect_b32 s49, s37, s47
	s_cselect_b32 s48, s43, s46
	s_cselect_b32 s47, s35, s63
	s_cselect_b32 s46, s61, s62
	s_cbranch_scc1 .Lpk2
	v_lshl_add_u64 v[184:185], s[44:45], 0, v[162:163]
	s_add_i32 m0, s31, 0xc000
	ds_read_b128 v[176:179], v191
	ds_read_b128 v[180:183], v191 offset:1024
	ds_read_b128 v[192:195], v191 offset:2048
	ds_read_b128 v[196:199], v191 offset:3072
	ds_read_b128 v[202:205], v191 offset:4096
	ds_read_b128 v[206:209], v191 offset:5120
	ds_read_b128 v[210:213], v191 offset:6144
	ds_read_b128 v[214:217], v191 offset:7168
	global_load_lds_dwordx4 v[184:185], off
	v_lshl_add_u64 v[184:185], s[44:45], 0, v[160:161]
	s_add_i32 m0, s31, 0xe000
	s_nop 0
	global_load_lds_dwordx4 v[184:185], off
	s_waitcnt vmcnt(8)
	s_waitcnt lgkmcnt(0)
	s_barrier
	s_setprio 1
	s_waitcnt lgkmcnt(0)
	v_mfma_f32_16x16x32_bf16 v[124:127], v[128:131], v[176:179], v[124:127]
	v_mfma_f32_16x16x32_bf16 v[120:123], v[136:139], v[176:179], v[120:123]
	v_mfma_f32_16x16x32_bf16 v[108:111], v[128:131], v[192:195], v[108:111]
	v_mfma_f32_16x16x32_bf16 v[104:107], v[136:139], v[192:195], v[104:107]
	v_mfma_f32_16x16x32_bf16 v[92:95], v[128:131], v[202:205], v[92:95]
	v_mfma_f32_16x16x32_bf16 v[88:91], v[136:139], v[202:205], v[88:91]
	v_mfma_f32_16x16x32_bf16 v[76:79], v[128:131], v[210:213], v[76:79]
	v_mfma_f32_16x16x32_bf16 v[72:75], v[136:139], v[210:213], v[72:75]
	v_mfma_f32_16x16x32_bf16 v[124:127], v[132:135], v[180:183], v[124:127]
	v_mfma_f32_16x16x32_bf16 v[120:123], v[140:143], v[180:183], v[120:123]
	v_mfma_f32_16x16x32_bf16 v[108:111], v[132:135], v[196:199], v[108:111]
	v_mfma_f32_16x16x32_bf16 v[104:107], v[140:143], v[196:199], v[104:107]
	v_mfma_f32_16x16x32_bf16 v[92:95], v[132:135], v[206:209], v[92:95]
	v_mfma_f32_16x16x32_bf16 v[88:91], v[140:143], v[206:209], v[88:91]
	v_mfma_f32_16x16x32_bf16 v[76:79], v[132:135], v[214:217], v[76:79]
	v_mfma_f32_16x16x32_bf16 v[72:75], v[140:143], v[214:217], v[72:75]
	s_setprio 0
	s_setprio 1
	v_mfma_f32_16x16x32_bf16 v[116:119], v[144:147], v[176:179], v[116:119]
	v_mfma_f32_16x16x32_bf16 v[112:115], v[168:171], v[176:179], v[112:115]
	v_mfma_f32_16x16x32_bf16 v[100:103], v[144:147], v[192:195], v[100:103]
	v_mfma_f32_16x16x32_bf16 v[96:99], v[168:171], v[192:195], v[96:99]
	v_mfma_f32_16x16x32_bf16 v[84:87], v[144:147], v[202:205], v[84:87]
	v_mfma_f32_16x16x32_bf16 v[80:83], v[168:171], v[202:205], v[80:83]
	v_mfma_f32_16x16x32_bf16 v[68:71], v[144:147], v[210:213], v[68:71]
	v_mfma_f32_16x16x32_bf16 v[64:67], v[168:171], v[210:213], v[64:67]
	v_mfma_f32_16x16x32_bf16 v[116:119], v[148:151], v[180:183], v[116:119]
	v_mfma_f32_16x16x32_bf16 v[112:115], v[172:175], v[180:183], v[112:115]
	v_mfma_f32_16x16x32_bf16 v[100:103], v[148:151], v[196:199], v[100:103]
	v_mfma_f32_16x16x32_bf16 v[96:99], v[172:175], v[196:199], v[96:99]
	v_mfma_f32_16x16x32_bf16 v[84:87], v[148:151], v[206:209], v[84:87]
	v_mfma_f32_16x16x32_bf16 v[80:83], v[172:175], v[206:209], v[80:83]
	v_mfma_f32_16x16x32_bf16 v[68:71], v[148:151], v[214:217], v[68:71]
	v_mfma_f32_16x16x32_bf16 v[64:67], v[172:175], v[214:217], v[64:67]
	s_setprio 0
	s_barrier
	s_add_i32 s65, s58, s30
	v_lshl_add_u64 v[184:185], s[46:47], 0, v[154:155]
	s_mov_b32 m0, s65
	ds_read_b128 v[176:179], v191 offset:16384
	ds_read_b128 v[180:183], v191 offset:17408
	ds_read_b128 v[192:195], v191 offset:18432
	ds_read_b128 v[196:199], v191 offset:19456
	ds_read_b128 v[202:205], v191 offset:20480
	ds_read_b128 v[206:209], v191 offset:21504
	ds_read_b128 v[210:213], v191 offset:22528
	ds_read_b128 v[214:217], v191 offset:23552
	global_load_lds_dwordx4 v[184:185], off
	s_add_i32 m0, s65, 0x2000
	s_add_u32 s66, s46, 0x40000
	v_lshl_add_u64 v[218:219], s[46:47], 0, v[158:159]
	s_addc_u32 s67, s47, 0
	s_add_i32 s65, s59, s30
	global_load_lds_dwordx4 v[218:219], off
	v_lshl_add_u64 v[220:221], s[66:67], 0, v[154:155]
	s_mov_b32 m0, s65
	v_lshl_add_u64 v[222:223], s[48:49], 0, v[156:157]
	global_load_lds_dwordx4 v[220:221], off
	v_lshl_add_u64 v[220:221], s[66:67], 0, v[158:159]
	s_add_i32 m0, s65, 0x2000
	s_nop 0
	global_load_lds_dwordx4 v[220:221], off
	v_lshl_add_u64 v[220:221], s[48:49], 0, v[152:153]
	s_mov_b32 m0, s31
	s_nop 0
	global_load_lds_dwordx4 v[220:221], off
	s_mov_b32 m0, s33
	s_nop 0
	global_load_lds_dwordx4 v[222:223], off
	s_waitcnt vmcnt(8)
	s_waitcnt lgkmcnt(0)
	s_barrier
; #define PG8_STAGE(bufoff, gbase, voff) do { _Pragma("unroll") for (int _i = 0; _i < 2; ++_i) \
;         __builtin_amdgcn_global_load_lds((const unsigned*)((const char*)(gbase) + (voff)[_i]), (PG8_LAS unsigned*)(lds + (bufoff) + ldsw + _i * 8192), 16, 0, 0); } while (0)
; #define PG8_LDA(dst, b, h) do { _Pragma("unroll") for (int m = 0; m < 4; ++m) _Pragma("unroll") for (int k = 0; k < 2; ++k) dst[m][k] = *(const PG8_LAS bf16x8*)(lds + PG8_SA(b, h) + aoff + m * 2048 + k * 1024); } while (0)
; #define PG8_LDB(dst, b, h) do { _Pragma("unroll") for (int n = 0; n < 2; ++n) _Pragma("unroll") for (int k = 0; k < 2; ++k) dst[n][k] = *(const PG8_LAS bf16x8*)(lds + PG8_SB(b, h) + boff + n * 2048 + k * 1024); } while (0)
; #define PG8_MMA(ai, bj, At, Bt) do { __builtin_amdgcn_s_setprio(1); _Pragma("unroll") for (int m = 0; m < 4; ++m) _Pragma("unroll") for (int n = 0; n < 2; ++n) _Pragma("unroll") for (int k = 0; k < 2; ++k) \
;         acc[ai][bj][m][n] = __builtin_amdgcn_mfma_f32_16x16x32_bf16(Bt[n][k], At[m][k], acc[ai][bj][m][n], 0, 0, 0); __builtin_amdgcn_s_setprio(0); } while (0)
; #define PG8_WAIT_V(n) asm volatile("s_waitcnt vmcnt(" #n ")" ::: "memory")
; #define PG8_WAIT_L(n) asm volatile("s_waitcnt lgkmcnt(" #n ")" ::: "memory")
; #define PG8_BAR __builtin_amdgcn_s_barrier()
; #define PG8_SCHED __builtin_amdgcn_sched_barrier(0)
; template <class Epi, class Sched, bool ALIGN_EPI = false, bool SP2 = false>
; __device__ __forceinline__ void gemm_phase(PG8_LAS unsigned char* lds, const Gemm g, const Sched& S, const Epi& E, int tid_in) {
;     ...
;             PG8_WAIT_V(8); PG8_WAIT_L(0); PG8_BAR; PG8_MMA(1, 0, At, B0); PG8_MMA(1, 1, At, B1); PG8_BAR; PG8_SCHED;
;             PG8_LDB(B0, 1, 0); PG8_LDB(B1, 1, 1); PG8_SCHED; PG8_LDA(At, 1, 0); PG8_STAGE(PG8_SA(0, 1), a2 + hstep, voffA);
;             PG8_WAIT_V(8); PG8_WAIT_L(0); PG8_BAR; PG8_MMA(0, 0, At, B0); PG8_MMA(0, 1, At, B1); PG8_BAR; PG8_SCHED;
	s_setprio 1
	s_waitcnt lgkmcnt(0)
	v_mfma_f32_16x16x32_bf16 v[60:63], v[128:131], v[176:179], v[60:63]
	v_mfma_f32_16x16x32_bf16 v[56:59], v[136:139], v[176:179], v[56:59]
	v_mfma_f32_16x16x32_bf16 v[44:47], v[128:131], v[192:195], v[44:47]
	v_mfma_f32_16x16x32_bf16 v[40:43], v[136:139], v[192:195], v[40:43]
	v_mfma_f32_16x16x32_bf16 v[28:31], v[128:131], v[202:205], v[28:31]
	v_mfma_f32_16x16x32_bf16 v[24:27], v[136:139], v[202:205], v[24:27]
	v_mfma_f32_16x16x32_bf16 v[12:15], v[128:131], v[210:213], v[12:15]
	v_mfma_f32_16x16x32_bf16 v[8:11], v[136:139], v[210:213], v[8:11]
	v_mfma_f32_16x16x32_bf16 v[60:63], v[132:135], v[180:183], v[60:63]
	v_mfma_f32_16x16x32_bf16 v[56:59], v[140:143], v[180:183], v[56:59]
	v_mfma_f32_16x16x32_bf16 v[44:47], v[132:135], v[196:199], v[44:47]
	v_mfma_f32_16x16x32_bf16 v[40:43], v[140:143], v[196:199], v[40:43]
	v_mfma_f32_16x16x32_bf16 v[28:31], v[132:135], v[206:209], v[28:31]
	v_mfma_f32_16x16x32_bf16 v[24:27], v[140:143], v[206:209], v[24:27]
	v_mfma_f32_16x16x32_bf16 v[12:15], v[132:135], v[214:217], v[12:15]
	v_mfma_f32_16x16x32_bf16 v[8:11], v[140:143], v[214:217], v[8:11]
	s_setprio 0
	s_setprio 1
	v_mfma_f32_16x16x32_bf16 v[52:55], v[144:147], v[176:179], v[52:55]
	v_mfma_f32_16x16x32_bf16 v[48:51], v[168:171], v[176:179], v[48:51]
	v_mfma_f32_16x16x32_bf16 v[36:39], v[144:147], v[192:195], v[36:39]
	v_mfma_f32_16x16x32_bf16 v[32:35], v[168:171], v[192:195], v[32:35]
	v_mfma_f32_16x16x32_bf16 v[20:23], v[144:147], v[202:205], v[20:23]
	v_mfma_f32_16x16x32_bf16 v[16:19], v[168:171], v[202:205], v[16:19]
	v_mfma_f32_16x16x32_bf16 v[4:7], v[144:147], v[210:213], v[4:7]
	v_mfma_f32_16x16x32_bf16 v[0:3], v[168:171], v[210:213], v[0:3]
	v_mfma_f32_16x16x32_bf16 v[52:55], v[148:151], v[180:183], v[52:55]
	v_mfma_f32_16x16x32_bf16 v[48:51], v[172:175], v[180:183], v[48:51]
	v_mfma_f32_16x16x32_bf16 v[36:39], v[148:151], v[196:199], v[36:39]
	v_mfma_f32_16x16x32_bf16 v[32:35], v[172:175], v[196:199], v[32:35]
	v_mfma_f32_16x16x32_bf16 v[20:23], v[148:151], v[206:209], v[20:23]
	v_mfma_f32_16x16x32_bf16 v[16:19], v[172:175], v[206:209], v[16:19]
	v_mfma_f32_16x16x32_bf16 v[4:7], v[148:151], v[214:217], v[4:7]
	v_mfma_f32_16x16x32_bf16 v[0:3], v[172:175], v[214:217], v[0:3]
	s_setprio 0
	s_barrier
	s_add_i32 s65, 0, 0x18000
	s_add_i32 s66, 0, 0x1c000
	v_add_u32_e32 v140, s65, v187
	v_add_u32_e32 v172, s66, v187
	ds_read_b128 v[128:131], v140
	ds_read_b128 v[132:135], v140 offset:1024
	ds_read_b128 v[136:139], v140 offset:2048
	ds_read_b128 v[140:143], v140 offset:3072
	ds_read_b128 v[144:147], v172
	ds_read_b128 v[148:151], v172 offset:1024
	ds_read_b128 v[168:171], v172 offset:2048
	ds_read_b128 v[172:175], v172 offset:3072
	s_add_u32 s48, s48, 0x40000
	s_addc_u32 s49, s49, 0
	s_mov_b32 m0, s50
	v_lshl_add_u64 v[224:225], s[48:49], 0, v[152:153]
	ds_read_b128 v[176:179], v191 offset:32768
	ds_read_b128 v[180:183], v191 offset:33792
	ds_read_b128 v[192:195], v191 offset:34816
	ds_read_b128 v[196:199], v191 offset:35840
	ds_read_b128 v[202:205], v191 offset:36864
	ds_read_b128 v[206:209], v191 offset:37888
	ds_read_b128 v[210:213], v191 offset:38912
	ds_read_b128 v[214:217], v191 offset:39936
	global_load_lds_dwordx4 v[224:225], off
	v_lshl_add_u64 v[224:225], s[48:49], 0, v[156:157]
	s_mov_b32 m0, s51
	s_nop 0
	global_load_lds_dwordx4 v[224:225], off
	s_waitcnt vmcnt(8)
	s_waitcnt lgkmcnt(0)
	s_barrier
	s_setprio 1
	s_waitcnt lgkmcnt(0)
	v_mfma_f32_16x16x32_bf16 v[124:127], v[128:131], v[176:179], v[124:127]
	v_mfma_f32_16x16x32_bf16 v[120:123], v[136:139], v[176:179], v[120:123]
	v_mfma_f32_16x16x32_bf16 v[108:111], v[128:131], v[192:195], v[108:111]
	v_mfma_f32_16x16x32_bf16 v[104:107], v[136:139], v[192:195], v[104:107]
	v_mfma_f32_16x16x32_bf16 v[92:95], v[128:131], v[202:205], v[92:95]
	v_mfma_f32_16x16x32_bf16 v[88:91], v[136:139], v[202:205], v[88:91]
	v_mfma_f32_16x16x32_bf16 v[76:79], v[128:131], v[210:213], v[76:79]
	v_mfma_f32_16x16x32_bf16 v[72:75], v[136:139], v[210:213], v[72:75]
	v_mfma_f32_16x16x32_bf16 v[124:127], v[132:135], v[180:183], v[124:127]
	v_mfma_f32_16x16x32_bf16 v[120:123], v[140:143], v[180:183], v[120:123]
	v_mfma_f32_16x16x32_bf16 v[108:111], v[132:135], v[196:199], v[108:111]
	v_mfma_f32_16x16x32_bf16 v[104:107], v[140:143], v[196:199], v[104:107]
	v_mfma_f32_16x16x32_bf16 v[92:95], v[132:135], v[206:209], v[92:95]
	v_mfma_f32_16x16x32_bf16 v[88:91], v[140:143], v[206:209], v[88:91]
	v_mfma_f32_16x16x32_bf16 v[76:79], v[132:135], v[214:217], v[76:79]
	v_mfma_f32_16x16x32_bf16 v[72:75], v[140:143], v[214:217], v[72:75]
	s_setprio 0
	s_setprio 1
	v_mfma_f32_16x16x32_bf16 v[116:119], v[144:147], v[176:179], v[116:119]
	v_mfma_f32_16x16x32_bf16 v[112:115], v[168:171], v[176:179], v[112:115]
	v_mfma_f32_16x16x32_bf16 v[100:103], v[144:147], v[192:195], v[100:103]
	v_mfma_f32_16x16x32_bf16 v[96:99], v[168:171], v[192:195], v[96:99]
	v_mfma_f32_16x16x32_bf16 v[84:87], v[144:147], v[202:205], v[84:87]
	v_mfma_f32_16x16x32_bf16 v[80:83], v[168:171], v[202:205], v[80:83]
	v_mfma_f32_16x16x32_bf16 v[68:71], v[144:147], v[210:213], v[68:71]
	v_mfma_f32_16x16x32_bf16 v[64:67], v[168:171], v[210:213], v[64:67]
	v_mfma_f32_16x16x32_bf16 v[116:119], v[148:151], v[180:183], v[116:119]
	v_mfma_f32_16x16x32_bf16 v[112:115], v[172:175], v[180:183], v[112:115]
	v_mfma_f32_16x16x32_bf16 v[100:103], v[148:151], v[196:199], v[100:103]
	v_mfma_f32_16x16x32_bf16 v[96:99], v[172:175], v[196:199], v[96:99]
	v_mfma_f32_16x16x32_bf16 v[84:87], v[148:151], v[206:209], v[84:87]
	v_mfma_f32_16x16x32_bf16 v[80:83], v[172:175], v[206:209], v[80:83]
	v_mfma_f32_16x16x32_bf16 v[68:71], v[148:151], v[214:217], v[68:71]
	v_mfma_f32_16x16x32_bf16 v[64:67], v[172:175], v[214:217], v[64:67]
	s_setprio 0
	s_barrier
; #define PG8_STAGE(bufoff, gbase, voff) do { _Pragma("unroll") for (int _i = 0; _i < 2; ++_i) \
;         __builtin_amdgcn_global_load_lds((const unsigned*)((const char*)(gbase) + (voff)[_i]), (PG8_LAS unsigned*)(lds + (bufoff) + ldsw + _i * 8192), 16, 0, 0); } while (0)
; #define PG8_LDA(dst, b, h) do { _Pragma("unroll") for (int m = 0; m < 4; ++m) _Pragma("unroll") for (int k = 0; k < 2; ++k) dst[m][k] = *(const PG8_LAS bf16x8*)(lds + PG8_SA(b, h) + aoff + m * 2048 + k * 1024); } while (0)
; #define PG8_MMA(ai, bj, At, Bt) do { __builtin_amdgcn_s_setprio(1); _Pragma("unroll") for (int m = 0; m < 4; ++m) _Pragma("unroll") for (int n = 0; n < 2; ++n) _Pragma("unroll") for (int k = 0; k < 2; ++k) \
;         acc[ai][bj][m][n] = __builtin_amdgcn_mfma_f32_16x16x32_bf16(Bt[n][k], At[m][k], acc[ai][bj][m][n], 0, 0, 0); __builtin_amdgcn_s_setprio(0); } while (0)
; #define PG8_WAIT_V(n) asm volatile("s_waitcnt vmcnt(" #n ")" ::: "memory")
; #define PG8_WAIT_L(n) asm volatile("s_waitcnt lgkmcnt(" #n ")" ::: "memory")
; #define PG8_BAR __builtin_amdgcn_s_barrier()
; #define PG8_SCHED __builtin_amdgcn_sched_barrier(0)
; template <class Epi, class Sched, bool ALIGN_EPI = false, bool SP2 = false>
; __device__ __forceinline__ void gemm_phase(PG8_LAS unsigned char* lds, const Gemm g, const Sched& S, const Epi& E, int tid_in) {
;     ...
;             PG8_LDA(At, 1, 1); PG8_STAGE(PG8_SB(1, 0), b3, voffB); PG8_STAGE(PG8_SB(1, 1), b3 + hstep, voffB); PG8_STAGE(PG8_SA(1, 0), a3, voffA);
;             PG8_WAIT_V(8); PG8_WAIT_L(0); PG8_BAR; PG8_MMA(1, 0, At, B0); PG8_MMA(1, 1, At, B1); PG8_BAR; PG8_SCHED;
	s_add_i32 s48, s65, s30
	v_lshl_add_u64 v[184:185], v[184:185], 0, s[24:25]
	s_mov_b32 m0, s48
	ds_read_b128 v[176:179], v191 offset:49152
	ds_read_b128 v[180:183], v191 offset:50176
	ds_read_b128 v[192:195], v191 offset:51200
	ds_read_b128 v[196:199], v191 offset:52224
	ds_read_b128 v[202:205], v191 offset:53248
	ds_read_b128 v[206:209], v191 offset:54272
	ds_read_b128 v[210:213], v191 offset:55296
	ds_read_b128 v[214:217], v191 offset:56320
	global_load_lds_dwordx4 v[184:185], off
	s_add_i32 m0, s48, 0x2000
	s_add_u32 s46, s46, 0x40080
	v_lshl_add_u64 v[184:185], v[218:219], 0, s[24:25]
	s_addc_u32 s47, s47, 0
	s_add_i32 s48, s66, s30
	global_load_lds_dwordx4 v[184:185], off
	v_lshl_add_u64 v[184:185], s[46:47], 0, v[154:155]
	s_mov_b32 m0, s48
	s_nop 0
	global_load_lds_dwordx4 v[184:185], off
	v_lshl_add_u64 v[184:185], s[46:47], 0, v[158:159]
	s_add_i32 m0, s48, 0x2000
	s_nop 0
	global_load_lds_dwordx4 v[184:185], off
	v_lshl_add_u64 v[184:185], v[220:221], 0, s[24:25]
	s_mov_b32 m0, s53
	s_nop 0
	global_load_lds_dwordx4 v[184:185], off
	v_lshl_add_u64 v[184:185], v[222:223], 0, s[24:25]
	s_mov_b32 m0, s54
	s_nop 0
	global_load_lds_dwordx4 v[184:185], off
	s_waitcnt vmcnt(8)
	s_waitcnt lgkmcnt(0)
	s_barrier
	s_setprio 1
	s_waitcnt lgkmcnt(0)
	v_mfma_f32_16x16x32_bf16 v[60:63], v[128:131], v[176:179], v[60:63]
	v_mfma_f32_16x16x32_bf16 v[56:59], v[136:139], v[176:179], v[56:59]
	v_mfma_f32_16x16x32_bf16 v[44:47], v[128:131], v[192:195], v[44:47]
	v_mfma_f32_16x16x32_bf16 v[40:43], v[136:139], v[192:195], v[40:43]
	v_mfma_f32_16x16x32_bf16 v[28:31], v[128:131], v[202:205], v[28:31]
	v_mfma_f32_16x16x32_bf16 v[24:27], v[136:139], v[202:205], v[24:27]
	v_mfma_f32_16x16x32_bf16 v[12:15], v[128:131], v[210:213], v[12:15]
	v_mfma_f32_16x16x32_bf16 v[8:11], v[136:139], v[210:213], v[8:11]
	v_mfma_f32_16x16x32_bf16 v[60:63], v[132:135], v[180:183], v[60:63]
	v_mfma_f32_16x16x32_bf16 v[56:59], v[140:143], v[180:183], v[56:59]
	v_mfma_f32_16x16x32_bf16 v[44:47], v[132:135], v[196:199], v[44:47]
	v_mfma_f32_16x16x32_bf16 v[40:43], v[140:143], v[196:199], v[40:43]
	v_mfma_f32_16x16x32_bf16 v[28:31], v[132:135], v[206:209], v[28:31]
	v_mfma_f32_16x16x32_bf16 v[24:27], v[140:143], v[206:209], v[24:27]
	v_mfma_f32_16x16x32_bf16 v[12:15], v[132:135], v[214:217], v[12:15]
	v_mfma_f32_16x16x32_bf16 v[8:11], v[140:143], v[214:217], v[8:11]
	s_setprio 0
	s_setprio 1
	v_mfma_f32_16x16x32_bf16 v[52:55], v[144:147], v[176:179], v[52:55]
	v_mfma_f32_16x16x32_bf16 v[48:51], v[168:171], v[176:179], v[48:51]
	v_mfma_f32_16x16x32_bf16 v[36:39], v[144:147], v[192:195], v[36:39]
	v_mfma_f32_16x16x32_bf16 v[32:35], v[168:171], v[192:195], v[32:35]
	v_mfma_f32_16x16x32_bf16 v[20:23], v[144:147], v[202:205], v[20:23]
	v_mfma_f32_16x16x32_bf16 v[16:19], v[168:171], v[202:205], v[16:19]
	v_mfma_f32_16x16x32_bf16 v[4:7], v[144:147], v[210:213], v[4:7]
	v_mfma_f32_16x16x32_bf16 v[0:3], v[168:171], v[210:213], v[0:3]
	v_mfma_f32_16x16x32_bf16 v[52:55], v[148:151], v[180:183], v[52:55]
	v_mfma_f32_16x16x32_bf16 v[48:51], v[172:175], v[180:183], v[48:51]
	v_mfma_f32_16x16x32_bf16 v[36:39], v[148:151], v[196:199], v[36:39]
	v_mfma_f32_16x16x32_bf16 v[32:35], v[172:175], v[196:199], v[32:35]
	v_mfma_f32_16x16x32_bf16 v[20:23], v[148:151], v[206:209], v[20:23]
	v_mfma_f32_16x16x32_bf16 v[16:19], v[172:175], v[206:209], v[16:19]
	v_mfma_f32_16x16x32_bf16 v[4:7], v[148:151], v[214:217], v[4:7]
	v_mfma_f32_16x16x32_bf16 v[0:3], v[172:175], v[214:217], v[0:3]
	s_setprio 0
	s_barrier
	s_add_i32 s64, s64, 2
	s_add_u32 s62, s62, 0x100
	s_addc_u32 s63, s63, 0
	s_add_u32 s44, s44, 0x100
	s_addc_u32 s45, s45, 0
	s_cmp_gt_u32 s64, 13
	s_cbranch_scc0 .LBB0_436
.Lpost2:
	s_and_b64 vcc, exec, s[26:27]
	s_cbranch_vccz .LBB0_439
	s_barrier

; #define PG8_STAGE(bufoff, gbase, voff) do { _Pragma("unroll") for (int _i = 0; _i < 2; ++_i) \
;         __builtin_amdgcn_global_load_lds((const unsigned*)((const char*)(gbase) + (voff)[_i]), (PG8_LAS unsigned*)(lds + (bufoff) + ldsw + _i * 8192), 16, 0, 0); } while (0)
; #define PG8_LDA(dst, b, h) do { _Pragma("unroll") for (int m = 0; m < 4; ++m) _Pragma("unroll") for (int k = 0; k < 2; ++k) dst[m][k] = *(const PG8_LAS bf16x8*)(lds + PG8_SA(b, h) + aoff + m * 2048 + k * 1024); } while (0)
; #define PG8_LDB(dst, b, h) do { _Pragma("unroll") for (int n = 0; n < 2; ++n) _Pragma("unroll") for (int k = 0; k < 2; ++k) dst[n][k] = *(const PG8_LAS bf16x8*)(lds + PG8_SB(b, h) + boff + n * 2048 + k * 1024); } while (0)
; #define PG8_MMA(ai, bj, At, Bt) do { __builtin_amdgcn_s_setprio(1); _Pragma("unroll") for (int m = 0; m < 4; ++m) _Pragma("unroll") for (int n = 0; n < 2; ++n) _Pragma("unroll") for (int k = 0; k < 2; ++k) \
;         acc[ai][bj][m][n] = __builtin_amdgcn_mfma_f32_16x16x32_bf16(Bt[n][k], At[m][k], acc[ai][bj][m][n], 0, 0, 0); __builtin_amdgcn_s_setprio(0); } while (0)
; #define PG8_WAIT_V(n) asm volatile("s_waitcnt vmcnt(" #n ")" ::: "memory")
; #define PG8_WAIT_L(n) asm volatile("s_waitcnt lgkmcnt(" #n ")" ::: "memory")
; #define PG8_BAR __builtin_amdgcn_s_barrier()
; #define PG8_SCHED __builtin_amdgcn_sched_barrier(0)
; template <class Epi, class Sched, bool ALIGN_EPI = false, bool SP2 = false>
; __device__ __forceinline__ void gemm_phase(PG8_LAS unsigned char* lds, const Gemm g, const Sched& S, const Epi& E, int tid_in) {
;     ...
;             if (last && has_next) S.a_ready(nxt);
;             if constexpr (SP2) {
;             PG8_LDB(B0, 0, 0); PG8_LDB(B1, 0, 1); PG8_SCHED; PG8_LDA(At, 0, 0); PG8_STAGE(PG8_SA(1, 1), a1 + hstep, voffA);
;             PG8_WAIT_V(8); PG8_WAIT_L(0); PG8_BAR; PG8_MMA(0, 0, At, B0); PG8_MMA(0, 1, At, B1); PG8_BAR; PG8_SCHED;
;             PG8_LDA(At, 0, 1); PG8_STAGE(PG8_SB(0, 0), b2, voffB); PG8_STAGE(PG8_SB(0, 1), b2 + hstep, voffB); PG8_STAGE(PG8_SA(0, 0), a2, voffA);
.Lpk2:
	s_or_b64 s[98:99], s[12:13], 1
	v_lshl_add_u64 v[184:185], s[44:45], 0, v[162:163]
	s_add_i32 m0, s31, 0xc000
	ds_read_b128 v[176:179], v191
	ds_read_b128 v[180:183], v191 offset:1024
	ds_read_b128 v[192:195], v191 offset:2048
	ds_read_b128 v[196:199], v191 offset:3072
	ds_read_b128 v[202:205], v191 offset:4096
	ds_read_b128 v[206:209], v191 offset:5120
	ds_read_b128 v[210:213], v191 offset:6144
	ds_read_b128 v[214:217], v191 offset:7168
	global_load_lds_dwordx4 v[184:185], off
	v_lshl_add_u64 v[184:185], s[44:45], 0, v[160:161]
	s_add_i32 m0, s31, 0xe000
	s_nop 0
	global_load_lds_dwordx4 v[184:185], off
	s_waitcnt vmcnt(8)
	s_waitcnt lgkmcnt(0)
	s_barrier
	s_setprio 1
	s_waitcnt lgkmcnt(0)
	v_mfma_f32_16x16x32_bf16 v[124:127], v[128:131], v[176:179], v[124:127]
	v_mfma_f32_16x16x32_bf16 v[120:123], v[136:139], v[176:179], v[120:123]
	v_mfma_f32_16x16x32_bf16 v[108:111], v[128:131], v[192:195], v[108:111]
	v_mfma_f32_16x16x32_bf16 v[104:107], v[136:139], v[192:195], v[104:107]
	v_mfma_f32_16x16x32_bf16 v[92:95], v[128:131], v[202:205], v[92:95]
	v_mfma_f32_16x16x32_bf16 v[88:91], v[136:139], v[202:205], v[88:91]
	v_mfma_f32_16x16x32_bf16 v[76:79], v[128:131], v[210:213], v[76:79]
	v_mfma_f32_16x16x32_bf16 v[72:75], v[136:139], v[210:213], v[72:75]
	v_mfma_f32_16x16x32_bf16 v[124:127], v[132:135], v[180:183], v[124:127]
	v_mfma_f32_16x16x32_bf16 v[120:123], v[140:143], v[180:183], v[120:123]
	v_mfma_f32_16x16x32_bf16 v[108:111], v[132:135], v[196:199], v[108:111]
	v_mfma_f32_16x16x32_bf16 v[104:107], v[140:143], v[196:199], v[104:107]
	v_mfma_f32_16x16x32_bf16 v[92:95], v[132:135], v[206:209], v[92:95]
	v_mfma_f32_16x16x32_bf16 v[88:91], v[140:143], v[206:209], v[88:91]
	v_mfma_f32_16x16x32_bf16 v[76:79], v[132:135], v[214:217], v[76:79]
	v_mfma_f32_16x16x32_bf16 v[72:75], v[140:143], v[214:217], v[72:75]
	s_setprio 0
	s_setprio 1
	v_mfma_f32_16x16x32_bf16 v[116:119], v[144:147], v[176:179], v[116:119]
	v_mfma_f32_16x16x32_bf16 v[112:115], v[168:171], v[176:179], v[112:115]
	v_mfma_f32_16x16x32_bf16 v[100:103], v[144:147], v[192:195], v[100:103]
	v_mfma_f32_16x16x32_bf16 v[96:99], v[168:171], v[192:195], v[96:99]
	v_mfma_f32_16x16x32_bf16 v[84:87], v[144:147], v[202:205], v[84:87]
	v_mfma_f32_16x16x32_bf16 v[80:83], v[168:171], v[202:205], v[80:83]
	v_mfma_f32_16x16x32_bf16 v[68:71], v[144:147], v[210:213], v[68:71]
	v_mfma_f32_16x16x32_bf16 v[64:67], v[168:171], v[210:213], v[64:67]
	v_mfma_f32_16x16x32_bf16 v[116:119], v[148:151], v[180:183], v[116:119]
	v_mfma_f32_16x16x32_bf16 v[112:115], v[172:175], v[180:183], v[112:115]
	v_mfma_f32_16x16x32_bf16 v[100:103], v[148:151], v[196:199], v[100:103]
	v_mfma_f32_16x16x32_bf16 v[96:99], v[172:175], v[196:199], v[96:99]
	v_mfma_f32_16x16x32_bf16 v[84:87], v[148:151], v[206:209], v[84:87]
	v_mfma_f32_16x16x32_bf16 v[80:83], v[172:175], v[206:209], v[80:83]
	v_mfma_f32_16x16x32_bf16 v[68:71], v[148:151], v[214:217], v[68:71]
	v_mfma_f32_16x16x32_bf16 v[64:67], v[172:175], v[214:217], v[64:67]
	s_setprio 0
	s_barrier
	s_add_i32 s65, s58, s30
	v_lshl_add_u64 v[184:185], s[46:47], 0, v[154:155]
	s_mov_b32 m0, s65
	ds_read_b128 v[176:179], v191 offset:16384
	ds_read_b128 v[180:183], v191 offset:17408
	ds_read_b128 v[192:195], v191 offset:18432
	ds_read_b128 v[196:199], v191 offset:19456
	ds_read_b128 v[202:205], v191 offset:20480
	ds_read_b128 v[206:209], v191 offset:21504
	ds_read_b128 v[210:213], v191 offset:22528
	ds_read_b128 v[214:217], v191 offset:23552
	s_mov_b64 exec, s[98:99]
	global_load_lds_dwordx4 v[184:185], off
	s_mov_b64 exec, -1
	s_add_i32 m0, s65, 0x2000
	s_add_u32 s66, s46, 0x40000
	v_lshl_add_u64 v[218:219], s[46:47], 0, v[158:159]
	s_addc_u32 s67, s47, 0
	s_add_i32 s65, s59, s30
	s_mov_b64 exec, s[98:99]
	global_load_lds_dwordx4 v[218:219], off
	s_mov_b64 exec, -1
	v_lshl_add_u64 v[220:221], s[66:67], 0, v[154:155]
	s_mov_b32 m0, s65
	v_lshl_add_u64 v[222:223], s[48:49], 0, v[156:157]
	s_mov_b64 exec, s[98:99]
	global_load_lds_dwordx4 v[220:221], off
	s_mov_b64 exec, -1
	v_lshl_add_u64 v[220:221], s[66:67], 0, v[158:159]
	s_add_i32 m0, s65, 0x2000
	s_nop 0
	s_mov_b64 exec, s[98:99]
	global_load_lds_dwordx4 v[220:221], off
	s_mov_b64 exec, -1
	v_lshl_add_u64 v[220:221], s[48:49], 0, v[152:153]
	s_mov_b32 m0, s31
	s_nop 0
	s_mov_b64 exec, s[98:99]
	global_load_lds_dwordx4 v[220:221], off
	s_mov_b64 exec, -1
	s_mov_b32 m0, s33
	s_nop 0
	s_mov_b64 exec, s[98:99]
	global_load_lds_dwordx4 v[222:223], off
	s_mov_b64 exec, -1
	s_waitcnt vmcnt(8)
	s_waitcnt lgkmcnt(0)
	s_barrier
; #define PG8_STAGE(bufoff, gbase, voff) do { _Pragma("unroll") for (int _i = 0; _i < 2; ++_i) \
;         __builtin_amdgcn_global_load_lds((const unsigned*)((const char*)(gbase) + (voff)[_i]), (PG8_LAS unsigned*)(lds + (bufoff) + ldsw + _i * 8192), 16, 0, 0); } while (0)
; #define PG8_LDA(dst, b, h) do { _Pragma("unroll") for (int m = 0; m < 4; ++m) _Pragma("unroll") for (int k = 0; k < 2; ++k) dst[m][k] = *(const PG8_LAS bf16x8*)(lds + PG8_SA(b, h) + aoff + m * 2048 + k * 1024); } while (0)
; #define PG8_LDB(dst, b, h) do { _Pragma("unroll") for (int n = 0; n < 2; ++n) _Pragma("unroll") for (int k = 0; k < 2; ++k) dst[n][k] = *(const PG8_LAS bf16x8*)(lds + PG8_SB(b, h) + boff + n * 2048 + k * 1024); } while (0)
; #define PG8_MMA(ai, bj, At, Bt) do { __builtin_amdgcn_s_setprio(1); _Pragma("unroll") for (int m = 0; m < 4; ++m) _Pragma("unroll") for (int n = 0; n < 2; ++n) _Pragma("unroll") for (int k = 0; k < 2; ++k) \
;         acc[ai][bj][m][n] = __builtin_amdgcn_mfma_f32_16x16x32_bf16(Bt[n][k], At[m][k], acc[ai][bj][m][n], 0, 0, 0); __builtin_amdgcn_s_setprio(0); } while (0)
; #define PG8_WAIT_V(n) asm volatile("s_waitcnt vmcnt(" #n ")" ::: "memory")
; #define PG8_WAIT_L(n) asm volatile("s_waitcnt lgkmcnt(" #n ")" ::: "memory")
; #define PG8_BAR __builtin_amdgcn_s_barrier()
; #define PG8_SCHED __builtin_amdgcn_sched_barrier(0)
; template <class Epi, class Sched, bool ALIGN_EPI = false, bool SP2 = false>
; __device__ __forceinline__ void gemm_phase(PG8_LAS unsigned char* lds, const Gemm g, const Sched& S, const Epi& E, int tid_in) {
;     ...
;             PG8_WAIT_V(8); PG8_WAIT_L(0); PG8_BAR; PG8_MMA(1, 0, At, B0); PG8_MMA(1, 1, At, B1); PG8_BAR; PG8_SCHED;
;             PG8_LDB(B0, 1, 0); PG8_LDB(B1, 1, 1); PG8_SCHED; PG8_LDA(At, 1, 0); PG8_STAGE(PG8_SA(0, 1), a2 + hstep, voffA);
;             PG8_WAIT_V(8); PG8_WAIT_L(0); PG8_BAR; PG8_MMA(0, 0, At, B0); PG8_MMA(0, 1, At, B1); PG8_BAR; PG8_SCHED;
	s_setprio 1
	s_waitcnt lgkmcnt(0)
	v_mfma_f32_16x16x32_bf16 v[60:63], v[128:131], v[176:179], v[60:63]
	v_mfma_f32_16x16x32_bf16 v[56:59], v[136:139], v[176:179], v[56:59]
	v_mfma_f32_16x16x32_bf16 v[44:47], v[128:131], v[192:195], v[44:47]
	v_mfma_f32_16x16x32_bf16 v[40:43], v[136:139], v[192:195], v[40:43]
	v_mfma_f32_16x16x32_bf16 v[28:31], v[128:131], v[202:205], v[28:31]
	v_mfma_f32_16x16x32_bf16 v[24:27], v[136:139], v[202:205], v[24:27]
	v_mfma_f32_16x16x32_bf16 v[12:15], v[128:131], v[210:213], v[12:15]
	v_mfma_f32_16x16x32_bf16 v[8:11], v[136:139], v[210:213], v[8:11]
	v_mfma_f32_16x16x32_bf16 v[60:63], v[132:135], v[180:183], v[60:63]
	v_mfma_f32_16x16x32_bf16 v[56:59], v[140:143], v[180:183], v[56:59]
	v_mfma_f32_16x16x32_bf16 v[44:47], v[132:135], v[196:199], v[44:47]
	v_mfma_f32_16x16x32_bf16 v[40:43], v[140:143], v[196:199], v[40:43]
	v_mfma_f32_16x16x32_bf16 v[28:31], v[132:135], v[206:209], v[28:31]
	v_mfma_f32_16x16x32_bf16 v[24:27], v[140:143], v[206:209], v[24:27]
	v_mfma_f32_16x16x32_bf16 v[12:15], v[132:135], v[214:217], v[12:15]
	v_mfma_f32_16x16x32_bf16 v[8:11], v[140:143], v[214:217], v[8:11]
	s_setprio 0
	s_setprio 1
	v_mfma_f32_16x16x32_bf16 v[52:55], v[144:147], v[176:179], v[52:55]
	v_mfma_f32_16x16x32_bf16 v[48:51], v[168:171], v[176:179], v[48:51]
	v_mfma_f32_16x16x32_bf16 v[36:39], v[144:147], v[192:195], v[36:39]
	v_mfma_f32_16x16x32_bf16 v[32:35], v[168:171], v[192:195], v[32:35]
	v_mfma_f32_16x16x32_bf16 v[20:23], v[144:147], v[202:205], v[20:23]
	v_mfma_f32_16x16x32_bf16 v[16:19], v[168:171], v[202:205], v[16:19]
	v_mfma_f32_16x16x32_bf16 v[4:7], v[144:147], v[210:213], v[4:7]
	v_mfma_f32_16x16x32_bf16 v[0:3], v[168:171], v[210:213], v[0:3]
	v_mfma_f32_16x16x32_bf16 v[52:55], v[148:151], v[180:183], v[52:55]
	v_mfma_f32_16x16x32_bf16 v[48:51], v[172:175], v[180:183], v[48:51]
	v_mfma_f32_16x16x32_bf16 v[36:39], v[148:151], v[196:199], v[36:39]
	v_mfma_f32_16x16x32_bf16 v[32:35], v[172:175], v[196:199], v[32:35]
	v_mfma_f32_16x16x32_bf16 v[20:23], v[148:151], v[206:209], v[20:23]
	v_mfma_f32_16x16x32_bf16 v[16:19], v[172:175], v[206:209], v[16:19]
	v_mfma_f32_16x16x32_bf16 v[4:7], v[148:151], v[214:217], v[4:7]
	v_mfma_f32_16x16x32_bf16 v[0:3], v[172:175], v[214:217], v[0:3]
	s_setprio 0
	s_barrier
	s_add_i32 s65, 0, 0x18000
	s_add_i32 s66, 0, 0x1c000
	v_add_u32_e32 v140, s65, v187
	v_add_u32_e32 v172, s66, v187
	ds_read_b128 v[128:131], v140
	ds_read_b128 v[132:135], v140 offset:1024
	ds_read_b128 v[136:139], v140 offset:2048
	ds_read_b128 v[140:143], v140 offset:3072
	ds_read_b128 v[144:147], v172
	ds_read_b128 v[148:151], v172 offset:1024
	ds_read_b128 v[168:171], v172 offset:2048
	ds_read_b128 v[172:175], v172 offset:3072
	s_add_u32 s48, s48, 0x40000
	s_addc_u32 s49, s49, 0
	s_mov_b32 m0, s50
	v_lshl_add_u64 v[224:225], s[48:49], 0, v[152:153]
	ds_read_b128 v[176:179], v191 offset:32768
	ds_read_b128 v[180:183], v191 offset:33792
	ds_read_b128 v[192:195], v191 offset:34816
	ds_read_b128 v[196:199], v191 offset:35840
	ds_read_b128 v[202:205], v191 offset:36864
	ds_read_b128 v[206:209], v191 offset:37888
	ds_read_b128 v[210:213], v191 offset:38912
	ds_read_b128 v[214:217], v191 offset:39936
	s_mov_b64 exec, s[98:99]
	global_load_lds_dwordx4 v[224:225], off
	s_mov_b64 exec, -1
	v_lshl_add_u64 v[224:225], s[48:49], 0, v[156:157]
	s_mov_b32 m0, s51
	s_nop 0
	s_mov_b64 exec, s[98:99]
	global_load_lds_dwordx4 v[224:225], off
	s_mov_b64 exec, -1
	s_waitcnt vmcnt(8)
	s_waitcnt lgkmcnt(0)
	s_barrier
	s_setprio 1
	s_waitcnt lgkmcnt(0)
	v_mfma_f32_16x16x32_bf16 v[124:127], v[128:131], v[176:179], v[124:127]
	v_mfma_f32_16x16x32_bf16 v[120:123], v[136:139], v[176:179], v[120:123]
	v_mfma_f32_16x16x32_bf16 v[108:111], v[128:131], v[192:195], v[108:111]
	v_mfma_f32_16x16x32_bf16 v[104:107], v[136:139], v[192:195], v[104:107]
	v_mfma_f32_16x16x32_bf16 v[92:95], v[128:131], v[202:205], v[92:95]
	v_mfma_f32_16x16x32_bf16 v[88:91], v[136:139], v[202:205], v[88:91]
	v_mfma_f32_16x16x32_bf16 v[76:79], v[128:131], v[210:213], v[76:79]
	v_mfma_f32_16x16x32_bf16 v[72:75], v[136:139], v[210:213], v[72:75]
	v_mfma_f32_16x16x32_bf16 v[124:127], v[132:135], v[180:183], v[124:127]
	v_mfma_f32_16x16x32_bf16 v[120:123], v[140:143], v[180:183], v[120:123]
	v_mfma_f32_16x16x32_bf16 v[108:111], v[132:135], v[196:199], v[108:111]
	v_mfma_f32_16x16x32_bf16 v[104:107], v[140:143], v[196:199], v[104:107]
	v_mfma_f32_16x16x32_bf16 v[92:95], v[132:135], v[206:209], v[92:95]
	v_mfma_f32_16x16x32_bf16 v[88:91], v[140:143], v[206:209], v[88:91]
	v_mfma_f32_16x16x32_bf16 v[76:79], v[132:135], v[214:217], v[76:79]
	v_mfma_f32_16x16x32_bf16 v[72:75], v[140:143], v[214:217], v[72:75]
	s_setprio 0
	s_setprio 1
	v_mfma_f32_16x16x32_bf16 v[116:119], v[144:147], v[176:179], v[116:119]
	v_mfma_f32_16x16x32_bf16 v[112:115], v[168:171], v[176:179], v[112:115]
	v_mfma_f32_16x16x32_bf16 v[100:103], v[144:147], v[192:195], v[100:103]
	v_mfma_f32_16x16x32_bf16 v[96:99], v[168:171], v[192:195], v[96:99]
	v_mfma_f32_16x16x32_bf16 v[84:87], v[144:147], v[202:205], v[84:87]
	v_mfma_f32_16x16x32_bf16 v[80:83], v[168:171], v[202:205], v[80:83]
	v_mfma_f32_16x16x32_bf16 v[68:71], v[144:147], v[210:213], v[68:71]
	v_mfma_f32_16x16x32_bf16 v[64:67], v[168:171], v[210:213], v[64:67]
	v_mfma_f32_16x16x32_bf16 v[116:119], v[148:151], v[180:183], v[116:119]
	v_mfma_f32_16x16x32_bf16 v[112:115], v[172:175], v[180:183], v[112:115]
	v_mfma_f32_16x16x32_bf16 v[100:103], v[148:151], v[196:199], v[100:103]
	v_mfma_f32_16x16x32_bf16 v[96:99], v[172:175], v[196:199], v[96:99]
	v_mfma_f32_16x16x32_bf16 v[84:87], v[148:151], v[206:209], v[84:87]
	v_mfma_f32_16x16x32_bf16 v[80:83], v[172:175], v[206:209], v[80:83]
	v_mfma_f32_16x16x32_bf16 v[68:71], v[148:151], v[214:217], v[68:71]
	v_mfma_f32_16x16x32_bf16 v[64:67], v[172:175], v[214:217], v[64:67]
	s_setprio 0
	s_barrier
; #define PG8_STAGE(bufoff, gbase, voff) do { _Pragma("unroll") for (int _i = 0; _i < 2; ++_i) \
;         __builtin_amdgcn_global_load_lds((const unsigned*)((const char*)(gbase) + (voff)[_i]), (PG8_LAS unsigned*)(lds + (bufoff) + ldsw + _i * 8192), 16, 0, 0); } while (0)
; #define PG8_LDA(dst, b, h) do { _Pragma("unroll") for (int m = 0; m < 4; ++m) _Pragma("unroll") for (int k = 0; k < 2; ++k) dst[m][k] = *(const PG8_LAS bf16x8*)(lds + PG8_SA(b, h) + aoff + m * 2048 + k * 1024); } while (0)
; #define PG8_MMA(ai, bj, At, Bt) do { __builtin_amdgcn_s_setprio(1); _Pragma("unroll") for (int m = 0; m < 4; ++m) _Pragma("unroll") for (int n = 0; n < 2; ++n) _Pragma("unroll") for (int k = 0; k < 2; ++k) \
;         acc[ai][bj][m][n] = __builtin_amdgcn_mfma_f32_16x16x32_bf16(Bt[n][k], At[m][k], acc[ai][bj][m][n], 0, 0, 0); __builtin_amdgcn_s_setprio(0); } while (0)
; #define PG8_WAIT_V(n) asm volatile("s_waitcnt vmcnt(" #n ")" ::: "memory")
; #define PG8_WAIT_L(n) asm volatile("s_waitcnt lgkmcnt(" #n ")" ::: "memory")
; #define PG8_BAR __builtin_amdgcn_s_barrier()
; #define PG8_SCHED __builtin_amdgcn_sched_barrier(0)
; template <class Epi, class Sched, bool ALIGN_EPI = false, bool SP2 = false>
; __device__ __forceinline__ void gemm_phase(PG8_LAS unsigned char* lds, const Gemm g, const Sched& S, const Epi& E, int tid_in) {
;     ...
;             PG8_LDA(At, 1, 1); PG8_STAGE(PG8_SB(1, 0), b3, voffB); PG8_STAGE(PG8_SB(1, 1), b3 + hstep, voffB); PG8_STAGE(PG8_SA(1, 0), a3, voffA);
;             PG8_WAIT_V(8); PG8_WAIT_L(0); PG8_BAR; PG8_MMA(1, 0, At, B0); PG8_MMA(1, 1, At, B1); PG8_BAR; PG8_SCHED;
	s_add_i32 s48, s65, s30
	v_lshl_add_u64 v[184:185], v[184:185], 0, s[24:25]
	s_mov_b32 m0, s48
	ds_read_b128 v[176:179], v191 offset:49152
	ds_read_b128 v[180:183], v191 offset:50176
	ds_read_b128 v[192:195], v191 offset:51200
	ds_read_b128 v[196:199], v191 offset:52224
	ds_read_b128 v[202:205], v191 offset:53248
	ds_read_b128 v[206:209], v191 offset:54272
	ds_read_b128 v[210:213], v191 offset:55296
	ds_read_b128 v[214:217], v191 offset:56320
	s_mov_b64 exec, s[98:99]
	global_load_lds_dwordx4 v[184:185], off
	s_mov_b64 exec, -1
	s_add_i32 m0, s48, 0x2000
	s_add_u32 s46, s46, 0x40080
	v_lshl_add_u64 v[184:185], v[218:219], 0, s[24:25]
	s_addc_u32 s47, s47, 0
	s_add_i32 s48, s66, s30
	s_mov_b64 exec, s[98:99]
	global_load_lds_dwordx4 v[184:185], off
	s_mov_b64 exec, -1
	v_lshl_add_u64 v[184:185], s[46:47], 0, v[154:155]
	s_mov_b32 m0, s48
	s_nop 0
	s_mov_b64 exec, s[98:99]
	global_load_lds_dwordx4 v[184:185], off
	s_mov_b64 exec, -1
	v_lshl_add_u64 v[184:185], s[46:47], 0, v[158:159]
	s_add_i32 m0, s48, 0x2000
	s_nop 0
	s_mov_b64 exec, s[98:99]
	global_load_lds_dwordx4 v[184:185], off
	s_mov_b64 exec, -1
	v_lshl_add_u64 v[184:185], v[220:221], 0, s[24:25]
	s_mov_b32 m0, s53
	s_nop 0
	s_mov_b64 exec, s[98:99]
	global_load_lds_dwordx4 v[184:185], off
	s_mov_b64 exec, -1
	v_lshl_add_u64 v[184:185], v[222:223], 0, s[24:25]
	s_mov_b32 m0, s54
	s_nop 0
	s_mov_b64 exec, s[98:99]
	global_load_lds_dwordx4 v[184:185], off
	s_mov_b64 exec, -1
	s_waitcnt vmcnt(8)
	s_waitcnt lgkmcnt(0)
	s_barrier
	s_setprio 1
	s_waitcnt lgkmcnt(0)
	v_mfma_f32_16x16x32_bf16 v[60:63], v[128:131], v[176:179], v[60:63]
	v_mfma_f32_16x16x32_bf16 v[56:59], v[136:139], v[176:179], v[56:59]
	v_mfma_f32_16x16x32_bf16 v[44:47], v[128:131], v[192:195], v[44:47]
	v_mfma_f32_16x16x32_bf16 v[40:43], v[136:139], v[192:195], v[40:43]
	v_mfma_f32_16x16x32_bf16 v[28:31], v[128:131], v[202:205], v[28:31]
	v_mfma_f32_16x16x32_bf16 v[24:27], v[136:139], v[202:205], v[24:27]
	v_mfma_f32_16x16x32_bf16 v[12:15], v[128:131], v[210:213], v[12:15]
	v_mfma_f32_16x16x32_bf16 v[8:11], v[136:139], v[210:213], v[8:11]
	v_mfma_f32_16x16x32_bf16 v[60:63], v[132:135], v[180:183], v[60:63]
	v_mfma_f32_16x16x32_bf16 v[56:59], v[140:143], v[180:183], v[56:59]
	v_mfma_f32_16x16x32_bf16 v[44:47], v[132:135], v[196:199], v[44:47]
	v_mfma_f32_16x16x32_bf16 v[40:43], v[140:143], v[196:199], v[40:43]
	v_mfma_f32_16x16x32_bf16 v[28:31], v[132:135], v[206:209], v[28:31]
	v_mfma_f32_16x16x32_bf16 v[24:27], v[140:143], v[206:209], v[24:27]
	v_mfma_f32_16x16x32_bf16 v[12:15], v[132:135], v[214:217], v[12:15]
	v_mfma_f32_16x16x32_bf16 v[8:11], v[140:143], v[214:217], v[8:11]
	s_setprio 0
	s_setprio 1
	v_mfma_f32_16x16x32_bf16 v[52:55], v[144:147], v[176:179], v[52:55]
	v_mfma_f32_16x16x32_bf16 v[48:51], v[168:171], v[176:179], v[48:51]
	v_mfma_f32_16x16x32_bf16 v[36:39], v[144:147], v[192:195], v[36:39]
	v_mfma_f32_16x16x32_bf16 v[32:35], v[168:171], v[192:195], v[32:35]
	v_mfma_f32_16x16x32_bf16 v[20:23], v[144:147], v[202:205], v[20:23]
	v_mfma_f32_16x16x32_bf16 v[16:19], v[168:171], v[202:205], v[16:19]
	v_mfma_f32_16x16x32_bf16 v[4:7], v[144:147], v[210:213], v[4:7]
	v_mfma_f32_16x16x32_bf16 v[0:3], v[168:171], v[210:213], v[0:3]
	v_mfma_f32_16x16x32_bf16 v[52:55], v[148:151], v[180:183], v[52:55]
	v_mfma_f32_16x16x32_bf16 v[48:51], v[172:175], v[180:183], v[48:51]
	v_mfma_f32_16x16x32_bf16 v[36:39], v[148:151], v[196:199], v[36:39]
	v_mfma_f32_16x16x32_bf16 v[32:35], v[172:175], v[196:199], v[32:35]
	v_mfma_f32_16x16x32_bf16 v[20:23], v[148:151], v[206:209], v[20:23]
	v_mfma_f32_16x16x32_bf16 v[16:19], v[172:175], v[206:209], v[16:19]
	v_mfma_f32_16x16x32_bf16 v[4:7], v[148:151], v[214:217], v[4:7]
	v_mfma_f32_16x16x32_bf16 v[0:3], v[172:175], v[214:217], v[0:3]
	s_setprio 0
	s_barrier
	s_add_i32 s64, s64, 2
	s_add_u32 s62, s62, 0x100
	s_addc_u32 s63, s63, 0
	s_add_u32 s44, s44, 0x100
	s_addc_u32 s45, s45, 0
	s_cmp_gt_u32 s64, 13
	s_branch .Lpost2

;     __device__ bool next(int i, Unit& u) const { if (i > 0) return false; const int t = c - first; if (t < 0 || t >= nM * nN) return false; u.pm = t % nM; u.pn = t / nM; return true; }
; #define PG8_STAGE(bufoff, gbase, voff) do { _Pragma("unroll") for (int _i = 0; _i < 2; ++_i) \
;         __builtin_amdgcn_global_load_lds((const unsigned*)((const char*)(gbase) + (voff)[_i]), (PG8_LAS unsigned*)(lds + (bufoff) + ldsw + _i * 8192), 16, 0, 0); } while (0)
; #define PG8_LDA(dst, b, h) do { _Pragma("unroll") for (int m = 0; m < 4; ++m) _Pragma("unroll") for (int k = 0; k < 2; ++k) dst[m][k] = *(const PG8_LAS bf16x8*)(lds + PG8_SA(b, h) + aoff + m * 2048 + k * 1024); } while (0)
; #define PG8_LDB(dst, b, h) do { _Pragma("unroll") for (int n = 0; n < 2; ++n) _Pragma("unroll") for (int k = 0; k < 2; ++k) dst[n][k] = *(const PG8_LAS bf16x8*)(lds + PG8_SB(b, h) + boff + n * 2048 + k * 1024); } while (0)
; #define PG8_WAIT_V(n) asm volatile("s_waitcnt vmcnt(" #n ")" ::: "memory")
; #define PG8_WAIT_L(n) asm volatile("s_waitcnt lgkmcnt(" #n ")" ::: "memory")
; #define PG8_BAR __builtin_amdgcn_s_barrier()
; template <class Epi, class Sched, bool ALIGN_EPI = false, bool SP2 = false>
; __device__ __forceinline__ void gemm_phase(PG8_LAS unsigned char* lds, const Gemm g, const Sched& S, const Epi& E, int tid_in) {
;     ...
;         const bool has_next = S.next(ui + 1, nxt);
;         const char* nA = has_next ? (const char*)g.A + (size_t)nxt.pm * tstep : cA; const char* nB = has_next ? (const char*)g.Bt + (size_t)nxt.pn * tstep : cB;
;         for (int t = 0; t < nt; t += 2) {
;             const bool last = (t == nt - 2);
;             const char* a1 = cA + (size_t)(t + 1) * kstep;
;             const char* a2 = last ? nA : cA + (size_t)(t + 2) * kstep; const char* b2 = last ? nB : cB + (size_t)(t + 2) * kstep;
;             const char* a3 = a2 + kstep; const char* b3 = b2 + kstep;
;             if (last && has_next) S.a_ready(nxt);
;             if constexpr (SP2) {
;             PG8_LDB(B0, 0, 0); PG8_LDB(B1, 0, 1); PG8_SCHED; PG8_LDA(At, 0, 0); PG8_STAGE(PG8_SA(1, 1), a1 + hstep, voffA);
;             PG8_WAIT_V(8); PG8_WAIT_L(0); PG8_BAR; PG8_MMA(0, 0, At, B0); PG8_MMA(0, 1, At, B1); PG8_BAR; PG8_SCHED;
;             PG8_LDA(At, 0, 1); PG8_STAGE(PG8_SB(0, 0), b2, voffB); PG8_STAGE(PG8_SB(0, 1), b2 + hstep, voffB); PG8_STAGE(PG8_SA(0, 0), a2, voffA);
.LBB0_520:
	ds_read_b128 v[146:149], v165
	ds_read_b128 v[176:179], v165 offset:1024
	ds_read_b128 v[180:183], v165 offset:2048
	ds_read_b128 v[184:187], v165 offset:3072
	ds_read_b128 v[188:191], v169
	ds_read_b128 v[192:195], v169 offset:1024
	ds_read_b128 v[196:199], v169 offset:2048
	ds_read_b128 v[202:205], v169 offset:3072
	s_add_u32 s40, s38, 0xfffc0080
	s_addc_u32 s41, s39, -1
	s_cmp_eq_u32 s62, 12
	s_cselect_b32 s45, s25, s41
	s_cselect_b32 s44, s58, s40
	s_cselect_b32 s41, s23, s61
	s_cselect_b32 s40, s59, s60
	s_cbranch_scc1 .Lpk3
	v_lshl_add_u64 v[150:151], s[38:39], 0, v[140:141]
	s_add_i32 m0, s37, 0xc000
	ds_read_b128 v[206:209], v173
	ds_read_b128 v[210:213], v173 offset:1024
	ds_read_b128 v[214:217], v173 offset:2048
	ds_read_b128 v[218:221], v173 offset:3072
	ds_read_b128 v[222:225], v173 offset:4096
	ds_read_b128 v[226:229], v173 offset:5120
	ds_read_b128 v[230:233], v173 offset:6144
	ds_read_b128 v[234:237], v173 offset:7168
	global_load_lds_dwordx4 v[150:151], off
	v_lshl_add_u64 v[150:151], s[38:39], 0, v[138:139]
	s_add_i32 m0, s37, 0xe000
	s_nop 0
	global_load_lds_dwordx4 v[150:151], off
	s_waitcnt vmcnt(8)
	s_waitcnt lgkmcnt(0)
	s_barrier
	s_setprio 1
	s_waitcnt lgkmcnt(0)
	v_mfma_f32_16x16x32_bf16 v[124:127], v[146:149], v[206:209], v[124:127]
	v_mfma_f32_16x16x32_bf16 v[120:123], v[180:183], v[206:209], v[120:123]
	v_mfma_f32_16x16x32_bf16 v[108:111], v[146:149], v[214:217], v[108:111]
	v_mfma_f32_16x16x32_bf16 v[104:107], v[180:183], v[214:217], v[104:107]
	v_mfma_f32_16x16x32_bf16 v[92:95], v[146:149], v[222:225], v[92:95]
	v_mfma_f32_16x16x32_bf16 v[88:91], v[180:183], v[222:225], v[88:91]
	v_mfma_f32_16x16x32_bf16 v[76:79], v[146:149], v[230:233], v[76:79]
	v_mfma_f32_16x16x32_bf16 v[72:75], v[180:183], v[230:233], v[72:75]
	v_mfma_f32_16x16x32_bf16 v[124:127], v[176:179], v[210:213], v[124:127]
	v_mfma_f32_16x16x32_bf16 v[120:123], v[184:187], v[210:213], v[120:123]
	v_mfma_f32_16x16x32_bf16 v[108:111], v[176:179], v[218:221], v[108:111]
	v_mfma_f32_16x16x32_bf16 v[104:107], v[184:187], v[218:221], v[104:107]
	v_mfma_f32_16x16x32_bf16 v[92:95], v[176:179], v[226:229], v[92:95]
	v_mfma_f32_16x16x32_bf16 v[88:91], v[184:187], v[226:229], v[88:91]
	v_mfma_f32_16x16x32_bf16 v[76:79], v[176:179], v[234:237], v[76:79]
	v_mfma_f32_16x16x32_bf16 v[72:75], v[184:187], v[234:237], v[72:75]
	s_setprio 0
	s_setprio 1
	v_mfma_f32_16x16x32_bf16 v[116:119], v[188:191], v[206:209], v[116:119]
	v_mfma_f32_16x16x32_bf16 v[112:115], v[196:199], v[206:209], v[112:115]
	v_mfma_f32_16x16x32_bf16 v[100:103], v[188:191], v[214:217], v[100:103]
	v_mfma_f32_16x16x32_bf16 v[96:99], v[196:199], v[214:217], v[96:99]
	v_mfma_f32_16x16x32_bf16 v[84:87], v[188:191], v[222:225], v[84:87]
	v_mfma_f32_16x16x32_bf16 v[80:83], v[196:199], v[222:225], v[80:83]
	v_mfma_f32_16x16x32_bf16 v[68:71], v[188:191], v[230:233], v[68:71]
	v_mfma_f32_16x16x32_bf16 v[64:67], v[196:199], v[230:233], v[64:67]
	v_mfma_f32_16x16x32_bf16 v[116:119], v[192:195], v[210:213], v[116:119]
	v_mfma_f32_16x16x32_bf16 v[112:115], v[202:205], v[210:213], v[112:115]
	v_mfma_f32_16x16x32_bf16 v[100:103], v[192:195], v[218:221], v[100:103]
	v_mfma_f32_16x16x32_bf16 v[96:99], v[202:205], v[218:221], v[96:99]
	v_mfma_f32_16x16x32_bf16 v[84:87], v[192:195], v[226:229], v[84:87]
	v_mfma_f32_16x16x32_bf16 v[80:83], v[202:205], v[226:229], v[80:83]
	v_mfma_f32_16x16x32_bf16 v[68:71], v[192:195], v[234:237], v[68:71]
	v_mfma_f32_16x16x32_bf16 v[64:67], v[202:205], v[234:237], v[64:67]
	s_setprio 0
	s_barrier
	s_add_i32 s63, s54, s30
	v_lshl_add_u64 v[150:151], s[40:41], 0, v[132:133]
	s_mov_b32 m0, s63
	ds_read_b128 v[206:209], v173 offset:16384
	ds_read_b128 v[210:213], v173 offset:17408
	ds_read_b128 v[214:217], v173 offset:18432
	ds_read_b128 v[218:221], v173 offset:19456
	ds_read_b128 v[222:225], v173 offset:20480
	ds_read_b128 v[226:229], v173 offset:21504
	ds_read_b128 v[230:233], v173 offset:22528
	ds_read_b128 v[234:237], v173 offset:23552
	global_load_lds_dwordx4 v[150:151], off
	s_add_i32 m0, s63, 0x2000
	s_add_u32 s64, s40, 0x40000
	v_lshl_add_u64 v[154:155], s[40:41], 0, v[128:129]
	s_addc_u32 s65, s41, 0
	s_add_i32 s63, s55, s30
	global_load_lds_dwordx4 v[154:155], off
	v_lshl_add_u64 v[158:159], s[64:65], 0, v[132:133]
	s_mov_b32 m0, s63
	v_lshl_add_u64 v[162:163], s[44:45], 0, v[130:131]
	global_load_lds_dwordx4 v[158:159], off
	v_lshl_add_u64 v[158:159], s[64:65], 0, v[128:129]
	s_add_i32 m0, s63, 0x2000
	s_nop 0
	global_load_lds_dwordx4 v[158:159], off
	v_lshl_add_u64 v[158:159], s[44:45], 0, v[134:135]
	s_mov_b32 m0, s37
	s_nop 0
	global_load_lds_dwordx4 v[158:159], off
	s_mov_b32 m0, s46
	s_nop 0
	global_load_lds_dwordx4 v[162:163], off
	s_waitcnt vmcnt(8)
	s_waitcnt lgkmcnt(0)
	s_barrier
; #define PG8_STAGE(bufoff, gbase, voff) do { _Pragma("unroll") for (int _i = 0; _i < 2; ++_i) \
;         __builtin_amdgcn_global_load_lds((const unsigned*)((const char*)(gbase) + (voff)[_i]), (PG8_LAS unsigned*)(lds + (bufoff) + ldsw + _i * 8192), 16, 0, 0); } while (0)
; #define PG8_LDA(dst, b, h) do { _Pragma("unroll") for (int m = 0; m < 4; ++m) _Pragma("unroll") for (int k = 0; k < 2; ++k) dst[m][k] = *(const PG8_LAS bf16x8*)(lds + PG8_SA(b, h) + aoff + m * 2048 + k * 1024); } while (0)
; #define PG8_LDB(dst, b, h) do { _Pragma("unroll") for (int n = 0; n < 2; ++n) _Pragma("unroll") for (int k = 0; k < 2; ++k) dst[n][k] = *(const PG8_LAS bf16x8*)(lds + PG8_SB(b, h) + boff + n * 2048 + k * 1024); } while (0)
; #define PG8_MMA(ai, bj, At, Bt) do { __builtin_amdgcn_s_setprio(1); _Pragma("unroll") for (int m = 0; m < 4; ++m) _Pragma("unroll") for (int n = 0; n < 2; ++n) _Pragma("unroll") for (int k = 0; k < 2; ++k) \
;         acc[ai][bj][m][n] = __builtin_amdgcn_mfma_f32_16x16x32_bf16(Bt[n][k], At[m][k], acc[ai][bj][m][n], 0, 0, 0); __builtin_amdgcn_s_setprio(0); } while (0)
; #define PG8_WAIT_V(n) asm volatile("s_waitcnt vmcnt(" #n ")" ::: "memory")
; #define PG8_WAIT_L(n) asm volatile("s_waitcnt lgkmcnt(" #n ")" ::: "memory")
; #define PG8_BAR __builtin_amdgcn_s_barrier()
; #define PG8_SCHED __builtin_amdgcn_sched_barrier(0)
; template <class Epi, class Sched, bool ALIGN_EPI = false, bool SP2 = false>
; __device__ __forceinline__ void gemm_phase(PG8_LAS unsigned char* lds, const Gemm g, const Sched& S, const Epi& E, int tid_in) {
;     ...
;             PG8_WAIT_V(8); PG8_WAIT_L(0); PG8_BAR; PG8_MMA(1, 0, At, B0); PG8_MMA(1, 1, At, B1); PG8_BAR; PG8_SCHED;
;             PG8_LDB(B0, 1, 0); PG8_LDB(B1, 1, 1); PG8_SCHED; PG8_LDA(At, 1, 0); PG8_STAGE(PG8_SA(0, 1), a2 + hstep, voffA);
;             PG8_WAIT_V(8); PG8_WAIT_L(0); PG8_BAR; PG8_MMA(0, 0, At, B0); PG8_MMA(0, 1, At, B1); PG8_BAR; PG8_SCHED;
	s_setprio 1
	s_waitcnt lgkmcnt(0)
	v_mfma_f32_16x16x32_bf16 v[60:63], v[146:149], v[206:209], v[60:63]
	v_mfma_f32_16x16x32_bf16 v[56:59], v[180:183], v[206:209], v[56:59]
	v_mfma_f32_16x16x32_bf16 v[44:47], v[146:149], v[214:217], v[44:47]
	v_mfma_f32_16x16x32_bf16 v[40:43], v[180:183], v[214:217], v[40:43]
	v_mfma_f32_16x16x32_bf16 v[28:31], v[146:149], v[222:225], v[28:31]
	v_mfma_f32_16x16x32_bf16 v[24:27], v[180:183], v[222:225], v[24:27]
	v_mfma_f32_16x16x32_bf16 v[12:15], v[146:149], v[230:233], v[12:15]
	v_mfma_f32_16x16x32_bf16 v[8:11], v[180:183], v[230:233], v[8:11]
	v_mfma_f32_16x16x32_bf16 v[60:63], v[176:179], v[210:213], v[60:63]
	v_mfma_f32_16x16x32_bf16 v[56:59], v[184:187], v[210:213], v[56:59]
	v_mfma_f32_16x16x32_bf16 v[44:47], v[176:179], v[218:221], v[44:47]
	v_mfma_f32_16x16x32_bf16 v[40:43], v[184:187], v[218:221], v[40:43]
	v_mfma_f32_16x16x32_bf16 v[28:31], v[176:179], v[226:229], v[28:31]
	v_mfma_f32_16x16x32_bf16 v[24:27], v[184:187], v[226:229], v[24:27]
	v_mfma_f32_16x16x32_bf16 v[12:15], v[176:179], v[234:237], v[12:15]
	v_mfma_f32_16x16x32_bf16 v[8:11], v[184:187], v[234:237], v[8:11]
	s_setprio 0
	s_setprio 1
	v_mfma_f32_16x16x32_bf16 v[52:55], v[188:191], v[206:209], v[52:55]
	v_mfma_f32_16x16x32_bf16 v[48:51], v[196:199], v[206:209], v[48:51]
	v_mfma_f32_16x16x32_bf16 v[36:39], v[188:191], v[214:217], v[36:39]
	v_mfma_f32_16x16x32_bf16 v[32:35], v[196:199], v[214:217], v[32:35]
	v_mfma_f32_16x16x32_bf16 v[20:23], v[188:191], v[222:225], v[20:23]
	v_mfma_f32_16x16x32_bf16 v[16:19], v[196:199], v[222:225], v[16:19]
	v_mfma_f32_16x16x32_bf16 v[4:7], v[188:191], v[230:233], v[4:7]
	v_mfma_f32_16x16x32_bf16 v[0:3], v[196:199], v[230:233], v[0:3]
	v_mfma_f32_16x16x32_bf16 v[52:55], v[192:195], v[210:213], v[52:55]
	v_mfma_f32_16x16x32_bf16 v[48:51], v[202:205], v[210:213], v[48:51]
	v_mfma_f32_16x16x32_bf16 v[36:39], v[192:195], v[218:221], v[36:39]
	v_mfma_f32_16x16x32_bf16 v[32:35], v[202:205], v[218:221], v[32:35]
	v_mfma_f32_16x16x32_bf16 v[20:23], v[192:195], v[226:229], v[20:23]
	v_mfma_f32_16x16x32_bf16 v[16:19], v[202:205], v[226:229], v[16:19]
	v_mfma_f32_16x16x32_bf16 v[4:7], v[192:195], v[234:237], v[4:7]
	v_mfma_f32_16x16x32_bf16 v[0:3], v[202:205], v[234:237], v[0:3]
	s_setprio 0
	s_barrier
	s_add_i32 s63, 0, 0x18000
	v_add_u32_e32 v152, s63, v157
	s_add_i32 s64, 0, 0x1c000
	ds_read_b128 v[146:149], v152
	ds_read_b128 v[176:179], v152 offset:1024
	ds_read_b128 v[180:183], v152 offset:2048
	ds_read_b128 v[184:187], v152 offset:3072
	v_add_u32_e32 v152, s64, v157
	ds_read_b128 v[188:191], v152
	ds_read_b128 v[192:195], v152 offset:1024
	ds_read_b128 v[196:199], v152 offset:2048
	ds_read_b128 v[202:205], v152 offset:3072
	s_add_u32 s44, s44, 0x40000
	s_addc_u32 s45, s45, 0
	s_mov_b32 m0, s47
	v_lshl_add_u64 v[166:167], s[44:45], 0, v[134:135]
	ds_read_b128 v[206:209], v173 offset:32768
	ds_read_b128 v[210:213], v173 offset:33792
	ds_read_b128 v[214:217], v173 offset:34816
	ds_read_b128 v[218:221], v173 offset:35840
	ds_read_b128 v[222:225], v173 offset:36864
	ds_read_b128 v[226:229], v173 offset:37888
	ds_read_b128 v[230:233], v173 offset:38912
	ds_read_b128 v[234:237], v173 offset:39936
	global_load_lds_dwordx4 v[166:167], off
	v_lshl_add_u64 v[166:167], s[44:45], 0, v[130:131]
	s_mov_b32 m0, s48
	s_nop 0
	global_load_lds_dwordx4 v[166:167], off
	s_waitcnt vmcnt(8)
	s_waitcnt lgkmcnt(0)
	s_barrier
	s_setprio 1
	s_waitcnt lgkmcnt(0)
	v_mfma_f32_16x16x32_bf16 v[124:127], v[146:149], v[206:209], v[124:127]
	v_mfma_f32_16x16x32_bf16 v[120:123], v[180:183], v[206:209], v[120:123]
	v_mfma_f32_16x16x32_bf16 v[108:111], v[146:149], v[214:217], v[108:111]
	v_mfma_f32_16x16x32_bf16 v[104:107], v[180:183], v[214:217], v[104:107]
	v_mfma_f32_16x16x32_bf16 v[92:95], v[146:149], v[222:225], v[92:95]
	v_mfma_f32_16x16x32_bf16 v[88:91], v[180:183], v[222:225], v[88:91]
	v_mfma_f32_16x16x32_bf16 v[76:79], v[146:149], v[230:233], v[76:79]
	v_mfma_f32_16x16x32_bf16 v[72:75], v[180:183], v[230:233], v[72:75]
	v_mfma_f32_16x16x32_bf16 v[124:127], v[176:179], v[210:213], v[124:127]
	v_mfma_f32_16x16x32_bf16 v[120:123], v[184:187], v[210:213], v[120:123]
	v_mfma_f32_16x16x32_bf16 v[108:111], v[176:179], v[218:221], v[108:111]
	v_mfma_f32_16x16x32_bf16 v[104:107], v[184:187], v[218:221], v[104:107]
	v_mfma_f32_16x16x32_bf16 v[92:95], v[176:179], v[226:229], v[92:95]
	v_mfma_f32_16x16x32_bf16 v[88:91], v[184:187], v[226:229], v[88:91]
	v_mfma_f32_16x16x32_bf16 v[76:79], v[176:179], v[234:237], v[76:79]
	v_mfma_f32_16x16x32_bf16 v[72:75], v[184:187], v[234:237], v[72:75]
	s_setprio 0
	s_setprio 1
	v_mfma_f32_16x16x32_bf16 v[116:119], v[188:191], v[206:209], v[116:119]
	v_mfma_f32_16x16x32_bf16 v[112:115], v[196:199], v[206:209], v[112:115]
	v_mfma_f32_16x16x32_bf16 v[100:103], v[188:191], v[214:217], v[100:103]
	v_mfma_f32_16x16x32_bf16 v[96:99], v[196:199], v[214:217], v[96:99]
	v_mfma_f32_16x16x32_bf16 v[84:87], v[188:191], v[222:225], v[84:87]
	v_mfma_f32_16x16x32_bf16 v[80:83], v[196:199], v[222:225], v[80:83]
	v_mfma_f32_16x16x32_bf16 v[68:71], v[188:191], v[230:233], v[68:71]
	v_mfma_f32_16x16x32_bf16 v[64:67], v[196:199], v[230:233], v[64:67]
	v_mfma_f32_16x16x32_bf16 v[116:119], v[192:195], v[210:213], v[116:119]
	v_mfma_f32_16x16x32_bf16 v[112:115], v[202:205], v[210:213], v[112:115]
	v_mfma_f32_16x16x32_bf16 v[100:103], v[192:195], v[218:221], v[100:103]
	v_mfma_f32_16x16x32_bf16 v[96:99], v[202:205], v[218:221], v[96:99]
	v_mfma_f32_16x16x32_bf16 v[84:87], v[192:195], v[226:229], v[84:87]
	v_mfma_f32_16x16x32_bf16 v[80:83], v[202:205], v[226:229], v[80:83]
	v_mfma_f32_16x16x32_bf16 v[68:71], v[192:195], v[234:237], v[68:71]
	v_mfma_f32_16x16x32_bf16 v[64:67], v[202:205], v[234:237], v[64:67]
	s_setprio 0
	s_barrier
; #define PG8_STAGE(bufoff, gbase, voff) do { _Pragma("unroll") for (int _i = 0; _i < 2; ++_i) \
;         __builtin_amdgcn_global_load_lds((const unsigned*)((const char*)(gbase) + (voff)[_i]), (PG8_LAS unsigned*)(lds + (bufoff) + ldsw + _i * 8192), 16, 0, 0); } while (0)
; #define PG8_LDA(dst, b, h) do { _Pragma("unroll") for (int m = 0; m < 4; ++m) _Pragma("unroll") for (int k = 0; k < 2; ++k) dst[m][k] = *(const PG8_LAS bf16x8*)(lds + PG8_SA(b, h) + aoff + m * 2048 + k * 1024); } while (0)
; #define PG8_MMA(ai, bj, At, Bt) do { __builtin_amdgcn_s_setprio(1); _Pragma("unroll") for (int m = 0; m < 4; ++m) _Pragma("unroll") for (int n = 0; n < 2; ++n) _Pragma("unroll") for (int k = 0; k < 2; ++k) \
;         acc[ai][bj][m][n] = __builtin_amdgcn_mfma_f32_16x16x32_bf16(Bt[n][k], At[m][k], acc[ai][bj][m][n], 0, 0, 0); __builtin_amdgcn_s_setprio(0); } while (0)
; #define PG8_WAIT_V(n) asm volatile("s_waitcnt vmcnt(" #n ")" ::: "memory")
; #define PG8_WAIT_L(n) asm volatile("s_waitcnt lgkmcnt(" #n ")" ::: "memory")
; #define PG8_BAR __builtin_amdgcn_s_barrier()
; #define PG8_SCHED __builtin_amdgcn_sched_barrier(0)
; template <class Epi, class Sched, bool ALIGN_EPI = false, bool SP2 = false>
; __device__ __forceinline__ void gemm_phase(PG8_LAS unsigned char* lds, const Gemm g, const Sched& S, const Epi& E, int tid_in) {
;     ...
;             PG8_LDA(At, 1, 1); PG8_STAGE(PG8_SB(1, 0), b3, voffB); PG8_STAGE(PG8_SB(1, 1), b3 + hstep, voffB); PG8_STAGE(PG8_SA(1, 0), a3, voffA);
;             PG8_WAIT_V(8); PG8_WAIT_L(0); PG8_BAR; PG8_MMA(1, 0, At, B0); PG8_MMA(1, 1, At, B1); PG8_BAR; PG8_SCHED;
	s_add_i32 s44, s63, s30
	v_lshl_add_u64 v[150:151], v[150:151], 0, s[16:17]
	s_mov_b32 m0, s44
	ds_read_b128 v[206:209], v173 offset:49152
	ds_read_b128 v[210:213], v173 offset:50176
	ds_read_b128 v[214:217], v173 offset:51200
	ds_read_b128 v[218:221], v173 offset:52224
	ds_read_b128 v[222:225], v173 offset:53248
	ds_read_b128 v[226:229], v173 offset:54272
	ds_read_b128 v[230:233], v173 offset:55296
	ds_read_b128 v[234:237], v173 offset:56320
	global_load_lds_dwordx4 v[150:151], off
	s_add_i32 m0, s44, 0x2000
	s_add_u32 s40, s40, 0x40080
	v_lshl_add_u64 v[150:151], v[154:155], 0, s[16:17]
	s_addc_u32 s41, s41, 0
	s_add_i32 s44, s64, s30
	global_load_lds_dwordx4 v[150:151], off
	v_lshl_add_u64 v[150:151], s[40:41], 0, v[132:133]
	s_mov_b32 m0, s44
	s_nop 0
	global_load_lds_dwordx4 v[150:151], off
	v_lshl_add_u64 v[150:151], s[40:41], 0, v[128:129]
	s_add_i32 m0, s44, 0x2000
	s_nop 0
	global_load_lds_dwordx4 v[150:151], off
	v_lshl_add_u64 v[150:151], v[158:159], 0, s[16:17]
	s_mov_b32 m0, s50
	s_nop 0
	global_load_lds_dwordx4 v[150:151], off
	v_lshl_add_u64 v[150:151], v[162:163], 0, s[16:17]
	s_mov_b32 m0, s51
	s_nop 0
	global_load_lds_dwordx4 v[150:151], off
	s_waitcnt vmcnt(8)
	s_waitcnt lgkmcnt(0)
	s_barrier
	s_setprio 1
	s_waitcnt lgkmcnt(0)
	v_mfma_f32_16x16x32_bf16 v[60:63], v[146:149], v[206:209], v[60:63]
	v_mfma_f32_16x16x32_bf16 v[56:59], v[180:183], v[206:209], v[56:59]
	v_mfma_f32_16x16x32_bf16 v[44:47], v[146:149], v[214:217], v[44:47]
	v_mfma_f32_16x16x32_bf16 v[40:43], v[180:183], v[214:217], v[40:43]
	v_mfma_f32_16x16x32_bf16 v[28:31], v[146:149], v[222:225], v[28:31]
	v_mfma_f32_16x16x32_bf16 v[24:27], v[180:183], v[222:225], v[24:27]
	v_mfma_f32_16x16x32_bf16 v[12:15], v[146:149], v[230:233], v[12:15]
	v_mfma_f32_16x16x32_bf16 v[8:11], v[180:183], v[230:233], v[8:11]
	v_mfma_f32_16x16x32_bf16 v[60:63], v[176:179], v[210:213], v[60:63]
	v_mfma_f32_16x16x32_bf16 v[56:59], v[184:187], v[210:213], v[56:59]
	v_mfma_f32_16x16x32_bf16 v[44:47], v[176:179], v[218:221], v[44:47]
	v_mfma_f32_16x16x32_bf16 v[40:43], v[184:187], v[218:221], v[40:43]
	v_mfma_f32_16x16x32_bf16 v[28:31], v[176:179], v[226:229], v[28:31]
	v_mfma_f32_16x16x32_bf16 v[24:27], v[184:187], v[226:229], v[24:27]
	v_mfma_f32_16x16x32_bf16 v[12:15], v[176:179], v[234:237], v[12:15]
	v_mfma_f32_16x16x32_bf16 v[8:11], v[184:187], v[234:237], v[8:11]
	s_setprio 0
	s_setprio 1
	v_mfma_f32_16x16x32_bf16 v[52:55], v[188:191], v[206:209], v[52:55]
	v_mfma_f32_16x16x32_bf16 v[48:51], v[196:199], v[206:209], v[48:51]
	v_mfma_f32_16x16x32_bf16 v[36:39], v[188:191], v[214:217], v[36:39]
	v_mfma_f32_16x16x32_bf16 v[32:35], v[196:199], v[214:217], v[32:35]
	v_mfma_f32_16x16x32_bf16 v[20:23], v[188:191], v[222:225], v[20:23]
	v_mfma_f32_16x16x32_bf16 v[16:19], v[196:199], v[222:225], v[16:19]
	v_mfma_f32_16x16x32_bf16 v[4:7], v[188:191], v[230:233], v[4:7]
	v_mfma_f32_16x16x32_bf16 v[0:3], v[196:199], v[230:233], v[0:3]
	v_mfma_f32_16x16x32_bf16 v[52:55], v[192:195], v[210:213], v[52:55]
	v_mfma_f32_16x16x32_bf16 v[48:51], v[202:205], v[210:213], v[48:51]
	v_mfma_f32_16x16x32_bf16 v[36:39], v[192:195], v[218:221], v[36:39]
	v_mfma_f32_16x16x32_bf16 v[32:35], v[202:205], v[218:221], v[32:35]
	v_mfma_f32_16x16x32_bf16 v[20:23], v[192:195], v[226:229], v[20:23]
	v_mfma_f32_16x16x32_bf16 v[16:19], v[202:205], v[226:229], v[16:19]
	v_mfma_f32_16x16x32_bf16 v[4:7], v[192:195], v[234:237], v[4:7]
	v_mfma_f32_16x16x32_bf16 v[0:3], v[202:205], v[234:237], v[0:3]
	s_setprio 0
	s_barrier
	s_add_i32 s62, s62, 2
	s_add_u32 s60, s60, 0x100
	s_addc_u32 s61, s61, 0
	s_add_u32 s38, s38, 0x100
	s_addc_u32 s39, s39, 0
	s_cmp_gt_u32 s62, 13
	s_cbranch_scc0 .LBB0_520

; #define PG8_STAGE(bufoff, gbase, voff) do { _Pragma("unroll") for (int _i = 0; _i < 2; ++_i) \
;         __builtin_amdgcn_global_load_lds((const unsigned*)((const char*)(gbase) + (voff)[_i]), (PG8_LAS unsigned*)(lds + (bufoff) + ldsw + _i * 8192), 16, 0, 0); } while (0)
; #define PG8_LDA(dst, b, h) do { _Pragma("unroll") for (int m = 0; m < 4; ++m) _Pragma("unroll") for (int k = 0; k < 2; ++k) dst[m][k] = *(const PG8_LAS bf16x8*)(lds + PG8_SA(b, h) + aoff + m * 2048 + k * 1024); } while (0)
; #define PG8_LDB(dst, b, h) do { _Pragma("unroll") for (int n = 0; n < 2; ++n) _Pragma("unroll") for (int k = 0; k < 2; ++k) dst[n][k] = *(const PG8_LAS bf16x8*)(lds + PG8_SB(b, h) + boff + n * 2048 + k * 1024); } while (0)
; #define PG8_MMA(ai, bj, At, Bt) do { __builtin_amdgcn_s_setprio(1); _Pragma("unroll") for (int m = 0; m < 4; ++m) _Pragma("unroll") for (int n = 0; n < 2; ++n) _Pragma("unroll") for (int k = 0; k < 2; ++k) \
;         acc[ai][bj][m][n] = __builtin_amdgcn_mfma_f32_16x16x32_bf16(Bt[n][k], At[m][k], acc[ai][bj][m][n], 0, 0, 0); __builtin_amdgcn_s_setprio(0); } while (0)
; #define PG8_WAIT_V(n) asm volatile("s_waitcnt vmcnt(" #n ")" ::: "memory")
; #define PG8_WAIT_L(n) asm volatile("s_waitcnt lgkmcnt(" #n ")" ::: "memory")
; #define PG8_BAR __builtin_amdgcn_s_barrier()
; #define PG8_SCHED __builtin_amdgcn_sched_barrier(0)
; template <class Epi, class Sched, bool ALIGN_EPI = false, bool SP2 = false>
; __device__ __forceinline__ void gemm_phase(PG8_LAS unsigned char* lds, const Gemm g, const Sched& S, const Epi& E, int tid_in) {
;     ...
;             if (last && has_next) S.a_ready(nxt);
;             if constexpr (SP2) {
;             PG8_LDB(B0, 0, 0); PG8_LDB(B1, 0, 1); PG8_SCHED; PG8_LDA(At, 0, 0); PG8_STAGE(PG8_SA(1, 1), a1 + hstep, voffA);
;             PG8_WAIT_V(8); PG8_WAIT_L(0); PG8_BAR; PG8_MMA(0, 0, At, B0); PG8_MMA(0, 1, At, B1); PG8_BAR; PG8_SCHED;
;             PG8_LDA(At, 0, 1); PG8_STAGE(PG8_SB(0, 0), b2, voffB); PG8_STAGE(PG8_SB(0, 1), b2 + hstep, voffB); PG8_STAGE(PG8_SA(0, 0), a2, voffA);
.Lpk3:
	s_or_b64 s[98:99], s[10:11], 1
	v_lshl_add_u64 v[150:151], s[38:39], 0, v[140:141]
	s_add_i32 m0, s37, 0xc000
	ds_read_b128 v[206:209], v173
	ds_read_b128 v[210:213], v173 offset:1024
	ds_read_b128 v[214:217], v173 offset:2048
	ds_read_b128 v[218:221], v173 offset:3072
	ds_read_b128 v[222:225], v173 offset:4096
	ds_read_b128 v[226:229], v173 offset:5120
	ds_read_b128 v[230:233], v173 offset:6144
	ds_read_b128 v[234:237], v173 offset:7168
	global_load_lds_dwordx4 v[150:151], off
	v_lshl_add_u64 v[150:151], s[38:39], 0, v[138:139]
	s_add_i32 m0, s37, 0xe000
	s_nop 0
	global_load_lds_dwordx4 v[150:151], off
	s_waitcnt vmcnt(8)
	s_waitcnt lgkmcnt(0)
	s_barrier
	s_setprio 1
	s_waitcnt lgkmcnt(0)
	v_mfma_f32_16x16x32_bf16 v[124:127], v[146:149], v[206:209], v[124:127]
	v_mfma_f32_16x16x32_bf16 v[120:123], v[180:183], v[206:209], v[120:123]
	v_mfma_f32_16x16x32_bf16 v[108:111], v[146:149], v[214:217], v[108:111]
	v_mfma_f32_16x16x32_bf16 v[104:107], v[180:183], v[214:217], v[104:107]
	v_mfma_f32_16x16x32_bf16 v[92:95], v[146:149], v[222:225], v[92:95]
	v_mfma_f32_16x16x32_bf16 v[88:91], v[180:183], v[222:225], v[88:91]
	v_mfma_f32_16x16x32_bf16 v[76:79], v[146:149], v[230:233], v[76:79]
	v_mfma_f32_16x16x32_bf16 v[72:75], v[180:183], v[230:233], v[72:75]
	v_mfma_f32_16x16x32_bf16 v[124:127], v[176:179], v[210:213], v[124:127]
	v_mfma_f32_16x16x32_bf16 v[120:123], v[184:187], v[210:213], v[120:123]
	v_mfma_f32_16x16x32_bf16 v[108:111], v[176:179], v[218:221], v[108:111]
	v_mfma_f32_16x16x32_bf16 v[104:107], v[184:187], v[218:221], v[104:107]
	v_mfma_f32_16x16x32_bf16 v[92:95], v[176:179], v[226:229], v[92:95]
	v_mfma_f32_16x16x32_bf16 v[88:91], v[184:187], v[226:229], v[88:91]
	v_mfma_f32_16x16x32_bf16 v[76:79], v[176:179], v[234:237], v[76:79]
	v_mfma_f32_16x16x32_bf16 v[72:75], v[184:187], v[234:237], v[72:75]
	s_setprio 0
	s_setprio 1
	v_mfma_f32_16x16x32_bf16 v[116:119], v[188:191], v[206:209], v[116:119]
	v_mfma_f32_16x16x32_bf16 v[112:115], v[196:199], v[206:209], v[112:115]
	v_mfma_f32_16x16x32_bf16 v[100:103], v[188:191], v[214:217], v[100:103]
	v_mfma_f32_16x16x32_bf16 v[96:99], v[196:199], v[214:217], v[96:99]
	v_mfma_f32_16x16x32_bf16 v[84:87], v[188:191], v[222:225], v[84:87]
	v_mfma_f32_16x16x32_bf16 v[80:83], v[196:199], v[222:225], v[80:83]
	v_mfma_f32_16x16x32_bf16 v[68:71], v[188:191], v[230:233], v[68:71]
	v_mfma_f32_16x16x32_bf16 v[64:67], v[196:199], v[230:233], v[64:67]
	v_mfma_f32_16x16x32_bf16 v[116:119], v[192:195], v[210:213], v[116:119]
	v_mfma_f32_16x16x32_bf16 v[112:115], v[202:205], v[210:213], v[112:115]
	v_mfma_f32_16x16x32_bf16 v[100:103], v[192:195], v[218:221], v[100:103]
	v_mfma_f32_16x16x32_bf16 v[96:99], v[202:205], v[218:221], v[96:99]
	v_mfma_f32_16x16x32_bf16 v[84:87], v[192:195], v[226:229], v[84:87]
	v_mfma_f32_16x16x32_bf16 v[80:83], v[202:205], v[226:229], v[80:83]
	v_mfma_f32_16x16x32_bf16 v[68:71], v[192:195], v[234:237], v[68:71]
	v_mfma_f32_16x16x32_bf16 v[64:67], v[202:205], v[234:237], v[64:67]
	s_setprio 0
	s_barrier
	s_add_i32 s63, s54, s30
	v_lshl_add_u64 v[150:151], s[40:41], 0, v[132:133]
	s_mov_b32 m0, s63
	ds_read_b128 v[206:209], v173 offset:16384
	ds_read_b128 v[210:213], v173 offset:17408
	ds_read_b128 v[214:217], v173 offset:18432
	ds_read_b128 v[218:221], v173 offset:19456
	ds_read_b128 v[222:225], v173 offset:20480
	ds_read_b128 v[226:229], v173 offset:21504
	ds_read_b128 v[230:233], v173 offset:22528
	ds_read_b128 v[234:237], v173 offset:23552
	s_mov_b64 exec, s[98:99]
	global_load_lds_dwordx4 v[150:151], off
	s_mov_b64 exec, -1
	s_add_i32 m0, s63, 0x2000
	s_add_u32 s64, s40, 0x40000
	v_lshl_add_u64 v[154:155], s[40:41], 0, v[128:129]
	s_addc_u32 s65, s41, 0
	s_add_i32 s63, s55, s30
	s_mov_b64 exec, s[98:99]
	global_load_lds_dwordx4 v[154:155], off
	s_mov_b64 exec, -1
	v_lshl_add_u64 v[158:159], s[64:65], 0, v[132:133]
	s_mov_b32 m0, s63
	v_lshl_add_u64 v[162:163], s[44:45], 0, v[130:131]
	s_mov_b64 exec, s[98:99]
	global_load_lds_dwordx4 v[158:159], off
	s_mov_b64 exec, -1
	v_lshl_add_u64 v[158:159], s[64:65], 0, v[128:129]
	s_add_i32 m0, s63, 0x2000
	s_nop 0
	s_mov_b64 exec, s[98:99]
	global_load_lds_dwordx4 v[158:159], off
	s_mov_b64 exec, -1
	v_lshl_add_u64 v[158:159], s[44:45], 0, v[134:135]
	s_mov_b32 m0, s37
	s_nop 0
	s_mov_b64 exec, s[98:99]
	global_load_lds_dwordx4 v[158:159], off
	s_mov_b64 exec, -1
	s_mov_b32 m0, s46
	s_nop 0
	s_mov_b64 exec, s[98:99]
	global_load_lds_dwordx4 v[162:163], off
	s_mov_b64 exec, -1
	s_waitcnt vmcnt(8)
	s_waitcnt lgkmcnt(0)
	s_barrier
; #define PG8_STAGE(bufoff, gbase, voff) do { _Pragma("unroll") for (int _i = 0; _i < 2; ++_i) \
;         __builtin_amdgcn_global_load_lds((const unsigned*)((const char*)(gbase) + (voff)[_i]), (PG8_LAS unsigned*)(lds + (bufoff) + ldsw + _i * 8192), 16, 0, 0); } while (0)
; #define PG8_LDA(dst, b, h) do { _Pragma("unroll") for (int m = 0; m < 4; ++m) _Pragma("unroll") for (int k = 0; k < 2; ++k) dst[m][k] = *(const PG8_LAS bf16x8*)(lds + PG8_SA(b, h) + aoff + m * 2048 + k * 1024); } while (0)
; #define PG8_LDB(dst, b, h) do { _Pragma("unroll") for (int n = 0; n < 2; ++n) _Pragma("unroll") for (int k = 0; k < 2; ++k) dst[n][k] = *(const PG8_LAS bf16x8*)(lds + PG8_SB(b, h) + boff + n * 2048 + k * 1024); } while (0)
; #define PG8_MMA(ai, bj, At, Bt) do { __builtin_amdgcn_s_setprio(1); _Pragma("unroll") for (int m = 0; m < 4; ++m) _Pragma("unroll") for (int n = 0; n < 2; ++n) _Pragma("unroll") for (int k = 0; k < 2; ++k) \
;         acc[ai][bj][m][n] = __builtin_amdgcn_mfma_f32_16x16x32_bf16(Bt[n][k], At[m][k], acc[ai][bj][m][n], 0, 0, 0); __builtin_amdgcn_s_setprio(0); } while (0)
; #define PG8_WAIT_V(n) asm volatile("s_waitcnt vmcnt(" #n ")" ::: "memory")
; #define PG8_WAIT_L(n) asm volatile("s_waitcnt lgkmcnt(" #n ")" ::: "memory")
; #define PG8_BAR __builtin_amdgcn_s_barrier()
; #define PG8_SCHED __builtin_amdgcn_sched_barrier(0)
; template <class Epi, class Sched, bool ALIGN_EPI = false, bool SP2 = false>
; __device__ __forceinline__ void gemm_phase(PG8_LAS unsigned char* lds, const Gemm g, const Sched& S, const Epi& E, int tid_in) {
;     ...
;             PG8_WAIT_V(8); PG8_WAIT_L(0); PG8_BAR; PG8_MMA(1, 0, At, B0); PG8_MMA(1, 1, At, B1); PG8_BAR; PG8_SCHED;
;             PG8_LDB(B0, 1, 0); PG8_LDB(B1, 1, 1); PG8_SCHED; PG8_LDA(At, 1, 0); PG8_STAGE(PG8_SA(0, 1), a2 + hstep, voffA);
;             PG8_WAIT_V(8); PG8_WAIT_L(0); PG8_BAR; PG8_MMA(0, 0, At, B0); PG8_MMA(0, 1, At, B1); PG8_BAR; PG8_SCHED;
	s_setprio 1
	s_waitcnt lgkmcnt(0)
	v_mfma_f32_16x16x32_bf16 v[60:63], v[146:149], v[206:209], v[60:63]
	v_mfma_f32_16x16x32_bf16 v[56:59], v[180:183], v[206:209], v[56:59]
	v_mfma_f32_16x16x32_bf16 v[44:47], v[146:149], v[214:217], v[44:47]
	v_mfma_f32_16x16x32_bf16 v[40:43], v[180:183], v[214:217], v[40:43]
	v_mfma_f32_16x16x32_bf16 v[28:31], v[146:149], v[222:225], v[28:31]
	v_mfma_f32_16x16x32_bf16 v[24:27], v[180:183], v[222:225], v[24:27]
	v_mfma_f32_16x16x32_bf16 v[12:15], v[146:149], v[230:233], v[12:15]
	v_mfma_f32_16x16x32_bf16 v[8:11], v[180:183], v[230:233], v[8:11]
	v_mfma_f32_16x16x32_bf16 v[60:63], v[176:179], v[210:213], v[60:63]
	v_mfma_f32_16x16x32_bf16 v[56:59], v[184:187], v[210:213], v[56:59]
	v_mfma_f32_16x16x32_bf16 v[44:47], v[176:179], v[218:221], v[44:47]
	v_mfma_f32_16x16x32_bf16 v[40:43], v[184:187], v[218:221], v[40:43]
	v_mfma_f32_16x16x32_bf16 v[28:31], v[176:179], v[226:229], v[28:31]
	v_mfma_f32_16x16x32_bf16 v[24:27], v[184:187], v[226:229], v[24:27]
	v_mfma_f32_16x16x32_bf16 v[12:15], v[176:179], v[234:237], v[12:15]
	v_mfma_f32_16x16x32_bf16 v[8:11], v[184:187], v[234:237], v[8:11]
	s_setprio 0
	s_setprio 1
	v_mfma_f32_16x16x32_bf16 v[52:55], v[188:191], v[206:209], v[52:55]
	v_mfma_f32_16x16x32_bf16 v[48:51], v[196:199], v[206:209], v[48:51]
	v_mfma_f32_16x16x32_bf16 v[36:39], v[188:191], v[214:217], v[36:39]
	v_mfma_f32_16x16x32_bf16 v[32:35], v[196:199], v[214:217], v[32:35]
	v_mfma_f32_16x16x32_bf16 v[20:23], v[188:191], v[222:225], v[20:23]
	v_mfma_f32_16x16x32_bf16 v[16:19], v[196:199], v[222:225], v[16:19]
	v_mfma_f32_16x16x32_bf16 v[4:7], v[188:191], v[230:233], v[4:7]
	v_mfma_f32_16x16x32_bf16 v[0:3], v[196:199], v[230:233], v[0:3]
	v_mfma_f32_16x16x32_bf16 v[52:55], v[192:195], v[210:213], v[52:55]
	v_mfma_f32_16x16x32_bf16 v[48:51], v[202:205], v[210:213], v[48:51]
	v_mfma_f32_16x16x32_bf16 v[36:39], v[192:195], v[218:221], v[36:39]
	v_mfma_f32_16x16x32_bf16 v[32:35], v[202:205], v[218:221], v[32:35]
	v_mfma_f32_16x16x32_bf16 v[20:23], v[192:195], v[226:229], v[20:23]
	v_mfma_f32_16x16x32_bf16 v[16:19], v[202:205], v[226:229], v[16:19]
	v_mfma_f32_16x16x32_bf16 v[4:7], v[192:195], v[234:237], v[4:7]
	v_mfma_f32_16x16x32_bf16 v[0:3], v[202:205], v[234:237], v[0:3]
	s_setprio 0
	s_barrier
	s_add_i32 s63, 0, 0x18000
	v_add_u32_e32 v152, s63, v157
	s_add_i32 s64, 0, 0x1c000
	ds_read_b128 v[146:149], v152
	ds_read_b128 v[176:179], v152 offset:1024
	ds_read_b128 v[180:183], v152 offset:2048
	ds_read_b128 v[184:187], v152 offset:3072
	v_add_u32_e32 v152, s64, v157
	ds_read_b128 v[188:191], v152
	ds_read_b128 v[192:195], v152 offset:1024
	ds_read_b128 v[196:199], v152 offset:2048
	ds_read_b128 v[202:205], v152 offset:3072
	s_add_u32 s44, s44, 0x40000
	s_addc_u32 s45, s45, 0
	s_mov_b32 m0, s47
	v_lshl_add_u64 v[166:167], s[44:45], 0, v[134:135]
	ds_read_b128 v[206:209], v173 offset:32768
	ds_read_b128 v[210:213], v173 offset:33792
	ds_read_b128 v[214:217], v173 offset:34816
	ds_read_b128 v[218:221], v173 offset:35840
	ds_read_b128 v[222:225], v173 offset:36864
	ds_read_b128 v[226:229], v173 offset:37888
	ds_read_b128 v[230:233], v173 offset:38912
	ds_read_b128 v[234:237], v173 offset:39936
	s_mov_b64 exec, s[98:99]
	global_load_lds_dwordx4 v[166:167], off
	s_mov_b64 exec, -1
	v_lshl_add_u64 v[166:167], s[44:45], 0, v[130:131]
	s_mov_b32 m0, s48
	s_nop 0
	s_mov_b64 exec, s[98:99]
	global_load_lds_dwordx4 v[166:167], off
	s_mov_b64 exec, -1
	s_waitcnt vmcnt(8)
	s_waitcnt lgkmcnt(0)
	s_barrier
	s_setprio 1
	s_waitcnt lgkmcnt(0)
	v_mfma_f32_16x16x32_bf16 v[124:127], v[146:149], v[206:209], v[124:127]
	v_mfma_f32_16x16x32_bf16 v[120:123], v[180:183], v[206:209], v[120:123]
	v_mfma_f32_16x16x32_bf16 v[108:111], v[146:149], v[214:217], v[108:111]
	v_mfma_f32_16x16x32_bf16 v[104:107], v[180:183], v[214:217], v[104:107]
	v_mfma_f32_16x16x32_bf16 v[92:95], v[146:149], v[222:225], v[92:95]
	v_mfma_f32_16x16x32_bf16 v[88:91], v[180:183], v[222:225], v[88:91]
	v_mfma_f32_16x16x32_bf16 v[76:79], v[146:149], v[230:233], v[76:79]
	v_mfma_f32_16x16x32_bf16 v[72:75], v[180:183], v[230:233], v[72:75]
	v_mfma_f32_16x16x32_bf16 v[124:127], v[176:179], v[210:213], v[124:127]
	v_mfma_f32_16x16x32_bf16 v[120:123], v[184:187], v[210:213], v[120:123]
	v_mfma_f32_16x16x32_bf16 v[108:111], v[176:179], v[218:221], v[108:111]
	v_mfma_f32_16x16x32_bf16 v[104:107], v[184:187], v[218:221], v[104:107]
	v_mfma_f32_16x16x32_bf16 v[92:95], v[176:179], v[226:229], v[92:95]
	v_mfma_f32_16x16x32_bf16 v[88:91], v[184:187], v[226:229], v[88:91]
	v_mfma_f32_16x16x32_bf16 v[76:79], v[176:179], v[234:237], v[76:79]
	v_mfma_f32_16x16x32_bf16 v[72:75], v[184:187], v[234:237], v[72:75]
	s_setprio 0
	s_setprio 1
	v_mfma_f32_16x16x32_bf16 v[116:119], v[188:191], v[206:209], v[116:119]
	v_mfma_f32_16x16x32_bf16 v[112:115], v[196:199], v[206:209], v[112:115]
	v_mfma_f32_16x16x32_bf16 v[100:103], v[188:191], v[214:217], v[100:103]
	v_mfma_f32_16x16x32_bf16 v[96:99], v[196:199], v[214:217], v[96:99]
	v_mfma_f32_16x16x32_bf16 v[84:87], v[188:191], v[222:225], v[84:87]
	v_mfma_f32_16x16x32_bf16 v[80:83], v[196:199], v[222:225], v[80:83]
	v_mfma_f32_16x16x32_bf16 v[68:71], v[188:191], v[230:233], v[68:71]
	v_mfma_f32_16x16x32_bf16 v[64:67], v[196:199], v[230:233], v[64:67]
	v_mfma_f32_16x16x32_bf16 v[116:119], v[192:195], v[210:213], v[116:119]
	v_mfma_f32_16x16x32_bf16 v[112:115], v[202:205], v[210:213], v[112:115]
	v_mfma_f32_16x16x32_bf16 v[100:103], v[192:195], v[218:221], v[100:103]
	v_mfma_f32_16x16x32_bf16 v[96:99], v[202:205], v[218:221], v[96:99]
	v_mfma_f32_16x16x32_bf16 v[84:87], v[192:195], v[226:229], v[84:87]
	v_mfma_f32_16x16x32_bf16 v[80:83], v[202:205], v[226:229], v[80:83]
	v_mfma_f32_16x16x32_bf16 v[68:71], v[192:195], v[234:237], v[68:71]
	v_mfma_f32_16x16x32_bf16 v[64:67], v[202:205], v[234:237], v[64:67]
	s_setprio 0
	s_barrier
; #define PG8_STAGE(bufoff, gbase, voff) do { _Pragma("unroll") for (int _i = 0; _i < 2; ++_i) \
;         __builtin_amdgcn_global_load_lds((const unsigned*)((const char*)(gbase) + (voff)[_i]), (PG8_LAS unsigned*)(lds + (bufoff) + ldsw + _i * 8192), 16, 0, 0); } while (0)
; #define PG8_LDA(dst, b, h) do { _Pragma("unroll") for (int m = 0; m < 4; ++m) _Pragma("unroll") for (int k = 0; k < 2; ++k) dst[m][k] = *(const PG8_LAS bf16x8*)(lds + PG8_SA(b, h) + aoff + m * 2048 + k * 1024); } while (0)
; #define PG8_MMA(ai, bj, At, Bt) do { __builtin_amdgcn_s_setprio(1); _Pragma("unroll") for (int m = 0; m < 4; ++m) _Pragma("unroll") for (int n = 0; n < 2; ++n) _Pragma("unroll") for (int k = 0; k < 2; ++k) \
;         acc[ai][bj][m][n] = __builtin_amdgcn_mfma_f32_16x16x32_bf16(Bt[n][k], At[m][k], acc[ai][bj][m][n], 0, 0, 0); __builtin_amdgcn_s_setprio(0); } while (0)
; #define PG8_WAIT_V(n) asm volatile("s_waitcnt vmcnt(" #n ")" ::: "memory")
; #define PG8_WAIT_L(n) asm volatile("s_waitcnt lgkmcnt(" #n ")" ::: "memory")
; #define PG8_BAR __builtin_amdgcn_s_barrier()
; #define PG8_SCHED __builtin_amdgcn_sched_barrier(0)
; template <class Epi, class Sched, bool ALIGN_EPI = false, bool SP2 = false>
; __device__ __forceinline__ void gemm_phase(PG8_LAS unsigned char* lds, const Gemm g, const Sched& S, const Epi& E, int tid_in) {
;     ...
;             PG8_LDA(At, 1, 1); PG8_STAGE(PG8_SB(1, 0), b3, voffB); PG8_STAGE(PG8_SB(1, 1), b3 + hstep, voffB); PG8_STAGE(PG8_SA(1, 0), a3, voffA);
;             PG8_WAIT_V(8); PG8_WAIT_L(0); PG8_BAR; PG8_MMA(1, 0, At, B0); PG8_MMA(1, 1, At, B1); PG8_BAR; PG8_SCHED;
	s_add_i32 s44, s63, s30
	v_lshl_add_u64 v[150:151], v[150:151], 0, s[16:17]
	s_mov_b32 m0, s44
	ds_read_b128 v[206:209], v173 offset:49152
	ds_read_b128 v[210:213], v173 offset:50176
	ds_read_b128 v[214:217], v173 offset:51200
	ds_read_b128 v[218:221], v173 offset:52224
	ds_read_b128 v[222:225], v173 offset:53248
	ds_read_b128 v[226:229], v173 offset:54272
	ds_read_b128 v[230:233], v173 offset:55296
	ds_read_b128 v[234:237], v173 offset:56320
	s_mov_b64 exec, s[98:99]
	global_load_lds_dwordx4 v[150:151], off
	s_mov_b64 exec, -1
	s_add_i32 m0, s44, 0x2000
	s_add_u32 s40, s40, 0x40080
	v_lshl_add_u64 v[150:151], v[154:155], 0, s[16:17]
	s_addc_u32 s41, s41, 0
	s_add_i32 s44, s64, s30
	s_mov_b64 exec, s[98:99]
	global_load_lds_dwordx4 v[150:151], off
	s_mov_b64 exec, -1
	v_lshl_add_u64 v[150:151], s[40:41], 0, v[132:133]
	s_mov_b32 m0, s44
	s_nop 0
	s_mov_b64 exec, s[98:99]
	global_load_lds_dwordx4 v[150:151], off
	s_mov_b64 exec, -1
	v_lshl_add_u64 v[150:151], s[40:41], 0, v[128:129]
	s_add_i32 m0, s44, 0x2000
	s_nop 0
	s_mov_b64 exec, s[98:99]
	global_load_lds_dwordx4 v[150:151], off
	s_mov_b64 exec, -1
	v_lshl_add_u64 v[150:151], v[158:159], 0, s[16:17]
	s_mov_b32 m0, s50
	s_nop 0
	s_mov_b64 exec, s[98:99]
	global_load_lds_dwordx4 v[150:151], off
	s_mov_b64 exec, -1
	v_lshl_add_u64 v[150:151], v[162:163], 0, s[16:17]
	s_mov_b32 m0, s51
	s_nop 0
	s_mov_b64 exec, s[98:99]
	global_load_lds_dwordx4 v[150:151], off
	s_mov_b64 exec, -1
	s_waitcnt vmcnt(8)
	s_waitcnt lgkmcnt(0)
	s_barrier
	s_setprio 1
	s_waitcnt lgkmcnt(0)
	v_mfma_f32_16x16x32_bf16 v[60:63], v[146:149], v[206:209], v[60:63]
	v_mfma_f32_16x16x32_bf16 v[56:59], v[180:183], v[206:209], v[56:59]
	v_mfma_f32_16x16x32_bf16 v[44:47], v[146:149], v[214:217], v[44:47]
	v_mfma_f32_16x16x32_bf16 v[40:43], v[180:183], v[214:217], v[40:43]
	v_mfma_f32_16x16x32_bf16 v[28:31], v[146:149], v[222:225], v[28:31]
	v_mfma_f32_16x16x32_bf16 v[24:27], v[180:183], v[222:225], v[24:27]
	v_mfma_f32_16x16x32_bf16 v[12:15], v[146:149], v[230:233], v[12:15]
	v_mfma_f32_16x16x32_bf16 v[8:11], v[180:183], v[230:233], v[8:11]
	v_mfma_f32_16x16x32_bf16 v[60:63], v[176:179], v[210:213], v[60:63]
	v_mfma_f32_16x16x32_bf16 v[56:59], v[184:187], v[210:213], v[56:59]
	v_mfma_f32_16x16x32_bf16 v[44:47], v[176:179], v[218:221], v[44:47]
	v_mfma_f32_16x16x32_bf16 v[40:43], v[184:187], v[218:221], v[40:43]
	v_mfma_f32_16x16x32_bf16 v[28:31], v[176:179], v[226:229], v[28:31]
	v_mfma_f32_16x16x32_bf16 v[24:27], v[184:187], v[226:229], v[24:27]
	v_mfma_f32_16x16x32_bf16 v[12:15], v[176:179], v[234:237], v[12:15]
	v_mfma_f32_16x16x32_bf16 v[8:11], v[184:187], v[234:237], v[8:11]
	s_setprio 0
	s_setprio 1
	v_mfma_f32_16x16x32_bf16 v[52:55], v[188:191], v[206:209], v[52:55]
	v_mfma_f32_16x16x32_bf16 v[48:51], v[196:199], v[206:209], v[48:51]
	v_mfma_f32_16x16x32_bf16 v[36:39], v[188:191], v[214:217], v[36:39]
	v_mfma_f32_16x16x32_bf16 v[32:35], v[196:199], v[214:217], v[32:35]
	v_mfma_f32_16x16x32_bf16 v[20:23], v[188:191], v[222:225], v[20:23]
	v_mfma_f32_16x16x32_bf16 v[16:19], v[196:199], v[222:225], v[16:19]
	v_mfma_f32_16x16x32_bf16 v[4:7], v[188:191], v[230:233], v[4:7]
	v_mfma_f32_16x16x32_bf16 v[0:3], v[196:199], v[230:233], v[0:3]
	v_mfma_f32_16x16x32_bf16 v[52:55], v[192:195], v[210:213], v[52:55]
	v_mfma_f32_16x16x32_bf16 v[48:51], v[202:205], v[210:213], v[48:51]
	v_mfma_f32_16x16x32_bf16 v[36:39], v[192:195], v[218:221], v[36:39]
	v_mfma_f32_16x16x32_bf16 v[32:35], v[202:205], v[218:221], v[32:35]
	v_mfma_f32_16x16x32_bf16 v[20:23], v[192:195], v[226:229], v[20:23]
	v_mfma_f32_16x16x32_bf16 v[16:19], v[202:205], v[226:229], v[16:19]
	v_mfma_f32_16x16x32_bf16 v[4:7], v[192:195], v[234:237], v[4:7]
	v_mfma_f32_16x16x32_bf16 v[0:3], v[202:205], v[234:237], v[0:3]
	s_setprio 0
	s_barrier
	s_add_i32 s62, s62, 2
	s_add_u32 s60, s60, 0x100
	s_addc_u32 s61, s61, 0
	s_add_u32 s38, s38, 0x100
	s_addc_u32 s39, s39, 0
	s_cmp_gt_u32 s62, 13
	s_branch .Lpost3

;     __device__ bool next(int i, Unit& u) const { if (i > 0) return false; const int t = c - first; if (t < 0 || t >= nM * nN) return false; u.pm = t % nM; u.pn = t / nM; return true; }
; #define PG8_STAGE(bufoff, gbase, voff) do { _Pragma("unroll") for (int _i = 0; _i < 2; ++_i) \
;         __builtin_amdgcn_global_load_lds((const unsigned*)((const char*)(gbase) + (voff)[_i]), (PG8_LAS unsigned*)(lds + (bufoff) + ldsw + _i * 8192), 16, 0, 0); } while (0)
; #define PG8_LDA(dst, b, h) do { _Pragma("unroll") for (int m = 0; m < 4; ++m) _Pragma("unroll") for (int k = 0; k < 2; ++k) dst[m][k] = *(const PG8_LAS bf16x8*)(lds + PG8_SA(b, h) + aoff + m * 2048 + k * 1024); } while (0)
; #define PG8_LDB(dst, b, h) do { _Pragma("unroll") for (int n = 0; n < 2; ++n) _Pragma("unroll") for (int k = 0; k < 2; ++k) dst[n][k] = *(const PG8_LAS bf16x8*)(lds + PG8_SB(b, h) + boff + n * 2048 + k * 1024); } while (0)
; #define PG8_WAIT_V(n) asm volatile("s_waitcnt vmcnt(" #n ")" ::: "memory")
; #define PG8_WAIT_L(n) asm volatile("s_waitcnt lgkmcnt(" #n ")" ::: "memory")
; #define PG8_BAR __builtin_amdgcn_s_barrier()
; template <class Epi, class Sched, bool ALIGN_EPI = false, bool SP2 = false>
; __device__ __forceinline__ void gemm_phase(PG8_LAS unsigned char* lds, const Gemm g, const Sched& S, const Epi& E, int tid_in) {
;     ...
;         const bool has_next = S.next(ui + 1, nxt);
;         const char* nA = has_next ? (const char*)g.A + (size_t)nxt.pm * tstep : cA; const char* nB = has_next ? (const char*)g.Bt + (size_t)nxt.pn * tstep : cB;
;         for (int t = 0; t < nt; t += 2) {
;             const bool last = (t == nt - 2);
;             const char* a1 = cA + (size_t)(t + 1) * kstep;
;             const char* a2 = last ? nA : cA + (size_t)(t + 2) * kstep; const char* b2 = last ? nB : cB + (size_t)(t + 2) * kstep;
;             const char* a3 = a2 + kstep; const char* b3 = b2 + kstep;
;             if (last && has_next) S.a_ready(nxt);
;             if constexpr (SP2) {
;             PG8_LDB(B0, 0, 0); PG8_LDB(B1, 0, 1); PG8_SCHED; PG8_LDA(At, 0, 0); PG8_STAGE(PG8_SA(1, 1), a1 + hstep, voffA);
;             PG8_WAIT_V(8); PG8_WAIT_L(0); PG8_BAR; PG8_MMA(0, 0, At, B0); PG8_MMA(0, 1, At, B1); PG8_BAR; PG8_SCHED;
;             PG8_LDA(At, 0, 1); PG8_STAGE(PG8_SB(0, 0), b2, voffB); PG8_STAGE(PG8_SB(0, 1), b2 + hstep, voffB); PG8_STAGE(PG8_SA(0, 0), a2, voffA);
.LBB0_602:
	ds_read_b128 v[128:131], v189
	ds_read_b128 v[132:135], v189 offset:1024
	ds_read_b128 v[136:139], v189 offset:2048
	ds_read_b128 v[140:143], v189 offset:3072
	ds_read_b128 v[144:147], v190
	ds_read_b128 v[148:151], v190 offset:1024
	ds_read_b128 v[168:171], v190 offset:2048
	ds_read_b128 v[172:175], v190 offset:3072
	s_add_u32 s40, s38, 0x100
	s_addc_u32 s41, s39, 0
	s_cmp_eq_u32 s64, 40
	s_cselect_b32 s47, s15, s41
	s_cselect_b32 s46, s14, s40
	s_cselect_b32 s45, s37, s63
	s_cselect_b32 s44, s36, s62
	s_cbranch_scc1 .Lpk4
	v_lshl_add_u64 v[184:185], s[38:39], 0, v[162:163]
	s_add_i32 m0, s31, 0xc000
	ds_read_b128 v[176:179], v191
	ds_read_b128 v[180:183], v191 offset:1024
	ds_read_b128 v[192:195], v191 offset:2048
	ds_read_b128 v[196:199], v191 offset:3072
	ds_read_b128 v[202:205], v191 offset:4096
	ds_read_b128 v[206:209], v191 offset:5120
	ds_read_b128 v[210:213], v191 offset:6144
	ds_read_b128 v[214:217], v191 offset:7168
	global_load_lds_dwordx4 v[184:185], off
	v_lshl_add_u64 v[184:185], s[38:39], 0, v[160:161]
	s_add_i32 m0, s31, 0xe000
	s_nop 0
	global_load_lds_dwordx4 v[184:185], off
	s_waitcnt vmcnt(8)
	s_waitcnt lgkmcnt(0)
	s_barrier
	s_setprio 1
	s_waitcnt lgkmcnt(0)
	v_mfma_f32_16x16x32_bf16 v[124:127], v[128:131], v[176:179], v[124:127]
	v_mfma_f32_16x16x32_bf16 v[120:123], v[136:139], v[176:179], v[120:123]
	v_mfma_f32_16x16x32_bf16 v[108:111], v[128:131], v[192:195], v[108:111]
	v_mfma_f32_16x16x32_bf16 v[104:107], v[136:139], v[192:195], v[104:107]
	v_mfma_f32_16x16x32_bf16 v[92:95], v[128:131], v[202:205], v[92:95]
	v_mfma_f32_16x16x32_bf16 v[88:91], v[136:139], v[202:205], v[88:91]
	v_mfma_f32_16x16x32_bf16 v[76:79], v[128:131], v[210:213], v[76:79]
	v_mfma_f32_16x16x32_bf16 v[72:75], v[136:139], v[210:213], v[72:75]
	v_mfma_f32_16x16x32_bf16 v[124:127], v[132:135], v[180:183], v[124:127]
	v_mfma_f32_16x16x32_bf16 v[120:123], v[140:143], v[180:183], v[120:123]
	v_mfma_f32_16x16x32_bf16 v[108:111], v[132:135], v[196:199], v[108:111]
	v_mfma_f32_16x16x32_bf16 v[104:107], v[140:143], v[196:199], v[104:107]
	v_mfma_f32_16x16x32_bf16 v[92:95], v[132:135], v[206:209], v[92:95]
	v_mfma_f32_16x16x32_bf16 v[88:91], v[140:143], v[206:209], v[88:91]
	v_mfma_f32_16x16x32_bf16 v[76:79], v[132:135], v[214:217], v[76:79]
	v_mfma_f32_16x16x32_bf16 v[72:75], v[140:143], v[214:217], v[72:75]
	s_setprio 0
	s_setprio 1
	v_mfma_f32_16x16x32_bf16 v[116:119], v[144:147], v[176:179], v[116:119]
	v_mfma_f32_16x16x32_bf16 v[112:115], v[168:171], v[176:179], v[112:115]
	v_mfma_f32_16x16x32_bf16 v[100:103], v[144:147], v[192:195], v[100:103]
	v_mfma_f32_16x16x32_bf16 v[96:99], v[168:171], v[192:195], v[96:99]
	v_mfma_f32_16x16x32_bf16 v[84:87], v[144:147], v[202:205], v[84:87]
	v_mfma_f32_16x16x32_bf16 v[80:83], v[168:171], v[202:205], v[80:83]
	v_mfma_f32_16x16x32_bf16 v[68:71], v[144:147], v[210:213], v[68:71]
	v_mfma_f32_16x16x32_bf16 v[64:67], v[168:171], v[210:213], v[64:67]
	v_mfma_f32_16x16x32_bf16 v[116:119], v[148:151], v[180:183], v[116:119]
	v_mfma_f32_16x16x32_bf16 v[112:115], v[172:175], v[180:183], v[112:115]
	v_mfma_f32_16x16x32_bf16 v[100:103], v[148:151], v[196:199], v[100:103]
	v_mfma_f32_16x16x32_bf16 v[96:99], v[172:175], v[196:199], v[96:99]
	v_mfma_f32_16x16x32_bf16 v[84:87], v[148:151], v[206:209], v[84:87]
	v_mfma_f32_16x16x32_bf16 v[80:83], v[172:175], v[206:209], v[80:83]
	v_mfma_f32_16x16x32_bf16 v[68:71], v[148:151], v[214:217], v[68:71]
	v_mfma_f32_16x16x32_bf16 v[64:67], v[172:175], v[214:217], v[64:67]
	s_setprio 0
	s_barrier
	s_add_i32 s38, s56, s30
	v_lshl_add_u64 v[184:185], s[44:45], 0, v[154:155]
	s_mov_b32 m0, s38
	ds_read_b128 v[176:179], v191 offset:16384
	ds_read_b128 v[180:183], v191 offset:17408
	ds_read_b128 v[192:195], v191 offset:18432
	ds_read_b128 v[196:199], v191 offset:19456
	ds_read_b128 v[202:205], v191 offset:20480
	ds_read_b128 v[206:209], v191 offset:21504
	ds_read_b128 v[210:213], v191 offset:22528
	ds_read_b128 v[214:217], v191 offset:23552
	global_load_lds_dwordx4 v[184:185], off
	s_add_i32 m0, s38, 0x2000
	s_add_u32 s38, s44, 0xb0000
	v_lshl_add_u64 v[218:219], s[44:45], 0, v[158:159]
	s_addc_u32 s39, s45, 0
	s_add_i32 s65, s57, s30
	global_load_lds_dwordx4 v[218:219], off
	v_lshl_add_u64 v[220:221], s[38:39], 0, v[154:155]
	s_mov_b32 m0, s65
	v_lshl_add_u64 v[222:223], s[46:47], 0, v[156:157]
	global_load_lds_dwordx4 v[220:221], off
	v_lshl_add_u64 v[220:221], s[38:39], 0, v[158:159]
	s_add_i32 m0, s65, 0x2000
	s_nop 0
	global_load_lds_dwordx4 v[220:221], off
	v_lshl_add_u64 v[220:221], s[46:47], 0, v[152:153]
	s_mov_b32 m0, s31
	s_nop 0
	global_load_lds_dwordx4 v[220:221], off
	s_mov_b32 m0, s33
	s_nop 0
	global_load_lds_dwordx4 v[222:223], off
	s_waitcnt vmcnt(8)
	s_waitcnt lgkmcnt(0)
	s_barrier
; #define PG8_STAGE(bufoff, gbase, voff) do { _Pragma("unroll") for (int _i = 0; _i < 2; ++_i) \
;         __builtin_amdgcn_global_load_lds((const unsigned*)((const char*)(gbase) + (voff)[_i]), (PG8_LAS unsigned*)(lds + (bufoff) + ldsw + _i * 8192), 16, 0, 0); } while (0)
; #define PG8_LDA(dst, b, h) do { _Pragma("unroll") for (int m = 0; m < 4; ++m) _Pragma("unroll") for (int k = 0; k < 2; ++k) dst[m][k] = *(const PG8_LAS bf16x8*)(lds + PG8_SA(b, h) + aoff + m * 2048 + k * 1024); } while (0)
; #define PG8_LDB(dst, b, h) do { _Pragma("unroll") for (int n = 0; n < 2; ++n) _Pragma("unroll") for (int k = 0; k < 2; ++k) dst[n][k] = *(const PG8_LAS bf16x8*)(lds + PG8_SB(b, h) + boff + n * 2048 + k * 1024); } while (0)
; #define PG8_MMA(ai, bj, At, Bt) do { __builtin_amdgcn_s_setprio(1); _Pragma("unroll") for (int m = 0; m < 4; ++m) _Pragma("unroll") for (int n = 0; n < 2; ++n) _Pragma("unroll") for (int k = 0; k < 2; ++k) \
;         acc[ai][bj][m][n] = __builtin_amdgcn_mfma_f32_16x16x32_bf16(Bt[n][k], At[m][k], acc[ai][bj][m][n], 0, 0, 0); __builtin_amdgcn_s_setprio(0); } while (0)
; #define PG8_WAIT_V(n) asm volatile("s_waitcnt vmcnt(" #n ")" ::: "memory")
; #define PG8_WAIT_L(n) asm volatile("s_waitcnt lgkmcnt(" #n ")" ::: "memory")
; #define PG8_BAR __builtin_amdgcn_s_barrier()
; #define PG8_SCHED __builtin_amdgcn_sched_barrier(0)
; template <class Epi, class Sched, bool ALIGN_EPI = false, bool SP2 = false>
; __device__ __forceinline__ void gemm_phase(PG8_LAS unsigned char* lds, const Gemm g, const Sched& S, const Epi& E, int tid_in) {
;     ...
;             PG8_WAIT_V(8); PG8_WAIT_L(0); PG8_BAR; PG8_MMA(1, 0, At, B0); PG8_MMA(1, 1, At, B1); PG8_BAR; PG8_SCHED;
;             PG8_LDB(B0, 1, 0); PG8_LDB(B1, 1, 1); PG8_SCHED; PG8_LDA(At, 1, 0); PG8_STAGE(PG8_SA(0, 1), a2 + hstep, voffA);
;             PG8_WAIT_V(8); PG8_WAIT_L(0); PG8_BAR; PG8_MMA(0, 0, At, B0); PG8_MMA(0, 1, At, B1); PG8_BAR; PG8_SCHED;
	s_setprio 1
	s_waitcnt lgkmcnt(0)
	v_mfma_f32_16x16x32_bf16 v[60:63], v[128:131], v[176:179], v[60:63]
	v_mfma_f32_16x16x32_bf16 v[56:59], v[136:139], v[176:179], v[56:59]
	v_mfma_f32_16x16x32_bf16 v[44:47], v[128:131], v[192:195], v[44:47]
	v_mfma_f32_16x16x32_bf16 v[40:43], v[136:139], v[192:195], v[40:43]
	v_mfma_f32_16x16x32_bf16 v[28:31], v[128:131], v[202:205], v[28:31]
	v_mfma_f32_16x16x32_bf16 v[24:27], v[136:139], v[202:205], v[24:27]
	v_mfma_f32_16x16x32_bf16 v[12:15], v[128:131], v[210:213], v[12:15]
	v_mfma_f32_16x16x32_bf16 v[8:11], v[136:139], v[210:213], v[8:11]
	v_mfma_f32_16x16x32_bf16 v[60:63], v[132:135], v[180:183], v[60:63]
	v_mfma_f32_16x16x32_bf16 v[56:59], v[140:143], v[180:183], v[56:59]
	v_mfma_f32_16x16x32_bf16 v[44:47], v[132:135], v[196:199], v[44:47]
	v_mfma_f32_16x16x32_bf16 v[40:43], v[140:143], v[196:199], v[40:43]
	v_mfma_f32_16x16x32_bf16 v[28:31], v[132:135], v[206:209], v[28:31]
	v_mfma_f32_16x16x32_bf16 v[24:27], v[140:143], v[206:209], v[24:27]
	v_mfma_f32_16x16x32_bf16 v[12:15], v[132:135], v[214:217], v[12:15]
	v_mfma_f32_16x16x32_bf16 v[8:11], v[140:143], v[214:217], v[8:11]
	s_setprio 0
	s_setprio 1
	v_mfma_f32_16x16x32_bf16 v[52:55], v[144:147], v[176:179], v[52:55]
	v_mfma_f32_16x16x32_bf16 v[48:51], v[168:171], v[176:179], v[48:51]
	v_mfma_f32_16x16x32_bf16 v[36:39], v[144:147], v[192:195], v[36:39]
	v_mfma_f32_16x16x32_bf16 v[32:35], v[168:171], v[192:195], v[32:35]
	v_mfma_f32_16x16x32_bf16 v[20:23], v[144:147], v[202:205], v[20:23]
	v_mfma_f32_16x16x32_bf16 v[16:19], v[168:171], v[202:205], v[16:19]
	v_mfma_f32_16x16x32_bf16 v[4:7], v[144:147], v[210:213], v[4:7]
	v_mfma_f32_16x16x32_bf16 v[0:3], v[168:171], v[210:213], v[0:3]
	v_mfma_f32_16x16x32_bf16 v[52:55], v[148:151], v[180:183], v[52:55]
	v_mfma_f32_16x16x32_bf16 v[48:51], v[172:175], v[180:183], v[48:51]
	v_mfma_f32_16x16x32_bf16 v[36:39], v[148:151], v[196:199], v[36:39]
	v_mfma_f32_16x16x32_bf16 v[32:35], v[172:175], v[196:199], v[32:35]
	v_mfma_f32_16x16x32_bf16 v[20:23], v[148:151], v[206:209], v[20:23]
	v_mfma_f32_16x16x32_bf16 v[16:19], v[172:175], v[206:209], v[16:19]
	v_mfma_f32_16x16x32_bf16 v[4:7], v[148:151], v[214:217], v[4:7]
	v_mfma_f32_16x16x32_bf16 v[0:3], v[172:175], v[214:217], v[0:3]
	s_setprio 0
	s_barrier
	s_add_i32 s65, 0, 0x18000
	s_add_i32 s66, 0, 0x1c000
	v_add_u32_e32 v140, s65, v187
	v_add_u32_e32 v172, s66, v187
	ds_read_b128 v[128:131], v140
	ds_read_b128 v[132:135], v140 offset:1024
	ds_read_b128 v[136:139], v140 offset:2048
	ds_read_b128 v[140:143], v140 offset:3072
	ds_read_b128 v[144:147], v172
	ds_read_b128 v[148:151], v172 offset:1024
	ds_read_b128 v[168:171], v172 offset:2048
	ds_read_b128 v[172:175], v172 offset:3072
	s_add_u32 s38, s46, 0xb0000
	s_addc_u32 s39, s47, 0
	s_mov_b32 m0, s48
	v_lshl_add_u64 v[224:225], s[38:39], 0, v[152:153]
	ds_read_b128 v[176:179], v191 offset:32768
	ds_read_b128 v[180:183], v191 offset:33792
	ds_read_b128 v[192:195], v191 offset:34816
	ds_read_b128 v[196:199], v191 offset:35840
	ds_read_b128 v[202:205], v191 offset:36864
	ds_read_b128 v[206:209], v191 offset:37888
	ds_read_b128 v[210:213], v191 offset:38912
	ds_read_b128 v[214:217], v191 offset:39936
	global_load_lds_dwordx4 v[224:225], off
	v_lshl_add_u64 v[224:225], s[38:39], 0, v[156:157]
	s_mov_b32 m0, s49
	s_nop 0
	global_load_lds_dwordx4 v[224:225], off
	s_waitcnt vmcnt(8)
	s_waitcnt lgkmcnt(0)
	s_barrier
	s_setprio 1
	s_waitcnt lgkmcnt(0)
	v_mfma_f32_16x16x32_bf16 v[124:127], v[128:131], v[176:179], v[124:127]
	v_mfma_f32_16x16x32_bf16 v[120:123], v[136:139], v[176:179], v[120:123]
	v_mfma_f32_16x16x32_bf16 v[108:111], v[128:131], v[192:195], v[108:111]
	v_mfma_f32_16x16x32_bf16 v[104:107], v[136:139], v[192:195], v[104:107]
	v_mfma_f32_16x16x32_bf16 v[92:95], v[128:131], v[202:205], v[92:95]
	v_mfma_f32_16x16x32_bf16 v[88:91], v[136:139], v[202:205], v[88:91]
	v_mfma_f32_16x16x32_bf16 v[76:79], v[128:131], v[210:213], v[76:79]
	v_mfma_f32_16x16x32_bf16 v[72:75], v[136:139], v[210:213], v[72:75]
	v_mfma_f32_16x16x32_bf16 v[124:127], v[132:135], v[180:183], v[124:127]
	v_mfma_f32_16x16x32_bf16 v[120:123], v[140:143], v[180:183], v[120:123]
	v_mfma_f32_16x16x32_bf16 v[108:111], v[132:135], v[196:199], v[108:111]
	v_mfma_f32_16x16x32_bf16 v[104:107], v[140:143], v[196:199], v[104:107]
	v_mfma_f32_16x16x32_bf16 v[92:95], v[132:135], v[206:209], v[92:95]
	v_mfma_f32_16x16x32_bf16 v[88:91], v[140:143], v[206:209], v[88:91]
	v_mfma_f32_16x16x32_bf16 v[76:79], v[132:135], v[214:217], v[76:79]
	v_mfma_f32_16x16x32_bf16 v[72:75], v[140:143], v[214:217], v[72:75]
	s_setprio 0
	s_setprio 1
	v_mfma_f32_16x16x32_bf16 v[116:119], v[144:147], v[176:179], v[116:119]
	v_mfma_f32_16x16x32_bf16 v[112:115], v[168:171], v[176:179], v[112:115]
	v_mfma_f32_16x16x32_bf16 v[100:103], v[144:147], v[192:195], v[100:103]
	v_mfma_f32_16x16x32_bf16 v[96:99], v[168:171], v[192:195], v[96:99]
	v_mfma_f32_16x16x32_bf16 v[84:87], v[144:147], v[202:205], v[84:87]
	v_mfma_f32_16x16x32_bf16 v[80:83], v[168:171], v[202:205], v[80:83]
	v_mfma_f32_16x16x32_bf16 v[68:71], v[144:147], v[210:213], v[68:71]
	v_mfma_f32_16x16x32_bf16 v[64:67], v[168:171], v[210:213], v[64:67]
	v_mfma_f32_16x16x32_bf16 v[116:119], v[148:151], v[180:183], v[116:119]
	v_mfma_f32_16x16x32_bf16 v[112:115], v[172:175], v[180:183], v[112:115]
	v_mfma_f32_16x16x32_bf16 v[100:103], v[148:151], v[196:199], v[100:103]
	v_mfma_f32_16x16x32_bf16 v[96:99], v[172:175], v[196:199], v[96:99]
	v_mfma_f32_16x16x32_bf16 v[84:87], v[148:151], v[206:209], v[84:87]
	v_mfma_f32_16x16x32_bf16 v[80:83], v[172:175], v[206:209], v[80:83]
	v_mfma_f32_16x16x32_bf16 v[68:71], v[148:151], v[214:217], v[68:71]
	v_mfma_f32_16x16x32_bf16 v[64:67], v[172:175], v[214:217], v[64:67]
	s_setprio 0
	s_barrier
; #define PG8_STAGE(bufoff, gbase, voff) do { _Pragma("unroll") for (int _i = 0; _i < 2; ++_i) \
;         __builtin_amdgcn_global_load_lds((const unsigned*)((const char*)(gbase) + (voff)[_i]), (PG8_LAS unsigned*)(lds + (bufoff) + ldsw + _i * 8192), 16, 0, 0); } while (0)
; #define PG8_LDA(dst, b, h) do { _Pragma("unroll") for (int m = 0; m < 4; ++m) _Pragma("unroll") for (int k = 0; k < 2; ++k) dst[m][k] = *(const PG8_LAS bf16x8*)(lds + PG8_SA(b, h) + aoff + m * 2048 + k * 1024); } while (0)
; #define PG8_MMA(ai, bj, At, Bt) do { __builtin_amdgcn_s_setprio(1); _Pragma("unroll") for (int m = 0; m < 4; ++m) _Pragma("unroll") for (int n = 0; n < 2; ++n) _Pragma("unroll") for (int k = 0; k < 2; ++k) \
;         acc[ai][bj][m][n] = __builtin_amdgcn_mfma_f32_16x16x32_bf16(Bt[n][k], At[m][k], acc[ai][bj][m][n], 0, 0, 0); __builtin_amdgcn_s_setprio(0); } while (0)
; #define PG8_WAIT_V(n) asm volatile("s_waitcnt vmcnt(" #n ")" ::: "memory")
; #define PG8_WAIT_L(n) asm volatile("s_waitcnt lgkmcnt(" #n ")" ::: "memory")
; #define PG8_BAR __builtin_amdgcn_s_barrier()
; #define PG8_SCHED __builtin_amdgcn_sched_barrier(0)
; template <class Epi, class Sched, bool ALIGN_EPI = false, bool SP2 = false>
; __device__ __forceinline__ void gemm_phase(PG8_LAS unsigned char* lds, const Gemm g, const Sched& S, const Epi& E, int tid_in) {
;     ...
;             PG8_LDA(At, 1, 1); PG8_STAGE(PG8_SB(1, 0), b3, voffB); PG8_STAGE(PG8_SB(1, 1), b3 + hstep, voffB); PG8_STAGE(PG8_SA(1, 0), a3, voffA);
;             PG8_WAIT_V(8); PG8_WAIT_L(0); PG8_BAR; PG8_MMA(1, 0, At, B0); PG8_MMA(1, 1, At, B1); PG8_BAR; PG8_SCHED;
	s_add_i32 s38, s65, s30
	v_lshl_add_u64 v[184:185], v[184:185], 0, s[26:27]
	s_mov_b32 m0, s38
	ds_read_b128 v[176:179], v191 offset:49152
	ds_read_b128 v[180:183], v191 offset:50176
	ds_read_b128 v[192:195], v191 offset:51200
	ds_read_b128 v[196:199], v191 offset:52224
	ds_read_b128 v[202:205], v191 offset:53248
	ds_read_b128 v[206:209], v191 offset:54272
	ds_read_b128 v[210:213], v191 offset:55296
	ds_read_b128 v[214:217], v191 offset:56320
	global_load_lds_dwordx4 v[184:185], off
	s_add_i32 m0, s38, 0x2000
	s_add_u32 s38, s44, 0xb0080
	v_lshl_add_u64 v[184:185], v[218:219], 0, s[26:27]
	s_addc_u32 s39, s45, 0
	s_add_i32 s44, s66, s30
	global_load_lds_dwordx4 v[184:185], off
	v_lshl_add_u64 v[184:185], s[38:39], 0, v[154:155]
	s_mov_b32 m0, s44
	s_nop 0
	global_load_lds_dwordx4 v[184:185], off
	v_lshl_add_u64 v[184:185], s[38:39], 0, v[158:159]
	s_add_i32 m0, s44, 0x2000
	s_nop 0
	global_load_lds_dwordx4 v[184:185], off
	v_lshl_add_u64 v[184:185], v[220:221], 0, s[26:27]
	s_mov_b32 m0, s51
	s_nop 0
	global_load_lds_dwordx4 v[184:185], off
	v_lshl_add_u64 v[184:185], v[222:223], 0, s[26:27]
	s_mov_b32 m0, s52
	s_nop 0
	global_load_lds_dwordx4 v[184:185], off
	s_waitcnt vmcnt(8)
	s_waitcnt lgkmcnt(0)
	s_barrier
	s_setprio 1
	s_waitcnt lgkmcnt(0)
	v_mfma_f32_16x16x32_bf16 v[60:63], v[128:131], v[176:179], v[60:63]
	v_mfma_f32_16x16x32_bf16 v[56:59], v[136:139], v[176:179], v[56:59]
	v_mfma_f32_16x16x32_bf16 v[44:47], v[128:131], v[192:195], v[44:47]
	v_mfma_f32_16x16x32_bf16 v[40:43], v[136:139], v[192:195], v[40:43]
	v_mfma_f32_16x16x32_bf16 v[28:31], v[128:131], v[202:205], v[28:31]
	v_mfma_f32_16x16x32_bf16 v[24:27], v[136:139], v[202:205], v[24:27]
	v_mfma_f32_16x16x32_bf16 v[12:15], v[128:131], v[210:213], v[12:15]
	v_mfma_f32_16x16x32_bf16 v[8:11], v[136:139], v[210:213], v[8:11]
	v_mfma_f32_16x16x32_bf16 v[60:63], v[132:135], v[180:183], v[60:63]
	v_mfma_f32_16x16x32_bf16 v[56:59], v[140:143], v[180:183], v[56:59]
	v_mfma_f32_16x16x32_bf16 v[44:47], v[132:135], v[196:199], v[44:47]
	v_mfma_f32_16x16x32_bf16 v[40:43], v[140:143], v[196:199], v[40:43]
	v_mfma_f32_16x16x32_bf16 v[28:31], v[132:135], v[206:209], v[28:31]
	v_mfma_f32_16x16x32_bf16 v[24:27], v[140:143], v[206:209], v[24:27]
	v_mfma_f32_16x16x32_bf16 v[12:15], v[132:135], v[214:217], v[12:15]
	v_mfma_f32_16x16x32_bf16 v[8:11], v[140:143], v[214:217], v[8:11]
	s_setprio 0
	s_setprio 1
	v_mfma_f32_16x16x32_bf16 v[52:55], v[144:147], v[176:179], v[52:55]
	v_mfma_f32_16x16x32_bf16 v[48:51], v[168:171], v[176:179], v[48:51]
	v_mfma_f32_16x16x32_bf16 v[36:39], v[144:147], v[192:195], v[36:39]
	v_mfma_f32_16x16x32_bf16 v[32:35], v[168:171], v[192:195], v[32:35]
	v_mfma_f32_16x16x32_bf16 v[20:23], v[144:147], v[202:205], v[20:23]
	v_mfma_f32_16x16x32_bf16 v[16:19], v[168:171], v[202:205], v[16:19]
	v_mfma_f32_16x16x32_bf16 v[4:7], v[144:147], v[210:213], v[4:7]
	v_mfma_f32_16x16x32_bf16 v[0:3], v[168:171], v[210:213], v[0:3]
	v_mfma_f32_16x16x32_bf16 v[52:55], v[148:151], v[180:183], v[52:55]
	v_mfma_f32_16x16x32_bf16 v[48:51], v[172:175], v[180:183], v[48:51]
	v_mfma_f32_16x16x32_bf16 v[36:39], v[148:151], v[196:199], v[36:39]
	v_mfma_f32_16x16x32_bf16 v[32:35], v[172:175], v[196:199], v[32:35]
	v_mfma_f32_16x16x32_bf16 v[20:23], v[148:151], v[206:209], v[20:23]
	v_mfma_f32_16x16x32_bf16 v[16:19], v[172:175], v[206:209], v[16:19]
	v_mfma_f32_16x16x32_bf16 v[4:7], v[148:151], v[214:217], v[4:7]
	v_mfma_f32_16x16x32_bf16 v[0:3], v[172:175], v[214:217], v[0:3]
	s_setprio 0
	s_barrier
	s_add_i32 s64, s64, 2
	s_add_u32 s62, s62, 0x100
	s_addc_u32 s63, s63, 0
	s_cmp_gt_u32 s64, 41
	s_mov_b64 s[38:39], s[40:41]
	s_cbranch_scc0 .LBB0_602
.Lpost4:
	s_and_b64 vcc, exec, s[34:35]
	s_cbranch_vccz .LBB0_605
	s_barrier

; #define PG8_STAGE(bufoff, gbase, voff) do { _Pragma("unroll") for (int _i = 0; _i < 2; ++_i) \
;         __builtin_amdgcn_global_load_lds((const unsigned*)((const char*)(gbase) + (voff)[_i]), (PG8_LAS unsigned*)(lds + (bufoff) + ldsw + _i * 8192), 16, 0, 0); } while (0)
; #define PG8_LDA(dst, b, h) do { _Pragma("unroll") for (int m = 0; m < 4; ++m) _Pragma("unroll") for (int k = 0; k < 2; ++k) dst[m][k] = *(const PG8_LAS bf16x8*)(lds + PG8_SA(b, h) + aoff + m * 2048 + k * 1024); } while (0)
; #define PG8_LDB(dst, b, h) do { _Pragma("unroll") for (int n = 0; n < 2; ++n) _Pragma("unroll") for (int k = 0; k < 2; ++k) dst[n][k] = *(const PG8_LAS bf16x8*)(lds + PG8_SB(b, h) + boff + n * 2048 + k * 1024); } while (0)
; #define PG8_MMA(ai, bj, At, Bt) do { __builtin_amdgcn_s_setprio(1); _Pragma("unroll") for (int m = 0; m < 4; ++m) _Pragma("unroll") for (int n = 0; n < 2; ++n) _Pragma("unroll") for (int k = 0; k < 2; ++k) \
;         acc[ai][bj][m][n] = __builtin_amdgcn_mfma_f32_16x16x32_bf16(Bt[n][k], At[m][k], acc[ai][bj][m][n], 0, 0, 0); __builtin_amdgcn_s_setprio(0); } while (0)
; #define PG8_WAIT_V(n) asm volatile("s_waitcnt vmcnt(" #n ")" ::: "memory")
; #define PG8_WAIT_L(n) asm volatile("s_waitcnt lgkmcnt(" #n ")" ::: "memory")
; #define PG8_BAR __builtin_amdgcn_s_barrier()
; #define PG8_SCHED __builtin_amdgcn_sched_barrier(0)
; template <class Epi, class Sched, bool ALIGN_EPI = false, bool SP2 = false>
; __device__ __forceinline__ void gemm_phase(PG8_LAS unsigned char* lds, const Gemm g, const Sched& S, const Epi& E, int tid_in) {
;     ...
;             if (last && has_next) S.a_ready(nxt);
;             if constexpr (SP2) {
;             PG8_LDB(B0, 0, 0); PG8_LDB(B1, 0, 1); PG8_SCHED; PG8_LDA(At, 0, 0); PG8_STAGE(PG8_SA(1, 1), a1 + hstep, voffA);
;             PG8_WAIT_V(8); PG8_WAIT_L(0); PG8_BAR; PG8_MMA(0, 0, At, B0); PG8_MMA(0, 1, At, B1); PG8_BAR; PG8_SCHED;
;             PG8_LDA(At, 0, 1); PG8_STAGE(PG8_SB(0, 0), b2, voffB); PG8_STAGE(PG8_SB(0, 1), b2 + hstep, voffB); PG8_STAGE(PG8_SA(0, 0), a2, voffA);
.Lpk4:
	s_mov_b64 s[98:99], 1
	v_lshl_add_u64 v[184:185], s[38:39], 0, v[162:163]
	s_add_i32 m0, s31, 0xc000
	ds_read_b128 v[176:179], v191
	ds_read_b128 v[180:183], v191 offset:1024
	ds_read_b128 v[192:195], v191 offset:2048
	ds_read_b128 v[196:199], v191 offset:3072
	ds_read_b128 v[202:205], v191 offset:4096
	ds_read_b128 v[206:209], v191 offset:5120
	ds_read_b128 v[210:213], v191 offset:6144
	ds_read_b128 v[214:217], v191 offset:7168
	global_load_lds_dwordx4 v[184:185], off
	v_lshl_add_u64 v[184:185], s[38:39], 0, v[160:161]
	s_add_i32 m0, s31, 0xe000
	s_nop 0
	global_load_lds_dwordx4 v[184:185], off
	s_waitcnt vmcnt(8)
	s_waitcnt lgkmcnt(0)
	s_barrier
	s_setprio 1
	s_waitcnt lgkmcnt(0)
	v_mfma_f32_16x16x32_bf16 v[124:127], v[128:131], v[176:179], v[124:127]
	v_mfma_f32_16x16x32_bf16 v[120:123], v[136:139], v[176:179], v[120:123]
	v_mfma_f32_16x16x32_bf16 v[108:111], v[128:131], v[192:195], v[108:111]
	v_mfma_f32_16x16x32_bf16 v[104:107], v[136:139], v[192:195], v[104:107]
	v_mfma_f32_16x16x32_bf16 v[92:95], v[128:131], v[202:205], v[92:95]
	v_mfma_f32_16x16x32_bf16 v[88:91], v[136:139], v[202:205], v[88:91]
	v_mfma_f32_16x16x32_bf16 v[76:79], v[128:131], v[210:213], v[76:79]
	v_mfma_f32_16x16x32_bf16 v[72:75], v[136:139], v[210:213], v[72:75]
	v_mfma_f32_16x16x32_bf16 v[124:127], v[132:135], v[180:183], v[124:127]
	v_mfma_f32_16x16x32_bf16 v[120:123], v[140:143], v[180:183], v[120:123]
	v_mfma_f32_16x16x32_bf16 v[108:111], v[132:135], v[196:199], v[108:111]
	v_mfma_f32_16x16x32_bf16 v[104:107], v[140:143], v[196:199], v[104:107]
	v_mfma_f32_16x16x32_bf16 v[92:95], v[132:135], v[206:209], v[92:95]
	v_mfma_f32_16x16x32_bf16 v[88:91], v[140:143], v[206:209], v[88:91]
	v_mfma_f32_16x16x32_bf16 v[76:79], v[132:135], v[214:217], v[76:79]
	v_mfma_f32_16x16x32_bf16 v[72:75], v[140:143], v[214:217], v[72:75]
	s_setprio 0
	s_setprio 1
	v_mfma_f32_16x16x32_bf16 v[116:119], v[144:147], v[176:179], v[116:119]
	v_mfma_f32_16x16x32_bf16 v[112:115], v[168:171], v[176:179], v[112:115]
	v_mfma_f32_16x16x32_bf16 v[100:103], v[144:147], v[192:195], v[100:103]
	v_mfma_f32_16x16x32_bf16 v[96:99], v[168:171], v[192:195], v[96:99]
	v_mfma_f32_16x16x32_bf16 v[84:87], v[144:147], v[202:205], v[84:87]
	v_mfma_f32_16x16x32_bf16 v[80:83], v[168:171], v[202:205], v[80:83]
	v_mfma_f32_16x16x32_bf16 v[68:71], v[144:147], v[210:213], v[68:71]
	v_mfma_f32_16x16x32_bf16 v[64:67], v[168:171], v[210:213], v[64:67]
	v_mfma_f32_16x16x32_bf16 v[116:119], v[148:151], v[180:183], v[116:119]
	v_mfma_f32_16x16x32_bf16 v[112:115], v[172:175], v[180:183], v[112:115]
	v_mfma_f32_16x16x32_bf16 v[100:103], v[148:151], v[196:199], v[100:103]
	v_mfma_f32_16x16x32_bf16 v[96:99], v[172:175], v[196:199], v[96:99]
	v_mfma_f32_16x16x32_bf16 v[84:87], v[148:151], v[206:209], v[84:87]
	v_mfma_f32_16x16x32_bf16 v[80:83], v[172:175], v[206:209], v[80:83]
	v_mfma_f32_16x16x32_bf16 v[68:71], v[148:151], v[214:217], v[68:71]
	v_mfma_f32_16x16x32_bf16 v[64:67], v[172:175], v[214:217], v[64:67]
	s_setprio 0
	s_barrier
	s_add_i32 s38, s56, s30
	v_lshl_add_u64 v[184:185], s[44:45], 0, v[154:155]
	s_mov_b32 m0, s38
	ds_read_b128 v[176:179], v191 offset:16384
	ds_read_b128 v[180:183], v191 offset:17408
	ds_read_b128 v[192:195], v191 offset:18432
	ds_read_b128 v[196:199], v191 offset:19456
	ds_read_b128 v[202:205], v191 offset:20480
	ds_read_b128 v[206:209], v191 offset:21504
	ds_read_b128 v[210:213], v191 offset:22528
	ds_read_b128 v[214:217], v191 offset:23552
	s_mov_b64 exec, s[98:99]
	global_load_lds_dwordx4 v[184:185], off
	s_mov_b64 exec, -1
	s_add_i32 m0, s38, 0x2000
	s_add_u32 s38, s44, 0xb0000
	v_lshl_add_u64 v[218:219], s[44:45], 0, v[158:159]
	s_addc_u32 s39, s45, 0
	s_add_i32 s65, s57, s30
	s_mov_b64 exec, s[98:99]
	global_load_lds_dwordx4 v[218:219], off
	s_mov_b64 exec, -1
	v_lshl_add_u64 v[220:221], s[38:39], 0, v[154:155]
	s_mov_b32 m0, s65
	v_lshl_add_u64 v[222:223], s[46:47], 0, v[156:157]
	s_mov_b64 exec, s[98:99]
	global_load_lds_dwordx4 v[220:221], off
	s_mov_b64 exec, -1
	v_lshl_add_u64 v[220:221], s[38:39], 0, v[158:159]
	s_add_i32 m0, s65, 0x2000
	s_nop 0
	s_mov_b64 exec, s[98:99]
	global_load_lds_dwordx4 v[220:221], off
	s_mov_b64 exec, -1
	v_lshl_add_u64 v[220:221], s[46:47], 0, v[152:153]
	s_mov_b32 m0, s31
	s_nop 0
	s_mov_b64 exec, s[98:99]
	global_load_lds_dwordx4 v[220:221], off
	s_mov_b64 exec, -1
	s_mov_b32 m0, s33
	s_nop 0
	s_mov_b64 exec, s[98:99]
	global_load_lds_dwordx4 v[222:223], off
	s_mov_b64 exec, -1
	s_waitcnt vmcnt(8)
	s_waitcnt lgkmcnt(0)
	s_barrier
; #define PG8_STAGE(bufoff, gbase, voff) do { _Pragma("unroll") for (int _i = 0; _i < 2; ++_i) \
;         __builtin_amdgcn_global_load_lds((const unsigned*)((const char*)(gbase) + (voff)[_i]), (PG8_LAS unsigned*)(lds + (bufoff) + ldsw + _i * 8192), 16, 0, 0); } while (0)
; #define PG8_LDA(dst, b, h) do { _Pragma("unroll") for (int m = 0; m < 4; ++m) _Pragma("unroll") for (int k = 0; k < 2; ++k) dst[m][k] = *(const PG8_LAS bf16x8*)(lds + PG8_SA(b, h) + aoff + m * 2048 + k * 1024); } while (0)
; #define PG8_LDB(dst, b, h) do { _Pragma("unroll") for (int n = 0; n < 2; ++n) _Pragma("unroll") for (int k = 0; k < 2; ++k) dst[n][k] = *(const PG8_LAS bf16x8*)(lds + PG8_SB(b, h) + boff + n * 2048 + k * 1024); } while (0)
; #define PG8_MMA(ai, bj, At, Bt) do { __builtin_amdgcn_s_setprio(1); _Pragma("unroll") for (int m = 0; m < 4; ++m) _Pragma("unroll") for (int n = 0; n < 2; ++n) _Pragma("unroll") for (int k = 0; k < 2; ++k) \
;         acc[ai][bj][m][n] = __builtin_amdgcn_mfma_f32_16x16x32_bf16(Bt[n][k], At[m][k], acc[ai][bj][m][n], 0, 0, 0); __builtin_amdgcn_s_setprio(0); } while (0)
; #define PG8_WAIT_V(n) asm volatile("s_waitcnt vmcnt(" #n ")" ::: "memory")
; #define PG8_WAIT_L(n) asm volatile("s_waitcnt lgkmcnt(" #n ")" ::: "memory")
; #define PG8_BAR __builtin_amdgcn_s_barrier()
; #define PG8_SCHED __builtin_amdgcn_sched_barrier(0)
; template <class Epi, class Sched, bool ALIGN_EPI = false, bool SP2 = false>
; __device__ __forceinline__ void gemm_phase(PG8_LAS unsigned char* lds, const Gemm g, const Sched& S, const Epi& E, int tid_in) {
;     ...
;             PG8_WAIT_V(8); PG8_WAIT_L(0); PG8_BAR; PG8_MMA(1, 0, At, B0); PG8_MMA(1, 1, At, B1); PG8_BAR; PG8_SCHED;
;             PG8_LDB(B0, 1, 0); PG8_LDB(B1, 1, 1); PG8_SCHED; PG8_LDA(At, 1, 0); PG8_STAGE(PG8_SA(0, 1), a2 + hstep, voffA);
;             PG8_WAIT_V(8); PG8_WAIT_L(0); PG8_BAR; PG8_MMA(0, 0, At, B0); PG8_MMA(0, 1, At, B1); PG8_BAR; PG8_SCHED;
	s_setprio 1
	s_waitcnt lgkmcnt(0)
	v_mfma_f32_16x16x32_bf16 v[60:63], v[128:131], v[176:179], v[60:63]
	v_mfma_f32_16x16x32_bf16 v[56:59], v[136:139], v[176:179], v[56:59]
	v_mfma_f32_16x16x32_bf16 v[44:47], v[128:131], v[192:195], v[44:47]
	v_mfma_f32_16x16x32_bf16 v[40:43], v[136:139], v[192:195], v[40:43]
	v_mfma_f32_16x16x32_bf16 v[28:31], v[128:131], v[202:205], v[28:31]
	v_mfma_f32_16x16x32_bf16 v[24:27], v[136:139], v[202:205], v[24:27]
	v_mfma_f32_16x16x32_bf16 v[12:15], v[128:131], v[210:213], v[12:15]
	v_mfma_f32_16x16x32_bf16 v[8:11], v[136:139], v[210:213], v[8:11]
	v_mfma_f32_16x16x32_bf16 v[60:63], v[132:135], v[180:183], v[60:63]
	v_mfma_f32_16x16x32_bf16 v[56:59], v[140:143], v[180:183], v[56:59]
	v_mfma_f32_16x16x32_bf16 v[44:47], v[132:135], v[196:199], v[44:47]
	v_mfma_f32_16x16x32_bf16 v[40:43], v[140:143], v[196:199], v[40:43]
	v_mfma_f32_16x16x32_bf16 v[28:31], v[132:135], v[206:209], v[28:31]
	v_mfma_f32_16x16x32_bf16 v[24:27], v[140:143], v[206:209], v[24:27]
	v_mfma_f32_16x16x32_bf16 v[12:15], v[132:135], v[214:217], v[12:15]
	v_mfma_f32_16x16x32_bf16 v[8:11], v[140:143], v[214:217], v[8:11]
	s_setprio 0
	s_setprio 1
	v_mfma_f32_16x16x32_bf16 v[52:55], v[144:147], v[176:179], v[52:55]
	v_mfma_f32_16x16x32_bf16 v[48:51], v[168:171], v[176:179], v[48:51]
	v_mfma_f32_16x16x32_bf16 v[36:39], v[144:147], v[192:195], v[36:39]
	v_mfma_f32_16x16x32_bf16 v[32:35], v[168:171], v[192:195], v[32:35]
	v_mfma_f32_16x16x32_bf16 v[20:23], v[144:147], v[202:205], v[20:23]
	v_mfma_f32_16x16x32_bf16 v[16:19], v[168:171], v[202:205], v[16:19]
	v_mfma_f32_16x16x32_bf16 v[4:7], v[144:147], v[210:213], v[4:7]
	v_mfma_f32_16x16x32_bf16 v[0:3], v[168:171], v[210:213], v[0:3]
	v_mfma_f32_16x16x32_bf16 v[52:55], v[148:151], v[180:183], v[52:55]
	v_mfma_f32_16x16x32_bf16 v[48:51], v[172:175], v[180:183], v[48:51]
	v_mfma_f32_16x16x32_bf16 v[36:39], v[148:151], v[196:199], v[36:39]
	v_mfma_f32_16x16x32_bf16 v[32:35], v[172:175], v[196:199], v[32:35]
	v_mfma_f32_16x16x32_bf16 v[20:23], v[148:151], v[206:209], v[20:23]
	v_mfma_f32_16x16x32_bf16 v[16:19], v[172:175], v[206:209], v[16:19]
	v_mfma_f32_16x16x32_bf16 v[4:7], v[148:151], v[214:217], v[4:7]
	v_mfma_f32_16x16x32_bf16 v[0:3], v[172:175], v[214:217], v[0:3]
	s_setprio 0
	s_barrier
	s_add_i32 s65, 0, 0x18000
	s_add_i32 s66, 0, 0x1c000
	v_add_u32_e32 v140, s65, v187
	v_add_u32_e32 v172, s66, v187
	ds_read_b128 v[128:131], v140
	ds_read_b128 v[132:135], v140 offset:1024
	ds_read_b128 v[136:139], v140 offset:2048
	ds_read_b128 v[140:143], v140 offset:3072
	ds_read_b128 v[144:147], v172
	ds_read_b128 v[148:151], v172 offset:1024
	ds_read_b128 v[168:171], v172 offset:2048
	ds_read_b128 v[172:175], v172 offset:3072
	s_add_u32 s38, s46, 0xb0000
	s_addc_u32 s39, s47, 0
	s_mov_b32 m0, s48
	v_lshl_add_u64 v[224:225], s[38:39], 0, v[152:153]
	ds_read_b128 v[176:179], v191 offset:32768
	ds_read_b128 v[180:183], v191 offset:33792
	ds_read_b128 v[192:195], v191 offset:34816
	ds_read_b128 v[196:199], v191 offset:35840
	ds_read_b128 v[202:205], v191 offset:36864
	ds_read_b128 v[206:209], v191 offset:37888
	ds_read_b128 v[210:213], v191 offset:38912
	ds_read_b128 v[214:217], v191 offset:39936
	s_mov_b64 exec, s[98:99]
	global_load_lds_dwordx4 v[224:225], off
	s_mov_b64 exec, -1
	v_lshl_add_u64 v[224:225], s[38:39], 0, v[156:157]
	s_mov_b32 m0, s49
	s_nop 0
	s_mov_b64 exec, s[98:99]
	global_load_lds_dwordx4 v[224:225], off
	s_mov_b64 exec, -1
	s_waitcnt vmcnt(8)
	s_waitcnt lgkmcnt(0)
	s_barrier
	s_setprio 1
	s_waitcnt lgkmcnt(0)
	v_mfma_f32_16x16x32_bf16 v[124:127], v[128:131], v[176:179], v[124:127]
	v_mfma_f32_16x16x32_bf16 v[120:123], v[136:139], v[176:179], v[120:123]
	v_mfma_f32_16x16x32_bf16 v[108:111], v[128:131], v[192:195], v[108:111]
	v_mfma_f32_16x16x32_bf16 v[104:107], v[136:139], v[192:195], v[104:107]
	v_mfma_f32_16x16x32_bf16 v[92:95], v[128:131], v[202:205], v[92:95]
	v_mfma_f32_16x16x32_bf16 v[88:91], v[136:139], v[202:205], v[88:91]
	v_mfma_f32_16x16x32_bf16 v[76:79], v[128:131], v[210:213], v[76:79]
	v_mfma_f32_16x16x32_bf16 v[72:75], v[136:139], v[210:213], v[72:75]
	v_mfma_f32_16x16x32_bf16 v[124:127], v[132:135], v[180:183], v[124:127]
	v_mfma_f32_16x16x32_bf16 v[120:123], v[140:143], v[180:183], v[120:123]
	v_mfma_f32_16x16x32_bf16 v[108:111], v[132:135], v[196:199], v[108:111]
	v_mfma_f32_16x16x32_bf16 v[104:107], v[140:143], v[196:199], v[104:107]
	v_mfma_f32_16x16x32_bf16 v[92:95], v[132:135], v[206:209], v[92:95]
	v_mfma_f32_16x16x32_bf16 v[88:91], v[140:143], v[206:209], v[88:91]
	v_mfma_f32_16x16x32_bf16 v[76:79], v[132:135], v[214:217], v[76:79]
	v_mfma_f32_16x16x32_bf16 v[72:75], v[140:143], v[214:217], v[72:75]
	s_setprio 0
	s_setprio 1
	v_mfma_f32_16x16x32_bf16 v[116:119], v[144:147], v[176:179], v[116:119]
	v_mfma_f32_16x16x32_bf16 v[112:115], v[168:171], v[176:179], v[112:115]
	v_mfma_f32_16x16x32_bf16 v[100:103], v[144:147], v[192:195], v[100:103]
	v_mfma_f32_16x16x32_bf16 v[96:99], v[168:171], v[192:195], v[96:99]
	v_mfma_f32_16x16x32_bf16 v[84:87], v[144:147], v[202:205], v[84:87]
	v_mfma_f32_16x16x32_bf16 v[80:83], v[168:171], v[202:205], v[80:83]
	v_mfma_f32_16x16x32_bf16 v[68:71], v[144:147], v[210:213], v[68:71]
	v_mfma_f32_16x16x32_bf16 v[64:67], v[168:171], v[210:213], v[64:67]
	v_mfma_f32_16x16x32_bf16 v[116:119], v[148:151], v[180:183], v[116:119]
	v_mfma_f32_16x16x32_bf16 v[112:115], v[172:175], v[180:183], v[112:115]
	v_mfma_f32_16x16x32_bf16 v[100:103], v[148:151], v[196:199], v[100:103]
	v_mfma_f32_16x16x32_bf16 v[96:99], v[172:175], v[196:199], v[96:99]
	v_mfma_f32_16x16x32_bf16 v[84:87], v[148:151], v[206:209], v[84:87]
	v_mfma_f32_16x16x32_bf16 v[80:83], v[172:175], v[206:209], v[80:83]
	v_mfma_f32_16x16x32_bf16 v[68:71], v[148:151], v[214:217], v[68:71]
	v_mfma_f32_16x16x32_bf16 v[64:67], v[172:175], v[214:217], v[64:67]
	s_setprio 0
	s_barrier
; #define PG8_STAGE(bufoff, gbase, voff) do { _Pragma("unroll") for (int _i = 0; _i < 2; ++_i) \
;         __builtin_amdgcn_global_load_lds((const unsigned*)((const char*)(gbase) + (voff)[_i]), (PG8_LAS unsigned*)(lds + (bufoff) + ldsw + _i * 8192), 16, 0, 0); } while (0)
; #define PG8_LDA(dst, b, h) do { _Pragma("unroll") for (int m = 0; m < 4; ++m) _Pragma("unroll") for (int k = 0; k < 2; ++k) dst[m][k] = *(const PG8_LAS bf16x8*)(lds + PG8_SA(b, h) + aoff + m * 2048 + k * 1024); } while (0)
; #define PG8_MMA(ai, bj, At, Bt) do { __builtin_amdgcn_s_setprio(1); _Pragma("unroll") for (int m = 0; m < 4; ++m) _Pragma("unroll") for (int n = 0; n < 2; ++n) _Pragma("unroll") for (int k = 0; k < 2; ++k) \
;         acc[ai][bj][m][n] = __builtin_amdgcn_mfma_f32_16x16x32_bf16(Bt[n][k], At[m][k], acc[ai][bj][m][n], 0, 0, 0); __builtin_amdgcn_s_setprio(0); } while (0)
; #define PG8_WAIT_V(n) asm volatile("s_waitcnt vmcnt(" #n ")" ::: "memory")
; #define PG8_WAIT_L(n) asm volatile("s_waitcnt lgkmcnt(" #n ")" ::: "memory")
; #define PG8_BAR __builtin_amdgcn_s_barrier()
; #define PG8_SCHED __builtin_amdgcn_sched_barrier(0)
; template <class Epi, class Sched, bool ALIGN_EPI = false, bool SP2 = false>
; __device__ __forceinline__ void gemm_phase(PG8_LAS unsigned char* lds, const Gemm g, const Sched& S, const Epi& E, int tid_in) {
;     ...
;             PG8_LDA(At, 1, 1); PG8_STAGE(PG8_SB(1, 0), b3, voffB); PG8_STAGE(PG8_SB(1, 1), b3 + hstep, voffB); PG8_STAGE(PG8_SA(1, 0), a3, voffA);
;             PG8_WAIT_V(8); PG8_WAIT_L(0); PG8_BAR; PG8_MMA(1, 0, At, B0); PG8_MMA(1, 1, At, B1); PG8_BAR; PG8_SCHED;
	s_add_i32 s38, s65, s30
	v_lshl_add_u64 v[184:185], v[184:185], 0, s[26:27]
	s_mov_b32 m0, s38
	ds_read_b128 v[176:179], v191 offset:49152
	ds_read_b128 v[180:183], v191 offset:50176
	ds_read_b128 v[192:195], v191 offset:51200
	ds_read_b128 v[196:199], v191 offset:52224
	ds_read_b128 v[202:205], v191 offset:53248
	ds_read_b128 v[206:209], v191 offset:54272
	ds_read_b128 v[210:213], v191 offset:55296
	ds_read_b128 v[214:217], v191 offset:56320
	s_mov_b64 exec, s[98:99]
	global_load_lds_dwordx4 v[184:185], off
	s_mov_b64 exec, -1
	s_add_i32 m0, s38, 0x2000
	s_add_u32 s38, s44, 0xb0080
	v_lshl_add_u64 v[184:185], v[218:219], 0, s[26:27]
	s_addc_u32 s39, s45, 0
	s_add_i32 s44, s66, s30
	s_mov_b64 exec, s[98:99]
	global_load_lds_dwordx4 v[184:185], off
	s_mov_b64 exec, -1
	v_lshl_add_u64 v[184:185], s[38:39], 0, v[154:155]
	s_mov_b32 m0, s44
	s_nop 0
	s_mov_b64 exec, s[98:99]
	global_load_lds_dwordx4 v[184:185], off
	s_mov_b64 exec, -1
	v_lshl_add_u64 v[184:185], s[38:39], 0, v[158:159]
	s_add_i32 m0, s44, 0x2000
	s_nop 0
	s_mov_b64 exec, s[98:99]
	global_load_lds_dwordx4 v[184:185], off
	s_mov_b64 exec, -1
	v_lshl_add_u64 v[184:185], v[220:221], 0, s[26:27]
	s_mov_b32 m0, s51
	s_nop 0
	s_mov_b64 exec, s[98:99]
	global_load_lds_dwordx4 v[184:185], off
	s_mov_b64 exec, -1
	v_lshl_add_u64 v[184:185], v[222:223], 0, s[26:27]
	s_mov_b32 m0, s52
	s_nop 0
	s_mov_b64 exec, s[98:99]
	global_load_lds_dwordx4 v[184:185], off
	s_mov_b64 exec, -1
	s_waitcnt vmcnt(8)
	s_waitcnt lgkmcnt(0)
	s_barrier
	s_setprio 1
	s_waitcnt lgkmcnt(0)
	v_mfma_f32_16x16x32_bf16 v[60:63], v[128:131], v[176:179], v[60:63]
	v_mfma_f32_16x16x32_bf16 v[56:59], v[136:139], v[176:179], v[56:59]
	v_mfma_f32_16x16x32_bf16 v[44:47], v[128:131], v[192:195], v[44:47]
	v_mfma_f32_16x16x32_bf16 v[40:43], v[136:139], v[192:195], v[40:43]
	v_mfma_f32_16x16x32_bf16 v[28:31], v[128:131], v[202:205], v[28:31]
	v_mfma_f32_16x16x32_bf16 v[24:27], v[136:139], v[202:205], v[24:27]
	v_mfma_f32_16x16x32_bf16 v[12:15], v[128:131], v[210:213], v[12:15]
	v_mfma_f32_16x16x32_bf16 v[8:11], v[136:139], v[210:213], v[8:11]
	v_mfma_f32_16x16x32_bf16 v[60:63], v[132:135], v[180:183], v[60:63]
	v_mfma_f32_16x16x32_bf16 v[56:59], v[140:143], v[180:183], v[56:59]
	v_mfma_f32_16x16x32_bf16 v[44:47], v[132:135], v[196:199], v[44:47]
	v_mfma_f32_16x16x32_bf16 v[40:43], v[140:143], v[196:199], v[40:43]
	v_mfma_f32_16x16x32_bf16 v[28:31], v[132:135], v[206:209], v[28:31]
	v_mfma_f32_16x16x32_bf16 v[24:27], v[140:143], v[206:209], v[24:27]
	v_mfma_f32_16x16x32_bf16 v[12:15], v[132:135], v[214:217], v[12:15]
	v_mfma_f32_16x16x32_bf16 v[8:11], v[140:143], v[214:217], v[8:11]
	s_setprio 0
	s_setprio 1
	v_mfma_f32_16x16x32_bf16 v[52:55], v[144:147], v[176:179], v[52:55]
	v_mfma_f32_16x16x32_bf16 v[48:51], v[168:171], v[176:179], v[48:51]
	v_mfma_f32_16x16x32_bf16 v[36:39], v[144:147], v[192:195], v[36:39]
	v_mfma_f32_16x16x32_bf16 v[32:35], v[168:171], v[192:195], v[32:35]
	v_mfma_f32_16x16x32_bf16 v[20:23], v[144:147], v[202:205], v[20:23]
	v_mfma_f32_16x16x32_bf16 v[16:19], v[168:171], v[202:205], v[16:19]
	v_mfma_f32_16x16x32_bf16 v[4:7], v[144:147], v[210:213], v[4:7]
	v_mfma_f32_16x16x32_bf16 v[0:3], v[168:171], v[210:213], v[0:3]
	v_mfma_f32_16x16x32_bf16 v[52:55], v[148:151], v[180:183], v[52:55]
	v_mfma_f32_16x16x32_bf16 v[48:51], v[172:175], v[180:183], v[48:51]
	v_mfma_f32_16x16x32_bf16 v[36:39], v[148:151], v[196:199], v[36:39]
	v_mfma_f32_16x16x32_bf16 v[32:35], v[172:175], v[196:199], v[32:35]
	v_mfma_f32_16x16x32_bf16 v[20:23], v[148:151], v[206:209], v[20:23]
	v_mfma_f32_16x16x32_bf16 v[16:19], v[172:175], v[206:209], v[16:19]
	v_mfma_f32_16x16x32_bf16 v[4:7], v[148:151], v[214:217], v[4:7]
	v_mfma_f32_16x16x32_bf16 v[0:3], v[172:175], v[214:217], v[0:3]
	s_setprio 0
	s_barrier
	s_add_i32 s64, s64, 2
	s_add_u32 s62, s62, 0x100
	s_addc_u32 s63, s63, 0
	s_cmp_gt_u32 s64, 41
	s_mov_b64 s[38:39], s[40:41]
	s_branch .Lpost4

; #define PG8_STAGE(bufoff, gbase, voff) do { _Pragma("unroll") for (int _i = 0; _i < 2; ++_i) \
;         __builtin_amdgcn_global_load_lds((const unsigned*)((const char*)(gbase) + (voff)[_i]), (PG8_LAS unsigned*)(lds + (bufoff) + ldsw + _i * 8192), 16, 0, 0); } while (0)
; #define PG8_LDA(dst, b, h) do { _Pragma("unroll") for (int m = 0; m < 4; ++m) _Pragma("unroll") for (int k = 0; k < 2; ++k) dst[m][k] = *(const PG8_LAS bf16x8*)(lds + PG8_SA(b, h) + aoff + m * 2048 + k * 1024); } while (0)
; #define PG8_LDB(dst, b, h) do { _Pragma("unroll") for (int n = 0; n < 2; ++n) _Pragma("unroll") for (int k = 0; k < 2; ++k) dst[n][k] = *(const PG8_LAS bf16x8*)(lds + PG8_SB(b, h) + boff + n * 2048 + k * 1024); } while (0)
; #define PG8_MMA(ai, bj, At, Bt) do { __builtin_amdgcn_s_setprio(1); _Pragma("unroll") for (int m = 0; m < 4; ++m) _Pragma("unroll") for (int n = 0; n < 2; ++n) _Pragma("unroll") for (int k = 0; k < 2; ++k) \
;         acc[ai][bj][m][n] = __builtin_amdgcn_mfma_f32_16x16x32_bf16(Bt[n][k], At[m][k], acc[ai][bj][m][n], 0, 0, 0); __builtin_amdgcn_s_setprio(0); } while (0)
; #define PG8_WAIT_V(n) asm volatile("s_waitcnt vmcnt(" #n ")" ::: "memory")
; #define PG8_BAR __builtin_amdgcn_s_barrier()
; template <class Epi, class Sched, bool ALIGN_EPI = false, bool SP2 = false>
; __device__ __forceinline__ void gemm_phase(PG8_LAS unsigned char* lds, const Gemm g, const Sched& S, const Epi& E, int tid_in) {
;     ...
;         for (int t = 0; t < nt; t += 2) {
;             const bool last = (t == nt - 2);
;             const char* a1 = cA + (size_t)(t + 1) * kstep;
;             const char* a2 = last ? nA : cA + (size_t)(t + 2) * kstep; const char* b2 = last ? nB : cB + (size_t)(t + 2) * kstep;
;             const char* a3 = a2 + kstep; const char* b3 = b2 + kstep;
;             if (last && has_next) S.a_ready(nxt);
;             if constexpr (SP2) {
;             PG8_LDB(B0, 0, 0); PG8_LDB(B1, 0, 1); PG8_SCHED; PG8_LDA(At, 0, 0); PG8_STAGE(PG8_SA(1, 1), a1 + hstep, voffA);
;             PG8_WAIT_V(8); PG8_WAIT_L(0); PG8_BAR; PG8_MMA(0, 0, At, B0); PG8_MMA(0, 1, At, B1); PG8_BAR; PG8_SCHED;
;             PG8_LDA(At, 0, 1); PG8_STAGE(PG8_SB(0, 0), b2, voffB); PG8_STAGE(PG8_SB(0, 1), b2 + hstep, voffB); PG8_STAGE(PG8_SA(0, 0), a2, voffA);
;             PG8_WAIT_V(8); PG8_WAIT_L(0); PG8_BAR; PG8_MMA(1, 0, At, B0); PG8_MMA(1, 1, At, B1); PG8_BAR; PG8_SCHED;
.LBB0_712:
	ds_read_b128 v[146:149], v180
	ds_read_b128 v[150:153], v180 offset:1024
	ds_read_b128 v[154:157], v180 offset:2048
	ds_read_b128 v[158:161], v180 offset:3072
	ds_read_b128 v[162:165], v181
	ds_read_b128 v[166:169], v181 offset:1024
	ds_read_b128 v[170:173], v181 offset:2048
	ds_read_b128 v[186:189], v181 offset:3072
	s_add_u32 s14, s12, 0xfffc0080
	s_addc_u32 s15, s13, -1
	s_cmp_eq_u32 s69, 12
	s_cselect_b32 s51, s37, s15
	s_cselect_b32 s50, s65, s14
	s_cselect_b32 s49, s35, s68
	s_cselect_b32 s48, s66, s67
	s_cbranch_scc1 .Lpk5
	v_lshl_add_u64 v[198:199], s[12:13], 0, v[140:141]
	s_add_i32 m0, s31, 0xc000
	ds_read_b128 v[190:193], v182
	ds_read_b128 v[194:197], v182 offset:1024
	ds_read_b128 v[202:205], v182 offset:2048
	ds_read_b128 v[206:209], v182 offset:3072
	ds_read_b128 v[210:213], v182 offset:4096
	ds_read_b128 v[214:217], v182 offset:5120
	ds_read_b128 v[218:221], v182 offset:6144
	ds_read_b128 v[222:225], v182 offset:7168
	global_load_lds_dwordx4 v[198:199], off
	v_lshl_add_u64 v[198:199], s[12:13], 0, v[138:139]
	s_add_i32 m0, s31, 0xe000
	s_nop 0
	global_load_lds_dwordx4 v[198:199], off
	s_waitcnt vmcnt(8)
	s_waitcnt lgkmcnt(0)
	s_barrier
	s_setprio 1
	s_waitcnt lgkmcnt(0)
	v_mfma_f32_16x16x32_bf16 v[124:127], v[146:149], v[190:193], v[124:127]
	v_mfma_f32_16x16x32_bf16 v[120:123], v[154:157], v[190:193], v[120:123]
	v_mfma_f32_16x16x32_bf16 v[108:111], v[146:149], v[202:205], v[108:111]
	v_mfma_f32_16x16x32_bf16 v[104:107], v[154:157], v[202:205], v[104:107]
	v_mfma_f32_16x16x32_bf16 v[92:95], v[146:149], v[210:213], v[92:95]
	v_mfma_f32_16x16x32_bf16 v[88:91], v[154:157], v[210:213], v[88:91]
	v_mfma_f32_16x16x32_bf16 v[76:79], v[146:149], v[218:221], v[76:79]
	v_mfma_f32_16x16x32_bf16 v[72:75], v[154:157], v[218:221], v[72:75]
	v_mfma_f32_16x16x32_bf16 v[124:127], v[150:153], v[194:197], v[124:127]
	v_mfma_f32_16x16x32_bf16 v[120:123], v[158:161], v[194:197], v[120:123]
	v_mfma_f32_16x16x32_bf16 v[108:111], v[150:153], v[206:209], v[108:111]
	v_mfma_f32_16x16x32_bf16 v[104:107], v[158:161], v[206:209], v[104:107]
	v_mfma_f32_16x16x32_bf16 v[92:95], v[150:153], v[214:217], v[92:95]
	v_mfma_f32_16x16x32_bf16 v[88:91], v[158:161], v[214:217], v[88:91]
	v_mfma_f32_16x16x32_bf16 v[76:79], v[150:153], v[222:225], v[76:79]
	v_mfma_f32_16x16x32_bf16 v[72:75], v[158:161], v[222:225], v[72:75]
	s_setprio 0
	s_setprio 1
	v_mfma_f32_16x16x32_bf16 v[116:119], v[162:165], v[190:193], v[116:119]
	v_mfma_f32_16x16x32_bf16 v[112:115], v[170:173], v[190:193], v[112:115]
	v_mfma_f32_16x16x32_bf16 v[100:103], v[162:165], v[202:205], v[100:103]
	v_mfma_f32_16x16x32_bf16 v[96:99], v[170:173], v[202:205], v[96:99]
	v_mfma_f32_16x16x32_bf16 v[84:87], v[162:165], v[210:213], v[84:87]
	v_mfma_f32_16x16x32_bf16 v[80:83], v[170:173], v[210:213], v[80:83]
	v_mfma_f32_16x16x32_bf16 v[68:71], v[162:165], v[218:221], v[68:71]
	v_mfma_f32_16x16x32_bf16 v[64:67], v[170:173], v[218:221], v[64:67]
	v_mfma_f32_16x16x32_bf16 v[116:119], v[166:169], v[194:197], v[116:119]
	v_mfma_f32_16x16x32_bf16 v[112:115], v[186:189], v[194:197], v[112:115]
	v_mfma_f32_16x16x32_bf16 v[100:103], v[166:169], v[206:209], v[100:103]
	v_mfma_f32_16x16x32_bf16 v[96:99], v[186:189], v[206:209], v[96:99]
	v_mfma_f32_16x16x32_bf16 v[84:87], v[166:169], v[214:217], v[84:87]
	v_mfma_f32_16x16x32_bf16 v[80:83], v[186:189], v[214:217], v[80:83]
	v_mfma_f32_16x16x32_bf16 v[68:71], v[166:169], v[222:225], v[68:71]
	v_mfma_f32_16x16x32_bf16 v[64:67], v[186:189], v[222:225], v[64:67]
	s_setprio 0
	s_barrier
	s_add_i32 s14, s62, s30
	v_lshl_add_u64 v[198:199], s[48:49], 0, v[130:131]
	s_mov_b32 m0, s14
	ds_read_b128 v[190:193], v182 offset:16384
	ds_read_b128 v[194:197], v182 offset:17408
	ds_read_b128 v[202:205], v182 offset:18432
	ds_read_b128 v[206:209], v182 offset:19456
	ds_read_b128 v[210:213], v182 offset:20480
	ds_read_b128 v[214:217], v182 offset:21504
	ds_read_b128 v[218:221], v182 offset:22528
	ds_read_b128 v[222:225], v182 offset:23552
	global_load_lds_dwordx4 v[198:199], off
	s_add_i32 m0, s14, 0x2000
	s_add_u32 s70, s48, 0x40000
	v_lshl_add_u64 v[226:227], s[48:49], 0, v[134:135]
	s_addc_u32 s71, s49, 0
	s_add_i32 s14, s63, s30
	global_load_lds_dwordx4 v[226:227], off
	v_lshl_add_u64 v[228:229], s[70:71], 0, v[130:131]
	s_mov_b32 m0, s14
	v_lshl_add_u64 v[230:231], s[50:51], 0, v[132:133]
	global_load_lds_dwordx4 v[228:229], off
	v_lshl_add_u64 v[228:229], s[70:71], 0, v[134:135]
	s_add_i32 m0, s14, 0x2000
	s_nop 0
	global_load_lds_dwordx4 v[228:229], off
	v_lshl_add_u64 v[228:229], s[50:51], 0, v[128:129]
	s_mov_b32 m0, s31
	s_nop 0
	global_load_lds_dwordx4 v[228:229], off
	s_mov_b32 m0, s33
	s_nop 0
	global_load_lds_dwordx4 v[230:231], off
	s_waitcnt vmcnt(8)
	s_waitcnt lgkmcnt(0)
	s_barrier
; #define PG8_STAGE(bufoff, gbase, voff) do { _Pragma("unroll") for (int _i = 0; _i < 2; ++_i) \
;         __builtin_amdgcn_global_load_lds((const unsigned*)((const char*)(gbase) + (voff)[_i]), (PG8_LAS unsigned*)(lds + (bufoff) + ldsw + _i * 8192), 16, 0, 0); } while (0)
; #define PG8_LDA(dst, b, h) do { _Pragma("unroll") for (int m = 0; m < 4; ++m) _Pragma("unroll") for (int k = 0; k < 2; ++k) dst[m][k] = *(const PG8_LAS bf16x8*)(lds + PG8_SA(b, h) + aoff + m * 2048 + k * 1024); } while (0)
; #define PG8_LDB(dst, b, h) do { _Pragma("unroll") for (int n = 0; n < 2; ++n) _Pragma("unroll") for (int k = 0; k < 2; ++k) dst[n][k] = *(const PG8_LAS bf16x8*)(lds + PG8_SB(b, h) + boff + n * 2048 + k * 1024); } while (0)
; #define PG8_MMA(ai, bj, At, Bt) do { __builtin_amdgcn_s_setprio(1); _Pragma("unroll") for (int m = 0; m < 4; ++m) _Pragma("unroll") for (int n = 0; n < 2; ++n) _Pragma("unroll") for (int k = 0; k < 2; ++k) \
;         acc[ai][bj][m][n] = __builtin_amdgcn_mfma_f32_16x16x32_bf16(Bt[n][k], At[m][k], acc[ai][bj][m][n], 0, 0, 0); __builtin_amdgcn_s_setprio(0); } while (0)
; #define PG8_WAIT_V(n) asm volatile("s_waitcnt vmcnt(" #n ")" ::: "memory")
; #define PG8_WAIT_L(n) asm volatile("s_waitcnt lgkmcnt(" #n ")" ::: "memory")
; #define PG8_BAR __builtin_amdgcn_s_barrier()
; #define PG8_SCHED __builtin_amdgcn_sched_barrier(0)
; template <class Epi, class Sched, bool ALIGN_EPI = false, bool SP2 = false>
; __device__ __forceinline__ void gemm_phase(PG8_LAS unsigned char* lds, const Gemm g, const Sched& S, const Epi& E, int tid_in) {
;     ...
;             PG8_WAIT_V(8); PG8_WAIT_L(0); PG8_BAR; PG8_MMA(1, 0, At, B0); PG8_MMA(1, 1, At, B1); PG8_BAR; PG8_SCHED;
;             PG8_LDB(B0, 1, 0); PG8_LDB(B1, 1, 1); PG8_SCHED; PG8_LDA(At, 1, 0); PG8_STAGE(PG8_SA(0, 1), a2 + hstep, voffA);
;             PG8_WAIT_V(8); PG8_WAIT_L(0); PG8_BAR; PG8_MMA(0, 0, At, B0); PG8_MMA(0, 1, At, B1); PG8_BAR; PG8_SCHED;
	s_setprio 1
	s_waitcnt lgkmcnt(0)
	v_mfma_f32_16x16x32_bf16 v[60:63], v[146:149], v[190:193], v[60:63]
	v_mfma_f32_16x16x32_bf16 v[56:59], v[154:157], v[190:193], v[56:59]
	v_mfma_f32_16x16x32_bf16 v[44:47], v[146:149], v[202:205], v[44:47]
	v_mfma_f32_16x16x32_bf16 v[40:43], v[154:157], v[202:205], v[40:43]
	v_mfma_f32_16x16x32_bf16 v[28:31], v[146:149], v[210:213], v[28:31]
	v_mfma_f32_16x16x32_bf16 v[24:27], v[154:157], v[210:213], v[24:27]
	v_mfma_f32_16x16x32_bf16 v[12:15], v[146:149], v[218:221], v[12:15]
	v_mfma_f32_16x16x32_bf16 v[8:11], v[154:157], v[218:221], v[8:11]
	v_mfma_f32_16x16x32_bf16 v[60:63], v[150:153], v[194:197], v[60:63]
	v_mfma_f32_16x16x32_bf16 v[56:59], v[158:161], v[194:197], v[56:59]
	v_mfma_f32_16x16x32_bf16 v[44:47], v[150:153], v[206:209], v[44:47]
	v_mfma_f32_16x16x32_bf16 v[40:43], v[158:161], v[206:209], v[40:43]
	v_mfma_f32_16x16x32_bf16 v[28:31], v[150:153], v[214:217], v[28:31]
	v_mfma_f32_16x16x32_bf16 v[24:27], v[158:161], v[214:217], v[24:27]
	v_mfma_f32_16x16x32_bf16 v[12:15], v[150:153], v[222:225], v[12:15]
	v_mfma_f32_16x16x32_bf16 v[8:11], v[158:161], v[222:225], v[8:11]
	s_setprio 0
	s_setprio 1
	v_mfma_f32_16x16x32_bf16 v[52:55], v[162:165], v[190:193], v[52:55]
	v_mfma_f32_16x16x32_bf16 v[48:51], v[170:173], v[190:193], v[48:51]
	v_mfma_f32_16x16x32_bf16 v[36:39], v[162:165], v[202:205], v[36:39]
	v_mfma_f32_16x16x32_bf16 v[32:35], v[170:173], v[202:205], v[32:35]
	v_mfma_f32_16x16x32_bf16 v[20:23], v[162:165], v[210:213], v[20:23]
	v_mfma_f32_16x16x32_bf16 v[16:19], v[170:173], v[210:213], v[16:19]
	v_mfma_f32_16x16x32_bf16 v[4:7], v[162:165], v[218:221], v[4:7]
	v_mfma_f32_16x16x32_bf16 v[0:3], v[170:173], v[218:221], v[0:3]
	v_mfma_f32_16x16x32_bf16 v[52:55], v[166:169], v[194:197], v[52:55]
	v_mfma_f32_16x16x32_bf16 v[48:51], v[186:189], v[194:197], v[48:51]
	v_mfma_f32_16x16x32_bf16 v[36:39], v[166:169], v[206:209], v[36:39]
	v_mfma_f32_16x16x32_bf16 v[32:35], v[186:189], v[206:209], v[32:35]
	v_mfma_f32_16x16x32_bf16 v[20:23], v[166:169], v[214:217], v[20:23]
	v_mfma_f32_16x16x32_bf16 v[16:19], v[186:189], v[214:217], v[16:19]
	v_mfma_f32_16x16x32_bf16 v[4:7], v[166:169], v[222:225], v[4:7]
	v_mfma_f32_16x16x32_bf16 v[0:3], v[186:189], v[222:225], v[0:3]
	s_setprio 0
	s_barrier
	s_add_i32 s14, 0, 0x18000
	s_add_i32 s15, 0, 0x1c000
	v_add_u32_e32 v158, s14, v175
	v_add_u32_e32 v186, s15, v175
	ds_read_b128 v[146:149], v158
	ds_read_b128 v[150:153], v158 offset:1024
	ds_read_b128 v[154:157], v158 offset:2048
	ds_read_b128 v[158:161], v158 offset:3072
	ds_read_b128 v[162:165], v186
	ds_read_b128 v[166:169], v186 offset:1024
	ds_read_b128 v[170:173], v186 offset:2048
	ds_read_b128 v[186:189], v186 offset:3072
	s_add_u32 s50, s50, 0x40000
	s_addc_u32 s51, s51, 0
	s_mov_b32 m0, s45
	v_lshl_add_u64 v[232:233], s[50:51], 0, v[128:129]
	ds_read_b128 v[190:193], v182 offset:32768
	ds_read_b128 v[194:197], v182 offset:33792
	ds_read_b128 v[202:205], v182 offset:34816
	ds_read_b128 v[206:209], v182 offset:35840
	ds_read_b128 v[210:213], v182 offset:36864
	ds_read_b128 v[214:217], v182 offset:37888
	ds_read_b128 v[218:221], v182 offset:38912
	ds_read_b128 v[222:225], v182 offset:39936
	global_load_lds_dwordx4 v[232:233], off
	v_lshl_add_u64 v[232:233], s[50:51], 0, v[132:133]
	s_mov_b32 m0, s47
	s_nop 0
	global_load_lds_dwordx4 v[232:233], off
	s_waitcnt vmcnt(8)
	s_waitcnt lgkmcnt(0)
	s_barrier
	s_setprio 1
	s_waitcnt lgkmcnt(0)
	v_mfma_f32_16x16x32_bf16 v[124:127], v[146:149], v[190:193], v[124:127]
	v_mfma_f32_16x16x32_bf16 v[120:123], v[154:157], v[190:193], v[120:123]
	v_mfma_f32_16x16x32_bf16 v[108:111], v[146:149], v[202:205], v[108:111]
	v_mfma_f32_16x16x32_bf16 v[104:107], v[154:157], v[202:205], v[104:107]
	v_mfma_f32_16x16x32_bf16 v[92:95], v[146:149], v[210:213], v[92:95]
	v_mfma_f32_16x16x32_bf16 v[88:91], v[154:157], v[210:213], v[88:91]
	v_mfma_f32_16x16x32_bf16 v[76:79], v[146:149], v[218:221], v[76:79]
	v_mfma_f32_16x16x32_bf16 v[72:75], v[154:157], v[218:221], v[72:75]
	v_mfma_f32_16x16x32_bf16 v[124:127], v[150:153], v[194:197], v[124:127]
	v_mfma_f32_16x16x32_bf16 v[120:123], v[158:161], v[194:197], v[120:123]
	v_mfma_f32_16x16x32_bf16 v[108:111], v[150:153], v[206:209], v[108:111]
	v_mfma_f32_16x16x32_bf16 v[104:107], v[158:161], v[206:209], v[104:107]
	v_mfma_f32_16x16x32_bf16 v[92:95], v[150:153], v[214:217], v[92:95]
	v_mfma_f32_16x16x32_bf16 v[88:91], v[158:161], v[214:217], v[88:91]
	v_mfma_f32_16x16x32_bf16 v[76:79], v[150:153], v[222:225], v[76:79]
	v_mfma_f32_16x16x32_bf16 v[72:75], v[158:161], v[222:225], v[72:75]
	s_setprio 0
	s_setprio 1
	v_mfma_f32_16x16x32_bf16 v[116:119], v[162:165], v[190:193], v[116:119]
	v_mfma_f32_16x16x32_bf16 v[112:115], v[170:173], v[190:193], v[112:115]
	v_mfma_f32_16x16x32_bf16 v[100:103], v[162:165], v[202:205], v[100:103]
	v_mfma_f32_16x16x32_bf16 v[96:99], v[170:173], v[202:205], v[96:99]
	v_mfma_f32_16x16x32_bf16 v[84:87], v[162:165], v[210:213], v[84:87]
	v_mfma_f32_16x16x32_bf16 v[80:83], v[170:173], v[210:213], v[80:83]
	v_mfma_f32_16x16x32_bf16 v[68:71], v[162:165], v[218:221], v[68:71]
	v_mfma_f32_16x16x32_bf16 v[64:67], v[170:173], v[218:221], v[64:67]
	v_mfma_f32_16x16x32_bf16 v[116:119], v[166:169], v[194:197], v[116:119]
	v_mfma_f32_16x16x32_bf16 v[112:115], v[186:189], v[194:197], v[112:115]
	v_mfma_f32_16x16x32_bf16 v[100:103], v[166:169], v[206:209], v[100:103]
	v_mfma_f32_16x16x32_bf16 v[96:99], v[186:189], v[206:209], v[96:99]
	v_mfma_f32_16x16x32_bf16 v[84:87], v[166:169], v[214:217], v[84:87]
	v_mfma_f32_16x16x32_bf16 v[80:83], v[186:189], v[214:217], v[80:83]
	v_mfma_f32_16x16x32_bf16 v[68:71], v[166:169], v[222:225], v[68:71]
	v_mfma_f32_16x16x32_bf16 v[64:67], v[186:189], v[222:225], v[64:67]
	s_setprio 0
	s_barrier
; #define PG8_STAGE(bufoff, gbase, voff) do { _Pragma("unroll") for (int _i = 0; _i < 2; ++_i) \
;         __builtin_amdgcn_global_load_lds((const unsigned*)((const char*)(gbase) + (voff)[_i]), (PG8_LAS unsigned*)(lds + (bufoff) + ldsw + _i * 8192), 16, 0, 0); } while (0)
; #define PG8_LDA(dst, b, h) do { _Pragma("unroll") for (int m = 0; m < 4; ++m) _Pragma("unroll") for (int k = 0; k < 2; ++k) dst[m][k] = *(const PG8_LAS bf16x8*)(lds + PG8_SA(b, h) + aoff + m * 2048 + k * 1024); } while (0)
; #define PG8_MMA(ai, bj, At, Bt) do { __builtin_amdgcn_s_setprio(1); _Pragma("unroll") for (int m = 0; m < 4; ++m) _Pragma("unroll") for (int n = 0; n < 2; ++n) _Pragma("unroll") for (int k = 0; k < 2; ++k) \
;         acc[ai][bj][m][n] = __builtin_amdgcn_mfma_f32_16x16x32_bf16(Bt[n][k], At[m][k], acc[ai][bj][m][n], 0, 0, 0); __builtin_amdgcn_s_setprio(0); } while (0)
; #define PG8_WAIT_V(n) asm volatile("s_waitcnt vmcnt(" #n ")" ::: "memory")
; #define PG8_WAIT_L(n) asm volatile("s_waitcnt lgkmcnt(" #n ")" ::: "memory")
; #define PG8_BAR __builtin_amdgcn_s_barrier()
; #define PG8_SCHED __builtin_amdgcn_sched_barrier(0)
; template <class Epi, class Sched, bool ALIGN_EPI = false, bool SP2 = false>
; __device__ __forceinline__ void gemm_phase(PG8_LAS unsigned char* lds, const Gemm g, const Sched& S, const Epi& E, int tid_in) {
;     ...
;             PG8_LDA(At, 1, 1); PG8_STAGE(PG8_SB(1, 0), b3, voffB); PG8_STAGE(PG8_SB(1, 1), b3 + hstep, voffB); PG8_STAGE(PG8_SA(1, 0), a3, voffA);
;             PG8_WAIT_V(8); PG8_WAIT_L(0); PG8_BAR; PG8_MMA(1, 0, At, B0); PG8_MMA(1, 1, At, B1); PG8_BAR; PG8_SCHED;
	s_add_i32 s14, s14, s30
	v_lshl_add_u64 v[198:199], v[198:199], 0, s[24:25]
	s_mov_b32 m0, s14
	ds_read_b128 v[190:193], v182 offset:49152
	ds_read_b128 v[194:197], v182 offset:50176
	ds_read_b128 v[202:205], v182 offset:51200
	ds_read_b128 v[206:209], v182 offset:52224
	ds_read_b128 v[210:213], v182 offset:53248
	ds_read_b128 v[214:217], v182 offset:54272
	ds_read_b128 v[218:221], v182 offset:55296
	ds_read_b128 v[222:225], v182 offset:56320
	global_load_lds_dwordx4 v[198:199], off
	s_add_i32 m0, s14, 0x2000
	s_add_u32 s48, s48, 0x40080
	v_lshl_add_u64 v[198:199], v[226:227], 0, s[24:25]
	s_addc_u32 s49, s49, 0
	s_add_i32 s14, s15, s30
	global_load_lds_dwordx4 v[198:199], off
	v_lshl_add_u64 v[198:199], s[48:49], 0, v[130:131]
	s_mov_b32 m0, s14
	s_nop 0
	global_load_lds_dwordx4 v[198:199], off
	v_lshl_add_u64 v[198:199], s[48:49], 0, v[134:135]
	s_add_i32 m0, s14, 0x2000
	s_nop 0
	global_load_lds_dwordx4 v[198:199], off
	v_lshl_add_u64 v[198:199], v[228:229], 0, s[24:25]
	s_mov_b32 m0, s56
	s_nop 0
	global_load_lds_dwordx4 v[198:199], off
	v_lshl_add_u64 v[198:199], v[230:231], 0, s[24:25]
	s_mov_b32 m0, s57
	s_nop 0
	global_load_lds_dwordx4 v[198:199], off
	s_waitcnt vmcnt(8)
	s_waitcnt lgkmcnt(0)
	s_barrier
	s_setprio 1
	s_waitcnt lgkmcnt(0)
	v_mfma_f32_16x16x32_bf16 v[60:63], v[146:149], v[190:193], v[60:63]
	v_mfma_f32_16x16x32_bf16 v[56:59], v[154:157], v[190:193], v[56:59]
	v_mfma_f32_16x16x32_bf16 v[44:47], v[146:149], v[202:205], v[44:47]
	v_mfma_f32_16x16x32_bf16 v[40:43], v[154:157], v[202:205], v[40:43]
	v_mfma_f32_16x16x32_bf16 v[28:31], v[146:149], v[210:213], v[28:31]
	v_mfma_f32_16x16x32_bf16 v[24:27], v[154:157], v[210:213], v[24:27]
	v_mfma_f32_16x16x32_bf16 v[12:15], v[146:149], v[218:221], v[12:15]
	v_mfma_f32_16x16x32_bf16 v[8:11], v[154:157], v[218:221], v[8:11]
	v_mfma_f32_16x16x32_bf16 v[60:63], v[150:153], v[194:197], v[60:63]
	v_mfma_f32_16x16x32_bf16 v[56:59], v[158:161], v[194:197], v[56:59]
	v_mfma_f32_16x16x32_bf16 v[44:47], v[150:153], v[206:209], v[44:47]
	v_mfma_f32_16x16x32_bf16 v[40:43], v[158:161], v[206:209], v[40:43]
	v_mfma_f32_16x16x32_bf16 v[28:31], v[150:153], v[214:217], v[28:31]
	v_mfma_f32_16x16x32_bf16 v[24:27], v[158:161], v[214:217], v[24:27]
	v_mfma_f32_16x16x32_bf16 v[12:15], v[150:153], v[222:225], v[12:15]
	v_mfma_f32_16x16x32_bf16 v[8:11], v[158:161], v[222:225], v[8:11]
	s_setprio 0
	s_setprio 1
	v_mfma_f32_16x16x32_bf16 v[52:55], v[162:165], v[190:193], v[52:55]
	v_mfma_f32_16x16x32_bf16 v[48:51], v[170:173], v[190:193], v[48:51]
	v_mfma_f32_16x16x32_bf16 v[36:39], v[162:165], v[202:205], v[36:39]
	v_mfma_f32_16x16x32_bf16 v[32:35], v[170:173], v[202:205], v[32:35]
	v_mfma_f32_16x16x32_bf16 v[20:23], v[162:165], v[210:213], v[20:23]
	v_mfma_f32_16x16x32_bf16 v[16:19], v[170:173], v[210:213], v[16:19]
	v_mfma_f32_16x16x32_bf16 v[4:7], v[162:165], v[218:221], v[4:7]
	v_mfma_f32_16x16x32_bf16 v[0:3], v[170:173], v[218:221], v[0:3]
	v_mfma_f32_16x16x32_bf16 v[52:55], v[166:169], v[194:197], v[52:55]
	v_mfma_f32_16x16x32_bf16 v[48:51], v[186:189], v[194:197], v[48:51]
	v_mfma_f32_16x16x32_bf16 v[36:39], v[166:169], v[206:209], v[36:39]
	v_mfma_f32_16x16x32_bf16 v[32:35], v[186:189], v[206:209], v[32:35]
	v_mfma_f32_16x16x32_bf16 v[20:23], v[166:169], v[214:217], v[20:23]
	v_mfma_f32_16x16x32_bf16 v[16:19], v[186:189], v[214:217], v[16:19]
	v_mfma_f32_16x16x32_bf16 v[4:7], v[166:169], v[222:225], v[4:7]
	v_mfma_f32_16x16x32_bf16 v[0:3], v[186:189], v[222:225], v[0:3]
	s_setprio 0
	s_barrier
	s_add_i32 s69, s69, 2
	s_add_u32 s67, s67, 0x100
	s_addc_u32 s68, s68, 0
	s_add_u32 s12, s12, 0x100
	s_addc_u32 s13, s13, 0
	s_cmp_gt_u32 s69, 13
	s_cbranch_scc0 .LBB0_712

; #define PG8_STAGE(bufoff, gbase, voff) do { _Pragma("unroll") for (int _i = 0; _i < 2; ++_i) \
;         __builtin_amdgcn_global_load_lds((const unsigned*)((const char*)(gbase) + (voff)[_i]), (PG8_LAS unsigned*)(lds + (bufoff) + ldsw + _i * 8192), 16, 0, 0); } while (0)
; #define PG8_LDA(dst, b, h) do { _Pragma("unroll") for (int m = 0; m < 4; ++m) _Pragma("unroll") for (int k = 0; k < 2; ++k) dst[m][k] = *(const PG8_LAS bf16x8*)(lds + PG8_SA(b, h) + aoff + m * 2048 + k * 1024); } while (0)
; #define PG8_LDB(dst, b, h) do { _Pragma("unroll") for (int n = 0; n < 2; ++n) _Pragma("unroll") for (int k = 0; k < 2; ++k) dst[n][k] = *(const PG8_LAS bf16x8*)(lds + PG8_SB(b, h) + boff + n * 2048 + k * 1024); } while (0)
; #define PG8_MMA(ai, bj, At, Bt) do { __builtin_amdgcn_s_setprio(1); _Pragma("unroll") for (int m = 0; m < 4; ++m) _Pragma("unroll") for (int n = 0; n < 2; ++n) _Pragma("unroll") for (int k = 0; k < 2; ++k) \
;         acc[ai][bj][m][n] = __builtin_amdgcn_mfma_f32_16x16x32_bf16(Bt[n][k], At[m][k], acc[ai][bj][m][n], 0, 0, 0); __builtin_amdgcn_s_setprio(0); } while (0)
; #define PG8_WAIT_V(n) asm volatile("s_waitcnt vmcnt(" #n ")" ::: "memory")
; #define PG8_WAIT_L(n) asm volatile("s_waitcnt lgkmcnt(" #n ")" ::: "memory")
; template <class Epi, class Sched, bool ALIGN_EPI = false, bool SP2 = false>
; __device__ __forceinline__ void gemm_phase(PG8_LAS unsigned char* lds, const Gemm g, const Sched& S, const Epi& E, int tid_in) {
;     ...
;             const bool last = (t == nt - 2);
;             const char* a1 = cA + (size_t)(t + 1) * kstep;
;             const char* a2 = last ? nA : cA + (size_t)(t + 2) * kstep; const char* b2 = last ? nB : cB + (size_t)(t + 2) * kstep;
;             const char* a3 = a2 + kstep; const char* b3 = b2 + kstep;
;             if (last && has_next) S.a_ready(nxt);
;             if constexpr (SP2) {
;             PG8_LDB(B0, 0, 0); PG8_LDB(B1, 0, 1); PG8_SCHED; PG8_LDA(At, 0, 0); PG8_STAGE(PG8_SA(1, 1), a1 + hstep, voffA);
;             PG8_WAIT_V(8); PG8_WAIT_L(0); PG8_BAR; PG8_MMA(0, 0, At, B0); PG8_MMA(0, 1, At, B1); PG8_BAR; PG8_SCHED;
;             PG8_LDA(At, 0, 1); PG8_STAGE(PG8_SB(0, 0), b2, voffB); PG8_STAGE(PG8_SB(0, 1), b2 + hstep, voffB); PG8_STAGE(PG8_SA(0, 0), a2, voffA);
;             PG8_WAIT_V(8); PG8_WAIT_L(0); PG8_BAR; PG8_MMA(1, 0, At, B0); PG8_MMA(1, 1, At, B1); PG8_BAR; PG8_SCHED;
.Lpk5:
	s_or_b64 s[98:99], s[10:11], 1
	v_lshl_add_u64 v[198:199], s[12:13], 0, v[140:141]
	s_add_i32 m0, s31, 0xc000
	ds_read_b128 v[190:193], v182
	ds_read_b128 v[194:197], v182 offset:1024
	ds_read_b128 v[202:205], v182 offset:2048
	ds_read_b128 v[206:209], v182 offset:3072
	ds_read_b128 v[210:213], v182 offset:4096
	ds_read_b128 v[214:217], v182 offset:5120
	ds_read_b128 v[218:221], v182 offset:6144
	ds_read_b128 v[222:225], v182 offset:7168
	global_load_lds_dwordx4 v[198:199], off
	v_lshl_add_u64 v[198:199], s[12:13], 0, v[138:139]
	s_add_i32 m0, s31, 0xe000
	s_nop 0
	global_load_lds_dwordx4 v[198:199], off
	s_waitcnt vmcnt(8)
	s_waitcnt lgkmcnt(0)
	s_barrier
	s_setprio 1
	s_waitcnt lgkmcnt(0)
	v_mfma_f32_16x16x32_bf16 v[124:127], v[146:149], v[190:193], v[124:127]
	v_mfma_f32_16x16x32_bf16 v[120:123], v[154:157], v[190:193], v[120:123]
	v_mfma_f32_16x16x32_bf16 v[108:111], v[146:149], v[202:205], v[108:111]
	v_mfma_f32_16x16x32_bf16 v[104:107], v[154:157], v[202:205], v[104:107]
	v_mfma_f32_16x16x32_bf16 v[92:95], v[146:149], v[210:213], v[92:95]
	v_mfma_f32_16x16x32_bf16 v[88:91], v[154:157], v[210:213], v[88:91]
	v_mfma_f32_16x16x32_bf16 v[76:79], v[146:149], v[218:221], v[76:79]
	v_mfma_f32_16x16x32_bf16 v[72:75], v[154:157], v[218:221], v[72:75]
	v_mfma_f32_16x16x32_bf16 v[124:127], v[150:153], v[194:197], v[124:127]
	v_mfma_f32_16x16x32_bf16 v[120:123], v[158:161], v[194:197], v[120:123]
	v_mfma_f32_16x16x32_bf16 v[108:111], v[150:153], v[206:209], v[108:111]
	v_mfma_f32_16x16x32_bf16 v[104:107], v[158:161], v[206:209], v[104:107]
	v_mfma_f32_16x16x32_bf16 v[92:95], v[150:153], v[214:217], v[92:95]
	v_mfma_f32_16x16x32_bf16 v[88:91], v[158:161], v[214:217], v[88:91]
	v_mfma_f32_16x16x32_bf16 v[76:79], v[150:153], v[222:225], v[76:79]
	v_mfma_f32_16x16x32_bf16 v[72:75], v[158:161], v[222:225], v[72:75]
	s_setprio 0
	s_setprio 1
	v_mfma_f32_16x16x32_bf16 v[116:119], v[162:165], v[190:193], v[116:119]
	v_mfma_f32_16x16x32_bf16 v[112:115], v[170:173], v[190:193], v[112:115]
	v_mfma_f32_16x16x32_bf16 v[100:103], v[162:165], v[202:205], v[100:103]
	v_mfma_f32_16x16x32_bf16 v[96:99], v[170:173], v[202:205], v[96:99]
	v_mfma_f32_16x16x32_bf16 v[84:87], v[162:165], v[210:213], v[84:87]
	v_mfma_f32_16x16x32_bf16 v[80:83], v[170:173], v[210:213], v[80:83]
	v_mfma_f32_16x16x32_bf16 v[68:71], v[162:165], v[218:221], v[68:71]
	v_mfma_f32_16x16x32_bf16 v[64:67], v[170:173], v[218:221], v[64:67]
	v_mfma_f32_16x16x32_bf16 v[116:119], v[166:169], v[194:197], v[116:119]
	v_mfma_f32_16x16x32_bf16 v[112:115], v[186:189], v[194:197], v[112:115]
	v_mfma_f32_16x16x32_bf16 v[100:103], v[166:169], v[206:209], v[100:103]
	v_mfma_f32_16x16x32_bf16 v[96:99], v[186:189], v[206:209], v[96:99]
	v_mfma_f32_16x16x32_bf16 v[84:87], v[166:169], v[214:217], v[84:87]
	v_mfma_f32_16x16x32_bf16 v[80:83], v[186:189], v[214:217], v[80:83]
	v_mfma_f32_16x16x32_bf16 v[68:71], v[166:169], v[222:225], v[68:71]
	v_mfma_f32_16x16x32_bf16 v[64:67], v[186:189], v[222:225], v[64:67]
	s_setprio 0
	s_barrier
	s_add_i32 s14, s62, s30
	v_lshl_add_u64 v[198:199], s[48:49], 0, v[130:131]
	s_mov_b32 m0, s14
	ds_read_b128 v[190:193], v182 offset:16384
	ds_read_b128 v[194:197], v182 offset:17408
	ds_read_b128 v[202:205], v182 offset:18432
	ds_read_b128 v[206:209], v182 offset:19456
	ds_read_b128 v[210:213], v182 offset:20480
	ds_read_b128 v[214:217], v182 offset:21504
	ds_read_b128 v[218:221], v182 offset:22528
	ds_read_b128 v[222:225], v182 offset:23552
	s_mov_b64 exec, s[98:99]
	global_load_lds_dwordx4 v[198:199], off
	s_mov_b64 exec, -1
	s_add_i32 m0, s14, 0x2000
	s_add_u32 s70, s48, 0x40000
	v_lshl_add_u64 v[226:227], s[48:49], 0, v[134:135]
	s_addc_u32 s71, s49, 0
	s_add_i32 s14, s63, s30
	s_mov_b64 exec, s[98:99]
	global_load_lds_dwordx4 v[226:227], off
	s_mov_b64 exec, -1
	v_lshl_add_u64 v[228:229], s[70:71], 0, v[130:131]
	s_mov_b32 m0, s14
	v_lshl_add_u64 v[230:231], s[50:51], 0, v[132:133]
	s_mov_b64 exec, s[98:99]
	global_load_lds_dwordx4 v[228:229], off
	s_mov_b64 exec, -1
	v_lshl_add_u64 v[228:229], s[70:71], 0, v[134:135]
	s_add_i32 m0, s14, 0x2000
	s_nop 0
	s_mov_b64 exec, s[98:99]
	global_load_lds_dwordx4 v[228:229], off
	s_mov_b64 exec, -1
	v_lshl_add_u64 v[228:229], s[50:51], 0, v[128:129]
	s_mov_b32 m0, s31
	s_nop 0
	s_mov_b64 exec, s[98:99]
	global_load_lds_dwordx4 v[228:229], off
	s_mov_b64 exec, -1
	s_mov_b32 m0, s33
	s_nop 0
	s_mov_b64 exec, s[98:99]
	global_load_lds_dwordx4 v[230:231], off
	s_mov_b64 exec, -1
	s_waitcnt vmcnt(8)
	s_waitcnt lgkmcnt(0)
	s_barrier
; #define PG8_STAGE(bufoff, gbase, voff) do { _Pragma("unroll") for (int _i = 0; _i < 2; ++_i) \
;         __builtin_amdgcn_global_load_lds((const unsigned*)((const char*)(gbase) + (voff)[_i]), (PG8_LAS unsigned*)(lds + (bufoff) + ldsw + _i * 8192), 16, 0, 0); } while (0)
; #define PG8_LDA(dst, b, h) do { _Pragma("unroll") for (int m = 0; m < 4; ++m) _Pragma("unroll") for (int k = 0; k < 2; ++k) dst[m][k] = *(const PG8_LAS bf16x8*)(lds + PG8_SA(b, h) + aoff + m * 2048 + k * 1024); } while (0)
; #define PG8_LDB(dst, b, h) do { _Pragma("unroll") for (int n = 0; n < 2; ++n) _Pragma("unroll") for (int k = 0; k < 2; ++k) dst[n][k] = *(const PG8_LAS bf16x8*)(lds + PG8_SB(b, h) + boff + n * 2048 + k * 1024); } while (0)
; #define PG8_MMA(ai, bj, At, Bt) do { __builtin_amdgcn_s_setprio(1); _Pragma("unroll") for (int m = 0; m < 4; ++m) _Pragma("unroll") for (int n = 0; n < 2; ++n) _Pragma("unroll") for (int k = 0; k < 2; ++k) \
;         acc[ai][bj][m][n] = __builtin_amdgcn_mfma_f32_16x16x32_bf16(Bt[n][k], At[m][k], acc[ai][bj][m][n], 0, 0, 0); __builtin_amdgcn_s_setprio(0); } while (0)
; #define PG8_WAIT_V(n) asm volatile("s_waitcnt vmcnt(" #n ")" ::: "memory")
; #define PG8_WAIT_L(n) asm volatile("s_waitcnt lgkmcnt(" #n ")" ::: "memory")
; #define PG8_BAR __builtin_amdgcn_s_barrier()
; #define PG8_SCHED __builtin_amdgcn_sched_barrier(0)
; template <class Epi, class Sched, bool ALIGN_EPI = false, bool SP2 = false>
; __device__ __forceinline__ void gemm_phase(PG8_LAS unsigned char* lds, const Gemm g, const Sched& S, const Epi& E, int tid_in) {
;     ...
;             PG8_WAIT_V(8); PG8_WAIT_L(0); PG8_BAR; PG8_MMA(1, 0, At, B0); PG8_MMA(1, 1, At, B1); PG8_BAR; PG8_SCHED;
;             PG8_LDB(B0, 1, 0); PG8_LDB(B1, 1, 1); PG8_SCHED; PG8_LDA(At, 1, 0); PG8_STAGE(PG8_SA(0, 1), a2 + hstep, voffA);
;             PG8_WAIT_V(8); PG8_WAIT_L(0); PG8_BAR; PG8_MMA(0, 0, At, B0); PG8_MMA(0, 1, At, B1); PG8_BAR; PG8_SCHED;
	s_setprio 1
	s_waitcnt lgkmcnt(0)
	v_mfma_f32_16x16x32_bf16 v[60:63], v[146:149], v[190:193], v[60:63]
	v_mfma_f32_16x16x32_bf16 v[56:59], v[154:157], v[190:193], v[56:59]
	v_mfma_f32_16x16x32_bf16 v[44:47], v[146:149], v[202:205], v[44:47]
	v_mfma_f32_16x16x32_bf16 v[40:43], v[154:157], v[202:205], v[40:43]
	v_mfma_f32_16x16x32_bf16 v[28:31], v[146:149], v[210:213], v[28:31]
	v_mfma_f32_16x16x32_bf16 v[24:27], v[154:157], v[210:213], v[24:27]
	v_mfma_f32_16x16x32_bf16 v[12:15], v[146:149], v[218:221], v[12:15]
	v_mfma_f32_16x16x32_bf16 v[8:11], v[154:157], v[218:221], v[8:11]
	v_mfma_f32_16x16x32_bf16 v[60:63], v[150:153], v[194:197], v[60:63]
	v_mfma_f32_16x16x32_bf16 v[56:59], v[158:161], v[194:197], v[56:59]
	v_mfma_f32_16x16x32_bf16 v[44:47], v[150:153], v[206:209], v[44:47]
	v_mfma_f32_16x16x32_bf16 v[40:43], v[158:161], v[206:209], v[40:43]
	v_mfma_f32_16x16x32_bf16 v[28:31], v[150:153], v[214:217], v[28:31]
	v_mfma_f32_16x16x32_bf16 v[24:27], v[158:161], v[214:217], v[24:27]
	v_mfma_f32_16x16x32_bf16 v[12:15], v[150:153], v[222:225], v[12:15]
	v_mfma_f32_16x16x32_bf16 v[8:11], v[158:161], v[222:225], v[8:11]
	s_setprio 0
	s_setprio 1
	v_mfma_f32_16x16x32_bf16 v[52:55], v[162:165], v[190:193], v[52:55]
	v_mfma_f32_16x16x32_bf16 v[48:51], v[170:173], v[190:193], v[48:51]
	v_mfma_f32_16x16x32_bf16 v[36:39], v[162:165], v[202:205], v[36:39]
	v_mfma_f32_16x16x32_bf16 v[32:35], v[170:173], v[202:205], v[32:35]
	v_mfma_f32_16x16x32_bf16 v[20:23], v[162:165], v[210:213], v[20:23]
	v_mfma_f32_16x16x32_bf16 v[16:19], v[170:173], v[210:213], v[16:19]
	v_mfma_f32_16x16x32_bf16 v[4:7], v[162:165], v[218:221], v[4:7]
	v_mfma_f32_16x16x32_bf16 v[0:3], v[170:173], v[218:221], v[0:3]
	v_mfma_f32_16x16x32_bf16 v[52:55], v[166:169], v[194:197], v[52:55]
	v_mfma_f32_16x16x32_bf16 v[48:51], v[186:189], v[194:197], v[48:51]
	v_mfma_f32_16x16x32_bf16 v[36:39], v[166:169], v[206:209], v[36:39]
	v_mfma_f32_16x16x32_bf16 v[32:35], v[186:189], v[206:209], v[32:35]
	v_mfma_f32_16x16x32_bf16 v[20:23], v[166:169], v[214:217], v[20:23]
	v_mfma_f32_16x16x32_bf16 v[16:19], v[186:189], v[214:217], v[16:19]
	v_mfma_f32_16x16x32_bf16 v[4:7], v[166:169], v[222:225], v[4:7]
	v_mfma_f32_16x16x32_bf16 v[0:3], v[186:189], v[222:225], v[0:3]
	s_setprio 0
	s_barrier
	s_add_i32 s14, 0, 0x18000
	s_add_i32 s15, 0, 0x1c000
	v_add_u32_e32 v158, s14, v175
	v_add_u32_e32 v186, s15, v175
	ds_read_b128 v[146:149], v158
	ds_read_b128 v[150:153], v158 offset:1024
	ds_read_b128 v[154:157], v158 offset:2048
	ds_read_b128 v[158:161], v158 offset:3072
	ds_read_b128 v[162:165], v186
	ds_read_b128 v[166:169], v186 offset:1024
	ds_read_b128 v[170:173], v186 offset:2048
	ds_read_b128 v[186:189], v186 offset:3072
	s_add_u32 s50, s50, 0x40000
	s_addc_u32 s51, s51, 0
	s_mov_b32 m0, s45
	v_lshl_add_u64 v[232:233], s[50:51], 0, v[128:129]
	ds_read_b128 v[190:193], v182 offset:32768
	ds_read_b128 v[194:197], v182 offset:33792
	ds_read_b128 v[202:205], v182 offset:34816
	ds_read_b128 v[206:209], v182 offset:35840
	ds_read_b128 v[210:213], v182 offset:36864
	ds_read_b128 v[214:217], v182 offset:37888
	ds_read_b128 v[218:221], v182 offset:38912
	ds_read_b128 v[222:225], v182 offset:39936
	s_mov_b64 exec, s[98:99]
	global_load_lds_dwordx4 v[232:233], off
	s_mov_b64 exec, -1
	v_lshl_add_u64 v[232:233], s[50:51], 0, v[132:133]
	s_mov_b32 m0, s47
	s_nop 0
	s_mov_b64 exec, s[98:99]
	global_load_lds_dwordx4 v[232:233], off
	s_mov_b64 exec, -1
	s_waitcnt vmcnt(8)
	s_waitcnt lgkmcnt(0)
	s_barrier
	s_setprio 1
	s_waitcnt lgkmcnt(0)
	v_mfma_f32_16x16x32_bf16 v[124:127], v[146:149], v[190:193], v[124:127]
	v_mfma_f32_16x16x32_bf16 v[120:123], v[154:157], v[190:193], v[120:123]
	v_mfma_f32_16x16x32_bf16 v[108:111], v[146:149], v[202:205], v[108:111]
	v_mfma_f32_16x16x32_bf16 v[104:107], v[154:157], v[202:205], v[104:107]
	v_mfma_f32_16x16x32_bf16 v[92:95], v[146:149], v[210:213], v[92:95]
	v_mfma_f32_16x16x32_bf16 v[88:91], v[154:157], v[210:213], v[88:91]
	v_mfma_f32_16x16x32_bf16 v[76:79], v[146:149], v[218:221], v[76:79]
	v_mfma_f32_16x16x32_bf16 v[72:75], v[154:157], v[218:221], v[72:75]
	v_mfma_f32_16x16x32_bf16 v[124:127], v[150:153], v[194:197], v[124:127]
	v_mfma_f32_16x16x32_bf16 v[120:123], v[158:161], v[194:197], v[120:123]
	v_mfma_f32_16x16x32_bf16 v[108:111], v[150:153], v[206:209], v[108:111]
	v_mfma_f32_16x16x32_bf16 v[104:107], v[158:161], v[206:209], v[104:107]
	v_mfma_f32_16x16x32_bf16 v[92:95], v[150:153], v[214:217], v[92:95]
	v_mfma_f32_16x16x32_bf16 v[88:91], v[158:161], v[214:217], v[88:91]
	v_mfma_f32_16x16x32_bf16 v[76:79], v[150:153], v[222:225], v[76:79]
	v_mfma_f32_16x16x32_bf16 v[72:75], v[158:161], v[222:225], v[72:75]
	s_setprio 0
	s_setprio 1
	v_mfma_f32_16x16x32_bf16 v[116:119], v[162:165], v[190:193], v[116:119]
	v_mfma_f32_16x16x32_bf16 v[112:115], v[170:173], v[190:193], v[112:115]
	v_mfma_f32_16x16x32_bf16 v[100:103], v[162:165], v[202:205], v[100:103]
	v_mfma_f32_16x16x32_bf16 v[96:99], v[170:173], v[202:205], v[96:99]
	v_mfma_f32_16x16x32_bf16 v[84:87], v[162:165], v[210:213], v[84:87]
	v_mfma_f32_16x16x32_bf16 v[80:83], v[170:173], v[210:213], v[80:83]
	v_mfma_f32_16x16x32_bf16 v[68:71], v[162:165], v[218:221], v[68:71]
	v_mfma_f32_16x16x32_bf16 v[64:67], v[170:173], v[218:221], v[64:67]
	v_mfma_f32_16x16x32_bf16 v[116:119], v[166:169], v[194:197], v[116:119]
	v_mfma_f32_16x16x32_bf16 v[112:115], v[186:189], v[194:197], v[112:115]
	v_mfma_f32_16x16x32_bf16 v[100:103], v[166:169], v[206:209], v[100:103]
	v_mfma_f32_16x16x32_bf16 v[96:99], v[186:189], v[206:209], v[96:99]
	v_mfma_f32_16x16x32_bf16 v[84:87], v[166:169], v[214:217], v[84:87]
	v_mfma_f32_16x16x32_bf16 v[80:83], v[186:189], v[214:217], v[80:83]
	v_mfma_f32_16x16x32_bf16 v[68:71], v[166:169], v[222:225], v[68:71]
	v_mfma_f32_16x16x32_bf16 v[64:67], v[186:189], v[222:225], v[64:67]
	s_setprio 0
	s_barrier
; #define PG8_STAGE(bufoff, gbase, voff) do { _Pragma("unroll") for (int _i = 0; _i < 2; ++_i) \
;         __builtin_amdgcn_global_load_lds((const unsigned*)((const char*)(gbase) + (voff)[_i]), (PG8_LAS unsigned*)(lds + (bufoff) + ldsw + _i * 8192), 16, 0, 0); } while (0)
; #define PG8_LDA(dst, b, h) do { _Pragma("unroll") for (int m = 0; m < 4; ++m) _Pragma("unroll") for (int k = 0; k < 2; ++k) dst[m][k] = *(const PG8_LAS bf16x8*)(lds + PG8_SA(b, h) + aoff + m * 2048 + k * 1024); } while (0)
; #define PG8_MMA(ai, bj, At, Bt) do { __builtin_amdgcn_s_setprio(1); _Pragma("unroll") for (int m = 0; m < 4; ++m) _Pragma("unroll") for (int n = 0; n < 2; ++n) _Pragma("unroll") for (int k = 0; k < 2; ++k) \
;         acc[ai][bj][m][n] = __builtin_amdgcn_mfma_f32_16x16x32_bf16(Bt[n][k], At[m][k], acc[ai][bj][m][n], 0, 0, 0); __builtin_amdgcn_s_setprio(0); } while (0)
; #define PG8_WAIT_V(n) asm volatile("s_waitcnt vmcnt(" #n ")" ::: "memory")
; #define PG8_WAIT_L(n) asm volatile("s_waitcnt lgkmcnt(" #n ")" ::: "memory")
; #define PG8_BAR __builtin_amdgcn_s_barrier()
; #define PG8_SCHED __builtin_amdgcn_sched_barrier(0)
; template <class Epi, class Sched, bool ALIGN_EPI = false, bool SP2 = false>
; __device__ __forceinline__ void gemm_phase(PG8_LAS unsigned char* lds, const Gemm g, const Sched& S, const Epi& E, int tid_in) {
;     ...
;             PG8_LDA(At, 1, 1); PG8_STAGE(PG8_SB(1, 0), b3, voffB); PG8_STAGE(PG8_SB(1, 1), b3 + hstep, voffB); PG8_STAGE(PG8_SA(1, 0), a3, voffA);
;             PG8_WAIT_V(8); PG8_WAIT_L(0); PG8_BAR; PG8_MMA(1, 0, At, B0); PG8_MMA(1, 1, At, B1); PG8_BAR; PG8_SCHED;
	s_add_i32 s14, s14, s30
	v_lshl_add_u64 v[198:199], v[198:199], 0, s[24:25]
	s_mov_b32 m0, s14
	ds_read_b128 v[190:193], v182 offset:49152
	ds_read_b128 v[194:197], v182 offset:50176
	ds_read_b128 v[202:205], v182 offset:51200
	ds_read_b128 v[206:209], v182 offset:52224
	ds_read_b128 v[210:213], v182 offset:53248
	ds_read_b128 v[214:217], v182 offset:54272
	ds_read_b128 v[218:221], v182 offset:55296
	ds_read_b128 v[222:225], v182 offset:56320
	s_mov_b64 exec, s[98:99]
	global_load_lds_dwordx4 v[198:199], off
	s_mov_b64 exec, -1
	s_add_i32 m0, s14, 0x2000
	s_add_u32 s48, s48, 0x40080
	v_lshl_add_u64 v[198:199], v[226:227], 0, s[24:25]
	s_addc_u32 s49, s49, 0
	s_add_i32 s14, s15, s30
	s_mov_b64 exec, s[98:99]
	global_load_lds_dwordx4 v[198:199], off
	s_mov_b64 exec, -1
	v_lshl_add_u64 v[198:199], s[48:49], 0, v[130:131]
	s_mov_b32 m0, s14
	s_nop 0
	s_mov_b64 exec, s[98:99]
	global_load_lds_dwordx4 v[198:199], off
	s_mov_b64 exec, -1
	v_lshl_add_u64 v[198:199], s[48:49], 0, v[134:135]
	s_add_i32 m0, s14, 0x2000
	s_nop 0
	s_mov_b64 exec, s[98:99]
	global_load_lds_dwordx4 v[198:199], off
	s_mov_b64 exec, -1
	v_lshl_add_u64 v[198:199], v[228:229], 0, s[24:25]
	s_mov_b32 m0, s56
	s_nop 0
	s_mov_b64 exec, s[98:99]
	global_load_lds_dwordx4 v[198:199], off
	s_mov_b64 exec, -1
	v_lshl_add_u64 v[198:199], v[230:231], 0, s[24:25]
	s_mov_b32 m0, s57
	s_nop 0
	s_mov_b64 exec, s[98:99]
	global_load_lds_dwordx4 v[198:199], off
	s_mov_b64 exec, -1
	s_waitcnt vmcnt(8)
	s_waitcnt lgkmcnt(0)
	s_barrier
	s_setprio 1
	s_waitcnt lgkmcnt(0)
	v_mfma_f32_16x16x32_bf16 v[60:63], v[146:149], v[190:193], v[60:63]
	v_mfma_f32_16x16x32_bf16 v[56:59], v[154:157], v[190:193], v[56:59]
	v_mfma_f32_16x16x32_bf16 v[44:47], v[146:149], v[202:205], v[44:47]
	v_mfma_f32_16x16x32_bf16 v[40:43], v[154:157], v[202:205], v[40:43]
	v_mfma_f32_16x16x32_bf16 v[28:31], v[146:149], v[210:213], v[28:31]
	v_mfma_f32_16x16x32_bf16 v[24:27], v[154:157], v[210:213], v[24:27]
	v_mfma_f32_16x16x32_bf16 v[12:15], v[146:149], v[218:221], v[12:15]
	v_mfma_f32_16x16x32_bf16 v[8:11], v[154:157], v[218:221], v[8:11]
	v_mfma_f32_16x16x32_bf16 v[60:63], v[150:153], v[194:197], v[60:63]
	v_mfma_f32_16x16x32_bf16 v[56:59], v[158:161], v[194:197], v[56:59]
	v_mfma_f32_16x16x32_bf16 v[44:47], v[150:153], v[206:209], v[44:47]
	v_mfma_f32_16x16x32_bf16 v[40:43], v[158:161], v[206:209], v[40:43]
	v_mfma_f32_16x16x32_bf16 v[28:31], v[150:153], v[214:217], v[28:31]
	v_mfma_f32_16x16x32_bf16 v[24:27], v[158:161], v[214:217], v[24:27]
	v_mfma_f32_16x16x32_bf16 v[12:15], v[150:153], v[222:225], v[12:15]
	v_mfma_f32_16x16x32_bf16 v[8:11], v[158:161], v[222:225], v[8:11]
	s_setprio 0
	s_setprio 1
	v_mfma_f32_16x16x32_bf16 v[52:55], v[162:165], v[190:193], v[52:55]
	v_mfma_f32_16x16x32_bf16 v[48:51], v[170:173], v[190:193], v[48:51]
	v_mfma_f32_16x16x32_bf16 v[36:39], v[162:165], v[202:205], v[36:39]
	v_mfma_f32_16x16x32_bf16 v[32:35], v[170:173], v[202:205], v[32:35]
	v_mfma_f32_16x16x32_bf16 v[20:23], v[162:165], v[210:213], v[20:23]
	v_mfma_f32_16x16x32_bf16 v[16:19], v[170:173], v[210:213], v[16:19]
	v_mfma_f32_16x16x32_bf16 v[4:7], v[162:165], v[218:221], v[4:7]
	v_mfma_f32_16x16x32_bf16 v[0:3], v[170:173], v[218:221], v[0:3]
	v_mfma_f32_16x16x32_bf16 v[52:55], v[166:169], v[194:197], v[52:55]
	v_mfma_f32_16x16x32_bf16 v[48:51], v[186:189], v[194:197], v[48:51]
	v_mfma_f32_16x16x32_bf16 v[36:39], v[166:169], v[206:209], v[36:39]
	v_mfma_f32_16x16x32_bf16 v[32:35], v[186:189], v[206:209], v[32:35]
	v_mfma_f32_16x16x32_bf16 v[20:23], v[166:169], v[214:217], v[20:23]
	v_mfma_f32_16x16x32_bf16 v[16:19], v[186:189], v[214:217], v[16:19]
	v_mfma_f32_16x16x32_bf16 v[4:7], v[166:169], v[222:225], v[4:7]
	v_mfma_f32_16x16x32_bf16 v[0:3], v[186:189], v[222:225], v[0:3]
	s_setprio 0
	s_barrier
	s_add_i32 s69, s69, 2
	s_add_u32 s67, s67, 0x100
	s_addc_u32 s68, s68, 0
	s_add_u32 s12, s12, 0x100
	s_addc_u32 s13, s13, 0
	s_cmp_gt_u32 s69, 13
	s_branch .Lpost5

; #define PG8_STAGE(bufoff, gbase, voff) do { _Pragma("unroll") for (int _i = 0; _i < 2; ++_i) \
;         __builtin_amdgcn_global_load_lds((const unsigned*)((const char*)(gbase) + (voff)[_i]), (PG8_LAS unsigned*)(lds + (bufoff) + ldsw + _i * 8192), 16, 0, 0); } while (0)
; #define PG8_LDA(dst, b, h) do { _Pragma("unroll") for (int m = 0; m < 4; ++m) _Pragma("unroll") for (int k = 0; k < 2; ++k) dst[m][k] = *(const PG8_LAS bf16x8*)(lds + PG8_SA(b, h) + aoff + m * 2048 + k * 1024); } while (0)
; #define PG8_LDB(dst, b, h) do { _Pragma("unroll") for (int n = 0; n < 2; ++n) _Pragma("unroll") for (int k = 0; k < 2; ++k) dst[n][k] = *(const PG8_LAS bf16x8*)(lds + PG8_SB(b, h) + boff + n * 2048 + k * 1024); } while (0)
; #define PG8_MMA(ai, bj, At, Bt) do { __builtin_amdgcn_s_setprio(1); _Pragma("unroll") for (int m = 0; m < 4; ++m) _Pragma("unroll") for (int n = 0; n < 2; ++n) _Pragma("unroll") for (int k = 0; k < 2; ++k) \
;         acc[ai][bj][m][n] = __builtin_amdgcn_mfma_f32_16x16x32_bf16(Bt[n][k], At[m][k], acc[ai][bj][m][n], 0, 0, 0); __builtin_amdgcn_s_setprio(0); } while (0)
; #define PG8_WAIT_V(n) asm volatile("s_waitcnt vmcnt(" #n ")" ::: "memory")
; #define PG8_BAR __builtin_amdgcn_s_barrier()
; template <class Epi, class Sched, bool ALIGN_EPI = false, bool SP2 = false>
; __device__ __forceinline__ void gemm_phase(PG8_LAS unsigned char* lds, const Gemm g, const Sched& S, const Epi& E, int tid_in) {
;     ...
;         for (int t = 0; t < nt; t += 2) {
;             const bool last = (t == nt - 2);
;             const char* a1 = cA + (size_t)(t + 1) * kstep;
;             const char* a2 = last ? nA : cA + (size_t)(t + 2) * kstep; const char* b2 = last ? nB : cB + (size_t)(t + 2) * kstep;
;             const char* a3 = a2 + kstep; const char* b3 = b2 + kstep;
;             if (last && has_next) S.a_ready(nxt);
;             if constexpr (SP2) {
;             PG8_LDB(B0, 0, 0); PG8_LDB(B1, 0, 1); PG8_SCHED; PG8_LDA(At, 0, 0); PG8_STAGE(PG8_SA(1, 1), a1 + hstep, voffA);
;             PG8_WAIT_V(8); PG8_WAIT_L(0); PG8_BAR; PG8_MMA(0, 0, At, B0); PG8_MMA(0, 1, At, B1); PG8_BAR; PG8_SCHED;
;             PG8_LDA(At, 0, 1); PG8_STAGE(PG8_SB(0, 0), b2, voffB); PG8_STAGE(PG8_SB(0, 1), b2 + hstep, voffB); PG8_STAGE(PG8_SA(0, 0), a2, voffA);
;             PG8_WAIT_V(8); PG8_WAIT_L(0); PG8_BAR; PG8_MMA(1, 0, At, B0); PG8_MMA(1, 1, At, B1); PG8_BAR; PG8_SCHED;
.LBB0_912:
	ds_read_b128 v[120:123], v189
	ds_read_b128 v[132:135], v189 offset:1024
	ds_read_b128 v[136:139], v189 offset:2048
	ds_read_b128 v[140:143], v189 offset:3072
	ds_read_b128 v[144:147], v190
	ds_read_b128 v[148:151], v190 offset:1024
	ds_read_b128 v[168:171], v190 offset:2048
	ds_read_b128 v[172:175], v190 offset:3072
	s_add_u32 s4, s56, 0xfffc0080
	s_addc_u32 s5, s57, -1
	s_cmp_eq_u32 vcc_lo, 12
	s_cselect_b32 s61, s49, s5
	s_cselect_b32 s60, s55, s4
	s_cselect_b32 s59, s47, s81
	s_cselect_b32 s58, s76, s80
	s_cbranch_scc1 .Lpk6
	v_lshl_add_u64 v[184:185], s[56:57], 0, v[162:163]
	s_add_i32 m0, s63, 0xc000
	ds_read_b128 v[176:179], v191
	ds_read_b128 v[180:183], v191 offset:1024
	ds_read_b128 v[192:195], v191 offset:2048
	ds_read_b128 v[196:199], v191 offset:3072
	ds_read_b128 v[202:205], v191 offset:4096
	ds_read_b128 v[206:209], v191 offset:5120
	ds_read_b128 v[210:213], v191 offset:6144
	ds_read_b128 v[214:217], v191 offset:7168
	global_load_lds_dwordx4 v[184:185], off
	v_lshl_add_u64 v[184:185], s[56:57], 0, v[160:161]
	s_add_i32 m0, s63, 0xe000
	s_nop 0
	global_load_lds_dwordx4 v[184:185], off
	s_waitcnt vmcnt(8)
	s_waitcnt lgkmcnt(0)
	s_barrier
	s_setprio 1
	s_waitcnt lgkmcnt(0)
	v_mfma_f32_16x16x32_bf16 v[128:131], v[120:123], v[176:179], v[128:131]
	v_mfma_f32_16x16x32_bf16 v[124:127], v[136:139], v[176:179], v[124:127]
	v_mfma_f32_16x16x32_bf16 v[108:111], v[120:123], v[192:195], v[108:111]
	v_mfma_f32_16x16x32_bf16 v[104:107], v[136:139], v[192:195], v[104:107]
	v_mfma_f32_16x16x32_bf16 v[92:95], v[120:123], v[202:205], v[92:95]
	v_mfma_f32_16x16x32_bf16 v[88:91], v[136:139], v[202:205], v[88:91]
	v_mfma_f32_16x16x32_bf16 v[76:79], v[120:123], v[210:213], v[76:79]
	v_mfma_f32_16x16x32_bf16 v[72:75], v[136:139], v[210:213], v[72:75]
	v_mfma_f32_16x16x32_bf16 v[128:131], v[132:135], v[180:183], v[128:131]
	v_mfma_f32_16x16x32_bf16 v[124:127], v[140:143], v[180:183], v[124:127]
	v_mfma_f32_16x16x32_bf16 v[108:111], v[132:135], v[196:199], v[108:111]
	v_mfma_f32_16x16x32_bf16 v[104:107], v[140:143], v[196:199], v[104:107]
	v_mfma_f32_16x16x32_bf16 v[92:95], v[132:135], v[206:209], v[92:95]
	v_mfma_f32_16x16x32_bf16 v[88:91], v[140:143], v[206:209], v[88:91]
	v_mfma_f32_16x16x32_bf16 v[76:79], v[132:135], v[214:217], v[76:79]
	v_mfma_f32_16x16x32_bf16 v[72:75], v[140:143], v[214:217], v[72:75]
	s_setprio 0
	s_setprio 1
	v_mfma_f32_16x16x32_bf16 v[116:119], v[144:147], v[176:179], v[116:119]
	v_mfma_f32_16x16x32_bf16 v[112:115], v[168:171], v[176:179], v[112:115]
	v_mfma_f32_16x16x32_bf16 v[100:103], v[144:147], v[192:195], v[100:103]
	v_mfma_f32_16x16x32_bf16 v[96:99], v[168:171], v[192:195], v[96:99]
	v_mfma_f32_16x16x32_bf16 v[84:87], v[144:147], v[202:205], v[84:87]
	v_mfma_f32_16x16x32_bf16 v[80:83], v[168:171], v[202:205], v[80:83]
	v_mfma_f32_16x16x32_bf16 v[68:71], v[144:147], v[210:213], v[68:71]
	v_mfma_f32_16x16x32_bf16 v[64:67], v[168:171], v[210:213], v[64:67]
	v_mfma_f32_16x16x32_bf16 v[116:119], v[148:151], v[180:183], v[116:119]
	v_mfma_f32_16x16x32_bf16 v[112:115], v[172:175], v[180:183], v[112:115]
	v_mfma_f32_16x16x32_bf16 v[100:103], v[148:151], v[196:199], v[100:103]
	v_mfma_f32_16x16x32_bf16 v[96:99], v[172:175], v[196:199], v[96:99]
	v_mfma_f32_16x16x32_bf16 v[84:87], v[148:151], v[206:209], v[84:87]
	v_mfma_f32_16x16x32_bf16 v[80:83], v[172:175], v[206:209], v[80:83]
	v_mfma_f32_16x16x32_bf16 v[68:71], v[148:151], v[214:217], v[68:71]
	v_mfma_f32_16x16x32_bf16 v[64:67], v[172:175], v[214:217], v[64:67]
	s_setprio 0
	s_barrier
	s_add_i32 s4, s73, s62
	v_lshl_add_u64 v[184:185], s[58:59], 0, v[154:155]
	s_mov_b32 m0, s4
	ds_read_b128 v[176:179], v191 offset:16384
	ds_read_b128 v[180:183], v191 offset:17408
	ds_read_b128 v[192:195], v191 offset:18432
	ds_read_b128 v[196:199], v191 offset:19456
	ds_read_b128 v[202:205], v191 offset:20480
	ds_read_b128 v[206:209], v191 offset:21504
	ds_read_b128 v[210:213], v191 offset:22528
	ds_read_b128 v[214:217], v191 offset:23552
	global_load_lds_dwordx4 v[184:185], off
	s_add_i32 m0, s4, 0x2000
	s_add_u32 s14, s58, 0x40000
	v_lshl_add_u64 v[218:219], s[58:59], 0, v[158:159]
	s_addc_u32 s15, s59, 0
	s_add_i32 s4, s78, s62
	global_load_lds_dwordx4 v[218:219], off
	v_lshl_add_u64 v[220:221], s[14:15], 0, v[154:155]
	s_mov_b32 m0, s4
	v_lshl_add_u64 v[222:223], s[60:61], 0, v[156:157]
	global_load_lds_dwordx4 v[220:221], off
	v_lshl_add_u64 v[220:221], s[14:15], 0, v[158:159]
	s_add_i32 m0, s4, 0x2000
	s_nop 0
	global_load_lds_dwordx4 v[220:221], off
	v_lshl_add_u64 v[220:221], s[60:61], 0, v[152:153]
	s_mov_b32 m0, s63
	s_nop 0
	global_load_lds_dwordx4 v[220:221], off
	s_mov_b32 m0, s64
	s_nop 0
	global_load_lds_dwordx4 v[222:223], off
	s_waitcnt vmcnt(8)
	s_waitcnt lgkmcnt(0)
	s_barrier
; #define PG8_STAGE(bufoff, gbase, voff) do { _Pragma("unroll") for (int _i = 0; _i < 2; ++_i) \
;         __builtin_amdgcn_global_load_lds((const unsigned*)((const char*)(gbase) + (voff)[_i]), (PG8_LAS unsigned*)(lds + (bufoff) + ldsw + _i * 8192), 16, 0, 0); } while (0)
; #define PG8_LDA(dst, b, h) do { _Pragma("unroll") for (int m = 0; m < 4; ++m) _Pragma("unroll") for (int k = 0; k < 2; ++k) dst[m][k] = *(const PG8_LAS bf16x8*)(lds + PG8_SA(b, h) + aoff + m * 2048 + k * 1024); } while (0)
; #define PG8_LDB(dst, b, h) do { _Pragma("unroll") for (int n = 0; n < 2; ++n) _Pragma("unroll") for (int k = 0; k < 2; ++k) dst[n][k] = *(const PG8_LAS bf16x8*)(lds + PG8_SB(b, h) + boff + n * 2048 + k * 1024); } while (0)
; #define PG8_MMA(ai, bj, At, Bt) do { __builtin_amdgcn_s_setprio(1); _Pragma("unroll") for (int m = 0; m < 4; ++m) _Pragma("unroll") for (int n = 0; n < 2; ++n) _Pragma("unroll") for (int k = 0; k < 2; ++k) \
;         acc[ai][bj][m][n] = __builtin_amdgcn_mfma_f32_16x16x32_bf16(Bt[n][k], At[m][k], acc[ai][bj][m][n], 0, 0, 0); __builtin_amdgcn_s_setprio(0); } while (0)
; #define PG8_WAIT_V(n) asm volatile("s_waitcnt vmcnt(" #n ")" ::: "memory")
; #define PG8_WAIT_L(n) asm volatile("s_waitcnt lgkmcnt(" #n ")" ::: "memory")
; #define PG8_BAR __builtin_amdgcn_s_barrier()
; #define PG8_SCHED __builtin_amdgcn_sched_barrier(0)
; template <class Epi, class Sched, bool ALIGN_EPI = false, bool SP2 = false>
; __device__ __forceinline__ void gemm_phase(PG8_LAS unsigned char* lds, const Gemm g, const Sched& S, const Epi& E, int tid_in) {
;     ...
;             PG8_WAIT_V(8); PG8_WAIT_L(0); PG8_BAR; PG8_MMA(1, 0, At, B0); PG8_MMA(1, 1, At, B1); PG8_BAR; PG8_SCHED;
;             PG8_LDB(B0, 1, 0); PG8_LDB(B1, 1, 1); PG8_SCHED; PG8_LDA(At, 1, 0); PG8_STAGE(PG8_SA(0, 1), a2 + hstep, voffA);
;             PG8_WAIT_V(8); PG8_WAIT_L(0); PG8_BAR; PG8_MMA(0, 0, At, B0); PG8_MMA(0, 1, At, B1); PG8_BAR; PG8_SCHED;
	s_setprio 1
	s_waitcnt lgkmcnt(0)
	v_mfma_f32_16x16x32_bf16 v[60:63], v[120:123], v[176:179], v[60:63]
	v_mfma_f32_16x16x32_bf16 v[56:59], v[136:139], v[176:179], v[56:59]
	v_mfma_f32_16x16x32_bf16 v[44:47], v[120:123], v[192:195], v[44:47]
	v_mfma_f32_16x16x32_bf16 v[40:43], v[136:139], v[192:195], v[40:43]
	v_mfma_f32_16x16x32_bf16 v[28:31], v[120:123], v[202:205], v[28:31]
	v_mfma_f32_16x16x32_bf16 v[24:27], v[136:139], v[202:205], v[24:27]
	v_mfma_f32_16x16x32_bf16 v[12:15], v[120:123], v[210:213], v[12:15]
	v_mfma_f32_16x16x32_bf16 v[8:11], v[136:139], v[210:213], v[8:11]
	v_mfma_f32_16x16x32_bf16 v[60:63], v[132:135], v[180:183], v[60:63]
	v_mfma_f32_16x16x32_bf16 v[56:59], v[140:143], v[180:183], v[56:59]
	v_mfma_f32_16x16x32_bf16 v[44:47], v[132:135], v[196:199], v[44:47]
	v_mfma_f32_16x16x32_bf16 v[40:43], v[140:143], v[196:199], v[40:43]
	v_mfma_f32_16x16x32_bf16 v[28:31], v[132:135], v[206:209], v[28:31]
	v_mfma_f32_16x16x32_bf16 v[24:27], v[140:143], v[206:209], v[24:27]
	v_mfma_f32_16x16x32_bf16 v[12:15], v[132:135], v[214:217], v[12:15]
	v_mfma_f32_16x16x32_bf16 v[8:11], v[140:143], v[214:217], v[8:11]
	s_setprio 0
	s_setprio 1
	v_mfma_f32_16x16x32_bf16 v[52:55], v[144:147], v[176:179], v[52:55]
	v_mfma_f32_16x16x32_bf16 v[48:51], v[168:171], v[176:179], v[48:51]
	v_mfma_f32_16x16x32_bf16 v[36:39], v[144:147], v[192:195], v[36:39]
	v_mfma_f32_16x16x32_bf16 v[32:35], v[168:171], v[192:195], v[32:35]
	v_mfma_f32_16x16x32_bf16 v[20:23], v[144:147], v[202:205], v[20:23]
	v_mfma_f32_16x16x32_bf16 v[16:19], v[168:171], v[202:205], v[16:19]
	v_mfma_f32_16x16x32_bf16 v[4:7], v[144:147], v[210:213], v[4:7]
	v_mfma_f32_16x16x32_bf16 v[0:3], v[168:171], v[210:213], v[0:3]
	v_mfma_f32_16x16x32_bf16 v[52:55], v[148:151], v[180:183], v[52:55]
	v_mfma_f32_16x16x32_bf16 v[48:51], v[172:175], v[180:183], v[48:51]
	v_mfma_f32_16x16x32_bf16 v[36:39], v[148:151], v[196:199], v[36:39]
	v_mfma_f32_16x16x32_bf16 v[32:35], v[172:175], v[196:199], v[32:35]
	v_mfma_f32_16x16x32_bf16 v[20:23], v[148:151], v[206:209], v[20:23]
	v_mfma_f32_16x16x32_bf16 v[16:19], v[172:175], v[206:209], v[16:19]
	v_mfma_f32_16x16x32_bf16 v[4:7], v[148:151], v[214:217], v[4:7]
	v_mfma_f32_16x16x32_bf16 v[0:3], v[172:175], v[214:217], v[0:3]
	s_setprio 0
	s_barrier
	s_add_i32 s4, 0, 0x18000
	s_add_i32 s5, 0, 0x1c000
	v_add_u32_e32 v140, s4, v187
	v_add_u32_e32 v172, s5, v187
	ds_read_b128 v[120:123], v140
	ds_read_b128 v[132:135], v140 offset:1024
	ds_read_b128 v[136:139], v140 offset:2048
	ds_read_b128 v[140:143], v140 offset:3072
	ds_read_b128 v[144:147], v172
	ds_read_b128 v[148:151], v172 offset:1024
	ds_read_b128 v[168:171], v172 offset:2048
	ds_read_b128 v[172:175], v172 offset:3072
	s_add_u32 s14, s60, 0x40000
	s_addc_u32 s15, s61, 0
	s_mov_b32 m0, s65
	v_lshl_add_u64 v[224:225], s[14:15], 0, v[152:153]
	ds_read_b128 v[176:179], v191 offset:32768
	ds_read_b128 v[180:183], v191 offset:33792
	ds_read_b128 v[192:195], v191 offset:34816
	ds_read_b128 v[196:199], v191 offset:35840
	ds_read_b128 v[202:205], v191 offset:36864
	ds_read_b128 v[206:209], v191 offset:37888
	ds_read_b128 v[210:213], v191 offset:38912
	ds_read_b128 v[214:217], v191 offset:39936
	global_load_lds_dwordx4 v[224:225], off
	v_lshl_add_u64 v[224:225], s[14:15], 0, v[156:157]
	s_mov_b32 m0, s66
	s_nop 0
	global_load_lds_dwordx4 v[224:225], off
	s_waitcnt vmcnt(8)
	s_waitcnt lgkmcnt(0)
	s_barrier
	s_setprio 1
	s_waitcnt lgkmcnt(0)
	v_mfma_f32_16x16x32_bf16 v[128:131], v[120:123], v[176:179], v[128:131]
	v_mfma_f32_16x16x32_bf16 v[124:127], v[136:139], v[176:179], v[124:127]
	v_mfma_f32_16x16x32_bf16 v[108:111], v[120:123], v[192:195], v[108:111]
	v_mfma_f32_16x16x32_bf16 v[104:107], v[136:139], v[192:195], v[104:107]
	v_mfma_f32_16x16x32_bf16 v[92:95], v[120:123], v[202:205], v[92:95]
	v_mfma_f32_16x16x32_bf16 v[88:91], v[136:139], v[202:205], v[88:91]
	v_mfma_f32_16x16x32_bf16 v[76:79], v[120:123], v[210:213], v[76:79]
	v_mfma_f32_16x16x32_bf16 v[72:75], v[136:139], v[210:213], v[72:75]
	v_mfma_f32_16x16x32_bf16 v[128:131], v[132:135], v[180:183], v[128:131]
	v_mfma_f32_16x16x32_bf16 v[124:127], v[140:143], v[180:183], v[124:127]
	v_mfma_f32_16x16x32_bf16 v[108:111], v[132:135], v[196:199], v[108:111]
	v_mfma_f32_16x16x32_bf16 v[104:107], v[140:143], v[196:199], v[104:107]
	v_mfma_f32_16x16x32_bf16 v[92:95], v[132:135], v[206:209], v[92:95]
	v_mfma_f32_16x16x32_bf16 v[88:91], v[140:143], v[206:209], v[88:91]
	v_mfma_f32_16x16x32_bf16 v[76:79], v[132:135], v[214:217], v[76:79]
	v_mfma_f32_16x16x32_bf16 v[72:75], v[140:143], v[214:217], v[72:75]
	s_setprio 0
	s_setprio 1
	v_mfma_f32_16x16x32_bf16 v[116:119], v[144:147], v[176:179], v[116:119]
	v_mfma_f32_16x16x32_bf16 v[112:115], v[168:171], v[176:179], v[112:115]
	v_mfma_f32_16x16x32_bf16 v[100:103], v[144:147], v[192:195], v[100:103]
	v_mfma_f32_16x16x32_bf16 v[96:99], v[168:171], v[192:195], v[96:99]
	v_mfma_f32_16x16x32_bf16 v[84:87], v[144:147], v[202:205], v[84:87]
	v_mfma_f32_16x16x32_bf16 v[80:83], v[168:171], v[202:205], v[80:83]
	v_mfma_f32_16x16x32_bf16 v[68:71], v[144:147], v[210:213], v[68:71]
	v_mfma_f32_16x16x32_bf16 v[64:67], v[168:171], v[210:213], v[64:67]
	v_mfma_f32_16x16x32_bf16 v[116:119], v[148:151], v[180:183], v[116:119]
	v_mfma_f32_16x16x32_bf16 v[112:115], v[172:175], v[180:183], v[112:115]
	v_mfma_f32_16x16x32_bf16 v[100:103], v[148:151], v[196:199], v[100:103]
	v_mfma_f32_16x16x32_bf16 v[96:99], v[172:175], v[196:199], v[96:99]
	v_mfma_f32_16x16x32_bf16 v[84:87], v[148:151], v[206:209], v[84:87]
	v_mfma_f32_16x16x32_bf16 v[80:83], v[172:175], v[206:209], v[80:83]
	v_mfma_f32_16x16x32_bf16 v[68:71], v[148:151], v[214:217], v[68:71]
	v_mfma_f32_16x16x32_bf16 v[64:67], v[172:175], v[214:217], v[64:67]
	s_setprio 0
	s_barrier
; #define PG8_STAGE(bufoff, gbase, voff) do { _Pragma("unroll") for (int _i = 0; _i < 2; ++_i) \
;         __builtin_amdgcn_global_load_lds((const unsigned*)((const char*)(gbase) + (voff)[_i]), (PG8_LAS unsigned*)(lds + (bufoff) + ldsw + _i * 8192), 16, 0, 0); } while (0)
; #define PG8_LDA(dst, b, h) do { _Pragma("unroll") for (int m = 0; m < 4; ++m) _Pragma("unroll") for (int k = 0; k < 2; ++k) dst[m][k] = *(const PG8_LAS bf16x8*)(lds + PG8_SA(b, h) + aoff + m * 2048 + k * 1024); } while (0)
; #define PG8_MMA(ai, bj, At, Bt) do { __builtin_amdgcn_s_setprio(1); _Pragma("unroll") for (int m = 0; m < 4; ++m) _Pragma("unroll") for (int n = 0; n < 2; ++n) _Pragma("unroll") for (int k = 0; k < 2; ++k) \
;         acc[ai][bj][m][n] = __builtin_amdgcn_mfma_f32_16x16x32_bf16(Bt[n][k], At[m][k], acc[ai][bj][m][n], 0, 0, 0); __builtin_amdgcn_s_setprio(0); } while (0)
; #define PG8_WAIT_V(n) asm volatile("s_waitcnt vmcnt(" #n ")" ::: "memory")
; #define PG8_WAIT_L(n) asm volatile("s_waitcnt lgkmcnt(" #n ")" ::: "memory")
; #define PG8_BAR __builtin_amdgcn_s_barrier()
; #define PG8_SCHED __builtin_amdgcn_sched_barrier(0)
; template <class Epi, class Sched, bool ALIGN_EPI = false, bool SP2 = false>
; __device__ __forceinline__ void gemm_phase(PG8_LAS unsigned char* lds, const Gemm g, const Sched& S, const Epi& E, int tid_in) {
;     ...
;             PG8_LDA(At, 1, 1); PG8_STAGE(PG8_SB(1, 0), b3, voffB); PG8_STAGE(PG8_SB(1, 1), b3 + hstep, voffB); PG8_STAGE(PG8_SA(1, 0), a3, voffA);
;             PG8_WAIT_V(8); PG8_WAIT_L(0); PG8_BAR; PG8_MMA(1, 0, At, B0); PG8_MMA(1, 1, At, B1); PG8_BAR; PG8_SCHED;
	s_add_i32 s4, s4, s62
	v_lshl_add_u64 v[184:185], v[184:185], 0, s[26:27]
	s_mov_b32 m0, s4
	ds_read_b128 v[176:179], v191 offset:49152
	ds_read_b128 v[180:183], v191 offset:50176
	ds_read_b128 v[192:195], v191 offset:51200
	ds_read_b128 v[196:199], v191 offset:52224
	ds_read_b128 v[202:205], v191 offset:53248
	ds_read_b128 v[206:209], v191 offset:54272
	ds_read_b128 v[210:213], v191 offset:55296
	ds_read_b128 v[214:217], v191 offset:56320
	global_load_lds_dwordx4 v[184:185], off
	s_add_i32 m0, s4, 0x2000
	s_add_u32 s14, s58, 0x40080
	v_lshl_add_u64 v[184:185], v[218:219], 0, s[26:27]
	s_addc_u32 s15, s59, 0
	s_add_i32 s4, s5, s62
	global_load_lds_dwordx4 v[184:185], off
	v_lshl_add_u64 v[184:185], s[14:15], 0, v[154:155]
	s_mov_b32 m0, s4
	s_nop 0
	global_load_lds_dwordx4 v[184:185], off
	v_lshl_add_u64 v[184:185], s[14:15], 0, v[158:159]
	s_add_i32 m0, s4, 0x2000
	s_nop 0
	global_load_lds_dwordx4 v[184:185], off
	v_lshl_add_u64 v[184:185], v[220:221], 0, s[26:27]
	s_mov_b32 m0, s68
	s_nop 0
	global_load_lds_dwordx4 v[184:185], off
	v_lshl_add_u64 v[184:185], v[222:223], 0, s[26:27]
	s_mov_b32 m0, s69
	s_nop 0
	global_load_lds_dwordx4 v[184:185], off
	s_waitcnt vmcnt(8)
	s_waitcnt lgkmcnt(0)
	s_barrier
	s_setprio 1
	s_waitcnt lgkmcnt(0)
	v_mfma_f32_16x16x32_bf16 v[60:63], v[120:123], v[176:179], v[60:63]
	v_mfma_f32_16x16x32_bf16 v[56:59], v[136:139], v[176:179], v[56:59]
	v_mfma_f32_16x16x32_bf16 v[44:47], v[120:123], v[192:195], v[44:47]
	v_mfma_f32_16x16x32_bf16 v[40:43], v[136:139], v[192:195], v[40:43]
	v_mfma_f32_16x16x32_bf16 v[28:31], v[120:123], v[202:205], v[28:31]
	v_mfma_f32_16x16x32_bf16 v[24:27], v[136:139], v[202:205], v[24:27]
	v_mfma_f32_16x16x32_bf16 v[12:15], v[120:123], v[210:213], v[12:15]
	v_mfma_f32_16x16x32_bf16 v[8:11], v[136:139], v[210:213], v[8:11]
	v_mfma_f32_16x16x32_bf16 v[60:63], v[132:135], v[180:183], v[60:63]
	v_mfma_f32_16x16x32_bf16 v[56:59], v[140:143], v[180:183], v[56:59]
	v_mfma_f32_16x16x32_bf16 v[44:47], v[132:135], v[196:199], v[44:47]
	v_mfma_f32_16x16x32_bf16 v[40:43], v[140:143], v[196:199], v[40:43]
	v_mfma_f32_16x16x32_bf16 v[28:31], v[132:135], v[206:209], v[28:31]
	v_mfma_f32_16x16x32_bf16 v[24:27], v[140:143], v[206:209], v[24:27]
	v_mfma_f32_16x16x32_bf16 v[12:15], v[132:135], v[214:217], v[12:15]
	v_mfma_f32_16x16x32_bf16 v[8:11], v[140:143], v[214:217], v[8:11]
	s_setprio 0
	s_setprio 1
	v_mfma_f32_16x16x32_bf16 v[52:55], v[144:147], v[176:179], v[52:55]
	v_mfma_f32_16x16x32_bf16 v[48:51], v[168:171], v[176:179], v[48:51]
	v_mfma_f32_16x16x32_bf16 v[36:39], v[144:147], v[192:195], v[36:39]
	v_mfma_f32_16x16x32_bf16 v[32:35], v[168:171], v[192:195], v[32:35]
	v_mfma_f32_16x16x32_bf16 v[20:23], v[144:147], v[202:205], v[20:23]
	v_mfma_f32_16x16x32_bf16 v[16:19], v[168:171], v[202:205], v[16:19]
	v_mfma_f32_16x16x32_bf16 v[4:7], v[144:147], v[210:213], v[4:7]
	v_mfma_f32_16x16x32_bf16 v[0:3], v[168:171], v[210:213], v[0:3]
	v_mfma_f32_16x16x32_bf16 v[52:55], v[148:151], v[180:183], v[52:55]
	v_mfma_f32_16x16x32_bf16 v[48:51], v[172:175], v[180:183], v[48:51]
	v_mfma_f32_16x16x32_bf16 v[36:39], v[148:151], v[196:199], v[36:39]
	v_mfma_f32_16x16x32_bf16 v[32:35], v[172:175], v[196:199], v[32:35]
	v_mfma_f32_16x16x32_bf16 v[20:23], v[148:151], v[206:209], v[20:23]
	v_mfma_f32_16x16x32_bf16 v[16:19], v[172:175], v[206:209], v[16:19]
	v_mfma_f32_16x16x32_bf16 v[4:7], v[148:151], v[214:217], v[4:7]
	v_mfma_f32_16x16x32_bf16 v[0:3], v[172:175], v[214:217], v[0:3]
	s_setprio 0
	s_barrier
	s_add_i32 vcc_lo, vcc_lo, 2
	s_add_u32 s80, s80, 0x100
	s_addc_u32 s81, s81, 0
	s_add_u32 s56, s56, 0x100
	s_addc_u32 s57, s57, 0
	s_cmp_gt_u32 vcc_lo, 13
	s_cbranch_scc0 .LBB0_912
.Lpost6:
	s_and_b64 vcc, exec, s[44:45]
	s_cbranch_vccz .LBB0_915
	s_barrier

; #define PG8_STAGE(bufoff, gbase, voff) do { _Pragma("unroll") for (int _i = 0; _i < 2; ++_i) \
;         __builtin_amdgcn_global_load_lds((const unsigned*)((const char*)(gbase) + (voff)[_i]), (PG8_LAS unsigned*)(lds + (bufoff) + ldsw + _i * 8192), 16, 0, 0); } while (0)
; #define PG8_LDA(dst, b, h) do { _Pragma("unroll") for (int m = 0; m < 4; ++m) _Pragma("unroll") for (int k = 0; k < 2; ++k) dst[m][k] = *(const PG8_LAS bf16x8*)(lds + PG8_SA(b, h) + aoff + m * 2048 + k * 1024); } while (0)
; #define PG8_LDB(dst, b, h) do { _Pragma("unroll") for (int n = 0; n < 2; ++n) _Pragma("unroll") for (int k = 0; k < 2; ++k) dst[n][k] = *(const PG8_LAS bf16x8*)(lds + PG8_SB(b, h) + boff + n * 2048 + k * 1024); } while (0)
; #define PG8_MMA(ai, bj, At, Bt) do { __builtin_amdgcn_s_setprio(1); _Pragma("unroll") for (int m = 0; m < 4; ++m) _Pragma("unroll") for (int n = 0; n < 2; ++n) _Pragma("unroll") for (int k = 0; k < 2; ++k) \
;         acc[ai][bj][m][n] = __builtin_amdgcn_mfma_f32_16x16x32_bf16(Bt[n][k], At[m][k], acc[ai][bj][m][n], 0, 0, 0); __builtin_amdgcn_s_setprio(0); } while (0)
; #define PG8_WAIT_V(n) asm volatile("s_waitcnt vmcnt(" #n ")" ::: "memory")
; #define PG8_WAIT_L(n) asm volatile("s_waitcnt lgkmcnt(" #n ")" ::: "memory")
; template <class Epi, class Sched, bool ALIGN_EPI = false, bool SP2 = false>
; __device__ __forceinline__ void gemm_phase(PG8_LAS unsigned char* lds, const Gemm g, const Sched& S, const Epi& E, int tid_in) {
;     ...
;             const bool last = (t == nt - 2);
;             const char* a1 = cA + (size_t)(t + 1) * kstep;
;             const char* a2 = last ? nA : cA + (size_t)(t + 2) * kstep; const char* b2 = last ? nB : cB + (size_t)(t + 2) * kstep;
;             const char* a3 = a2 + kstep; const char* b3 = b2 + kstep;
;             if (last && has_next) S.a_ready(nxt);
;             if constexpr (SP2) {
;             PG8_LDB(B0, 0, 0); PG8_LDB(B1, 0, 1); PG8_SCHED; PG8_LDA(At, 0, 0); PG8_STAGE(PG8_SA(1, 1), a1 + hstep, voffA);
;             PG8_WAIT_V(8); PG8_WAIT_L(0); PG8_BAR; PG8_MMA(0, 0, At, B0); PG8_MMA(0, 1, At, B1); PG8_BAR; PG8_SCHED;
;             PG8_LDA(At, 0, 1); PG8_STAGE(PG8_SB(0, 0), b2, voffB); PG8_STAGE(PG8_SB(0, 1), b2 + hstep, voffB); PG8_STAGE(PG8_SA(0, 0), a2, voffA);
;             PG8_WAIT_V(8); PG8_WAIT_L(0); PG8_BAR; PG8_MMA(1, 0, At, B0); PG8_MMA(1, 1, At, B1); PG8_BAR; PG8_SCHED;
.Lpk6:
	s_or_b64 s[98:99], s[16:17], 1
	v_lshl_add_u64 v[184:185], s[56:57], 0, v[162:163]
	s_add_i32 m0, s63, 0xc000
	ds_read_b128 v[176:179], v191
	ds_read_b128 v[180:183], v191 offset:1024
	ds_read_b128 v[192:195], v191 offset:2048
	ds_read_b128 v[196:199], v191 offset:3072
	ds_read_b128 v[202:205], v191 offset:4096
	ds_read_b128 v[206:209], v191 offset:5120
	ds_read_b128 v[210:213], v191 offset:6144
	ds_read_b128 v[214:217], v191 offset:7168
	global_load_lds_dwordx4 v[184:185], off
	v_lshl_add_u64 v[184:185], s[56:57], 0, v[160:161]
	s_add_i32 m0, s63, 0xe000
	s_nop 0
	global_load_lds_dwordx4 v[184:185], off
	s_waitcnt vmcnt(8)
	s_waitcnt lgkmcnt(0)
	s_barrier
	s_setprio 1
	s_waitcnt lgkmcnt(0)
	v_mfma_f32_16x16x32_bf16 v[128:131], v[120:123], v[176:179], v[128:131]
	v_mfma_f32_16x16x32_bf16 v[124:127], v[136:139], v[176:179], v[124:127]
	v_mfma_f32_16x16x32_bf16 v[108:111], v[120:123], v[192:195], v[108:111]
	v_mfma_f32_16x16x32_bf16 v[104:107], v[136:139], v[192:195], v[104:107]
	v_mfma_f32_16x16x32_bf16 v[92:95], v[120:123], v[202:205], v[92:95]
	v_mfma_f32_16x16x32_bf16 v[88:91], v[136:139], v[202:205], v[88:91]
	v_mfma_f32_16x16x32_bf16 v[76:79], v[120:123], v[210:213], v[76:79]
	v_mfma_f32_16x16x32_bf16 v[72:75], v[136:139], v[210:213], v[72:75]
	v_mfma_f32_16x16x32_bf16 v[128:131], v[132:135], v[180:183], v[128:131]
	v_mfma_f32_16x16x32_bf16 v[124:127], v[140:143], v[180:183], v[124:127]
	v_mfma_f32_16x16x32_bf16 v[108:111], v[132:135], v[196:199], v[108:111]
	v_mfma_f32_16x16x32_bf16 v[104:107], v[140:143], v[196:199], v[104:107]
	v_mfma_f32_16x16x32_bf16 v[92:95], v[132:135], v[206:209], v[92:95]
	v_mfma_f32_16x16x32_bf16 v[88:91], v[140:143], v[206:209], v[88:91]
	v_mfma_f32_16x16x32_bf16 v[76:79], v[132:135], v[214:217], v[76:79]
	v_mfma_f32_16x16x32_bf16 v[72:75], v[140:143], v[214:217], v[72:75]
	s_setprio 0
	s_setprio 1
	v_mfma_f32_16x16x32_bf16 v[116:119], v[144:147], v[176:179], v[116:119]
	v_mfma_f32_16x16x32_bf16 v[112:115], v[168:171], v[176:179], v[112:115]
	v_mfma_f32_16x16x32_bf16 v[100:103], v[144:147], v[192:195], v[100:103]
	v_mfma_f32_16x16x32_bf16 v[96:99], v[168:171], v[192:195], v[96:99]
	v_mfma_f32_16x16x32_bf16 v[84:87], v[144:147], v[202:205], v[84:87]
	v_mfma_f32_16x16x32_bf16 v[80:83], v[168:171], v[202:205], v[80:83]
	v_mfma_f32_16x16x32_bf16 v[68:71], v[144:147], v[210:213], v[68:71]
	v_mfma_f32_16x16x32_bf16 v[64:67], v[168:171], v[210:213], v[64:67]
	v_mfma_f32_16x16x32_bf16 v[116:119], v[148:151], v[180:183], v[116:119]
	v_mfma_f32_16x16x32_bf16 v[112:115], v[172:175], v[180:183], v[112:115]
	v_mfma_f32_16x16x32_bf16 v[100:103], v[148:151], v[196:199], v[100:103]
	v_mfma_f32_16x16x32_bf16 v[96:99], v[172:175], v[196:199], v[96:99]
	v_mfma_f32_16x16x32_bf16 v[84:87], v[148:151], v[206:209], v[84:87]
	v_mfma_f32_16x16x32_bf16 v[80:83], v[172:175], v[206:209], v[80:83]
	v_mfma_f32_16x16x32_bf16 v[68:71], v[148:151], v[214:217], v[68:71]
	v_mfma_f32_16x16x32_bf16 v[64:67], v[172:175], v[214:217], v[64:67]
	s_setprio 0
	s_barrier
	s_add_i32 s4, s73, s62
	v_lshl_add_u64 v[184:185], s[58:59], 0, v[154:155]
	s_mov_b32 m0, s4
	ds_read_b128 v[176:179], v191 offset:16384
	ds_read_b128 v[180:183], v191 offset:17408
	ds_read_b128 v[192:195], v191 offset:18432
	ds_read_b128 v[196:199], v191 offset:19456
	ds_read_b128 v[202:205], v191 offset:20480
	ds_read_b128 v[206:209], v191 offset:21504
	ds_read_b128 v[210:213], v191 offset:22528
	ds_read_b128 v[214:217], v191 offset:23552
	s_mov_b64 exec, s[98:99]
	global_load_lds_dwordx4 v[184:185], off
	s_mov_b64 exec, -1
	s_add_i32 m0, s4, 0x2000
	s_add_u32 s14, s58, 0x40000
	v_lshl_add_u64 v[218:219], s[58:59], 0, v[158:159]
	s_addc_u32 s15, s59, 0
	s_add_i32 s4, s78, s62
	s_mov_b64 exec, s[98:99]
	global_load_lds_dwordx4 v[218:219], off
	s_mov_b64 exec, -1
	v_lshl_add_u64 v[220:221], s[14:15], 0, v[154:155]
	s_mov_b32 m0, s4
	v_lshl_add_u64 v[222:223], s[60:61], 0, v[156:157]
	s_mov_b64 exec, s[98:99]
	global_load_lds_dwordx4 v[220:221], off
	s_mov_b64 exec, -1
	v_lshl_add_u64 v[220:221], s[14:15], 0, v[158:159]
	s_add_i32 m0, s4, 0x2000
	s_nop 0
	s_mov_b64 exec, s[98:99]
	global_load_lds_dwordx4 v[220:221], off
	s_mov_b64 exec, -1
	v_lshl_add_u64 v[220:221], s[60:61], 0, v[152:153]
	s_mov_b32 m0, s63
	s_nop 0
	s_mov_b64 exec, s[98:99]
	global_load_lds_dwordx4 v[220:221], off
	s_mov_b64 exec, -1
	s_mov_b32 m0, s64
	s_nop 0
	s_mov_b64 exec, s[98:99]
	global_load_lds_dwordx4 v[222:223], off
	s_mov_b64 exec, -1
	s_waitcnt vmcnt(8)
	s_waitcnt lgkmcnt(0)
	s_barrier
; #define PG8_STAGE(bufoff, gbase, voff) do { _Pragma("unroll") for (int _i = 0; _i < 2; ++_i) \
;         __builtin_amdgcn_global_load_lds((const unsigned*)((const char*)(gbase) + (voff)[_i]), (PG8_LAS unsigned*)(lds + (bufoff) + ldsw + _i * 8192), 16, 0, 0); } while (0)
; #define PG8_LDA(dst, b, h) do { _Pragma("unroll") for (int m = 0; m < 4; ++m) _Pragma("unroll") for (int k = 0; k < 2; ++k) dst[m][k] = *(const PG8_LAS bf16x8*)(lds + PG8_SA(b, h) + aoff + m * 2048 + k * 1024); } while (0)
; #define PG8_LDB(dst, b, h) do { _Pragma("unroll") for (int n = 0; n < 2; ++n) _Pragma("unroll") for (int k = 0; k < 2; ++k) dst[n][k] = *(const PG8_LAS bf16x8*)(lds + PG8_SB(b, h) + boff + n * 2048 + k * 1024); } while (0)
; #define PG8_MMA(ai, bj, At, Bt) do { __builtin_amdgcn_s_setprio(1); _Pragma("unroll") for (int m = 0; m < 4; ++m) _Pragma("unroll") for (int n = 0; n < 2; ++n) _Pragma("unroll") for (int k = 0; k < 2; ++k) \
;         acc[ai][bj][m][n] = __builtin_amdgcn_mfma_f32_16x16x32_bf16(Bt[n][k], At[m][k], acc[ai][bj][m][n], 0, 0, 0); __builtin_amdgcn_s_setprio(0); } while (0)
; #define PG8_WAIT_V(n) asm volatile("s_waitcnt vmcnt(" #n ")" ::: "memory")
; #define PG8_WAIT_L(n) asm volatile("s_waitcnt lgkmcnt(" #n ")" ::: "memory")
; #define PG8_BAR __builtin_amdgcn_s_barrier()
; #define PG8_SCHED __builtin_amdgcn_sched_barrier(0)
; template <class Epi, class Sched, bool ALIGN_EPI = false, bool SP2 = false>
; __device__ __forceinline__ void gemm_phase(PG8_LAS unsigned char* lds, const Gemm g, const Sched& S, const Epi& E, int tid_in) {
;     ...
;             PG8_WAIT_V(8); PG8_WAIT_L(0); PG8_BAR; PG8_MMA(1, 0, At, B0); PG8_MMA(1, 1, At, B1); PG8_BAR; PG8_SCHED;
;             PG8_LDB(B0, 1, 0); PG8_LDB(B1, 1, 1); PG8_SCHED; PG8_LDA(At, 1, 0); PG8_STAGE(PG8_SA(0, 1), a2 + hstep, voffA);
;             PG8_WAIT_V(8); PG8_WAIT_L(0); PG8_BAR; PG8_MMA(0, 0, At, B0); PG8_MMA(0, 1, At, B1); PG8_BAR; PG8_SCHED;
	s_setprio 1
	s_waitcnt lgkmcnt(0)
	v_mfma_f32_16x16x32_bf16 v[60:63], v[120:123], v[176:179], v[60:63]
	v_mfma_f32_16x16x32_bf16 v[56:59], v[136:139], v[176:179], v[56:59]
	v_mfma_f32_16x16x32_bf16 v[44:47], v[120:123], v[192:195], v[44:47]
	v_mfma_f32_16x16x32_bf16 v[40:43], v[136:139], v[192:195], v[40:43]
	v_mfma_f32_16x16x32_bf16 v[28:31], v[120:123], v[202:205], v[28:31]
	v_mfma_f32_16x16x32_bf16 v[24:27], v[136:139], v[202:205], v[24:27]
	v_mfma_f32_16x16x32_bf16 v[12:15], v[120:123], v[210:213], v[12:15]
	v_mfma_f32_16x16x32_bf16 v[8:11], v[136:139], v[210:213], v[8:11]
	v_mfma_f32_16x16x32_bf16 v[60:63], v[132:135], v[180:183], v[60:63]
	v_mfma_f32_16x16x32_bf16 v[56:59], v[140:143], v[180:183], v[56:59]
	v_mfma_f32_16x16x32_bf16 v[44:47], v[132:135], v[196:199], v[44:47]
	v_mfma_f32_16x16x32_bf16 v[40:43], v[140:143], v[196:199], v[40:43]
	v_mfma_f32_16x16x32_bf16 v[28:31], v[132:135], v[206:209], v[28:31]
	v_mfma_f32_16x16x32_bf16 v[24:27], v[140:143], v[206:209], v[24:27]
	v_mfma_f32_16x16x32_bf16 v[12:15], v[132:135], v[214:217], v[12:15]
	v_mfma_f32_16x16x32_bf16 v[8:11], v[140:143], v[214:217], v[8:11]
	s_setprio 0
	s_setprio 1
	v_mfma_f32_16x16x32_bf16 v[52:55], v[144:147], v[176:179], v[52:55]
	v_mfma_f32_16x16x32_bf16 v[48:51], v[168:171], v[176:179], v[48:51]
	v_mfma_f32_16x16x32_bf16 v[36:39], v[144:147], v[192:195], v[36:39]
	v_mfma_f32_16x16x32_bf16 v[32:35], v[168:171], v[192:195], v[32:35]
	v_mfma_f32_16x16x32_bf16 v[20:23], v[144:147], v[202:205], v[20:23]
	v_mfma_f32_16x16x32_bf16 v[16:19], v[168:171], v[202:205], v[16:19]
	v_mfma_f32_16x16x32_bf16 v[4:7], v[144:147], v[210:213], v[4:7]
	v_mfma_f32_16x16x32_bf16 v[0:3], v[168:171], v[210:213], v[0:3]
	v_mfma_f32_16x16x32_bf16 v[52:55], v[148:151], v[180:183], v[52:55]
	v_mfma_f32_16x16x32_bf16 v[48:51], v[172:175], v[180:183], v[48:51]
	v_mfma_f32_16x16x32_bf16 v[36:39], v[148:151], v[196:199], v[36:39]
	v_mfma_f32_16x16x32_bf16 v[32:35], v[172:175], v[196:199], v[32:35]
	v_mfma_f32_16x16x32_bf16 v[20:23], v[148:151], v[206:209], v[20:23]
	v_mfma_f32_16x16x32_bf16 v[16:19], v[172:175], v[206:209], v[16:19]
	v_mfma_f32_16x16x32_bf16 v[4:7], v[148:151], v[214:217], v[4:7]
	v_mfma_f32_16x16x32_bf16 v[0:3], v[172:175], v[214:217], v[0:3]
	s_setprio 0
	s_barrier
	s_add_i32 s4, 0, 0x18000
	s_add_i32 s5, 0, 0x1c000
	v_add_u32_e32 v140, s4, v187
	v_add_u32_e32 v172, s5, v187
	ds_read_b128 v[120:123], v140
	ds_read_b128 v[132:135], v140 offset:1024
	ds_read_b128 v[136:139], v140 offset:2048
	ds_read_b128 v[140:143], v140 offset:3072
	ds_read_b128 v[144:147], v172
	ds_read_b128 v[148:151], v172 offset:1024
	ds_read_b128 v[168:171], v172 offset:2048
	ds_read_b128 v[172:175], v172 offset:3072
	s_add_u32 s14, s60, 0x40000
	s_addc_u32 s15, s61, 0
	s_mov_b32 m0, s65
	v_lshl_add_u64 v[224:225], s[14:15], 0, v[152:153]
	ds_read_b128 v[176:179], v191 offset:32768
	ds_read_b128 v[180:183], v191 offset:33792
	ds_read_b128 v[192:195], v191 offset:34816
	ds_read_b128 v[196:199], v191 offset:35840
	ds_read_b128 v[202:205], v191 offset:36864
	ds_read_b128 v[206:209], v191 offset:37888
	ds_read_b128 v[210:213], v191 offset:38912
	ds_read_b128 v[214:217], v191 offset:39936
	s_mov_b64 exec, s[98:99]
	global_load_lds_dwordx4 v[224:225], off
	s_mov_b64 exec, -1
	v_lshl_add_u64 v[224:225], s[14:15], 0, v[156:157]
	s_mov_b32 m0, s66
	s_nop 0
	s_mov_b64 exec, s[98:99]
	global_load_lds_dwordx4 v[224:225], off
	s_mov_b64 exec, -1
	s_waitcnt vmcnt(8)
	s_waitcnt lgkmcnt(0)
	s_barrier
	s_setprio 1
	s_waitcnt lgkmcnt(0)
	v_mfma_f32_16x16x32_bf16 v[128:131], v[120:123], v[176:179], v[128:131]
	v_mfma_f32_16x16x32_bf16 v[124:127], v[136:139], v[176:179], v[124:127]
	v_mfma_f32_16x16x32_bf16 v[108:111], v[120:123], v[192:195], v[108:111]
	v_mfma_f32_16x16x32_bf16 v[104:107], v[136:139], v[192:195], v[104:107]
	v_mfma_f32_16x16x32_bf16 v[92:95], v[120:123], v[202:205], v[92:95]
	v_mfma_f32_16x16x32_bf16 v[88:91], v[136:139], v[202:205], v[88:91]
	v_mfma_f32_16x16x32_bf16 v[76:79], v[120:123], v[210:213], v[76:79]
	v_mfma_f32_16x16x32_bf16 v[72:75], v[136:139], v[210:213], v[72:75]
	v_mfma_f32_16x16x32_bf16 v[128:131], v[132:135], v[180:183], v[128:131]
	v_mfma_f32_16x16x32_bf16 v[124:127], v[140:143], v[180:183], v[124:127]
	v_mfma_f32_16x16x32_bf16 v[108:111], v[132:135], v[196:199], v[108:111]
	v_mfma_f32_16x16x32_bf16 v[104:107], v[140:143], v[196:199], v[104:107]
	v_mfma_f32_16x16x32_bf16 v[92:95], v[132:135], v[206:209], v[92:95]
	v_mfma_f32_16x16x32_bf16 v[88:91], v[140:143], v[206:209], v[88:91]
	v_mfma_f32_16x16x32_bf16 v[76:79], v[132:135], v[214:217], v[76:79]
	v_mfma_f32_16x16x32_bf16 v[72:75], v[140:143], v[214:217], v[72:75]
	s_setprio 0
	s_setprio 1
	v_mfma_f32_16x16x32_bf16 v[116:119], v[144:147], v[176:179], v[116:119]
	v_mfma_f32_16x16x32_bf16 v[112:115], v[168:171], v[176:179], v[112:115]
	v_mfma_f32_16x16x32_bf16 v[100:103], v[144:147], v[192:195], v[100:103]
	v_mfma_f32_16x16x32_bf16 v[96:99], v[168:171], v[192:195], v[96:99]
	v_mfma_f32_16x16x32_bf16 v[84:87], v[144:147], v[202:205], v[84:87]
	v_mfma_f32_16x16x32_bf16 v[80:83], v[168:171], v[202:205], v[80:83]
	v_mfma_f32_16x16x32_bf16 v[68:71], v[144:147], v[210:213], v[68:71]
	v_mfma_f32_16x16x32_bf16 v[64:67], v[168:171], v[210:213], v[64:67]
	v_mfma_f32_16x16x32_bf16 v[116:119], v[148:151], v[180:183], v[116:119]
	v_mfma_f32_16x16x32_bf16 v[112:115], v[172:175], v[180:183], v[112:115]
	v_mfma_f32_16x16x32_bf16 v[100:103], v[148:151], v[196:199], v[100:103]
	v_mfma_f32_16x16x32_bf16 v[96:99], v[172:175], v[196:199], v[96:99]
	v_mfma_f32_16x16x32_bf16 v[84:87], v[148:151], v[206:209], v[84:87]
	v_mfma_f32_16x16x32_bf16 v[80:83], v[172:175], v[206:209], v[80:83]
	v_mfma_f32_16x16x32_bf16 v[68:71], v[148:151], v[214:217], v[68:71]
	v_mfma_f32_16x16x32_bf16 v[64:67], v[172:175], v[214:217], v[64:67]
	s_setprio 0
	s_barrier
; #define PG8_STAGE(bufoff, gbase, voff) do { _Pragma("unroll") for (int _i = 0; _i < 2; ++_i) \
;         __builtin_amdgcn_global_load_lds((const unsigned*)((const char*)(gbase) + (voff)[_i]), (PG8_LAS unsigned*)(lds + (bufoff) + ldsw + _i * 8192), 16, 0, 0); } while (0)
; #define PG8_LDA(dst, b, h) do { _Pragma("unroll") for (int m = 0; m < 4; ++m) _Pragma("unroll") for (int k = 0; k < 2; ++k) dst[m][k] = *(const PG8_LAS bf16x8*)(lds + PG8_SA(b, h) + aoff + m * 2048 + k * 1024); } while (0)
; #define PG8_MMA(ai, bj, At, Bt) do { __builtin_amdgcn_s_setprio(1); _Pragma("unroll") for (int m = 0; m < 4; ++m) _Pragma("unroll") for (int n = 0; n < 2; ++n) _Pragma("unroll") for (int k = 0; k < 2; ++k) \
;         acc[ai][bj][m][n] = __builtin_amdgcn_mfma_f32_16x16x32_bf16(Bt[n][k], At[m][k], acc[ai][bj][m][n], 0, 0, 0); __builtin_amdgcn_s_setprio(0); } while (0)
; #define PG8_WAIT_V(n) asm volatile("s_waitcnt vmcnt(" #n ")" ::: "memory")
; #define PG8_WAIT_L(n) asm volatile("s_waitcnt lgkmcnt(" #n ")" ::: "memory")
; #define PG8_BAR __builtin_amdgcn_s_barrier()
; #define PG8_SCHED __builtin_amdgcn_sched_barrier(0)
; template <class Epi, class Sched, bool ALIGN_EPI = false, bool SP2 = false>
; __device__ __forceinline__ void gemm_phase(PG8_LAS unsigned char* lds, const Gemm g, const Sched& S, const Epi& E, int tid_in) {
;     ...
;             PG8_LDA(At, 1, 1); PG8_STAGE(PG8_SB(1, 0), b3, voffB); PG8_STAGE(PG8_SB(1, 1), b3 + hstep, voffB); PG8_STAGE(PG8_SA(1, 0), a3, voffA);
;             PG8_WAIT_V(8); PG8_WAIT_L(0); PG8_BAR; PG8_MMA(1, 0, At, B0); PG8_MMA(1, 1, At, B1); PG8_BAR; PG8_SCHED;
	s_add_i32 s4, s4, s62
	v_lshl_add_u64 v[184:185], v[184:185], 0, s[26:27]
	s_mov_b32 m0, s4
	ds_read_b128 v[176:179], v191 offset:49152
	ds_read_b128 v[180:183], v191 offset:50176
	ds_read_b128 v[192:195], v191 offset:51200
	ds_read_b128 v[196:199], v191 offset:52224
	ds_read_b128 v[202:205], v191 offset:53248
	ds_read_b128 v[206:209], v191 offset:54272
	ds_read_b128 v[210:213], v191 offset:55296
	ds_read_b128 v[214:217], v191 offset:56320
	s_mov_b64 exec, s[98:99]
	global_load_lds_dwordx4 v[184:185], off
	s_mov_b64 exec, -1
	s_add_i32 m0, s4, 0x2000
	s_add_u32 s14, s58, 0x40080
	v_lshl_add_u64 v[184:185], v[218:219], 0, s[26:27]
	s_addc_u32 s15, s59, 0
	s_add_i32 s4, s5, s62
	s_mov_b64 exec, s[98:99]
	global_load_lds_dwordx4 v[184:185], off
	s_mov_b64 exec, -1
	v_lshl_add_u64 v[184:185], s[14:15], 0, v[154:155]
	s_mov_b32 m0, s4
	s_nop 0
	s_mov_b64 exec, s[98:99]
	global_load_lds_dwordx4 v[184:185], off
	s_mov_b64 exec, -1
	v_lshl_add_u64 v[184:185], s[14:15], 0, v[158:159]
	s_add_i32 m0, s4, 0x2000
	s_nop 0
	s_mov_b64 exec, s[98:99]
	global_load_lds_dwordx4 v[184:185], off
	s_mov_b64 exec, -1
	v_lshl_add_u64 v[184:185], v[220:221], 0, s[26:27]
	s_mov_b32 m0, s68
	s_nop 0
	s_mov_b64 exec, s[98:99]
	global_load_lds_dwordx4 v[184:185], off
	s_mov_b64 exec, -1
	v_lshl_add_u64 v[184:185], v[222:223], 0, s[26:27]
	s_mov_b32 m0, s69
	s_nop 0
	s_mov_b64 exec, s[98:99]
	global_load_lds_dwordx4 v[184:185], off
	s_mov_b64 exec, -1
	s_waitcnt vmcnt(8)
	s_waitcnt lgkmcnt(0)
	s_barrier
	s_setprio 1
	s_waitcnt lgkmcnt(0)
	v_mfma_f32_16x16x32_bf16 v[60:63], v[120:123], v[176:179], v[60:63]
	v_mfma_f32_16x16x32_bf16 v[56:59], v[136:139], v[176:179], v[56:59]
	v_mfma_f32_16x16x32_bf16 v[44:47], v[120:123], v[192:195], v[44:47]
	v_mfma_f32_16x16x32_bf16 v[40:43], v[136:139], v[192:195], v[40:43]
	v_mfma_f32_16x16x32_bf16 v[28:31], v[120:123], v[202:205], v[28:31]
	v_mfma_f32_16x16x32_bf16 v[24:27], v[136:139], v[202:205], v[24:27]
	v_mfma_f32_16x16x32_bf16 v[12:15], v[120:123], v[210:213], v[12:15]
	v_mfma_f32_16x16x32_bf16 v[8:11], v[136:139], v[210:213], v[8:11]
	v_mfma_f32_16x16x32_bf16 v[60:63], v[132:135], v[180:183], v[60:63]
	v_mfma_f32_16x16x32_bf16 v[56:59], v[140:143], v[180:183], v[56:59]
	v_mfma_f32_16x16x32_bf16 v[44:47], v[132:135], v[196:199], v[44:47]
	v_mfma_f32_16x16x32_bf16 v[40:43], v[140:143], v[196:199], v[40:43]
	v_mfma_f32_16x16x32_bf16 v[28:31], v[132:135], v[206:209], v[28:31]
	v_mfma_f32_16x16x32_bf16 v[24:27], v[140:143], v[206:209], v[24:27]
	v_mfma_f32_16x16x32_bf16 v[12:15], v[132:135], v[214:217], v[12:15]
	v_mfma_f32_16x16x32_bf16 v[8:11], v[140:143], v[214:217], v[8:11]
	s_setprio 0
	s_setprio 1
	v_mfma_f32_16x16x32_bf16 v[52:55], v[144:147], v[176:179], v[52:55]
	v_mfma_f32_16x16x32_bf16 v[48:51], v[168:171], v[176:179], v[48:51]
	v_mfma_f32_16x16x32_bf16 v[36:39], v[144:147], v[192:195], v[36:39]
	v_mfma_f32_16x16x32_bf16 v[32:35], v[168:171], v[192:195], v[32:35]
	v_mfma_f32_16x16x32_bf16 v[20:23], v[144:147], v[202:205], v[20:23]
	v_mfma_f32_16x16x32_bf16 v[16:19], v[168:171], v[202:205], v[16:19]
	v_mfma_f32_16x16x32_bf16 v[4:7], v[144:147], v[210:213], v[4:7]
	v_mfma_f32_16x16x32_bf16 v[0:3], v[168:171], v[210:213], v[0:3]
	v_mfma_f32_16x16x32_bf16 v[52:55], v[148:151], v[180:183], v[52:55]
	v_mfma_f32_16x16x32_bf16 v[48:51], v[172:175], v[180:183], v[48:51]
	v_mfma_f32_16x16x32_bf16 v[36:39], v[148:151], v[196:199], v[36:39]
	v_mfma_f32_16x16x32_bf16 v[32:35], v[172:175], v[196:199], v[32:35]
	v_mfma_f32_16x16x32_bf16 v[20:23], v[148:151], v[206:209], v[20:23]
	v_mfma_f32_16x16x32_bf16 v[16:19], v[172:175], v[206:209], v[16:19]
	v_mfma_f32_16x16x32_bf16 v[4:7], v[148:151], v[214:217], v[4:7]
	v_mfma_f32_16x16x32_bf16 v[0:3], v[172:175], v[214:217], v[0:3]
	s_setprio 0
	s_barrier
	s_add_i32 vcc_lo, vcc_lo, 2
	s_add_u32 s80, s80, 0x100
	s_addc_u32 s81, s81, 0
	s_add_u32 s56, s56, 0x100
	s_addc_u32 s57, s57, 0
	s_cmp_gt_u32 vcc_lo, 13
	s_branch .Lpost6

; #define PG8_STAGE(bufoff, gbase, voff) do { _Pragma("unroll") for (int _i = 0; _i < 2; ++_i) \
;         __builtin_amdgcn_global_load_lds((const unsigned*)((const char*)(gbase) + (voff)[_i]), (PG8_LAS unsigned*)(lds + (bufoff) + ldsw + _i * 8192), 16, 0, 0); } while (0)
; #define PG8_LDA(dst, b, h) do { _Pragma("unroll") for (int m = 0; m < 4; ++m) _Pragma("unroll") for (int k = 0; k < 2; ++k) dst[m][k] = *(const PG8_LAS bf16x8*)(lds + PG8_SA(b, h) + aoff + m * 2048 + k * 1024); } while (0)
; #define PG8_LDB(dst, b, h) do { _Pragma("unroll") for (int n = 0; n < 2; ++n) _Pragma("unroll") for (int k = 0; k < 2; ++k) dst[n][k] = *(const PG8_LAS bf16x8*)(lds + PG8_SB(b, h) + boff + n * 2048 + k * 1024); } while (0)
; #define PG8_MMA(ai, bj, At, Bt) do { __builtin_amdgcn_s_setprio(1); _Pragma("unroll") for (int m = 0; m < 4; ++m) _Pragma("unroll") for (int n = 0; n < 2; ++n) _Pragma("unroll") for (int k = 0; k < 2; ++k) \
;         acc[ai][bj][m][n] = __builtin_amdgcn_mfma_f32_16x16x32_bf16(Bt[n][k], At[m][k], acc[ai][bj][m][n], 0, 0, 0); __builtin_amdgcn_s_setprio(0); } while (0)
; #define PG8_WAIT_V(n) asm volatile("s_waitcnt vmcnt(" #n ")" ::: "memory")
; #define PG8_BAR __builtin_amdgcn_s_barrier()
; template <class Epi, class Sched, bool ALIGN_EPI = false, bool SP2 = false>
; __device__ __forceinline__ void gemm_phase(PG8_LAS unsigned char* lds, const Gemm g, const Sched& S, const Epi& E, int tid_in) {
;     ...
;         for (int t = 0; t < nt; t += 2) {
;             const bool last = (t == nt - 2);
;             const char* a1 = cA + (size_t)(t + 1) * kstep;
;             const char* a2 = last ? nA : cA + (size_t)(t + 2) * kstep; const char* b2 = last ? nB : cB + (size_t)(t + 2) * kstep;
;             const char* a3 = a2 + kstep; const char* b3 = b2 + kstep;
;             if (last && has_next) S.a_ready(nxt);
;             if constexpr (SP2) {
;             PG8_LDB(B0, 0, 0); PG8_LDB(B1, 0, 1); PG8_SCHED; PG8_LDA(At, 0, 0); PG8_STAGE(PG8_SA(1, 1), a1 + hstep, voffA);
;             PG8_WAIT_V(8); PG8_WAIT_L(0); PG8_BAR; PG8_MMA(0, 0, At, B0); PG8_MMA(0, 1, At, B1); PG8_BAR; PG8_SCHED;
;             PG8_LDA(At, 0, 1); PG8_STAGE(PG8_SB(0, 0), b2, voffB); PG8_STAGE(PG8_SB(0, 1), b2 + hstep, voffB); PG8_STAGE(PG8_SA(0, 0), a2, voffA);
;             PG8_WAIT_V(8); PG8_WAIT_L(0); PG8_BAR; PG8_MMA(1, 0, At, B0); PG8_MMA(1, 1, At, B1); PG8_BAR; PG8_SCHED;
.LBB0_996:
	ds_read_b128 v[146:149], v167
	ds_read_b128 v[150:153], v167 offset:1024
	ds_read_b128 v[176:179], v167 offset:2048
	ds_read_b128 v[180:183], v167 offset:3072
	ds_read_b128 v[184:187], v171
	ds_read_b128 v[188:191], v171 offset:1024
	ds_read_b128 v[192:195], v171 offset:2048
	ds_read_b128 v[196:199], v171 offset:3072
	s_add_u32 s4, s50, 0xfffc0080
	s_addc_u32 s5, s51, -1
	s_cmp_eq_u32 s73, 12
	s_cselect_b32 s55, s43, s5
	s_cselect_b32 s54, s69, s4
	s_cselect_b32 s53, s27, s72
	s_cselect_b32 s52, s70, s71
	s_cbranch_scc1 .Lpk7
	v_lshl_add_u64 v[156:157], s[50:51], 0, v[140:141]
	s_add_i32 m0, s57, 0xc000
	ds_read_b128 v[202:205], v173
	ds_read_b128 v[206:209], v173 offset:1024
	ds_read_b128 v[210:213], v173 offset:2048
	ds_read_b128 v[214:217], v173 offset:3072
	ds_read_b128 v[218:221], v173 offset:4096
	ds_read_b128 v[222:225], v173 offset:5120
	ds_read_b128 v[226:229], v173 offset:6144
	ds_read_b128 v[230:233], v173 offset:7168
	global_load_lds_dwordx4 v[156:157], off
	v_lshl_add_u64 v[156:157], s[50:51], 0, v[138:139]
	s_add_i32 m0, s57, 0xe000
	s_nop 0
	global_load_lds_dwordx4 v[156:157], off
	s_waitcnt vmcnt(8)
	s_waitcnt lgkmcnt(0)
	s_barrier
	s_setprio 1
	s_waitcnt lgkmcnt(0)
	v_mfma_f32_16x16x32_bf16 v[124:127], v[146:149], v[202:205], v[124:127]
	v_mfma_f32_16x16x32_bf16 v[120:123], v[176:179], v[202:205], v[120:123]
	v_mfma_f32_16x16x32_bf16 v[108:111], v[146:149], v[210:213], v[108:111]
	v_mfma_f32_16x16x32_bf16 v[104:107], v[176:179], v[210:213], v[104:107]
	v_mfma_f32_16x16x32_bf16 v[92:95], v[146:149], v[218:221], v[92:95]
	v_mfma_f32_16x16x32_bf16 v[88:91], v[176:179], v[218:221], v[88:91]
	v_mfma_f32_16x16x32_bf16 v[76:79], v[146:149], v[226:229], v[76:79]
	v_mfma_f32_16x16x32_bf16 v[72:75], v[176:179], v[226:229], v[72:75]
	v_mfma_f32_16x16x32_bf16 v[124:127], v[150:153], v[206:209], v[124:127]
	v_mfma_f32_16x16x32_bf16 v[120:123], v[180:183], v[206:209], v[120:123]
	v_mfma_f32_16x16x32_bf16 v[108:111], v[150:153], v[214:217], v[108:111]
	v_mfma_f32_16x16x32_bf16 v[104:107], v[180:183], v[214:217], v[104:107]
	v_mfma_f32_16x16x32_bf16 v[92:95], v[150:153], v[222:225], v[92:95]
	v_mfma_f32_16x16x32_bf16 v[88:91], v[180:183], v[222:225], v[88:91]
	v_mfma_f32_16x16x32_bf16 v[76:79], v[150:153], v[230:233], v[76:79]
	v_mfma_f32_16x16x32_bf16 v[72:75], v[180:183], v[230:233], v[72:75]
	s_setprio 0
	s_setprio 1
	v_mfma_f32_16x16x32_bf16 v[116:119], v[184:187], v[202:205], v[116:119]
	v_mfma_f32_16x16x32_bf16 v[112:115], v[192:195], v[202:205], v[112:115]
	v_mfma_f32_16x16x32_bf16 v[100:103], v[184:187], v[210:213], v[100:103]
	v_mfma_f32_16x16x32_bf16 v[96:99], v[192:195], v[210:213], v[96:99]
	v_mfma_f32_16x16x32_bf16 v[84:87], v[184:187], v[218:221], v[84:87]
	v_mfma_f32_16x16x32_bf16 v[80:83], v[192:195], v[218:221], v[80:83]
	v_mfma_f32_16x16x32_bf16 v[68:71], v[184:187], v[226:229], v[68:71]
	v_mfma_f32_16x16x32_bf16 v[64:67], v[192:195], v[226:229], v[64:67]
	v_mfma_f32_16x16x32_bf16 v[116:119], v[188:191], v[206:209], v[116:119]
	v_mfma_f32_16x16x32_bf16 v[112:115], v[196:199], v[206:209], v[112:115]
	v_mfma_f32_16x16x32_bf16 v[100:103], v[188:191], v[214:217], v[100:103]
	v_mfma_f32_16x16x32_bf16 v[96:99], v[196:199], v[214:217], v[96:99]
	v_mfma_f32_16x16x32_bf16 v[84:87], v[188:191], v[222:225], v[84:87]
	v_mfma_f32_16x16x32_bf16 v[80:83], v[196:199], v[222:225], v[80:83]
	v_mfma_f32_16x16x32_bf16 v[68:71], v[188:191], v[230:233], v[68:71]
	v_mfma_f32_16x16x32_bf16 v[64:67], v[196:199], v[230:233], v[64:67]
	s_setprio 0
	s_barrier
	s_add_i32 s4, s66, s33
	v_lshl_add_u64 v[156:157], s[52:53], 0, v[132:133]
	s_mov_b32 m0, s4
	ds_read_b128 v[202:205], v173 offset:16384
	ds_read_b128 v[206:209], v173 offset:17408
	ds_read_b128 v[210:213], v173 offset:18432
	ds_read_b128 v[214:217], v173 offset:19456
	ds_read_b128 v[218:221], v173 offset:20480
	ds_read_b128 v[222:225], v173 offset:21504
	ds_read_b128 v[226:229], v173 offset:22528
	ds_read_b128 v[230:233], v173 offset:23552
	global_load_lds_dwordx4 v[156:157], off
	s_add_i32 m0, s4, 0x2000
	s_add_u32 s14, s52, 0x40000
	v_lshl_add_u64 v[160:161], s[52:53], 0, v[128:129]
	s_addc_u32 s15, s53, 0
	s_add_i32 s4, s67, s33
	global_load_lds_dwordx4 v[160:161], off
	v_lshl_add_u64 v[164:165], s[14:15], 0, v[132:133]
	s_mov_b32 m0, s4
	v_lshl_add_u64 v[168:169], s[54:55], 0, v[130:131]
	global_load_lds_dwordx4 v[164:165], off
	v_lshl_add_u64 v[164:165], s[14:15], 0, v[128:129]
	s_add_i32 m0, s4, 0x2000
	s_nop 0
	global_load_lds_dwordx4 v[164:165], off
	v_lshl_add_u64 v[164:165], s[54:55], 0, v[134:135]
	s_mov_b32 m0, s57
	s_nop 0
	global_load_lds_dwordx4 v[164:165], off
	s_mov_b32 m0, s58
	s_nop 0
	global_load_lds_dwordx4 v[168:169], off
	s_waitcnt vmcnt(8)
	s_waitcnt lgkmcnt(0)
	s_barrier
; #define PG8_STAGE(bufoff, gbase, voff) do { _Pragma("unroll") for (int _i = 0; _i < 2; ++_i) \
;         __builtin_amdgcn_global_load_lds((const unsigned*)((const char*)(gbase) + (voff)[_i]), (PG8_LAS unsigned*)(lds + (bufoff) + ldsw + _i * 8192), 16, 0, 0); } while (0)
; #define PG8_LDA(dst, b, h) do { _Pragma("unroll") for (int m = 0; m < 4; ++m) _Pragma("unroll") for (int k = 0; k < 2; ++k) dst[m][k] = *(const PG8_LAS bf16x8*)(lds + PG8_SA(b, h) + aoff + m * 2048 + k * 1024); } while (0)
; #define PG8_LDB(dst, b, h) do { _Pragma("unroll") for (int n = 0; n < 2; ++n) _Pragma("unroll") for (int k = 0; k < 2; ++k) dst[n][k] = *(const PG8_LAS bf16x8*)(lds + PG8_SB(b, h) + boff + n * 2048 + k * 1024); } while (0)
; #define PG8_MMA(ai, bj, At, Bt) do { __builtin_amdgcn_s_setprio(1); _Pragma("unroll") for (int m = 0; m < 4; ++m) _Pragma("unroll") for (int n = 0; n < 2; ++n) _Pragma("unroll") for (int k = 0; k < 2; ++k) \
;         acc[ai][bj][m][n] = __builtin_amdgcn_mfma_f32_16x16x32_bf16(Bt[n][k], At[m][k], acc[ai][bj][m][n], 0, 0, 0); __builtin_amdgcn_s_setprio(0); } while (0)
; #define PG8_WAIT_V(n) asm volatile("s_waitcnt vmcnt(" #n ")" ::: "memory")
; #define PG8_WAIT_L(n) asm volatile("s_waitcnt lgkmcnt(" #n ")" ::: "memory")
; #define PG8_BAR __builtin_amdgcn_s_barrier()
; #define PG8_SCHED __builtin_amdgcn_sched_barrier(0)
; template <class Epi, class Sched, bool ALIGN_EPI = false, bool SP2 = false>
; __device__ __forceinline__ void gemm_phase(PG8_LAS unsigned char* lds, const Gemm g, const Sched& S, const Epi& E, int tid_in) {
;     ...
;             PG8_WAIT_V(8); PG8_WAIT_L(0); PG8_BAR; PG8_MMA(1, 0, At, B0); PG8_MMA(1, 1, At, B1); PG8_BAR; PG8_SCHED;
;             PG8_LDB(B0, 1, 0); PG8_LDB(B1, 1, 1); PG8_SCHED; PG8_LDA(At, 1, 0); PG8_STAGE(PG8_SA(0, 1), a2 + hstep, voffA);
;             PG8_WAIT_V(8); PG8_WAIT_L(0); PG8_BAR; PG8_MMA(0, 0, At, B0); PG8_MMA(0, 1, At, B1); PG8_BAR; PG8_SCHED;
	s_setprio 1
	s_waitcnt lgkmcnt(0)
	v_mfma_f32_16x16x32_bf16 v[60:63], v[146:149], v[202:205], v[60:63]
	v_mfma_f32_16x16x32_bf16 v[56:59], v[176:179], v[202:205], v[56:59]
	v_mfma_f32_16x16x32_bf16 v[44:47], v[146:149], v[210:213], v[44:47]
	v_mfma_f32_16x16x32_bf16 v[40:43], v[176:179], v[210:213], v[40:43]
	v_mfma_f32_16x16x32_bf16 v[28:31], v[146:149], v[218:221], v[28:31]
	v_mfma_f32_16x16x32_bf16 v[24:27], v[176:179], v[218:221], v[24:27]
	v_mfma_f32_16x16x32_bf16 v[12:15], v[146:149], v[226:229], v[12:15]
	v_mfma_f32_16x16x32_bf16 v[8:11], v[176:179], v[226:229], v[8:11]
	v_mfma_f32_16x16x32_bf16 v[60:63], v[150:153], v[206:209], v[60:63]
	v_mfma_f32_16x16x32_bf16 v[56:59], v[180:183], v[206:209], v[56:59]
	v_mfma_f32_16x16x32_bf16 v[44:47], v[150:153], v[214:217], v[44:47]
	v_mfma_f32_16x16x32_bf16 v[40:43], v[180:183], v[214:217], v[40:43]
	v_mfma_f32_16x16x32_bf16 v[28:31], v[150:153], v[222:225], v[28:31]
	v_mfma_f32_16x16x32_bf16 v[24:27], v[180:183], v[222:225], v[24:27]
	v_mfma_f32_16x16x32_bf16 v[12:15], v[150:153], v[230:233], v[12:15]
	v_mfma_f32_16x16x32_bf16 v[8:11], v[180:183], v[230:233], v[8:11]
	s_setprio 0
	s_setprio 1
	v_mfma_f32_16x16x32_bf16 v[52:55], v[184:187], v[202:205], v[52:55]
	v_mfma_f32_16x16x32_bf16 v[48:51], v[192:195], v[202:205], v[48:51]
	v_mfma_f32_16x16x32_bf16 v[36:39], v[184:187], v[210:213], v[36:39]
	v_mfma_f32_16x16x32_bf16 v[32:35], v[192:195], v[210:213], v[32:35]
	v_mfma_f32_16x16x32_bf16 v[20:23], v[184:187], v[218:221], v[20:23]
	v_mfma_f32_16x16x32_bf16 v[16:19], v[192:195], v[218:221], v[16:19]
	v_mfma_f32_16x16x32_bf16 v[4:7], v[184:187], v[226:229], v[4:7]
	v_mfma_f32_16x16x32_bf16 v[0:3], v[192:195], v[226:229], v[0:3]
	v_mfma_f32_16x16x32_bf16 v[52:55], v[188:191], v[206:209], v[52:55]
	v_mfma_f32_16x16x32_bf16 v[48:51], v[196:199], v[206:209], v[48:51]
	v_mfma_f32_16x16x32_bf16 v[36:39], v[188:191], v[214:217], v[36:39]
	v_mfma_f32_16x16x32_bf16 v[32:35], v[196:199], v[214:217], v[32:35]
	v_mfma_f32_16x16x32_bf16 v[20:23], v[188:191], v[222:225], v[20:23]
	v_mfma_f32_16x16x32_bf16 v[16:19], v[196:199], v[222:225], v[16:19]
	v_mfma_f32_16x16x32_bf16 v[4:7], v[188:191], v[230:233], v[4:7]
	v_mfma_f32_16x16x32_bf16 v[0:3], v[196:199], v[230:233], v[0:3]
	s_setprio 0
	s_barrier
	s_add_i32 s4, 0, 0x18000
	v_add_u32_e32 v154, s4, v159
	s_add_i32 s5, 0, 0x1c000
	ds_read_b128 v[146:149], v154
	ds_read_b128 v[150:153], v154 offset:1024
	ds_read_b128 v[176:179], v154 offset:2048
	ds_read_b128 v[180:183], v154 offset:3072
	v_add_u32_e32 v154, s5, v159
	ds_read_b128 v[184:187], v154
	ds_read_b128 v[188:191], v154 offset:1024
	ds_read_b128 v[192:195], v154 offset:2048
	ds_read_b128 v[196:199], v154 offset:3072
	s_add_u32 s14, s54, 0x40000
	s_addc_u32 s15, s55, 0
	s_mov_b32 m0, s59
	v_lshl_add_u64 v[234:235], s[14:15], 0, v[134:135]
	ds_read_b128 v[202:205], v173 offset:32768
	ds_read_b128 v[206:209], v173 offset:33792
	ds_read_b128 v[210:213], v173 offset:34816
	ds_read_b128 v[214:217], v173 offset:35840
	ds_read_b128 v[218:221], v173 offset:36864
	ds_read_b128 v[222:225], v173 offset:37888
	ds_read_b128 v[226:229], v173 offset:38912
	ds_read_b128 v[230:233], v173 offset:39936
	global_load_lds_dwordx4 v[234:235], off
	v_lshl_add_u64 v[234:235], s[14:15], 0, v[130:131]
	s_mov_b32 m0, s60
	s_nop 0
	global_load_lds_dwordx4 v[234:235], off
	s_waitcnt vmcnt(8)
	s_waitcnt lgkmcnt(0)
	s_barrier
	s_setprio 1
	s_waitcnt lgkmcnt(0)
	v_mfma_f32_16x16x32_bf16 v[124:127], v[146:149], v[202:205], v[124:127]
	v_mfma_f32_16x16x32_bf16 v[120:123], v[176:179], v[202:205], v[120:123]
	v_mfma_f32_16x16x32_bf16 v[108:111], v[146:149], v[210:213], v[108:111]
	v_mfma_f32_16x16x32_bf16 v[104:107], v[176:179], v[210:213], v[104:107]
	v_mfma_f32_16x16x32_bf16 v[92:95], v[146:149], v[218:221], v[92:95]
	v_mfma_f32_16x16x32_bf16 v[88:91], v[176:179], v[218:221], v[88:91]
	v_mfma_f32_16x16x32_bf16 v[76:79], v[146:149], v[226:229], v[76:79]
	v_mfma_f32_16x16x32_bf16 v[72:75], v[176:179], v[226:229], v[72:75]
	v_mfma_f32_16x16x32_bf16 v[124:127], v[150:153], v[206:209], v[124:127]
	v_mfma_f32_16x16x32_bf16 v[120:123], v[180:183], v[206:209], v[120:123]
	v_mfma_f32_16x16x32_bf16 v[108:111], v[150:153], v[214:217], v[108:111]
	v_mfma_f32_16x16x32_bf16 v[104:107], v[180:183], v[214:217], v[104:107]
	v_mfma_f32_16x16x32_bf16 v[92:95], v[150:153], v[222:225], v[92:95]
	v_mfma_f32_16x16x32_bf16 v[88:91], v[180:183], v[222:225], v[88:91]
	v_mfma_f32_16x16x32_bf16 v[76:79], v[150:153], v[230:233], v[76:79]
	v_mfma_f32_16x16x32_bf16 v[72:75], v[180:183], v[230:233], v[72:75]
	s_setprio 0
	s_setprio 1
	v_mfma_f32_16x16x32_bf16 v[116:119], v[184:187], v[202:205], v[116:119]
	v_mfma_f32_16x16x32_bf16 v[112:115], v[192:195], v[202:205], v[112:115]
	v_mfma_f32_16x16x32_bf16 v[100:103], v[184:187], v[210:213], v[100:103]
	v_mfma_f32_16x16x32_bf16 v[96:99], v[192:195], v[210:213], v[96:99]
	v_mfma_f32_16x16x32_bf16 v[84:87], v[184:187], v[218:221], v[84:87]
	v_mfma_f32_16x16x32_bf16 v[80:83], v[192:195], v[218:221], v[80:83]
	v_mfma_f32_16x16x32_bf16 v[68:71], v[184:187], v[226:229], v[68:71]
	v_mfma_f32_16x16x32_bf16 v[64:67], v[192:195], v[226:229], v[64:67]
	v_mfma_f32_16x16x32_bf16 v[116:119], v[188:191], v[206:209], v[116:119]
	v_mfma_f32_16x16x32_bf16 v[112:115], v[196:199], v[206:209], v[112:115]
	v_mfma_f32_16x16x32_bf16 v[100:103], v[188:191], v[214:217], v[100:103]
	v_mfma_f32_16x16x32_bf16 v[96:99], v[196:199], v[214:217], v[96:99]
	v_mfma_f32_16x16x32_bf16 v[84:87], v[188:191], v[222:225], v[84:87]
	v_mfma_f32_16x16x32_bf16 v[80:83], v[196:199], v[222:225], v[80:83]
	v_mfma_f32_16x16x32_bf16 v[68:71], v[188:191], v[230:233], v[68:71]
	v_mfma_f32_16x16x32_bf16 v[64:67], v[196:199], v[230:233], v[64:67]
	s_setprio 0
	s_barrier
; #define PG8_STAGE(bufoff, gbase, voff) do { _Pragma("unroll") for (int _i = 0; _i < 2; ++_i) \
;         __builtin_amdgcn_global_load_lds((const unsigned*)((const char*)(gbase) + (voff)[_i]), (PG8_LAS unsigned*)(lds + (bufoff) + ldsw + _i * 8192), 16, 0, 0); } while (0)
; #define PG8_LDA(dst, b, h) do { _Pragma("unroll") for (int m = 0; m < 4; ++m) _Pragma("unroll") for (int k = 0; k < 2; ++k) dst[m][k] = *(const PG8_LAS bf16x8*)(lds + PG8_SA(b, h) + aoff + m * 2048 + k * 1024); } while (0)
; #define PG8_MMA(ai, bj, At, Bt) do { __builtin_amdgcn_s_setprio(1); _Pragma("unroll") for (int m = 0; m < 4; ++m) _Pragma("unroll") for (int n = 0; n < 2; ++n) _Pragma("unroll") for (int k = 0; k < 2; ++k) \
;         acc[ai][bj][m][n] = __builtin_amdgcn_mfma_f32_16x16x32_bf16(Bt[n][k], At[m][k], acc[ai][bj][m][n], 0, 0, 0); __builtin_amdgcn_s_setprio(0); } while (0)
; #define PG8_WAIT_V(n) asm volatile("s_waitcnt vmcnt(" #n ")" ::: "memory")
; #define PG8_WAIT_L(n) asm volatile("s_waitcnt lgkmcnt(" #n ")" ::: "memory")
; #define PG8_BAR __builtin_amdgcn_s_barrier()
; #define PG8_SCHED __builtin_amdgcn_sched_barrier(0)
; template <class Epi, class Sched, bool ALIGN_EPI = false, bool SP2 = false>
; __device__ __forceinline__ void gemm_phase(PG8_LAS unsigned char* lds, const Gemm g, const Sched& S, const Epi& E, int tid_in) {
;     ...
;             PG8_LDA(At, 1, 1); PG8_STAGE(PG8_SB(1, 0), b3, voffB); PG8_STAGE(PG8_SB(1, 1), b3 + hstep, voffB); PG8_STAGE(PG8_SA(1, 0), a3, voffA);
;             PG8_WAIT_V(8); PG8_WAIT_L(0); PG8_BAR; PG8_MMA(1, 0, At, B0); PG8_MMA(1, 1, At, B1); PG8_BAR; PG8_SCHED;
	s_add_i32 s4, s4, s33
	v_lshl_add_u64 v[156:157], v[156:157], 0, s[22:23]
	s_mov_b32 m0, s4
	ds_read_b128 v[202:205], v173 offset:49152
	ds_read_b128 v[206:209], v173 offset:50176
	ds_read_b128 v[210:213], v173 offset:51200
	ds_read_b128 v[214:217], v173 offset:52224
	ds_read_b128 v[218:221], v173 offset:53248
	ds_read_b128 v[222:225], v173 offset:54272
	ds_read_b128 v[226:229], v173 offset:55296
	ds_read_b128 v[230:233], v173 offset:56320
	global_load_lds_dwordx4 v[156:157], off
	s_add_i32 m0, s4, 0x2000
	s_add_u32 s14, s52, 0x40080
	v_lshl_add_u64 v[156:157], v[160:161], 0, s[22:23]
	s_addc_u32 s15, s53, 0
	s_add_i32 s4, s5, s33
	global_load_lds_dwordx4 v[156:157], off
	v_lshl_add_u64 v[156:157], s[14:15], 0, v[132:133]
	s_mov_b32 m0, s4
	s_nop 0
	global_load_lds_dwordx4 v[156:157], off
	v_lshl_add_u64 v[156:157], s[14:15], 0, v[128:129]
	s_add_i32 m0, s4, 0x2000
	s_nop 0
	global_load_lds_dwordx4 v[156:157], off
	v_lshl_add_u64 v[156:157], v[164:165], 0, s[22:23]
	s_mov_b32 m0, s62
	s_nop 0
	global_load_lds_dwordx4 v[156:157], off
	v_lshl_add_u64 v[156:157], v[168:169], 0, s[22:23]
	s_mov_b32 m0, s63
	s_nop 0
	global_load_lds_dwordx4 v[156:157], off
	s_waitcnt vmcnt(8)
	s_waitcnt lgkmcnt(0)
	s_barrier
	s_setprio 1
	s_waitcnt lgkmcnt(0)
	v_mfma_f32_16x16x32_bf16 v[60:63], v[146:149], v[202:205], v[60:63]
	v_mfma_f32_16x16x32_bf16 v[56:59], v[176:179], v[202:205], v[56:59]
	v_mfma_f32_16x16x32_bf16 v[44:47], v[146:149], v[210:213], v[44:47]
	v_mfma_f32_16x16x32_bf16 v[40:43], v[176:179], v[210:213], v[40:43]
	v_mfma_f32_16x16x32_bf16 v[28:31], v[146:149], v[218:221], v[28:31]
	v_mfma_f32_16x16x32_bf16 v[24:27], v[176:179], v[218:221], v[24:27]
	v_mfma_f32_16x16x32_bf16 v[12:15], v[146:149], v[226:229], v[12:15]
	v_mfma_f32_16x16x32_bf16 v[8:11], v[176:179], v[226:229], v[8:11]
	v_mfma_f32_16x16x32_bf16 v[60:63], v[150:153], v[206:209], v[60:63]
	v_mfma_f32_16x16x32_bf16 v[56:59], v[180:183], v[206:209], v[56:59]
	v_mfma_f32_16x16x32_bf16 v[44:47], v[150:153], v[214:217], v[44:47]
	v_mfma_f32_16x16x32_bf16 v[40:43], v[180:183], v[214:217], v[40:43]
	v_mfma_f32_16x16x32_bf16 v[28:31], v[150:153], v[222:225], v[28:31]
	v_mfma_f32_16x16x32_bf16 v[24:27], v[180:183], v[222:225], v[24:27]
	v_mfma_f32_16x16x32_bf16 v[12:15], v[150:153], v[230:233], v[12:15]
	v_mfma_f32_16x16x32_bf16 v[8:11], v[180:183], v[230:233], v[8:11]
	s_setprio 0
	s_setprio 1
	v_mfma_f32_16x16x32_bf16 v[52:55], v[184:187], v[202:205], v[52:55]
	v_mfma_f32_16x16x32_bf16 v[48:51], v[192:195], v[202:205], v[48:51]
	v_mfma_f32_16x16x32_bf16 v[36:39], v[184:187], v[210:213], v[36:39]
	v_mfma_f32_16x16x32_bf16 v[32:35], v[192:195], v[210:213], v[32:35]
	v_mfma_f32_16x16x32_bf16 v[20:23], v[184:187], v[218:221], v[20:23]
	v_mfma_f32_16x16x32_bf16 v[16:19], v[192:195], v[218:221], v[16:19]
	v_mfma_f32_16x16x32_bf16 v[4:7], v[184:187], v[226:229], v[4:7]
	v_mfma_f32_16x16x32_bf16 v[0:3], v[192:195], v[226:229], v[0:3]
	v_mfma_f32_16x16x32_bf16 v[52:55], v[188:191], v[206:209], v[52:55]
	v_mfma_f32_16x16x32_bf16 v[48:51], v[196:199], v[206:209], v[48:51]
	v_mfma_f32_16x16x32_bf16 v[36:39], v[188:191], v[214:217], v[36:39]
	v_mfma_f32_16x16x32_bf16 v[32:35], v[196:199], v[214:217], v[32:35]
	v_mfma_f32_16x16x32_bf16 v[20:23], v[188:191], v[222:225], v[20:23]
	v_mfma_f32_16x16x32_bf16 v[16:19], v[196:199], v[222:225], v[16:19]
	v_mfma_f32_16x16x32_bf16 v[4:7], v[188:191], v[230:233], v[4:7]
	v_mfma_f32_16x16x32_bf16 v[0:3], v[196:199], v[230:233], v[0:3]
	s_setprio 0
	s_barrier
	s_add_i32 s73, s73, 2
	s_add_u32 s71, s71, 0x100
	s_addc_u32 s72, s72, 0
	s_add_u32 s50, s50, 0x100
	s_addc_u32 s51, s51, 0
	s_cmp_gt_u32 s73, 13
	s_cbranch_scc0 .LBB0_996
.Lpost7:
	s_and_b64 vcc, exec, s[24:25]
	s_cbranch_vccz .LBB0_999
	s_barrier

; #define PG8_STAGE(bufoff, gbase, voff) do { _Pragma("unroll") for (int _i = 0; _i < 2; ++_i) \
;         __builtin_amdgcn_global_load_lds((const unsigned*)((const char*)(gbase) + (voff)[_i]), (PG8_LAS unsigned*)(lds + (bufoff) + ldsw + _i * 8192), 16, 0, 0); } while (0)
; #define PG8_LDA(dst, b, h) do { _Pragma("unroll") for (int m = 0; m < 4; ++m) _Pragma("unroll") for (int k = 0; k < 2; ++k) dst[m][k] = *(const PG8_LAS bf16x8*)(lds + PG8_SA(b, h) + aoff + m * 2048 + k * 1024); } while (0)
; #define PG8_LDB(dst, b, h) do { _Pragma("unroll") for (int n = 0; n < 2; ++n) _Pragma("unroll") for (int k = 0; k < 2; ++k) dst[n][k] = *(const PG8_LAS bf16x8*)(lds + PG8_SB(b, h) + boff + n * 2048 + k * 1024); } while (0)
; #define PG8_MMA(ai, bj, At, Bt) do { __builtin_amdgcn_s_setprio(1); _Pragma("unroll") for (int m = 0; m < 4; ++m) _Pragma("unroll") for (int n = 0; n < 2; ++n) _Pragma("unroll") for (int k = 0; k < 2; ++k) \
;         acc[ai][bj][m][n] = __builtin_amdgcn_mfma_f32_16x16x32_bf16(Bt[n][k], At[m][k], acc[ai][bj][m][n], 0, 0, 0); __builtin_amdgcn_s_setprio(0); } while (0)
; #define PG8_WAIT_V(n) asm volatile("s_waitcnt vmcnt(" #n ")" ::: "memory")
; #define PG8_WAIT_L(n) asm volatile("s_waitcnt lgkmcnt(" #n ")" ::: "memory")
; template <class Epi, class Sched, bool ALIGN_EPI = false, bool SP2 = false>
; __device__ __forceinline__ void gemm_phase(PG8_LAS unsigned char* lds, const Gemm g, const Sched& S, const Epi& E, int tid_in) {
;     ...
;             const bool last = (t == nt - 2);
;             const char* a1 = cA + (size_t)(t + 1) * kstep;
;             const char* a2 = last ? nA : cA + (size_t)(t + 2) * kstep; const char* b2 = last ? nB : cB + (size_t)(t + 2) * kstep;
;             const char* a3 = a2 + kstep; const char* b3 = b2 + kstep;
;             if (last && has_next) S.a_ready(nxt);
;             if constexpr (SP2) {
;             PG8_LDB(B0, 0, 0); PG8_LDB(B1, 0, 1); PG8_SCHED; PG8_LDA(At, 0, 0); PG8_STAGE(PG8_SA(1, 1), a1 + hstep, voffA);
;             PG8_WAIT_V(8); PG8_WAIT_L(0); PG8_BAR; PG8_MMA(0, 0, At, B0); PG8_MMA(0, 1, At, B1); PG8_BAR; PG8_SCHED;
;             PG8_LDA(At, 0, 1); PG8_STAGE(PG8_SB(0, 0), b2, voffB); PG8_STAGE(PG8_SB(0, 1), b2 + hstep, voffB); PG8_STAGE(PG8_SA(0, 0), a2, voffA);
;             PG8_WAIT_V(8); PG8_WAIT_L(0); PG8_BAR; PG8_MMA(1, 0, At, B0); PG8_MMA(1, 1, At, B1); PG8_BAR; PG8_SCHED;
.Lpk7:
	s_or_b64 s[98:99], s[16:17], 1
	v_lshl_add_u64 v[156:157], s[50:51], 0, v[140:141]
	s_add_i32 m0, s57, 0xc000
	ds_read_b128 v[202:205], v173
	ds_read_b128 v[206:209], v173 offset:1024
	ds_read_b128 v[210:213], v173 offset:2048
	ds_read_b128 v[214:217], v173 offset:3072
	ds_read_b128 v[218:221], v173 offset:4096
	ds_read_b128 v[222:225], v173 offset:5120
	ds_read_b128 v[226:229], v173 offset:6144
	ds_read_b128 v[230:233], v173 offset:7168
	global_load_lds_dwordx4 v[156:157], off
	v_lshl_add_u64 v[156:157], s[50:51], 0, v[138:139]
	s_add_i32 m0, s57, 0xe000
	s_nop 0
	global_load_lds_dwordx4 v[156:157], off
	s_waitcnt vmcnt(8)
	s_waitcnt lgkmcnt(0)
	s_barrier
	s_setprio 1
	s_waitcnt lgkmcnt(0)
	v_mfma_f32_16x16x32_bf16 v[124:127], v[146:149], v[202:205], v[124:127]
	v_mfma_f32_16x16x32_bf16 v[120:123], v[176:179], v[202:205], v[120:123]
	v_mfma_f32_16x16x32_bf16 v[108:111], v[146:149], v[210:213], v[108:111]
	v_mfma_f32_16x16x32_bf16 v[104:107], v[176:179], v[210:213], v[104:107]
	v_mfma_f32_16x16x32_bf16 v[92:95], v[146:149], v[218:221], v[92:95]
	v_mfma_f32_16x16x32_bf16 v[88:91], v[176:179], v[218:221], v[88:91]
	v_mfma_f32_16x16x32_bf16 v[76:79], v[146:149], v[226:229], v[76:79]
	v_mfma_f32_16x16x32_bf16 v[72:75], v[176:179], v[226:229], v[72:75]
	v_mfma_f32_16x16x32_bf16 v[124:127], v[150:153], v[206:209], v[124:127]
	v_mfma_f32_16x16x32_bf16 v[120:123], v[180:183], v[206:209], v[120:123]
	v_mfma_f32_16x16x32_bf16 v[108:111], v[150:153], v[214:217], v[108:111]
	v_mfma_f32_16x16x32_bf16 v[104:107], v[180:183], v[214:217], v[104:107]
	v_mfma_f32_16x16x32_bf16 v[92:95], v[150:153], v[222:225], v[92:95]
	v_mfma_f32_16x16x32_bf16 v[88:91], v[180:183], v[222:225], v[88:91]
	v_mfma_f32_16x16x32_bf16 v[76:79], v[150:153], v[230:233], v[76:79]
	v_mfma_f32_16x16x32_bf16 v[72:75], v[180:183], v[230:233], v[72:75]
	s_setprio 0
	s_setprio 1
	v_mfma_f32_16x16x32_bf16 v[116:119], v[184:187], v[202:205], v[116:119]
	v_mfma_f32_16x16x32_bf16 v[112:115], v[192:195], v[202:205], v[112:115]
	v_mfma_f32_16x16x32_bf16 v[100:103], v[184:187], v[210:213], v[100:103]
	v_mfma_f32_16x16x32_bf16 v[96:99], v[192:195], v[210:213], v[96:99]
	v_mfma_f32_16x16x32_bf16 v[84:87], v[184:187], v[218:221], v[84:87]
	v_mfma_f32_16x16x32_bf16 v[80:83], v[192:195], v[218:221], v[80:83]
	v_mfma_f32_16x16x32_bf16 v[68:71], v[184:187], v[226:229], v[68:71]
	v_mfma_f32_16x16x32_bf16 v[64:67], v[192:195], v[226:229], v[64:67]
	v_mfma_f32_16x16x32_bf16 v[116:119], v[188:191], v[206:209], v[116:119]
	v_mfma_f32_16x16x32_bf16 v[112:115], v[196:199], v[206:209], v[112:115]
	v_mfma_f32_16x16x32_bf16 v[100:103], v[188:191], v[214:217], v[100:103]
	v_mfma_f32_16x16x32_bf16 v[96:99], v[196:199], v[214:217], v[96:99]
	v_mfma_f32_16x16x32_bf16 v[84:87], v[188:191], v[222:225], v[84:87]
	v_mfma_f32_16x16x32_bf16 v[80:83], v[196:199], v[222:225], v[80:83]
	v_mfma_f32_16x16x32_bf16 v[68:71], v[188:191], v[230:233], v[68:71]
	v_mfma_f32_16x16x32_bf16 v[64:67], v[196:199], v[230:233], v[64:67]
	s_setprio 0
	s_barrier
	s_add_i32 s4, s66, s33
	v_lshl_add_u64 v[156:157], s[52:53], 0, v[132:133]
	s_mov_b32 m0, s4
	ds_read_b128 v[202:205], v173 offset:16384
	ds_read_b128 v[206:209], v173 offset:17408
	ds_read_b128 v[210:213], v173 offset:18432
	ds_read_b128 v[214:217], v173 offset:19456
	ds_read_b128 v[218:221], v173 offset:20480
	ds_read_b128 v[222:225], v173 offset:21504
	ds_read_b128 v[226:229], v173 offset:22528
	ds_read_b128 v[230:233], v173 offset:23552
	s_mov_b64 exec, s[98:99]
	global_load_lds_dwordx4 v[156:157], off
	s_mov_b64 exec, -1
	s_add_i32 m0, s4, 0x2000
	s_add_u32 s14, s52, 0x40000
	v_lshl_add_u64 v[160:161], s[52:53], 0, v[128:129]
	s_addc_u32 s15, s53, 0
	s_add_i32 s4, s67, s33
	s_mov_b64 exec, s[98:99]
	global_load_lds_dwordx4 v[160:161], off
	s_mov_b64 exec, -1
	v_lshl_add_u64 v[164:165], s[14:15], 0, v[132:133]
	s_mov_b32 m0, s4
	v_lshl_add_u64 v[168:169], s[54:55], 0, v[130:131]
	s_mov_b64 exec, s[98:99]
	global_load_lds_dwordx4 v[164:165], off
	s_mov_b64 exec, -1
	v_lshl_add_u64 v[164:165], s[14:15], 0, v[128:129]
	s_add_i32 m0, s4, 0x2000
	s_nop 0
	s_mov_b64 exec, s[98:99]
	global_load_lds_dwordx4 v[164:165], off
	s_mov_b64 exec, -1
	v_lshl_add_u64 v[164:165], s[54:55], 0, v[134:135]
	s_mov_b32 m0, s57
	s_nop 0
	s_mov_b64 exec, s[98:99]
	global_load_lds_dwordx4 v[164:165], off
	s_mov_b64 exec, -1
	s_mov_b32 m0, s58
	s_nop 0
	s_mov_b64 exec, s[98:99]
	global_load_lds_dwordx4 v[168:169], off
	s_mov_b64 exec, -1
	s_waitcnt vmcnt(8)
	s_waitcnt lgkmcnt(0)
	s_barrier
; #define PG8_STAGE(bufoff, gbase, voff) do { _Pragma("unroll") for (int _i = 0; _i < 2; ++_i) \
;         __builtin_amdgcn_global_load_lds((const unsigned*)((const char*)(gbase) + (voff)[_i]), (PG8_LAS unsigned*)(lds + (bufoff) + ldsw + _i * 8192), 16, 0, 0); } while (0)
; #define PG8_LDA(dst, b, h) do { _Pragma("unroll") for (int m = 0; m < 4; ++m) _Pragma("unroll") for (int k = 0; k < 2; ++k) dst[m][k] = *(const PG8_LAS bf16x8*)(lds + PG8_SA(b, h) + aoff + m * 2048 + k * 1024); } while (0)
; #define PG8_LDB(dst, b, h) do { _Pragma("unroll") for (int n = 0; n < 2; ++n) _Pragma("unroll") for (int k = 0; k < 2; ++k) dst[n][k] = *(const PG8_LAS bf16x8*)(lds + PG8_SB(b, h) + boff + n * 2048 + k * 1024); } while (0)
; #define PG8_MMA(ai, bj, At, Bt) do { __builtin_amdgcn_s_setprio(1); _Pragma("unroll") for (int m = 0; m < 4; ++m) _Pragma("unroll") for (int n = 0; n < 2; ++n) _Pragma("unroll") for (int k = 0; k < 2; ++k) \
;         acc[ai][bj][m][n] = __builtin_amdgcn_mfma_f32_16x16x32_bf16(Bt[n][k], At[m][k], acc[ai][bj][m][n], 0, 0, 0); __builtin_amdgcn_s_setprio(0); } while (0)
; #define PG8_WAIT_V(n) asm volatile("s_waitcnt vmcnt(" #n ")" ::: "memory")
; #define PG8_WAIT_L(n) asm volatile("s_waitcnt lgkmcnt(" #n ")" ::: "memory")
; #define PG8_BAR __builtin_amdgcn_s_barrier()
; #define PG8_SCHED __builtin_amdgcn_sched_barrier(0)
; template <class Epi, class Sched, bool ALIGN_EPI = false, bool SP2 = false>
; __device__ __forceinline__ void gemm_phase(PG8_LAS unsigned char* lds, const Gemm g, const Sched& S, const Epi& E, int tid_in) {
;     ...
;             PG8_WAIT_V(8); PG8_WAIT_L(0); PG8_BAR; PG8_MMA(1, 0, At, B0); PG8_MMA(1, 1, At, B1); PG8_BAR; PG8_SCHED;
;             PG8_LDB(B0, 1, 0); PG8_LDB(B1, 1, 1); PG8_SCHED; PG8_LDA(At, 1, 0); PG8_STAGE(PG8_SA(0, 1), a2 + hstep, voffA);
;             PG8_WAIT_V(8); PG8_WAIT_L(0); PG8_BAR; PG8_MMA(0, 0, At, B0); PG8_MMA(0, 1, At, B1); PG8_BAR; PG8_SCHED;
	s_setprio 1
	s_waitcnt lgkmcnt(0)
	v_mfma_f32_16x16x32_bf16 v[60:63], v[146:149], v[202:205], v[60:63]
	v_mfma_f32_16x16x32_bf16 v[56:59], v[176:179], v[202:205], v[56:59]
	v_mfma_f32_16x16x32_bf16 v[44:47], v[146:149], v[210:213], v[44:47]
	v_mfma_f32_16x16x32_bf16 v[40:43], v[176:179], v[210:213], v[40:43]
	v_mfma_f32_16x16x32_bf16 v[28:31], v[146:149], v[218:221], v[28:31]
	v_mfma_f32_16x16x32_bf16 v[24:27], v[176:179], v[218:221], v[24:27]
	v_mfma_f32_16x16x32_bf16 v[12:15], v[146:149], v[226:229], v[12:15]
	v_mfma_f32_16x16x32_bf16 v[8:11], v[176:179], v[226:229], v[8:11]
	v_mfma_f32_16x16x32_bf16 v[60:63], v[150:153], v[206:209], v[60:63]
	v_mfma_f32_16x16x32_bf16 v[56:59], v[180:183], v[206:209], v[56:59]
	v_mfma_f32_16x16x32_bf16 v[44:47], v[150:153], v[214:217], v[44:47]
	v_mfma_f32_16x16x32_bf16 v[40:43], v[180:183], v[214:217], v[40:43]
	v_mfma_f32_16x16x32_bf16 v[28:31], v[150:153], v[222:225], v[28:31]
	v_mfma_f32_16x16x32_bf16 v[24:27], v[180:183], v[222:225], v[24:27]
	v_mfma_f32_16x16x32_bf16 v[12:15], v[150:153], v[230:233], v[12:15]
	v_mfma_f32_16x16x32_bf16 v[8:11], v[180:183], v[230:233], v[8:11]
	s_setprio 0
	s_setprio 1
	v_mfma_f32_16x16x32_bf16 v[52:55], v[184:187], v[202:205], v[52:55]
	v_mfma_f32_16x16x32_bf16 v[48:51], v[192:195], v[202:205], v[48:51]
	v_mfma_f32_16x16x32_bf16 v[36:39], v[184:187], v[210:213], v[36:39]
	v_mfma_f32_16x16x32_bf16 v[32:35], v[192:195], v[210:213], v[32:35]
	v_mfma_f32_16x16x32_bf16 v[20:23], v[184:187], v[218:221], v[20:23]
	v_mfma_f32_16x16x32_bf16 v[16:19], v[192:195], v[218:221], v[16:19]
	v_mfma_f32_16x16x32_bf16 v[4:7], v[184:187], v[226:229], v[4:7]
	v_mfma_f32_16x16x32_bf16 v[0:3], v[192:195], v[226:229], v[0:3]
	v_mfma_f32_16x16x32_bf16 v[52:55], v[188:191], v[206:209], v[52:55]
	v_mfma_f32_16x16x32_bf16 v[48:51], v[196:199], v[206:209], v[48:51]
	v_mfma_f32_16x16x32_bf16 v[36:39], v[188:191], v[214:217], v[36:39]
	v_mfma_f32_16x16x32_bf16 v[32:35], v[196:199], v[214:217], v[32:35]
	v_mfma_f32_16x16x32_bf16 v[20:23], v[188:191], v[222:225], v[20:23]
	v_mfma_f32_16x16x32_bf16 v[16:19], v[196:199], v[222:225], v[16:19]
	v_mfma_f32_16x16x32_bf16 v[4:7], v[188:191], v[230:233], v[4:7]
	v_mfma_f32_16x16x32_bf16 v[0:3], v[196:199], v[230:233], v[0:3]
	s_setprio 0
	s_barrier
	s_add_i32 s4, 0, 0x18000
	v_add_u32_e32 v154, s4, v159
	s_add_i32 s5, 0, 0x1c000
	ds_read_b128 v[146:149], v154
	ds_read_b128 v[150:153], v154 offset:1024
	ds_read_b128 v[176:179], v154 offset:2048
	ds_read_b128 v[180:183], v154 offset:3072
	v_add_u32_e32 v154, s5, v159
	ds_read_b128 v[184:187], v154
	ds_read_b128 v[188:191], v154 offset:1024
	ds_read_b128 v[192:195], v154 offset:2048
	ds_read_b128 v[196:199], v154 offset:3072
	s_add_u32 s14, s54, 0x40000
	s_addc_u32 s15, s55, 0
	s_mov_b32 m0, s59
	v_lshl_add_u64 v[234:235], s[14:15], 0, v[134:135]
	ds_read_b128 v[202:205], v173 offset:32768
	ds_read_b128 v[206:209], v173 offset:33792
	ds_read_b128 v[210:213], v173 offset:34816
	ds_read_b128 v[214:217], v173 offset:35840
	ds_read_b128 v[218:221], v173 offset:36864
	ds_read_b128 v[222:225], v173 offset:37888
	ds_read_b128 v[226:229], v173 offset:38912
	ds_read_b128 v[230:233], v173 offset:39936
	s_mov_b64 exec, s[98:99]
	global_load_lds_dwordx4 v[234:235], off
	s_mov_b64 exec, -1
	v_lshl_add_u64 v[234:235], s[14:15], 0, v[130:131]
	s_mov_b32 m0, s60
	s_nop 0
	s_mov_b64 exec, s[98:99]
	global_load_lds_dwordx4 v[234:235], off
	s_mov_b64 exec, -1
	s_waitcnt vmcnt(8)
	s_waitcnt lgkmcnt(0)
	s_barrier
	s_setprio 1
	s_waitcnt lgkmcnt(0)
	v_mfma_f32_16x16x32_bf16 v[124:127], v[146:149], v[202:205], v[124:127]
	v_mfma_f32_16x16x32_bf16 v[120:123], v[176:179], v[202:205], v[120:123]
	v_mfma_f32_16x16x32_bf16 v[108:111], v[146:149], v[210:213], v[108:111]
	v_mfma_f32_16x16x32_bf16 v[104:107], v[176:179], v[210:213], v[104:107]
	v_mfma_f32_16x16x32_bf16 v[92:95], v[146:149], v[218:221], v[92:95]
	v_mfma_f32_16x16x32_bf16 v[88:91], v[176:179], v[218:221], v[88:91]
	v_mfma_f32_16x16x32_bf16 v[76:79], v[146:149], v[226:229], v[76:79]
	v_mfma_f32_16x16x32_bf16 v[72:75], v[176:179], v[226:229], v[72:75]
	v_mfma_f32_16x16x32_bf16 v[124:127], v[150:153], v[206:209], v[124:127]
	v_mfma_f32_16x16x32_bf16 v[120:123], v[180:183], v[206:209], v[120:123]
	v_mfma_f32_16x16x32_bf16 v[108:111], v[150:153], v[214:217], v[108:111]
	v_mfma_f32_16x16x32_bf16 v[104:107], v[180:183], v[214:217], v[104:107]
	v_mfma_f32_16x16x32_bf16 v[92:95], v[150:153], v[222:225], v[92:95]
	v_mfma_f32_16x16x32_bf16 v[88:91], v[180:183], v[222:225], v[88:91]
	v_mfma_f32_16x16x32_bf16 v[76:79], v[150:153], v[230:233], v[76:79]
	v_mfma_f32_16x16x32_bf16 v[72:75], v[180:183], v[230:233], v[72:75]
	s_setprio 0
	s_setprio 1
	v_mfma_f32_16x16x32_bf16 v[116:119], v[184:187], v[202:205], v[116:119]
	v_mfma_f32_16x16x32_bf16 v[112:115], v[192:195], v[202:205], v[112:115]
	v_mfma_f32_16x16x32_bf16 v[100:103], v[184:187], v[210:213], v[100:103]
	v_mfma_f32_16x16x32_bf16 v[96:99], v[192:195], v[210:213], v[96:99]
	v_mfma_f32_16x16x32_bf16 v[84:87], v[184:187], v[218:221], v[84:87]
	v_mfma_f32_16x16x32_bf16 v[80:83], v[192:195], v[218:221], v[80:83]
	v_mfma_f32_16x16x32_bf16 v[68:71], v[184:187], v[226:229], v[68:71]
	v_mfma_f32_16x16x32_bf16 v[64:67], v[192:195], v[226:229], v[64:67]
	v_mfma_f32_16x16x32_bf16 v[116:119], v[188:191], v[206:209], v[116:119]
	v_mfma_f32_16x16x32_bf16 v[112:115], v[196:199], v[206:209], v[112:115]
	v_mfma_f32_16x16x32_bf16 v[100:103], v[188:191], v[214:217], v[100:103]
	v_mfma_f32_16x16x32_bf16 v[96:99], v[196:199], v[214:217], v[96:99]
	v_mfma_f32_16x16x32_bf16 v[84:87], v[188:191], v[222:225], v[84:87]
	v_mfma_f32_16x16x32_bf16 v[80:83], v[196:199], v[222:225], v[80:83]
	v_mfma_f32_16x16x32_bf16 v[68:71], v[188:191], v[230:233], v[68:71]
	v_mfma_f32_16x16x32_bf16 v[64:67], v[196:199], v[230:233], v[64:67]
	s_setprio 0
	s_barrier
; #define PG8_STAGE(bufoff, gbase, voff) do { _Pragma("unroll") for (int _i = 0; _i < 2; ++_i) \
;         __builtin_amdgcn_global_load_lds((const unsigned*)((const char*)(gbase) + (voff)[_i]), (PG8_LAS unsigned*)(lds + (bufoff) + ldsw + _i * 8192), 16, 0, 0); } while (0)
; #define PG8_LDA(dst, b, h) do { _Pragma("unroll") for (int m = 0; m < 4; ++m) _Pragma("unroll") for (int k = 0; k < 2; ++k) dst[m][k] = *(const PG8_LAS bf16x8*)(lds + PG8_SA(b, h) + aoff + m * 2048 + k * 1024); } while (0)
; #define PG8_MMA(ai, bj, At, Bt) do { __builtin_amdgcn_s_setprio(1); _Pragma("unroll") for (int m = 0; m < 4; ++m) _Pragma("unroll") for (int n = 0; n < 2; ++n) _Pragma("unroll") for (int k = 0; k < 2; ++k) \
;         acc[ai][bj][m][n] = __builtin_amdgcn_mfma_f32_16x16x32_bf16(Bt[n][k], At[m][k], acc[ai][bj][m][n], 0, 0, 0); __builtin_amdgcn_s_setprio(0); } while (0)
; #define PG8_WAIT_V(n) asm volatile("s_waitcnt vmcnt(" #n ")" ::: "memory")
; #define PG8_WAIT_L(n) asm volatile("s_waitcnt lgkmcnt(" #n ")" ::: "memory")
; #define PG8_BAR __builtin_amdgcn_s_barrier()
; #define PG8_SCHED __builtin_amdgcn_sched_barrier(0)
; template <class Epi, class Sched, bool ALIGN_EPI = false, bool SP2 = false>
; __device__ __forceinline__ void gemm_phase(PG8_LAS unsigned char* lds, const Gemm g, const Sched& S, const Epi& E, int tid_in) {
;     ...
;             PG8_LDA(At, 1, 1); PG8_STAGE(PG8_SB(1, 0), b3, voffB); PG8_STAGE(PG8_SB(1, 1), b3 + hstep, voffB); PG8_STAGE(PG8_SA(1, 0), a3, voffA);
;             PG8_WAIT_V(8); PG8_WAIT_L(0); PG8_BAR; PG8_MMA(1, 0, At, B0); PG8_MMA(1, 1, At, B1); PG8_BAR; PG8_SCHED;
	s_add_i32 s4, s4, s33
	v_lshl_add_u64 v[156:157], v[156:157], 0, s[22:23]
	s_mov_b32 m0, s4
	ds_read_b128 v[202:205], v173 offset:49152
	ds_read_b128 v[206:209], v173 offset:50176
	ds_read_b128 v[210:213], v173 offset:51200
	ds_read_b128 v[214:217], v173 offset:52224
	ds_read_b128 v[218:221], v173 offset:53248
	ds_read_b128 v[222:225], v173 offset:54272
	ds_read_b128 v[226:229], v173 offset:55296
	ds_read_b128 v[230:233], v173 offset:56320
	s_mov_b64 exec, s[98:99]
	global_load_lds_dwordx4 v[156:157], off
	s_mov_b64 exec, -1
	s_add_i32 m0, s4, 0x2000
	s_add_u32 s14, s52, 0x40080
	v_lshl_add_u64 v[156:157], v[160:161], 0, s[22:23]
	s_addc_u32 s15, s53, 0
	s_add_i32 s4, s5, s33
	s_mov_b64 exec, s[98:99]
	global_load_lds_dwordx4 v[156:157], off
	s_mov_b64 exec, -1
	v_lshl_add_u64 v[156:157], s[14:15], 0, v[132:133]
	s_mov_b32 m0, s4
	s_nop 0
	s_mov_b64 exec, s[98:99]
	global_load_lds_dwordx4 v[156:157], off
	s_mov_b64 exec, -1
	v_lshl_add_u64 v[156:157], s[14:15], 0, v[128:129]
	s_add_i32 m0, s4, 0x2000
	s_nop 0
	s_mov_b64 exec, s[98:99]
	global_load_lds_dwordx4 v[156:157], off
	s_mov_b64 exec, -1
	v_lshl_add_u64 v[156:157], v[164:165], 0, s[22:23]
	s_mov_b32 m0, s62
	s_nop 0
	s_mov_b64 exec, s[98:99]
	global_load_lds_dwordx4 v[156:157], off
	s_mov_b64 exec, -1
	v_lshl_add_u64 v[156:157], v[168:169], 0, s[22:23]
	s_mov_b32 m0, s63
	s_nop 0
	s_mov_b64 exec, s[98:99]
	global_load_lds_dwordx4 v[156:157], off
	s_mov_b64 exec, -1
	s_waitcnt vmcnt(8)
	s_waitcnt lgkmcnt(0)
	s_barrier
	s_setprio 1
	s_waitcnt lgkmcnt(0)
	v_mfma_f32_16x16x32_bf16 v[60:63], v[146:149], v[202:205], v[60:63]
	v_mfma_f32_16x16x32_bf16 v[56:59], v[176:179], v[202:205], v[56:59]
	v_mfma_f32_16x16x32_bf16 v[44:47], v[146:149], v[210:213], v[44:47]
	v_mfma_f32_16x16x32_bf16 v[40:43], v[176:179], v[210:213], v[40:43]
	v_mfma_f32_16x16x32_bf16 v[28:31], v[146:149], v[218:221], v[28:31]
	v_mfma_f32_16x16x32_bf16 v[24:27], v[176:179], v[218:221], v[24:27]
	v_mfma_f32_16x16x32_bf16 v[12:15], v[146:149], v[226:229], v[12:15]
	v_mfma_f32_16x16x32_bf16 v[8:11], v[176:179], v[226:229], v[8:11]
	v_mfma_f32_16x16x32_bf16 v[60:63], v[150:153], v[206:209], v[60:63]
	v_mfma_f32_16x16x32_bf16 v[56:59], v[180:183], v[206:209], v[56:59]
	v_mfma_f32_16x16x32_bf16 v[44:47], v[150:153], v[214:217], v[44:47]
	v_mfma_f32_16x16x32_bf16 v[40:43], v[180:183], v[214:217], v[40:43]
	v_mfma_f32_16x16x32_bf16 v[28:31], v[150:153], v[222:225], v[28:31]
	v_mfma_f32_16x16x32_bf16 v[24:27], v[180:183], v[222:225], v[24:27]
	v_mfma_f32_16x16x32_bf16 v[12:15], v[150:153], v[230:233], v[12:15]
	v_mfma_f32_16x16x32_bf16 v[8:11], v[180:183], v[230:233], v[8:11]
	s_setprio 0
	s_setprio 1
	v_mfma_f32_16x16x32_bf16 v[52:55], v[184:187], v[202:205], v[52:55]
	v_mfma_f32_16x16x32_bf16 v[48:51], v[192:195], v[202:205], v[48:51]
	v_mfma_f32_16x16x32_bf16 v[36:39], v[184:187], v[210:213], v[36:39]
	v_mfma_f32_16x16x32_bf16 v[32:35], v[192:195], v[210:213], v[32:35]
	v_mfma_f32_16x16x32_bf16 v[20:23], v[184:187], v[218:221], v[20:23]
	v_mfma_f32_16x16x32_bf16 v[16:19], v[192:195], v[218:221], v[16:19]
	v_mfma_f32_16x16x32_bf16 v[4:7], v[184:187], v[226:229], v[4:7]
	v_mfma_f32_16x16x32_bf16 v[0:3], v[192:195], v[226:229], v[0:3]
	v_mfma_f32_16x16x32_bf16 v[52:55], v[188:191], v[206:209], v[52:55]
	v_mfma_f32_16x16x32_bf16 v[48:51], v[196:199], v[206:209], v[48:51]
	v_mfma_f32_16x16x32_bf16 v[36:39], v[188:191], v[214:217], v[36:39]
	v_mfma_f32_16x16x32_bf16 v[32:35], v[196:199], v[214:217], v[32:35]
	v_mfma_f32_16x16x32_bf16 v[20:23], v[188:191], v[222:225], v[20:23]
	v_mfma_f32_16x16x32_bf16 v[16:19], v[196:199], v[222:225], v[16:19]
	v_mfma_f32_16x16x32_bf16 v[4:7], v[188:191], v[230:233], v[4:7]
	v_mfma_f32_16x16x32_bf16 v[0:3], v[196:199], v[230:233], v[0:3]
	s_setprio 0
	s_barrier
	s_add_i32 s73, s73, 2
	s_add_u32 s71, s71, 0x100
	s_addc_u32 s72, s72, 0
	s_add_u32 s50, s50, 0x100
	s_addc_u32 s51, s51, 0
	s_cmp_gt_u32 s73, 13
	s_branch .Lpost7

; #define PG8_STAGE(bufoff, gbase, voff) do { _Pragma("unroll") for (int _i = 0; _i < 2; ++_i) \
;         __builtin_amdgcn_global_load_lds((const unsigned*)((const char*)(gbase) + (voff)[_i]), (PG8_LAS unsigned*)(lds + (bufoff) + ldsw + _i * 8192), 16, 0, 0); } while (0)
; #define PG8_LDA(dst, b, h) do { _Pragma("unroll") for (int m = 0; m < 4; ++m) _Pragma("unroll") for (int k = 0; k < 2; ++k) dst[m][k] = *(const PG8_LAS bf16x8*)(lds + PG8_SA(b, h) + aoff + m * 2048 + k * 1024); } while (0)
; #define PG8_LDB(dst, b, h) do { _Pragma("unroll") for (int n = 0; n < 2; ++n) _Pragma("unroll") for (int k = 0; k < 2; ++k) dst[n][k] = *(const PG8_LAS bf16x8*)(lds + PG8_SB(b, h) + boff + n * 2048 + k * 1024); } while (0)
; #define PG8_MMA(ai, bj, At, Bt) do { __builtin_amdgcn_s_setprio(1); _Pragma("unroll") for (int m = 0; m < 4; ++m) _Pragma("unroll") for (int n = 0; n < 2; ++n) _Pragma("unroll") for (int k = 0; k < 2; ++k) \
;         acc[ai][bj][m][n] = __builtin_amdgcn_mfma_f32_16x16x32_bf16(Bt[n][k], At[m][k], acc[ai][bj][m][n], 0, 0, 0); __builtin_amdgcn_s_setprio(0); } while (0)
; #define PG8_WAIT_V(n) asm volatile("s_waitcnt vmcnt(" #n ")" ::: "memory")
; #define PG8_BAR __builtin_amdgcn_s_barrier()
; template <class Epi, class Sched, bool ALIGN_EPI = false, bool SP2 = false>
; __device__ __forceinline__ void gemm_phase(PG8_LAS unsigned char* lds, const Gemm g, const Sched& S, const Epi& E, int tid_in) {
;     ...
;         for (int t = 0; t < nt; t += 2) {
;             const bool last = (t == nt - 2);
;             const char* a1 = cA + (size_t)(t + 1) * kstep;
;             const char* a2 = last ? nA : cA + (size_t)(t + 2) * kstep; const char* b2 = last ? nB : cB + (size_t)(t + 2) * kstep;
;             const char* a3 = a2 + kstep; const char* b3 = b2 + kstep;
;             if (last && has_next) S.a_ready(nxt);
;             if constexpr (SP2) {
;             PG8_LDB(B0, 0, 0); PG8_LDB(B1, 0, 1); PG8_SCHED; PG8_LDA(At, 0, 0); PG8_STAGE(PG8_SA(1, 1), a1 + hstep, voffA);
;             PG8_WAIT_V(8); PG8_WAIT_L(0); PG8_BAR; PG8_MMA(0, 0, At, B0); PG8_MMA(0, 1, At, B1); PG8_BAR; PG8_SCHED;
;             PG8_LDA(At, 0, 1); PG8_STAGE(PG8_SB(0, 0), b2, voffB); PG8_STAGE(PG8_SB(0, 1), b2 + hstep, voffB); PG8_STAGE(PG8_SA(0, 0), a2, voffA);
;             PG8_WAIT_V(8); PG8_WAIT_L(0); PG8_BAR; PG8_MMA(1, 0, At, B0); PG8_MMA(1, 1, At, B1); PG8_BAR; PG8_SCHED;
.LBB0_1078:
	ds_read_b128 v[120:123], v189
	ds_read_b128 v[132:135], v189 offset:1024
	ds_read_b128 v[136:139], v189 offset:2048
	ds_read_b128 v[140:143], v189 offset:3072
	ds_read_b128 v[144:147], v190
	ds_read_b128 v[148:151], v190 offset:1024
	ds_read_b128 v[168:171], v190 offset:2048
	ds_read_b128 v[172:175], v190 offset:3072
	s_add_u32 s52, s50, 0x100
	s_addc_u32 s53, s51, 0
	s_cmp_eq_u32 s78, 40
	s_cselect_b32 s57, s21, s53
	s_cselect_b32 s56, s20, s52
	s_cselect_b32 s55, s49, s76
	s_cselect_b32 s54, s48, s73
	s_cbranch_scc1 .Lpk8
	v_lshl_add_u64 v[184:185], s[50:51], 0, v[162:163]
	s_add_i32 m0, s40, 0xc000
	ds_read_b128 v[176:179], v191
	ds_read_b128 v[180:183], v191 offset:1024
	ds_read_b128 v[192:195], v191 offset:2048
	ds_read_b128 v[196:199], v191 offset:3072
	ds_read_b128 v[202:205], v191 offset:4096
	ds_read_b128 v[206:209], v191 offset:5120
	ds_read_b128 v[210:213], v191 offset:6144
	ds_read_b128 v[214:217], v191 offset:7168
	global_load_lds_dwordx4 v[184:185], off
	v_lshl_add_u64 v[184:185], s[50:51], 0, v[160:161]
	s_add_i32 m0, s40, 0xe000
	s_nop 0
	global_load_lds_dwordx4 v[184:185], off
	s_waitcnt vmcnt(8)
	s_waitcnt lgkmcnt(0)
	s_barrier
	s_setprio 1
	s_waitcnt lgkmcnt(0)
	v_mfma_f32_16x16x32_bf16 v[128:131], v[120:123], v[176:179], v[128:131]
	v_mfma_f32_16x16x32_bf16 v[124:127], v[136:139], v[176:179], v[124:127]
	v_mfma_f32_16x16x32_bf16 v[108:111], v[120:123], v[192:195], v[108:111]
	v_mfma_f32_16x16x32_bf16 v[104:107], v[136:139], v[192:195], v[104:107]
	v_mfma_f32_16x16x32_bf16 v[92:95], v[120:123], v[202:205], v[92:95]
	v_mfma_f32_16x16x32_bf16 v[88:91], v[136:139], v[202:205], v[88:91]
	v_mfma_f32_16x16x32_bf16 v[76:79], v[120:123], v[210:213], v[76:79]
	v_mfma_f32_16x16x32_bf16 v[72:75], v[136:139], v[210:213], v[72:75]
	v_mfma_f32_16x16x32_bf16 v[128:131], v[132:135], v[180:183], v[128:131]
	v_mfma_f32_16x16x32_bf16 v[124:127], v[140:143], v[180:183], v[124:127]
	v_mfma_f32_16x16x32_bf16 v[108:111], v[132:135], v[196:199], v[108:111]
	v_mfma_f32_16x16x32_bf16 v[104:107], v[140:143], v[196:199], v[104:107]
	v_mfma_f32_16x16x32_bf16 v[92:95], v[132:135], v[206:209], v[92:95]
	v_mfma_f32_16x16x32_bf16 v[88:91], v[140:143], v[206:209], v[88:91]
	v_mfma_f32_16x16x32_bf16 v[76:79], v[132:135], v[214:217], v[76:79]
	v_mfma_f32_16x16x32_bf16 v[72:75], v[140:143], v[214:217], v[72:75]
	s_setprio 0
	s_setprio 1
	v_mfma_f32_16x16x32_bf16 v[116:119], v[144:147], v[176:179], v[116:119]
	v_mfma_f32_16x16x32_bf16 v[112:115], v[168:171], v[176:179], v[112:115]
	v_mfma_f32_16x16x32_bf16 v[100:103], v[144:147], v[192:195], v[100:103]
	v_mfma_f32_16x16x32_bf16 v[96:99], v[168:171], v[192:195], v[96:99]
	v_mfma_f32_16x16x32_bf16 v[84:87], v[144:147], v[202:205], v[84:87]
	v_mfma_f32_16x16x32_bf16 v[80:83], v[168:171], v[202:205], v[80:83]
	v_mfma_f32_16x16x32_bf16 v[68:71], v[144:147], v[210:213], v[68:71]
	v_mfma_f32_16x16x32_bf16 v[64:67], v[168:171], v[210:213], v[64:67]
	v_mfma_f32_16x16x32_bf16 v[116:119], v[148:151], v[180:183], v[116:119]
	v_mfma_f32_16x16x32_bf16 v[112:115], v[172:175], v[180:183], v[112:115]
	v_mfma_f32_16x16x32_bf16 v[100:103], v[148:151], v[196:199], v[100:103]
	v_mfma_f32_16x16x32_bf16 v[96:99], v[172:175], v[196:199], v[96:99]
	v_mfma_f32_16x16x32_bf16 v[84:87], v[148:151], v[206:209], v[84:87]
	v_mfma_f32_16x16x32_bf16 v[80:83], v[172:175], v[206:209], v[80:83]
	v_mfma_f32_16x16x32_bf16 v[68:71], v[148:151], v[214:217], v[68:71]
	v_mfma_f32_16x16x32_bf16 v[64:67], v[172:175], v[214:217], v[64:67]
	s_setprio 0
	s_barrier
	s_add_i32 s4, s67, s33
	v_lshl_add_u64 v[184:185], s[54:55], 0, v[154:155]
	s_mov_b32 m0, s4
	ds_read_b128 v[176:179], v191 offset:16384
	ds_read_b128 v[180:183], v191 offset:17408
	ds_read_b128 v[192:195], v191 offset:18432
	ds_read_b128 v[196:199], v191 offset:19456
	ds_read_b128 v[202:205], v191 offset:20480
	ds_read_b128 v[206:209], v191 offset:21504
	ds_read_b128 v[210:213], v191 offset:22528
	ds_read_b128 v[214:217], v191 offset:23552
	global_load_lds_dwordx4 v[184:185], off
	s_add_i32 m0, s4, 0x2000
	s_add_u32 s14, s54, 0xb0000
	v_lshl_add_u64 v[218:219], s[54:55], 0, v[158:159]
	s_addc_u32 s15, s55, 0
	s_add_i32 s4, s68, s33
	global_load_lds_dwordx4 v[218:219], off
	v_lshl_add_u64 v[220:221], s[14:15], 0, v[154:155]
	s_mov_b32 m0, s4
	v_lshl_add_u64 v[222:223], s[56:57], 0, v[156:157]
	global_load_lds_dwordx4 v[220:221], off
	v_lshl_add_u64 v[220:221], s[14:15], 0, v[158:159]
	s_add_i32 m0, s4, 0x2000
	s_nop 0
	global_load_lds_dwordx4 v[220:221], off
	v_lshl_add_u64 v[220:221], s[56:57], 0, v[152:153]
	s_mov_b32 m0, s40
	s_nop 0
	global_load_lds_dwordx4 v[220:221], off
	s_mov_b32 m0, s58
	s_nop 0
	global_load_lds_dwordx4 v[222:223], off
	s_waitcnt vmcnt(8)
	s_waitcnt lgkmcnt(0)
	s_barrier
; #define PG8_STAGE(bufoff, gbase, voff) do { _Pragma("unroll") for (int _i = 0; _i < 2; ++_i) \
;         __builtin_amdgcn_global_load_lds((const unsigned*)((const char*)(gbase) + (voff)[_i]), (PG8_LAS unsigned*)(lds + (bufoff) + ldsw + _i * 8192), 16, 0, 0); } while (0)
; #define PG8_LDA(dst, b, h) do { _Pragma("unroll") for (int m = 0; m < 4; ++m) _Pragma("unroll") for (int k = 0; k < 2; ++k) dst[m][k] = *(const PG8_LAS bf16x8*)(lds + PG8_SA(b, h) + aoff + m * 2048 + k * 1024); } while (0)
; #define PG8_LDB(dst, b, h) do { _Pragma("unroll") for (int n = 0; n < 2; ++n) _Pragma("unroll") for (int k = 0; k < 2; ++k) dst[n][k] = *(const PG8_LAS bf16x8*)(lds + PG8_SB(b, h) + boff + n * 2048 + k * 1024); } while (0)
; #define PG8_MMA(ai, bj, At, Bt) do { __builtin_amdgcn_s_setprio(1); _Pragma("unroll") for (int m = 0; m < 4; ++m) _Pragma("unroll") for (int n = 0; n < 2; ++n) _Pragma("unroll") for (int k = 0; k < 2; ++k) \
;         acc[ai][bj][m][n] = __builtin_amdgcn_mfma_f32_16x16x32_bf16(Bt[n][k], At[m][k], acc[ai][bj][m][n], 0, 0, 0); __builtin_amdgcn_s_setprio(0); } while (0)
; #define PG8_WAIT_V(n) asm volatile("s_waitcnt vmcnt(" #n ")" ::: "memory")
; #define PG8_WAIT_L(n) asm volatile("s_waitcnt lgkmcnt(" #n ")" ::: "memory")
; #define PG8_BAR __builtin_amdgcn_s_barrier()
; #define PG8_SCHED __builtin_amdgcn_sched_barrier(0)
; template <class Epi, class Sched, bool ALIGN_EPI = false, bool SP2 = false>
; __device__ __forceinline__ void gemm_phase(PG8_LAS unsigned char* lds, const Gemm g, const Sched& S, const Epi& E, int tid_in) {
;     ...
;             PG8_WAIT_V(8); PG8_WAIT_L(0); PG8_BAR; PG8_MMA(1, 0, At, B0); PG8_MMA(1, 1, At, B1); PG8_BAR; PG8_SCHED;
;             PG8_LDB(B0, 1, 0); PG8_LDB(B1, 1, 1); PG8_SCHED; PG8_LDA(At, 1, 0); PG8_STAGE(PG8_SA(0, 1), a2 + hstep, voffA);
;             PG8_WAIT_V(8); PG8_WAIT_L(0); PG8_BAR; PG8_MMA(0, 0, At, B0); PG8_MMA(0, 1, At, B1); PG8_BAR; PG8_SCHED;
	s_setprio 1
	s_waitcnt lgkmcnt(0)
	v_mfma_f32_16x16x32_bf16 v[60:63], v[120:123], v[176:179], v[60:63]
	v_mfma_f32_16x16x32_bf16 v[56:59], v[136:139], v[176:179], v[56:59]
	v_mfma_f32_16x16x32_bf16 v[44:47], v[120:123], v[192:195], v[44:47]
	v_mfma_f32_16x16x32_bf16 v[40:43], v[136:139], v[192:195], v[40:43]
	v_mfma_f32_16x16x32_bf16 v[28:31], v[120:123], v[202:205], v[28:31]
	v_mfma_f32_16x16x32_bf16 v[24:27], v[136:139], v[202:205], v[24:27]
	v_mfma_f32_16x16x32_bf16 v[12:15], v[120:123], v[210:213], v[12:15]
	v_mfma_f32_16x16x32_bf16 v[8:11], v[136:139], v[210:213], v[8:11]
	v_mfma_f32_16x16x32_bf16 v[60:63], v[132:135], v[180:183], v[60:63]
	v_mfma_f32_16x16x32_bf16 v[56:59], v[140:143], v[180:183], v[56:59]
	v_mfma_f32_16x16x32_bf16 v[44:47], v[132:135], v[196:199], v[44:47]
	v_mfma_f32_16x16x32_bf16 v[40:43], v[140:143], v[196:199], v[40:43]
	v_mfma_f32_16x16x32_bf16 v[28:31], v[132:135], v[206:209], v[28:31]
	v_mfma_f32_16x16x32_bf16 v[24:27], v[140:143], v[206:209], v[24:27]
	v_mfma_f32_16x16x32_bf16 v[12:15], v[132:135], v[214:217], v[12:15]
	v_mfma_f32_16x16x32_bf16 v[8:11], v[140:143], v[214:217], v[8:11]
	s_setprio 0
	s_setprio 1
	v_mfma_f32_16x16x32_bf16 v[52:55], v[144:147], v[176:179], v[52:55]
	v_mfma_f32_16x16x32_bf16 v[48:51], v[168:171], v[176:179], v[48:51]
	v_mfma_f32_16x16x32_bf16 v[36:39], v[144:147], v[192:195], v[36:39]
	v_mfma_f32_16x16x32_bf16 v[32:35], v[168:171], v[192:195], v[32:35]
	v_mfma_f32_16x16x32_bf16 v[20:23], v[144:147], v[202:205], v[20:23]
	v_mfma_f32_16x16x32_bf16 v[16:19], v[168:171], v[202:205], v[16:19]
	v_mfma_f32_16x16x32_bf16 v[4:7], v[144:147], v[210:213], v[4:7]
	v_mfma_f32_16x16x32_bf16 v[0:3], v[168:171], v[210:213], v[0:3]
	v_mfma_f32_16x16x32_bf16 v[52:55], v[148:151], v[180:183], v[52:55]
	v_mfma_f32_16x16x32_bf16 v[48:51], v[172:175], v[180:183], v[48:51]
	v_mfma_f32_16x16x32_bf16 v[36:39], v[148:151], v[196:199], v[36:39]
	v_mfma_f32_16x16x32_bf16 v[32:35], v[172:175], v[196:199], v[32:35]
	v_mfma_f32_16x16x32_bf16 v[20:23], v[148:151], v[206:209], v[20:23]
	v_mfma_f32_16x16x32_bf16 v[16:19], v[172:175], v[206:209], v[16:19]
	v_mfma_f32_16x16x32_bf16 v[4:7], v[148:151], v[214:217], v[4:7]
	v_mfma_f32_16x16x32_bf16 v[0:3], v[172:175], v[214:217], v[0:3]
	s_setprio 0
	s_barrier
	s_add_i32 s4, 0, 0x18000
	s_add_i32 s5, 0, 0x1c000
	v_add_u32_e32 v140, s4, v187
	v_add_u32_e32 v172, s5, v187
	ds_read_b128 v[120:123], v140
	ds_read_b128 v[132:135], v140 offset:1024
	ds_read_b128 v[136:139], v140 offset:2048
	ds_read_b128 v[140:143], v140 offset:3072
	ds_read_b128 v[144:147], v172
	ds_read_b128 v[148:151], v172 offset:1024
	ds_read_b128 v[168:171], v172 offset:2048
	ds_read_b128 v[172:175], v172 offset:3072
	s_add_u32 s14, s56, 0xb0000
	s_addc_u32 s15, s57, 0
	s_mov_b32 m0, s59
	v_lshl_add_u64 v[224:225], s[14:15], 0, v[152:153]
	ds_read_b128 v[176:179], v191 offset:32768
	ds_read_b128 v[180:183], v191 offset:33792
	ds_read_b128 v[192:195], v191 offset:34816
	ds_read_b128 v[196:199], v191 offset:35840
	ds_read_b128 v[202:205], v191 offset:36864
	ds_read_b128 v[206:209], v191 offset:37888
	ds_read_b128 v[210:213], v191 offset:38912
	ds_read_b128 v[214:217], v191 offset:39936
	global_load_lds_dwordx4 v[224:225], off
	v_lshl_add_u64 v[224:225], s[14:15], 0, v[156:157]
	s_mov_b32 m0, s60
	s_nop 0
	global_load_lds_dwordx4 v[224:225], off
	s_waitcnt vmcnt(8)
	s_waitcnt lgkmcnt(0)
	s_barrier
	s_setprio 1
	s_waitcnt lgkmcnt(0)
	v_mfma_f32_16x16x32_bf16 v[128:131], v[120:123], v[176:179], v[128:131]
	v_mfma_f32_16x16x32_bf16 v[124:127], v[136:139], v[176:179], v[124:127]
	v_mfma_f32_16x16x32_bf16 v[108:111], v[120:123], v[192:195], v[108:111]
	v_mfma_f32_16x16x32_bf16 v[104:107], v[136:139], v[192:195], v[104:107]
	v_mfma_f32_16x16x32_bf16 v[92:95], v[120:123], v[202:205], v[92:95]
	v_mfma_f32_16x16x32_bf16 v[88:91], v[136:139], v[202:205], v[88:91]
	v_mfma_f32_16x16x32_bf16 v[76:79], v[120:123], v[210:213], v[76:79]
	v_mfma_f32_16x16x32_bf16 v[72:75], v[136:139], v[210:213], v[72:75]
	v_mfma_f32_16x16x32_bf16 v[128:131], v[132:135], v[180:183], v[128:131]
	v_mfma_f32_16x16x32_bf16 v[124:127], v[140:143], v[180:183], v[124:127]
	v_mfma_f32_16x16x32_bf16 v[108:111], v[132:135], v[196:199], v[108:111]
	v_mfma_f32_16x16x32_bf16 v[104:107], v[140:143], v[196:199], v[104:107]
	v_mfma_f32_16x16x32_bf16 v[92:95], v[132:135], v[206:209], v[92:95]
	v_mfma_f32_16x16x32_bf16 v[88:91], v[140:143], v[206:209], v[88:91]
	v_mfma_f32_16x16x32_bf16 v[76:79], v[132:135], v[214:217], v[76:79]
	v_mfma_f32_16x16x32_bf16 v[72:75], v[140:143], v[214:217], v[72:75]
	s_setprio 0
	s_setprio 1
	v_mfma_f32_16x16x32_bf16 v[116:119], v[144:147], v[176:179], v[116:119]
	v_mfma_f32_16x16x32_bf16 v[112:115], v[168:171], v[176:179], v[112:115]
	v_mfma_f32_16x16x32_bf16 v[100:103], v[144:147], v[192:195], v[100:103]
	v_mfma_f32_16x16x32_bf16 v[96:99], v[168:171], v[192:195], v[96:99]
	v_mfma_f32_16x16x32_bf16 v[84:87], v[144:147], v[202:205], v[84:87]
	v_mfma_f32_16x16x32_bf16 v[80:83], v[168:171], v[202:205], v[80:83]
	v_mfma_f32_16x16x32_bf16 v[68:71], v[144:147], v[210:213], v[68:71]
	v_mfma_f32_16x16x32_bf16 v[64:67], v[168:171], v[210:213], v[64:67]
	v_mfma_f32_16x16x32_bf16 v[116:119], v[148:151], v[180:183], v[116:119]
	v_mfma_f32_16x16x32_bf16 v[112:115], v[172:175], v[180:183], v[112:115]
	v_mfma_f32_16x16x32_bf16 v[100:103], v[148:151], v[196:199], v[100:103]
	v_mfma_f32_16x16x32_bf16 v[96:99], v[172:175], v[196:199], v[96:99]
	v_mfma_f32_16x16x32_bf16 v[84:87], v[148:151], v[206:209], v[84:87]
	v_mfma_f32_16x16x32_bf16 v[80:83], v[172:175], v[206:209], v[80:83]
	v_mfma_f32_16x16x32_bf16 v[68:71], v[148:151], v[214:217], v[68:71]
	v_mfma_f32_16x16x32_bf16 v[64:67], v[172:175], v[214:217], v[64:67]
	s_setprio 0
	s_barrier
; #define PG8_STAGE(bufoff, gbase, voff) do { _Pragma("unroll") for (int _i = 0; _i < 2; ++_i) \
;         __builtin_amdgcn_global_load_lds((const unsigned*)((const char*)(gbase) + (voff)[_i]), (PG8_LAS unsigned*)(lds + (bufoff) + ldsw + _i * 8192), 16, 0, 0); } while (0)
; #define PG8_LDA(dst, b, h) do { _Pragma("unroll") for (int m = 0; m < 4; ++m) _Pragma("unroll") for (int k = 0; k < 2; ++k) dst[m][k] = *(const PG8_LAS bf16x8*)(lds + PG8_SA(b, h) + aoff + m * 2048 + k * 1024); } while (0)
; #define PG8_MMA(ai, bj, At, Bt) do { __builtin_amdgcn_s_setprio(1); _Pragma("unroll") for (int m = 0; m < 4; ++m) _Pragma("unroll") for (int n = 0; n < 2; ++n) _Pragma("unroll") for (int k = 0; k < 2; ++k) \
;         acc[ai][bj][m][n] = __builtin_amdgcn_mfma_f32_16x16x32_bf16(Bt[n][k], At[m][k], acc[ai][bj][m][n], 0, 0, 0); __builtin_amdgcn_s_setprio(0); } while (0)
; #define PG8_WAIT_V(n) asm volatile("s_waitcnt vmcnt(" #n ")" ::: "memory")
; #define PG8_WAIT_L(n) asm volatile("s_waitcnt lgkmcnt(" #n ")" ::: "memory")
; #define PG8_BAR __builtin_amdgcn_s_barrier()
; #define PG8_SCHED __builtin_amdgcn_sched_barrier(0)
; template <class Epi, class Sched, bool ALIGN_EPI = false, bool SP2 = false>
; __device__ __forceinline__ void gemm_phase(PG8_LAS unsigned char* lds, const Gemm g, const Sched& S, const Epi& E, int tid_in) {
;     ...
;             PG8_LDA(At, 1, 1); PG8_STAGE(PG8_SB(1, 0), b3, voffB); PG8_STAGE(PG8_SB(1, 1), b3 + hstep, voffB); PG8_STAGE(PG8_SA(1, 0), a3, voffA);
;             PG8_WAIT_V(8); PG8_WAIT_L(0); PG8_BAR; PG8_MMA(1, 0, At, B0); PG8_MMA(1, 1, At, B1); PG8_BAR; PG8_SCHED;
	s_add_i32 s4, s4, s33
	v_lshl_add_u64 v[184:185], v[184:185], 0, s[44:45]
	s_mov_b32 m0, s4
	ds_read_b128 v[176:179], v191 offset:49152
	ds_read_b128 v[180:183], v191 offset:50176
	ds_read_b128 v[192:195], v191 offset:51200
	ds_read_b128 v[196:199], v191 offset:52224
	ds_read_b128 v[202:205], v191 offset:53248
	ds_read_b128 v[206:209], v191 offset:54272
	ds_read_b128 v[210:213], v191 offset:55296
	ds_read_b128 v[214:217], v191 offset:56320
	global_load_lds_dwordx4 v[184:185], off
	s_add_i32 m0, s4, 0x2000
	s_add_u32 s14, s54, 0xb0080
	v_lshl_add_u64 v[184:185], v[218:219], 0, s[44:45]
	s_addc_u32 s15, s55, 0
	s_add_i32 s4, s5, s33
	global_load_lds_dwordx4 v[184:185], off
	v_lshl_add_u64 v[184:185], s[14:15], 0, v[154:155]
	s_mov_b32 m0, s4
	s_nop 0
	global_load_lds_dwordx4 v[184:185], off
	v_lshl_add_u64 v[184:185], s[14:15], 0, v[158:159]
	s_add_i32 m0, s4, 0x2000
	s_nop 0
	global_load_lds_dwordx4 v[184:185], off
	v_lshl_add_u64 v[184:185], v[220:221], 0, s[44:45]
	s_mov_b32 m0, s62
	s_nop 0
	global_load_lds_dwordx4 v[184:185], off
	v_lshl_add_u64 v[184:185], v[222:223], 0, s[44:45]
	s_mov_b32 m0, s63
	s_nop 0
	global_load_lds_dwordx4 v[184:185], off
	s_waitcnt vmcnt(8)
	s_waitcnt lgkmcnt(0)
	s_barrier
	s_setprio 1
	s_waitcnt lgkmcnt(0)
	v_mfma_f32_16x16x32_bf16 v[60:63], v[120:123], v[176:179], v[60:63]
	v_mfma_f32_16x16x32_bf16 v[56:59], v[136:139], v[176:179], v[56:59]
	v_mfma_f32_16x16x32_bf16 v[44:47], v[120:123], v[192:195], v[44:47]
	v_mfma_f32_16x16x32_bf16 v[40:43], v[136:139], v[192:195], v[40:43]
	v_mfma_f32_16x16x32_bf16 v[28:31], v[120:123], v[202:205], v[28:31]
	v_mfma_f32_16x16x32_bf16 v[24:27], v[136:139], v[202:205], v[24:27]
	v_mfma_f32_16x16x32_bf16 v[12:15], v[120:123], v[210:213], v[12:15]
	v_mfma_f32_16x16x32_bf16 v[8:11], v[136:139], v[210:213], v[8:11]
	v_mfma_f32_16x16x32_bf16 v[60:63], v[132:135], v[180:183], v[60:63]
	v_mfma_f32_16x16x32_bf16 v[56:59], v[140:143], v[180:183], v[56:59]
	v_mfma_f32_16x16x32_bf16 v[44:47], v[132:135], v[196:199], v[44:47]
	v_mfma_f32_16x16x32_bf16 v[40:43], v[140:143], v[196:199], v[40:43]
	v_mfma_f32_16x16x32_bf16 v[28:31], v[132:135], v[206:209], v[28:31]
	v_mfma_f32_16x16x32_bf16 v[24:27], v[140:143], v[206:209], v[24:27]
	v_mfma_f32_16x16x32_bf16 v[12:15], v[132:135], v[214:217], v[12:15]
	v_mfma_f32_16x16x32_bf16 v[8:11], v[140:143], v[214:217], v[8:11]
	s_setprio 0
	s_setprio 1
	v_mfma_f32_16x16x32_bf16 v[52:55], v[144:147], v[176:179], v[52:55]
	v_mfma_f32_16x16x32_bf16 v[48:51], v[168:171], v[176:179], v[48:51]
	v_mfma_f32_16x16x32_bf16 v[36:39], v[144:147], v[192:195], v[36:39]
	v_mfma_f32_16x16x32_bf16 v[32:35], v[168:171], v[192:195], v[32:35]
	v_mfma_f32_16x16x32_bf16 v[20:23], v[144:147], v[202:205], v[20:23]
	v_mfma_f32_16x16x32_bf16 v[16:19], v[168:171], v[202:205], v[16:19]
	v_mfma_f32_16x16x32_bf16 v[4:7], v[144:147], v[210:213], v[4:7]
	v_mfma_f32_16x16x32_bf16 v[0:3], v[168:171], v[210:213], v[0:3]
	v_mfma_f32_16x16x32_bf16 v[52:55], v[148:151], v[180:183], v[52:55]
	v_mfma_f32_16x16x32_bf16 v[48:51], v[172:175], v[180:183], v[48:51]
	v_mfma_f32_16x16x32_bf16 v[36:39], v[148:151], v[196:199], v[36:39]
	v_mfma_f32_16x16x32_bf16 v[32:35], v[172:175], v[196:199], v[32:35]
	v_mfma_f32_16x16x32_bf16 v[20:23], v[148:151], v[206:209], v[20:23]
	v_mfma_f32_16x16x32_bf16 v[16:19], v[172:175], v[206:209], v[16:19]
	v_mfma_f32_16x16x32_bf16 v[4:7], v[148:151], v[214:217], v[4:7]
	v_mfma_f32_16x16x32_bf16 v[0:3], v[172:175], v[214:217], v[0:3]
	s_setprio 0
	s_barrier
	s_add_i32 s78, s78, 2
	s_add_u32 s73, s73, 0x100
	s_addc_u32 s76, s76, 0
	s_cmp_gt_u32 s78, 41
	s_mov_b64 s[50:51], s[52:53]
	s_cbranch_scc0 .LBB0_1078
.Lpost8:
	s_and_b64 vcc, exec, s[46:47]
	s_cbranch_vccz .LBB0_1081
	s_barrier

; #define PG8_STAGE(bufoff, gbase, voff) do { _Pragma("unroll") for (int _i = 0; _i < 2; ++_i) \
;         __builtin_amdgcn_global_load_lds((const unsigned*)((const char*)(gbase) + (voff)[_i]), (PG8_LAS unsigned*)(lds + (bufoff) + ldsw + _i * 8192), 16, 0, 0); } while (0)
; #define PG8_LDA(dst, b, h) do { _Pragma("unroll") for (int m = 0; m < 4; ++m) _Pragma("unroll") for (int k = 0; k < 2; ++k) dst[m][k] = *(const PG8_LAS bf16x8*)(lds + PG8_SA(b, h) + aoff + m * 2048 + k * 1024); } while (0)
; #define PG8_LDB(dst, b, h) do { _Pragma("unroll") for (int n = 0; n < 2; ++n) _Pragma("unroll") for (int k = 0; k < 2; ++k) dst[n][k] = *(const PG8_LAS bf16x8*)(lds + PG8_SB(b, h) + boff + n * 2048 + k * 1024); } while (0)
; #define PG8_MMA(ai, bj, At, Bt) do { __builtin_amdgcn_s_setprio(1); _Pragma("unroll") for (int m = 0; m < 4; ++m) _Pragma("unroll") for (int n = 0; n < 2; ++n) _Pragma("unroll") for (int k = 0; k < 2; ++k) \
;         acc[ai][bj][m][n] = __builtin_amdgcn_mfma_f32_16x16x32_bf16(Bt[n][k], At[m][k], acc[ai][bj][m][n], 0, 0, 0); __builtin_amdgcn_s_setprio(0); } while (0)
; #define PG8_WAIT_V(n) asm volatile("s_waitcnt vmcnt(" #n ")" ::: "memory")
; #define PG8_WAIT_L(n) asm volatile("s_waitcnt lgkmcnt(" #n ")" ::: "memory")
; template <class Epi, class Sched, bool ALIGN_EPI = false, bool SP2 = false>
; __device__ __forceinline__ void gemm_phase(PG8_LAS unsigned char* lds, const Gemm g, const Sched& S, const Epi& E, int tid_in) {
;     ...
;             const bool last = (t == nt - 2);
;             const char* a1 = cA + (size_t)(t + 1) * kstep;
;             const char* a2 = last ? nA : cA + (size_t)(t + 2) * kstep; const char* b2 = last ? nB : cB + (size_t)(t + 2) * kstep;
;             const char* a3 = a2 + kstep; const char* b3 = b2 + kstep;
;             if (last && has_next) S.a_ready(nxt);
;             if constexpr (SP2) {
;             PG8_LDB(B0, 0, 0); PG8_LDB(B1, 0, 1); PG8_SCHED; PG8_LDA(At, 0, 0); PG8_STAGE(PG8_SA(1, 1), a1 + hstep, voffA);
;             PG8_WAIT_V(8); PG8_WAIT_L(0); PG8_BAR; PG8_MMA(0, 0, At, B0); PG8_MMA(0, 1, At, B1); PG8_BAR; PG8_SCHED;
;             PG8_LDA(At, 0, 1); PG8_STAGE(PG8_SB(0, 0), b2, voffB); PG8_STAGE(PG8_SB(0, 1), b2 + hstep, voffB); PG8_STAGE(PG8_SA(0, 0), a2, voffA);
;             PG8_WAIT_V(8); PG8_WAIT_L(0); PG8_BAR; PG8_MMA(1, 0, At, B0); PG8_MMA(1, 1, At, B1); PG8_BAR; PG8_SCHED;
.Lpk8:
	s_mov_b64 s[98:99], 1
	v_lshl_add_u64 v[184:185], s[50:51], 0, v[162:163]
	s_add_i32 m0, s40, 0xc000
	ds_read_b128 v[176:179], v191
	ds_read_b128 v[180:183], v191 offset:1024
	ds_read_b128 v[192:195], v191 offset:2048
	ds_read_b128 v[196:199], v191 offset:3072
	ds_read_b128 v[202:205], v191 offset:4096
	ds_read_b128 v[206:209], v191 offset:5120
	ds_read_b128 v[210:213], v191 offset:6144
	ds_read_b128 v[214:217], v191 offset:7168
	global_load_lds_dwordx4 v[184:185], off
	v_lshl_add_u64 v[184:185], s[50:51], 0, v[160:161]
	s_add_i32 m0, s40, 0xe000
	s_nop 0
	global_load_lds_dwordx4 v[184:185], off
	s_waitcnt vmcnt(8)
	s_waitcnt lgkmcnt(0)
	s_barrier
	s_setprio 1
	s_waitcnt lgkmcnt(0)
	v_mfma_f32_16x16x32_bf16 v[128:131], v[120:123], v[176:179], v[128:131]
	v_mfma_f32_16x16x32_bf16 v[124:127], v[136:139], v[176:179], v[124:127]
	v_mfma_f32_16x16x32_bf16 v[108:111], v[120:123], v[192:195], v[108:111]
	v_mfma_f32_16x16x32_bf16 v[104:107], v[136:139], v[192:195], v[104:107]
	v_mfma_f32_16x16x32_bf16 v[92:95], v[120:123], v[202:205], v[92:95]
	v_mfma_f32_16x16x32_bf16 v[88:91], v[136:139], v[202:205], v[88:91]
	v_mfma_f32_16x16x32_bf16 v[76:79], v[120:123], v[210:213], v[76:79]
	v_mfma_f32_16x16x32_bf16 v[72:75], v[136:139], v[210:213], v[72:75]
	v_mfma_f32_16x16x32_bf16 v[128:131], v[132:135], v[180:183], v[128:131]
	v_mfma_f32_16x16x32_bf16 v[124:127], v[140:143], v[180:183], v[124:127]
	v_mfma_f32_16x16x32_bf16 v[108:111], v[132:135], v[196:199], v[108:111]
	v_mfma_f32_16x16x32_bf16 v[104:107], v[140:143], v[196:199], v[104:107]
	v_mfma_f32_16x16x32_bf16 v[92:95], v[132:135], v[206:209], v[92:95]
	v_mfma_f32_16x16x32_bf16 v[88:91], v[140:143], v[206:209], v[88:91]
	v_mfma_f32_16x16x32_bf16 v[76:79], v[132:135], v[214:217], v[76:79]
	v_mfma_f32_16x16x32_bf16 v[72:75], v[140:143], v[214:217], v[72:75]
	s_setprio 0
	s_setprio 1
	v_mfma_f32_16x16x32_bf16 v[116:119], v[144:147], v[176:179], v[116:119]
	v_mfma_f32_16x16x32_bf16 v[112:115], v[168:171], v[176:179], v[112:115]
	v_mfma_f32_16x16x32_bf16 v[100:103], v[144:147], v[192:195], v[100:103]
	v_mfma_f32_16x16x32_bf16 v[96:99], v[168:171], v[192:195], v[96:99]
	v_mfma_f32_16x16x32_bf16 v[84:87], v[144:147], v[202:205], v[84:87]
	v_mfma_f32_16x16x32_bf16 v[80:83], v[168:171], v[202:205], v[80:83]
	v_mfma_f32_16x16x32_bf16 v[68:71], v[144:147], v[210:213], v[68:71]
	v_mfma_f32_16x16x32_bf16 v[64:67], v[168:171], v[210:213], v[64:67]
	v_mfma_f32_16x16x32_bf16 v[116:119], v[148:151], v[180:183], v[116:119]
	v_mfma_f32_16x16x32_bf16 v[112:115], v[172:175], v[180:183], v[112:115]
	v_mfma_f32_16x16x32_bf16 v[100:103], v[148:151], v[196:199], v[100:103]
	v_mfma_f32_16x16x32_bf16 v[96:99], v[172:175], v[196:199], v[96:99]
	v_mfma_f32_16x16x32_bf16 v[84:87], v[148:151], v[206:209], v[84:87]
	v_mfma_f32_16x16x32_bf16 v[80:83], v[172:175], v[206:209], v[80:83]
	v_mfma_f32_16x16x32_bf16 v[68:71], v[148:151], v[214:217], v[68:71]
	v_mfma_f32_16x16x32_bf16 v[64:67], v[172:175], v[214:217], v[64:67]
	s_setprio 0
	s_barrier
	s_add_i32 s4, s67, s33
	v_lshl_add_u64 v[184:185], s[54:55], 0, v[154:155]
	s_mov_b32 m0, s4
	ds_read_b128 v[176:179], v191 offset:16384
	ds_read_b128 v[180:183], v191 offset:17408
	ds_read_b128 v[192:195], v191 offset:18432
	ds_read_b128 v[196:199], v191 offset:19456
	ds_read_b128 v[202:205], v191 offset:20480
	ds_read_b128 v[206:209], v191 offset:21504
	ds_read_b128 v[210:213], v191 offset:22528
	ds_read_b128 v[214:217], v191 offset:23552
	s_mov_b64 exec, s[98:99]
	global_load_lds_dwordx4 v[184:185], off
	s_mov_b64 exec, -1
	s_add_i32 m0, s4, 0x2000
	s_add_u32 s14, s54, 0xb0000
	v_lshl_add_u64 v[218:219], s[54:55], 0, v[158:159]
	s_addc_u32 s15, s55, 0
	s_add_i32 s4, s68, s33
	s_mov_b64 exec, s[98:99]
	global_load_lds_dwordx4 v[218:219], off
	s_mov_b64 exec, -1
	v_lshl_add_u64 v[220:221], s[14:15], 0, v[154:155]
	s_mov_b32 m0, s4
	v_lshl_add_u64 v[222:223], s[56:57], 0, v[156:157]
	s_mov_b64 exec, s[98:99]
	global_load_lds_dwordx4 v[220:221], off
	s_mov_b64 exec, -1
	v_lshl_add_u64 v[220:221], s[14:15], 0, v[158:159]
	s_add_i32 m0, s4, 0x2000
	s_nop 0
	s_mov_b64 exec, s[98:99]
	global_load_lds_dwordx4 v[220:221], off
	s_mov_b64 exec, -1
	v_lshl_add_u64 v[220:221], s[56:57], 0, v[152:153]
	s_mov_b32 m0, s40
	s_nop 0
	s_mov_b64 exec, s[98:99]
	global_load_lds_dwordx4 v[220:221], off
	s_mov_b64 exec, -1
	s_mov_b32 m0, s58
	s_nop 0
	s_mov_b64 exec, s[98:99]
	global_load_lds_dwordx4 v[222:223], off
	s_mov_b64 exec, -1
	s_waitcnt vmcnt(8)
	s_waitcnt lgkmcnt(0)
	s_barrier
; #define PG8_STAGE(bufoff, gbase, voff) do { _Pragma("unroll") for (int _i = 0; _i < 2; ++_i) \
;         __builtin_amdgcn_global_load_lds((const unsigned*)((const char*)(gbase) + (voff)[_i]), (PG8_LAS unsigned*)(lds + (bufoff) + ldsw + _i * 8192), 16, 0, 0); } while (0)
; #define PG8_LDA(dst, b, h) do { _Pragma("unroll") for (int m = 0; m < 4; ++m) _Pragma("unroll") for (int k = 0; k < 2; ++k) dst[m][k] = *(const PG8_LAS bf16x8*)(lds + PG8_SA(b, h) + aoff + m * 2048 + k * 1024); } while (0)
; #define PG8_LDB(dst, b, h) do { _Pragma("unroll") for (int n = 0; n < 2; ++n) _Pragma("unroll") for (int k = 0; k < 2; ++k) dst[n][k] = *(const PG8_LAS bf16x8*)(lds + PG8_SB(b, h) + boff + n * 2048 + k * 1024); } while (0)
; #define PG8_MMA(ai, bj, At, Bt) do { __builtin_amdgcn_s_setprio(1); _Pragma("unroll") for (int m = 0; m < 4; ++m) _Pragma("unroll") for (int n = 0; n < 2; ++n) _Pragma("unroll") for (int k = 0; k < 2; ++k) \
;         acc[ai][bj][m][n] = __builtin_amdgcn_mfma_f32_16x16x32_bf16(Bt[n][k], At[m][k], acc[ai][bj][m][n], 0, 0, 0); __builtin_amdgcn_s_setprio(0); } while (0)
; #define PG8_WAIT_V(n) asm volatile("s_waitcnt vmcnt(" #n ")" ::: "memory")
; #define PG8_WAIT_L(n) asm volatile("s_waitcnt lgkmcnt(" #n ")" ::: "memory")
; #define PG8_BAR __builtin_amdgcn_s_barrier()
; #define PG8_SCHED __builtin_amdgcn_sched_barrier(0)
; template <class Epi, class Sched, bool ALIGN_EPI = false, bool SP2 = false>
; __device__ __forceinline__ void gemm_phase(PG8_LAS unsigned char* lds, const Gemm g, const Sched& S, const Epi& E, int tid_in) {
;     ...
;             PG8_WAIT_V(8); PG8_WAIT_L(0); PG8_BAR; PG8_MMA(1, 0, At, B0); PG8_MMA(1, 1, At, B1); PG8_BAR; PG8_SCHED;
;             PG8_LDB(B0, 1, 0); PG8_LDB(B1, 1, 1); PG8_SCHED; PG8_LDA(At, 1, 0); PG8_STAGE(PG8_SA(0, 1), a2 + hstep, voffA);
;             PG8_WAIT_V(8); PG8_WAIT_L(0); PG8_BAR; PG8_MMA(0, 0, At, B0); PG8_MMA(0, 1, At, B1); PG8_BAR; PG8_SCHED;
	s_setprio 1
	s_waitcnt lgkmcnt(0)
	v_mfma_f32_16x16x32_bf16 v[60:63], v[120:123], v[176:179], v[60:63]
	v_mfma_f32_16x16x32_bf16 v[56:59], v[136:139], v[176:179], v[56:59]
	v_mfma_f32_16x16x32_bf16 v[44:47], v[120:123], v[192:195], v[44:47]
	v_mfma_f32_16x16x32_bf16 v[40:43], v[136:139], v[192:195], v[40:43]
	v_mfma_f32_16x16x32_bf16 v[28:31], v[120:123], v[202:205], v[28:31]
	v_mfma_f32_16x16x32_bf16 v[24:27], v[136:139], v[202:205], v[24:27]
	v_mfma_f32_16x16x32_bf16 v[12:15], v[120:123], v[210:213], v[12:15]
	v_mfma_f32_16x16x32_bf16 v[8:11], v[136:139], v[210:213], v[8:11]
	v_mfma_f32_16x16x32_bf16 v[60:63], v[132:135], v[180:183], v[60:63]
	v_mfma_f32_16x16x32_bf16 v[56:59], v[140:143], v[180:183], v[56:59]
	v_mfma_f32_16x16x32_bf16 v[44:47], v[132:135], v[196:199], v[44:47]
	v_mfma_f32_16x16x32_bf16 v[40:43], v[140:143], v[196:199], v[40:43]
	v_mfma_f32_16x16x32_bf16 v[28:31], v[132:135], v[206:209], v[28:31]
	v_mfma_f32_16x16x32_bf16 v[24:27], v[140:143], v[206:209], v[24:27]
	v_mfma_f32_16x16x32_bf16 v[12:15], v[132:135], v[214:217], v[12:15]
	v_mfma_f32_16x16x32_bf16 v[8:11], v[140:143], v[214:217], v[8:11]
	s_setprio 0
	s_setprio 1
	v_mfma_f32_16x16x32_bf16 v[52:55], v[144:147], v[176:179], v[52:55]
	v_mfma_f32_16x16x32_bf16 v[48:51], v[168:171], v[176:179], v[48:51]
	v_mfma_f32_16x16x32_bf16 v[36:39], v[144:147], v[192:195], v[36:39]
	v_mfma_f32_16x16x32_bf16 v[32:35], v[168:171], v[192:195], v[32:35]
	v_mfma_f32_16x16x32_bf16 v[20:23], v[144:147], v[202:205], v[20:23]
	v_mfma_f32_16x16x32_bf16 v[16:19], v[168:171], v[202:205], v[16:19]
	v_mfma_f32_16x16x32_bf16 v[4:7], v[144:147], v[210:213], v[4:7]
	v_mfma_f32_16x16x32_bf16 v[0:3], v[168:171], v[210:213], v[0:3]
	v_mfma_f32_16x16x32_bf16 v[52:55], v[148:151], v[180:183], v[52:55]
	v_mfma_f32_16x16x32_bf16 v[48:51], v[172:175], v[180:183], v[48:51]
	v_mfma_f32_16x16x32_bf16 v[36:39], v[148:151], v[196:199], v[36:39]
	v_mfma_f32_16x16x32_bf16 v[32:35], v[172:175], v[196:199], v[32:35]
	v_mfma_f32_16x16x32_bf16 v[20:23], v[148:151], v[206:209], v[20:23]
	v_mfma_f32_16x16x32_bf16 v[16:19], v[172:175], v[206:209], v[16:19]
	v_mfma_f32_16x16x32_bf16 v[4:7], v[148:151], v[214:217], v[4:7]
	v_mfma_f32_16x16x32_bf16 v[0:3], v[172:175], v[214:217], v[0:3]
	s_setprio 0
	s_barrier
	s_add_i32 s4, 0, 0x18000
	s_add_i32 s5, 0, 0x1c000
	v_add_u32_e32 v140, s4, v187
	v_add_u32_e32 v172, s5, v187
	ds_read_b128 v[120:123], v140
	ds_read_b128 v[132:135], v140 offset:1024
	ds_read_b128 v[136:139], v140 offset:2048
	ds_read_b128 v[140:143], v140 offset:3072
	ds_read_b128 v[144:147], v172
	ds_read_b128 v[148:151], v172 offset:1024
	ds_read_b128 v[168:171], v172 offset:2048
	ds_read_b128 v[172:175], v172 offset:3072
	s_add_u32 s14, s56, 0xb0000
	s_addc_u32 s15, s57, 0
	s_mov_b32 m0, s59
	v_lshl_add_u64 v[224:225], s[14:15], 0, v[152:153]
	ds_read_b128 v[176:179], v191 offset:32768
	ds_read_b128 v[180:183], v191 offset:33792
	ds_read_b128 v[192:195], v191 offset:34816
	ds_read_b128 v[196:199], v191 offset:35840
	ds_read_b128 v[202:205], v191 offset:36864
	ds_read_b128 v[206:209], v191 offset:37888
	ds_read_b128 v[210:213], v191 offset:38912
	ds_read_b128 v[214:217], v191 offset:39936
	s_mov_b64 exec, s[98:99]
	global_load_lds_dwordx4 v[224:225], off
	s_mov_b64 exec, -1
	v_lshl_add_u64 v[224:225], s[14:15], 0, v[156:157]
	s_mov_b32 m0, s60
	s_nop 0
	s_mov_b64 exec, s[98:99]
	global_load_lds_dwordx4 v[224:225], off
	s_mov_b64 exec, -1
	s_waitcnt vmcnt(8)
	s_waitcnt lgkmcnt(0)
	s_barrier
	s_setprio 1
	s_waitcnt lgkmcnt(0)
	v_mfma_f32_16x16x32_bf16 v[128:131], v[120:123], v[176:179], v[128:131]
	v_mfma_f32_16x16x32_bf16 v[124:127], v[136:139], v[176:179], v[124:127]
	v_mfma_f32_16x16x32_bf16 v[108:111], v[120:123], v[192:195], v[108:111]
	v_mfma_f32_16x16x32_bf16 v[104:107], v[136:139], v[192:195], v[104:107]
	v_mfma_f32_16x16x32_bf16 v[92:95], v[120:123], v[202:205], v[92:95]
	v_mfma_f32_16x16x32_bf16 v[88:91], v[136:139], v[202:205], v[88:91]
	v_mfma_f32_16x16x32_bf16 v[76:79], v[120:123], v[210:213], v[76:79]
	v_mfma_f32_16x16x32_bf16 v[72:75], v[136:139], v[210:213], v[72:75]
	v_mfma_f32_16x16x32_bf16 v[128:131], v[132:135], v[180:183], v[128:131]
	v_mfma_f32_16x16x32_bf16 v[124:127], v[140:143], v[180:183], v[124:127]
	v_mfma_f32_16x16x32_bf16 v[108:111], v[132:135], v[196:199], v[108:111]
	v_mfma_f32_16x16x32_bf16 v[104:107], v[140:143], v[196:199], v[104:107]
	v_mfma_f32_16x16x32_bf16 v[92:95], v[132:135], v[206:209], v[92:95]
	v_mfma_f32_16x16x32_bf16 v[88:91], v[140:143], v[206:209], v[88:91]
	v_mfma_f32_16x16x32_bf16 v[76:79], v[132:135], v[214:217], v[76:79]
	v_mfma_f32_16x16x32_bf16 v[72:75], v[140:143], v[214:217], v[72:75]
	s_setprio 0
	s_setprio 1
	v_mfma_f32_16x16x32_bf16 v[116:119], v[144:147], v[176:179], v[116:119]
	v_mfma_f32_16x16x32_bf16 v[112:115], v[168:171], v[176:179], v[112:115]
	v_mfma_f32_16x16x32_bf16 v[100:103], v[144:147], v[192:195], v[100:103]
	v_mfma_f32_16x16x32_bf16 v[96:99], v[168:171], v[192:195], v[96:99]
	v_mfma_f32_16x16x32_bf16 v[84:87], v[144:147], v[202:205], v[84:87]
	v_mfma_f32_16x16x32_bf16 v[80:83], v[168:171], v[202:205], v[80:83]
	v_mfma_f32_16x16x32_bf16 v[68:71], v[144:147], v[210:213], v[68:71]
	v_mfma_f32_16x16x32_bf16 v[64:67], v[168:171], v[210:213], v[64:67]
	v_mfma_f32_16x16x32_bf16 v[116:119], v[148:151], v[180:183], v[116:119]
	v_mfma_f32_16x16x32_bf16 v[112:115], v[172:175], v[180:183], v[112:115]
	v_mfma_f32_16x16x32_bf16 v[100:103], v[148:151], v[196:199], v[100:103]
	v_mfma_f32_16x16x32_bf16 v[96:99], v[172:175], v[196:199], v[96:99]
	v_mfma_f32_16x16x32_bf16 v[84:87], v[148:151], v[206:209], v[84:87]
	v_mfma_f32_16x16x32_bf16 v[80:83], v[172:175], v[206:209], v[80:83]
	v_mfma_f32_16x16x32_bf16 v[68:71], v[148:151], v[214:217], v[68:71]
	v_mfma_f32_16x16x32_bf16 v[64:67], v[172:175], v[214:217], v[64:67]
	s_setprio 0
	s_barrier
; #define PG8_STAGE(bufoff, gbase, voff) do { _Pragma("unroll") for (int _i = 0; _i < 2; ++_i) \
;         __builtin_amdgcn_global_load_lds((const unsigned*)((const char*)(gbase) + (voff)[_i]), (PG8_LAS unsigned*)(lds + (bufoff) + ldsw + _i * 8192), 16, 0, 0); } while (0)
; #define PG8_LDA(dst, b, h) do { _Pragma("unroll") for (int m = 0; m < 4; ++m) _Pragma("unroll") for (int k = 0; k < 2; ++k) dst[m][k] = *(const PG8_LAS bf16x8*)(lds + PG8_SA(b, h) + aoff + m * 2048 + k * 1024); } while (0)
; #define PG8_MMA(ai, bj, At, Bt) do { __builtin_amdgcn_s_setprio(1); _Pragma("unroll") for (int m = 0; m < 4; ++m) _Pragma("unroll") for (int n = 0; n < 2; ++n) _Pragma("unroll") for (int k = 0; k < 2; ++k) \
;         acc[ai][bj][m][n] = __builtin_amdgcn_mfma_f32_16x16x32_bf16(Bt[n][k], At[m][k], acc[ai][bj][m][n], 0, 0, 0); __builtin_amdgcn_s_setprio(0); } while (0)
; #define PG8_WAIT_V(n) asm volatile("s_waitcnt vmcnt(" #n ")" ::: "memory")
; #define PG8_WAIT_L(n) asm volatile("s_waitcnt lgkmcnt(" #n ")" ::: "memory")
; #define PG8_BAR __builtin_amdgcn_s_barrier()
; #define PG8_SCHED __builtin_amdgcn_sched_barrier(0)
; template <class Epi, class Sched, bool ALIGN_EPI = false, bool SP2 = false>
; __device__ __forceinline__ void gemm_phase(PG8_LAS unsigned char* lds, const Gemm g, const Sched& S, const Epi& E, int tid_in) {
;     ...
;             PG8_LDA(At, 1, 1); PG8_STAGE(PG8_SB(1, 0), b3, voffB); PG8_STAGE(PG8_SB(1, 1), b3 + hstep, voffB); PG8_STAGE(PG8_SA(1, 0), a3, voffA);
;             PG8_WAIT_V(8); PG8_WAIT_L(0); PG8_BAR; PG8_MMA(1, 0, At, B0); PG8_MMA(1, 1, At, B1); PG8_BAR; PG8_SCHED;
	s_add_i32 s4, s4, s33
	v_lshl_add_u64 v[184:185], v[184:185], 0, s[44:45]
	s_mov_b32 m0, s4
	ds_read_b128 v[176:179], v191 offset:49152
	ds_read_b128 v[180:183], v191 offset:50176
	ds_read_b128 v[192:195], v191 offset:51200
	ds_read_b128 v[196:199], v191 offset:52224
	ds_read_b128 v[202:205], v191 offset:53248
	ds_read_b128 v[206:209], v191 offset:54272
	ds_read_b128 v[210:213], v191 offset:55296
	ds_read_b128 v[214:217], v191 offset:56320
	s_mov_b64 exec, s[98:99]
	global_load_lds_dwordx4 v[184:185], off
	s_mov_b64 exec, -1
	s_add_i32 m0, s4, 0x2000
	s_add_u32 s14, s54, 0xb0080
	v_lshl_add_u64 v[184:185], v[218:219], 0, s[44:45]
	s_addc_u32 s15, s55, 0
	s_add_i32 s4, s5, s33
	s_mov_b64 exec, s[98:99]
	global_load_lds_dwordx4 v[184:185], off
	s_mov_b64 exec, -1
	v_lshl_add_u64 v[184:185], s[14:15], 0, v[154:155]
	s_mov_b32 m0, s4
	s_nop 0
	s_mov_b64 exec, s[98:99]
	global_load_lds_dwordx4 v[184:185], off
	s_mov_b64 exec, -1
	v_lshl_add_u64 v[184:185], s[14:15], 0, v[158:159]
	s_add_i32 m0, s4, 0x2000
	s_nop 0
	s_mov_b64 exec, s[98:99]
	global_load_lds_dwordx4 v[184:185], off
	s_mov_b64 exec, -1
	v_lshl_add_u64 v[184:185], v[220:221], 0, s[44:45]
	s_mov_b32 m0, s62
	s_nop 0
	s_mov_b64 exec, s[98:99]
	global_load_lds_dwordx4 v[184:185], off
	s_mov_b64 exec, -1
	v_lshl_add_u64 v[184:185], v[222:223], 0, s[44:45]
	s_mov_b32 m0, s63
	s_nop 0
	s_mov_b64 exec, s[98:99]
	global_load_lds_dwordx4 v[184:185], off
	s_mov_b64 exec, -1
	s_waitcnt vmcnt(8)
	s_waitcnt lgkmcnt(0)
	s_barrier
	s_setprio 1
	s_waitcnt lgkmcnt(0)
	v_mfma_f32_16x16x32_bf16 v[60:63], v[120:123], v[176:179], v[60:63]
	v_mfma_f32_16x16x32_bf16 v[56:59], v[136:139], v[176:179], v[56:59]
	v_mfma_f32_16x16x32_bf16 v[44:47], v[120:123], v[192:195], v[44:47]
	v_mfma_f32_16x16x32_bf16 v[40:43], v[136:139], v[192:195], v[40:43]
	v_mfma_f32_16x16x32_bf16 v[28:31], v[120:123], v[202:205], v[28:31]
	v_mfma_f32_16x16x32_bf16 v[24:27], v[136:139], v[202:205], v[24:27]
	v_mfma_f32_16x16x32_bf16 v[12:15], v[120:123], v[210:213], v[12:15]
	v_mfma_f32_16x16x32_bf16 v[8:11], v[136:139], v[210:213], v[8:11]
	v_mfma_f32_16x16x32_bf16 v[60:63], v[132:135], v[180:183], v[60:63]
	v_mfma_f32_16x16x32_bf16 v[56:59], v[140:143], v[180:183], v[56:59]
	v_mfma_f32_16x16x32_bf16 v[44:47], v[132:135], v[196:199], v[44:47]
	v_mfma_f32_16x16x32_bf16 v[40:43], v[140:143], v[196:199], v[40:43]
	v_mfma_f32_16x16x32_bf16 v[28:31], v[132:135], v[206:209], v[28:31]
	v_mfma_f32_16x16x32_bf16 v[24:27], v[140:143], v[206:209], v[24:27]
	v_mfma_f32_16x16x32_bf16 v[12:15], v[132:135], v[214:217], v[12:15]
	v_mfma_f32_16x16x32_bf16 v[8:11], v[140:143], v[214:217], v[8:11]
	s_setprio 0
	s_setprio 1
	v_mfma_f32_16x16x32_bf16 v[52:55], v[144:147], v[176:179], v[52:55]
	v_mfma_f32_16x16x32_bf16 v[48:51], v[168:171], v[176:179], v[48:51]
	v_mfma_f32_16x16x32_bf16 v[36:39], v[144:147], v[192:195], v[36:39]
	v_mfma_f32_16x16x32_bf16 v[32:35], v[168:171], v[192:195], v[32:35]
	v_mfma_f32_16x16x32_bf16 v[20:23], v[144:147], v[202:205], v[20:23]
	v_mfma_f32_16x16x32_bf16 v[16:19], v[168:171], v[202:205], v[16:19]
	v_mfma_f32_16x16x32_bf16 v[4:7], v[144:147], v[210:213], v[4:7]
	v_mfma_f32_16x16x32_bf16 v[0:3], v[168:171], v[210:213], v[0:3]
	v_mfma_f32_16x16x32_bf16 v[52:55], v[148:151], v[180:183], v[52:55]
	v_mfma_f32_16x16x32_bf16 v[48:51], v[172:175], v[180:183], v[48:51]
	v_mfma_f32_16x16x32_bf16 v[36:39], v[148:151], v[196:199], v[36:39]
	v_mfma_f32_16x16x32_bf16 v[32:35], v[172:175], v[196:199], v[32:35]
	v_mfma_f32_16x16x32_bf16 v[20:23], v[148:151], v[206:209], v[20:23]
	v_mfma_f32_16x16x32_bf16 v[16:19], v[172:175], v[206:209], v[16:19]
	v_mfma_f32_16x16x32_bf16 v[4:7], v[148:151], v[214:217], v[4:7]
	v_mfma_f32_16x16x32_bf16 v[0:3], v[172:175], v[214:217], v[0:3]
	s_setprio 0
	s_barrier
	s_add_i32 s78, s78, 2
	s_add_u32 s73, s73, 0x100
	s_addc_u32 s76, s76, 0
	s_cmp_gt_u32 s78, 41
	s_mov_b64 s[50:51], s[52:53]
	s_branch .Lpost8

; #define PG8_STAGE(bufoff, gbase, voff) do { _Pragma("unroll") for (int _i = 0; _i < 2; ++_i) \
;         __builtin_amdgcn_global_load_lds((const unsigned*)((const char*)(gbase) + (voff)[_i]), (PG8_LAS unsigned*)(lds + (bufoff) + ldsw + _i * 8192), 16, 0, 0); } while (0)
; #define PG8_LDA(dst, b, h) do { _Pragma("unroll") for (int m = 0; m < 4; ++m) _Pragma("unroll") for (int k = 0; k < 2; ++k) dst[m][k] = *(const PG8_LAS bf16x8*)(lds + PG8_SA(b, h) + aoff + m * 2048 + k * 1024); } while (0)
; #define PG8_LDB(dst, b, h) do { _Pragma("unroll") for (int n = 0; n < 2; ++n) _Pragma("unroll") for (int k = 0; k < 2; ++k) dst[n][k] = *(const PG8_LAS bf16x8*)(lds + PG8_SB(b, h) + boff + n * 2048 + k * 1024); } while (0)
; #define PG8_MMA(ai, bj, At, Bt) do { __builtin_amdgcn_s_setprio(1); _Pragma("unroll") for (int m = 0; m < 4; ++m) _Pragma("unroll") for (int n = 0; n < 2; ++n) _Pragma("unroll") for (int k = 0; k < 2; ++k) \
;         acc[ai][bj][m][n] = __builtin_amdgcn_mfma_f32_16x16x32_bf16(Bt[n][k], At[m][k], acc[ai][bj][m][n], 0, 0, 0); __builtin_amdgcn_s_setprio(0); } while (0)
; #define PG8_WAIT_V(n) asm volatile("s_waitcnt vmcnt(" #n ")" ::: "memory")
; #define PG8_BAR __builtin_amdgcn_s_barrier()
; template <class Epi, class Sched, bool ALIGN_EPI = false, bool SP2 = false>
; __device__ __forceinline__ void gemm_phase(PG8_LAS unsigned char* lds, const Gemm g, const Sched& S, const Epi& E, int tid_in) {
;     ...
;         for (int t = 0; t < nt; t += 2) {
;             const bool last = (t == nt - 2);
;             const char* a1 = cA + (size_t)(t + 1) * kstep;
;             const char* a2 = last ? nA : cA + (size_t)(t + 2) * kstep; const char* b2 = last ? nB : cB + (size_t)(t + 2) * kstep;
;             const char* a3 = a2 + kstep; const char* b3 = b2 + kstep;
;             if (last && has_next) S.a_ready(nxt);
;             if constexpr (SP2) {
;             PG8_LDB(B0, 0, 0); PG8_LDB(B1, 0, 1); PG8_SCHED; PG8_LDA(At, 0, 0); PG8_STAGE(PG8_SA(1, 1), a1 + hstep, voffA);
;             PG8_WAIT_V(8); PG8_WAIT_L(0); PG8_BAR; PG8_MMA(0, 0, At, B0); PG8_MMA(0, 1, At, B1); PG8_BAR; PG8_SCHED;
;             PG8_LDA(At, 0, 1); PG8_STAGE(PG8_SB(0, 0), b2, voffB); PG8_STAGE(PG8_SB(0, 1), b2 + hstep, voffB); PG8_STAGE(PG8_SA(0, 0), a2, voffA);
;             PG8_WAIT_V(8); PG8_WAIT_L(0); PG8_BAR; PG8_MMA(1, 0, At, B0); PG8_MMA(1, 1, At, B1); PG8_BAR; PG8_SCHED;
.LBB0_1188:
	ds_read_b128 v[148:151], v198
	ds_read_b128 v[152:155], v198 offset:1024
	ds_read_b128 v[156:159], v198 offset:2048
	ds_read_b128 v[160:163], v198 offset:3072
	ds_read_b128 v[164:167], v199
	ds_read_b128 v[168:171], v199 offset:1024
	ds_read_b128 v[172:175], v199 offset:2048
	ds_read_b128 v[176:179], v199 offset:3072
	s_add_u32 s4, s46, 0xfffc0080
	s_addc_u32 s5, s47, -1
	s_cmp_eq_u32 s53, 12
	s_cselect_b32 s55, s0, s5
	s_cselect_b32 s54, s13, s4
	s_cselect_b32 s49, s25, s51
	s_cselect_b32 s48, s27, s33
	s_cbranch_scc1 .Lpk9
	v_lshl_add_u64 v[226:227], s[46:47], 0, v[142:143]
	s_add_i32 m0, s62, 0xc000
	ds_read_b128 v[180:183], v200
	ds_read_b128 v[184:187], v200 offset:1024
	ds_read_b128 v[188:191], v200 offset:2048
	ds_read_b128 v[206:209], v200 offset:3072
	ds_read_b128 v[210:213], v200 offset:4096
	ds_read_b128 v[214:217], v200 offset:5120
	ds_read_b128 v[218:221], v200 offset:6144
	ds_read_b128 v[222:225], v200 offset:7168
	global_load_lds_dwordx4 v[226:227], off
	v_lshl_add_u64 v[226:227], s[46:47], 0, v[140:141]
	s_add_i32 m0, s62, 0xe000
	s_nop 0
	global_load_lds_dwordx4 v[226:227], off
	s_waitcnt vmcnt(8)
	s_waitcnt lgkmcnt(0)
	s_barrier
	s_setprio 1
	s_waitcnt lgkmcnt(0)
	v_mfma_f32_16x16x32_bf16 v[124:127], v[148:151], v[180:183], v[124:127]
	v_mfma_f32_16x16x32_bf16 v[120:123], v[156:159], v[180:183], v[120:123]
	v_mfma_f32_16x16x32_bf16 v[108:111], v[148:151], v[188:191], v[108:111]
	v_mfma_f32_16x16x32_bf16 v[104:107], v[156:159], v[188:191], v[104:107]
	v_mfma_f32_16x16x32_bf16 v[92:95], v[148:151], v[210:213], v[92:95]
	v_mfma_f32_16x16x32_bf16 v[88:91], v[156:159], v[210:213], v[88:91]
	v_mfma_f32_16x16x32_bf16 v[76:79], v[148:151], v[218:221], v[76:79]
	v_mfma_f32_16x16x32_bf16 v[72:75], v[156:159], v[218:221], v[72:75]
	v_mfma_f32_16x16x32_bf16 v[124:127], v[152:155], v[184:187], v[124:127]
	v_mfma_f32_16x16x32_bf16 v[120:123], v[160:163], v[184:187], v[120:123]
	v_mfma_f32_16x16x32_bf16 v[108:111], v[152:155], v[206:209], v[108:111]
	v_mfma_f32_16x16x32_bf16 v[104:107], v[160:163], v[206:209], v[104:107]
	v_mfma_f32_16x16x32_bf16 v[92:95], v[152:155], v[214:217], v[92:95]
	v_mfma_f32_16x16x32_bf16 v[88:91], v[160:163], v[214:217], v[88:91]
	v_mfma_f32_16x16x32_bf16 v[76:79], v[152:155], v[222:225], v[76:79]
	v_mfma_f32_16x16x32_bf16 v[72:75], v[160:163], v[222:225], v[72:75]
	s_setprio 0
	s_setprio 1
	v_mfma_f32_16x16x32_bf16 v[116:119], v[164:167], v[180:183], v[116:119]
	v_mfma_f32_16x16x32_bf16 v[112:115], v[172:175], v[180:183], v[112:115]
	v_mfma_f32_16x16x32_bf16 v[100:103], v[164:167], v[188:191], v[100:103]
	v_mfma_f32_16x16x32_bf16 v[96:99], v[172:175], v[188:191], v[96:99]
	v_mfma_f32_16x16x32_bf16 v[84:87], v[164:167], v[210:213], v[84:87]
	v_mfma_f32_16x16x32_bf16 v[80:83], v[172:175], v[210:213], v[80:83]
	v_mfma_f32_16x16x32_bf16 v[68:71], v[164:167], v[218:221], v[68:71]
	v_mfma_f32_16x16x32_bf16 v[64:67], v[172:175], v[218:221], v[64:67]
	v_mfma_f32_16x16x32_bf16 v[116:119], v[168:171], v[184:187], v[116:119]
	v_mfma_f32_16x16x32_bf16 v[112:115], v[176:179], v[184:187], v[112:115]
	v_mfma_f32_16x16x32_bf16 v[100:103], v[168:171], v[206:209], v[100:103]
	v_mfma_f32_16x16x32_bf16 v[96:99], v[176:179], v[206:209], v[96:99]
	v_mfma_f32_16x16x32_bf16 v[84:87], v[168:171], v[214:217], v[84:87]
	v_mfma_f32_16x16x32_bf16 v[80:83], v[176:179], v[214:217], v[80:83]
	v_mfma_f32_16x16x32_bf16 v[68:71], v[168:171], v[222:225], v[68:71]
	v_mfma_f32_16x16x32_bf16 v[64:67], v[176:179], v[222:225], v[64:67]
	s_setprio 0
	s_barrier
	s_add_i32 s4, s73, s61
	v_lshl_add_u64 v[226:227], s[48:49], 0, v[130:131]
	s_mov_b32 m0, s4
	ds_read_b128 v[180:183], v200 offset:16384
	ds_read_b128 v[184:187], v200 offset:17408
	ds_read_b128 v[188:191], v200 offset:18432
	ds_read_b128 v[206:209], v200 offset:19456
	ds_read_b128 v[210:213], v200 offset:20480
	ds_read_b128 v[214:217], v200 offset:21504
	ds_read_b128 v[218:221], v200 offset:22528
	ds_read_b128 v[222:225], v200 offset:23552
	global_load_lds_dwordx4 v[226:227], off
	s_add_i32 m0, s4, 0x2000
	s_add_u32 s56, s48, 0x40000
	v_lshl_add_u64 v[228:229], s[48:49], 0, v[134:135]
	s_addc_u32 s57, s49, 0
	s_add_i32 s4, s40, s61
	global_load_lds_dwordx4 v[228:229], off
	v_lshl_add_u64 v[230:231], s[56:57], 0, v[130:131]
	s_mov_b32 m0, s4
	v_lshl_add_u64 v[232:233], s[54:55], 0, v[132:133]
	global_load_lds_dwordx4 v[230:231], off
	v_lshl_add_u64 v[230:231], s[56:57], 0, v[134:135]
	s_add_i32 m0, s4, 0x2000
	s_nop 0
	global_load_lds_dwordx4 v[230:231], off
	v_lshl_add_u64 v[230:231], s[54:55], 0, v[128:129]
	s_mov_b32 m0, s62
	s_nop 0
	global_load_lds_dwordx4 v[230:231], off
	s_mov_b32 m0, s63
	s_nop 0
	global_load_lds_dwordx4 v[232:233], off
	s_waitcnt vmcnt(8)
	s_waitcnt lgkmcnt(0)
	s_barrier
; #define PG8_STAGE(bufoff, gbase, voff) do { _Pragma("unroll") for (int _i = 0; _i < 2; ++_i) \
;         __builtin_amdgcn_global_load_lds((const unsigned*)((const char*)(gbase) + (voff)[_i]), (PG8_LAS unsigned*)(lds + (bufoff) + ldsw + _i * 8192), 16, 0, 0); } while (0)
; #define PG8_LDA(dst, b, h) do { _Pragma("unroll") for (int m = 0; m < 4; ++m) _Pragma("unroll") for (int k = 0; k < 2; ++k) dst[m][k] = *(const PG8_LAS bf16x8*)(lds + PG8_SA(b, h) + aoff + m * 2048 + k * 1024); } while (0)
; #define PG8_LDB(dst, b, h) do { _Pragma("unroll") for (int n = 0; n < 2; ++n) _Pragma("unroll") for (int k = 0; k < 2; ++k) dst[n][k] = *(const PG8_LAS bf16x8*)(lds + PG8_SB(b, h) + boff + n * 2048 + k * 1024); } while (0)
; #define PG8_MMA(ai, bj, At, Bt) do { __builtin_amdgcn_s_setprio(1); _Pragma("unroll") for (int m = 0; m < 4; ++m) _Pragma("unroll") for (int n = 0; n < 2; ++n) _Pragma("unroll") for (int k = 0; k < 2; ++k) \
;         acc[ai][bj][m][n] = __builtin_amdgcn_mfma_f32_16x16x32_bf16(Bt[n][k], At[m][k], acc[ai][bj][m][n], 0, 0, 0); __builtin_amdgcn_s_setprio(0); } while (0)
; #define PG8_WAIT_V(n) asm volatile("s_waitcnt vmcnt(" #n ")" ::: "memory")
; #define PG8_WAIT_L(n) asm volatile("s_waitcnt lgkmcnt(" #n ")" ::: "memory")
; #define PG8_BAR __builtin_amdgcn_s_barrier()
; #define PG8_SCHED __builtin_amdgcn_sched_barrier(0)
; template <class Epi, class Sched, bool ALIGN_EPI = false, bool SP2 = false>
; __device__ __forceinline__ void gemm_phase(PG8_LAS unsigned char* lds, const Gemm g, const Sched& S, const Epi& E, int tid_in) {
;     ...
;             PG8_WAIT_V(8); PG8_WAIT_L(0); PG8_BAR; PG8_MMA(1, 0, At, B0); PG8_MMA(1, 1, At, B1); PG8_BAR; PG8_SCHED;
;             PG8_LDB(B0, 1, 0); PG8_LDB(B1, 1, 1); PG8_SCHED; PG8_LDA(At, 1, 0); PG8_STAGE(PG8_SA(0, 1), a2 + hstep, voffA);
;             PG8_WAIT_V(8); PG8_WAIT_L(0); PG8_BAR; PG8_MMA(0, 0, At, B0); PG8_MMA(0, 1, At, B1); PG8_BAR; PG8_SCHED;
;             PG8_LDA(At, 1, 1); PG8_STAGE(PG8_SB(1, 0), b3, voffB); PG8_STAGE(PG8_SB(1, 1), b3 + hstep, voffB); PG8_STAGE(PG8_SA(1, 0), a3, voffA);
	s_setprio 1
	s_waitcnt lgkmcnt(0)
	v_mfma_f32_16x16x32_bf16 v[60:63], v[148:151], v[180:183], v[60:63]
	v_mfma_f32_16x16x32_bf16 v[56:59], v[156:159], v[180:183], v[56:59]
	v_mfma_f32_16x16x32_bf16 v[44:47], v[148:151], v[188:191], v[44:47]
	v_mfma_f32_16x16x32_bf16 v[40:43], v[156:159], v[188:191], v[40:43]
	v_mfma_f32_16x16x32_bf16 v[28:31], v[148:151], v[210:213], v[28:31]
	v_mfma_f32_16x16x32_bf16 v[24:27], v[156:159], v[210:213], v[24:27]
	v_mfma_f32_16x16x32_bf16 v[12:15], v[148:151], v[218:221], v[12:15]
	v_mfma_f32_16x16x32_bf16 v[8:11], v[156:159], v[218:221], v[8:11]
	v_mfma_f32_16x16x32_bf16 v[60:63], v[152:155], v[184:187], v[60:63]
	v_mfma_f32_16x16x32_bf16 v[56:59], v[160:163], v[184:187], v[56:59]
	v_mfma_f32_16x16x32_bf16 v[44:47], v[152:155], v[206:209], v[44:47]
	v_mfma_f32_16x16x32_bf16 v[40:43], v[160:163], v[206:209], v[40:43]
	v_mfma_f32_16x16x32_bf16 v[28:31], v[152:155], v[214:217], v[28:31]
	v_mfma_f32_16x16x32_bf16 v[24:27], v[160:163], v[214:217], v[24:27]
	v_mfma_f32_16x16x32_bf16 v[12:15], v[152:155], v[222:225], v[12:15]
	v_mfma_f32_16x16x32_bf16 v[8:11], v[160:163], v[222:225], v[8:11]
	s_setprio 0
	s_setprio 1
	v_mfma_f32_16x16x32_bf16 v[52:55], v[164:167], v[180:183], v[52:55]
	v_mfma_f32_16x16x32_bf16 v[48:51], v[172:175], v[180:183], v[48:51]
	v_mfma_f32_16x16x32_bf16 v[36:39], v[164:167], v[188:191], v[36:39]
	v_mfma_f32_16x16x32_bf16 v[32:35], v[172:175], v[188:191], v[32:35]
	v_mfma_f32_16x16x32_bf16 v[20:23], v[164:167], v[210:213], v[20:23]
	v_mfma_f32_16x16x32_bf16 v[16:19], v[172:175], v[210:213], v[16:19]
	v_mfma_f32_16x16x32_bf16 v[4:7], v[164:167], v[218:221], v[4:7]
	v_mfma_f32_16x16x32_bf16 v[0:3], v[172:175], v[218:221], v[0:3]
	v_mfma_f32_16x16x32_bf16 v[52:55], v[168:171], v[184:187], v[52:55]
	v_mfma_f32_16x16x32_bf16 v[48:51], v[176:179], v[184:187], v[48:51]
	v_mfma_f32_16x16x32_bf16 v[36:39], v[168:171], v[206:209], v[36:39]
	v_mfma_f32_16x16x32_bf16 v[32:35], v[176:179], v[206:209], v[32:35]
	v_mfma_f32_16x16x32_bf16 v[20:23], v[168:171], v[214:217], v[20:23]
	v_mfma_f32_16x16x32_bf16 v[16:19], v[176:179], v[214:217], v[16:19]
	v_mfma_f32_16x16x32_bf16 v[4:7], v[168:171], v[222:225], v[4:7]
	v_mfma_f32_16x16x32_bf16 v[0:3], v[176:179], v[222:225], v[0:3]
	s_setprio 0
	s_barrier
	s_add_i32 s4, 0, 0x18000
	s_add_i32 s5, 0, 0x1c000
	v_add_u32_e32 v160, s4, v193
	v_add_u32_e32 v176, s5, v193
	ds_read_b128 v[148:151], v160
	ds_read_b128 v[152:155], v160 offset:1024
	ds_read_b128 v[156:159], v160 offset:2048
	ds_read_b128 v[160:163], v160 offset:3072
	ds_read_b128 v[164:167], v176
	ds_read_b128 v[168:171], v176 offset:1024
	ds_read_b128 v[172:175], v176 offset:2048
	ds_read_b128 v[176:179], v176 offset:3072
	s_add_u32 s54, s54, 0x40000
	s_addc_u32 s55, s55, 0
	s_mov_b32 m0, s64
	v_lshl_add_u64 v[234:235], s[54:55], 0, v[128:129]
	ds_read_b128 v[180:183], v200 offset:32768
	ds_read_b128 v[184:187], v200 offset:33792
	ds_read_b128 v[188:191], v200 offset:34816
	ds_read_b128 v[206:209], v200 offset:35840
	ds_read_b128 v[210:213], v200 offset:36864
	ds_read_b128 v[214:217], v200 offset:37888
	ds_read_b128 v[218:221], v200 offset:38912
	ds_read_b128 v[222:225], v200 offset:39936
	global_load_lds_dwordx4 v[234:235], off
	v_lshl_add_u64 v[234:235], s[54:55], 0, v[132:133]
	s_mov_b32 m0, s65
	s_nop 0
	global_load_lds_dwordx4 v[234:235], off
	s_waitcnt vmcnt(8)
	s_waitcnt lgkmcnt(0)
	s_barrier
	s_setprio 1
	s_waitcnt lgkmcnt(0)
	v_mfma_f32_16x16x32_bf16 v[124:127], v[148:151], v[180:183], v[124:127]
	v_mfma_f32_16x16x32_bf16 v[120:123], v[156:159], v[180:183], v[120:123]
	v_mfma_f32_16x16x32_bf16 v[108:111], v[148:151], v[188:191], v[108:111]
	v_mfma_f32_16x16x32_bf16 v[104:107], v[156:159], v[188:191], v[104:107]
	v_mfma_f32_16x16x32_bf16 v[92:95], v[148:151], v[210:213], v[92:95]
	v_mfma_f32_16x16x32_bf16 v[88:91], v[156:159], v[210:213], v[88:91]
	v_mfma_f32_16x16x32_bf16 v[76:79], v[148:151], v[218:221], v[76:79]
	v_mfma_f32_16x16x32_bf16 v[72:75], v[156:159], v[218:221], v[72:75]
	v_mfma_f32_16x16x32_bf16 v[124:127], v[152:155], v[184:187], v[124:127]
	v_mfma_f32_16x16x32_bf16 v[120:123], v[160:163], v[184:187], v[120:123]
	v_mfma_f32_16x16x32_bf16 v[108:111], v[152:155], v[206:209], v[108:111]
	v_mfma_f32_16x16x32_bf16 v[104:107], v[160:163], v[206:209], v[104:107]
	v_mfma_f32_16x16x32_bf16 v[92:95], v[152:155], v[214:217], v[92:95]
	v_mfma_f32_16x16x32_bf16 v[88:91], v[160:163], v[214:217], v[88:91]
	v_mfma_f32_16x16x32_bf16 v[76:79], v[152:155], v[222:225], v[76:79]
	v_mfma_f32_16x16x32_bf16 v[72:75], v[160:163], v[222:225], v[72:75]
	s_setprio 0
	s_setprio 1
	v_mfma_f32_16x16x32_bf16 v[116:119], v[164:167], v[180:183], v[116:119]
	v_mfma_f32_16x16x32_bf16 v[112:115], v[172:175], v[180:183], v[112:115]
	v_mfma_f32_16x16x32_bf16 v[100:103], v[164:167], v[188:191], v[100:103]
	v_mfma_f32_16x16x32_bf16 v[96:99], v[172:175], v[188:191], v[96:99]
	v_mfma_f32_16x16x32_bf16 v[84:87], v[164:167], v[210:213], v[84:87]
	v_mfma_f32_16x16x32_bf16 v[80:83], v[172:175], v[210:213], v[80:83]
	v_mfma_f32_16x16x32_bf16 v[68:71], v[164:167], v[218:221], v[68:71]
	v_mfma_f32_16x16x32_bf16 v[64:67], v[172:175], v[218:221], v[64:67]
	v_mfma_f32_16x16x32_bf16 v[116:119], v[168:171], v[184:187], v[116:119]
	v_mfma_f32_16x16x32_bf16 v[112:115], v[176:179], v[184:187], v[112:115]
	v_mfma_f32_16x16x32_bf16 v[100:103], v[168:171], v[206:209], v[100:103]
	v_mfma_f32_16x16x32_bf16 v[96:99], v[176:179], v[206:209], v[96:99]
	v_mfma_f32_16x16x32_bf16 v[84:87], v[168:171], v[214:217], v[84:87]
	v_mfma_f32_16x16x32_bf16 v[80:83], v[176:179], v[214:217], v[80:83]
	v_mfma_f32_16x16x32_bf16 v[68:71], v[168:171], v[222:225], v[68:71]
	v_mfma_f32_16x16x32_bf16 v[64:67], v[176:179], v[222:225], v[64:67]
	s_setprio 0
	s_barrier
; #define PG8_STAGE(bufoff, gbase, voff) do { _Pragma("unroll") for (int _i = 0; _i < 2; ++_i) \
;         __builtin_amdgcn_global_load_lds((const unsigned*)((const char*)(gbase) + (voff)[_i]), (PG8_LAS unsigned*)(lds + (bufoff) + ldsw + _i * 8192), 16, 0, 0); } while (0)
; #define PG8_LDA(dst, b, h) do { _Pragma("unroll") for (int m = 0; m < 4; ++m) _Pragma("unroll") for (int k = 0; k < 2; ++k) dst[m][k] = *(const PG8_LAS bf16x8*)(lds + PG8_SA(b, h) + aoff + m * 2048 + k * 1024); } while (0)
; #define PG8_MMA(ai, bj, At, Bt) do { __builtin_amdgcn_s_setprio(1); _Pragma("unroll") for (int m = 0; m < 4; ++m) _Pragma("unroll") for (int n = 0; n < 2; ++n) _Pragma("unroll") for (int k = 0; k < 2; ++k) \
;         acc[ai][bj][m][n] = __builtin_amdgcn_mfma_f32_16x16x32_bf16(Bt[n][k], At[m][k], acc[ai][bj][m][n], 0, 0, 0); __builtin_amdgcn_s_setprio(0); } while (0)
; #define PG8_WAIT_V(n) asm volatile("s_waitcnt vmcnt(" #n ")" ::: "memory")
; #define PG8_WAIT_L(n) asm volatile("s_waitcnt lgkmcnt(" #n ")" ::: "memory")
; #define PG8_BAR __builtin_amdgcn_s_barrier()
; #define PG8_SCHED __builtin_amdgcn_sched_barrier(0)
; template <class Epi, class Sched, bool ALIGN_EPI = false, bool SP2 = false>
; __device__ __forceinline__ void gemm_phase(PG8_LAS unsigned char* lds, const Gemm g, const Sched& S, const Epi& E, int tid_in) {
;     ...
;             PG8_LDA(At, 1, 1); PG8_STAGE(PG8_SB(1, 0), b3, voffB); PG8_STAGE(PG8_SB(1, 1), b3 + hstep, voffB); PG8_STAGE(PG8_SA(1, 0), a3, voffA);
;             PG8_WAIT_V(8); PG8_WAIT_L(0); PG8_BAR; PG8_MMA(1, 0, At, B0); PG8_MMA(1, 1, At, B1); PG8_BAR; PG8_SCHED;
;     ...
;         if constexpr (ALIGN_EPI) { if (wr == 0) PG8_BAR; }
	s_add_i32 s4, s4, s61
	v_lshl_add_u64 v[226:227], v[226:227], 0, s[20:21]
	s_mov_b32 m0, s4
	ds_read_b128 v[180:183], v200 offset:49152
	ds_read_b128 v[184:187], v200 offset:50176
	ds_read_b128 v[188:191], v200 offset:51200
	ds_read_b128 v[206:209], v200 offset:52224
	ds_read_b128 v[210:213], v200 offset:53248
	ds_read_b128 v[214:217], v200 offset:54272
	ds_read_b128 v[218:221], v200 offset:55296
	ds_read_b128 v[222:225], v200 offset:56320
	global_load_lds_dwordx4 v[226:227], off
	s_add_i32 m0, s4, 0x2000
	s_add_u32 s48, s48, 0x40080
	v_lshl_add_u64 v[226:227], v[228:229], 0, s[20:21]
	s_addc_u32 s49, s49, 0
	s_add_i32 s4, s5, s61
	global_load_lds_dwordx4 v[226:227], off
	v_lshl_add_u64 v[226:227], s[48:49], 0, v[130:131]
	s_mov_b32 m0, s4
	s_nop 0
	global_load_lds_dwordx4 v[226:227], off
	v_lshl_add_u64 v[226:227], s[48:49], 0, v[134:135]
	s_add_i32 m0, s4, 0x2000
	s_nop 0
	global_load_lds_dwordx4 v[226:227], off
	v_lshl_add_u64 v[226:227], v[230:231], 0, s[20:21]
	s_mov_b32 m0, s68
	s_nop 0
	global_load_lds_dwordx4 v[226:227], off
	v_lshl_add_u64 v[226:227], v[232:233], 0, s[20:21]
	s_mov_b32 m0, s69
	s_nop 0
	global_load_lds_dwordx4 v[226:227], off
	s_waitcnt vmcnt(8)
	s_waitcnt lgkmcnt(0)
	s_barrier
	s_setprio 1
	s_waitcnt lgkmcnt(0)
	v_mfma_f32_16x16x32_bf16 v[60:63], v[148:151], v[180:183], v[60:63]
	v_mfma_f32_16x16x32_bf16 v[56:59], v[156:159], v[180:183], v[56:59]
	v_mfma_f32_16x16x32_bf16 v[44:47], v[148:151], v[188:191], v[44:47]
	v_mfma_f32_16x16x32_bf16 v[40:43], v[156:159], v[188:191], v[40:43]
	v_mfma_f32_16x16x32_bf16 v[28:31], v[148:151], v[210:213], v[28:31]
	v_mfma_f32_16x16x32_bf16 v[24:27], v[156:159], v[210:213], v[24:27]
	v_mfma_f32_16x16x32_bf16 v[12:15], v[148:151], v[218:221], v[12:15]
	v_mfma_f32_16x16x32_bf16 v[8:11], v[156:159], v[218:221], v[8:11]
	v_mfma_f32_16x16x32_bf16 v[60:63], v[152:155], v[184:187], v[60:63]
	v_mfma_f32_16x16x32_bf16 v[56:59], v[160:163], v[184:187], v[56:59]
	v_mfma_f32_16x16x32_bf16 v[44:47], v[152:155], v[206:209], v[44:47]
	v_mfma_f32_16x16x32_bf16 v[40:43], v[160:163], v[206:209], v[40:43]
	v_mfma_f32_16x16x32_bf16 v[28:31], v[152:155], v[214:217], v[28:31]
	v_mfma_f32_16x16x32_bf16 v[24:27], v[160:163], v[214:217], v[24:27]
	v_mfma_f32_16x16x32_bf16 v[12:15], v[152:155], v[222:225], v[12:15]
	v_mfma_f32_16x16x32_bf16 v[8:11], v[160:163], v[222:225], v[8:11]
	s_setprio 0
	s_setprio 1
	v_mfma_f32_16x16x32_bf16 v[52:55], v[164:167], v[180:183], v[52:55]
	v_mfma_f32_16x16x32_bf16 v[48:51], v[172:175], v[180:183], v[48:51]
	v_mfma_f32_16x16x32_bf16 v[36:39], v[164:167], v[188:191], v[36:39]
	v_mfma_f32_16x16x32_bf16 v[32:35], v[172:175], v[188:191], v[32:35]
	v_mfma_f32_16x16x32_bf16 v[20:23], v[164:167], v[210:213], v[20:23]
	v_mfma_f32_16x16x32_bf16 v[16:19], v[172:175], v[210:213], v[16:19]
	v_mfma_f32_16x16x32_bf16 v[4:7], v[164:167], v[218:221], v[4:7]
	v_mfma_f32_16x16x32_bf16 v[0:3], v[172:175], v[218:221], v[0:3]
	v_mfma_f32_16x16x32_bf16 v[52:55], v[168:171], v[184:187], v[52:55]
	v_mfma_f32_16x16x32_bf16 v[48:51], v[176:179], v[184:187], v[48:51]
	v_mfma_f32_16x16x32_bf16 v[36:39], v[168:171], v[206:209], v[36:39]
	v_mfma_f32_16x16x32_bf16 v[32:35], v[176:179], v[206:209], v[32:35]
	v_mfma_f32_16x16x32_bf16 v[20:23], v[168:171], v[214:217], v[20:23]
	v_mfma_f32_16x16x32_bf16 v[16:19], v[176:179], v[214:217], v[16:19]
	v_mfma_f32_16x16x32_bf16 v[4:7], v[168:171], v[222:225], v[4:7]
	v_mfma_f32_16x16x32_bf16 v[0:3], v[176:179], v[222:225], v[0:3]
	s_setprio 0
	s_barrier
	s_add_i32 s53, s53, 2
	s_add_u32 s33, s33, 0x100
	s_addc_u32 s51, s51, 0
	s_add_u32 s46, s46, 0x100
	s_addc_u32 s47, s47, 0
	s_cmp_gt_u32 s53, 13
	s_cbranch_scc0 .LBB0_1188
.Lpost9:
	s_and_b64 vcc, exec, s[22:23]
	s_cbranch_vccz .LBB0_1191
	s_barrier

; #define PG8_STAGE(bufoff, gbase, voff) do { _Pragma("unroll") for (int _i = 0; _i < 2; ++_i) \
;         __builtin_amdgcn_global_load_lds((const unsigned*)((const char*)(gbase) + (voff)[_i]), (PG8_LAS unsigned*)(lds + (bufoff) + ldsw + _i * 8192), 16, 0, 0); } while (0)
; #define PG8_LDA(dst, b, h) do { _Pragma("unroll") for (int m = 0; m < 4; ++m) _Pragma("unroll") for (int k = 0; k < 2; ++k) dst[m][k] = *(const PG8_LAS bf16x8*)(lds + PG8_SA(b, h) + aoff + m * 2048 + k * 1024); } while (0)
; #define PG8_LDB(dst, b, h) do { _Pragma("unroll") for (int n = 0; n < 2; ++n) _Pragma("unroll") for (int k = 0; k < 2; ++k) dst[n][k] = *(const PG8_LAS bf16x8*)(lds + PG8_SB(b, h) + boff + n * 2048 + k * 1024); } while (0)
; #define PG8_MMA(ai, bj, At, Bt) do { __builtin_amdgcn_s_setprio(1); _Pragma("unroll") for (int m = 0; m < 4; ++m) _Pragma("unroll") for (int n = 0; n < 2; ++n) _Pragma("unroll") for (int k = 0; k < 2; ++k) \
;         acc[ai][bj][m][n] = __builtin_amdgcn_mfma_f32_16x16x32_bf16(Bt[n][k], At[m][k], acc[ai][bj][m][n], 0, 0, 0); __builtin_amdgcn_s_setprio(0); } while (0)
; #define PG8_WAIT_V(n) asm volatile("s_waitcnt vmcnt(" #n ")" ::: "memory")
; #define PG8_WAIT_L(n) asm volatile("s_waitcnt lgkmcnt(" #n ")" ::: "memory")
; #define PG8_BAR __builtin_amdgcn_s_barrier()
; #define PG8_SCHED __builtin_amdgcn_sched_barrier(0)
; template <class Epi, class Sched, bool ALIGN_EPI = false, bool SP2 = false>
; __device__ __forceinline__ void gemm_phase(PG8_LAS unsigned char* lds, const Gemm g, const Sched& S, const Epi& E, int tid_in) {
;     ...
;             PG8_LDB(B0, 0, 0); PG8_LDB(B1, 0, 1); PG8_SCHED; PG8_LDA(At, 0, 0); PG8_STAGE(PG8_SA(1, 1), a1 + hstep, voffA);
;             PG8_WAIT_V(8); PG8_WAIT_L(0); PG8_BAR; PG8_MMA(0, 0, At, B0); PG8_MMA(0, 1, At, B1); PG8_BAR; PG8_SCHED;
;             PG8_LDA(At, 0, 1); PG8_STAGE(PG8_SB(0, 0), b2, voffB); PG8_STAGE(PG8_SB(0, 1), b2 + hstep, voffB); PG8_STAGE(PG8_SA(0, 0), a2, voffA);
;             PG8_WAIT_V(8); PG8_WAIT_L(0); PG8_BAR; PG8_MMA(1, 0, At, B0); PG8_MMA(1, 1, At, B1); PG8_BAR; PG8_SCHED;
.Lpk9:
	s_or_b64 s[98:99], s[14:15], 1
	v_lshl_add_u64 v[226:227], s[46:47], 0, v[142:143]
	s_add_i32 m0, s62, 0xc000
	ds_read_b128 v[180:183], v200
	ds_read_b128 v[184:187], v200 offset:1024
	ds_read_b128 v[188:191], v200 offset:2048
	ds_read_b128 v[206:209], v200 offset:3072
	ds_read_b128 v[210:213], v200 offset:4096
	ds_read_b128 v[214:217], v200 offset:5120
	ds_read_b128 v[218:221], v200 offset:6144
	ds_read_b128 v[222:225], v200 offset:7168
	global_load_lds_dwordx4 v[226:227], off
	v_lshl_add_u64 v[226:227], s[46:47], 0, v[140:141]
	s_add_i32 m0, s62, 0xe000
	s_nop 0
	global_load_lds_dwordx4 v[226:227], off
	s_waitcnt vmcnt(8)
	s_waitcnt lgkmcnt(0)
	s_barrier
	s_setprio 1
	s_waitcnt lgkmcnt(0)
	v_mfma_f32_16x16x32_bf16 v[124:127], v[148:151], v[180:183], v[124:127]
	v_mfma_f32_16x16x32_bf16 v[120:123], v[156:159], v[180:183], v[120:123]
	v_mfma_f32_16x16x32_bf16 v[108:111], v[148:151], v[188:191], v[108:111]
	v_mfma_f32_16x16x32_bf16 v[104:107], v[156:159], v[188:191], v[104:107]
	v_mfma_f32_16x16x32_bf16 v[92:95], v[148:151], v[210:213], v[92:95]
	v_mfma_f32_16x16x32_bf16 v[88:91], v[156:159], v[210:213], v[88:91]
	v_mfma_f32_16x16x32_bf16 v[76:79], v[148:151], v[218:221], v[76:79]
	v_mfma_f32_16x16x32_bf16 v[72:75], v[156:159], v[218:221], v[72:75]
	v_mfma_f32_16x16x32_bf16 v[124:127], v[152:155], v[184:187], v[124:127]
	v_mfma_f32_16x16x32_bf16 v[120:123], v[160:163], v[184:187], v[120:123]
	v_mfma_f32_16x16x32_bf16 v[108:111], v[152:155], v[206:209], v[108:111]
	v_mfma_f32_16x16x32_bf16 v[104:107], v[160:163], v[206:209], v[104:107]
	v_mfma_f32_16x16x32_bf16 v[92:95], v[152:155], v[214:217], v[92:95]
	v_mfma_f32_16x16x32_bf16 v[88:91], v[160:163], v[214:217], v[88:91]
	v_mfma_f32_16x16x32_bf16 v[76:79], v[152:155], v[222:225], v[76:79]
	v_mfma_f32_16x16x32_bf16 v[72:75], v[160:163], v[222:225], v[72:75]
	s_setprio 0
	s_setprio 1
	v_mfma_f32_16x16x32_bf16 v[116:119], v[164:167], v[180:183], v[116:119]
	v_mfma_f32_16x16x32_bf16 v[112:115], v[172:175], v[180:183], v[112:115]
	v_mfma_f32_16x16x32_bf16 v[100:103], v[164:167], v[188:191], v[100:103]
	v_mfma_f32_16x16x32_bf16 v[96:99], v[172:175], v[188:191], v[96:99]
	v_mfma_f32_16x16x32_bf16 v[84:87], v[164:167], v[210:213], v[84:87]
	v_mfma_f32_16x16x32_bf16 v[80:83], v[172:175], v[210:213], v[80:83]
	v_mfma_f32_16x16x32_bf16 v[68:71], v[164:167], v[218:221], v[68:71]
	v_mfma_f32_16x16x32_bf16 v[64:67], v[172:175], v[218:221], v[64:67]
	v_mfma_f32_16x16x32_bf16 v[116:119], v[168:171], v[184:187], v[116:119]
	v_mfma_f32_16x16x32_bf16 v[112:115], v[176:179], v[184:187], v[112:115]
	v_mfma_f32_16x16x32_bf16 v[100:103], v[168:171], v[206:209], v[100:103]
	v_mfma_f32_16x16x32_bf16 v[96:99], v[176:179], v[206:209], v[96:99]
	v_mfma_f32_16x16x32_bf16 v[84:87], v[168:171], v[214:217], v[84:87]
	v_mfma_f32_16x16x32_bf16 v[80:83], v[176:179], v[214:217], v[80:83]
	v_mfma_f32_16x16x32_bf16 v[68:71], v[168:171], v[222:225], v[68:71]
	v_mfma_f32_16x16x32_bf16 v[64:67], v[176:179], v[222:225], v[64:67]
	s_setprio 0
	s_barrier
	s_add_i32 s4, s73, s61
	v_lshl_add_u64 v[226:227], s[48:49], 0, v[130:131]
	s_mov_b32 m0, s4
	ds_read_b128 v[180:183], v200 offset:16384
	ds_read_b128 v[184:187], v200 offset:17408
	ds_read_b128 v[188:191], v200 offset:18432
	ds_read_b128 v[206:209], v200 offset:19456
	ds_read_b128 v[210:213], v200 offset:20480
	ds_read_b128 v[214:217], v200 offset:21504
	ds_read_b128 v[218:221], v200 offset:22528
	ds_read_b128 v[222:225], v200 offset:23552
	s_mov_b64 exec, s[98:99]
	global_load_lds_dwordx4 v[226:227], off
	s_mov_b64 exec, -1
	s_add_i32 m0, s4, 0x2000
	s_add_u32 s56, s48, 0x40000
	v_lshl_add_u64 v[228:229], s[48:49], 0, v[134:135]
	s_addc_u32 s57, s49, 0
	s_add_i32 s4, s40, s61
	s_mov_b64 exec, s[98:99]
	global_load_lds_dwordx4 v[228:229], off
	s_mov_b64 exec, -1
	v_lshl_add_u64 v[230:231], s[56:57], 0, v[130:131]
	s_mov_b32 m0, s4
	v_lshl_add_u64 v[232:233], s[54:55], 0, v[132:133]
	s_mov_b64 exec, s[98:99]
	global_load_lds_dwordx4 v[230:231], off
	s_mov_b64 exec, -1
	v_lshl_add_u64 v[230:231], s[56:57], 0, v[134:135]
	s_add_i32 m0, s4, 0x2000
	s_nop 0
	s_mov_b64 exec, s[98:99]
	global_load_lds_dwordx4 v[230:231], off
	s_mov_b64 exec, -1
	v_lshl_add_u64 v[230:231], s[54:55], 0, v[128:129]
	s_mov_b32 m0, s62
	s_nop 0
	s_mov_b64 exec, s[98:99]
	global_load_lds_dwordx4 v[230:231], off
	s_mov_b64 exec, -1
	s_mov_b32 m0, s63
	s_nop 0
	s_mov_b64 exec, s[98:99]
	global_load_lds_dwordx4 v[232:233], off
	s_mov_b64 exec, -1
	s_waitcnt vmcnt(8)
	s_waitcnt lgkmcnt(0)
	s_barrier
; #define PG8_STAGE(bufoff, gbase, voff) do { _Pragma("unroll") for (int _i = 0; _i < 2; ++_i) \
;         __builtin_amdgcn_global_load_lds((const unsigned*)((const char*)(gbase) + (voff)[_i]), (PG8_LAS unsigned*)(lds + (bufoff) + ldsw + _i * 8192), 16, 0, 0); } while (0)
; #define PG8_LDA(dst, b, h) do { _Pragma("unroll") for (int m = 0; m < 4; ++m) _Pragma("unroll") for (int k = 0; k < 2; ++k) dst[m][k] = *(const PG8_LAS bf16x8*)(lds + PG8_SA(b, h) + aoff + m * 2048 + k * 1024); } while (0)
; #define PG8_LDB(dst, b, h) do { _Pragma("unroll") for (int n = 0; n < 2; ++n) _Pragma("unroll") for (int k = 0; k < 2; ++k) dst[n][k] = *(const PG8_LAS bf16x8*)(lds + PG8_SB(b, h) + boff + n * 2048 + k * 1024); } while (0)
; #define PG8_MMA(ai, bj, At, Bt) do { __builtin_amdgcn_s_setprio(1); _Pragma("unroll") for (int m = 0; m < 4; ++m) _Pragma("unroll") for (int n = 0; n < 2; ++n) _Pragma("unroll") for (int k = 0; k < 2; ++k) \
;         acc[ai][bj][m][n] = __builtin_amdgcn_mfma_f32_16x16x32_bf16(Bt[n][k], At[m][k], acc[ai][bj][m][n], 0, 0, 0); __builtin_amdgcn_s_setprio(0); } while (0)
; #define PG8_WAIT_V(n) asm volatile("s_waitcnt vmcnt(" #n ")" ::: "memory")
; #define PG8_WAIT_L(n) asm volatile("s_waitcnt lgkmcnt(" #n ")" ::: "memory")
; #define PG8_BAR __builtin_amdgcn_s_barrier()
; #define PG8_SCHED __builtin_amdgcn_sched_barrier(0)
; template <class Epi, class Sched, bool ALIGN_EPI = false, bool SP2 = false>
; __device__ __forceinline__ void gemm_phase(PG8_LAS unsigned char* lds, const Gemm g, const Sched& S, const Epi& E, int tid_in) {
;     ...
;             PG8_WAIT_V(8); PG8_WAIT_L(0); PG8_BAR; PG8_MMA(1, 0, At, B0); PG8_MMA(1, 1, At, B1); PG8_BAR; PG8_SCHED;
;             PG8_LDB(B0, 1, 0); PG8_LDB(B1, 1, 1); PG8_SCHED; PG8_LDA(At, 1, 0); PG8_STAGE(PG8_SA(0, 1), a2 + hstep, voffA);
;             PG8_WAIT_V(8); PG8_WAIT_L(0); PG8_BAR; PG8_MMA(0, 0, At, B0); PG8_MMA(0, 1, At, B1); PG8_BAR; PG8_SCHED;
	s_setprio 1
	s_waitcnt lgkmcnt(0)
	v_mfma_f32_16x16x32_bf16 v[60:63], v[148:151], v[180:183], v[60:63]
	v_mfma_f32_16x16x32_bf16 v[56:59], v[156:159], v[180:183], v[56:59]
	v_mfma_f32_16x16x32_bf16 v[44:47], v[148:151], v[188:191], v[44:47]
	v_mfma_f32_16x16x32_bf16 v[40:43], v[156:159], v[188:191], v[40:43]
	v_mfma_f32_16x16x32_bf16 v[28:31], v[148:151], v[210:213], v[28:31]
	v_mfma_f32_16x16x32_bf16 v[24:27], v[156:159], v[210:213], v[24:27]
	v_mfma_f32_16x16x32_bf16 v[12:15], v[148:151], v[218:221], v[12:15]
	v_mfma_f32_16x16x32_bf16 v[8:11], v[156:159], v[218:221], v[8:11]
	v_mfma_f32_16x16x32_bf16 v[60:63], v[152:155], v[184:187], v[60:63]
	v_mfma_f32_16x16x32_bf16 v[56:59], v[160:163], v[184:187], v[56:59]
	v_mfma_f32_16x16x32_bf16 v[44:47], v[152:155], v[206:209], v[44:47]
	v_mfma_f32_16x16x32_bf16 v[40:43], v[160:163], v[206:209], v[40:43]
	v_mfma_f32_16x16x32_bf16 v[28:31], v[152:155], v[214:217], v[28:31]
	v_mfma_f32_16x16x32_bf16 v[24:27], v[160:163], v[214:217], v[24:27]
	v_mfma_f32_16x16x32_bf16 v[12:15], v[152:155], v[222:225], v[12:15]
	v_mfma_f32_16x16x32_bf16 v[8:11], v[160:163], v[222:225], v[8:11]
	s_setprio 0
	s_setprio 1
	v_mfma_f32_16x16x32_bf16 v[52:55], v[164:167], v[180:183], v[52:55]
	v_mfma_f32_16x16x32_bf16 v[48:51], v[172:175], v[180:183], v[48:51]
	v_mfma_f32_16x16x32_bf16 v[36:39], v[164:167], v[188:191], v[36:39]
	v_mfma_f32_16x16x32_bf16 v[32:35], v[172:175], v[188:191], v[32:35]
	v_mfma_f32_16x16x32_bf16 v[20:23], v[164:167], v[210:213], v[20:23]
	v_mfma_f32_16x16x32_bf16 v[16:19], v[172:175], v[210:213], v[16:19]
	v_mfma_f32_16x16x32_bf16 v[4:7], v[164:167], v[218:221], v[4:7]
	v_mfma_f32_16x16x32_bf16 v[0:3], v[172:175], v[218:221], v[0:3]
	v_mfma_f32_16x16x32_bf16 v[52:55], v[168:171], v[184:187], v[52:55]
	v_mfma_f32_16x16x32_bf16 v[48:51], v[176:179], v[184:187], v[48:51]
	v_mfma_f32_16x16x32_bf16 v[36:39], v[168:171], v[206:209], v[36:39]
	v_mfma_f32_16x16x32_bf16 v[32:35], v[176:179], v[206:209], v[32:35]
	v_mfma_f32_16x16x32_bf16 v[20:23], v[168:171], v[214:217], v[20:23]
	v_mfma_f32_16x16x32_bf16 v[16:19], v[176:179], v[214:217], v[16:19]
	v_mfma_f32_16x16x32_bf16 v[4:7], v[168:171], v[222:225], v[4:7]
	v_mfma_f32_16x16x32_bf16 v[0:3], v[176:179], v[222:225], v[0:3]
	s_setprio 0
	s_barrier
	s_add_i32 s4, 0, 0x18000
	s_add_i32 s5, 0, 0x1c000
	v_add_u32_e32 v160, s4, v193
	v_add_u32_e32 v176, s5, v193
	ds_read_b128 v[148:151], v160
	ds_read_b128 v[152:155], v160 offset:1024
	ds_read_b128 v[156:159], v160 offset:2048
	ds_read_b128 v[160:163], v160 offset:3072
	ds_read_b128 v[164:167], v176
	ds_read_b128 v[168:171], v176 offset:1024
	ds_read_b128 v[172:175], v176 offset:2048
	ds_read_b128 v[176:179], v176 offset:3072
	s_add_u32 s54, s54, 0x40000
	s_addc_u32 s55, s55, 0
	s_mov_b32 m0, s64
	v_lshl_add_u64 v[234:235], s[54:55], 0, v[128:129]
	ds_read_b128 v[180:183], v200 offset:32768
	ds_read_b128 v[184:187], v200 offset:33792
	ds_read_b128 v[188:191], v200 offset:34816
	ds_read_b128 v[206:209], v200 offset:35840
	ds_read_b128 v[210:213], v200 offset:36864
	ds_read_b128 v[214:217], v200 offset:37888
	ds_read_b128 v[218:221], v200 offset:38912
	ds_read_b128 v[222:225], v200 offset:39936
	s_mov_b64 exec, s[98:99]
	global_load_lds_dwordx4 v[234:235], off
	s_mov_b64 exec, -1
	v_lshl_add_u64 v[234:235], s[54:55], 0, v[132:133]
	s_mov_b32 m0, s65
	s_nop 0
	s_mov_b64 exec, s[98:99]
	global_load_lds_dwordx4 v[234:235], off
	s_mov_b64 exec, -1
	s_waitcnt vmcnt(8)
	s_waitcnt lgkmcnt(0)
	s_barrier
	s_setprio 1
	s_waitcnt lgkmcnt(0)
	v_mfma_f32_16x16x32_bf16 v[124:127], v[148:151], v[180:183], v[124:127]
	v_mfma_f32_16x16x32_bf16 v[120:123], v[156:159], v[180:183], v[120:123]
	v_mfma_f32_16x16x32_bf16 v[108:111], v[148:151], v[188:191], v[108:111]
	v_mfma_f32_16x16x32_bf16 v[104:107], v[156:159], v[188:191], v[104:107]
	v_mfma_f32_16x16x32_bf16 v[92:95], v[148:151], v[210:213], v[92:95]
	v_mfma_f32_16x16x32_bf16 v[88:91], v[156:159], v[210:213], v[88:91]
	v_mfma_f32_16x16x32_bf16 v[76:79], v[148:151], v[218:221], v[76:79]
	v_mfma_f32_16x16x32_bf16 v[72:75], v[156:159], v[218:221], v[72:75]
	v_mfma_f32_16x16x32_bf16 v[124:127], v[152:155], v[184:187], v[124:127]
	v_mfma_f32_16x16x32_bf16 v[120:123], v[160:163], v[184:187], v[120:123]
	v_mfma_f32_16x16x32_bf16 v[108:111], v[152:155], v[206:209], v[108:111]
	v_mfma_f32_16x16x32_bf16 v[104:107], v[160:163], v[206:209], v[104:107]
	v_mfma_f32_16x16x32_bf16 v[92:95], v[152:155], v[214:217], v[92:95]
	v_mfma_f32_16x16x32_bf16 v[88:91], v[160:163], v[214:217], v[88:91]
	v_mfma_f32_16x16x32_bf16 v[76:79], v[152:155], v[222:225], v[76:79]
	v_mfma_f32_16x16x32_bf16 v[72:75], v[160:163], v[222:225], v[72:75]
	s_setprio 0
	s_setprio 1
	v_mfma_f32_16x16x32_bf16 v[116:119], v[164:167], v[180:183], v[116:119]
	v_mfma_f32_16x16x32_bf16 v[112:115], v[172:175], v[180:183], v[112:115]
	v_mfma_f32_16x16x32_bf16 v[100:103], v[164:167], v[188:191], v[100:103]
	v_mfma_f32_16x16x32_bf16 v[96:99], v[172:175], v[188:191], v[96:99]
	v_mfma_f32_16x16x32_bf16 v[84:87], v[164:167], v[210:213], v[84:87]
	v_mfma_f32_16x16x32_bf16 v[80:83], v[172:175], v[210:213], v[80:83]
	v_mfma_f32_16x16x32_bf16 v[68:71], v[164:167], v[218:221], v[68:71]
	v_mfma_f32_16x16x32_bf16 v[64:67], v[172:175], v[218:221], v[64:67]
	v_mfma_f32_16x16x32_bf16 v[116:119], v[168:171], v[184:187], v[116:119]
	v_mfma_f32_16x16x32_bf16 v[112:115], v[176:179], v[184:187], v[112:115]
	v_mfma_f32_16x16x32_bf16 v[100:103], v[168:171], v[206:209], v[100:103]
	v_mfma_f32_16x16x32_bf16 v[96:99], v[176:179], v[206:209], v[96:99]
	v_mfma_f32_16x16x32_bf16 v[84:87], v[168:171], v[214:217], v[84:87]
	v_mfma_f32_16x16x32_bf16 v[80:83], v[176:179], v[214:217], v[80:83]
	v_mfma_f32_16x16x32_bf16 v[68:71], v[168:171], v[222:225], v[68:71]
	v_mfma_f32_16x16x32_bf16 v[64:67], v[176:179], v[222:225], v[64:67]
	s_setprio 0
	s_barrier
; #define PG8_STAGE(bufoff, gbase, voff) do { _Pragma("unroll") for (int _i = 0; _i < 2; ++_i) \
;         __builtin_amdgcn_global_load_lds((const unsigned*)((const char*)(gbase) + (voff)[_i]), (PG8_LAS unsigned*)(lds + (bufoff) + ldsw + _i * 8192), 16, 0, 0); } while (0)
; #define PG8_LDA(dst, b, h) do { _Pragma("unroll") for (int m = 0; m < 4; ++m) _Pragma("unroll") for (int k = 0; k < 2; ++k) dst[m][k] = *(const PG8_LAS bf16x8*)(lds + PG8_SA(b, h) + aoff + m * 2048 + k * 1024); } while (0)
; #define PG8_MMA(ai, bj, At, Bt) do { __builtin_amdgcn_s_setprio(1); _Pragma("unroll") for (int m = 0; m < 4; ++m) _Pragma("unroll") for (int n = 0; n < 2; ++n) _Pragma("unroll") for (int k = 0; k < 2; ++k) \
;         acc[ai][bj][m][n] = __builtin_amdgcn_mfma_f32_16x16x32_bf16(Bt[n][k], At[m][k], acc[ai][bj][m][n], 0, 0, 0); __builtin_amdgcn_s_setprio(0); } while (0)
; #define PG8_WAIT_V(n) asm volatile("s_waitcnt vmcnt(" #n ")" ::: "memory")
; #define PG8_WAIT_L(n) asm volatile("s_waitcnt lgkmcnt(" #n ")" ::: "memory")
; #define PG8_BAR __builtin_amdgcn_s_barrier()
; #define PG8_SCHED __builtin_amdgcn_sched_barrier(0)
; template <class Epi, class Sched, bool ALIGN_EPI = false, bool SP2 = false>
; __device__ __forceinline__ void gemm_phase(PG8_LAS unsigned char* lds, const Gemm g, const Sched& S, const Epi& E, int tid_in) {
;     ...
;             PG8_LDA(At, 1, 1); PG8_STAGE(PG8_SB(1, 0), b3, voffB); PG8_STAGE(PG8_SB(1, 1), b3 + hstep, voffB); PG8_STAGE(PG8_SA(1, 0), a3, voffA);
;             PG8_WAIT_V(8); PG8_WAIT_L(0); PG8_BAR; PG8_MMA(1, 0, At, B0); PG8_MMA(1, 1, At, B1); PG8_BAR; PG8_SCHED;
	s_add_i32 s4, s4, s61
	v_lshl_add_u64 v[226:227], v[226:227], 0, s[20:21]
	s_mov_b32 m0, s4
	ds_read_b128 v[180:183], v200 offset:49152
	ds_read_b128 v[184:187], v200 offset:50176
	ds_read_b128 v[188:191], v200 offset:51200
	ds_read_b128 v[206:209], v200 offset:52224
	ds_read_b128 v[210:213], v200 offset:53248
	ds_read_b128 v[214:217], v200 offset:54272
	ds_read_b128 v[218:221], v200 offset:55296
	ds_read_b128 v[222:225], v200 offset:56320
	s_mov_b64 exec, s[98:99]
	global_load_lds_dwordx4 v[226:227], off
	s_mov_b64 exec, -1
	s_add_i32 m0, s4, 0x2000
	s_add_u32 s48, s48, 0x40080
	v_lshl_add_u64 v[226:227], v[228:229], 0, s[20:21]
	s_addc_u32 s49, s49, 0
	s_add_i32 s4, s5, s61
	s_mov_b64 exec, s[98:99]
	global_load_lds_dwordx4 v[226:227], off
	s_mov_b64 exec, -1
	v_lshl_add_u64 v[226:227], s[48:49], 0, v[130:131]
	s_mov_b32 m0, s4
	s_nop 0
	s_mov_b64 exec, s[98:99]
	global_load_lds_dwordx4 v[226:227], off
	s_mov_b64 exec, -1
	v_lshl_add_u64 v[226:227], s[48:49], 0, v[134:135]
	s_add_i32 m0, s4, 0x2000
	s_nop 0
	s_mov_b64 exec, s[98:99]
	global_load_lds_dwordx4 v[226:227], off
	s_mov_b64 exec, -1
	v_lshl_add_u64 v[226:227], v[230:231], 0, s[20:21]
	s_mov_b32 m0, s68
	s_nop 0
	s_mov_b64 exec, s[98:99]
	global_load_lds_dwordx4 v[226:227], off
	s_mov_b64 exec, -1
	v_lshl_add_u64 v[226:227], v[232:233], 0, s[20:21]
	s_mov_b32 m0, s69
	s_nop 0
	s_mov_b64 exec, s[98:99]
	global_load_lds_dwordx4 v[226:227], off
	s_mov_b64 exec, -1
	s_waitcnt vmcnt(8)
	s_waitcnt lgkmcnt(0)
	s_barrier
	s_setprio 1
	s_waitcnt lgkmcnt(0)
	v_mfma_f32_16x16x32_bf16 v[60:63], v[148:151], v[180:183], v[60:63]
	v_mfma_f32_16x16x32_bf16 v[56:59], v[156:159], v[180:183], v[56:59]
	v_mfma_f32_16x16x32_bf16 v[44:47], v[148:151], v[188:191], v[44:47]
	v_mfma_f32_16x16x32_bf16 v[40:43], v[156:159], v[188:191], v[40:43]
	v_mfma_f32_16x16x32_bf16 v[28:31], v[148:151], v[210:213], v[28:31]
	v_mfma_f32_16x16x32_bf16 v[24:27], v[156:159], v[210:213], v[24:27]
	v_mfma_f32_16x16x32_bf16 v[12:15], v[148:151], v[218:221], v[12:15]
	v_mfma_f32_16x16x32_bf16 v[8:11], v[156:159], v[218:221], v[8:11]
	v_mfma_f32_16x16x32_bf16 v[60:63], v[152:155], v[184:187], v[60:63]
	v_mfma_f32_16x16x32_bf16 v[56:59], v[160:163], v[184:187], v[56:59]
	v_mfma_f32_16x16x32_bf16 v[44:47], v[152:155], v[206:209], v[44:47]
	v_mfma_f32_16x16x32_bf16 v[40:43], v[160:163], v[206:209], v[40:43]
	v_mfma_f32_16x16x32_bf16 v[28:31], v[152:155], v[214:217], v[28:31]
	v_mfma_f32_16x16x32_bf16 v[24:27], v[160:163], v[214:217], v[24:27]
	v_mfma_f32_16x16x32_bf16 v[12:15], v[152:155], v[222:225], v[12:15]
	v_mfma_f32_16x16x32_bf16 v[8:11], v[160:163], v[222:225], v[8:11]
	s_setprio 0
	s_setprio 1
	v_mfma_f32_16x16x32_bf16 v[52:55], v[164:167], v[180:183], v[52:55]
	v_mfma_f32_16x16x32_bf16 v[48:51], v[172:175], v[180:183], v[48:51]
	v_mfma_f32_16x16x32_bf16 v[36:39], v[164:167], v[188:191], v[36:39]
	v_mfma_f32_16x16x32_bf16 v[32:35], v[172:175], v[188:191], v[32:35]
	v_mfma_f32_16x16x32_bf16 v[20:23], v[164:167], v[210:213], v[20:23]
	v_mfma_f32_16x16x32_bf16 v[16:19], v[172:175], v[210:213], v[16:19]
	v_mfma_f32_16x16x32_bf16 v[4:7], v[164:167], v[218:221], v[4:7]
	v_mfma_f32_16x16x32_bf16 v[0:3], v[172:175], v[218:221], v[0:3]
	v_mfma_f32_16x16x32_bf16 v[52:55], v[168:171], v[184:187], v[52:55]
	v_mfma_f32_16x16x32_bf16 v[48:51], v[176:179], v[184:187], v[48:51]
	v_mfma_f32_16x16x32_bf16 v[36:39], v[168:171], v[206:209], v[36:39]
	v_mfma_f32_16x16x32_bf16 v[32:35], v[176:179], v[206:209], v[32:35]
	v_mfma_f32_16x16x32_bf16 v[20:23], v[168:171], v[214:217], v[20:23]
	v_mfma_f32_16x16x32_bf16 v[16:19], v[176:179], v[214:217], v[16:19]
	v_mfma_f32_16x16x32_bf16 v[4:7], v[168:171], v[222:225], v[4:7]
	v_mfma_f32_16x16x32_bf16 v[0:3], v[176:179], v[222:225], v[0:3]
	s_setprio 0
	s_barrier
	s_add_i32 s53, s53, 2
	s_add_u32 s33, s33, 0x100
	s_addc_u32 s51, s51, 0
	s_add_u32 s46, s46, 0x100
	s_addc_u32 s47, s47, 0
	s_cmp_gt_u32 s53, 13
	s_branch .Lpost9

; #define PG8_STAGE(bufoff, gbase, voff) do { _Pragma("unroll") for (int _i = 0; _i < 2; ++_i) \
;         __builtin_amdgcn_global_load_lds((const unsigned*)((const char*)(gbase) + (voff)[_i]), (PG8_LAS unsigned*)(lds + (bufoff) + ldsw + _i * 8192), 16, 0, 0); } while (0)
; #define PG8_LDA(dst, b, h) do { _Pragma("unroll") for (int m = 0; m < 4; ++m) _Pragma("unroll") for (int k = 0; k < 2; ++k) dst[m][k] = *(const PG8_LAS bf16x8*)(lds + PG8_SA(b, h) + aoff + m * 2048 + k * 1024); } while (0)
; #define PG8_LDB(dst, b, h) do { _Pragma("unroll") for (int n = 0; n < 2; ++n) _Pragma("unroll") for (int k = 0; k < 2; ++k) dst[n][k] = *(const PG8_LAS bf16x8*)(lds + PG8_SB(b, h) + boff + n * 2048 + k * 1024); } while (0)
; #define PG8_MMA(ai, bj, At, Bt) do { __builtin_amdgcn_s_setprio(1); _Pragma("unroll") for (int m = 0; m < 4; ++m) _Pragma("unroll") for (int n = 0; n < 2; ++n) _Pragma("unroll") for (int k = 0; k < 2; ++k) \
;         acc[ai][bj][m][n] = __builtin_amdgcn_mfma_f32_16x16x32_bf16(Bt[n][k], At[m][k], acc[ai][bj][m][n], 0, 0, 0); __builtin_amdgcn_s_setprio(0); } while (0)
; #define PG8_WAIT_V(n) asm volatile("s_waitcnt vmcnt(" #n ")" ::: "memory")
; #define PG8_BAR __builtin_amdgcn_s_barrier()
; template <class Epi, class Sched, bool ALIGN_EPI = false, bool SP2 = false>
; __device__ __forceinline__ void gemm_phase(PG8_LAS unsigned char* lds, const Gemm g, const Sched& S, const Epi& E, int tid_in) {
;     ...
;         for (int t = 0; t < nt; t += 2) {
;             const bool last = (t == nt - 2);
;             const char* a1 = cA + (size_t)(t + 1) * kstep;
;             const char* a2 = last ? nA : cA + (size_t)(t + 2) * kstep; const char* b2 = last ? nB : cB + (size_t)(t + 2) * kstep;
;             const char* a3 = a2 + kstep; const char* b3 = b2 + kstep;
;             if (last && has_next) S.a_ready(nxt);
;             if constexpr (SP2) {
;             PG8_LDB(B0, 0, 0); PG8_LDB(B1, 0, 1); PG8_SCHED; PG8_LDA(At, 0, 0); PG8_STAGE(PG8_SA(1, 1), a1 + hstep, voffA);
;             PG8_WAIT_V(8); PG8_WAIT_L(0); PG8_BAR; PG8_MMA(0, 0, At, B0); PG8_MMA(0, 1, At, B1); PG8_BAR; PG8_SCHED;
;             PG8_LDA(At, 0, 1); PG8_STAGE(PG8_SB(0, 0), b2, voffB); PG8_STAGE(PG8_SB(0, 1), b2 + hstep, voffB); PG8_STAGE(PG8_SA(0, 0), a2, voffA);
;             PG8_WAIT_V(8); PG8_WAIT_L(0); PG8_BAR; PG8_MMA(1, 0, At, B0); PG8_MMA(1, 1, At, B1); PG8_BAR; PG8_SCHED;
.LBB0_1504:
	ds_read_b128 v[120:123], v189
	ds_read_b128 v[132:135], v189 offset:1024
	ds_read_b128 v[136:139], v189 offset:2048
	ds_read_b128 v[140:143], v189 offset:3072
	ds_read_b128 v[144:147], v190
	ds_read_b128 v[148:151], v190 offset:1024
	ds_read_b128 v[168:171], v190 offset:2048
	ds_read_b128 v[172:175], v190 offset:3072
	s_add_u32 s4, s52, 0xfffc0080
	s_addc_u32 s5, s53, -1
	s_cmp_eq_u32 s70, 12
	s_cselect_b32 s57, s45, s5
	s_cselect_b32 s56, s51, s4
	s_cselect_b32 s55, s43, s69
	s_cselect_b32 s54, s67, s68
	s_cbranch_scc1 .Lpk10
	v_lshl_add_u64 v[184:185], s[52:53], 0, v[162:163]
	s_add_i32 m0, s13, 0xc000
	ds_read_b128 v[176:179], v191
	ds_read_b128 v[180:183], v191 offset:1024
	ds_read_b128 v[192:195], v191 offset:2048
	ds_read_b128 v[196:199], v191 offset:3072
	ds_read_b128 v[202:205], v191 offset:4096
	ds_read_b128 v[206:209], v191 offset:5120
	ds_read_b128 v[210:213], v191 offset:6144
	ds_read_b128 v[214:217], v191 offset:7168
	global_load_lds_dwordx4 v[184:185], off
	v_lshl_add_u64 v[184:185], s[52:53], 0, v[160:161]
	s_add_i32 m0, s13, 0xe000
	s_nop 0
	global_load_lds_dwordx4 v[184:185], off
	s_waitcnt vmcnt(8)
	s_waitcnt lgkmcnt(0)
	s_barrier
	s_setprio 1
	s_waitcnt lgkmcnt(0)
	v_mfma_f32_16x16x32_bf16 v[128:131], v[120:123], v[176:179], v[128:131]
	v_mfma_f32_16x16x32_bf16 v[124:127], v[136:139], v[176:179], v[124:127]
	v_mfma_f32_16x16x32_bf16 v[108:111], v[120:123], v[192:195], v[108:111]
	v_mfma_f32_16x16x32_bf16 v[104:107], v[136:139], v[192:195], v[104:107]
	v_mfma_f32_16x16x32_bf16 v[92:95], v[120:123], v[202:205], v[92:95]
	v_mfma_f32_16x16x32_bf16 v[88:91], v[136:139], v[202:205], v[88:91]
	v_mfma_f32_16x16x32_bf16 v[76:79], v[120:123], v[210:213], v[76:79]
	v_mfma_f32_16x16x32_bf16 v[72:75], v[136:139], v[210:213], v[72:75]
	v_mfma_f32_16x16x32_bf16 v[128:131], v[132:135], v[180:183], v[128:131]
	v_mfma_f32_16x16x32_bf16 v[124:127], v[140:143], v[180:183], v[124:127]
	v_mfma_f32_16x16x32_bf16 v[108:111], v[132:135], v[196:199], v[108:111]
	v_mfma_f32_16x16x32_bf16 v[104:107], v[140:143], v[196:199], v[104:107]
	v_mfma_f32_16x16x32_bf16 v[92:95], v[132:135], v[206:209], v[92:95]
	v_mfma_f32_16x16x32_bf16 v[88:91], v[140:143], v[206:209], v[88:91]
	v_mfma_f32_16x16x32_bf16 v[76:79], v[132:135], v[214:217], v[76:79]
	v_mfma_f32_16x16x32_bf16 v[72:75], v[140:143], v[214:217], v[72:75]
	s_setprio 0
	s_setprio 1
	v_mfma_f32_16x16x32_bf16 v[116:119], v[144:147], v[176:179], v[116:119]
	v_mfma_f32_16x16x32_bf16 v[112:115], v[168:171], v[176:179], v[112:115]
	v_mfma_f32_16x16x32_bf16 v[100:103], v[144:147], v[192:195], v[100:103]
	v_mfma_f32_16x16x32_bf16 v[96:99], v[168:171], v[192:195], v[96:99]
	v_mfma_f32_16x16x32_bf16 v[84:87], v[144:147], v[202:205], v[84:87]
	v_mfma_f32_16x16x32_bf16 v[80:83], v[168:171], v[202:205], v[80:83]
	v_mfma_f32_16x16x32_bf16 v[68:71], v[144:147], v[210:213], v[68:71]
	v_mfma_f32_16x16x32_bf16 v[64:67], v[168:171], v[210:213], v[64:67]
	v_mfma_f32_16x16x32_bf16 v[116:119], v[148:151], v[180:183], v[116:119]
	v_mfma_f32_16x16x32_bf16 v[112:115], v[172:175], v[180:183], v[112:115]
	v_mfma_f32_16x16x32_bf16 v[100:103], v[148:151], v[196:199], v[100:103]
	v_mfma_f32_16x16x32_bf16 v[96:99], v[172:175], v[196:199], v[96:99]
	v_mfma_f32_16x16x32_bf16 v[84:87], v[148:151], v[206:209], v[84:87]
	v_mfma_f32_16x16x32_bf16 v[80:83], v[172:175], v[206:209], v[80:83]
	v_mfma_f32_16x16x32_bf16 v[68:71], v[148:151], v[214:217], v[68:71]
	v_mfma_f32_16x16x32_bf16 v[64:67], v[172:175], v[214:217], v[64:67]
	s_setprio 0
	s_barrier
	s_add_i32 s4, s64, s12
	v_lshl_add_u64 v[184:185], s[54:55], 0, v[154:155]
	s_mov_b32 m0, s4
	ds_read_b128 v[176:179], v191 offset:16384
	ds_read_b128 v[180:183], v191 offset:17408
	ds_read_b128 v[192:195], v191 offset:18432
	ds_read_b128 v[196:199], v191 offset:19456
	ds_read_b128 v[202:205], v191 offset:20480
	ds_read_b128 v[206:209], v191 offset:21504
	ds_read_b128 v[210:213], v191 offset:22528
	ds_read_b128 v[214:217], v191 offset:23552
	global_load_lds_dwordx4 v[184:185], off
	s_add_i32 m0, s4, 0x2000
	s_add_u32 s72, s54, 0x40000
	v_lshl_add_u64 v[218:219], s[54:55], 0, v[158:159]
	s_addc_u32 s73, s55, 0
	s_add_i32 s4, s65, s12
	global_load_lds_dwordx4 v[218:219], off
	v_lshl_add_u64 v[220:221], s[72:73], 0, v[154:155]
	s_mov_b32 m0, s4
	v_lshl_add_u64 v[222:223], s[56:57], 0, v[156:157]
	global_load_lds_dwordx4 v[220:221], off
	v_lshl_add_u64 v[220:221], s[72:73], 0, v[158:159]
	s_add_i32 m0, s4, 0x2000
	s_nop 0
	global_load_lds_dwordx4 v[220:221], off
	v_lshl_add_u64 v[220:221], s[56:57], 0, v[152:153]
	s_mov_b32 m0, s13
	s_nop 0
	global_load_lds_dwordx4 v[220:221], off
	s_mov_b32 m0, s33
	s_nop 0
	global_load_lds_dwordx4 v[222:223], off
	s_waitcnt vmcnt(8)
	s_waitcnt lgkmcnt(0)
	s_barrier
; #define PG8_STAGE(bufoff, gbase, voff) do { _Pragma("unroll") for (int _i = 0; _i < 2; ++_i) \
;         __builtin_amdgcn_global_load_lds((const unsigned*)((const char*)(gbase) + (voff)[_i]), (PG8_LAS unsigned*)(lds + (bufoff) + ldsw + _i * 8192), 16, 0, 0); } while (0)
; #define PG8_LDA(dst, b, h) do { _Pragma("unroll") for (int m = 0; m < 4; ++m) _Pragma("unroll") for (int k = 0; k < 2; ++k) dst[m][k] = *(const PG8_LAS bf16x8*)(lds + PG8_SA(b, h) + aoff + m * 2048 + k * 1024); } while (0)
; #define PG8_LDB(dst, b, h) do { _Pragma("unroll") for (int n = 0; n < 2; ++n) _Pragma("unroll") for (int k = 0; k < 2; ++k) dst[n][k] = *(const PG8_LAS bf16x8*)(lds + PG8_SB(b, h) + boff + n * 2048 + k * 1024); } while (0)
; #define PG8_MMA(ai, bj, At, Bt) do { __builtin_amdgcn_s_setprio(1); _Pragma("unroll") for (int m = 0; m < 4; ++m) _Pragma("unroll") for (int n = 0; n < 2; ++n) _Pragma("unroll") for (int k = 0; k < 2; ++k) \
;         acc[ai][bj][m][n] = __builtin_amdgcn_mfma_f32_16x16x32_bf16(Bt[n][k], At[m][k], acc[ai][bj][m][n], 0, 0, 0); __builtin_amdgcn_s_setprio(0); } while (0)
; #define PG8_WAIT_V(n) asm volatile("s_waitcnt vmcnt(" #n ")" ::: "memory")
; #define PG8_WAIT_L(n) asm volatile("s_waitcnt lgkmcnt(" #n ")" ::: "memory")
; #define PG8_BAR __builtin_amdgcn_s_barrier()
; #define PG8_SCHED __builtin_amdgcn_sched_barrier(0)
; template <class Epi, class Sched, bool ALIGN_EPI = false, bool SP2 = false>
; __device__ __forceinline__ void gemm_phase(PG8_LAS unsigned char* lds, const Gemm g, const Sched& S, const Epi& E, int tid_in) {
;     ...
;             PG8_WAIT_V(8); PG8_WAIT_L(0); PG8_BAR; PG8_MMA(1, 0, At, B0); PG8_MMA(1, 1, At, B1); PG8_BAR; PG8_SCHED;
;             PG8_LDB(B0, 1, 0); PG8_LDB(B1, 1, 1); PG8_SCHED; PG8_LDA(At, 1, 0); PG8_STAGE(PG8_SA(0, 1), a2 + hstep, voffA);
;             PG8_WAIT_V(8); PG8_WAIT_L(0); PG8_BAR; PG8_MMA(0, 0, At, B0); PG8_MMA(0, 1, At, B1); PG8_BAR; PG8_SCHED;
;             PG8_LDA(At, 1, 1); PG8_STAGE(PG8_SB(1, 0), b3, voffB); PG8_STAGE(PG8_SB(1, 1), b3 + hstep, voffB); PG8_STAGE(PG8_SA(1, 0), a3, voffA);
	s_setprio 1
	s_waitcnt lgkmcnt(0)
	v_mfma_f32_16x16x32_bf16 v[60:63], v[120:123], v[176:179], v[60:63]
	v_mfma_f32_16x16x32_bf16 v[56:59], v[136:139], v[176:179], v[56:59]
	v_mfma_f32_16x16x32_bf16 v[44:47], v[120:123], v[192:195], v[44:47]
	v_mfma_f32_16x16x32_bf16 v[40:43], v[136:139], v[192:195], v[40:43]
	v_mfma_f32_16x16x32_bf16 v[28:31], v[120:123], v[202:205], v[28:31]
	v_mfma_f32_16x16x32_bf16 v[24:27], v[136:139], v[202:205], v[24:27]
	v_mfma_f32_16x16x32_bf16 v[12:15], v[120:123], v[210:213], v[12:15]
	v_mfma_f32_16x16x32_bf16 v[8:11], v[136:139], v[210:213], v[8:11]
	v_mfma_f32_16x16x32_bf16 v[60:63], v[132:135], v[180:183], v[60:63]
	v_mfma_f32_16x16x32_bf16 v[56:59], v[140:143], v[180:183], v[56:59]
	v_mfma_f32_16x16x32_bf16 v[44:47], v[132:135], v[196:199], v[44:47]
	v_mfma_f32_16x16x32_bf16 v[40:43], v[140:143], v[196:199], v[40:43]
	v_mfma_f32_16x16x32_bf16 v[28:31], v[132:135], v[206:209], v[28:31]
	v_mfma_f32_16x16x32_bf16 v[24:27], v[140:143], v[206:209], v[24:27]
	v_mfma_f32_16x16x32_bf16 v[12:15], v[132:135], v[214:217], v[12:15]
	v_mfma_f32_16x16x32_bf16 v[8:11], v[140:143], v[214:217], v[8:11]
	s_setprio 0
	s_setprio 1
	v_mfma_f32_16x16x32_bf16 v[52:55], v[144:147], v[176:179], v[52:55]
	v_mfma_f32_16x16x32_bf16 v[48:51], v[168:171], v[176:179], v[48:51]
	v_mfma_f32_16x16x32_bf16 v[36:39], v[144:147], v[192:195], v[36:39]
	v_mfma_f32_16x16x32_bf16 v[32:35], v[168:171], v[192:195], v[32:35]
	v_mfma_f32_16x16x32_bf16 v[20:23], v[144:147], v[202:205], v[20:23]
	v_mfma_f32_16x16x32_bf16 v[16:19], v[168:171], v[202:205], v[16:19]
	v_mfma_f32_16x16x32_bf16 v[4:7], v[144:147], v[210:213], v[4:7]
	v_mfma_f32_16x16x32_bf16 v[0:3], v[168:171], v[210:213], v[0:3]
	v_mfma_f32_16x16x32_bf16 v[52:55], v[148:151], v[180:183], v[52:55]
	v_mfma_f32_16x16x32_bf16 v[48:51], v[172:175], v[180:183], v[48:51]
	v_mfma_f32_16x16x32_bf16 v[36:39], v[148:151], v[196:199], v[36:39]
	v_mfma_f32_16x16x32_bf16 v[32:35], v[172:175], v[196:199], v[32:35]
	v_mfma_f32_16x16x32_bf16 v[20:23], v[148:151], v[206:209], v[20:23]
	v_mfma_f32_16x16x32_bf16 v[16:19], v[172:175], v[206:209], v[16:19]
	v_mfma_f32_16x16x32_bf16 v[4:7], v[148:151], v[214:217], v[4:7]
	v_mfma_f32_16x16x32_bf16 v[0:3], v[172:175], v[214:217], v[0:3]
	s_setprio 0
	s_barrier
	s_add_i32 s4, 0, 0x18000
	s_add_i32 s5, 0, 0x1c000
	v_add_u32_e32 v140, s4, v187
	v_add_u32_e32 v172, s5, v187
	ds_read_b128 v[120:123], v140
	ds_read_b128 v[132:135], v140 offset:1024
	ds_read_b128 v[136:139], v140 offset:2048
	ds_read_b128 v[140:143], v140 offset:3072
	ds_read_b128 v[144:147], v172
	ds_read_b128 v[148:151], v172 offset:1024
	ds_read_b128 v[168:171], v172 offset:2048
	ds_read_b128 v[172:175], v172 offset:3072
	s_add_u32 s56, s56, 0x40000
	s_addc_u32 s57, s57, 0
	s_mov_b32 m0, s40
	v_lshl_add_u64 v[224:225], s[56:57], 0, v[152:153]
	ds_read_b128 v[176:179], v191 offset:32768
	ds_read_b128 v[180:183], v191 offset:33792
	ds_read_b128 v[192:195], v191 offset:34816
	ds_read_b128 v[196:199], v191 offset:35840
	ds_read_b128 v[202:205], v191 offset:36864
	ds_read_b128 v[206:209], v191 offset:37888
	ds_read_b128 v[210:213], v191 offset:38912
	ds_read_b128 v[214:217], v191 offset:39936
	global_load_lds_dwordx4 v[224:225], off
	v_lshl_add_u64 v[224:225], s[56:57], 0, v[156:157]
	s_mov_b32 m0, s41
	s_nop 0
	global_load_lds_dwordx4 v[224:225], off
	s_waitcnt vmcnt(8)
	s_waitcnt lgkmcnt(0)
	s_barrier
	s_setprio 1
	s_waitcnt lgkmcnt(0)
	v_mfma_f32_16x16x32_bf16 v[128:131], v[120:123], v[176:179], v[128:131]
	v_mfma_f32_16x16x32_bf16 v[124:127], v[136:139], v[176:179], v[124:127]
	v_mfma_f32_16x16x32_bf16 v[108:111], v[120:123], v[192:195], v[108:111]
	v_mfma_f32_16x16x32_bf16 v[104:107], v[136:139], v[192:195], v[104:107]
	v_mfma_f32_16x16x32_bf16 v[92:95], v[120:123], v[202:205], v[92:95]
	v_mfma_f32_16x16x32_bf16 v[88:91], v[136:139], v[202:205], v[88:91]
	v_mfma_f32_16x16x32_bf16 v[76:79], v[120:123], v[210:213], v[76:79]
	v_mfma_f32_16x16x32_bf16 v[72:75], v[136:139], v[210:213], v[72:75]
	v_mfma_f32_16x16x32_bf16 v[128:131], v[132:135], v[180:183], v[128:131]
	v_mfma_f32_16x16x32_bf16 v[124:127], v[140:143], v[180:183], v[124:127]
	v_mfma_f32_16x16x32_bf16 v[108:111], v[132:135], v[196:199], v[108:111]
	v_mfma_f32_16x16x32_bf16 v[104:107], v[140:143], v[196:199], v[104:107]
	v_mfma_f32_16x16x32_bf16 v[92:95], v[132:135], v[206:209], v[92:95]
	v_mfma_f32_16x16x32_bf16 v[88:91], v[140:143], v[206:209], v[88:91]
	v_mfma_f32_16x16x32_bf16 v[76:79], v[132:135], v[214:217], v[76:79]
	v_mfma_f32_16x16x32_bf16 v[72:75], v[140:143], v[214:217], v[72:75]
	s_setprio 0
	s_setprio 1
	v_mfma_f32_16x16x32_bf16 v[116:119], v[144:147], v[176:179], v[116:119]
	v_mfma_f32_16x16x32_bf16 v[112:115], v[168:171], v[176:179], v[112:115]
	v_mfma_f32_16x16x32_bf16 v[100:103], v[144:147], v[192:195], v[100:103]
	v_mfma_f32_16x16x32_bf16 v[96:99], v[168:171], v[192:195], v[96:99]
	v_mfma_f32_16x16x32_bf16 v[84:87], v[144:147], v[202:205], v[84:87]
	v_mfma_f32_16x16x32_bf16 v[80:83], v[168:171], v[202:205], v[80:83]
	v_mfma_f32_16x16x32_bf16 v[68:71], v[144:147], v[210:213], v[68:71]
	v_mfma_f32_16x16x32_bf16 v[64:67], v[168:171], v[210:213], v[64:67]
	v_mfma_f32_16x16x32_bf16 v[116:119], v[148:151], v[180:183], v[116:119]
	v_mfma_f32_16x16x32_bf16 v[112:115], v[172:175], v[180:183], v[112:115]
	v_mfma_f32_16x16x32_bf16 v[100:103], v[148:151], v[196:199], v[100:103]
	v_mfma_f32_16x16x32_bf16 v[96:99], v[172:175], v[196:199], v[96:99]
	v_mfma_f32_16x16x32_bf16 v[84:87], v[148:151], v[206:209], v[84:87]
	v_mfma_f32_16x16x32_bf16 v[80:83], v[172:175], v[206:209], v[80:83]
	v_mfma_f32_16x16x32_bf16 v[68:71], v[148:151], v[214:217], v[68:71]
	v_mfma_f32_16x16x32_bf16 v[64:67], v[172:175], v[214:217], v[64:67]
	s_setprio 0
	s_barrier
; #define PG8_STAGE(bufoff, gbase, voff) do { _Pragma("unroll") for (int _i = 0; _i < 2; ++_i) \
;         __builtin_amdgcn_global_load_lds((const unsigned*)((const char*)(gbase) + (voff)[_i]), (PG8_LAS unsigned*)(lds + (bufoff) + ldsw + _i * 8192), 16, 0, 0); } while (0)
; #define PG8_LDA(dst, b, h) do { _Pragma("unroll") for (int m = 0; m < 4; ++m) _Pragma("unroll") for (int k = 0; k < 2; ++k) dst[m][k] = *(const PG8_LAS bf16x8*)(lds + PG8_SA(b, h) + aoff + m * 2048 + k * 1024); } while (0)
; #define PG8_MMA(ai, bj, At, Bt) do { __builtin_amdgcn_s_setprio(1); _Pragma("unroll") for (int m = 0; m < 4; ++m) _Pragma("unroll") for (int n = 0; n < 2; ++n) _Pragma("unroll") for (int k = 0; k < 2; ++k) \
;         acc[ai][bj][m][n] = __builtin_amdgcn_mfma_f32_16x16x32_bf16(Bt[n][k], At[m][k], acc[ai][bj][m][n], 0, 0, 0); __builtin_amdgcn_s_setprio(0); } while (0)
; #define PG8_WAIT_V(n) asm volatile("s_waitcnt vmcnt(" #n ")" ::: "memory")
; #define PG8_WAIT_L(n) asm volatile("s_waitcnt lgkmcnt(" #n ")" ::: "memory")
; #define PG8_BAR __builtin_amdgcn_s_barrier()
; #define PG8_SCHED __builtin_amdgcn_sched_barrier(0)
; template <class Epi, class Sched, bool ALIGN_EPI = false, bool SP2 = false>
; __device__ __forceinline__ void gemm_phase(PG8_LAS unsigned char* lds, const Gemm g, const Sched& S, const Epi& E, int tid_in) {
;     ...
;             PG8_LDA(At, 1, 1); PG8_STAGE(PG8_SB(1, 0), b3, voffB); PG8_STAGE(PG8_SB(1, 1), b3 + hstep, voffB); PG8_STAGE(PG8_SA(1, 0), a3, voffA);
;             PG8_WAIT_V(8); PG8_WAIT_L(0); PG8_BAR; PG8_MMA(1, 0, At, B0); PG8_MMA(1, 1, At, B1); PG8_BAR; PG8_SCHED;
	s_add_i32 s4, s4, s12
	v_lshl_add_u64 v[184:185], v[184:185], 0, s[24:25]
	s_mov_b32 m0, s4
	ds_read_b128 v[176:179], v191 offset:49152
	ds_read_b128 v[180:183], v191 offset:50176
	ds_read_b128 v[192:195], v191 offset:51200
	ds_read_b128 v[196:199], v191 offset:52224
	ds_read_b128 v[202:205], v191 offset:53248
	ds_read_b128 v[206:209], v191 offset:54272
	ds_read_b128 v[210:213], v191 offset:55296
	ds_read_b128 v[214:217], v191 offset:56320
	global_load_lds_dwordx4 v[184:185], off
	s_add_i32 m0, s4, 0x2000
	s_add_u32 s54, s54, 0x40080
	v_lshl_add_u64 v[184:185], v[218:219], 0, s[24:25]
	s_addc_u32 s55, s55, 0
	s_add_i32 s4, s5, s12
	global_load_lds_dwordx4 v[184:185], off
	v_lshl_add_u64 v[184:185], s[54:55], 0, v[154:155]
	s_mov_b32 m0, s4
	s_nop 0
	global_load_lds_dwordx4 v[184:185], off
	v_lshl_add_u64 v[184:185], s[54:55], 0, v[158:159]
	s_add_i32 m0, s4, 0x2000
	s_nop 0
	global_load_lds_dwordx4 v[184:185], off
	v_lshl_add_u64 v[184:185], v[220:221], 0, s[24:25]
	s_mov_b32 m0, s59
	s_nop 0
	global_load_lds_dwordx4 v[184:185], off
	v_lshl_add_u64 v[184:185], v[222:223], 0, s[24:25]
	s_mov_b32 m0, s60
	s_nop 0
	global_load_lds_dwordx4 v[184:185], off
	s_waitcnt vmcnt(8)
	s_waitcnt lgkmcnt(0)
	s_barrier
	s_setprio 1
	s_waitcnt lgkmcnt(0)
	v_mfma_f32_16x16x32_bf16 v[60:63], v[120:123], v[176:179], v[60:63]
	v_mfma_f32_16x16x32_bf16 v[56:59], v[136:139], v[176:179], v[56:59]
	v_mfma_f32_16x16x32_bf16 v[44:47], v[120:123], v[192:195], v[44:47]
	v_mfma_f32_16x16x32_bf16 v[40:43], v[136:139], v[192:195], v[40:43]
	v_mfma_f32_16x16x32_bf16 v[28:31], v[120:123], v[202:205], v[28:31]
	v_mfma_f32_16x16x32_bf16 v[24:27], v[136:139], v[202:205], v[24:27]
	v_mfma_f32_16x16x32_bf16 v[12:15], v[120:123], v[210:213], v[12:15]
	v_mfma_f32_16x16x32_bf16 v[8:11], v[136:139], v[210:213], v[8:11]
	v_mfma_f32_16x16x32_bf16 v[60:63], v[132:135], v[180:183], v[60:63]
	v_mfma_f32_16x16x32_bf16 v[56:59], v[140:143], v[180:183], v[56:59]
	v_mfma_f32_16x16x32_bf16 v[44:47], v[132:135], v[196:199], v[44:47]
	v_mfma_f32_16x16x32_bf16 v[40:43], v[140:143], v[196:199], v[40:43]
	v_mfma_f32_16x16x32_bf16 v[28:31], v[132:135], v[206:209], v[28:31]
	v_mfma_f32_16x16x32_bf16 v[24:27], v[140:143], v[206:209], v[24:27]
	v_mfma_f32_16x16x32_bf16 v[12:15], v[132:135], v[214:217], v[12:15]
	v_mfma_f32_16x16x32_bf16 v[8:11], v[140:143], v[214:217], v[8:11]
	s_setprio 0
	s_setprio 1
	v_mfma_f32_16x16x32_bf16 v[52:55], v[144:147], v[176:179], v[52:55]
	v_mfma_f32_16x16x32_bf16 v[48:51], v[168:171], v[176:179], v[48:51]
	v_mfma_f32_16x16x32_bf16 v[36:39], v[144:147], v[192:195], v[36:39]
	v_mfma_f32_16x16x32_bf16 v[32:35], v[168:171], v[192:195], v[32:35]
	v_mfma_f32_16x16x32_bf16 v[20:23], v[144:147], v[202:205], v[20:23]
	v_mfma_f32_16x16x32_bf16 v[16:19], v[168:171], v[202:205], v[16:19]
	v_mfma_f32_16x16x32_bf16 v[4:7], v[144:147], v[210:213], v[4:7]
	v_mfma_f32_16x16x32_bf16 v[0:3], v[168:171], v[210:213], v[0:3]
	v_mfma_f32_16x16x32_bf16 v[52:55], v[148:151], v[180:183], v[52:55]
	v_mfma_f32_16x16x32_bf16 v[48:51], v[172:175], v[180:183], v[48:51]
	v_mfma_f32_16x16x32_bf16 v[36:39], v[148:151], v[196:199], v[36:39]
	v_mfma_f32_16x16x32_bf16 v[32:35], v[172:175], v[196:199], v[32:35]
	v_mfma_f32_16x16x32_bf16 v[20:23], v[148:151], v[206:209], v[20:23]
	v_mfma_f32_16x16x32_bf16 v[16:19], v[172:175], v[206:209], v[16:19]
	v_mfma_f32_16x16x32_bf16 v[4:7], v[148:151], v[214:217], v[4:7]
	v_mfma_f32_16x16x32_bf16 v[0:3], v[172:175], v[214:217], v[0:3]
	s_setprio 0
	s_barrier
	s_add_i32 s70, s70, 2
	s_add_u32 s68, s68, 0x100
	s_addc_u32 s69, s69, 0
	s_add_u32 s52, s52, 0x100
	s_addc_u32 s53, s53, 0
	s_cmp_gt_u32 s70, 13
	s_cbranch_scc0 .LBB0_1504

; #define PG8_STAGE(bufoff, gbase, voff) do { _Pragma("unroll") for (int _i = 0; _i < 2; ++_i) \
;         __builtin_amdgcn_global_load_lds((const unsigned*)((const char*)(gbase) + (voff)[_i]), (PG8_LAS unsigned*)(lds + (bufoff) + ldsw + _i * 8192), 16, 0, 0); } while (0)
; #define PG8_LDA(dst, b, h) do { _Pragma("unroll") for (int m = 0; m < 4; ++m) _Pragma("unroll") for (int k = 0; k < 2; ++k) dst[m][k] = *(const PG8_LAS bf16x8*)(lds + PG8_SA(b, h) + aoff + m * 2048 + k * 1024); } while (0)
; #define PG8_LDB(dst, b, h) do { _Pragma("unroll") for (int n = 0; n < 2; ++n) _Pragma("unroll") for (int k = 0; k < 2; ++k) dst[n][k] = *(const PG8_LAS bf16x8*)(lds + PG8_SB(b, h) + boff + n * 2048 + k * 1024); } while (0)
; #define PG8_MMA(ai, bj, At, Bt) do { __builtin_amdgcn_s_setprio(1); _Pragma("unroll") for (int m = 0; m < 4; ++m) _Pragma("unroll") for (int n = 0; n < 2; ++n) _Pragma("unroll") for (int k = 0; k < 2; ++k) \
;         acc[ai][bj][m][n] = __builtin_amdgcn_mfma_f32_16x16x32_bf16(Bt[n][k], At[m][k], acc[ai][bj][m][n], 0, 0, 0); __builtin_amdgcn_s_setprio(0); } while (0)
; #define PG8_WAIT_V(n) asm volatile("s_waitcnt vmcnt(" #n ")" ::: "memory")
; #define PG8_WAIT_L(n) asm volatile("s_waitcnt lgkmcnt(" #n ")" ::: "memory")
; #define PG8_BAR __builtin_amdgcn_s_barrier()
; #define PG8_SCHED __builtin_amdgcn_sched_barrier(0)
; template <class Epi, class Sched, bool ALIGN_EPI = false, bool SP2 = false>
; __device__ __forceinline__ void gemm_phase(PG8_LAS unsigned char* lds, const Gemm g, const Sched& S, const Epi& E, int tid_in) {
;     ...
;             PG8_LDB(B0, 0, 0); PG8_LDB(B1, 0, 1); PG8_SCHED; PG8_LDA(At, 0, 0); PG8_STAGE(PG8_SA(1, 1), a1 + hstep, voffA);
;             PG8_WAIT_V(8); PG8_WAIT_L(0); PG8_BAR; PG8_MMA(0, 0, At, B0); PG8_MMA(0, 1, At, B1); PG8_BAR; PG8_SCHED;
;             PG8_LDA(At, 0, 1); PG8_STAGE(PG8_SB(0, 0), b2, voffB); PG8_STAGE(PG8_SB(0, 1), b2 + hstep, voffB); PG8_STAGE(PG8_SA(0, 0), a2, voffA);
;             PG8_WAIT_V(8); PG8_WAIT_L(0); PG8_BAR; PG8_MMA(1, 0, At, B0); PG8_MMA(1, 1, At, B1); PG8_BAR; PG8_SCHED;
.Lpk10:
	s_or_b64 s[98:99], s[14:15], 1
	v_lshl_add_u64 v[184:185], s[52:53], 0, v[162:163]
	s_add_i32 m0, s13, 0xc000
	ds_read_b128 v[176:179], v191
	ds_read_b128 v[180:183], v191 offset:1024
	ds_read_b128 v[192:195], v191 offset:2048
	ds_read_b128 v[196:199], v191 offset:3072
	ds_read_b128 v[202:205], v191 offset:4096
	ds_read_b128 v[206:209], v191 offset:5120
	ds_read_b128 v[210:213], v191 offset:6144
	ds_read_b128 v[214:217], v191 offset:7168
	global_load_lds_dwordx4 v[184:185], off
	v_lshl_add_u64 v[184:185], s[52:53], 0, v[160:161]
	s_add_i32 m0, s13, 0xe000
	s_nop 0
	global_load_lds_dwordx4 v[184:185], off
	s_waitcnt vmcnt(8)
	s_waitcnt lgkmcnt(0)
	s_barrier
	s_setprio 1
	s_waitcnt lgkmcnt(0)
	v_mfma_f32_16x16x32_bf16 v[128:131], v[120:123], v[176:179], v[128:131]
	v_mfma_f32_16x16x32_bf16 v[124:127], v[136:139], v[176:179], v[124:127]
	v_mfma_f32_16x16x32_bf16 v[108:111], v[120:123], v[192:195], v[108:111]
	v_mfma_f32_16x16x32_bf16 v[104:107], v[136:139], v[192:195], v[104:107]
	v_mfma_f32_16x16x32_bf16 v[92:95], v[120:123], v[202:205], v[92:95]
	v_mfma_f32_16x16x32_bf16 v[88:91], v[136:139], v[202:205], v[88:91]
	v_mfma_f32_16x16x32_bf16 v[76:79], v[120:123], v[210:213], v[76:79]
	v_mfma_f32_16x16x32_bf16 v[72:75], v[136:139], v[210:213], v[72:75]
	v_mfma_f32_16x16x32_bf16 v[128:131], v[132:135], v[180:183], v[128:131]
	v_mfma_f32_16x16x32_bf16 v[124:127], v[140:143], v[180:183], v[124:127]
	v_mfma_f32_16x16x32_bf16 v[108:111], v[132:135], v[196:199], v[108:111]
	v_mfma_f32_16x16x32_bf16 v[104:107], v[140:143], v[196:199], v[104:107]
	v_mfma_f32_16x16x32_bf16 v[92:95], v[132:135], v[206:209], v[92:95]
	v_mfma_f32_16x16x32_bf16 v[88:91], v[140:143], v[206:209], v[88:91]
	v_mfma_f32_16x16x32_bf16 v[76:79], v[132:135], v[214:217], v[76:79]
	v_mfma_f32_16x16x32_bf16 v[72:75], v[140:143], v[214:217], v[72:75]
	s_setprio 0
	s_setprio 1
	v_mfma_f32_16x16x32_bf16 v[116:119], v[144:147], v[176:179], v[116:119]
	v_mfma_f32_16x16x32_bf16 v[112:115], v[168:171], v[176:179], v[112:115]
	v_mfma_f32_16x16x32_bf16 v[100:103], v[144:147], v[192:195], v[100:103]
	v_mfma_f32_16x16x32_bf16 v[96:99], v[168:171], v[192:195], v[96:99]
	v_mfma_f32_16x16x32_bf16 v[84:87], v[144:147], v[202:205], v[84:87]
	v_mfma_f32_16x16x32_bf16 v[80:83], v[168:171], v[202:205], v[80:83]
	v_mfma_f32_16x16x32_bf16 v[68:71], v[144:147], v[210:213], v[68:71]
	v_mfma_f32_16x16x32_bf16 v[64:67], v[168:171], v[210:213], v[64:67]
	v_mfma_f32_16x16x32_bf16 v[116:119], v[148:151], v[180:183], v[116:119]
	v_mfma_f32_16x16x32_bf16 v[112:115], v[172:175], v[180:183], v[112:115]
	v_mfma_f32_16x16x32_bf16 v[100:103], v[148:151], v[196:199], v[100:103]
	v_mfma_f32_16x16x32_bf16 v[96:99], v[172:175], v[196:199], v[96:99]
	v_mfma_f32_16x16x32_bf16 v[84:87], v[148:151], v[206:209], v[84:87]
	v_mfma_f32_16x16x32_bf16 v[80:83], v[172:175], v[206:209], v[80:83]
	v_mfma_f32_16x16x32_bf16 v[68:71], v[148:151], v[214:217], v[68:71]
	v_mfma_f32_16x16x32_bf16 v[64:67], v[172:175], v[214:217], v[64:67]
	s_setprio 0
	s_barrier
	s_add_i32 s4, s64, s12
	v_lshl_add_u64 v[184:185], s[54:55], 0, v[154:155]
	s_mov_b32 m0, s4
	ds_read_b128 v[176:179], v191 offset:16384
	ds_read_b128 v[180:183], v191 offset:17408
	ds_read_b128 v[192:195], v191 offset:18432
	ds_read_b128 v[196:199], v191 offset:19456
	ds_read_b128 v[202:205], v191 offset:20480
	ds_read_b128 v[206:209], v191 offset:21504
	ds_read_b128 v[210:213], v191 offset:22528
	ds_read_b128 v[214:217], v191 offset:23552
	s_mov_b64 exec, s[98:99]
	global_load_lds_dwordx4 v[184:185], off
	s_mov_b64 exec, -1
	s_add_i32 m0, s4, 0x2000
	s_add_u32 s72, s54, 0x40000
	v_lshl_add_u64 v[218:219], s[54:55], 0, v[158:159]
	s_addc_u32 s73, s55, 0
	s_add_i32 s4, s65, s12
	s_mov_b64 exec, s[98:99]
	global_load_lds_dwordx4 v[218:219], off
	s_mov_b64 exec, -1
	v_lshl_add_u64 v[220:221], s[72:73], 0, v[154:155]
	s_mov_b32 m0, s4
	v_lshl_add_u64 v[222:223], s[56:57], 0, v[156:157]
	s_mov_b64 exec, s[98:99]
	global_load_lds_dwordx4 v[220:221], off
	s_mov_b64 exec, -1
	v_lshl_add_u64 v[220:221], s[72:73], 0, v[158:159]
	s_add_i32 m0, s4, 0x2000
	s_nop 0
	s_mov_b64 exec, s[98:99]
	global_load_lds_dwordx4 v[220:221], off
	s_mov_b64 exec, -1
	v_lshl_add_u64 v[220:221], s[56:57], 0, v[152:153]
	s_mov_b32 m0, s13
	s_nop 0
	s_mov_b64 exec, s[98:99]
	global_load_lds_dwordx4 v[220:221], off
	s_mov_b64 exec, -1
	s_mov_b32 m0, s33
	s_nop 0
	s_mov_b64 exec, s[98:99]
	global_load_lds_dwordx4 v[222:223], off
	s_mov_b64 exec, -1
	s_waitcnt vmcnt(8)
	s_waitcnt lgkmcnt(0)
	s_barrier
; #define PG8_STAGE(bufoff, gbase, voff) do { _Pragma("unroll") for (int _i = 0; _i < 2; ++_i) \
;         __builtin_amdgcn_global_load_lds((const unsigned*)((const char*)(gbase) + (voff)[_i]), (PG8_LAS unsigned*)(lds + (bufoff) + ldsw + _i * 8192), 16, 0, 0); } while (0)
; #define PG8_LDA(dst, b, h) do { _Pragma("unroll") for (int m = 0; m < 4; ++m) _Pragma("unroll") for (int k = 0; k < 2; ++k) dst[m][k] = *(const PG8_LAS bf16x8*)(lds + PG8_SA(b, h) + aoff + m * 2048 + k * 1024); } while (0)
; #define PG8_LDB(dst, b, h) do { _Pragma("unroll") for (int n = 0; n < 2; ++n) _Pragma("unroll") for (int k = 0; k < 2; ++k) dst[n][k] = *(const PG8_LAS bf16x8*)(lds + PG8_SB(b, h) + boff + n * 2048 + k * 1024); } while (0)
; #define PG8_MMA(ai, bj, At, Bt) do { __builtin_amdgcn_s_setprio(1); _Pragma("unroll") for (int m = 0; m < 4; ++m) _Pragma("unroll") for (int n = 0; n < 2; ++n) _Pragma("unroll") for (int k = 0; k < 2; ++k) \
;         acc[ai][bj][m][n] = __builtin_amdgcn_mfma_f32_16x16x32_bf16(Bt[n][k], At[m][k], acc[ai][bj][m][n], 0, 0, 0); __builtin_amdgcn_s_setprio(0); } while (0)
; #define PG8_WAIT_V(n) asm volatile("s_waitcnt vmcnt(" #n ")" ::: "memory")
; #define PG8_WAIT_L(n) asm volatile("s_waitcnt lgkmcnt(" #n ")" ::: "memory")
; #define PG8_BAR __builtin_amdgcn_s_barrier()
; #define PG8_SCHED __builtin_amdgcn_sched_barrier(0)
; template <class Epi, class Sched, bool ALIGN_EPI = false, bool SP2 = false>
; __device__ __forceinline__ void gemm_phase(PG8_LAS unsigned char* lds, const Gemm g, const Sched& S, const Epi& E, int tid_in) {
;     ...
;             PG8_WAIT_V(8); PG8_WAIT_L(0); PG8_BAR; PG8_MMA(1, 0, At, B0); PG8_MMA(1, 1, At, B1); PG8_BAR; PG8_SCHED;
;             PG8_LDB(B0, 1, 0); PG8_LDB(B1, 1, 1); PG8_SCHED; PG8_LDA(At, 1, 0); PG8_STAGE(PG8_SA(0, 1), a2 + hstep, voffA);
;             PG8_WAIT_V(8); PG8_WAIT_L(0); PG8_BAR; PG8_MMA(0, 0, At, B0); PG8_MMA(0, 1, At, B1); PG8_BAR; PG8_SCHED;
	s_setprio 1
	s_waitcnt lgkmcnt(0)
	v_mfma_f32_16x16x32_bf16 v[60:63], v[120:123], v[176:179], v[60:63]
	v_mfma_f32_16x16x32_bf16 v[56:59], v[136:139], v[176:179], v[56:59]
	v_mfma_f32_16x16x32_bf16 v[44:47], v[120:123], v[192:195], v[44:47]
	v_mfma_f32_16x16x32_bf16 v[40:43], v[136:139], v[192:195], v[40:43]
	v_mfma_f32_16x16x32_bf16 v[28:31], v[120:123], v[202:205], v[28:31]
	v_mfma_f32_16x16x32_bf16 v[24:27], v[136:139], v[202:205], v[24:27]
	v_mfma_f32_16x16x32_bf16 v[12:15], v[120:123], v[210:213], v[12:15]
	v_mfma_f32_16x16x32_bf16 v[8:11], v[136:139], v[210:213], v[8:11]
	v_mfma_f32_16x16x32_bf16 v[60:63], v[132:135], v[180:183], v[60:63]
	v_mfma_f32_16x16x32_bf16 v[56:59], v[140:143], v[180:183], v[56:59]
	v_mfma_f32_16x16x32_bf16 v[44:47], v[132:135], v[196:199], v[44:47]
	v_mfma_f32_16x16x32_bf16 v[40:43], v[140:143], v[196:199], v[40:43]
	v_mfma_f32_16x16x32_bf16 v[28:31], v[132:135], v[206:209], v[28:31]
	v_mfma_f32_16x16x32_bf16 v[24:27], v[140:143], v[206:209], v[24:27]
	v_mfma_f32_16x16x32_bf16 v[12:15], v[132:135], v[214:217], v[12:15]
	v_mfma_f32_16x16x32_bf16 v[8:11], v[140:143], v[214:217], v[8:11]
	s_setprio 0
	s_setprio 1
	v_mfma_f32_16x16x32_bf16 v[52:55], v[144:147], v[176:179], v[52:55]
	v_mfma_f32_16x16x32_bf16 v[48:51], v[168:171], v[176:179], v[48:51]
	v_mfma_f32_16x16x32_bf16 v[36:39], v[144:147], v[192:195], v[36:39]
	v_mfma_f32_16x16x32_bf16 v[32:35], v[168:171], v[192:195], v[32:35]
	v_mfma_f32_16x16x32_bf16 v[20:23], v[144:147], v[202:205], v[20:23]
	v_mfma_f32_16x16x32_bf16 v[16:19], v[168:171], v[202:205], v[16:19]
	v_mfma_f32_16x16x32_bf16 v[4:7], v[144:147], v[210:213], v[4:7]
	v_mfma_f32_16x16x32_bf16 v[0:3], v[168:171], v[210:213], v[0:3]
	v_mfma_f32_16x16x32_bf16 v[52:55], v[148:151], v[180:183], v[52:55]
	v_mfma_f32_16x16x32_bf16 v[48:51], v[172:175], v[180:183], v[48:51]
	v_mfma_f32_16x16x32_bf16 v[36:39], v[148:151], v[196:199], v[36:39]
	v_mfma_f32_16x16x32_bf16 v[32:35], v[172:175], v[196:199], v[32:35]
	v_mfma_f32_16x16x32_bf16 v[20:23], v[148:151], v[206:209], v[20:23]
	v_mfma_f32_16x16x32_bf16 v[16:19], v[172:175], v[206:209], v[16:19]
	v_mfma_f32_16x16x32_bf16 v[4:7], v[148:151], v[214:217], v[4:7]
	v_mfma_f32_16x16x32_bf16 v[0:3], v[172:175], v[214:217], v[0:3]
	s_setprio 0
	s_barrier
	s_add_i32 s4, 0, 0x18000
	s_add_i32 s5, 0, 0x1c000
	v_add_u32_e32 v140, s4, v187
	v_add_u32_e32 v172, s5, v187
	ds_read_b128 v[120:123], v140
	ds_read_b128 v[132:135], v140 offset:1024
	ds_read_b128 v[136:139], v140 offset:2048
	ds_read_b128 v[140:143], v140 offset:3072
	ds_read_b128 v[144:147], v172
	ds_read_b128 v[148:151], v172 offset:1024
	ds_read_b128 v[168:171], v172 offset:2048
	ds_read_b128 v[172:175], v172 offset:3072
	s_add_u32 s56, s56, 0x40000
	s_addc_u32 s57, s57, 0
	s_mov_b32 m0, s40
	v_lshl_add_u64 v[224:225], s[56:57], 0, v[152:153]
	ds_read_b128 v[176:179], v191 offset:32768
	ds_read_b128 v[180:183], v191 offset:33792
	ds_read_b128 v[192:195], v191 offset:34816
	ds_read_b128 v[196:199], v191 offset:35840
	ds_read_b128 v[202:205], v191 offset:36864
	ds_read_b128 v[206:209], v191 offset:37888
	ds_read_b128 v[210:213], v191 offset:38912
	ds_read_b128 v[214:217], v191 offset:39936
	s_mov_b64 exec, s[98:99]
	global_load_lds_dwordx4 v[224:225], off
	s_mov_b64 exec, -1
	v_lshl_add_u64 v[224:225], s[56:57], 0, v[156:157]
	s_mov_b32 m0, s41
	s_nop 0
	s_mov_b64 exec, s[98:99]
	global_load_lds_dwordx4 v[224:225], off
	s_mov_b64 exec, -1
	s_waitcnt vmcnt(8)
	s_waitcnt lgkmcnt(0)
	s_barrier
	s_setprio 1
	s_waitcnt lgkmcnt(0)
	v_mfma_f32_16x16x32_bf16 v[128:131], v[120:123], v[176:179], v[128:131]
	v_mfma_f32_16x16x32_bf16 v[124:127], v[136:139], v[176:179], v[124:127]
	v_mfma_f32_16x16x32_bf16 v[108:111], v[120:123], v[192:195], v[108:111]
	v_mfma_f32_16x16x32_bf16 v[104:107], v[136:139], v[192:195], v[104:107]
	v_mfma_f32_16x16x32_bf16 v[92:95], v[120:123], v[202:205], v[92:95]
	v_mfma_f32_16x16x32_bf16 v[88:91], v[136:139], v[202:205], v[88:91]
	v_mfma_f32_16x16x32_bf16 v[76:79], v[120:123], v[210:213], v[76:79]
	v_mfma_f32_16x16x32_bf16 v[72:75], v[136:139], v[210:213], v[72:75]
	v_mfma_f32_16x16x32_bf16 v[128:131], v[132:135], v[180:183], v[128:131]
	v_mfma_f32_16x16x32_bf16 v[124:127], v[140:143], v[180:183], v[124:127]
	v_mfma_f32_16x16x32_bf16 v[108:111], v[132:135], v[196:199], v[108:111]
	v_mfma_f32_16x16x32_bf16 v[104:107], v[140:143], v[196:199], v[104:107]
	v_mfma_f32_16x16x32_bf16 v[92:95], v[132:135], v[206:209], v[92:95]
	v_mfma_f32_16x16x32_bf16 v[88:91], v[140:143], v[206:209], v[88:91]
	v_mfma_f32_16x16x32_bf16 v[76:79], v[132:135], v[214:217], v[76:79]
	v_mfma_f32_16x16x32_bf16 v[72:75], v[140:143], v[214:217], v[72:75]
	s_setprio 0
	s_setprio 1
	v_mfma_f32_16x16x32_bf16 v[116:119], v[144:147], v[176:179], v[116:119]
	v_mfma_f32_16x16x32_bf16 v[112:115], v[168:171], v[176:179], v[112:115]
	v_mfma_f32_16x16x32_bf16 v[100:103], v[144:147], v[192:195], v[100:103]
	v_mfma_f32_16x16x32_bf16 v[96:99], v[168:171], v[192:195], v[96:99]
	v_mfma_f32_16x16x32_bf16 v[84:87], v[144:147], v[202:205], v[84:87]
	v_mfma_f32_16x16x32_bf16 v[80:83], v[168:171], v[202:205], v[80:83]
	v_mfma_f32_16x16x32_bf16 v[68:71], v[144:147], v[210:213], v[68:71]
	v_mfma_f32_16x16x32_bf16 v[64:67], v[168:171], v[210:213], v[64:67]
	v_mfma_f32_16x16x32_bf16 v[116:119], v[148:151], v[180:183], v[116:119]
	v_mfma_f32_16x16x32_bf16 v[112:115], v[172:175], v[180:183], v[112:115]
	v_mfma_f32_16x16x32_bf16 v[100:103], v[148:151], v[196:199], v[100:103]
	v_mfma_f32_16x16x32_bf16 v[96:99], v[172:175], v[196:199], v[96:99]
	v_mfma_f32_16x16x32_bf16 v[84:87], v[148:151], v[206:209], v[84:87]
	v_mfma_f32_16x16x32_bf16 v[80:83], v[172:175], v[206:209], v[80:83]
	v_mfma_f32_16x16x32_bf16 v[68:71], v[148:151], v[214:217], v[68:71]
	v_mfma_f32_16x16x32_bf16 v[64:67], v[172:175], v[214:217], v[64:67]
	s_setprio 0
	s_barrier
; #define PG8_STAGE(bufoff, gbase, voff) do { _Pragma("unroll") for (int _i = 0; _i < 2; ++_i) \
;         __builtin_amdgcn_global_load_lds((const unsigned*)((const char*)(gbase) + (voff)[_i]), (PG8_LAS unsigned*)(lds + (bufoff) + ldsw + _i * 8192), 16, 0, 0); } while (0)
; #define PG8_LDA(dst, b, h) do { _Pragma("unroll") for (int m = 0; m < 4; ++m) _Pragma("unroll") for (int k = 0; k < 2; ++k) dst[m][k] = *(const PG8_LAS bf16x8*)(lds + PG8_SA(b, h) + aoff + m * 2048 + k * 1024); } while (0)
; #define PG8_MMA(ai, bj, At, Bt) do { __builtin_amdgcn_s_setprio(1); _Pragma("unroll") for (int m = 0; m < 4; ++m) _Pragma("unroll") for (int n = 0; n < 2; ++n) _Pragma("unroll") for (int k = 0; k < 2; ++k) \
;         acc[ai][bj][m][n] = __builtin_amdgcn_mfma_f32_16x16x32_bf16(Bt[n][k], At[m][k], acc[ai][bj][m][n], 0, 0, 0); __builtin_amdgcn_s_setprio(0); } while (0)
; #define PG8_WAIT_V(n) asm volatile("s_waitcnt vmcnt(" #n ")" ::: "memory")
; #define PG8_WAIT_L(n) asm volatile("s_waitcnt lgkmcnt(" #n ")" ::: "memory")
; #define PG8_BAR __builtin_amdgcn_s_barrier()
; #define PG8_SCHED __builtin_amdgcn_sched_barrier(0)
; template <class Epi, class Sched, bool ALIGN_EPI = false, bool SP2 = false>
; __device__ __forceinline__ void gemm_phase(PG8_LAS unsigned char* lds, const Gemm g, const Sched& S, const Epi& E, int tid_in) {
;     ...
;             PG8_LDA(At, 1, 1); PG8_STAGE(PG8_SB(1, 0), b3, voffB); PG8_STAGE(PG8_SB(1, 1), b3 + hstep, voffB); PG8_STAGE(PG8_SA(1, 0), a3, voffA);
;             PG8_WAIT_V(8); PG8_WAIT_L(0); PG8_BAR; PG8_MMA(1, 0, At, B0); PG8_MMA(1, 1, At, B1); PG8_BAR; PG8_SCHED;
	s_add_i32 s4, s4, s12
	v_lshl_add_u64 v[184:185], v[184:185], 0, s[24:25]
	s_mov_b32 m0, s4
	ds_read_b128 v[176:179], v191 offset:49152
	ds_read_b128 v[180:183], v191 offset:50176
	ds_read_b128 v[192:195], v191 offset:51200
	ds_read_b128 v[196:199], v191 offset:52224
	ds_read_b128 v[202:205], v191 offset:53248
	ds_read_b128 v[206:209], v191 offset:54272
	ds_read_b128 v[210:213], v191 offset:55296
	ds_read_b128 v[214:217], v191 offset:56320
	s_mov_b64 exec, s[98:99]
	global_load_lds_dwordx4 v[184:185], off
	s_mov_b64 exec, -1
	s_add_i32 m0, s4, 0x2000
	s_add_u32 s54, s54, 0x40080
	v_lshl_add_u64 v[184:185], v[218:219], 0, s[24:25]
	s_addc_u32 s55, s55, 0
	s_add_i32 s4, s5, s12
	s_mov_b64 exec, s[98:99]
	global_load_lds_dwordx4 v[184:185], off
	s_mov_b64 exec, -1
	v_lshl_add_u64 v[184:185], s[54:55], 0, v[154:155]
	s_mov_b32 m0, s4
	s_nop 0
	s_mov_b64 exec, s[98:99]
	global_load_lds_dwordx4 v[184:185], off
	s_mov_b64 exec, -1
	v_lshl_add_u64 v[184:185], s[54:55], 0, v[158:159]
	s_add_i32 m0, s4, 0x2000
	s_nop 0
	s_mov_b64 exec, s[98:99]
	global_load_lds_dwordx4 v[184:185], off
	s_mov_b64 exec, -1
	v_lshl_add_u64 v[184:185], v[220:221], 0, s[24:25]
	s_mov_b32 m0, s59
	s_nop 0
	s_mov_b64 exec, s[98:99]
	global_load_lds_dwordx4 v[184:185], off
	s_mov_b64 exec, -1
	v_lshl_add_u64 v[184:185], v[222:223], 0, s[24:25]
	s_mov_b32 m0, s60
	s_nop 0
	s_mov_b64 exec, s[98:99]
	global_load_lds_dwordx4 v[184:185], off
	s_mov_b64 exec, -1
	s_waitcnt vmcnt(8)
	s_waitcnt lgkmcnt(0)
	s_barrier
	s_setprio 1
	s_waitcnt lgkmcnt(0)
	v_mfma_f32_16x16x32_bf16 v[60:63], v[120:123], v[176:179], v[60:63]
	v_mfma_f32_16x16x32_bf16 v[56:59], v[136:139], v[176:179], v[56:59]
	v_mfma_f32_16x16x32_bf16 v[44:47], v[120:123], v[192:195], v[44:47]
	v_mfma_f32_16x16x32_bf16 v[40:43], v[136:139], v[192:195], v[40:43]
	v_mfma_f32_16x16x32_bf16 v[28:31], v[120:123], v[202:205], v[28:31]
	v_mfma_f32_16x16x32_bf16 v[24:27], v[136:139], v[202:205], v[24:27]
	v_mfma_f32_16x16x32_bf16 v[12:15], v[120:123], v[210:213], v[12:15]
	v_mfma_f32_16x16x32_bf16 v[8:11], v[136:139], v[210:213], v[8:11]
	v_mfma_f32_16x16x32_bf16 v[60:63], v[132:135], v[180:183], v[60:63]
	v_mfma_f32_16x16x32_bf16 v[56:59], v[140:143], v[180:183], v[56:59]
	v_mfma_f32_16x16x32_bf16 v[44:47], v[132:135], v[196:199], v[44:47]
	v_mfma_f32_16x16x32_bf16 v[40:43], v[140:143], v[196:199], v[40:43]
	v_mfma_f32_16x16x32_bf16 v[28:31], v[132:135], v[206:209], v[28:31]
	v_mfma_f32_16x16x32_bf16 v[24:27], v[140:143], v[206:209], v[24:27]
	v_mfma_f32_16x16x32_bf16 v[12:15], v[132:135], v[214:217], v[12:15]
	v_mfma_f32_16x16x32_bf16 v[8:11], v[140:143], v[214:217], v[8:11]
	s_setprio 0
	s_setprio 1
	v_mfma_f32_16x16x32_bf16 v[52:55], v[144:147], v[176:179], v[52:55]
	v_mfma_f32_16x16x32_bf16 v[48:51], v[168:171], v[176:179], v[48:51]
	v_mfma_f32_16x16x32_bf16 v[36:39], v[144:147], v[192:195], v[36:39]
	v_mfma_f32_16x16x32_bf16 v[32:35], v[168:171], v[192:195], v[32:35]
	v_mfma_f32_16x16x32_bf16 v[20:23], v[144:147], v[202:205], v[20:23]
	v_mfma_f32_16x16x32_bf16 v[16:19], v[168:171], v[202:205], v[16:19]
	v_mfma_f32_16x16x32_bf16 v[4:7], v[144:147], v[210:213], v[4:7]
	v_mfma_f32_16x16x32_bf16 v[0:3], v[168:171], v[210:213], v[0:3]
	v_mfma_f32_16x16x32_bf16 v[52:55], v[148:151], v[180:183], v[52:55]
	v_mfma_f32_16x16x32_bf16 v[48:51], v[172:175], v[180:183], v[48:51]
	v_mfma_f32_16x16x32_bf16 v[36:39], v[148:151], v[196:199], v[36:39]
	v_mfma_f32_16x16x32_bf16 v[32:35], v[172:175], v[196:199], v[32:35]
	v_mfma_f32_16x16x32_bf16 v[20:23], v[148:151], v[206:209], v[20:23]
	v_mfma_f32_16x16x32_bf16 v[16:19], v[172:175], v[206:209], v[16:19]
	v_mfma_f32_16x16x32_bf16 v[4:7], v[148:151], v[214:217], v[4:7]
	v_mfma_f32_16x16x32_bf16 v[0:3], v[172:175], v[214:217], v[0:3]
	s_setprio 0
	s_barrier
	s_add_i32 s70, s70, 2
	s_add_u32 s68, s68, 0x100
	s_addc_u32 s69, s69, 0
	s_add_u32 s52, s52, 0x100
	s_addc_u32 s53, s53, 0
	s_cmp_gt_u32 s70, 13
	s_branch .Lpost10

; #define PG8_STAGE(bufoff, gbase, voff) do { _Pragma("unroll") for (int _i = 0; _i < 2; ++_i) \
;         __builtin_amdgcn_global_load_lds((const unsigned*)((const char*)(gbase) + (voff)[_i]), (PG8_LAS unsigned*)(lds + (bufoff) + ldsw + _i * 8192), 16, 0, 0); } while (0)
; #define PG8_LDA(dst, b, h) do { _Pragma("unroll") for (int m = 0; m < 4; ++m) _Pragma("unroll") for (int k = 0; k < 2; ++k) dst[m][k] = *(const PG8_LAS bf16x8*)(lds + PG8_SA(b, h) + aoff + m * 2048 + k * 1024); } while (0)
; #define PG8_LDB(dst, b, h) do { _Pragma("unroll") for (int n = 0; n < 2; ++n) _Pragma("unroll") for (int k = 0; k < 2; ++k) dst[n][k] = *(const PG8_LAS bf16x8*)(lds + PG8_SB(b, h) + boff + n * 2048 + k * 1024); } while (0)
; #define PG8_MMA(ai, bj, At, Bt) do { __builtin_amdgcn_s_setprio(1); _Pragma("unroll") for (int m = 0; m < 4; ++m) _Pragma("unroll") for (int n = 0; n < 2; ++n) _Pragma("unroll") for (int k = 0; k < 2; ++k) \
;         acc[ai][bj][m][n] = __builtin_amdgcn_mfma_f32_16x16x32_bf16(Bt[n][k], At[m][k], acc[ai][bj][m][n], 0, 0, 0); __builtin_amdgcn_s_setprio(0); } while (0)
; #define PG8_WAIT_V(n) asm volatile("s_waitcnt vmcnt(" #n ")" ::: "memory")
; #define PG8_BAR __builtin_amdgcn_s_barrier()
; template <class Epi, class Sched, bool ALIGN_EPI = false, bool SP2 = false>
; __device__ __forceinline__ void gemm_phase(PG8_LAS unsigned char* lds, const Gemm g, const Sched& S, const Epi& E, int tid_in) {
;     ...
;         for (int t = 0; t < nt; t += 2) {
;             const bool last = (t == nt - 2);
;             const char* a1 = cA + (size_t)(t + 1) * kstep;
;             const char* a2 = last ? nA : cA + (size_t)(t + 2) * kstep; const char* b2 = last ? nB : cB + (size_t)(t + 2) * kstep;
;             const char* a3 = a2 + kstep; const char* b3 = b2 + kstep;
;             if (last && has_next) S.a_ready(nxt);
;             if constexpr (SP2) {
;             PG8_LDB(B0, 0, 0); PG8_LDB(B1, 0, 1); PG8_SCHED; PG8_LDA(At, 0, 0); PG8_STAGE(PG8_SA(1, 1), a1 + hstep, voffA);
;             PG8_WAIT_V(8); PG8_WAIT_L(0); PG8_BAR; PG8_MMA(0, 0, At, B0); PG8_MMA(0, 1, At, B1); PG8_BAR; PG8_SCHED;
;             PG8_LDA(At, 0, 1); PG8_STAGE(PG8_SB(0, 0), b2, voffB); PG8_STAGE(PG8_SB(0, 1), b2 + hstep, voffB); PG8_STAGE(PG8_SA(0, 0), a2, voffA);
;             PG8_WAIT_V(8); PG8_WAIT_L(0); PG8_BAR; PG8_MMA(1, 0, At, B0); PG8_MMA(1, 1, At, B1); PG8_BAR; PG8_SCHED;
.LBB0_1588:
	ds_read_b128 v[146:149], v165
	ds_read_b128 v[176:179], v165 offset:1024
	ds_read_b128 v[180:183], v165 offset:2048
	ds_read_b128 v[184:187], v165 offset:3072
	ds_read_b128 v[188:191], v169
	ds_read_b128 v[192:195], v169 offset:1024
	ds_read_b128 v[196:199], v169 offset:2048
	ds_read_b128 v[202:205], v169 offset:3072
	s_add_u32 s4, s46, 0xfffc0080
	s_addc_u32 s5, s47, -1
	s_cmp_eq_u32 s66, 12
	s_cselect_b32 s51, s25, s5
	s_cselect_b32 s50, s62, s4
	s_cselect_b32 s49, s23, s65
	s_cselect_b32 s48, s63, s64
	s_cbranch_scc1 .Lpk11
	v_lshl_add_u64 v[150:151], s[46:47], 0, v[140:141]
	s_add_i32 m0, s40, 0xc000
	ds_read_b128 v[206:209], v173
	ds_read_b128 v[210:213], v173 offset:1024
	ds_read_b128 v[214:217], v173 offset:2048
	ds_read_b128 v[218:221], v173 offset:3072
	ds_read_b128 v[222:225], v173 offset:4096
	ds_read_b128 v[226:229], v173 offset:5120
	ds_read_b128 v[230:233], v173 offset:6144
	ds_read_b128 v[234:237], v173 offset:7168
	global_load_lds_dwordx4 v[150:151], off
	v_lshl_add_u64 v[150:151], s[46:47], 0, v[138:139]
	s_add_i32 m0, s40, 0xe000
	s_nop 0
	global_load_lds_dwordx4 v[150:151], off
	s_waitcnt vmcnt(8)
	s_waitcnt lgkmcnt(0)
	s_barrier
	s_setprio 1
	s_waitcnt lgkmcnt(0)
	v_mfma_f32_16x16x32_bf16 v[124:127], v[146:149], v[206:209], v[124:127]
	v_mfma_f32_16x16x32_bf16 v[120:123], v[180:183], v[206:209], v[120:123]
	v_mfma_f32_16x16x32_bf16 v[108:111], v[146:149], v[214:217], v[108:111]
	v_mfma_f32_16x16x32_bf16 v[104:107], v[180:183], v[214:217], v[104:107]
	v_mfma_f32_16x16x32_bf16 v[92:95], v[146:149], v[222:225], v[92:95]
	v_mfma_f32_16x16x32_bf16 v[88:91], v[180:183], v[222:225], v[88:91]
	v_mfma_f32_16x16x32_bf16 v[76:79], v[146:149], v[230:233], v[76:79]
	v_mfma_f32_16x16x32_bf16 v[72:75], v[180:183], v[230:233], v[72:75]
	v_mfma_f32_16x16x32_bf16 v[124:127], v[176:179], v[210:213], v[124:127]
	v_mfma_f32_16x16x32_bf16 v[120:123], v[184:187], v[210:213], v[120:123]
	v_mfma_f32_16x16x32_bf16 v[108:111], v[176:179], v[218:221], v[108:111]
	v_mfma_f32_16x16x32_bf16 v[104:107], v[184:187], v[218:221], v[104:107]
	v_mfma_f32_16x16x32_bf16 v[92:95], v[176:179], v[226:229], v[92:95]
	v_mfma_f32_16x16x32_bf16 v[88:91], v[184:187], v[226:229], v[88:91]
	v_mfma_f32_16x16x32_bf16 v[76:79], v[176:179], v[234:237], v[76:79]
	v_mfma_f32_16x16x32_bf16 v[72:75], v[184:187], v[234:237], v[72:75]
	s_setprio 0
	s_setprio 1
	v_mfma_f32_16x16x32_bf16 v[116:119], v[188:191], v[206:209], v[116:119]
	v_mfma_f32_16x16x32_bf16 v[112:115], v[196:199], v[206:209], v[112:115]
	v_mfma_f32_16x16x32_bf16 v[100:103], v[188:191], v[214:217], v[100:103]
	v_mfma_f32_16x16x32_bf16 v[96:99], v[196:199], v[214:217], v[96:99]
	v_mfma_f32_16x16x32_bf16 v[84:87], v[188:191], v[222:225], v[84:87]
	v_mfma_f32_16x16x32_bf16 v[80:83], v[196:199], v[222:225], v[80:83]
	v_mfma_f32_16x16x32_bf16 v[68:71], v[188:191], v[230:233], v[68:71]
	v_mfma_f32_16x16x32_bf16 v[64:67], v[196:199], v[230:233], v[64:67]
	v_mfma_f32_16x16x32_bf16 v[116:119], v[192:195], v[210:213], v[116:119]
	v_mfma_f32_16x16x32_bf16 v[112:115], v[202:205], v[210:213], v[112:115]
	v_mfma_f32_16x16x32_bf16 v[100:103], v[192:195], v[218:221], v[100:103]
	v_mfma_f32_16x16x32_bf16 v[96:99], v[202:205], v[218:221], v[96:99]
	v_mfma_f32_16x16x32_bf16 v[84:87], v[192:195], v[226:229], v[84:87]
	v_mfma_f32_16x16x32_bf16 v[80:83], v[202:205], v[226:229], v[80:83]
	v_mfma_f32_16x16x32_bf16 v[68:71], v[192:195], v[234:237], v[68:71]
	v_mfma_f32_16x16x32_bf16 v[64:67], v[202:205], v[234:237], v[64:67]
	s_setprio 0
	s_barrier
	s_add_i32 s4, s58, s12
	v_lshl_add_u64 v[150:151], s[48:49], 0, v[132:133]
	s_mov_b32 m0, s4
	ds_read_b128 v[206:209], v173 offset:16384
	ds_read_b128 v[210:213], v173 offset:17408
	ds_read_b128 v[214:217], v173 offset:18432
	ds_read_b128 v[218:221], v173 offset:19456
	ds_read_b128 v[222:225], v173 offset:20480
	ds_read_b128 v[226:229], v173 offset:21504
	ds_read_b128 v[230:233], v173 offset:22528
	ds_read_b128 v[234:237], v173 offset:23552
	global_load_lds_dwordx4 v[150:151], off
	s_add_i32 m0, s4, 0x2000
	s_add_u32 s68, s48, 0x40000
	v_lshl_add_u64 v[154:155], s[48:49], 0, v[128:129]
	s_addc_u32 s69, s49, 0
	s_add_i32 s4, s59, s12
	global_load_lds_dwordx4 v[154:155], off
	v_lshl_add_u64 v[158:159], s[68:69], 0, v[132:133]
	s_mov_b32 m0, s4
	v_lshl_add_u64 v[162:163], s[50:51], 0, v[130:131]
	global_load_lds_dwordx4 v[158:159], off
	v_lshl_add_u64 v[158:159], s[68:69], 0, v[128:129]
	s_add_i32 m0, s4, 0x2000
	s_nop 0
	global_load_lds_dwordx4 v[158:159], off
	v_lshl_add_u64 v[158:159], s[50:51], 0, v[134:135]
	s_mov_b32 m0, s40
	s_nop 0
	global_load_lds_dwordx4 v[158:159], off
	s_mov_b32 m0, s41
	s_nop 0
	global_load_lds_dwordx4 v[162:163], off
	s_waitcnt vmcnt(8)
	s_waitcnt lgkmcnt(0)
	s_barrier
; #define PG8_STAGE(bufoff, gbase, voff) do { _Pragma("unroll") for (int _i = 0; _i < 2; ++_i) \
;         __builtin_amdgcn_global_load_lds((const unsigned*)((const char*)(gbase) + (voff)[_i]), (PG8_LAS unsigned*)(lds + (bufoff) + ldsw + _i * 8192), 16, 0, 0); } while (0)
; #define PG8_LDA(dst, b, h) do { _Pragma("unroll") for (int m = 0; m < 4; ++m) _Pragma("unroll") for (int k = 0; k < 2; ++k) dst[m][k] = *(const PG8_LAS bf16x8*)(lds + PG8_SA(b, h) + aoff + m * 2048 + k * 1024); } while (0)
; #define PG8_LDB(dst, b, h) do { _Pragma("unroll") for (int n = 0; n < 2; ++n) _Pragma("unroll") for (int k = 0; k < 2; ++k) dst[n][k] = *(const PG8_LAS bf16x8*)(lds + PG8_SB(b, h) + boff + n * 2048 + k * 1024); } while (0)
; #define PG8_MMA(ai, bj, At, Bt) do { __builtin_amdgcn_s_setprio(1); _Pragma("unroll") for (int m = 0; m < 4; ++m) _Pragma("unroll") for (int n = 0; n < 2; ++n) _Pragma("unroll") for (int k = 0; k < 2; ++k) \
;         acc[ai][bj][m][n] = __builtin_amdgcn_mfma_f32_16x16x32_bf16(Bt[n][k], At[m][k], acc[ai][bj][m][n], 0, 0, 0); __builtin_amdgcn_s_setprio(0); } while (0)
; #define PG8_WAIT_V(n) asm volatile("s_waitcnt vmcnt(" #n ")" ::: "memory")
; #define PG8_WAIT_L(n) asm volatile("s_waitcnt lgkmcnt(" #n ")" ::: "memory")
; #define PG8_BAR __builtin_amdgcn_s_barrier()
; #define PG8_SCHED __builtin_amdgcn_sched_barrier(0)
; template <class Epi, class Sched, bool ALIGN_EPI = false, bool SP2 = false>
; __device__ __forceinline__ void gemm_phase(PG8_LAS unsigned char* lds, const Gemm g, const Sched& S, const Epi& E, int tid_in) {
;     ...
;             PG8_WAIT_V(8); PG8_WAIT_L(0); PG8_BAR; PG8_MMA(1, 0, At, B0); PG8_MMA(1, 1, At, B1); PG8_BAR; PG8_SCHED;
;             PG8_LDB(B0, 1, 0); PG8_LDB(B1, 1, 1); PG8_SCHED; PG8_LDA(At, 1, 0); PG8_STAGE(PG8_SA(0, 1), a2 + hstep, voffA);
;             PG8_WAIT_V(8); PG8_WAIT_L(0); PG8_BAR; PG8_MMA(0, 0, At, B0); PG8_MMA(0, 1, At, B1); PG8_BAR; PG8_SCHED;
;             PG8_LDA(At, 1, 1); PG8_STAGE(PG8_SB(1, 0), b3, voffB); PG8_STAGE(PG8_SB(1, 1), b3 + hstep, voffB); PG8_STAGE(PG8_SA(1, 0), a3, voffA);
	s_setprio 1
	s_waitcnt lgkmcnt(0)
	v_mfma_f32_16x16x32_bf16 v[60:63], v[146:149], v[206:209], v[60:63]
	v_mfma_f32_16x16x32_bf16 v[56:59], v[180:183], v[206:209], v[56:59]
	v_mfma_f32_16x16x32_bf16 v[44:47], v[146:149], v[214:217], v[44:47]
	v_mfma_f32_16x16x32_bf16 v[40:43], v[180:183], v[214:217], v[40:43]
	v_mfma_f32_16x16x32_bf16 v[28:31], v[146:149], v[222:225], v[28:31]
	v_mfma_f32_16x16x32_bf16 v[24:27], v[180:183], v[222:225], v[24:27]
	v_mfma_f32_16x16x32_bf16 v[12:15], v[146:149], v[230:233], v[12:15]
	v_mfma_f32_16x16x32_bf16 v[8:11], v[180:183], v[230:233], v[8:11]
	v_mfma_f32_16x16x32_bf16 v[60:63], v[176:179], v[210:213], v[60:63]
	v_mfma_f32_16x16x32_bf16 v[56:59], v[184:187], v[210:213], v[56:59]
	v_mfma_f32_16x16x32_bf16 v[44:47], v[176:179], v[218:221], v[44:47]
	v_mfma_f32_16x16x32_bf16 v[40:43], v[184:187], v[218:221], v[40:43]
	v_mfma_f32_16x16x32_bf16 v[28:31], v[176:179], v[226:229], v[28:31]
	v_mfma_f32_16x16x32_bf16 v[24:27], v[184:187], v[226:229], v[24:27]
	v_mfma_f32_16x16x32_bf16 v[12:15], v[176:179], v[234:237], v[12:15]
	v_mfma_f32_16x16x32_bf16 v[8:11], v[184:187], v[234:237], v[8:11]
	s_setprio 0
	s_setprio 1
	v_mfma_f32_16x16x32_bf16 v[52:55], v[188:191], v[206:209], v[52:55]
	v_mfma_f32_16x16x32_bf16 v[48:51], v[196:199], v[206:209], v[48:51]
	v_mfma_f32_16x16x32_bf16 v[36:39], v[188:191], v[214:217], v[36:39]
	v_mfma_f32_16x16x32_bf16 v[32:35], v[196:199], v[214:217], v[32:35]
	v_mfma_f32_16x16x32_bf16 v[20:23], v[188:191], v[222:225], v[20:23]
	v_mfma_f32_16x16x32_bf16 v[16:19], v[196:199], v[222:225], v[16:19]
	v_mfma_f32_16x16x32_bf16 v[4:7], v[188:191], v[230:233], v[4:7]
	v_mfma_f32_16x16x32_bf16 v[0:3], v[196:199], v[230:233], v[0:3]
	v_mfma_f32_16x16x32_bf16 v[52:55], v[192:195], v[210:213], v[52:55]
	v_mfma_f32_16x16x32_bf16 v[48:51], v[202:205], v[210:213], v[48:51]
	v_mfma_f32_16x16x32_bf16 v[36:39], v[192:195], v[218:221], v[36:39]
	v_mfma_f32_16x16x32_bf16 v[32:35], v[202:205], v[218:221], v[32:35]
	v_mfma_f32_16x16x32_bf16 v[20:23], v[192:195], v[226:229], v[20:23]
	v_mfma_f32_16x16x32_bf16 v[16:19], v[202:205], v[226:229], v[16:19]
	v_mfma_f32_16x16x32_bf16 v[4:7], v[192:195], v[234:237], v[4:7]
	v_mfma_f32_16x16x32_bf16 v[0:3], v[202:205], v[234:237], v[0:3]
	s_setprio 0
	s_barrier
	s_add_i32 s4, 0, 0x18000
	v_add_u32_e32 v152, s4, v157
	s_add_i32 s5, 0, 0x1c000
	ds_read_b128 v[146:149], v152
	ds_read_b128 v[176:179], v152 offset:1024
	ds_read_b128 v[180:183], v152 offset:2048
	ds_read_b128 v[184:187], v152 offset:3072
	v_add_u32_e32 v152, s5, v157
	ds_read_b128 v[188:191], v152
	ds_read_b128 v[192:195], v152 offset:1024
	ds_read_b128 v[196:199], v152 offset:2048
	ds_read_b128 v[202:205], v152 offset:3072
	s_add_u32 s50, s50, 0x40000
	s_addc_u32 s51, s51, 0
	s_mov_b32 m0, s45
	v_lshl_add_u64 v[166:167], s[50:51], 0, v[134:135]
	ds_read_b128 v[206:209], v173 offset:32768
	ds_read_b128 v[210:213], v173 offset:33792
	ds_read_b128 v[214:217], v173 offset:34816
	ds_read_b128 v[218:221], v173 offset:35840
	ds_read_b128 v[222:225], v173 offset:36864
	ds_read_b128 v[226:229], v173 offset:37888
	ds_read_b128 v[230:233], v173 offset:38912
	ds_read_b128 v[234:237], v173 offset:39936
	global_load_lds_dwordx4 v[166:167], off
	v_lshl_add_u64 v[166:167], s[50:51], 0, v[130:131]
	s_mov_b32 m0, s52
	s_nop 0
	global_load_lds_dwordx4 v[166:167], off
	s_waitcnt vmcnt(8)
	s_waitcnt lgkmcnt(0)
	s_barrier
	s_setprio 1
	s_waitcnt lgkmcnt(0)
	v_mfma_f32_16x16x32_bf16 v[124:127], v[146:149], v[206:209], v[124:127]
	v_mfma_f32_16x16x32_bf16 v[120:123], v[180:183], v[206:209], v[120:123]
	v_mfma_f32_16x16x32_bf16 v[108:111], v[146:149], v[214:217], v[108:111]
	v_mfma_f32_16x16x32_bf16 v[104:107], v[180:183], v[214:217], v[104:107]
	v_mfma_f32_16x16x32_bf16 v[92:95], v[146:149], v[222:225], v[92:95]
	v_mfma_f32_16x16x32_bf16 v[88:91], v[180:183], v[222:225], v[88:91]
	v_mfma_f32_16x16x32_bf16 v[76:79], v[146:149], v[230:233], v[76:79]
	v_mfma_f32_16x16x32_bf16 v[72:75], v[180:183], v[230:233], v[72:75]
	v_mfma_f32_16x16x32_bf16 v[124:127], v[176:179], v[210:213], v[124:127]
	v_mfma_f32_16x16x32_bf16 v[120:123], v[184:187], v[210:213], v[120:123]
	v_mfma_f32_16x16x32_bf16 v[108:111], v[176:179], v[218:221], v[108:111]
	v_mfma_f32_16x16x32_bf16 v[104:107], v[184:187], v[218:221], v[104:107]
	v_mfma_f32_16x16x32_bf16 v[92:95], v[176:179], v[226:229], v[92:95]
	v_mfma_f32_16x16x32_bf16 v[88:91], v[184:187], v[226:229], v[88:91]
	v_mfma_f32_16x16x32_bf16 v[76:79], v[176:179], v[234:237], v[76:79]
	v_mfma_f32_16x16x32_bf16 v[72:75], v[184:187], v[234:237], v[72:75]
	s_setprio 0
	s_setprio 1
	v_mfma_f32_16x16x32_bf16 v[116:119], v[188:191], v[206:209], v[116:119]
	v_mfma_f32_16x16x32_bf16 v[112:115], v[196:199], v[206:209], v[112:115]
	v_mfma_f32_16x16x32_bf16 v[100:103], v[188:191], v[214:217], v[100:103]
	v_mfma_f32_16x16x32_bf16 v[96:99], v[196:199], v[214:217], v[96:99]
	v_mfma_f32_16x16x32_bf16 v[84:87], v[188:191], v[222:225], v[84:87]
	v_mfma_f32_16x16x32_bf16 v[80:83], v[196:199], v[222:225], v[80:83]
	v_mfma_f32_16x16x32_bf16 v[68:71], v[188:191], v[230:233], v[68:71]
	v_mfma_f32_16x16x32_bf16 v[64:67], v[196:199], v[230:233], v[64:67]
	v_mfma_f32_16x16x32_bf16 v[116:119], v[192:195], v[210:213], v[116:119]
	v_mfma_f32_16x16x32_bf16 v[112:115], v[202:205], v[210:213], v[112:115]
	v_mfma_f32_16x16x32_bf16 v[100:103], v[192:195], v[218:221], v[100:103]
	v_mfma_f32_16x16x32_bf16 v[96:99], v[202:205], v[218:221], v[96:99]
	v_mfma_f32_16x16x32_bf16 v[84:87], v[192:195], v[226:229], v[84:87]
	v_mfma_f32_16x16x32_bf16 v[80:83], v[202:205], v[226:229], v[80:83]
	v_mfma_f32_16x16x32_bf16 v[68:71], v[192:195], v[234:237], v[68:71]
	v_mfma_f32_16x16x32_bf16 v[64:67], v[202:205], v[234:237], v[64:67]
	s_setprio 0
	s_barrier
; #define PG8_STAGE(bufoff, gbase, voff) do { _Pragma("unroll") for (int _i = 0; _i < 2; ++_i) \
;         __builtin_amdgcn_global_load_lds((const unsigned*)((const char*)(gbase) + (voff)[_i]), (PG8_LAS unsigned*)(lds + (bufoff) + ldsw + _i * 8192), 16, 0, 0); } while (0)
; #define PG8_LDA(dst, b, h) do { _Pragma("unroll") for (int m = 0; m < 4; ++m) _Pragma("unroll") for (int k = 0; k < 2; ++k) dst[m][k] = *(const PG8_LAS bf16x8*)(lds + PG8_SA(b, h) + aoff + m * 2048 + k * 1024); } while (0)
; #define PG8_MMA(ai, bj, At, Bt) do { __builtin_amdgcn_s_setprio(1); _Pragma("unroll") for (int m = 0; m < 4; ++m) _Pragma("unroll") for (int n = 0; n < 2; ++n) _Pragma("unroll") for (int k = 0; k < 2; ++k) \
;         acc[ai][bj][m][n] = __builtin_amdgcn_mfma_f32_16x16x32_bf16(Bt[n][k], At[m][k], acc[ai][bj][m][n], 0, 0, 0); __builtin_amdgcn_s_setprio(0); } while (0)
; #define PG8_WAIT_V(n) asm volatile("s_waitcnt vmcnt(" #n ")" ::: "memory")
; #define PG8_WAIT_L(n) asm volatile("s_waitcnt lgkmcnt(" #n ")" ::: "memory")
; #define PG8_BAR __builtin_amdgcn_s_barrier()
; #define PG8_SCHED __builtin_amdgcn_sched_barrier(0)
; template <class Epi, class Sched, bool ALIGN_EPI = false, bool SP2 = false>
; __device__ __forceinline__ void gemm_phase(PG8_LAS unsigned char* lds, const Gemm g, const Sched& S, const Epi& E, int tid_in) {
;     ...
;             PG8_LDA(At, 1, 1); PG8_STAGE(PG8_SB(1, 0), b3, voffB); PG8_STAGE(PG8_SB(1, 1), b3 + hstep, voffB); PG8_STAGE(PG8_SA(1, 0), a3, voffA);
;             PG8_WAIT_V(8); PG8_WAIT_L(0); PG8_BAR; PG8_MMA(1, 0, At, B0); PG8_MMA(1, 1, At, B1); PG8_BAR; PG8_SCHED;
;     ...
;         if constexpr (ALIGN_EPI) { if (wr == 0) PG8_BAR; }
	s_add_i32 s4, s4, s12
	v_lshl_add_u64 v[150:151], v[150:151], 0, s[18:19]
	s_mov_b32 m0, s4
	ds_read_b128 v[206:209], v173 offset:49152
	ds_read_b128 v[210:213], v173 offset:50176
	ds_read_b128 v[214:217], v173 offset:51200
	ds_read_b128 v[218:221], v173 offset:52224
	ds_read_b128 v[222:225], v173 offset:53248
	ds_read_b128 v[226:229], v173 offset:54272
	ds_read_b128 v[230:233], v173 offset:55296
	ds_read_b128 v[234:237], v173 offset:56320
	global_load_lds_dwordx4 v[150:151], off
	s_add_i32 m0, s4, 0x2000
	s_add_u32 s48, s48, 0x40080
	v_lshl_add_u64 v[150:151], v[154:155], 0, s[18:19]
	s_addc_u32 s49, s49, 0
	s_add_i32 s4, s5, s12
	global_load_lds_dwordx4 v[150:151], off
	v_lshl_add_u64 v[150:151], s[48:49], 0, v[132:133]
	s_mov_b32 m0, s4
	s_nop 0
	global_load_lds_dwordx4 v[150:151], off
	v_lshl_add_u64 v[150:151], s[48:49], 0, v[128:129]
	s_add_i32 m0, s4, 0x2000
	s_nop 0
	global_load_lds_dwordx4 v[150:151], off
	v_lshl_add_u64 v[150:151], v[158:159], 0, s[18:19]
	s_mov_b32 m0, s54
	s_nop 0
	global_load_lds_dwordx4 v[150:151], off
	v_lshl_add_u64 v[150:151], v[162:163], 0, s[18:19]
	s_mov_b32 m0, s55
	s_nop 0
	global_load_lds_dwordx4 v[150:151], off
	s_waitcnt vmcnt(8)
	s_waitcnt lgkmcnt(0)
	s_barrier
	s_setprio 1
	s_waitcnt lgkmcnt(0)
	v_mfma_f32_16x16x32_bf16 v[60:63], v[146:149], v[206:209], v[60:63]
	v_mfma_f32_16x16x32_bf16 v[56:59], v[180:183], v[206:209], v[56:59]
	v_mfma_f32_16x16x32_bf16 v[44:47], v[146:149], v[214:217], v[44:47]
	v_mfma_f32_16x16x32_bf16 v[40:43], v[180:183], v[214:217], v[40:43]
	v_mfma_f32_16x16x32_bf16 v[28:31], v[146:149], v[222:225], v[28:31]
	v_mfma_f32_16x16x32_bf16 v[24:27], v[180:183], v[222:225], v[24:27]
	v_mfma_f32_16x16x32_bf16 v[12:15], v[146:149], v[230:233], v[12:15]
	v_mfma_f32_16x16x32_bf16 v[8:11], v[180:183], v[230:233], v[8:11]
	v_mfma_f32_16x16x32_bf16 v[60:63], v[176:179], v[210:213], v[60:63]
	v_mfma_f32_16x16x32_bf16 v[56:59], v[184:187], v[210:213], v[56:59]
	v_mfma_f32_16x16x32_bf16 v[44:47], v[176:179], v[218:221], v[44:47]
	v_mfma_f32_16x16x32_bf16 v[40:43], v[184:187], v[218:221], v[40:43]
	v_mfma_f32_16x16x32_bf16 v[28:31], v[176:179], v[226:229], v[28:31]
	v_mfma_f32_16x16x32_bf16 v[24:27], v[184:187], v[226:229], v[24:27]
	v_mfma_f32_16x16x32_bf16 v[12:15], v[176:179], v[234:237], v[12:15]
	v_mfma_f32_16x16x32_bf16 v[8:11], v[184:187], v[234:237], v[8:11]
	s_setprio 0
	s_setprio 1
	v_mfma_f32_16x16x32_bf16 v[52:55], v[188:191], v[206:209], v[52:55]
	v_mfma_f32_16x16x32_bf16 v[48:51], v[196:199], v[206:209], v[48:51]
	v_mfma_f32_16x16x32_bf16 v[36:39], v[188:191], v[214:217], v[36:39]
	v_mfma_f32_16x16x32_bf16 v[32:35], v[196:199], v[214:217], v[32:35]
	v_mfma_f32_16x16x32_bf16 v[20:23], v[188:191], v[222:225], v[20:23]
	v_mfma_f32_16x16x32_bf16 v[16:19], v[196:199], v[222:225], v[16:19]
	v_mfma_f32_16x16x32_bf16 v[4:7], v[188:191], v[230:233], v[4:7]
	v_mfma_f32_16x16x32_bf16 v[0:3], v[196:199], v[230:233], v[0:3]
	v_mfma_f32_16x16x32_bf16 v[52:55], v[192:195], v[210:213], v[52:55]
	v_mfma_f32_16x16x32_bf16 v[48:51], v[202:205], v[210:213], v[48:51]
	v_mfma_f32_16x16x32_bf16 v[36:39], v[192:195], v[218:221], v[36:39]
	v_mfma_f32_16x16x32_bf16 v[32:35], v[202:205], v[218:221], v[32:35]
	v_mfma_f32_16x16x32_bf16 v[20:23], v[192:195], v[226:229], v[20:23]
	v_mfma_f32_16x16x32_bf16 v[16:19], v[202:205], v[226:229], v[16:19]
	v_mfma_f32_16x16x32_bf16 v[4:7], v[192:195], v[234:237], v[4:7]
	v_mfma_f32_16x16x32_bf16 v[0:3], v[202:205], v[234:237], v[0:3]
	s_setprio 0
	s_barrier
	s_add_i32 s66, s66, 2
	s_add_u32 s64, s64, 0x100
	s_addc_u32 s65, s65, 0
	s_add_u32 s46, s46, 0x100
	s_addc_u32 s47, s47, 0
	s_cmp_gt_u32 s66, 13
	s_cbranch_scc0 .LBB0_1588
.Lpost11:
	s_and_b64 vcc, exec, s[20:21]
	s_cbranch_vccz .LBB0_1591
	s_barrier

; #define PG8_STAGE(bufoff, gbase, voff) do { _Pragma("unroll") for (int _i = 0; _i < 2; ++_i) \
;         __builtin_amdgcn_global_load_lds((const unsigned*)((const char*)(gbase) + (voff)[_i]), (PG8_LAS unsigned*)(lds + (bufoff) + ldsw + _i * 8192), 16, 0, 0); } while (0)
; #define PG8_LDA(dst, b, h) do { _Pragma("unroll") for (int m = 0; m < 4; ++m) _Pragma("unroll") for (int k = 0; k < 2; ++k) dst[m][k] = *(const PG8_LAS bf16x8*)(lds + PG8_SA(b, h) + aoff + m * 2048 + k * 1024); } while (0)
; #define PG8_LDB(dst, b, h) do { _Pragma("unroll") for (int n = 0; n < 2; ++n) _Pragma("unroll") for (int k = 0; k < 2; ++k) dst[n][k] = *(const PG8_LAS bf16x8*)(lds + PG8_SB(b, h) + boff + n * 2048 + k * 1024); } while (0)
; #define PG8_MMA(ai, bj, At, Bt) do { __builtin_amdgcn_s_setprio(1); _Pragma("unroll") for (int m = 0; m < 4; ++m) _Pragma("unroll") for (int n = 0; n < 2; ++n) _Pragma("unroll") for (int k = 0; k < 2; ++k) \
;         acc[ai][bj][m][n] = __builtin_amdgcn_mfma_f32_16x16x32_bf16(Bt[n][k], At[m][k], acc[ai][bj][m][n], 0, 0, 0); __builtin_amdgcn_s_setprio(0); } while (0)
; #define PG8_WAIT_V(n) asm volatile("s_waitcnt vmcnt(" #n ")" ::: "memory")
; #define PG8_WAIT_L(n) asm volatile("s_waitcnt lgkmcnt(" #n ")" ::: "memory")
; #define PG8_BAR __builtin_amdgcn_s_barrier()
; #define PG8_SCHED __builtin_amdgcn_sched_barrier(0)
; template <class Epi, class Sched, bool ALIGN_EPI = false, bool SP2 = false>
; __device__ __forceinline__ void gemm_phase(PG8_LAS unsigned char* lds, const Gemm g, const Sched& S, const Epi& E, int tid_in) {
;     ...
;             PG8_LDB(B0, 0, 0); PG8_LDB(B1, 0, 1); PG8_SCHED; PG8_LDA(At, 0, 0); PG8_STAGE(PG8_SA(1, 1), a1 + hstep, voffA);
;             PG8_WAIT_V(8); PG8_WAIT_L(0); PG8_BAR; PG8_MMA(0, 0, At, B0); PG8_MMA(0, 1, At, B1); PG8_BAR; PG8_SCHED;
;             PG8_LDA(At, 0, 1); PG8_STAGE(PG8_SB(0, 0), b2, voffB); PG8_STAGE(PG8_SB(0, 1), b2 + hstep, voffB); PG8_STAGE(PG8_SA(0, 0), a2, voffA);
;             PG8_WAIT_V(8); PG8_WAIT_L(0); PG8_BAR; PG8_MMA(1, 0, At, B0); PG8_MMA(1, 1, At, B1); PG8_BAR; PG8_SCHED;
.Lpk11:
	s_or_b64 s[98:99], s[8:9], 1
	v_lshl_add_u64 v[150:151], s[46:47], 0, v[140:141]
	s_add_i32 m0, s40, 0xc000
	ds_read_b128 v[206:209], v173
	ds_read_b128 v[210:213], v173 offset:1024
	ds_read_b128 v[214:217], v173 offset:2048
	ds_read_b128 v[218:221], v173 offset:3072
	ds_read_b128 v[222:225], v173 offset:4096
	ds_read_b128 v[226:229], v173 offset:5120
	ds_read_b128 v[230:233], v173 offset:6144
	ds_read_b128 v[234:237], v173 offset:7168
	global_load_lds_dwordx4 v[150:151], off
	v_lshl_add_u64 v[150:151], s[46:47], 0, v[138:139]
	s_add_i32 m0, s40, 0xe000
	s_nop 0
	global_load_lds_dwordx4 v[150:151], off
	s_waitcnt vmcnt(8)
	s_waitcnt lgkmcnt(0)
	s_barrier
	s_setprio 1
	s_waitcnt lgkmcnt(0)
	v_mfma_f32_16x16x32_bf16 v[124:127], v[146:149], v[206:209], v[124:127]
	v_mfma_f32_16x16x32_bf16 v[120:123], v[180:183], v[206:209], v[120:123]
	v_mfma_f32_16x16x32_bf16 v[108:111], v[146:149], v[214:217], v[108:111]
	v_mfma_f32_16x16x32_bf16 v[104:107], v[180:183], v[214:217], v[104:107]
	v_mfma_f32_16x16x32_bf16 v[92:95], v[146:149], v[222:225], v[92:95]
	v_mfma_f32_16x16x32_bf16 v[88:91], v[180:183], v[222:225], v[88:91]
	v_mfma_f32_16x16x32_bf16 v[76:79], v[146:149], v[230:233], v[76:79]
	v_mfma_f32_16x16x32_bf16 v[72:75], v[180:183], v[230:233], v[72:75]
	v_mfma_f32_16x16x32_bf16 v[124:127], v[176:179], v[210:213], v[124:127]
	v_mfma_f32_16x16x32_bf16 v[120:123], v[184:187], v[210:213], v[120:123]
	v_mfma_f32_16x16x32_bf16 v[108:111], v[176:179], v[218:221], v[108:111]
	v_mfma_f32_16x16x32_bf16 v[104:107], v[184:187], v[218:221], v[104:107]
	v_mfma_f32_16x16x32_bf16 v[92:95], v[176:179], v[226:229], v[92:95]
	v_mfma_f32_16x16x32_bf16 v[88:91], v[184:187], v[226:229], v[88:91]
	v_mfma_f32_16x16x32_bf16 v[76:79], v[176:179], v[234:237], v[76:79]
	v_mfma_f32_16x16x32_bf16 v[72:75], v[184:187], v[234:237], v[72:75]
	s_setprio 0
	s_setprio 1
	v_mfma_f32_16x16x32_bf16 v[116:119], v[188:191], v[206:209], v[116:119]
	v_mfma_f32_16x16x32_bf16 v[112:115], v[196:199], v[206:209], v[112:115]
	v_mfma_f32_16x16x32_bf16 v[100:103], v[188:191], v[214:217], v[100:103]
	v_mfma_f32_16x16x32_bf16 v[96:99], v[196:199], v[214:217], v[96:99]
	v_mfma_f32_16x16x32_bf16 v[84:87], v[188:191], v[222:225], v[84:87]
	v_mfma_f32_16x16x32_bf16 v[80:83], v[196:199], v[222:225], v[80:83]
	v_mfma_f32_16x16x32_bf16 v[68:71], v[188:191], v[230:233], v[68:71]
	v_mfma_f32_16x16x32_bf16 v[64:67], v[196:199], v[230:233], v[64:67]
	v_mfma_f32_16x16x32_bf16 v[116:119], v[192:195], v[210:213], v[116:119]
	v_mfma_f32_16x16x32_bf16 v[112:115], v[202:205], v[210:213], v[112:115]
	v_mfma_f32_16x16x32_bf16 v[100:103], v[192:195], v[218:221], v[100:103]
	v_mfma_f32_16x16x32_bf16 v[96:99], v[202:205], v[218:221], v[96:99]
	v_mfma_f32_16x16x32_bf16 v[84:87], v[192:195], v[226:229], v[84:87]
	v_mfma_f32_16x16x32_bf16 v[80:83], v[202:205], v[226:229], v[80:83]
	v_mfma_f32_16x16x32_bf16 v[68:71], v[192:195], v[234:237], v[68:71]
	v_mfma_f32_16x16x32_bf16 v[64:67], v[202:205], v[234:237], v[64:67]
	s_setprio 0
	s_barrier
	s_add_i32 s4, s58, s12
	v_lshl_add_u64 v[150:151], s[48:49], 0, v[132:133]
	s_mov_b32 m0, s4
	ds_read_b128 v[206:209], v173 offset:16384
	ds_read_b128 v[210:213], v173 offset:17408
	ds_read_b128 v[214:217], v173 offset:18432
	ds_read_b128 v[218:221], v173 offset:19456
	ds_read_b128 v[222:225], v173 offset:20480
	ds_read_b128 v[226:229], v173 offset:21504
	ds_read_b128 v[230:233], v173 offset:22528
	ds_read_b128 v[234:237], v173 offset:23552
	s_mov_b64 exec, s[98:99]
	global_load_lds_dwordx4 v[150:151], off
	s_mov_b64 exec, -1
	s_add_i32 m0, s4, 0x2000
	s_add_u32 s68, s48, 0x40000
	v_lshl_add_u64 v[154:155], s[48:49], 0, v[128:129]
	s_addc_u32 s69, s49, 0
	s_add_i32 s4, s59, s12
	s_mov_b64 exec, s[98:99]
	global_load_lds_dwordx4 v[154:155], off
	s_mov_b64 exec, -1
	v_lshl_add_u64 v[158:159], s[68:69], 0, v[132:133]
	s_mov_b32 m0, s4
	v_lshl_add_u64 v[162:163], s[50:51], 0, v[130:131]
	s_mov_b64 exec, s[98:99]
	global_load_lds_dwordx4 v[158:159], off
	s_mov_b64 exec, -1
	v_lshl_add_u64 v[158:159], s[68:69], 0, v[128:129]
	s_add_i32 m0, s4, 0x2000
	s_nop 0
	s_mov_b64 exec, s[98:99]
	global_load_lds_dwordx4 v[158:159], off
	s_mov_b64 exec, -1
	v_lshl_add_u64 v[158:159], s[50:51], 0, v[134:135]
	s_mov_b32 m0, s40
	s_nop 0
	s_mov_b64 exec, s[98:99]
	global_load_lds_dwordx4 v[158:159], off
	s_mov_b64 exec, -1
	s_mov_b32 m0, s41
	s_nop 0
	s_mov_b64 exec, s[98:99]
	global_load_lds_dwordx4 v[162:163], off
	s_mov_b64 exec, -1
	s_waitcnt vmcnt(8)
	s_waitcnt lgkmcnt(0)
	s_barrier
; #define PG8_STAGE(bufoff, gbase, voff) do { _Pragma("unroll") for (int _i = 0; _i < 2; ++_i) \
;         __builtin_amdgcn_global_load_lds((const unsigned*)((const char*)(gbase) + (voff)[_i]), (PG8_LAS unsigned*)(lds + (bufoff) + ldsw + _i * 8192), 16, 0, 0); } while (0)
; #define PG8_LDA(dst, b, h) do { _Pragma("unroll") for (int m = 0; m < 4; ++m) _Pragma("unroll") for (int k = 0; k < 2; ++k) dst[m][k] = *(const PG8_LAS bf16x8*)(lds + PG8_SA(b, h) + aoff + m * 2048 + k * 1024); } while (0)
; #define PG8_LDB(dst, b, h) do { _Pragma("unroll") for (int n = 0; n < 2; ++n) _Pragma("unroll") for (int k = 0; k < 2; ++k) dst[n][k] = *(const PG8_LAS bf16x8*)(lds + PG8_SB(b, h) + boff + n * 2048 + k * 1024); } while (0)
; #define PG8_MMA(ai, bj, At, Bt) do { __builtin_amdgcn_s_setprio(1); _Pragma("unroll") for (int m = 0; m < 4; ++m) _Pragma("unroll") for (int n = 0; n < 2; ++n) _Pragma("unroll") for (int k = 0; k < 2; ++k) \
;         acc[ai][bj][m][n] = __builtin_amdgcn_mfma_f32_16x16x32_bf16(Bt[n][k], At[m][k], acc[ai][bj][m][n], 0, 0, 0); __builtin_amdgcn_s_setprio(0); } while (0)
; #define PG8_WAIT_V(n) asm volatile("s_waitcnt vmcnt(" #n ")" ::: "memory")
; #define PG8_WAIT_L(n) asm volatile("s_waitcnt lgkmcnt(" #n ")" ::: "memory")
; #define PG8_BAR __builtin_amdgcn_s_barrier()
; #define PG8_SCHED __builtin_amdgcn_sched_barrier(0)
; template <class Epi, class Sched, bool ALIGN_EPI = false, bool SP2 = false>
; __device__ __forceinline__ void gemm_phase(PG8_LAS unsigned char* lds, const Gemm g, const Sched& S, const Epi& E, int tid_in) {
;     ...
;             PG8_WAIT_V(8); PG8_WAIT_L(0); PG8_BAR; PG8_MMA(1, 0, At, B0); PG8_MMA(1, 1, At, B1); PG8_BAR; PG8_SCHED;
;             PG8_LDB(B0, 1, 0); PG8_LDB(B1, 1, 1); PG8_SCHED; PG8_LDA(At, 1, 0); PG8_STAGE(PG8_SA(0, 1), a2 + hstep, voffA);
;             PG8_WAIT_V(8); PG8_WAIT_L(0); PG8_BAR; PG8_MMA(0, 0, At, B0); PG8_MMA(0, 1, At, B1); PG8_BAR; PG8_SCHED;
	s_setprio 1
	s_waitcnt lgkmcnt(0)
	v_mfma_f32_16x16x32_bf16 v[60:63], v[146:149], v[206:209], v[60:63]
	v_mfma_f32_16x16x32_bf16 v[56:59], v[180:183], v[206:209], v[56:59]
	v_mfma_f32_16x16x32_bf16 v[44:47], v[146:149], v[214:217], v[44:47]
	v_mfma_f32_16x16x32_bf16 v[40:43], v[180:183], v[214:217], v[40:43]
	v_mfma_f32_16x16x32_bf16 v[28:31], v[146:149], v[222:225], v[28:31]
	v_mfma_f32_16x16x32_bf16 v[24:27], v[180:183], v[222:225], v[24:27]
	v_mfma_f32_16x16x32_bf16 v[12:15], v[146:149], v[230:233], v[12:15]
	v_mfma_f32_16x16x32_bf16 v[8:11], v[180:183], v[230:233], v[8:11]
	v_mfma_f32_16x16x32_bf16 v[60:63], v[176:179], v[210:213], v[60:63]
	v_mfma_f32_16x16x32_bf16 v[56:59], v[184:187], v[210:213], v[56:59]
	v_mfma_f32_16x16x32_bf16 v[44:47], v[176:179], v[218:221], v[44:47]
	v_mfma_f32_16x16x32_bf16 v[40:43], v[184:187], v[218:221], v[40:43]
	v_mfma_f32_16x16x32_bf16 v[28:31], v[176:179], v[226:229], v[28:31]
	v_mfma_f32_16x16x32_bf16 v[24:27], v[184:187], v[226:229], v[24:27]
	v_mfma_f32_16x16x32_bf16 v[12:15], v[176:179], v[234:237], v[12:15]
	v_mfma_f32_16x16x32_bf16 v[8:11], v[184:187], v[234:237], v[8:11]
	s_setprio 0
	s_setprio 1
	v_mfma_f32_16x16x32_bf16 v[52:55], v[188:191], v[206:209], v[52:55]
	v_mfma_f32_16x16x32_bf16 v[48:51], v[196:199], v[206:209], v[48:51]
	v_mfma_f32_16x16x32_bf16 v[36:39], v[188:191], v[214:217], v[36:39]
	v_mfma_f32_16x16x32_bf16 v[32:35], v[196:199], v[214:217], v[32:35]
	v_mfma_f32_16x16x32_bf16 v[20:23], v[188:191], v[222:225], v[20:23]
	v_mfma_f32_16x16x32_bf16 v[16:19], v[196:199], v[222:225], v[16:19]
	v_mfma_f32_16x16x32_bf16 v[4:7], v[188:191], v[230:233], v[4:7]
	v_mfma_f32_16x16x32_bf16 v[0:3], v[196:199], v[230:233], v[0:3]
	v_mfma_f32_16x16x32_bf16 v[52:55], v[192:195], v[210:213], v[52:55]
	v_mfma_f32_16x16x32_bf16 v[48:51], v[202:205], v[210:213], v[48:51]
	v_mfma_f32_16x16x32_bf16 v[36:39], v[192:195], v[218:221], v[36:39]
	v_mfma_f32_16x16x32_bf16 v[32:35], v[202:205], v[218:221], v[32:35]
	v_mfma_f32_16x16x32_bf16 v[20:23], v[192:195], v[226:229], v[20:23]
	v_mfma_f32_16x16x32_bf16 v[16:19], v[202:205], v[226:229], v[16:19]
	v_mfma_f32_16x16x32_bf16 v[4:7], v[192:195], v[234:237], v[4:7]
	v_mfma_f32_16x16x32_bf16 v[0:3], v[202:205], v[234:237], v[0:3]
	s_setprio 0
	s_barrier
	s_add_i32 s4, 0, 0x18000
	v_add_u32_e32 v152, s4, v157
	s_add_i32 s5, 0, 0x1c000
	ds_read_b128 v[146:149], v152
	ds_read_b128 v[176:179], v152 offset:1024
	ds_read_b128 v[180:183], v152 offset:2048
	ds_read_b128 v[184:187], v152 offset:3072
	v_add_u32_e32 v152, s5, v157
	ds_read_b128 v[188:191], v152
	ds_read_b128 v[192:195], v152 offset:1024
	ds_read_b128 v[196:199], v152 offset:2048
	ds_read_b128 v[202:205], v152 offset:3072
	s_add_u32 s50, s50, 0x40000
	s_addc_u32 s51, s51, 0
	s_mov_b32 m0, s45
	v_lshl_add_u64 v[166:167], s[50:51], 0, v[134:135]
	ds_read_b128 v[206:209], v173 offset:32768
	ds_read_b128 v[210:213], v173 offset:33792
	ds_read_b128 v[214:217], v173 offset:34816
	ds_read_b128 v[218:221], v173 offset:35840
	ds_read_b128 v[222:225], v173 offset:36864
	ds_read_b128 v[226:229], v173 offset:37888
	ds_read_b128 v[230:233], v173 offset:38912
	ds_read_b128 v[234:237], v173 offset:39936
	s_mov_b64 exec, s[98:99]
	global_load_lds_dwordx4 v[166:167], off
	s_mov_b64 exec, -1
	v_lshl_add_u64 v[166:167], s[50:51], 0, v[130:131]
	s_mov_b32 m0, s52
	s_nop 0
	s_mov_b64 exec, s[98:99]
	global_load_lds_dwordx4 v[166:167], off
	s_mov_b64 exec, -1
	s_waitcnt vmcnt(8)
	s_waitcnt lgkmcnt(0)
	s_barrier
	s_setprio 1
	s_waitcnt lgkmcnt(0)
	v_mfma_f32_16x16x32_bf16 v[124:127], v[146:149], v[206:209], v[124:127]
	v_mfma_f32_16x16x32_bf16 v[120:123], v[180:183], v[206:209], v[120:123]
	v_mfma_f32_16x16x32_bf16 v[108:111], v[146:149], v[214:217], v[108:111]
	v_mfma_f32_16x16x32_bf16 v[104:107], v[180:183], v[214:217], v[104:107]
	v_mfma_f32_16x16x32_bf16 v[92:95], v[146:149], v[222:225], v[92:95]
	v_mfma_f32_16x16x32_bf16 v[88:91], v[180:183], v[222:225], v[88:91]
	v_mfma_f32_16x16x32_bf16 v[76:79], v[146:149], v[230:233], v[76:79]
	v_mfma_f32_16x16x32_bf16 v[72:75], v[180:183], v[230:233], v[72:75]
	v_mfma_f32_16x16x32_bf16 v[124:127], v[176:179], v[210:213], v[124:127]
	v_mfma_f32_16x16x32_bf16 v[120:123], v[184:187], v[210:213], v[120:123]
	v_mfma_f32_16x16x32_bf16 v[108:111], v[176:179], v[218:221], v[108:111]
	v_mfma_f32_16x16x32_bf16 v[104:107], v[184:187], v[218:221], v[104:107]
	v_mfma_f32_16x16x32_bf16 v[92:95], v[176:179], v[226:229], v[92:95]
	v_mfma_f32_16x16x32_bf16 v[88:91], v[184:187], v[226:229], v[88:91]
	v_mfma_f32_16x16x32_bf16 v[76:79], v[176:179], v[234:237], v[76:79]
	v_mfma_f32_16x16x32_bf16 v[72:75], v[184:187], v[234:237], v[72:75]
	s_setprio 0
	s_setprio 1
	v_mfma_f32_16x16x32_bf16 v[116:119], v[188:191], v[206:209], v[116:119]
	v_mfma_f32_16x16x32_bf16 v[112:115], v[196:199], v[206:209], v[112:115]
	v_mfma_f32_16x16x32_bf16 v[100:103], v[188:191], v[214:217], v[100:103]
	v_mfma_f32_16x16x32_bf16 v[96:99], v[196:199], v[214:217], v[96:99]
	v_mfma_f32_16x16x32_bf16 v[84:87], v[188:191], v[222:225], v[84:87]
	v_mfma_f32_16x16x32_bf16 v[80:83], v[196:199], v[222:225], v[80:83]
	v_mfma_f32_16x16x32_bf16 v[68:71], v[188:191], v[230:233], v[68:71]
	v_mfma_f32_16x16x32_bf16 v[64:67], v[196:199], v[230:233], v[64:67]
	v_mfma_f32_16x16x32_bf16 v[116:119], v[192:195], v[210:213], v[116:119]
	v_mfma_f32_16x16x32_bf16 v[112:115], v[202:205], v[210:213], v[112:115]
	v_mfma_f32_16x16x32_bf16 v[100:103], v[192:195], v[218:221], v[100:103]
	v_mfma_f32_16x16x32_bf16 v[96:99], v[202:205], v[218:221], v[96:99]
	v_mfma_f32_16x16x32_bf16 v[84:87], v[192:195], v[226:229], v[84:87]
	v_mfma_f32_16x16x32_bf16 v[80:83], v[202:205], v[226:229], v[80:83]
	v_mfma_f32_16x16x32_bf16 v[68:71], v[192:195], v[234:237], v[68:71]
	v_mfma_f32_16x16x32_bf16 v[64:67], v[202:205], v[234:237], v[64:67]
	s_setprio 0
	s_barrier
; #define PG8_STAGE(bufoff, gbase, voff) do { _Pragma("unroll") for (int _i = 0; _i < 2; ++_i) \
;         __builtin_amdgcn_global_load_lds((const unsigned*)((const char*)(gbase) + (voff)[_i]), (PG8_LAS unsigned*)(lds + (bufoff) + ldsw + _i * 8192), 16, 0, 0); } while (0)
; #define PG8_LDA(dst, b, h) do { _Pragma("unroll") for (int m = 0; m < 4; ++m) _Pragma("unroll") for (int k = 0; k < 2; ++k) dst[m][k] = *(const PG8_LAS bf16x8*)(lds + PG8_SA(b, h) + aoff + m * 2048 + k * 1024); } while (0)
; #define PG8_MMA(ai, bj, At, Bt) do { __builtin_amdgcn_s_setprio(1); _Pragma("unroll") for (int m = 0; m < 4; ++m) _Pragma("unroll") for (int n = 0; n < 2; ++n) _Pragma("unroll") for (int k = 0; k < 2; ++k) \
;         acc[ai][bj][m][n] = __builtin_amdgcn_mfma_f32_16x16x32_bf16(Bt[n][k], At[m][k], acc[ai][bj][m][n], 0, 0, 0); __builtin_amdgcn_s_setprio(0); } while (0)
; #define PG8_WAIT_V(n) asm volatile("s_waitcnt vmcnt(" #n ")" ::: "memory")
; #define PG8_WAIT_L(n) asm volatile("s_waitcnt lgkmcnt(" #n ")" ::: "memory")
; #define PG8_BAR __builtin_amdgcn_s_barrier()
; #define PG8_SCHED __builtin_amdgcn_sched_barrier(0)
; template <class Epi, class Sched, bool ALIGN_EPI = false, bool SP2 = false>
; __device__ __forceinline__ void gemm_phase(PG8_LAS unsigned char* lds, const Gemm g, const Sched& S, const Epi& E, int tid_in) {
;     ...
;             PG8_LDA(At, 1, 1); PG8_STAGE(PG8_SB(1, 0), b3, voffB); PG8_STAGE(PG8_SB(1, 1), b3 + hstep, voffB); PG8_STAGE(PG8_SA(1, 0), a3, voffA);
;             PG8_WAIT_V(8); PG8_WAIT_L(0); PG8_BAR; PG8_MMA(1, 0, At, B0); PG8_MMA(1, 1, At, B1); PG8_BAR; PG8_SCHED;
	s_add_i32 s4, s4, s12
	v_lshl_add_u64 v[150:151], v[150:151], 0, s[18:19]
	s_mov_b32 m0, s4
	ds_read_b128 v[206:209], v173 offset:49152
	ds_read_b128 v[210:213], v173 offset:50176
	ds_read_b128 v[214:217], v173 offset:51200
	ds_read_b128 v[218:221], v173 offset:52224
	ds_read_b128 v[222:225], v173 offset:53248
	ds_read_b128 v[226:229], v173 offset:54272
	ds_read_b128 v[230:233], v173 offset:55296
	ds_read_b128 v[234:237], v173 offset:56320
	s_mov_b64 exec, s[98:99]
	global_load_lds_dwordx4 v[150:151], off
	s_mov_b64 exec, -1
	s_add_i32 m0, s4, 0x2000
	s_add_u32 s48, s48, 0x40080
	v_lshl_add_u64 v[150:151], v[154:155], 0, s[18:19]
	s_addc_u32 s49, s49, 0
	s_add_i32 s4, s5, s12
	s_mov_b64 exec, s[98:99]
	global_load_lds_dwordx4 v[150:151], off
	s_mov_b64 exec, -1
	v_lshl_add_u64 v[150:151], s[48:49], 0, v[132:133]
	s_mov_b32 m0, s4
	s_nop 0
	s_mov_b64 exec, s[98:99]
	global_load_lds_dwordx4 v[150:151], off
	s_mov_b64 exec, -1
	v_lshl_add_u64 v[150:151], s[48:49], 0, v[128:129]
	s_add_i32 m0, s4, 0x2000
	s_nop 0
	s_mov_b64 exec, s[98:99]
	global_load_lds_dwordx4 v[150:151], off
	s_mov_b64 exec, -1
	v_lshl_add_u64 v[150:151], v[158:159], 0, s[18:19]
	s_mov_b32 m0, s54
	s_nop 0
	s_mov_b64 exec, s[98:99]
	global_load_lds_dwordx4 v[150:151], off
	s_mov_b64 exec, -1
	v_lshl_add_u64 v[150:151], v[162:163], 0, s[18:19]
	s_mov_b32 m0, s55
	s_nop 0
	s_mov_b64 exec, s[98:99]
	global_load_lds_dwordx4 v[150:151], off
	s_mov_b64 exec, -1
	s_waitcnt vmcnt(8)
	s_waitcnt lgkmcnt(0)
	s_barrier
	s_setprio 1
	s_waitcnt lgkmcnt(0)
	v_mfma_f32_16x16x32_bf16 v[60:63], v[146:149], v[206:209], v[60:63]
	v_mfma_f32_16x16x32_bf16 v[56:59], v[180:183], v[206:209], v[56:59]
	v_mfma_f32_16x16x32_bf16 v[44:47], v[146:149], v[214:217], v[44:47]
	v_mfma_f32_16x16x32_bf16 v[40:43], v[180:183], v[214:217], v[40:43]
	v_mfma_f32_16x16x32_bf16 v[28:31], v[146:149], v[222:225], v[28:31]
	v_mfma_f32_16x16x32_bf16 v[24:27], v[180:183], v[222:225], v[24:27]
	v_mfma_f32_16x16x32_bf16 v[12:15], v[146:149], v[230:233], v[12:15]
	v_mfma_f32_16x16x32_bf16 v[8:11], v[180:183], v[230:233], v[8:11]
	v_mfma_f32_16x16x32_bf16 v[60:63], v[176:179], v[210:213], v[60:63]
	v_mfma_f32_16x16x32_bf16 v[56:59], v[184:187], v[210:213], v[56:59]
	v_mfma_f32_16x16x32_bf16 v[44:47], v[176:179], v[218:221], v[44:47]
	v_mfma_f32_16x16x32_bf16 v[40:43], v[184:187], v[218:221], v[40:43]
	v_mfma_f32_16x16x32_bf16 v[28:31], v[176:179], v[226:229], v[28:31]
	v_mfma_f32_16x16x32_bf16 v[24:27], v[184:187], v[226:229], v[24:27]
	v_mfma_f32_16x16x32_bf16 v[12:15], v[176:179], v[234:237], v[12:15]
	v_mfma_f32_16x16x32_bf16 v[8:11], v[184:187], v[234:237], v[8:11]
	s_setprio 0
	s_setprio 1
	v_mfma_f32_16x16x32_bf16 v[52:55], v[188:191], v[206:209], v[52:55]
	v_mfma_f32_16x16x32_bf16 v[48:51], v[196:199], v[206:209], v[48:51]
	v_mfma_f32_16x16x32_bf16 v[36:39], v[188:191], v[214:217], v[36:39]
	v_mfma_f32_16x16x32_bf16 v[32:35], v[196:199], v[214:217], v[32:35]
	v_mfma_f32_16x16x32_bf16 v[20:23], v[188:191], v[222:225], v[20:23]
	v_mfma_f32_16x16x32_bf16 v[16:19], v[196:199], v[222:225], v[16:19]
	v_mfma_f32_16x16x32_bf16 v[4:7], v[188:191], v[230:233], v[4:7]
	v_mfma_f32_16x16x32_bf16 v[0:3], v[196:199], v[230:233], v[0:3]
	v_mfma_f32_16x16x32_bf16 v[52:55], v[192:195], v[210:213], v[52:55]
	v_mfma_f32_16x16x32_bf16 v[48:51], v[202:205], v[210:213], v[48:51]
	v_mfma_f32_16x16x32_bf16 v[36:39], v[192:195], v[218:221], v[36:39]
	v_mfma_f32_16x16x32_bf16 v[32:35], v[202:205], v[218:221], v[32:35]
	v_mfma_f32_16x16x32_bf16 v[20:23], v[192:195], v[226:229], v[20:23]
	v_mfma_f32_16x16x32_bf16 v[16:19], v[202:205], v[226:229], v[16:19]
	v_mfma_f32_16x16x32_bf16 v[4:7], v[192:195], v[234:237], v[4:7]
	v_mfma_f32_16x16x32_bf16 v[0:3], v[202:205], v[234:237], v[0:3]
	s_setprio 0
	s_barrier
	s_add_i32 s66, s66, 2
	s_add_u32 s64, s64, 0x100
	s_addc_u32 s65, s65, 0
	s_add_u32 s46, s46, 0x100
	s_addc_u32 s47, s47, 0
	s_cmp_gt_u32 s66, 13
	s_branch .Lpost11

; #define PG8_STAGE(bufoff, gbase, voff) do { _Pragma("unroll") for (int _i = 0; _i < 2; ++_i) \
;         __builtin_amdgcn_global_load_lds((const unsigned*)((const char*)(gbase) + (voff)[_i]), (PG8_LAS unsigned*)(lds + (bufoff) + ldsw + _i * 8192), 16, 0, 0); } while (0)
; #define PG8_LDA(dst, b, h) do { _Pragma("unroll") for (int m = 0; m < 4; ++m) _Pragma("unroll") for (int k = 0; k < 2; ++k) dst[m][k] = *(const PG8_LAS bf16x8*)(lds + PG8_SA(b, h) + aoff + m * 2048 + k * 1024); } while (0)
; #define PG8_LDB(dst, b, h) do { _Pragma("unroll") for (int n = 0; n < 2; ++n) _Pragma("unroll") for (int k = 0; k < 2; ++k) dst[n][k] = *(const PG8_LAS bf16x8*)(lds + PG8_SB(b, h) + boff + n * 2048 + k * 1024); } while (0)
; #define PG8_MMA(ai, bj, At, Bt) do { __builtin_amdgcn_s_setprio(1); _Pragma("unroll") for (int m = 0; m < 4; ++m) _Pragma("unroll") for (int n = 0; n < 2; ++n) _Pragma("unroll") for (int k = 0; k < 2; ++k) \
;         acc[ai][bj][m][n] = __builtin_amdgcn_mfma_f32_16x16x32_bf16(Bt[n][k], At[m][k], acc[ai][bj][m][n], 0, 0, 0); __builtin_amdgcn_s_setprio(0); } while (0)
; #define PG8_WAIT_V(n) asm volatile("s_waitcnt vmcnt(" #n ")" ::: "memory")
; #define PG8_BAR __builtin_amdgcn_s_barrier()
; template <class Epi, class Sched, bool ALIGN_EPI = false, bool SP2 = false>
; __device__ __forceinline__ void gemm_phase(PG8_LAS unsigned char* lds, const Gemm g, const Sched& S, const Epi& E, int tid_in) {
;     ...
;         for (int t = 0; t < nt; t += 2) {
;             const bool last = (t == nt - 2);
;             const char* a1 = cA + (size_t)(t + 1) * kstep;
;             const char* a2 = last ? nA : cA + (size_t)(t + 2) * kstep; const char* b2 = last ? nB : cB + (size_t)(t + 2) * kstep;
;             const char* a3 = a2 + kstep; const char* b3 = b2 + kstep;
;             if (last && has_next) S.a_ready(nxt);
;             if constexpr (SP2) {
;             PG8_LDB(B0, 0, 0); PG8_LDB(B1, 0, 1); PG8_SCHED; PG8_LDA(At, 0, 0); PG8_STAGE(PG8_SA(1, 1), a1 + hstep, voffA);
;             PG8_WAIT_V(8); PG8_WAIT_L(0); PG8_BAR; PG8_MMA(0, 0, At, B0); PG8_MMA(0, 1, At, B1); PG8_BAR; PG8_SCHED;
;             PG8_LDA(At, 0, 1); PG8_STAGE(PG8_SB(0, 0), b2, voffB); PG8_STAGE(PG8_SB(0, 1), b2 + hstep, voffB); PG8_STAGE(PG8_SA(0, 0), a2, voffA);
;             PG8_WAIT_V(8); PG8_WAIT_L(0); PG8_BAR; PG8_MMA(1, 0, At, B0); PG8_MMA(1, 1, At, B1); PG8_BAR; PG8_SCHED;
.LBB0_1670:
	ds_read_b128 v[120:123], v189
	ds_read_b128 v[132:135], v189 offset:1024
	ds_read_b128 v[136:139], v189 offset:2048
	ds_read_b128 v[140:143], v189 offset:3072
	ds_read_b128 v[144:147], v190
	ds_read_b128 v[148:151], v190 offset:1024
	ds_read_b128 v[168:171], v190 offset:2048
	ds_read_b128 v[172:175], v190 offset:3072
	s_add_u32 s48, s46, 0x100
	s_addc_u32 s49, s47, 0
	s_cmp_eq_u32 s68, 40
	s_cselect_b32 s53, s17, s49
	s_cselect_b32 s52, s16, s48
	s_cselect_b32 s51, s45, s67
	s_cselect_b32 s50, s44, s66
	s_cbranch_scc1 .Lpk12
	v_lshl_add_u64 v[184:185], s[46:47], 0, v[162:163]
	s_add_i32 m0, s13, 0xc000
	ds_read_b128 v[176:179], v191
	ds_read_b128 v[180:183], v191 offset:1024
	ds_read_b128 v[192:195], v191 offset:2048
	ds_read_b128 v[196:199], v191 offset:3072
	ds_read_b128 v[202:205], v191 offset:4096
	ds_read_b128 v[206:209], v191 offset:5120
	ds_read_b128 v[210:213], v191 offset:6144
	ds_read_b128 v[214:217], v191 offset:7168
	global_load_lds_dwordx4 v[184:185], off
	v_lshl_add_u64 v[184:185], s[46:47], 0, v[160:161]
	s_add_i32 m0, s13, 0xe000
	s_nop 0
	global_load_lds_dwordx4 v[184:185], off
	s_waitcnt vmcnt(8)
	s_waitcnt lgkmcnt(0)
	s_barrier
	s_setprio 1
	s_waitcnt lgkmcnt(0)
	v_mfma_f32_16x16x32_bf16 v[128:131], v[120:123], v[176:179], v[128:131]
	v_mfma_f32_16x16x32_bf16 v[124:127], v[136:139], v[176:179], v[124:127]
	v_mfma_f32_16x16x32_bf16 v[108:111], v[120:123], v[192:195], v[108:111]
	v_mfma_f32_16x16x32_bf16 v[104:107], v[136:139], v[192:195], v[104:107]
	v_mfma_f32_16x16x32_bf16 v[92:95], v[120:123], v[202:205], v[92:95]
	v_mfma_f32_16x16x32_bf16 v[88:91], v[136:139], v[202:205], v[88:91]
	v_mfma_f32_16x16x32_bf16 v[76:79], v[120:123], v[210:213], v[76:79]
	v_mfma_f32_16x16x32_bf16 v[72:75], v[136:139], v[210:213], v[72:75]
	v_mfma_f32_16x16x32_bf16 v[128:131], v[132:135], v[180:183], v[128:131]
	v_mfma_f32_16x16x32_bf16 v[124:127], v[140:143], v[180:183], v[124:127]
	v_mfma_f32_16x16x32_bf16 v[108:111], v[132:135], v[196:199], v[108:111]
	v_mfma_f32_16x16x32_bf16 v[104:107], v[140:143], v[196:199], v[104:107]
	v_mfma_f32_16x16x32_bf16 v[92:95], v[132:135], v[206:209], v[92:95]
	v_mfma_f32_16x16x32_bf16 v[88:91], v[140:143], v[206:209], v[88:91]
	v_mfma_f32_16x16x32_bf16 v[76:79], v[132:135], v[214:217], v[76:79]
	v_mfma_f32_16x16x32_bf16 v[72:75], v[140:143], v[214:217], v[72:75]
	s_setprio 0
	s_setprio 1
	v_mfma_f32_16x16x32_bf16 v[116:119], v[144:147], v[176:179], v[116:119]
	v_mfma_f32_16x16x32_bf16 v[112:115], v[168:171], v[176:179], v[112:115]
	v_mfma_f32_16x16x32_bf16 v[100:103], v[144:147], v[192:195], v[100:103]
	v_mfma_f32_16x16x32_bf16 v[96:99], v[168:171], v[192:195], v[96:99]
	v_mfma_f32_16x16x32_bf16 v[84:87], v[144:147], v[202:205], v[84:87]
	v_mfma_f32_16x16x32_bf16 v[80:83], v[168:171], v[202:205], v[80:83]
	v_mfma_f32_16x16x32_bf16 v[68:71], v[144:147], v[210:213], v[68:71]
	v_mfma_f32_16x16x32_bf16 v[64:67], v[168:171], v[210:213], v[64:67]
	v_mfma_f32_16x16x32_bf16 v[116:119], v[148:151], v[180:183], v[116:119]
	v_mfma_f32_16x16x32_bf16 v[112:115], v[172:175], v[180:183], v[112:115]
	v_mfma_f32_16x16x32_bf16 v[100:103], v[148:151], v[196:199], v[100:103]
	v_mfma_f32_16x16x32_bf16 v[96:99], v[172:175], v[196:199], v[96:99]
	v_mfma_f32_16x16x32_bf16 v[84:87], v[148:151], v[206:209], v[84:87]
	v_mfma_f32_16x16x32_bf16 v[80:83], v[172:175], v[206:209], v[80:83]
	v_mfma_f32_16x16x32_bf16 v[68:71], v[148:151], v[214:217], v[68:71]
	v_mfma_f32_16x16x32_bf16 v[64:67], v[172:175], v[214:217], v[64:67]
	s_setprio 0
	s_barrier
	s_add_i32 s4, s60, s12
	v_lshl_add_u64 v[184:185], s[50:51], 0, v[154:155]
	s_mov_b32 m0, s4
	ds_read_b128 v[176:179], v191 offset:16384
	ds_read_b128 v[180:183], v191 offset:17408
	ds_read_b128 v[192:195], v191 offset:18432
	ds_read_b128 v[196:199], v191 offset:19456
	ds_read_b128 v[202:205], v191 offset:20480
	ds_read_b128 v[206:209], v191 offset:21504
	ds_read_b128 v[210:213], v191 offset:22528
	ds_read_b128 v[214:217], v191 offset:23552
	global_load_lds_dwordx4 v[184:185], off
	s_add_i32 m0, s4, 0x2000
	s_add_u32 s46, s50, 0xb0000
	v_lshl_add_u64 v[218:219], s[50:51], 0, v[158:159]
	s_addc_u32 s47, s51, 0
	s_add_i32 s4, s61, s12
	global_load_lds_dwordx4 v[218:219], off
	v_lshl_add_u64 v[220:221], s[46:47], 0, v[154:155]
	s_mov_b32 m0, s4
	v_lshl_add_u64 v[222:223], s[52:53], 0, v[156:157]
	global_load_lds_dwordx4 v[220:221], off
	v_lshl_add_u64 v[220:221], s[46:47], 0, v[158:159]
	s_add_i32 m0, s4, 0x2000
	s_nop 0
	global_load_lds_dwordx4 v[220:221], off
	v_lshl_add_u64 v[220:221], s[52:53], 0, v[152:153]
	s_mov_b32 m0, s13
	s_nop 0
	global_load_lds_dwordx4 v[220:221], off
	s_mov_b32 m0, s33
	s_nop 0
	global_load_lds_dwordx4 v[222:223], off
	s_waitcnt vmcnt(8)
	s_waitcnt lgkmcnt(0)
	s_barrier
; #define PG8_STAGE(bufoff, gbase, voff) do { _Pragma("unroll") for (int _i = 0; _i < 2; ++_i) \
;         __builtin_amdgcn_global_load_lds((const unsigned*)((const char*)(gbase) + (voff)[_i]), (PG8_LAS unsigned*)(lds + (bufoff) + ldsw + _i * 8192), 16, 0, 0); } while (0)
; #define PG8_LDA(dst, b, h) do { _Pragma("unroll") for (int m = 0; m < 4; ++m) _Pragma("unroll") for (int k = 0; k < 2; ++k) dst[m][k] = *(const PG8_LAS bf16x8*)(lds + PG8_SA(b, h) + aoff + m * 2048 + k * 1024); } while (0)
; #define PG8_LDB(dst, b, h) do { _Pragma("unroll") for (int n = 0; n < 2; ++n) _Pragma("unroll") for (int k = 0; k < 2; ++k) dst[n][k] = *(const PG8_LAS bf16x8*)(lds + PG8_SB(b, h) + boff + n * 2048 + k * 1024); } while (0)
; #define PG8_MMA(ai, bj, At, Bt) do { __builtin_amdgcn_s_setprio(1); _Pragma("unroll") for (int m = 0; m < 4; ++m) _Pragma("unroll") for (int n = 0; n < 2; ++n) _Pragma("unroll") for (int k = 0; k < 2; ++k) \
;         acc[ai][bj][m][n] = __builtin_amdgcn_mfma_f32_16x16x32_bf16(Bt[n][k], At[m][k], acc[ai][bj][m][n], 0, 0, 0); __builtin_amdgcn_s_setprio(0); } while (0)
; #define PG8_WAIT_V(n) asm volatile("s_waitcnt vmcnt(" #n ")" ::: "memory")
; #define PG8_WAIT_L(n) asm volatile("s_waitcnt lgkmcnt(" #n ")" ::: "memory")
; #define PG8_BAR __builtin_amdgcn_s_barrier()
; #define PG8_SCHED __builtin_amdgcn_sched_barrier(0)
; template <class Epi, class Sched, bool ALIGN_EPI = false, bool SP2 = false>
; __device__ __forceinline__ void gemm_phase(PG8_LAS unsigned char* lds, const Gemm g, const Sched& S, const Epi& E, int tid_in) {
;     ...
;             PG8_WAIT_V(8); PG8_WAIT_L(0); PG8_BAR; PG8_MMA(1, 0, At, B0); PG8_MMA(1, 1, At, B1); PG8_BAR; PG8_SCHED;
;             PG8_LDB(B0, 1, 0); PG8_LDB(B1, 1, 1); PG8_SCHED; PG8_LDA(At, 1, 0); PG8_STAGE(PG8_SA(0, 1), a2 + hstep, voffA);
;             PG8_WAIT_V(8); PG8_WAIT_L(0); PG8_BAR; PG8_MMA(0, 0, At, B0); PG8_MMA(0, 1, At, B1); PG8_BAR; PG8_SCHED;
;             PG8_LDA(At, 1, 1); PG8_STAGE(PG8_SB(1, 0), b3, voffB); PG8_STAGE(PG8_SB(1, 1), b3 + hstep, voffB); PG8_STAGE(PG8_SA(1, 0), a3, voffA);
	s_setprio 1
	s_waitcnt lgkmcnt(0)
	v_mfma_f32_16x16x32_bf16 v[60:63], v[120:123], v[176:179], v[60:63]
	v_mfma_f32_16x16x32_bf16 v[56:59], v[136:139], v[176:179], v[56:59]
	v_mfma_f32_16x16x32_bf16 v[44:47], v[120:123], v[192:195], v[44:47]
	v_mfma_f32_16x16x32_bf16 v[40:43], v[136:139], v[192:195], v[40:43]
	v_mfma_f32_16x16x32_bf16 v[28:31], v[120:123], v[202:205], v[28:31]
	v_mfma_f32_16x16x32_bf16 v[24:27], v[136:139], v[202:205], v[24:27]
	v_mfma_f32_16x16x32_bf16 v[12:15], v[120:123], v[210:213], v[12:15]
	v_mfma_f32_16x16x32_bf16 v[8:11], v[136:139], v[210:213], v[8:11]
	v_mfma_f32_16x16x32_bf16 v[60:63], v[132:135], v[180:183], v[60:63]
	v_mfma_f32_16x16x32_bf16 v[56:59], v[140:143], v[180:183], v[56:59]
	v_mfma_f32_16x16x32_bf16 v[44:47], v[132:135], v[196:199], v[44:47]
	v_mfma_f32_16x16x32_bf16 v[40:43], v[140:143], v[196:199], v[40:43]
	v_mfma_f32_16x16x32_bf16 v[28:31], v[132:135], v[206:209], v[28:31]
	v_mfma_f32_16x16x32_bf16 v[24:27], v[140:143], v[206:209], v[24:27]
	v_mfma_f32_16x16x32_bf16 v[12:15], v[132:135], v[214:217], v[12:15]
	v_mfma_f32_16x16x32_bf16 v[8:11], v[140:143], v[214:217], v[8:11]
	s_setprio 0
	s_setprio 1
	v_mfma_f32_16x16x32_bf16 v[52:55], v[144:147], v[176:179], v[52:55]
	v_mfma_f32_16x16x32_bf16 v[48:51], v[168:171], v[176:179], v[48:51]
	v_mfma_f32_16x16x32_bf16 v[36:39], v[144:147], v[192:195], v[36:39]
	v_mfma_f32_16x16x32_bf16 v[32:35], v[168:171], v[192:195], v[32:35]
	v_mfma_f32_16x16x32_bf16 v[20:23], v[144:147], v[202:205], v[20:23]
	v_mfma_f32_16x16x32_bf16 v[16:19], v[168:171], v[202:205], v[16:19]
	v_mfma_f32_16x16x32_bf16 v[4:7], v[144:147], v[210:213], v[4:7]
	v_mfma_f32_16x16x32_bf16 v[0:3], v[168:171], v[210:213], v[0:3]
	v_mfma_f32_16x16x32_bf16 v[52:55], v[148:151], v[180:183], v[52:55]
	v_mfma_f32_16x16x32_bf16 v[48:51], v[172:175], v[180:183], v[48:51]
	v_mfma_f32_16x16x32_bf16 v[36:39], v[148:151], v[196:199], v[36:39]
	v_mfma_f32_16x16x32_bf16 v[32:35], v[172:175], v[196:199], v[32:35]
	v_mfma_f32_16x16x32_bf16 v[20:23], v[148:151], v[206:209], v[20:23]
	v_mfma_f32_16x16x32_bf16 v[16:19], v[172:175], v[206:209], v[16:19]
	v_mfma_f32_16x16x32_bf16 v[4:7], v[148:151], v[214:217], v[4:7]
	v_mfma_f32_16x16x32_bf16 v[0:3], v[172:175], v[214:217], v[0:3]
	s_setprio 0
	s_barrier
	s_add_i32 s4, 0, 0x18000
	s_add_i32 s5, 0, 0x1c000
	v_add_u32_e32 v140, s4, v187
	v_add_u32_e32 v172, s5, v187
	ds_read_b128 v[120:123], v140
	ds_read_b128 v[132:135], v140 offset:1024
	ds_read_b128 v[136:139], v140 offset:2048
	ds_read_b128 v[140:143], v140 offset:3072
	ds_read_b128 v[144:147], v172
	ds_read_b128 v[148:151], v172 offset:1024
	ds_read_b128 v[168:171], v172 offset:2048
	ds_read_b128 v[172:175], v172 offset:3072
	s_add_u32 s46, s52, 0xb0000
	s_addc_u32 s47, s53, 0
	s_mov_b32 m0, s40
	v_lshl_add_u64 v[224:225], s[46:47], 0, v[152:153]
	ds_read_b128 v[176:179], v191 offset:32768
	ds_read_b128 v[180:183], v191 offset:33792
	ds_read_b128 v[192:195], v191 offset:34816
	ds_read_b128 v[196:199], v191 offset:35840
	ds_read_b128 v[202:205], v191 offset:36864
	ds_read_b128 v[206:209], v191 offset:37888
	ds_read_b128 v[210:213], v191 offset:38912
	ds_read_b128 v[214:217], v191 offset:39936
	global_load_lds_dwordx4 v[224:225], off
	v_lshl_add_u64 v[224:225], s[46:47], 0, v[156:157]
	s_mov_b32 m0, s41
	s_nop 0
	global_load_lds_dwordx4 v[224:225], off
	s_waitcnt vmcnt(8)
	s_waitcnt lgkmcnt(0)
	s_barrier
	s_setprio 1
	s_waitcnt lgkmcnt(0)
	v_mfma_f32_16x16x32_bf16 v[128:131], v[120:123], v[176:179], v[128:131]
	v_mfma_f32_16x16x32_bf16 v[124:127], v[136:139], v[176:179], v[124:127]
	v_mfma_f32_16x16x32_bf16 v[108:111], v[120:123], v[192:195], v[108:111]
	v_mfma_f32_16x16x32_bf16 v[104:107], v[136:139], v[192:195], v[104:107]
	v_mfma_f32_16x16x32_bf16 v[92:95], v[120:123], v[202:205], v[92:95]
	v_mfma_f32_16x16x32_bf16 v[88:91], v[136:139], v[202:205], v[88:91]
	v_mfma_f32_16x16x32_bf16 v[76:79], v[120:123], v[210:213], v[76:79]
	v_mfma_f32_16x16x32_bf16 v[72:75], v[136:139], v[210:213], v[72:75]
	v_mfma_f32_16x16x32_bf16 v[128:131], v[132:135], v[180:183], v[128:131]
	v_mfma_f32_16x16x32_bf16 v[124:127], v[140:143], v[180:183], v[124:127]
	v_mfma_f32_16x16x32_bf16 v[108:111], v[132:135], v[196:199], v[108:111]
	v_mfma_f32_16x16x32_bf16 v[104:107], v[140:143], v[196:199], v[104:107]
	v_mfma_f32_16x16x32_bf16 v[92:95], v[132:135], v[206:209], v[92:95]
	v_mfma_f32_16x16x32_bf16 v[88:91], v[140:143], v[206:209], v[88:91]
	v_mfma_f32_16x16x32_bf16 v[76:79], v[132:135], v[214:217], v[76:79]
	v_mfma_f32_16x16x32_bf16 v[72:75], v[140:143], v[214:217], v[72:75]
	s_setprio 0
	s_setprio 1
	v_mfma_f32_16x16x32_bf16 v[116:119], v[144:147], v[176:179], v[116:119]
	v_mfma_f32_16x16x32_bf16 v[112:115], v[168:171], v[176:179], v[112:115]
	v_mfma_f32_16x16x32_bf16 v[100:103], v[144:147], v[192:195], v[100:103]
	v_mfma_f32_16x16x32_bf16 v[96:99], v[168:171], v[192:195], v[96:99]
	v_mfma_f32_16x16x32_bf16 v[84:87], v[144:147], v[202:205], v[84:87]
	v_mfma_f32_16x16x32_bf16 v[80:83], v[168:171], v[202:205], v[80:83]
	v_mfma_f32_16x16x32_bf16 v[68:71], v[144:147], v[210:213], v[68:71]
	v_mfma_f32_16x16x32_bf16 v[64:67], v[168:171], v[210:213], v[64:67]
	v_mfma_f32_16x16x32_bf16 v[116:119], v[148:151], v[180:183], v[116:119]
	v_mfma_f32_16x16x32_bf16 v[112:115], v[172:175], v[180:183], v[112:115]
	v_mfma_f32_16x16x32_bf16 v[100:103], v[148:151], v[196:199], v[100:103]
	v_mfma_f32_16x16x32_bf16 v[96:99], v[172:175], v[196:199], v[96:99]
	v_mfma_f32_16x16x32_bf16 v[84:87], v[148:151], v[206:209], v[84:87]
	v_mfma_f32_16x16x32_bf16 v[80:83], v[172:175], v[206:209], v[80:83]
	v_mfma_f32_16x16x32_bf16 v[68:71], v[148:151], v[214:217], v[68:71]
	v_mfma_f32_16x16x32_bf16 v[64:67], v[172:175], v[214:217], v[64:67]
	s_setprio 0
	s_barrier
; #define PG8_STAGE(bufoff, gbase, voff) do { _Pragma("unroll") for (int _i = 0; _i < 2; ++_i) \
;         __builtin_amdgcn_global_load_lds((const unsigned*)((const char*)(gbase) + (voff)[_i]), (PG8_LAS unsigned*)(lds + (bufoff) + ldsw + _i * 8192), 16, 0, 0); } while (0)
; #define PG8_LDA(dst, b, h) do { _Pragma("unroll") for (int m = 0; m < 4; ++m) _Pragma("unroll") for (int k = 0; k < 2; ++k) dst[m][k] = *(const PG8_LAS bf16x8*)(lds + PG8_SA(b, h) + aoff + m * 2048 + k * 1024); } while (0)
; #define PG8_MMA(ai, bj, At, Bt) do { __builtin_amdgcn_s_setprio(1); _Pragma("unroll") for (int m = 0; m < 4; ++m) _Pragma("unroll") for (int n = 0; n < 2; ++n) _Pragma("unroll") for (int k = 0; k < 2; ++k) \
;         acc[ai][bj][m][n] = __builtin_amdgcn_mfma_f32_16x16x32_bf16(Bt[n][k], At[m][k], acc[ai][bj][m][n], 0, 0, 0); __builtin_amdgcn_s_setprio(0); } while (0)
; #define PG8_WAIT_V(n) asm volatile("s_waitcnt vmcnt(" #n ")" ::: "memory")
; #define PG8_WAIT_L(n) asm volatile("s_waitcnt lgkmcnt(" #n ")" ::: "memory")
; #define PG8_BAR __builtin_amdgcn_s_barrier()
; #define PG8_SCHED __builtin_amdgcn_sched_barrier(0)
; template <class Epi, class Sched, bool ALIGN_EPI = false, bool SP2 = false>
; __device__ __forceinline__ void gemm_phase(PG8_LAS unsigned char* lds, const Gemm g, const Sched& S, const Epi& E, int tid_in) {
;     ...
;             PG8_LDA(At, 1, 1); PG8_STAGE(PG8_SB(1, 0), b3, voffB); PG8_STAGE(PG8_SB(1, 1), b3 + hstep, voffB); PG8_STAGE(PG8_SA(1, 0), a3, voffA);
;             PG8_WAIT_V(8); PG8_WAIT_L(0); PG8_BAR; PG8_MMA(1, 0, At, B0); PG8_MMA(1, 1, At, B1); PG8_BAR; PG8_SCHED;
;     ...
;         if constexpr (ALIGN_EPI) { if (wr == 0) PG8_BAR; }
	s_add_i32 s4, s4, s12
	v_lshl_add_u64 v[184:185], v[184:185], 0, s[26:27]
	s_mov_b32 m0, s4
	ds_read_b128 v[176:179], v191 offset:49152
	ds_read_b128 v[180:183], v191 offset:50176
	ds_read_b128 v[192:195], v191 offset:51200
	ds_read_b128 v[196:199], v191 offset:52224
	ds_read_b128 v[202:205], v191 offset:53248
	ds_read_b128 v[206:209], v191 offset:54272
	ds_read_b128 v[210:213], v191 offset:55296
	ds_read_b128 v[214:217], v191 offset:56320
	global_load_lds_dwordx4 v[184:185], off
	s_add_i32 m0, s4, 0x2000
	s_add_u32 s46, s50, 0xb0080
	v_lshl_add_u64 v[184:185], v[218:219], 0, s[26:27]
	s_addc_u32 s47, s51, 0
	s_add_i32 s4, s5, s12
	global_load_lds_dwordx4 v[184:185], off
	v_lshl_add_u64 v[184:185], s[46:47], 0, v[154:155]
	s_mov_b32 m0, s4
	s_nop 0
	global_load_lds_dwordx4 v[184:185], off
	v_lshl_add_u64 v[184:185], s[46:47], 0, v[158:159]
	s_add_i32 m0, s4, 0x2000
	s_nop 0
	global_load_lds_dwordx4 v[184:185], off
	v_lshl_add_u64 v[184:185], v[220:221], 0, s[26:27]
	s_mov_b32 m0, s55
	s_nop 0
	global_load_lds_dwordx4 v[184:185], off
	v_lshl_add_u64 v[184:185], v[222:223], 0, s[26:27]
	s_mov_b32 m0, s56
	s_nop 0
	global_load_lds_dwordx4 v[184:185], off
	s_waitcnt vmcnt(8)
	s_waitcnt lgkmcnt(0)
	s_barrier
	s_setprio 1
	s_waitcnt lgkmcnt(0)
	v_mfma_f32_16x16x32_bf16 v[60:63], v[120:123], v[176:179], v[60:63]
	v_mfma_f32_16x16x32_bf16 v[56:59], v[136:139], v[176:179], v[56:59]
	v_mfma_f32_16x16x32_bf16 v[44:47], v[120:123], v[192:195], v[44:47]
	v_mfma_f32_16x16x32_bf16 v[40:43], v[136:139], v[192:195], v[40:43]
	v_mfma_f32_16x16x32_bf16 v[28:31], v[120:123], v[202:205], v[28:31]
	v_mfma_f32_16x16x32_bf16 v[24:27], v[136:139], v[202:205], v[24:27]
	v_mfma_f32_16x16x32_bf16 v[12:15], v[120:123], v[210:213], v[12:15]
	v_mfma_f32_16x16x32_bf16 v[8:11], v[136:139], v[210:213], v[8:11]
	v_mfma_f32_16x16x32_bf16 v[60:63], v[132:135], v[180:183], v[60:63]
	v_mfma_f32_16x16x32_bf16 v[56:59], v[140:143], v[180:183], v[56:59]
	v_mfma_f32_16x16x32_bf16 v[44:47], v[132:135], v[196:199], v[44:47]
	v_mfma_f32_16x16x32_bf16 v[40:43], v[140:143], v[196:199], v[40:43]
	v_mfma_f32_16x16x32_bf16 v[28:31], v[132:135], v[206:209], v[28:31]
	v_mfma_f32_16x16x32_bf16 v[24:27], v[140:143], v[206:209], v[24:27]
	v_mfma_f32_16x16x32_bf16 v[12:15], v[132:135], v[214:217], v[12:15]
	v_mfma_f32_16x16x32_bf16 v[8:11], v[140:143], v[214:217], v[8:11]
	s_setprio 0
	s_setprio 1
	v_mfma_f32_16x16x32_bf16 v[52:55], v[144:147], v[176:179], v[52:55]
	v_mfma_f32_16x16x32_bf16 v[48:51], v[168:171], v[176:179], v[48:51]
	v_mfma_f32_16x16x32_bf16 v[36:39], v[144:147], v[192:195], v[36:39]
	v_mfma_f32_16x16x32_bf16 v[32:35], v[168:171], v[192:195], v[32:35]
	v_mfma_f32_16x16x32_bf16 v[20:23], v[144:147], v[202:205], v[20:23]
	v_mfma_f32_16x16x32_bf16 v[16:19], v[168:171], v[202:205], v[16:19]
	v_mfma_f32_16x16x32_bf16 v[4:7], v[144:147], v[210:213], v[4:7]
	v_mfma_f32_16x16x32_bf16 v[0:3], v[168:171], v[210:213], v[0:3]
	v_mfma_f32_16x16x32_bf16 v[52:55], v[148:151], v[180:183], v[52:55]
	v_mfma_f32_16x16x32_bf16 v[48:51], v[172:175], v[180:183], v[48:51]
	v_mfma_f32_16x16x32_bf16 v[36:39], v[148:151], v[196:199], v[36:39]
	v_mfma_f32_16x16x32_bf16 v[32:35], v[172:175], v[196:199], v[32:35]
	v_mfma_f32_16x16x32_bf16 v[20:23], v[148:151], v[206:209], v[20:23]
	v_mfma_f32_16x16x32_bf16 v[16:19], v[172:175], v[206:209], v[16:19]
	v_mfma_f32_16x16x32_bf16 v[4:7], v[148:151], v[214:217], v[4:7]
	v_mfma_f32_16x16x32_bf16 v[0:3], v[172:175], v[214:217], v[0:3]
	s_setprio 0
	s_barrier
	s_add_i32 s68, s68, 2
	s_add_u32 s66, s66, 0x100
	s_addc_u32 s67, s67, 0
	s_cmp_gt_u32 s68, 41
	s_mov_b64 s[46:47], s[48:49]
	s_cbranch_scc0 .LBB0_1670
.Lpost12:
	s_and_b64 vcc, exec, s[42:43]
	s_cbranch_vccz .LBB0_1673
	s_barrier

; #define PG8_STAGE(bufoff, gbase, voff) do { _Pragma("unroll") for (int _i = 0; _i < 2; ++_i) \
;         __builtin_amdgcn_global_load_lds((const unsigned*)((const char*)(gbase) + (voff)[_i]), (PG8_LAS unsigned*)(lds + (bufoff) + ldsw + _i * 8192), 16, 0, 0); } while (0)
; #define PG8_LDA(dst, b, h) do { _Pragma("unroll") for (int m = 0; m < 4; ++m) _Pragma("unroll") for (int k = 0; k < 2; ++k) dst[m][k] = *(const PG8_LAS bf16x8*)(lds + PG8_SA(b, h) + aoff + m * 2048 + k * 1024); } while (0)
; #define PG8_LDB(dst, b, h) do { _Pragma("unroll") for (int n = 0; n < 2; ++n) _Pragma("unroll") for (int k = 0; k < 2; ++k) dst[n][k] = *(const PG8_LAS bf16x8*)(lds + PG8_SB(b, h) + boff + n * 2048 + k * 1024); } while (0)
; #define PG8_MMA(ai, bj, At, Bt) do { __builtin_amdgcn_s_setprio(1); _Pragma("unroll") for (int m = 0; m < 4; ++m) _Pragma("unroll") for (int n = 0; n < 2; ++n) _Pragma("unroll") for (int k = 0; k < 2; ++k) \
;         acc[ai][bj][m][n] = __builtin_amdgcn_mfma_f32_16x16x32_bf16(Bt[n][k], At[m][k], acc[ai][bj][m][n], 0, 0, 0); __builtin_amdgcn_s_setprio(0); } while (0)
; #define PG8_WAIT_V(n) asm volatile("s_waitcnt vmcnt(" #n ")" ::: "memory")
; #define PG8_WAIT_L(n) asm volatile("s_waitcnt lgkmcnt(" #n ")" ::: "memory")
; #define PG8_BAR __builtin_amdgcn_s_barrier()
; #define PG8_SCHED __builtin_amdgcn_sched_barrier(0)
; template <class Epi, class Sched, bool ALIGN_EPI = false, bool SP2 = false>
; __device__ __forceinline__ void gemm_phase(PG8_LAS unsigned char* lds, const Gemm g, const Sched& S, const Epi& E, int tid_in) {
;     ...
;             PG8_LDB(B0, 0, 0); PG8_LDB(B1, 0, 1); PG8_SCHED; PG8_LDA(At, 0, 0); PG8_STAGE(PG8_SA(1, 1), a1 + hstep, voffA);
;             PG8_WAIT_V(8); PG8_WAIT_L(0); PG8_BAR; PG8_MMA(0, 0, At, B0); PG8_MMA(0, 1, At, B1); PG8_BAR; PG8_SCHED;
;             PG8_LDA(At, 0, 1); PG8_STAGE(PG8_SB(0, 0), b2, voffB); PG8_STAGE(PG8_SB(0, 1), b2 + hstep, voffB); PG8_STAGE(PG8_SA(0, 0), a2, voffA);
;             PG8_WAIT_V(8); PG8_WAIT_L(0); PG8_BAR; PG8_MMA(1, 0, At, B0); PG8_MMA(1, 1, At, B1); PG8_BAR; PG8_SCHED;
.Lpk12:
	s_mov_b64 s[98:99], 1
	v_lshl_add_u64 v[184:185], s[46:47], 0, v[162:163]
	s_add_i32 m0, s13, 0xc000
	ds_read_b128 v[176:179], v191
	ds_read_b128 v[180:183], v191 offset:1024
	ds_read_b128 v[192:195], v191 offset:2048
	ds_read_b128 v[196:199], v191 offset:3072
	ds_read_b128 v[202:205], v191 offset:4096
	ds_read_b128 v[206:209], v191 offset:5120
	ds_read_b128 v[210:213], v191 offset:6144
	ds_read_b128 v[214:217], v191 offset:7168
	global_load_lds_dwordx4 v[184:185], off
	v_lshl_add_u64 v[184:185], s[46:47], 0, v[160:161]
	s_add_i32 m0, s13, 0xe000
	s_nop 0
	global_load_lds_dwordx4 v[184:185], off
	s_waitcnt vmcnt(8)
	s_waitcnt lgkmcnt(0)
	s_barrier
	s_setprio 1
	s_waitcnt lgkmcnt(0)
	v_mfma_f32_16x16x32_bf16 v[128:131], v[120:123], v[176:179], v[128:131]
	v_mfma_f32_16x16x32_bf16 v[124:127], v[136:139], v[176:179], v[124:127]
	v_mfma_f32_16x16x32_bf16 v[108:111], v[120:123], v[192:195], v[108:111]
	v_mfma_f32_16x16x32_bf16 v[104:107], v[136:139], v[192:195], v[104:107]
	v_mfma_f32_16x16x32_bf16 v[92:95], v[120:123], v[202:205], v[92:95]
	v_mfma_f32_16x16x32_bf16 v[88:91], v[136:139], v[202:205], v[88:91]
	v_mfma_f32_16x16x32_bf16 v[76:79], v[120:123], v[210:213], v[76:79]
	v_mfma_f32_16x16x32_bf16 v[72:75], v[136:139], v[210:213], v[72:75]
	v_mfma_f32_16x16x32_bf16 v[128:131], v[132:135], v[180:183], v[128:131]
	v_mfma_f32_16x16x32_bf16 v[124:127], v[140:143], v[180:183], v[124:127]
	v_mfma_f32_16x16x32_bf16 v[108:111], v[132:135], v[196:199], v[108:111]
	v_mfma_f32_16x16x32_bf16 v[104:107], v[140:143], v[196:199], v[104:107]
	v_mfma_f32_16x16x32_bf16 v[92:95], v[132:135], v[206:209], v[92:95]
	v_mfma_f32_16x16x32_bf16 v[88:91], v[140:143], v[206:209], v[88:91]
	v_mfma_f32_16x16x32_bf16 v[76:79], v[132:135], v[214:217], v[76:79]
	v_mfma_f32_16x16x32_bf16 v[72:75], v[140:143], v[214:217], v[72:75]
	s_setprio 0
	s_setprio 1
	v_mfma_f32_16x16x32_bf16 v[116:119], v[144:147], v[176:179], v[116:119]
	v_mfma_f32_16x16x32_bf16 v[112:115], v[168:171], v[176:179], v[112:115]
	v_mfma_f32_16x16x32_bf16 v[100:103], v[144:147], v[192:195], v[100:103]
	v_mfma_f32_16x16x32_bf16 v[96:99], v[168:171], v[192:195], v[96:99]
	v_mfma_f32_16x16x32_bf16 v[84:87], v[144:147], v[202:205], v[84:87]
	v_mfma_f32_16x16x32_bf16 v[80:83], v[168:171], v[202:205], v[80:83]
	v_mfma_f32_16x16x32_bf16 v[68:71], v[144:147], v[210:213], v[68:71]
	v_mfma_f32_16x16x32_bf16 v[64:67], v[168:171], v[210:213], v[64:67]
	v_mfma_f32_16x16x32_bf16 v[116:119], v[148:151], v[180:183], v[116:119]
	v_mfma_f32_16x16x32_bf16 v[112:115], v[172:175], v[180:183], v[112:115]
	v_mfma_f32_16x16x32_bf16 v[100:103], v[148:151], v[196:199], v[100:103]
	v_mfma_f32_16x16x32_bf16 v[96:99], v[172:175], v[196:199], v[96:99]
	v_mfma_f32_16x16x32_bf16 v[84:87], v[148:151], v[206:209], v[84:87]
	v_mfma_f32_16x16x32_bf16 v[80:83], v[172:175], v[206:209], v[80:83]
	v_mfma_f32_16x16x32_bf16 v[68:71], v[148:151], v[214:217], v[68:71]
	v_mfma_f32_16x16x32_bf16 v[64:67], v[172:175], v[214:217], v[64:67]
	s_setprio 0
	s_barrier
	s_add_i32 s4, s60, s12
	v_lshl_add_u64 v[184:185], s[50:51], 0, v[154:155]
	s_mov_b32 m0, s4
	ds_read_b128 v[176:179], v191 offset:16384
	ds_read_b128 v[180:183], v191 offset:17408
	ds_read_b128 v[192:195], v191 offset:18432
	ds_read_b128 v[196:199], v191 offset:19456
	ds_read_b128 v[202:205], v191 offset:20480
	ds_read_b128 v[206:209], v191 offset:21504
	ds_read_b128 v[210:213], v191 offset:22528
	ds_read_b128 v[214:217], v191 offset:23552
	s_mov_b64 exec, s[98:99]
	global_load_lds_dwordx4 v[184:185], off
	s_mov_b64 exec, -1
	s_add_i32 m0, s4, 0x2000
	s_add_u32 s46, s50, 0xb0000
	v_lshl_add_u64 v[218:219], s[50:51], 0, v[158:159]
	s_addc_u32 s47, s51, 0
	s_add_i32 s4, s61, s12
	s_mov_b64 exec, s[98:99]
	global_load_lds_dwordx4 v[218:219], off
	s_mov_b64 exec, -1
	v_lshl_add_u64 v[220:221], s[46:47], 0, v[154:155]
	s_mov_b32 m0, s4
	v_lshl_add_u64 v[222:223], s[52:53], 0, v[156:157]
	s_mov_b64 exec, s[98:99]
	global_load_lds_dwordx4 v[220:221], off
	s_mov_b64 exec, -1
	v_lshl_add_u64 v[220:221], s[46:47], 0, v[158:159]
	s_add_i32 m0, s4, 0x2000
	s_nop 0
	s_mov_b64 exec, s[98:99]
	global_load_lds_dwordx4 v[220:221], off
	s_mov_b64 exec, -1
	v_lshl_add_u64 v[220:221], s[52:53], 0, v[152:153]
	s_mov_b32 m0, s13
	s_nop 0
	s_mov_b64 exec, s[98:99]
	global_load_lds_dwordx4 v[220:221], off
	s_mov_b64 exec, -1
	s_mov_b32 m0, s33
	s_nop 0
	s_mov_b64 exec, s[98:99]
	global_load_lds_dwordx4 v[222:223], off
	s_mov_b64 exec, -1
	s_waitcnt vmcnt(8)
	s_waitcnt lgkmcnt(0)
	s_barrier
; #define PG8_STAGE(bufoff, gbase, voff) do { _Pragma("unroll") for (int _i = 0; _i < 2; ++_i) \
;         __builtin_amdgcn_global_load_lds((const unsigned*)((const char*)(gbase) + (voff)[_i]), (PG8_LAS unsigned*)(lds + (bufoff) + ldsw + _i * 8192), 16, 0, 0); } while (0)
; #define PG8_LDA(dst, b, h) do { _Pragma("unroll") for (int m = 0; m < 4; ++m) _Pragma("unroll") for (int k = 0; k < 2; ++k) dst[m][k] = *(const PG8_LAS bf16x8*)(lds + PG8_SA(b, h) + aoff + m * 2048 + k * 1024); } while (0)
; #define PG8_LDB(dst, b, h) do { _Pragma("unroll") for (int n = 0; n < 2; ++n) _Pragma("unroll") for (int k = 0; k < 2; ++k) dst[n][k] = *(const PG8_LAS bf16x8*)(lds + PG8_SB(b, h) + boff + n * 2048 + k * 1024); } while (0)
; #define PG8_MMA(ai, bj, At, Bt) do { __builtin_amdgcn_s_setprio(1); _Pragma("unroll") for (int m = 0; m < 4; ++m) _Pragma("unroll") for (int n = 0; n < 2; ++n) _Pragma("unroll") for (int k = 0; k < 2; ++k) \
;         acc[ai][bj][m][n] = __builtin_amdgcn_mfma_f32_16x16x32_bf16(Bt[n][k], At[m][k], acc[ai][bj][m][n], 0, 0, 0); __builtin_amdgcn_s_setprio(0); } while (0)
; #define PG8_WAIT_V(n) asm volatile("s_waitcnt vmcnt(" #n ")" ::: "memory")
; #define PG8_WAIT_L(n) asm volatile("s_waitcnt lgkmcnt(" #n ")" ::: "memory")
; #define PG8_BAR __builtin_amdgcn_s_barrier()
; #define PG8_SCHED __builtin_amdgcn_sched_barrier(0)
; template <class Epi, class Sched, bool ALIGN_EPI = false, bool SP2 = false>
; __device__ __forceinline__ void gemm_phase(PG8_LAS unsigned char* lds, const Gemm g, const Sched& S, const Epi& E, int tid_in) {
;     ...
;             PG8_WAIT_V(8); PG8_WAIT_L(0); PG8_BAR; PG8_MMA(1, 0, At, B0); PG8_MMA(1, 1, At, B1); PG8_BAR; PG8_SCHED;
;             PG8_LDB(B0, 1, 0); PG8_LDB(B1, 1, 1); PG8_SCHED; PG8_LDA(At, 1, 0); PG8_STAGE(PG8_SA(0, 1), a2 + hstep, voffA);
;             PG8_WAIT_V(8); PG8_WAIT_L(0); PG8_BAR; PG8_MMA(0, 0, At, B0); PG8_MMA(0, 1, At, B1); PG8_BAR; PG8_SCHED;
	s_setprio 1
	s_waitcnt lgkmcnt(0)
	v_mfma_f32_16x16x32_bf16 v[60:63], v[120:123], v[176:179], v[60:63]
	v_mfma_f32_16x16x32_bf16 v[56:59], v[136:139], v[176:179], v[56:59]
	v_mfma_f32_16x16x32_bf16 v[44:47], v[120:123], v[192:195], v[44:47]
	v_mfma_f32_16x16x32_bf16 v[40:43], v[136:139], v[192:195], v[40:43]
	v_mfma_f32_16x16x32_bf16 v[28:31], v[120:123], v[202:205], v[28:31]
	v_mfma_f32_16x16x32_bf16 v[24:27], v[136:139], v[202:205], v[24:27]
	v_mfma_f32_16x16x32_bf16 v[12:15], v[120:123], v[210:213], v[12:15]
	v_mfma_f32_16x16x32_bf16 v[8:11], v[136:139], v[210:213], v[8:11]
	v_mfma_f32_16x16x32_bf16 v[60:63], v[132:135], v[180:183], v[60:63]
	v_mfma_f32_16x16x32_bf16 v[56:59], v[140:143], v[180:183], v[56:59]
	v_mfma_f32_16x16x32_bf16 v[44:47], v[132:135], v[196:199], v[44:47]
	v_mfma_f32_16x16x32_bf16 v[40:43], v[140:143], v[196:199], v[40:43]
	v_mfma_f32_16x16x32_bf16 v[28:31], v[132:135], v[206:209], v[28:31]
	v_mfma_f32_16x16x32_bf16 v[24:27], v[140:143], v[206:209], v[24:27]
	v_mfma_f32_16x16x32_bf16 v[12:15], v[132:135], v[214:217], v[12:15]
	v_mfma_f32_16x16x32_bf16 v[8:11], v[140:143], v[214:217], v[8:11]
	s_setprio 0
	s_setprio 1
	v_mfma_f32_16x16x32_bf16 v[52:55], v[144:147], v[176:179], v[52:55]
	v_mfma_f32_16x16x32_bf16 v[48:51], v[168:171], v[176:179], v[48:51]
	v_mfma_f32_16x16x32_bf16 v[36:39], v[144:147], v[192:195], v[36:39]
	v_mfma_f32_16x16x32_bf16 v[32:35], v[168:171], v[192:195], v[32:35]
	v_mfma_f32_16x16x32_bf16 v[20:23], v[144:147], v[202:205], v[20:23]
	v_mfma_f32_16x16x32_bf16 v[16:19], v[168:171], v[202:205], v[16:19]
	v_mfma_f32_16x16x32_bf16 v[4:7], v[144:147], v[210:213], v[4:7]
	v_mfma_f32_16x16x32_bf16 v[0:3], v[168:171], v[210:213], v[0:3]
	v_mfma_f32_16x16x32_bf16 v[52:55], v[148:151], v[180:183], v[52:55]
	v_mfma_f32_16x16x32_bf16 v[48:51], v[172:175], v[180:183], v[48:51]
	v_mfma_f32_16x16x32_bf16 v[36:39], v[148:151], v[196:199], v[36:39]
	v_mfma_f32_16x16x32_bf16 v[32:35], v[172:175], v[196:199], v[32:35]
	v_mfma_f32_16x16x32_bf16 v[20:23], v[148:151], v[206:209], v[20:23]
	v_mfma_f32_16x16x32_bf16 v[16:19], v[172:175], v[206:209], v[16:19]
	v_mfma_f32_16x16x32_bf16 v[4:7], v[148:151], v[214:217], v[4:7]
	v_mfma_f32_16x16x32_bf16 v[0:3], v[172:175], v[214:217], v[0:3]
	s_setprio 0
	s_barrier
	s_add_i32 s4, 0, 0x18000
	s_add_i32 s5, 0, 0x1c000
	v_add_u32_e32 v140, s4, v187
	v_add_u32_e32 v172, s5, v187
	ds_read_b128 v[120:123], v140
	ds_read_b128 v[132:135], v140 offset:1024
	ds_read_b128 v[136:139], v140 offset:2048
	ds_read_b128 v[140:143], v140 offset:3072
	ds_read_b128 v[144:147], v172
	ds_read_b128 v[148:151], v172 offset:1024
	ds_read_b128 v[168:171], v172 offset:2048
	ds_read_b128 v[172:175], v172 offset:3072
	s_add_u32 s46, s52, 0xb0000
	s_addc_u32 s47, s53, 0
	s_mov_b32 m0, s40
	v_lshl_add_u64 v[224:225], s[46:47], 0, v[152:153]
	ds_read_b128 v[176:179], v191 offset:32768
	ds_read_b128 v[180:183], v191 offset:33792
	ds_read_b128 v[192:195], v191 offset:34816
	ds_read_b128 v[196:199], v191 offset:35840
	ds_read_b128 v[202:205], v191 offset:36864
	ds_read_b128 v[206:209], v191 offset:37888
	ds_read_b128 v[210:213], v191 offset:38912
	ds_read_b128 v[214:217], v191 offset:39936
	s_mov_b64 exec, s[98:99]
	global_load_lds_dwordx4 v[224:225], off
	s_mov_b64 exec, -1
	v_lshl_add_u64 v[224:225], s[46:47], 0, v[156:157]
	s_mov_b32 m0, s41
	s_nop 0
	s_mov_b64 exec, s[98:99]
	global_load_lds_dwordx4 v[224:225], off
	s_mov_b64 exec, -1
	s_waitcnt vmcnt(8)
	s_waitcnt lgkmcnt(0)
	s_barrier
	s_setprio 1
	s_waitcnt lgkmcnt(0)
	v_mfma_f32_16x16x32_bf16 v[128:131], v[120:123], v[176:179], v[128:131]
	v_mfma_f32_16x16x32_bf16 v[124:127], v[136:139], v[176:179], v[124:127]
	v_mfma_f32_16x16x32_bf16 v[108:111], v[120:123], v[192:195], v[108:111]
	v_mfma_f32_16x16x32_bf16 v[104:107], v[136:139], v[192:195], v[104:107]
	v_mfma_f32_16x16x32_bf16 v[92:95], v[120:123], v[202:205], v[92:95]
	v_mfma_f32_16x16x32_bf16 v[88:91], v[136:139], v[202:205], v[88:91]
	v_mfma_f32_16x16x32_bf16 v[76:79], v[120:123], v[210:213], v[76:79]
	v_mfma_f32_16x16x32_bf16 v[72:75], v[136:139], v[210:213], v[72:75]
	v_mfma_f32_16x16x32_bf16 v[128:131], v[132:135], v[180:183], v[128:131]
	v_mfma_f32_16x16x32_bf16 v[124:127], v[140:143], v[180:183], v[124:127]
	v_mfma_f32_16x16x32_bf16 v[108:111], v[132:135], v[196:199], v[108:111]
	v_mfma_f32_16x16x32_bf16 v[104:107], v[140:143], v[196:199], v[104:107]
	v_mfma_f32_16x16x32_bf16 v[92:95], v[132:135], v[206:209], v[92:95]
	v_mfma_f32_16x16x32_bf16 v[88:91], v[140:143], v[206:209], v[88:91]
	v_mfma_f32_16x16x32_bf16 v[76:79], v[132:135], v[214:217], v[76:79]
	v_mfma_f32_16x16x32_bf16 v[72:75], v[140:143], v[214:217], v[72:75]
	s_setprio 0
	s_setprio 1
	v_mfma_f32_16x16x32_bf16 v[116:119], v[144:147], v[176:179], v[116:119]
	v_mfma_f32_16x16x32_bf16 v[112:115], v[168:171], v[176:179], v[112:115]
	v_mfma_f32_16x16x32_bf16 v[100:103], v[144:147], v[192:195], v[100:103]
	v_mfma_f32_16x16x32_bf16 v[96:99], v[168:171], v[192:195], v[96:99]
	v_mfma_f32_16x16x32_bf16 v[84:87], v[144:147], v[202:205], v[84:87]
	v_mfma_f32_16x16x32_bf16 v[80:83], v[168:171], v[202:205], v[80:83]
	v_mfma_f32_16x16x32_bf16 v[68:71], v[144:147], v[210:213], v[68:71]
	v_mfma_f32_16x16x32_bf16 v[64:67], v[168:171], v[210:213], v[64:67]
	v_mfma_f32_16x16x32_bf16 v[116:119], v[148:151], v[180:183], v[116:119]
	v_mfma_f32_16x16x32_bf16 v[112:115], v[172:175], v[180:183], v[112:115]
	v_mfma_f32_16x16x32_bf16 v[100:103], v[148:151], v[196:199], v[100:103]
	v_mfma_f32_16x16x32_bf16 v[96:99], v[172:175], v[196:199], v[96:99]
	v_mfma_f32_16x16x32_bf16 v[84:87], v[148:151], v[206:209], v[84:87]
	v_mfma_f32_16x16x32_bf16 v[80:83], v[172:175], v[206:209], v[80:83]
	v_mfma_f32_16x16x32_bf16 v[68:71], v[148:151], v[214:217], v[68:71]
	v_mfma_f32_16x16x32_bf16 v[64:67], v[172:175], v[214:217], v[64:67]
	s_setprio 0
	s_barrier
; #define PG8_STAGE(bufoff, gbase, voff) do { _Pragma("unroll") for (int _i = 0; _i < 2; ++_i) \
;         __builtin_amdgcn_global_load_lds((const unsigned*)((const char*)(gbase) + (voff)[_i]), (PG8_LAS unsigned*)(lds + (bufoff) + ldsw + _i * 8192), 16, 0, 0); } while (0)
; #define PG8_LDA(dst, b, h) do { _Pragma("unroll") for (int m = 0; m < 4; ++m) _Pragma("unroll") for (int k = 0; k < 2; ++k) dst[m][k] = *(const PG8_LAS bf16x8*)(lds + PG8_SA(b, h) + aoff + m * 2048 + k * 1024); } while (0)
; #define PG8_MMA(ai, bj, At, Bt) do { __builtin_amdgcn_s_setprio(1); _Pragma("unroll") for (int m = 0; m < 4; ++m) _Pragma("unroll") for (int n = 0; n < 2; ++n) _Pragma("unroll") for (int k = 0; k < 2; ++k) \
;         acc[ai][bj][m][n] = __builtin_amdgcn_mfma_f32_16x16x32_bf16(Bt[n][k], At[m][k], acc[ai][bj][m][n], 0, 0, 0); __builtin_amdgcn_s_setprio(0); } while (0)
; #define PG8_WAIT_V(n) asm volatile("s_waitcnt vmcnt(" #n ")" ::: "memory")
; #define PG8_WAIT_L(n) asm volatile("s_waitcnt lgkmcnt(" #n ")" ::: "memory")
; #define PG8_BAR __builtin_amdgcn_s_barrier()
; #define PG8_SCHED __builtin_amdgcn_sched_barrier(0)
; template <class Epi, class Sched, bool ALIGN_EPI = false, bool SP2 = false>
; __device__ __forceinline__ void gemm_phase(PG8_LAS unsigned char* lds, const Gemm g, const Sched& S, const Epi& E, int tid_in) {
;     ...
;             PG8_LDA(At, 1, 1); PG8_STAGE(PG8_SB(1, 0), b3, voffB); PG8_STAGE(PG8_SB(1, 1), b3 + hstep, voffB); PG8_STAGE(PG8_SA(1, 0), a3, voffA);
;             PG8_WAIT_V(8); PG8_WAIT_L(0); PG8_BAR; PG8_MMA(1, 0, At, B0); PG8_MMA(1, 1, At, B1); PG8_BAR; PG8_SCHED;
	s_add_i32 s4, s4, s12
	v_lshl_add_u64 v[184:185], v[184:185], 0, s[26:27]
	s_mov_b32 m0, s4
	ds_read_b128 v[176:179], v191 offset:49152
	ds_read_b128 v[180:183], v191 offset:50176
	ds_read_b128 v[192:195], v191 offset:51200
	ds_read_b128 v[196:199], v191 offset:52224
	ds_read_b128 v[202:205], v191 offset:53248
	ds_read_b128 v[206:209], v191 offset:54272
	ds_read_b128 v[210:213], v191 offset:55296
	ds_read_b128 v[214:217], v191 offset:56320
	s_mov_b64 exec, s[98:99]
	global_load_lds_dwordx4 v[184:185], off
	s_mov_b64 exec, -1
	s_add_i32 m0, s4, 0x2000
	s_add_u32 s46, s50, 0xb0080
	v_lshl_add_u64 v[184:185], v[218:219], 0, s[26:27]
	s_addc_u32 s47, s51, 0
	s_add_i32 s4, s5, s12
	s_mov_b64 exec, s[98:99]
	global_load_lds_dwordx4 v[184:185], off
	s_mov_b64 exec, -1
	v_lshl_add_u64 v[184:185], s[46:47], 0, v[154:155]
	s_mov_b32 m0, s4
	s_nop 0
	s_mov_b64 exec, s[98:99]
	global_load_lds_dwordx4 v[184:185], off
	s_mov_b64 exec, -1
	v_lshl_add_u64 v[184:185], s[46:47], 0, v[158:159]
	s_add_i32 m0, s4, 0x2000
	s_nop 0
	s_mov_b64 exec, s[98:99]
	global_load_lds_dwordx4 v[184:185], off
	s_mov_b64 exec, -1
	v_lshl_add_u64 v[184:185], v[220:221], 0, s[26:27]
	s_mov_b32 m0, s55
	s_nop 0
	s_mov_b64 exec, s[98:99]
	global_load_lds_dwordx4 v[184:185], off
	s_mov_b64 exec, -1
	v_lshl_add_u64 v[184:185], v[222:223], 0, s[26:27]
	s_mov_b32 m0, s56
	s_nop 0
	s_mov_b64 exec, s[98:99]
	global_load_lds_dwordx4 v[184:185], off
	s_mov_b64 exec, -1
	s_waitcnt vmcnt(8)
	s_waitcnt lgkmcnt(0)
	s_barrier
	s_setprio 1
	s_waitcnt lgkmcnt(0)
	v_mfma_f32_16x16x32_bf16 v[60:63], v[120:123], v[176:179], v[60:63]
	v_mfma_f32_16x16x32_bf16 v[56:59], v[136:139], v[176:179], v[56:59]
	v_mfma_f32_16x16x32_bf16 v[44:47], v[120:123], v[192:195], v[44:47]
	v_mfma_f32_16x16x32_bf16 v[40:43], v[136:139], v[192:195], v[40:43]
	v_mfma_f32_16x16x32_bf16 v[28:31], v[120:123], v[202:205], v[28:31]
	v_mfma_f32_16x16x32_bf16 v[24:27], v[136:139], v[202:205], v[24:27]
	v_mfma_f32_16x16x32_bf16 v[12:15], v[120:123], v[210:213], v[12:15]
	v_mfma_f32_16x16x32_bf16 v[8:11], v[136:139], v[210:213], v[8:11]
	v_mfma_f32_16x16x32_bf16 v[60:63], v[132:135], v[180:183], v[60:63]
	v_mfma_f32_16x16x32_bf16 v[56:59], v[140:143], v[180:183], v[56:59]
	v_mfma_f32_16x16x32_bf16 v[44:47], v[132:135], v[196:199], v[44:47]
	v_mfma_f32_16x16x32_bf16 v[40:43], v[140:143], v[196:199], v[40:43]
	v_mfma_f32_16x16x32_bf16 v[28:31], v[132:135], v[206:209], v[28:31]
	v_mfma_f32_16x16x32_bf16 v[24:27], v[140:143], v[206:209], v[24:27]
	v_mfma_f32_16x16x32_bf16 v[12:15], v[132:135], v[214:217], v[12:15]
	v_mfma_f32_16x16x32_bf16 v[8:11], v[140:143], v[214:217], v[8:11]
	s_setprio 0
	s_setprio 1
	v_mfma_f32_16x16x32_bf16 v[52:55], v[144:147], v[176:179], v[52:55]
	v_mfma_f32_16x16x32_bf16 v[48:51], v[168:171], v[176:179], v[48:51]
	v_mfma_f32_16x16x32_bf16 v[36:39], v[144:147], v[192:195], v[36:39]
	v_mfma_f32_16x16x32_bf16 v[32:35], v[168:171], v[192:195], v[32:35]
	v_mfma_f32_16x16x32_bf16 v[20:23], v[144:147], v[202:205], v[20:23]
	v_mfma_f32_16x16x32_bf16 v[16:19], v[168:171], v[202:205], v[16:19]
	v_mfma_f32_16x16x32_bf16 v[4:7], v[144:147], v[210:213], v[4:7]
	v_mfma_f32_16x16x32_bf16 v[0:3], v[168:171], v[210:213], v[0:3]
	v_mfma_f32_16x16x32_bf16 v[52:55], v[148:151], v[180:183], v[52:55]
	v_mfma_f32_16x16x32_bf16 v[48:51], v[172:175], v[180:183], v[48:51]
	v_mfma_f32_16x16x32_bf16 v[36:39], v[148:151], v[196:199], v[36:39]
	v_mfma_f32_16x16x32_bf16 v[32:35], v[172:175], v[196:199], v[32:35]
	v_mfma_f32_16x16x32_bf16 v[20:23], v[148:151], v[206:209], v[20:23]
	v_mfma_f32_16x16x32_bf16 v[16:19], v[172:175], v[206:209], v[16:19]
	v_mfma_f32_16x16x32_bf16 v[4:7], v[148:151], v[214:217], v[4:7]
	v_mfma_f32_16x16x32_bf16 v[0:3], v[172:175], v[214:217], v[0:3]
	s_setprio 0
	s_barrier
	s_add_i32 s68, s68, 2
	s_add_u32 s66, s66, 0x100
	s_addc_u32 s67, s67, 0
	s_cmp_gt_u32 s68, 41
	s_mov_b64 s[46:47], s[48:49]
	s_branch .Lpost12

; #define PG8_STAGE(bufoff, gbase, voff) do { _Pragma("unroll") for (int _i = 0; _i < 2; ++_i) \
;         __builtin_amdgcn_global_load_lds((const unsigned*)((const char*)(gbase) + (voff)[_i]), (PG8_LAS unsigned*)(lds + (bufoff) + ldsw + _i * 8192), 16, 0, 0); } while (0)
; #define PG8_LDA(dst, b, h) do { _Pragma("unroll") for (int m = 0; m < 4; ++m) _Pragma("unroll") for (int k = 0; k < 2; ++k) dst[m][k] = *(const PG8_LAS bf16x8*)(lds + PG8_SA(b, h) + aoff + m * 2048 + k * 1024); } while (0)
; #define PG8_LDB(dst, b, h) do { _Pragma("unroll") for (int n = 0; n < 2; ++n) _Pragma("unroll") for (int k = 0; k < 2; ++k) dst[n][k] = *(const PG8_LAS bf16x8*)(lds + PG8_SB(b, h) + boff + n * 2048 + k * 1024); } while (0)
; #define PG8_MMA(ai, bj, At, Bt) do { __builtin_amdgcn_s_setprio(1); _Pragma("unroll") for (int m = 0; m < 4; ++m) _Pragma("unroll") for (int n = 0; n < 2; ++n) _Pragma("unroll") for (int k = 0; k < 2; ++k) \
;         acc[ai][bj][m][n] = __builtin_amdgcn_mfma_f32_16x16x32_bf16(Bt[n][k], At[m][k], acc[ai][bj][m][n], 0, 0, 0); __builtin_amdgcn_s_setprio(0); } while (0)
; #define PG8_WAIT_V(n) asm volatile("s_waitcnt vmcnt(" #n ")" ::: "memory")
; #define PG8_BAR __builtin_amdgcn_s_barrier()
; template <class Epi, class Sched, bool ALIGN_EPI = false, bool SP2 = false>
; __device__ __forceinline__ void gemm_phase(PG8_LAS unsigned char* lds, const Gemm g, const Sched& S, const Epi& E, int tid_in) {
;     ...
;         for (int t = 0; t < nt; t += 2) {
;             const bool last = (t == nt - 2);
;             const char* a1 = cA + (size_t)(t + 1) * kstep;
;             const char* a2 = last ? nA : cA + (size_t)(t + 2) * kstep; const char* b2 = last ? nB : cB + (size_t)(t + 2) * kstep;
;             const char* a3 = a2 + kstep; const char* b3 = b2 + kstep;
;             if (last && has_next) S.a_ready(nxt);
;             if constexpr (SP2) {
;             PG8_LDB(B0, 0, 0); PG8_LDB(B1, 0, 1); PG8_SCHED; PG8_LDA(At, 0, 0); PG8_STAGE(PG8_SA(1, 1), a1 + hstep, voffA);
;             PG8_WAIT_V(8); PG8_WAIT_L(0); PG8_BAR; PG8_MMA(0, 0, At, B0); PG8_MMA(0, 1, At, B1); PG8_BAR; PG8_SCHED;
;             PG8_LDA(At, 0, 1); PG8_STAGE(PG8_SB(0, 0), b2, voffB); PG8_STAGE(PG8_SB(0, 1), b2 + hstep, voffB); PG8_STAGE(PG8_SA(0, 0), a2, voffA);
;             PG8_WAIT_V(8); PG8_WAIT_L(0); PG8_BAR; PG8_MMA(1, 0, At, B0); PG8_MMA(1, 1, At, B1); PG8_BAR; PG8_SCHED;
.LBB0_1756:
	ds_read_b128 v[146:149], v180
	ds_read_b128 v[150:153], v180 offset:1024
	ds_read_b128 v[154:157], v180 offset:2048
	ds_read_b128 v[158:161], v180 offset:3072
	ds_read_b128 v[162:165], v181
	ds_read_b128 v[166:169], v181 offset:1024
	ds_read_b128 v[170:173], v181 offset:2048
	ds_read_b128 v[186:189], v181 offset:3072
	s_add_u32 s4, s46, 0xfffc0080
	s_addc_u32 s5, s47, -1
	s_cmp_eq_u32 s72, 12
	s_cselect_b32 s51, s9, s5
	s_cselect_b32 s50, s25, s4
	s_cselect_b32 s49, s23, s71
	s_cselect_b32 s48, s69, s70
	s_cbranch_scc1 .Lpk13
	v_lshl_add_u64 v[198:199], s[46:47], 0, v[140:141]
	s_add_i32 m0, s40, 0xc000
	ds_read_b128 v[190:193], v182
	ds_read_b128 v[194:197], v182 offset:1024
	ds_read_b128 v[202:205], v182 offset:2048
	ds_read_b128 v[206:209], v182 offset:3072
	ds_read_b128 v[210:213], v182 offset:4096
	ds_read_b128 v[214:217], v182 offset:5120
	ds_read_b128 v[218:221], v182 offset:6144
	ds_read_b128 v[222:225], v182 offset:7168
	global_load_lds_dwordx4 v[198:199], off
	v_lshl_add_u64 v[198:199], s[46:47], 0, v[138:139]
	s_add_i32 m0, s40, 0xe000
	s_nop 0
	global_load_lds_dwordx4 v[198:199], off
	s_waitcnt vmcnt(8)
	s_waitcnt lgkmcnt(0)
	s_barrier
	s_setprio 1
	s_waitcnt lgkmcnt(0)
	v_mfma_f32_16x16x32_bf16 v[124:127], v[146:149], v[190:193], v[124:127]
	v_mfma_f32_16x16x32_bf16 v[120:123], v[154:157], v[190:193], v[120:123]
	v_mfma_f32_16x16x32_bf16 v[108:111], v[146:149], v[202:205], v[108:111]
	v_mfma_f32_16x16x32_bf16 v[104:107], v[154:157], v[202:205], v[104:107]
	v_mfma_f32_16x16x32_bf16 v[92:95], v[146:149], v[210:213], v[92:95]
	v_mfma_f32_16x16x32_bf16 v[88:91], v[154:157], v[210:213], v[88:91]
	v_mfma_f32_16x16x32_bf16 v[76:79], v[146:149], v[218:221], v[76:79]
	v_mfma_f32_16x16x32_bf16 v[72:75], v[154:157], v[218:221], v[72:75]
	v_mfma_f32_16x16x32_bf16 v[124:127], v[150:153], v[194:197], v[124:127]
	v_mfma_f32_16x16x32_bf16 v[120:123], v[158:161], v[194:197], v[120:123]
	v_mfma_f32_16x16x32_bf16 v[108:111], v[150:153], v[206:209], v[108:111]
	v_mfma_f32_16x16x32_bf16 v[104:107], v[158:161], v[206:209], v[104:107]
	v_mfma_f32_16x16x32_bf16 v[92:95], v[150:153], v[214:217], v[92:95]
	v_mfma_f32_16x16x32_bf16 v[88:91], v[158:161], v[214:217], v[88:91]
	v_mfma_f32_16x16x32_bf16 v[76:79], v[150:153], v[222:225], v[76:79]
	v_mfma_f32_16x16x32_bf16 v[72:75], v[158:161], v[222:225], v[72:75]
	s_setprio 0
	s_setprio 1
	v_mfma_f32_16x16x32_bf16 v[116:119], v[162:165], v[190:193], v[116:119]
	v_mfma_f32_16x16x32_bf16 v[112:115], v[170:173], v[190:193], v[112:115]
	v_mfma_f32_16x16x32_bf16 v[100:103], v[162:165], v[202:205], v[100:103]
	v_mfma_f32_16x16x32_bf16 v[96:99], v[170:173], v[202:205], v[96:99]
	v_mfma_f32_16x16x32_bf16 v[84:87], v[162:165], v[210:213], v[84:87]
	v_mfma_f32_16x16x32_bf16 v[80:83], v[170:173], v[210:213], v[80:83]
	v_mfma_f32_16x16x32_bf16 v[68:71], v[162:165], v[218:221], v[68:71]
	v_mfma_f32_16x16x32_bf16 v[64:67], v[170:173], v[218:221], v[64:67]
	v_mfma_f32_16x16x32_bf16 v[116:119], v[166:169], v[194:197], v[116:119]
	v_mfma_f32_16x16x32_bf16 v[112:115], v[186:189], v[194:197], v[112:115]
	v_mfma_f32_16x16x32_bf16 v[100:103], v[166:169], v[206:209], v[100:103]
	v_mfma_f32_16x16x32_bf16 v[96:99], v[186:189], v[206:209], v[96:99]
	v_mfma_f32_16x16x32_bf16 v[84:87], v[166:169], v[214:217], v[84:87]
	v_mfma_f32_16x16x32_bf16 v[80:83], v[186:189], v[214:217], v[80:83]
	v_mfma_f32_16x16x32_bf16 v[68:71], v[166:169], v[222:225], v[68:71]
	v_mfma_f32_16x16x32_bf16 v[64:67], v[186:189], v[222:225], v[64:67]
	s_setprio 0
	s_barrier
	s_add_i32 s4, s66, s33
	v_lshl_add_u64 v[198:199], s[48:49], 0, v[130:131]
	s_mov_b32 m0, s4
	ds_read_b128 v[190:193], v182 offset:16384
	ds_read_b128 v[194:197], v182 offset:17408
	ds_read_b128 v[202:205], v182 offset:18432
	ds_read_b128 v[206:209], v182 offset:19456
	ds_read_b128 v[210:213], v182 offset:20480
	ds_read_b128 v[214:217], v182 offset:21504
	ds_read_b128 v[218:221], v182 offset:22528
	ds_read_b128 v[222:225], v182 offset:23552
	global_load_lds_dwordx4 v[198:199], off
	s_add_i32 m0, s4, 0x2000
	s_add_u32 s78, s48, 0x40000
	v_lshl_add_u64 v[226:227], s[48:49], 0, v[134:135]
	s_addc_u32 s79, s49, 0
	s_add_i32 s4, s67, s33
	global_load_lds_dwordx4 v[226:227], off
	v_lshl_add_u64 v[228:229], s[78:79], 0, v[130:131]
	s_mov_b32 m0, s4
	v_lshl_add_u64 v[230:231], s[50:51], 0, v[132:133]
	global_load_lds_dwordx4 v[228:229], off
	v_lshl_add_u64 v[228:229], s[78:79], 0, v[134:135]
	s_add_i32 m0, s4, 0x2000
	s_nop 0
	global_load_lds_dwordx4 v[228:229], off
	v_lshl_add_u64 v[228:229], s[50:51], 0, v[128:129]
	s_mov_b32 m0, s40
	s_nop 0
	global_load_lds_dwordx4 v[228:229], off
	s_mov_b32 m0, s41
	s_nop 0
	global_load_lds_dwordx4 v[230:231], off
	s_waitcnt vmcnt(8)
	s_waitcnt lgkmcnt(0)
	s_barrier
; #define PG8_STAGE(bufoff, gbase, voff) do { _Pragma("unroll") for (int _i = 0; _i < 2; ++_i) \
;         __builtin_amdgcn_global_load_lds((const unsigned*)((const char*)(gbase) + (voff)[_i]), (PG8_LAS unsigned*)(lds + (bufoff) + ldsw + _i * 8192), 16, 0, 0); } while (0)
; #define PG8_LDA(dst, b, h) do { _Pragma("unroll") for (int m = 0; m < 4; ++m) _Pragma("unroll") for (int k = 0; k < 2; ++k) dst[m][k] = *(const PG8_LAS bf16x8*)(lds + PG8_SA(b, h) + aoff + m * 2048 + k * 1024); } while (0)
; #define PG8_LDB(dst, b, h) do { _Pragma("unroll") for (int n = 0; n < 2; ++n) _Pragma("unroll") for (int k = 0; k < 2; ++k) dst[n][k] = *(const PG8_LAS bf16x8*)(lds + PG8_SB(b, h) + boff + n * 2048 + k * 1024); } while (0)
; #define PG8_MMA(ai, bj, At, Bt) do { __builtin_amdgcn_s_setprio(1); _Pragma("unroll") for (int m = 0; m < 4; ++m) _Pragma("unroll") for (int n = 0; n < 2; ++n) _Pragma("unroll") for (int k = 0; k < 2; ++k) \
;         acc[ai][bj][m][n] = __builtin_amdgcn_mfma_f32_16x16x32_bf16(Bt[n][k], At[m][k], acc[ai][bj][m][n], 0, 0, 0); __builtin_amdgcn_s_setprio(0); } while (0)
; #define PG8_WAIT_V(n) asm volatile("s_waitcnt vmcnt(" #n ")" ::: "memory")
; #define PG8_WAIT_L(n) asm volatile("s_waitcnt lgkmcnt(" #n ")" ::: "memory")
; #define PG8_BAR __builtin_amdgcn_s_barrier()
; #define PG8_SCHED __builtin_amdgcn_sched_barrier(0)
; template <class Epi, class Sched, bool ALIGN_EPI = false, bool SP2 = false>
; __device__ __forceinline__ void gemm_phase(PG8_LAS unsigned char* lds, const Gemm g, const Sched& S, const Epi& E, int tid_in) {
;     ...
;             PG8_WAIT_V(8); PG8_WAIT_L(0); PG8_BAR; PG8_MMA(1, 0, At, B0); PG8_MMA(1, 1, At, B1); PG8_BAR; PG8_SCHED;
;             PG8_LDB(B0, 1, 0); PG8_LDB(B1, 1, 1); PG8_SCHED; PG8_LDA(At, 1, 0); PG8_STAGE(PG8_SA(0, 1), a2 + hstep, voffA);
;             PG8_WAIT_V(8); PG8_WAIT_L(0); PG8_BAR; PG8_MMA(0, 0, At, B0); PG8_MMA(0, 1, At, B1); PG8_BAR; PG8_SCHED;
	s_setprio 1
	s_waitcnt lgkmcnt(0)
	v_mfma_f32_16x16x32_bf16 v[60:63], v[146:149], v[190:193], v[60:63]
	v_mfma_f32_16x16x32_bf16 v[56:59], v[154:157], v[190:193], v[56:59]
	v_mfma_f32_16x16x32_bf16 v[44:47], v[146:149], v[202:205], v[44:47]
	v_mfma_f32_16x16x32_bf16 v[40:43], v[154:157], v[202:205], v[40:43]
	v_mfma_f32_16x16x32_bf16 v[28:31], v[146:149], v[210:213], v[28:31]
	v_mfma_f32_16x16x32_bf16 v[24:27], v[154:157], v[210:213], v[24:27]
	v_mfma_f32_16x16x32_bf16 v[12:15], v[146:149], v[218:221], v[12:15]
	v_mfma_f32_16x16x32_bf16 v[8:11], v[154:157], v[218:221], v[8:11]
	v_mfma_f32_16x16x32_bf16 v[60:63], v[150:153], v[194:197], v[60:63]
	v_mfma_f32_16x16x32_bf16 v[56:59], v[158:161], v[194:197], v[56:59]
	v_mfma_f32_16x16x32_bf16 v[44:47], v[150:153], v[206:209], v[44:47]
	v_mfma_f32_16x16x32_bf16 v[40:43], v[158:161], v[206:209], v[40:43]
	v_mfma_f32_16x16x32_bf16 v[28:31], v[150:153], v[214:217], v[28:31]
	v_mfma_f32_16x16x32_bf16 v[24:27], v[158:161], v[214:217], v[24:27]
	v_mfma_f32_16x16x32_bf16 v[12:15], v[150:153], v[222:225], v[12:15]
	v_mfma_f32_16x16x32_bf16 v[8:11], v[158:161], v[222:225], v[8:11]
	s_setprio 0
	s_setprio 1
	v_mfma_f32_16x16x32_bf16 v[52:55], v[162:165], v[190:193], v[52:55]
	v_mfma_f32_16x16x32_bf16 v[48:51], v[170:173], v[190:193], v[48:51]
	v_mfma_f32_16x16x32_bf16 v[36:39], v[162:165], v[202:205], v[36:39]
	v_mfma_f32_16x16x32_bf16 v[32:35], v[170:173], v[202:205], v[32:35]
	v_mfma_f32_16x16x32_bf16 v[20:23], v[162:165], v[210:213], v[20:23]
	v_mfma_f32_16x16x32_bf16 v[16:19], v[170:173], v[210:213], v[16:19]
	v_mfma_f32_16x16x32_bf16 v[4:7], v[162:165], v[218:221], v[4:7]
	v_mfma_f32_16x16x32_bf16 v[0:3], v[170:173], v[218:221], v[0:3]
	v_mfma_f32_16x16x32_bf16 v[52:55], v[166:169], v[194:197], v[52:55]
	v_mfma_f32_16x16x32_bf16 v[48:51], v[186:189], v[194:197], v[48:51]
	v_mfma_f32_16x16x32_bf16 v[36:39], v[166:169], v[206:209], v[36:39]
	v_mfma_f32_16x16x32_bf16 v[32:35], v[186:189], v[206:209], v[32:35]
	v_mfma_f32_16x16x32_bf16 v[20:23], v[166:169], v[214:217], v[20:23]
	v_mfma_f32_16x16x32_bf16 v[16:19], v[186:189], v[214:217], v[16:19]
	v_mfma_f32_16x16x32_bf16 v[4:7], v[166:169], v[222:225], v[4:7]
	v_mfma_f32_16x16x32_bf16 v[0:3], v[186:189], v[222:225], v[0:3]
	s_setprio 0
	s_barrier
	s_add_i32 s4, 0, 0x18000
	s_add_i32 s5, 0, 0x1c000
	v_add_u32_e32 v158, s4, v175
	v_add_u32_e32 v186, s5, v175
	ds_read_b128 v[146:149], v158
	ds_read_b128 v[150:153], v158 offset:1024
	ds_read_b128 v[154:157], v158 offset:2048
	ds_read_b128 v[158:161], v158 offset:3072
	ds_read_b128 v[162:165], v186
	ds_read_b128 v[166:169], v186 offset:1024
	ds_read_b128 v[170:173], v186 offset:2048
	ds_read_b128 v[186:189], v186 offset:3072
	s_add_u32 s50, s50, 0x40000
	s_addc_u32 s51, s51, 0
	s_mov_b32 m0, s45
	v_lshl_add_u64 v[232:233], s[50:51], 0, v[128:129]
	ds_read_b128 v[190:193], v182 offset:32768
	ds_read_b128 v[194:197], v182 offset:33792
	ds_read_b128 v[202:205], v182 offset:34816
	ds_read_b128 v[206:209], v182 offset:35840
	ds_read_b128 v[210:213], v182 offset:36864
	ds_read_b128 v[214:217], v182 offset:37888
	ds_read_b128 v[218:221], v182 offset:38912
	ds_read_b128 v[222:225], v182 offset:39936
	global_load_lds_dwordx4 v[232:233], off
	v_lshl_add_u64 v[232:233], s[50:51], 0, v[132:133]
	s_mov_b32 m0, s52
	s_nop 0
	global_load_lds_dwordx4 v[232:233], off
	s_waitcnt vmcnt(8)
	s_waitcnt lgkmcnt(0)
	s_barrier
	s_setprio 1
	s_waitcnt lgkmcnt(0)
	v_mfma_f32_16x16x32_bf16 v[124:127], v[146:149], v[190:193], v[124:127]
	v_mfma_f32_16x16x32_bf16 v[120:123], v[154:157], v[190:193], v[120:123]
	v_mfma_f32_16x16x32_bf16 v[108:111], v[146:149], v[202:205], v[108:111]
	v_mfma_f32_16x16x32_bf16 v[104:107], v[154:157], v[202:205], v[104:107]
	v_mfma_f32_16x16x32_bf16 v[92:95], v[146:149], v[210:213], v[92:95]
	v_mfma_f32_16x16x32_bf16 v[88:91], v[154:157], v[210:213], v[88:91]
	v_mfma_f32_16x16x32_bf16 v[76:79], v[146:149], v[218:221], v[76:79]
	v_mfma_f32_16x16x32_bf16 v[72:75], v[154:157], v[218:221], v[72:75]
	v_mfma_f32_16x16x32_bf16 v[124:127], v[150:153], v[194:197], v[124:127]
	v_mfma_f32_16x16x32_bf16 v[120:123], v[158:161], v[194:197], v[120:123]
	v_mfma_f32_16x16x32_bf16 v[108:111], v[150:153], v[206:209], v[108:111]
	v_mfma_f32_16x16x32_bf16 v[104:107], v[158:161], v[206:209], v[104:107]
	v_mfma_f32_16x16x32_bf16 v[92:95], v[150:153], v[214:217], v[92:95]
	v_mfma_f32_16x16x32_bf16 v[88:91], v[158:161], v[214:217], v[88:91]
	v_mfma_f32_16x16x32_bf16 v[76:79], v[150:153], v[222:225], v[76:79]
	v_mfma_f32_16x16x32_bf16 v[72:75], v[158:161], v[222:225], v[72:75]
	s_setprio 0
	s_setprio 1
	v_mfma_f32_16x16x32_bf16 v[116:119], v[162:165], v[190:193], v[116:119]
	v_mfma_f32_16x16x32_bf16 v[112:115], v[170:173], v[190:193], v[112:115]
	v_mfma_f32_16x16x32_bf16 v[100:103], v[162:165], v[202:205], v[100:103]
	v_mfma_f32_16x16x32_bf16 v[96:99], v[170:173], v[202:205], v[96:99]
	v_mfma_f32_16x16x32_bf16 v[84:87], v[162:165], v[210:213], v[84:87]
	v_mfma_f32_16x16x32_bf16 v[80:83], v[170:173], v[210:213], v[80:83]
	v_mfma_f32_16x16x32_bf16 v[68:71], v[162:165], v[218:221], v[68:71]
	v_mfma_f32_16x16x32_bf16 v[64:67], v[170:173], v[218:221], v[64:67]
	v_mfma_f32_16x16x32_bf16 v[116:119], v[166:169], v[194:197], v[116:119]
	v_mfma_f32_16x16x32_bf16 v[112:115], v[186:189], v[194:197], v[112:115]
	v_mfma_f32_16x16x32_bf16 v[100:103], v[166:169], v[206:209], v[100:103]
	v_mfma_f32_16x16x32_bf16 v[96:99], v[186:189], v[206:209], v[96:99]
	v_mfma_f32_16x16x32_bf16 v[84:87], v[166:169], v[214:217], v[84:87]
	v_mfma_f32_16x16x32_bf16 v[80:83], v[186:189], v[214:217], v[80:83]
	v_mfma_f32_16x16x32_bf16 v[68:71], v[166:169], v[222:225], v[68:71]
	v_mfma_f32_16x16x32_bf16 v[64:67], v[186:189], v[222:225], v[64:67]
	s_setprio 0
	s_barrier
; #define PG8_STAGE(bufoff, gbase, voff) do { _Pragma("unroll") for (int _i = 0; _i < 2; ++_i) \
;         __builtin_amdgcn_global_load_lds((const unsigned*)((const char*)(gbase) + (voff)[_i]), (PG8_LAS unsigned*)(lds + (bufoff) + ldsw + _i * 8192), 16, 0, 0); } while (0)
; #define PG8_LDA(dst, b, h) do { _Pragma("unroll") for (int m = 0; m < 4; ++m) _Pragma("unroll") for (int k = 0; k < 2; ++k) dst[m][k] = *(const PG8_LAS bf16x8*)(lds + PG8_SA(b, h) + aoff + m * 2048 + k * 1024); } while (0)
; #define PG8_MMA(ai, bj, At, Bt) do { __builtin_amdgcn_s_setprio(1); _Pragma("unroll") for (int m = 0; m < 4; ++m) _Pragma("unroll") for (int n = 0; n < 2; ++n) _Pragma("unroll") for (int k = 0; k < 2; ++k) \
;         acc[ai][bj][m][n] = __builtin_amdgcn_mfma_f32_16x16x32_bf16(Bt[n][k], At[m][k], acc[ai][bj][m][n], 0, 0, 0); __builtin_amdgcn_s_setprio(0); } while (0)
; #define PG8_WAIT_V(n) asm volatile("s_waitcnt vmcnt(" #n ")" ::: "memory")
; #define PG8_WAIT_L(n) asm volatile("s_waitcnt lgkmcnt(" #n ")" ::: "memory")
; #define PG8_BAR __builtin_amdgcn_s_barrier()
; #define PG8_SCHED __builtin_amdgcn_sched_barrier(0)
; template <class Epi, class Sched, bool ALIGN_EPI = false, bool SP2 = false>
; __device__ __forceinline__ void gemm_phase(PG8_LAS unsigned char* lds, const Gemm g, const Sched& S, const Epi& E, int tid_in) {
;     ...
;         for (int t = 0; t < nt; t += 2) {
;             const bool last = (t == nt - 2);
;             const char* a1 = cA + (size_t)(t + 1) * kstep;
;             const char* a2 = last ? nA : cA + (size_t)(t + 2) * kstep; const char* b2 = last ? nB : cB + (size_t)(t + 2) * kstep;
;     ...
;             PG8_LDA(At, 1, 1); PG8_STAGE(PG8_SB(1, 0), b3, voffB); PG8_STAGE(PG8_SB(1, 1), b3 + hstep, voffB); PG8_STAGE(PG8_SA(1, 0), a3, voffA);
;             PG8_WAIT_V(8); PG8_WAIT_L(0); PG8_BAR; PG8_MMA(1, 0, At, B0); PG8_MMA(1, 1, At, B1); PG8_BAR; PG8_SCHED;
	s_add_i32 s4, s4, s33
	v_lshl_add_u64 v[198:199], v[198:199], 0, s[16:17]
	s_mov_b32 m0, s4
	ds_read_b128 v[190:193], v182 offset:49152
	ds_read_b128 v[194:197], v182 offset:50176
	ds_read_b128 v[202:205], v182 offset:51200
	ds_read_b128 v[206:209], v182 offset:52224
	ds_read_b128 v[210:213], v182 offset:53248
	ds_read_b128 v[214:217], v182 offset:54272
	ds_read_b128 v[218:221], v182 offset:55296
	ds_read_b128 v[222:225], v182 offset:56320
	global_load_lds_dwordx4 v[198:199], off
	s_add_i32 m0, s4, 0x2000
	s_add_u32 s48, s48, 0x40080
	v_lshl_add_u64 v[198:199], v[226:227], 0, s[16:17]
	s_addc_u32 s49, s49, 0
	s_add_i32 s4, s5, s33
	global_load_lds_dwordx4 v[198:199], off
	v_lshl_add_u64 v[198:199], s[48:49], 0, v[130:131]
	s_mov_b32 m0, s4
	s_nop 0
	global_load_lds_dwordx4 v[198:199], off
	v_lshl_add_u64 v[198:199], s[48:49], 0, v[134:135]
	s_add_i32 m0, s4, 0x2000
	s_nop 0
	global_load_lds_dwordx4 v[198:199], off
	v_lshl_add_u64 v[198:199], v[228:229], 0, s[16:17]
	s_mov_b32 m0, s61
	s_nop 0
	global_load_lds_dwordx4 v[198:199], off
	v_lshl_add_u64 v[198:199], v[230:231], 0, s[16:17]
	s_mov_b32 m0, s62
	s_nop 0
	global_load_lds_dwordx4 v[198:199], off
	s_waitcnt vmcnt(8)
	s_waitcnt lgkmcnt(0)
	s_barrier
	s_setprio 1
	s_waitcnt lgkmcnt(0)
	v_mfma_f32_16x16x32_bf16 v[60:63], v[146:149], v[190:193], v[60:63]
	v_mfma_f32_16x16x32_bf16 v[56:59], v[154:157], v[190:193], v[56:59]
	v_mfma_f32_16x16x32_bf16 v[44:47], v[146:149], v[202:205], v[44:47]
	v_mfma_f32_16x16x32_bf16 v[40:43], v[154:157], v[202:205], v[40:43]
	v_mfma_f32_16x16x32_bf16 v[28:31], v[146:149], v[210:213], v[28:31]
	v_mfma_f32_16x16x32_bf16 v[24:27], v[154:157], v[210:213], v[24:27]
	v_mfma_f32_16x16x32_bf16 v[12:15], v[146:149], v[218:221], v[12:15]
	v_mfma_f32_16x16x32_bf16 v[8:11], v[154:157], v[218:221], v[8:11]
	v_mfma_f32_16x16x32_bf16 v[60:63], v[150:153], v[194:197], v[60:63]
	v_mfma_f32_16x16x32_bf16 v[56:59], v[158:161], v[194:197], v[56:59]
	v_mfma_f32_16x16x32_bf16 v[44:47], v[150:153], v[206:209], v[44:47]
	v_mfma_f32_16x16x32_bf16 v[40:43], v[158:161], v[206:209], v[40:43]
	v_mfma_f32_16x16x32_bf16 v[28:31], v[150:153], v[214:217], v[28:31]
	v_mfma_f32_16x16x32_bf16 v[24:27], v[158:161], v[214:217], v[24:27]
	v_mfma_f32_16x16x32_bf16 v[12:15], v[150:153], v[222:225], v[12:15]
	v_mfma_f32_16x16x32_bf16 v[8:11], v[158:161], v[222:225], v[8:11]
	s_setprio 0
	s_setprio 1
	v_mfma_f32_16x16x32_bf16 v[52:55], v[162:165], v[190:193], v[52:55]
	v_mfma_f32_16x16x32_bf16 v[48:51], v[170:173], v[190:193], v[48:51]
	v_mfma_f32_16x16x32_bf16 v[36:39], v[162:165], v[202:205], v[36:39]
	v_mfma_f32_16x16x32_bf16 v[32:35], v[170:173], v[202:205], v[32:35]
	v_mfma_f32_16x16x32_bf16 v[20:23], v[162:165], v[210:213], v[20:23]
	v_mfma_f32_16x16x32_bf16 v[16:19], v[170:173], v[210:213], v[16:19]
	v_mfma_f32_16x16x32_bf16 v[4:7], v[162:165], v[218:221], v[4:7]
	v_mfma_f32_16x16x32_bf16 v[0:3], v[170:173], v[218:221], v[0:3]
	v_mfma_f32_16x16x32_bf16 v[52:55], v[166:169], v[194:197], v[52:55]
	v_mfma_f32_16x16x32_bf16 v[48:51], v[186:189], v[194:197], v[48:51]
	v_mfma_f32_16x16x32_bf16 v[36:39], v[166:169], v[206:209], v[36:39]
	v_mfma_f32_16x16x32_bf16 v[32:35], v[186:189], v[206:209], v[32:35]
	v_mfma_f32_16x16x32_bf16 v[20:23], v[166:169], v[214:217], v[20:23]
	v_mfma_f32_16x16x32_bf16 v[16:19], v[186:189], v[214:217], v[16:19]
	v_mfma_f32_16x16x32_bf16 v[4:7], v[166:169], v[222:225], v[4:7]
	v_mfma_f32_16x16x32_bf16 v[0:3], v[186:189], v[222:225], v[0:3]
	s_setprio 0
	s_barrier
	s_add_i32 s72, s72, 2
	s_add_u32 s70, s70, 0x100
	s_addc_u32 s71, s71, 0
	s_add_u32 s46, s46, 0x100
	s_addc_u32 s47, s47, 0
	s_cmp_gt_u32 s72, 13
	s_cbranch_scc0 .LBB0_1756

; #define PG8_STAGE(bufoff, gbase, voff) do { _Pragma("unroll") for (int _i = 0; _i < 2; ++_i) \
;         __builtin_amdgcn_global_load_lds((const unsigned*)((const char*)(gbase) + (voff)[_i]), (PG8_LAS unsigned*)(lds + (bufoff) + ldsw + _i * 8192), 16, 0, 0); } while (0)
; #define PG8_LDA(dst, b, h) do { _Pragma("unroll") for (int m = 0; m < 4; ++m) _Pragma("unroll") for (int k = 0; k < 2; ++k) dst[m][k] = *(const PG8_LAS bf16x8*)(lds + PG8_SA(b, h) + aoff + m * 2048 + k * 1024); } while (0)
; #define PG8_LDB(dst, b, h) do { _Pragma("unroll") for (int n = 0; n < 2; ++n) _Pragma("unroll") for (int k = 0; k < 2; ++k) dst[n][k] = *(const PG8_LAS bf16x8*)(lds + PG8_SB(b, h) + boff + n * 2048 + k * 1024); } while (0)
; #define PG8_MMA(ai, bj, At, Bt) do { __builtin_amdgcn_s_setprio(1); _Pragma("unroll") for (int m = 0; m < 4; ++m) _Pragma("unroll") for (int n = 0; n < 2; ++n) _Pragma("unroll") for (int k = 0; k < 2; ++k) \
;         acc[ai][bj][m][n] = __builtin_amdgcn_mfma_f32_16x16x32_bf16(Bt[n][k], At[m][k], acc[ai][bj][m][n], 0, 0, 0); __builtin_amdgcn_s_setprio(0); } while (0)
; #define PG8_WAIT_V(n) asm volatile("s_waitcnt vmcnt(" #n ")" ::: "memory")
; #define PG8_WAIT_L(n) asm volatile("s_waitcnt lgkmcnt(" #n ")" ::: "memory")
; #define PG8_BAR __builtin_amdgcn_s_barrier()
; #define PG8_SCHED __builtin_amdgcn_sched_barrier(0)
; template <class Epi, class Sched, bool ALIGN_EPI = false, bool SP2 = false>
; __device__ __forceinline__ void gemm_phase(PG8_LAS unsigned char* lds, const Gemm g, const Sched& S, const Epi& E, int tid_in) {
;     ...
;             PG8_LDB(B0, 0, 0); PG8_LDB(B1, 0, 1); PG8_SCHED; PG8_LDA(At, 0, 0); PG8_STAGE(PG8_SA(1, 1), a1 + hstep, voffA);
;             PG8_WAIT_V(8); PG8_WAIT_L(0); PG8_BAR; PG8_MMA(0, 0, At, B0); PG8_MMA(0, 1, At, B1); PG8_BAR; PG8_SCHED;
;             PG8_LDA(At, 0, 1); PG8_STAGE(PG8_SB(0, 0), b2, voffB); PG8_STAGE(PG8_SB(0, 1), b2 + hstep, voffB); PG8_STAGE(PG8_SA(0, 0), a2, voffA);
;             PG8_WAIT_V(8); PG8_WAIT_L(0); PG8_BAR; PG8_MMA(1, 0, At, B0); PG8_MMA(1, 1, At, B1); PG8_BAR; PG8_SCHED;
.Lpk13:
	s_or_b64 s[98:99], s[6:7], 1
	v_lshl_add_u64 v[198:199], s[46:47], 0, v[140:141]
	s_add_i32 m0, s40, 0xc000
	ds_read_b128 v[190:193], v182
	ds_read_b128 v[194:197], v182 offset:1024
	ds_read_b128 v[202:205], v182 offset:2048
	ds_read_b128 v[206:209], v182 offset:3072
	ds_read_b128 v[210:213], v182 offset:4096
	ds_read_b128 v[214:217], v182 offset:5120
	ds_read_b128 v[218:221], v182 offset:6144
	ds_read_b128 v[222:225], v182 offset:7168
	global_load_lds_dwordx4 v[198:199], off
	v_lshl_add_u64 v[198:199], s[46:47], 0, v[138:139]
	s_add_i32 m0, s40, 0xe000
	s_nop 0
	global_load_lds_dwordx4 v[198:199], off
	s_waitcnt vmcnt(8)
	s_waitcnt lgkmcnt(0)
	s_barrier
	s_setprio 1
	s_waitcnt lgkmcnt(0)
	v_mfma_f32_16x16x32_bf16 v[124:127], v[146:149], v[190:193], v[124:127]
	v_mfma_f32_16x16x32_bf16 v[120:123], v[154:157], v[190:193], v[120:123]
	v_mfma_f32_16x16x32_bf16 v[108:111], v[146:149], v[202:205], v[108:111]
	v_mfma_f32_16x16x32_bf16 v[104:107], v[154:157], v[202:205], v[104:107]
	v_mfma_f32_16x16x32_bf16 v[92:95], v[146:149], v[210:213], v[92:95]
	v_mfma_f32_16x16x32_bf16 v[88:91], v[154:157], v[210:213], v[88:91]
	v_mfma_f32_16x16x32_bf16 v[76:79], v[146:149], v[218:221], v[76:79]
	v_mfma_f32_16x16x32_bf16 v[72:75], v[154:157], v[218:221], v[72:75]
	v_mfma_f32_16x16x32_bf16 v[124:127], v[150:153], v[194:197], v[124:127]
	v_mfma_f32_16x16x32_bf16 v[120:123], v[158:161], v[194:197], v[120:123]
	v_mfma_f32_16x16x32_bf16 v[108:111], v[150:153], v[206:209], v[108:111]
	v_mfma_f32_16x16x32_bf16 v[104:107], v[158:161], v[206:209], v[104:107]
	v_mfma_f32_16x16x32_bf16 v[92:95], v[150:153], v[214:217], v[92:95]
	v_mfma_f32_16x16x32_bf16 v[88:91], v[158:161], v[214:217], v[88:91]
	v_mfma_f32_16x16x32_bf16 v[76:79], v[150:153], v[222:225], v[76:79]
	v_mfma_f32_16x16x32_bf16 v[72:75], v[158:161], v[222:225], v[72:75]
	s_setprio 0
	s_setprio 1
	v_mfma_f32_16x16x32_bf16 v[116:119], v[162:165], v[190:193], v[116:119]
	v_mfma_f32_16x16x32_bf16 v[112:115], v[170:173], v[190:193], v[112:115]
	v_mfma_f32_16x16x32_bf16 v[100:103], v[162:165], v[202:205], v[100:103]
	v_mfma_f32_16x16x32_bf16 v[96:99], v[170:173], v[202:205], v[96:99]
	v_mfma_f32_16x16x32_bf16 v[84:87], v[162:165], v[210:213], v[84:87]
	v_mfma_f32_16x16x32_bf16 v[80:83], v[170:173], v[210:213], v[80:83]
	v_mfma_f32_16x16x32_bf16 v[68:71], v[162:165], v[218:221], v[68:71]
	v_mfma_f32_16x16x32_bf16 v[64:67], v[170:173], v[218:221], v[64:67]
	v_mfma_f32_16x16x32_bf16 v[116:119], v[166:169], v[194:197], v[116:119]
	v_mfma_f32_16x16x32_bf16 v[112:115], v[186:189], v[194:197], v[112:115]
	v_mfma_f32_16x16x32_bf16 v[100:103], v[166:169], v[206:209], v[100:103]
	v_mfma_f32_16x16x32_bf16 v[96:99], v[186:189], v[206:209], v[96:99]
	v_mfma_f32_16x16x32_bf16 v[84:87], v[166:169], v[214:217], v[84:87]
	v_mfma_f32_16x16x32_bf16 v[80:83], v[186:189], v[214:217], v[80:83]
	v_mfma_f32_16x16x32_bf16 v[68:71], v[166:169], v[222:225], v[68:71]
	v_mfma_f32_16x16x32_bf16 v[64:67], v[186:189], v[222:225], v[64:67]
	s_setprio 0
	s_barrier
	s_add_i32 s4, s66, s33
	v_lshl_add_u64 v[198:199], s[48:49], 0, v[130:131]
	s_mov_b32 m0, s4
	ds_read_b128 v[190:193], v182 offset:16384
	ds_read_b128 v[194:197], v182 offset:17408
	ds_read_b128 v[202:205], v182 offset:18432
	ds_read_b128 v[206:209], v182 offset:19456
	ds_read_b128 v[210:213], v182 offset:20480
	ds_read_b128 v[214:217], v182 offset:21504
	ds_read_b128 v[218:221], v182 offset:22528
	ds_read_b128 v[222:225], v182 offset:23552
	s_mov_b64 exec, s[98:99]
	global_load_lds_dwordx4 v[198:199], off
	s_mov_b64 exec, -1
	s_add_i32 m0, s4, 0x2000
	s_add_u32 s78, s48, 0x40000
	v_lshl_add_u64 v[226:227], s[48:49], 0, v[134:135]
	s_addc_u32 s79, s49, 0
	s_add_i32 s4, s67, s33
	s_mov_b64 exec, s[98:99]
	global_load_lds_dwordx4 v[226:227], off
	s_mov_b64 exec, -1
	v_lshl_add_u64 v[228:229], s[78:79], 0, v[130:131]
	s_mov_b32 m0, s4
	v_lshl_add_u64 v[230:231], s[50:51], 0, v[132:133]
	s_mov_b64 exec, s[98:99]
	global_load_lds_dwordx4 v[228:229], off
	s_mov_b64 exec, -1
	v_lshl_add_u64 v[228:229], s[78:79], 0, v[134:135]
	s_add_i32 m0, s4, 0x2000
	s_nop 0
	s_mov_b64 exec, s[98:99]
	global_load_lds_dwordx4 v[228:229], off
	s_mov_b64 exec, -1
	v_lshl_add_u64 v[228:229], s[50:51], 0, v[128:129]
	s_mov_b32 m0, s40
	s_nop 0
	s_mov_b64 exec, s[98:99]
	global_load_lds_dwordx4 v[228:229], off
	s_mov_b64 exec, -1
	s_mov_b32 m0, s41
	s_nop 0
	s_mov_b64 exec, s[98:99]
	global_load_lds_dwordx4 v[230:231], off
	s_mov_b64 exec, -1
	s_waitcnt vmcnt(8)
	s_waitcnt lgkmcnt(0)
	s_barrier
; #define PG8_STAGE(bufoff, gbase, voff) do { _Pragma("unroll") for (int _i = 0; _i < 2; ++_i) \
;         __builtin_amdgcn_global_load_lds((const unsigned*)((const char*)(gbase) + (voff)[_i]), (PG8_LAS unsigned*)(lds + (bufoff) + ldsw + _i * 8192), 16, 0, 0); } while (0)
; #define PG8_LDA(dst, b, h) do { _Pragma("unroll") for (int m = 0; m < 4; ++m) _Pragma("unroll") for (int k = 0; k < 2; ++k) dst[m][k] = *(const PG8_LAS bf16x8*)(lds + PG8_SA(b, h) + aoff + m * 2048 + k * 1024); } while (0)
; #define PG8_LDB(dst, b, h) do { _Pragma("unroll") for (int n = 0; n < 2; ++n) _Pragma("unroll") for (int k = 0; k < 2; ++k) dst[n][k] = *(const PG8_LAS bf16x8*)(lds + PG8_SB(b, h) + boff + n * 2048 + k * 1024); } while (0)
; #define PG8_MMA(ai, bj, At, Bt) do { __builtin_amdgcn_s_setprio(1); _Pragma("unroll") for (int m = 0; m < 4; ++m) _Pragma("unroll") for (int n = 0; n < 2; ++n) _Pragma("unroll") for (int k = 0; k < 2; ++k) \
;         acc[ai][bj][m][n] = __builtin_amdgcn_mfma_f32_16x16x32_bf16(Bt[n][k], At[m][k], acc[ai][bj][m][n], 0, 0, 0); __builtin_amdgcn_s_setprio(0); } while (0)
; #define PG8_WAIT_V(n) asm volatile("s_waitcnt vmcnt(" #n ")" ::: "memory")
; #define PG8_WAIT_L(n) asm volatile("s_waitcnt lgkmcnt(" #n ")" ::: "memory")
; #define PG8_BAR __builtin_amdgcn_s_barrier()
; #define PG8_SCHED __builtin_amdgcn_sched_barrier(0)
; template <class Epi, class Sched, bool ALIGN_EPI = false, bool SP2 = false>
; __device__ __forceinline__ void gemm_phase(PG8_LAS unsigned char* lds, const Gemm g, const Sched& S, const Epi& E, int tid_in) {
;     ...
;             PG8_WAIT_V(8); PG8_WAIT_L(0); PG8_BAR; PG8_MMA(1, 0, At, B0); PG8_MMA(1, 1, At, B1); PG8_BAR; PG8_SCHED;
;             PG8_LDB(B0, 1, 0); PG8_LDB(B1, 1, 1); PG8_SCHED; PG8_LDA(At, 1, 0); PG8_STAGE(PG8_SA(0, 1), a2 + hstep, voffA);
;             PG8_WAIT_V(8); PG8_WAIT_L(0); PG8_BAR; PG8_MMA(0, 0, At, B0); PG8_MMA(0, 1, At, B1); PG8_BAR; PG8_SCHED;
	s_setprio 1
	s_waitcnt lgkmcnt(0)
	v_mfma_f32_16x16x32_bf16 v[60:63], v[146:149], v[190:193], v[60:63]
	v_mfma_f32_16x16x32_bf16 v[56:59], v[154:157], v[190:193], v[56:59]
	v_mfma_f32_16x16x32_bf16 v[44:47], v[146:149], v[202:205], v[44:47]
	v_mfma_f32_16x16x32_bf16 v[40:43], v[154:157], v[202:205], v[40:43]
	v_mfma_f32_16x16x32_bf16 v[28:31], v[146:149], v[210:213], v[28:31]
	v_mfma_f32_16x16x32_bf16 v[24:27], v[154:157], v[210:213], v[24:27]
	v_mfma_f32_16x16x32_bf16 v[12:15], v[146:149], v[218:221], v[12:15]
	v_mfma_f32_16x16x32_bf16 v[8:11], v[154:157], v[218:221], v[8:11]
	v_mfma_f32_16x16x32_bf16 v[60:63], v[150:153], v[194:197], v[60:63]
	v_mfma_f32_16x16x32_bf16 v[56:59], v[158:161], v[194:197], v[56:59]
	v_mfma_f32_16x16x32_bf16 v[44:47], v[150:153], v[206:209], v[44:47]
	v_mfma_f32_16x16x32_bf16 v[40:43], v[158:161], v[206:209], v[40:43]
	v_mfma_f32_16x16x32_bf16 v[28:31], v[150:153], v[214:217], v[28:31]
	v_mfma_f32_16x16x32_bf16 v[24:27], v[158:161], v[214:217], v[24:27]
	v_mfma_f32_16x16x32_bf16 v[12:15], v[150:153], v[222:225], v[12:15]
	v_mfma_f32_16x16x32_bf16 v[8:11], v[158:161], v[222:225], v[8:11]
	s_setprio 0
	s_setprio 1
	v_mfma_f32_16x16x32_bf16 v[52:55], v[162:165], v[190:193], v[52:55]
	v_mfma_f32_16x16x32_bf16 v[48:51], v[170:173], v[190:193], v[48:51]
	v_mfma_f32_16x16x32_bf16 v[36:39], v[162:165], v[202:205], v[36:39]
	v_mfma_f32_16x16x32_bf16 v[32:35], v[170:173], v[202:205], v[32:35]
	v_mfma_f32_16x16x32_bf16 v[20:23], v[162:165], v[210:213], v[20:23]
	v_mfma_f32_16x16x32_bf16 v[16:19], v[170:173], v[210:213], v[16:19]
	v_mfma_f32_16x16x32_bf16 v[4:7], v[162:165], v[218:221], v[4:7]
	v_mfma_f32_16x16x32_bf16 v[0:3], v[170:173], v[218:221], v[0:3]
	v_mfma_f32_16x16x32_bf16 v[52:55], v[166:169], v[194:197], v[52:55]
	v_mfma_f32_16x16x32_bf16 v[48:51], v[186:189], v[194:197], v[48:51]
	v_mfma_f32_16x16x32_bf16 v[36:39], v[166:169], v[206:209], v[36:39]
	v_mfma_f32_16x16x32_bf16 v[32:35], v[186:189], v[206:209], v[32:35]
	v_mfma_f32_16x16x32_bf16 v[20:23], v[166:169], v[214:217], v[20:23]
	v_mfma_f32_16x16x32_bf16 v[16:19], v[186:189], v[214:217], v[16:19]
	v_mfma_f32_16x16x32_bf16 v[4:7], v[166:169], v[222:225], v[4:7]
	v_mfma_f32_16x16x32_bf16 v[0:3], v[186:189], v[222:225], v[0:3]
	s_setprio 0
	s_barrier
	s_add_i32 s4, 0, 0x18000
	s_add_i32 s5, 0, 0x1c000
	v_add_u32_e32 v158, s4, v175
	v_add_u32_e32 v186, s5, v175
	ds_read_b128 v[146:149], v158
	ds_read_b128 v[150:153], v158 offset:1024
	ds_read_b128 v[154:157], v158 offset:2048
	ds_read_b128 v[158:161], v158 offset:3072
	ds_read_b128 v[162:165], v186
	ds_read_b128 v[166:169], v186 offset:1024
	ds_read_b128 v[170:173], v186 offset:2048
	ds_read_b128 v[186:189], v186 offset:3072
	s_add_u32 s50, s50, 0x40000
	s_addc_u32 s51, s51, 0
	s_mov_b32 m0, s45
	v_lshl_add_u64 v[232:233], s[50:51], 0, v[128:129]
	ds_read_b128 v[190:193], v182 offset:32768
	ds_read_b128 v[194:197], v182 offset:33792
	ds_read_b128 v[202:205], v182 offset:34816
	ds_read_b128 v[206:209], v182 offset:35840
	ds_read_b128 v[210:213], v182 offset:36864
	ds_read_b128 v[214:217], v182 offset:37888
	ds_read_b128 v[218:221], v182 offset:38912
	ds_read_b128 v[222:225], v182 offset:39936
	s_mov_b64 exec, s[98:99]
	global_load_lds_dwordx4 v[232:233], off
	s_mov_b64 exec, -1
	v_lshl_add_u64 v[232:233], s[50:51], 0, v[132:133]
	s_mov_b32 m0, s52
	s_nop 0
	s_mov_b64 exec, s[98:99]
	global_load_lds_dwordx4 v[232:233], off
	s_mov_b64 exec, -1
	s_waitcnt vmcnt(8)
	s_waitcnt lgkmcnt(0)
	s_barrier
	s_setprio 1
	s_waitcnt lgkmcnt(0)
	v_mfma_f32_16x16x32_bf16 v[124:127], v[146:149], v[190:193], v[124:127]
	v_mfma_f32_16x16x32_bf16 v[120:123], v[154:157], v[190:193], v[120:123]
	v_mfma_f32_16x16x32_bf16 v[108:111], v[146:149], v[202:205], v[108:111]
	v_mfma_f32_16x16x32_bf16 v[104:107], v[154:157], v[202:205], v[104:107]
	v_mfma_f32_16x16x32_bf16 v[92:95], v[146:149], v[210:213], v[92:95]
	v_mfma_f32_16x16x32_bf16 v[88:91], v[154:157], v[210:213], v[88:91]
	v_mfma_f32_16x16x32_bf16 v[76:79], v[146:149], v[218:221], v[76:79]
	v_mfma_f32_16x16x32_bf16 v[72:75], v[154:157], v[218:221], v[72:75]
	v_mfma_f32_16x16x32_bf16 v[124:127], v[150:153], v[194:197], v[124:127]
	v_mfma_f32_16x16x32_bf16 v[120:123], v[158:161], v[194:197], v[120:123]
	v_mfma_f32_16x16x32_bf16 v[108:111], v[150:153], v[206:209], v[108:111]
	v_mfma_f32_16x16x32_bf16 v[104:107], v[158:161], v[206:209], v[104:107]
	v_mfma_f32_16x16x32_bf16 v[92:95], v[150:153], v[214:217], v[92:95]
	v_mfma_f32_16x16x32_bf16 v[88:91], v[158:161], v[214:217], v[88:91]
	v_mfma_f32_16x16x32_bf16 v[76:79], v[150:153], v[222:225], v[76:79]
	v_mfma_f32_16x16x32_bf16 v[72:75], v[158:161], v[222:225], v[72:75]
	s_setprio 0
	s_setprio 1
	v_mfma_f32_16x16x32_bf16 v[116:119], v[162:165], v[190:193], v[116:119]
	v_mfma_f32_16x16x32_bf16 v[112:115], v[170:173], v[190:193], v[112:115]
	v_mfma_f32_16x16x32_bf16 v[100:103], v[162:165], v[202:205], v[100:103]
	v_mfma_f32_16x16x32_bf16 v[96:99], v[170:173], v[202:205], v[96:99]
	v_mfma_f32_16x16x32_bf16 v[84:87], v[162:165], v[210:213], v[84:87]
	v_mfma_f32_16x16x32_bf16 v[80:83], v[170:173], v[210:213], v[80:83]
	v_mfma_f32_16x16x32_bf16 v[68:71], v[162:165], v[218:221], v[68:71]
	v_mfma_f32_16x16x32_bf16 v[64:67], v[170:173], v[218:221], v[64:67]
	v_mfma_f32_16x16x32_bf16 v[116:119], v[166:169], v[194:197], v[116:119]
	v_mfma_f32_16x16x32_bf16 v[112:115], v[186:189], v[194:197], v[112:115]
	v_mfma_f32_16x16x32_bf16 v[100:103], v[166:169], v[206:209], v[100:103]
	v_mfma_f32_16x16x32_bf16 v[96:99], v[186:189], v[206:209], v[96:99]
	v_mfma_f32_16x16x32_bf16 v[84:87], v[166:169], v[214:217], v[84:87]
	v_mfma_f32_16x16x32_bf16 v[80:83], v[186:189], v[214:217], v[80:83]
	v_mfma_f32_16x16x32_bf16 v[68:71], v[166:169], v[222:225], v[68:71]
	v_mfma_f32_16x16x32_bf16 v[64:67], v[186:189], v[222:225], v[64:67]
	s_setprio 0
	s_barrier
; #define PG8_STAGE(bufoff, gbase, voff) do { _Pragma("unroll") for (int _i = 0; _i < 2; ++_i) \
;         __builtin_amdgcn_global_load_lds((const unsigned*)((const char*)(gbase) + (voff)[_i]), (PG8_LAS unsigned*)(lds + (bufoff) + ldsw + _i * 8192), 16, 0, 0); } while (0)
; #define PG8_LDA(dst, b, h) do { _Pragma("unroll") for (int m = 0; m < 4; ++m) _Pragma("unroll") for (int k = 0; k < 2; ++k) dst[m][k] = *(const PG8_LAS bf16x8*)(lds + PG8_SA(b, h) + aoff + m * 2048 + k * 1024); } while (0)
; #define PG8_MMA(ai, bj, At, Bt) do { __builtin_amdgcn_s_setprio(1); _Pragma("unroll") for (int m = 0; m < 4; ++m) _Pragma("unroll") for (int n = 0; n < 2; ++n) _Pragma("unroll") for (int k = 0; k < 2; ++k) \
;         acc[ai][bj][m][n] = __builtin_amdgcn_mfma_f32_16x16x32_bf16(Bt[n][k], At[m][k], acc[ai][bj][m][n], 0, 0, 0); __builtin_amdgcn_s_setprio(0); } while (0)
; #define PG8_WAIT_V(n) asm volatile("s_waitcnt vmcnt(" #n ")" ::: "memory")
; #define PG8_WAIT_L(n) asm volatile("s_waitcnt lgkmcnt(" #n ")" ::: "memory")
; #define PG8_BAR __builtin_amdgcn_s_barrier()
; #define PG8_SCHED __builtin_amdgcn_sched_barrier(0)
; template <class Epi, class Sched, bool ALIGN_EPI = false, bool SP2 = false>
; __device__ __forceinline__ void gemm_phase(PG8_LAS unsigned char* lds, const Gemm g, const Sched& S, const Epi& E, int tid_in) {
;     ...
;             PG8_LDA(At, 1, 1); PG8_STAGE(PG8_SB(1, 0), b3, voffB); PG8_STAGE(PG8_SB(1, 1), b3 + hstep, voffB); PG8_STAGE(PG8_SA(1, 0), a3, voffA);
;             PG8_WAIT_V(8); PG8_WAIT_L(0); PG8_BAR; PG8_MMA(1, 0, At, B0); PG8_MMA(1, 1, At, B1); PG8_BAR; PG8_SCHED;
	s_add_i32 s4, s4, s33
	v_lshl_add_u64 v[198:199], v[198:199], 0, s[16:17]
	s_mov_b32 m0, s4
	ds_read_b128 v[190:193], v182 offset:49152
	ds_read_b128 v[194:197], v182 offset:50176
	ds_read_b128 v[202:205], v182 offset:51200
	ds_read_b128 v[206:209], v182 offset:52224
	ds_read_b128 v[210:213], v182 offset:53248
	ds_read_b128 v[214:217], v182 offset:54272
	ds_read_b128 v[218:221], v182 offset:55296
	ds_read_b128 v[222:225], v182 offset:56320
	s_mov_b64 exec, s[98:99]
	global_load_lds_dwordx4 v[198:199], off
	s_mov_b64 exec, -1
	s_add_i32 m0, s4, 0x2000
	s_add_u32 s48, s48, 0x40080
	v_lshl_add_u64 v[198:199], v[226:227], 0, s[16:17]
	s_addc_u32 s49, s49, 0
	s_add_i32 s4, s5, s33
	s_mov_b64 exec, s[98:99]
	global_load_lds_dwordx4 v[198:199], off
	s_mov_b64 exec, -1
	v_lshl_add_u64 v[198:199], s[48:49], 0, v[130:131]
	s_mov_b32 m0, s4
	s_nop 0
	s_mov_b64 exec, s[98:99]
	global_load_lds_dwordx4 v[198:199], off
	s_mov_b64 exec, -1
	v_lshl_add_u64 v[198:199], s[48:49], 0, v[134:135]
	s_add_i32 m0, s4, 0x2000
	s_nop 0
	s_mov_b64 exec, s[98:99]
	global_load_lds_dwordx4 v[198:199], off
	s_mov_b64 exec, -1
	v_lshl_add_u64 v[198:199], v[228:229], 0, s[16:17]
	s_mov_b32 m0, s61
	s_nop 0
	s_mov_b64 exec, s[98:99]
	global_load_lds_dwordx4 v[198:199], off
	s_mov_b64 exec, -1
	v_lshl_add_u64 v[198:199], v[230:231], 0, s[16:17]
	s_mov_b32 m0, s62
	s_nop 0
	s_mov_b64 exec, s[98:99]
	global_load_lds_dwordx4 v[198:199], off
	s_mov_b64 exec, -1
	s_waitcnt vmcnt(8)
	s_waitcnt lgkmcnt(0)
	s_barrier
	s_setprio 1
	s_waitcnt lgkmcnt(0)
	v_mfma_f32_16x16x32_bf16 v[60:63], v[146:149], v[190:193], v[60:63]
	v_mfma_f32_16x16x32_bf16 v[56:59], v[154:157], v[190:193], v[56:59]
	v_mfma_f32_16x16x32_bf16 v[44:47], v[146:149], v[202:205], v[44:47]
	v_mfma_f32_16x16x32_bf16 v[40:43], v[154:157], v[202:205], v[40:43]
	v_mfma_f32_16x16x32_bf16 v[28:31], v[146:149], v[210:213], v[28:31]
	v_mfma_f32_16x16x32_bf16 v[24:27], v[154:157], v[210:213], v[24:27]
	v_mfma_f32_16x16x32_bf16 v[12:15], v[146:149], v[218:221], v[12:15]
	v_mfma_f32_16x16x32_bf16 v[8:11], v[154:157], v[218:221], v[8:11]
	v_mfma_f32_16x16x32_bf16 v[60:63], v[150:153], v[194:197], v[60:63]
	v_mfma_f32_16x16x32_bf16 v[56:59], v[158:161], v[194:197], v[56:59]
	v_mfma_f32_16x16x32_bf16 v[44:47], v[150:153], v[206:209], v[44:47]
	v_mfma_f32_16x16x32_bf16 v[40:43], v[158:161], v[206:209], v[40:43]
	v_mfma_f32_16x16x32_bf16 v[28:31], v[150:153], v[214:217], v[28:31]
	v_mfma_f32_16x16x32_bf16 v[24:27], v[158:161], v[214:217], v[24:27]
	v_mfma_f32_16x16x32_bf16 v[12:15], v[150:153], v[222:225], v[12:15]
	v_mfma_f32_16x16x32_bf16 v[8:11], v[158:161], v[222:225], v[8:11]
	s_setprio 0
	s_setprio 1
	v_mfma_f32_16x16x32_bf16 v[52:55], v[162:165], v[190:193], v[52:55]
	v_mfma_f32_16x16x32_bf16 v[48:51], v[170:173], v[190:193], v[48:51]
	v_mfma_f32_16x16x32_bf16 v[36:39], v[162:165], v[202:205], v[36:39]
	v_mfma_f32_16x16x32_bf16 v[32:35], v[170:173], v[202:205], v[32:35]
	v_mfma_f32_16x16x32_bf16 v[20:23], v[162:165], v[210:213], v[20:23]
	v_mfma_f32_16x16x32_bf16 v[16:19], v[170:173], v[210:213], v[16:19]
	v_mfma_f32_16x16x32_bf16 v[4:7], v[162:165], v[218:221], v[4:7]
	v_mfma_f32_16x16x32_bf16 v[0:3], v[170:173], v[218:221], v[0:3]
	v_mfma_f32_16x16x32_bf16 v[52:55], v[166:169], v[194:197], v[52:55]
	v_mfma_f32_16x16x32_bf16 v[48:51], v[186:189], v[194:197], v[48:51]
	v_mfma_f32_16x16x32_bf16 v[36:39], v[166:169], v[206:209], v[36:39]
	v_mfma_f32_16x16x32_bf16 v[32:35], v[186:189], v[206:209], v[32:35]
	v_mfma_f32_16x16x32_bf16 v[20:23], v[166:169], v[214:217], v[20:23]
	v_mfma_f32_16x16x32_bf16 v[16:19], v[186:189], v[214:217], v[16:19]
	v_mfma_f32_16x16x32_bf16 v[4:7], v[166:169], v[222:225], v[4:7]
	v_mfma_f32_16x16x32_bf16 v[0:3], v[186:189], v[222:225], v[0:3]
	s_setprio 0
	s_barrier
	s_add_i32 s72, s72, 2
	s_add_u32 s70, s70, 0x100
	s_addc_u32 s71, s71, 0
	s_add_u32 s46, s46, 0x100
	s_addc_u32 s47, s47, 0
	s_cmp_gt_u32 s72, 13
	s_branch .Lpost13

; #define PG8_STAGE(bufoff, gbase, voff) do { _Pragma("unroll") for (int _i = 0; _i < 2; ++_i) \
;         __builtin_amdgcn_global_load_lds((const unsigned*)((const char*)(gbase) + (voff)[_i]), (PG8_LAS unsigned*)(lds + (bufoff) + ldsw + _i * 8192), 16, 0, 0); } while (0)
; #define PG8_LDA(dst, b, h) do { _Pragma("unroll") for (int m = 0; m < 4; ++m) _Pragma("unroll") for (int k = 0; k < 2; ++k) dst[m][k] = *(const PG8_LAS bf16x8*)(lds + PG8_SA(b, h) + aoff + m * 2048 + k * 1024); } while (0)
; #define PG8_LDB(dst, b, h) do { _Pragma("unroll") for (int n = 0; n < 2; ++n) _Pragma("unroll") for (int k = 0; k < 2; ++k) dst[n][k] = *(const PG8_LAS bf16x8*)(lds + PG8_SB(b, h) + boff + n * 2048 + k * 1024); } while (0)
; #define PG8_MMA(ai, bj, At, Bt) do { __builtin_amdgcn_s_setprio(1); _Pragma("unroll") for (int m = 0; m < 4; ++m) _Pragma("unroll") for (int n = 0; n < 2; ++n) _Pragma("unroll") for (int k = 0; k < 2; ++k) \
;         acc[ai][bj][m][n] = __builtin_amdgcn_mfma_f32_16x16x32_bf16(Bt[n][k], At[m][k], acc[ai][bj][m][n], 0, 0, 0); __builtin_amdgcn_s_setprio(0); } while (0)
; #define PG8_WAIT_V(n) asm volatile("s_waitcnt vmcnt(" #n ")" ::: "memory")
; #define PG8_BAR __builtin_amdgcn_s_barrier()
; template <class Epi, class Sched, bool ALIGN_EPI = false, bool SP2 = false>
; __device__ __forceinline__ void gemm_phase(PG8_LAS unsigned char* lds, const Gemm g, const Sched& S, const Epi& E, int tid_in) {
;     ...
;         for (int t = 0; t < nt; t += 2) {
;             const bool last = (t == nt - 2);
;             const char* a1 = cA + (size_t)(t + 1) * kstep;
;             const char* a2 = last ? nA : cA + (size_t)(t + 2) * kstep; const char* b2 = last ? nB : cB + (size_t)(t + 2) * kstep;
;             const char* a3 = a2 + kstep; const char* b3 = b2 + kstep;
;             if (last && has_next) S.a_ready(nxt);
;             if constexpr (SP2) {
;             PG8_LDB(B0, 0, 0); PG8_LDB(B1, 0, 1); PG8_SCHED; PG8_LDA(At, 0, 0); PG8_STAGE(PG8_SA(1, 1), a1 + hstep, voffA);
;             PG8_WAIT_V(8); PG8_WAIT_L(0); PG8_BAR; PG8_MMA(0, 0, At, B0); PG8_MMA(0, 1, At, B1); PG8_BAR; PG8_SCHED;
;             PG8_LDA(At, 0, 1); PG8_STAGE(PG8_SB(0, 0), b2, voffB); PG8_STAGE(PG8_SB(0, 1), b2 + hstep, voffB); PG8_STAGE(PG8_SA(0, 0), a2, voffA);
;             PG8_WAIT_V(8); PG8_WAIT_L(0); PG8_BAR; PG8_MMA(1, 0, At, B0); PG8_MMA(1, 1, At, B1); PG8_BAR; PG8_SCHED;
.LBB0_1956:
	ds_read_b128 v[128:131], v189
	ds_read_b128 v[132:135], v189 offset:1024
	ds_read_b128 v[136:139], v189 offset:2048
	ds_read_b128 v[140:143], v189 offset:3072
	ds_read_b128 v[144:147], v190
	ds_read_b128 v[148:151], v190 offset:1024
	ds_read_b128 v[168:171], v190 offset:2048
	ds_read_b128 v[172:175], v190 offset:3072
	s_add_u32 s42, s40, 0xfffc0080
	s_addc_u32 s43, s41, -1
	s_cmp_eq_u32 s57, 12
	s_cselect_b32 s45, s27, s43
	s_cselect_b32 s44, s39, s42
	s_cselect_b32 s43, s25, s56
	s_cselect_b32 s42, s54, s55
	s_cbranch_scc1 .Lpk14
	v_lshl_add_u64 v[184:185], s[40:41], 0, v[162:163]
	s_add_i32 m0, s12, 0xc000
	ds_read_b128 v[176:179], v191
	ds_read_b128 v[180:183], v191 offset:1024
	ds_read_b128 v[192:195], v191 offset:2048
	ds_read_b128 v[196:199], v191 offset:3072
	ds_read_b128 v[202:205], v191 offset:4096
	ds_read_b128 v[206:209], v191 offset:5120
	ds_read_b128 v[210:213], v191 offset:6144
	ds_read_b128 v[214:217], v191 offset:7168
	global_load_lds_dwordx4 v[184:185], off
	v_lshl_add_u64 v[184:185], s[40:41], 0, v[160:161]
	s_add_i32 m0, s12, 0xe000
	s_nop 0
	global_load_lds_dwordx4 v[184:185], off
	s_waitcnt vmcnt(8)
	s_waitcnt lgkmcnt(0)
	s_barrier
	s_setprio 1
	s_waitcnt lgkmcnt(0)
	v_mfma_f32_16x16x32_bf16 v[124:127], v[128:131], v[176:179], v[124:127]
	v_mfma_f32_16x16x32_bf16 v[120:123], v[136:139], v[176:179], v[120:123]
	v_mfma_f32_16x16x32_bf16 v[108:111], v[128:131], v[192:195], v[108:111]
	v_mfma_f32_16x16x32_bf16 v[104:107], v[136:139], v[192:195], v[104:107]
	v_mfma_f32_16x16x32_bf16 v[92:95], v[128:131], v[202:205], v[92:95]
	v_mfma_f32_16x16x32_bf16 v[88:91], v[136:139], v[202:205], v[88:91]
	v_mfma_f32_16x16x32_bf16 v[76:79], v[128:131], v[210:213], v[76:79]
	v_mfma_f32_16x16x32_bf16 v[72:75], v[136:139], v[210:213], v[72:75]
	v_mfma_f32_16x16x32_bf16 v[124:127], v[132:135], v[180:183], v[124:127]
	v_mfma_f32_16x16x32_bf16 v[120:123], v[140:143], v[180:183], v[120:123]
	v_mfma_f32_16x16x32_bf16 v[108:111], v[132:135], v[196:199], v[108:111]
	v_mfma_f32_16x16x32_bf16 v[104:107], v[140:143], v[196:199], v[104:107]
	v_mfma_f32_16x16x32_bf16 v[92:95], v[132:135], v[206:209], v[92:95]
	v_mfma_f32_16x16x32_bf16 v[88:91], v[140:143], v[206:209], v[88:91]
	v_mfma_f32_16x16x32_bf16 v[76:79], v[132:135], v[214:217], v[76:79]
	v_mfma_f32_16x16x32_bf16 v[72:75], v[140:143], v[214:217], v[72:75]
	s_setprio 0
	s_setprio 1
	v_mfma_f32_16x16x32_bf16 v[116:119], v[144:147], v[176:179], v[116:119]
	v_mfma_f32_16x16x32_bf16 v[112:115], v[168:171], v[176:179], v[112:115]
	v_mfma_f32_16x16x32_bf16 v[100:103], v[144:147], v[192:195], v[100:103]
	v_mfma_f32_16x16x32_bf16 v[96:99], v[168:171], v[192:195], v[96:99]
	v_mfma_f32_16x16x32_bf16 v[84:87], v[144:147], v[202:205], v[84:87]
	v_mfma_f32_16x16x32_bf16 v[80:83], v[168:171], v[202:205], v[80:83]
	v_mfma_f32_16x16x32_bf16 v[68:71], v[144:147], v[210:213], v[68:71]
	v_mfma_f32_16x16x32_bf16 v[64:67], v[168:171], v[210:213], v[64:67]
	v_mfma_f32_16x16x32_bf16 v[116:119], v[148:151], v[180:183], v[116:119]
	v_mfma_f32_16x16x32_bf16 v[112:115], v[172:175], v[180:183], v[112:115]
	v_mfma_f32_16x16x32_bf16 v[100:103], v[148:151], v[196:199], v[100:103]
	v_mfma_f32_16x16x32_bf16 v[96:99], v[172:175], v[196:199], v[96:99]
	v_mfma_f32_16x16x32_bf16 v[84:87], v[148:151], v[206:209], v[84:87]
	v_mfma_f32_16x16x32_bf16 v[80:83], v[172:175], v[206:209], v[80:83]
	v_mfma_f32_16x16x32_bf16 v[68:71], v[148:151], v[214:217], v[68:71]
	v_mfma_f32_16x16x32_bf16 v[64:67], v[172:175], v[214:217], v[64:67]
	s_setprio 0
	s_barrier
	s_add_i32 s58, s51, s5
	v_lshl_add_u64 v[184:185], s[42:43], 0, v[154:155]
	s_mov_b32 m0, s58
	ds_read_b128 v[176:179], v191 offset:16384
	ds_read_b128 v[180:183], v191 offset:17408
	ds_read_b128 v[192:195], v191 offset:18432
	ds_read_b128 v[196:199], v191 offset:19456
	ds_read_b128 v[202:205], v191 offset:20480
	ds_read_b128 v[206:209], v191 offset:21504
	ds_read_b128 v[210:213], v191 offset:22528
	ds_read_b128 v[214:217], v191 offset:23552
	global_load_lds_dwordx4 v[184:185], off
	s_add_i32 m0, s58, 0x2000
	s_add_u32 s58, s42, 0x40000
	v_lshl_add_u64 v[218:219], s[42:43], 0, v[158:159]
	s_addc_u32 s59, s43, 0
	s_add_i32 s60, s52, s5
	global_load_lds_dwordx4 v[218:219], off
	v_lshl_add_u64 v[220:221], s[58:59], 0, v[154:155]
	s_mov_b32 m0, s60
	v_lshl_add_u64 v[222:223], s[44:45], 0, v[156:157]
	global_load_lds_dwordx4 v[220:221], off
	v_lshl_add_u64 v[220:221], s[58:59], 0, v[158:159]
	s_add_i32 m0, s60, 0x2000
	s_nop 0
	global_load_lds_dwordx4 v[220:221], off
	v_lshl_add_u64 v[220:221], s[44:45], 0, v[152:153]
	s_mov_b32 m0, s12
	s_nop 0
	global_load_lds_dwordx4 v[220:221], off
	s_mov_b32 m0, s13
	s_nop 0
	global_load_lds_dwordx4 v[222:223], off
	s_waitcnt vmcnt(8)
	s_waitcnt lgkmcnt(0)
	s_barrier
; #define PG8_STAGE(bufoff, gbase, voff) do { _Pragma("unroll") for (int _i = 0; _i < 2; ++_i) \
;         __builtin_amdgcn_global_load_lds((const unsigned*)((const char*)(gbase) + (voff)[_i]), (PG8_LAS unsigned*)(lds + (bufoff) + ldsw + _i * 8192), 16, 0, 0); } while (0)
; #define PG8_LDA(dst, b, h) do { _Pragma("unroll") for (int m = 0; m < 4; ++m) _Pragma("unroll") for (int k = 0; k < 2; ++k) dst[m][k] = *(const PG8_LAS bf16x8*)(lds + PG8_SA(b, h) + aoff + m * 2048 + k * 1024); } while (0)
; #define PG8_LDB(dst, b, h) do { _Pragma("unroll") for (int n = 0; n < 2; ++n) _Pragma("unroll") for (int k = 0; k < 2; ++k) dst[n][k] = *(const PG8_LAS bf16x8*)(lds + PG8_SB(b, h) + boff + n * 2048 + k * 1024); } while (0)
; #define PG8_MMA(ai, bj, At, Bt) do { __builtin_amdgcn_s_setprio(1); _Pragma("unroll") for (int m = 0; m < 4; ++m) _Pragma("unroll") for (int n = 0; n < 2; ++n) _Pragma("unroll") for (int k = 0; k < 2; ++k) \
;         acc[ai][bj][m][n] = __builtin_amdgcn_mfma_f32_16x16x32_bf16(Bt[n][k], At[m][k], acc[ai][bj][m][n], 0, 0, 0); __builtin_amdgcn_s_setprio(0); } while (0)
; #define PG8_WAIT_V(n) asm volatile("s_waitcnt vmcnt(" #n ")" ::: "memory")
; #define PG8_WAIT_L(n) asm volatile("s_waitcnt lgkmcnt(" #n ")" ::: "memory")
; #define PG8_BAR __builtin_amdgcn_s_barrier()
; #define PG8_SCHED __builtin_amdgcn_sched_barrier(0)
; template <class Epi, class Sched, bool ALIGN_EPI = false, bool SP2 = false>
; __device__ __forceinline__ void gemm_phase(PG8_LAS unsigned char* lds, const Gemm g, const Sched& S, const Epi& E, int tid_in) {
;     ...
;             PG8_WAIT_V(8); PG8_WAIT_L(0); PG8_BAR; PG8_MMA(1, 0, At, B0); PG8_MMA(1, 1, At, B1); PG8_BAR; PG8_SCHED;
;             PG8_LDB(B0, 1, 0); PG8_LDB(B1, 1, 1); PG8_SCHED; PG8_LDA(At, 1, 0); PG8_STAGE(PG8_SA(0, 1), a2 + hstep, voffA);
;             PG8_WAIT_V(8); PG8_WAIT_L(0); PG8_BAR; PG8_MMA(0, 0, At, B0); PG8_MMA(0, 1, At, B1); PG8_BAR; PG8_SCHED;
	s_setprio 1
	s_waitcnt lgkmcnt(0)
	v_mfma_f32_16x16x32_bf16 v[60:63], v[128:131], v[176:179], v[60:63]
	v_mfma_f32_16x16x32_bf16 v[56:59], v[136:139], v[176:179], v[56:59]
	v_mfma_f32_16x16x32_bf16 v[44:47], v[128:131], v[192:195], v[44:47]
	v_mfma_f32_16x16x32_bf16 v[40:43], v[136:139], v[192:195], v[40:43]
	v_mfma_f32_16x16x32_bf16 v[28:31], v[128:131], v[202:205], v[28:31]
	v_mfma_f32_16x16x32_bf16 v[24:27], v[136:139], v[202:205], v[24:27]
	v_mfma_f32_16x16x32_bf16 v[12:15], v[128:131], v[210:213], v[12:15]
	v_mfma_f32_16x16x32_bf16 v[8:11], v[136:139], v[210:213], v[8:11]
	v_mfma_f32_16x16x32_bf16 v[60:63], v[132:135], v[180:183], v[60:63]
	v_mfma_f32_16x16x32_bf16 v[56:59], v[140:143], v[180:183], v[56:59]
	v_mfma_f32_16x16x32_bf16 v[44:47], v[132:135], v[196:199], v[44:47]
	v_mfma_f32_16x16x32_bf16 v[40:43], v[140:143], v[196:199], v[40:43]
	v_mfma_f32_16x16x32_bf16 v[28:31], v[132:135], v[206:209], v[28:31]
	v_mfma_f32_16x16x32_bf16 v[24:27], v[140:143], v[206:209], v[24:27]
	v_mfma_f32_16x16x32_bf16 v[12:15], v[132:135], v[214:217], v[12:15]
	v_mfma_f32_16x16x32_bf16 v[8:11], v[140:143], v[214:217], v[8:11]
	s_setprio 0
	s_setprio 1
	v_mfma_f32_16x16x32_bf16 v[52:55], v[144:147], v[176:179], v[52:55]
	v_mfma_f32_16x16x32_bf16 v[48:51], v[168:171], v[176:179], v[48:51]
	v_mfma_f32_16x16x32_bf16 v[36:39], v[144:147], v[192:195], v[36:39]
	v_mfma_f32_16x16x32_bf16 v[32:35], v[168:171], v[192:195], v[32:35]
	v_mfma_f32_16x16x32_bf16 v[20:23], v[144:147], v[202:205], v[20:23]
	v_mfma_f32_16x16x32_bf16 v[16:19], v[168:171], v[202:205], v[16:19]
	v_mfma_f32_16x16x32_bf16 v[4:7], v[144:147], v[210:213], v[4:7]
	v_mfma_f32_16x16x32_bf16 v[0:3], v[168:171], v[210:213], v[0:3]
	v_mfma_f32_16x16x32_bf16 v[52:55], v[148:151], v[180:183], v[52:55]
	v_mfma_f32_16x16x32_bf16 v[48:51], v[172:175], v[180:183], v[48:51]
	v_mfma_f32_16x16x32_bf16 v[36:39], v[148:151], v[196:199], v[36:39]
	v_mfma_f32_16x16x32_bf16 v[32:35], v[172:175], v[196:199], v[32:35]
	v_mfma_f32_16x16x32_bf16 v[20:23], v[148:151], v[206:209], v[20:23]
	v_mfma_f32_16x16x32_bf16 v[16:19], v[172:175], v[206:209], v[16:19]
	v_mfma_f32_16x16x32_bf16 v[4:7], v[148:151], v[214:217], v[4:7]
	v_mfma_f32_16x16x32_bf16 v[0:3], v[172:175], v[214:217], v[0:3]
	s_setprio 0
	s_barrier
	s_add_i32 s58, 0, 0x18000
	s_add_i32 s59, 0, 0x1c000
	v_add_u32_e32 v140, s58, v187
	v_add_u32_e32 v172, s59, v187
	ds_read_b128 v[128:131], v140
	ds_read_b128 v[132:135], v140 offset:1024
	ds_read_b128 v[136:139], v140 offset:2048
	ds_read_b128 v[140:143], v140 offset:3072
	ds_read_b128 v[144:147], v172
	ds_read_b128 v[148:151], v172 offset:1024
	ds_read_b128 v[168:171], v172 offset:2048
	ds_read_b128 v[172:175], v172 offset:3072
	s_add_u32 s44, s44, 0x40000
	s_addc_u32 s45, s45, 0
	s_mov_b32 m0, s30
	v_lshl_add_u64 v[224:225], s[44:45], 0, v[152:153]
	ds_read_b128 v[176:179], v191 offset:32768
	ds_read_b128 v[180:183], v191 offset:33792
	ds_read_b128 v[192:195], v191 offset:34816
	ds_read_b128 v[196:199], v191 offset:35840
	ds_read_b128 v[202:205], v191 offset:36864
	ds_read_b128 v[206:209], v191 offset:37888
	ds_read_b128 v[210:213], v191 offset:38912
	ds_read_b128 v[214:217], v191 offset:39936
	global_load_lds_dwordx4 v[224:225], off
	v_lshl_add_u64 v[224:225], s[44:45], 0, v[156:157]
	s_mov_b32 m0, s31
	s_nop 0
	global_load_lds_dwordx4 v[224:225], off
	s_waitcnt vmcnt(8)
	s_waitcnt lgkmcnt(0)
	s_barrier
	s_setprio 1
	s_waitcnt lgkmcnt(0)
	v_mfma_f32_16x16x32_bf16 v[124:127], v[128:131], v[176:179], v[124:127]
	v_mfma_f32_16x16x32_bf16 v[120:123], v[136:139], v[176:179], v[120:123]
	v_mfma_f32_16x16x32_bf16 v[108:111], v[128:131], v[192:195], v[108:111]
	v_mfma_f32_16x16x32_bf16 v[104:107], v[136:139], v[192:195], v[104:107]
	v_mfma_f32_16x16x32_bf16 v[92:95], v[128:131], v[202:205], v[92:95]
	v_mfma_f32_16x16x32_bf16 v[88:91], v[136:139], v[202:205], v[88:91]
	v_mfma_f32_16x16x32_bf16 v[76:79], v[128:131], v[210:213], v[76:79]
	v_mfma_f32_16x16x32_bf16 v[72:75], v[136:139], v[210:213], v[72:75]
	v_mfma_f32_16x16x32_bf16 v[124:127], v[132:135], v[180:183], v[124:127]
	v_mfma_f32_16x16x32_bf16 v[120:123], v[140:143], v[180:183], v[120:123]
	v_mfma_f32_16x16x32_bf16 v[108:111], v[132:135], v[196:199], v[108:111]
	v_mfma_f32_16x16x32_bf16 v[104:107], v[140:143], v[196:199], v[104:107]
	v_mfma_f32_16x16x32_bf16 v[92:95], v[132:135], v[206:209], v[92:95]
	v_mfma_f32_16x16x32_bf16 v[88:91], v[140:143], v[206:209], v[88:91]
	v_mfma_f32_16x16x32_bf16 v[76:79], v[132:135], v[214:217], v[76:79]
	v_mfma_f32_16x16x32_bf16 v[72:75], v[140:143], v[214:217], v[72:75]
	s_setprio 0
	s_setprio 1
	v_mfma_f32_16x16x32_bf16 v[116:119], v[144:147], v[176:179], v[116:119]
	v_mfma_f32_16x16x32_bf16 v[112:115], v[168:171], v[176:179], v[112:115]
	v_mfma_f32_16x16x32_bf16 v[100:103], v[144:147], v[192:195], v[100:103]
	v_mfma_f32_16x16x32_bf16 v[96:99], v[168:171], v[192:195], v[96:99]
	v_mfma_f32_16x16x32_bf16 v[84:87], v[144:147], v[202:205], v[84:87]
	v_mfma_f32_16x16x32_bf16 v[80:83], v[168:171], v[202:205], v[80:83]
	v_mfma_f32_16x16x32_bf16 v[68:71], v[144:147], v[210:213], v[68:71]
	v_mfma_f32_16x16x32_bf16 v[64:67], v[168:171], v[210:213], v[64:67]
	v_mfma_f32_16x16x32_bf16 v[116:119], v[148:151], v[180:183], v[116:119]
	v_mfma_f32_16x16x32_bf16 v[112:115], v[172:175], v[180:183], v[112:115]
	v_mfma_f32_16x16x32_bf16 v[100:103], v[148:151], v[196:199], v[100:103]
	v_mfma_f32_16x16x32_bf16 v[96:99], v[172:175], v[196:199], v[96:99]
	v_mfma_f32_16x16x32_bf16 v[84:87], v[148:151], v[206:209], v[84:87]
	v_mfma_f32_16x16x32_bf16 v[80:83], v[172:175], v[206:209], v[80:83]
	v_mfma_f32_16x16x32_bf16 v[68:71], v[148:151], v[214:217], v[68:71]
	v_mfma_f32_16x16x32_bf16 v[64:67], v[172:175], v[214:217], v[64:67]
	s_setprio 0
	s_barrier
; #define PG8_STAGE(bufoff, gbase, voff) do { _Pragma("unroll") for (int _i = 0; _i < 2; ++_i) \
;         __builtin_amdgcn_global_load_lds((const unsigned*)((const char*)(gbase) + (voff)[_i]), (PG8_LAS unsigned*)(lds + (bufoff) + ldsw + _i * 8192), 16, 0, 0); } while (0)
; #define PG8_LDA(dst, b, h) do { _Pragma("unroll") for (int m = 0; m < 4; ++m) _Pragma("unroll") for (int k = 0; k < 2; ++k) dst[m][k] = *(const PG8_LAS bf16x8*)(lds + PG8_SA(b, h) + aoff + m * 2048 + k * 1024); } while (0)
; #define PG8_MMA(ai, bj, At, Bt) do { __builtin_amdgcn_s_setprio(1); _Pragma("unroll") for (int m = 0; m < 4; ++m) _Pragma("unroll") for (int n = 0; n < 2; ++n) _Pragma("unroll") for (int k = 0; k < 2; ++k) \
;         acc[ai][bj][m][n] = __builtin_amdgcn_mfma_f32_16x16x32_bf16(Bt[n][k], At[m][k], acc[ai][bj][m][n], 0, 0, 0); __builtin_amdgcn_s_setprio(0); } while (0)
; #define PG8_WAIT_V(n) asm volatile("s_waitcnt vmcnt(" #n ")" ::: "memory")
; #define PG8_WAIT_L(n) asm volatile("s_waitcnt lgkmcnt(" #n ")" ::: "memory")
; #define PG8_BAR __builtin_amdgcn_s_barrier()
; #define PG8_SCHED __builtin_amdgcn_sched_barrier(0)
; template <class Epi, class Sched, bool ALIGN_EPI = false, bool SP2 = false>
; __device__ __forceinline__ void gemm_phase(PG8_LAS unsigned char* lds, const Gemm g, const Sched& S, const Epi& E, int tid_in) {
;     ...
;         for (int t = 0; t < nt; t += 2) {
;             const bool last = (t == nt - 2);
;             const char* a1 = cA + (size_t)(t + 1) * kstep;
;             const char* a2 = last ? nA : cA + (size_t)(t + 2) * kstep; const char* b2 = last ? nB : cB + (size_t)(t + 2) * kstep;
;     ...
;             PG8_LDA(At, 1, 1); PG8_STAGE(PG8_SB(1, 0), b3, voffB); PG8_STAGE(PG8_SB(1, 1), b3 + hstep, voffB); PG8_STAGE(PG8_SA(1, 0), a3, voffA);
;             PG8_WAIT_V(8); PG8_WAIT_L(0); PG8_BAR; PG8_MMA(1, 0, At, B0); PG8_MMA(1, 1, At, B1); PG8_BAR; PG8_SCHED;
	s_add_i32 s44, s58, s5
	v_lshl_add_u64 v[184:185], v[184:185], 0, s[20:21]
	s_mov_b32 m0, s44
	ds_read_b128 v[176:179], v191 offset:49152
	ds_read_b128 v[180:183], v191 offset:50176
	ds_read_b128 v[192:195], v191 offset:51200
	ds_read_b128 v[196:199], v191 offset:52224
	ds_read_b128 v[202:205], v191 offset:53248
	ds_read_b128 v[206:209], v191 offset:54272
	ds_read_b128 v[210:213], v191 offset:55296
	ds_read_b128 v[214:217], v191 offset:56320
	global_load_lds_dwordx4 v[184:185], off
	s_add_i32 m0, s44, 0x2000
	s_add_u32 s42, s42, 0x40080
	v_lshl_add_u64 v[184:185], v[218:219], 0, s[20:21]
	s_addc_u32 s43, s43, 0
	s_add_i32 s44, s59, s5
	global_load_lds_dwordx4 v[184:185], off
	v_lshl_add_u64 v[184:185], s[42:43], 0, v[154:155]
	s_mov_b32 m0, s44
	s_nop 0
	global_load_lds_dwordx4 v[184:185], off
	v_lshl_add_u64 v[184:185], s[42:43], 0, v[158:159]
	s_add_i32 m0, s44, 0x2000
	s_nop 0
	global_load_lds_dwordx4 v[184:185], off
	v_lshl_add_u64 v[184:185], v[220:221], 0, s[20:21]
	s_mov_b32 m0, s46
	s_nop 0
	global_load_lds_dwordx4 v[184:185], off
	v_lshl_add_u64 v[184:185], v[222:223], 0, s[20:21]
	s_mov_b32 m0, s47
	s_nop 0
	global_load_lds_dwordx4 v[184:185], off
	s_waitcnt vmcnt(8)
	s_waitcnt lgkmcnt(0)
	s_barrier
	s_setprio 1
	s_waitcnt lgkmcnt(0)
	v_mfma_f32_16x16x32_bf16 v[60:63], v[128:131], v[176:179], v[60:63]
	v_mfma_f32_16x16x32_bf16 v[56:59], v[136:139], v[176:179], v[56:59]
	v_mfma_f32_16x16x32_bf16 v[44:47], v[128:131], v[192:195], v[44:47]
	v_mfma_f32_16x16x32_bf16 v[40:43], v[136:139], v[192:195], v[40:43]
	v_mfma_f32_16x16x32_bf16 v[28:31], v[128:131], v[202:205], v[28:31]
	v_mfma_f32_16x16x32_bf16 v[24:27], v[136:139], v[202:205], v[24:27]
	v_mfma_f32_16x16x32_bf16 v[12:15], v[128:131], v[210:213], v[12:15]
	v_mfma_f32_16x16x32_bf16 v[8:11], v[136:139], v[210:213], v[8:11]
	v_mfma_f32_16x16x32_bf16 v[60:63], v[132:135], v[180:183], v[60:63]
	v_mfma_f32_16x16x32_bf16 v[56:59], v[140:143], v[180:183], v[56:59]
	v_mfma_f32_16x16x32_bf16 v[44:47], v[132:135], v[196:199], v[44:47]
	v_mfma_f32_16x16x32_bf16 v[40:43], v[140:143], v[196:199], v[40:43]
	v_mfma_f32_16x16x32_bf16 v[28:31], v[132:135], v[206:209], v[28:31]
	v_mfma_f32_16x16x32_bf16 v[24:27], v[140:143], v[206:209], v[24:27]
	v_mfma_f32_16x16x32_bf16 v[12:15], v[132:135], v[214:217], v[12:15]
	v_mfma_f32_16x16x32_bf16 v[8:11], v[140:143], v[214:217], v[8:11]
	s_setprio 0
	s_setprio 1
	v_mfma_f32_16x16x32_bf16 v[52:55], v[144:147], v[176:179], v[52:55]
	v_mfma_f32_16x16x32_bf16 v[48:51], v[168:171], v[176:179], v[48:51]
	v_mfma_f32_16x16x32_bf16 v[36:39], v[144:147], v[192:195], v[36:39]
	v_mfma_f32_16x16x32_bf16 v[32:35], v[168:171], v[192:195], v[32:35]
	v_mfma_f32_16x16x32_bf16 v[20:23], v[144:147], v[202:205], v[20:23]
	v_mfma_f32_16x16x32_bf16 v[16:19], v[168:171], v[202:205], v[16:19]
	v_mfma_f32_16x16x32_bf16 v[4:7], v[144:147], v[210:213], v[4:7]
	v_mfma_f32_16x16x32_bf16 v[0:3], v[168:171], v[210:213], v[0:3]
	v_mfma_f32_16x16x32_bf16 v[52:55], v[148:151], v[180:183], v[52:55]
	v_mfma_f32_16x16x32_bf16 v[48:51], v[172:175], v[180:183], v[48:51]
	v_mfma_f32_16x16x32_bf16 v[36:39], v[148:151], v[196:199], v[36:39]
	v_mfma_f32_16x16x32_bf16 v[32:35], v[172:175], v[196:199], v[32:35]
	v_mfma_f32_16x16x32_bf16 v[20:23], v[148:151], v[206:209], v[20:23]
	v_mfma_f32_16x16x32_bf16 v[16:19], v[172:175], v[206:209], v[16:19]
	v_mfma_f32_16x16x32_bf16 v[4:7], v[148:151], v[214:217], v[4:7]
	v_mfma_f32_16x16x32_bf16 v[0:3], v[172:175], v[214:217], v[0:3]
	s_setprio 0
	s_barrier
	s_add_i32 s57, s57, 2
	s_add_u32 s55, s55, 0x100
	s_addc_u32 s56, s56, 0
	s_add_u32 s40, s40, 0x100
	s_addc_u32 s41, s41, 0
	s_cmp_gt_u32 s57, 13
	s_cbranch_scc0 .LBB0_1956

; #define PG8_STAGE(bufoff, gbase, voff) do { _Pragma("unroll") for (int _i = 0; _i < 2; ++_i) \
;         __builtin_amdgcn_global_load_lds((const unsigned*)((const char*)(gbase) + (voff)[_i]), (PG8_LAS unsigned*)(lds + (bufoff) + ldsw + _i * 8192), 16, 0, 0); } while (0)
; #define PG8_LDA(dst, b, h) do { _Pragma("unroll") for (int m = 0; m < 4; ++m) _Pragma("unroll") for (int k = 0; k < 2; ++k) dst[m][k] = *(const PG8_LAS bf16x8*)(lds + PG8_SA(b, h) + aoff + m * 2048 + k * 1024); } while (0)
; #define PG8_LDB(dst, b, h) do { _Pragma("unroll") for (int n = 0; n < 2; ++n) _Pragma("unroll") for (int k = 0; k < 2; ++k) dst[n][k] = *(const PG8_LAS bf16x8*)(lds + PG8_SB(b, h) + boff + n * 2048 + k * 1024); } while (0)
; #define PG8_MMA(ai, bj, At, Bt) do { __builtin_amdgcn_s_setprio(1); _Pragma("unroll") for (int m = 0; m < 4; ++m) _Pragma("unroll") for (int n = 0; n < 2; ++n) _Pragma("unroll") for (int k = 0; k < 2; ++k) \
;         acc[ai][bj][m][n] = __builtin_amdgcn_mfma_f32_16x16x32_bf16(Bt[n][k], At[m][k], acc[ai][bj][m][n], 0, 0, 0); __builtin_amdgcn_s_setprio(0); } while (0)
; #define PG8_WAIT_V(n) asm volatile("s_waitcnt vmcnt(" #n ")" ::: "memory")
; #define PG8_WAIT_L(n) asm volatile("s_waitcnt lgkmcnt(" #n ")" ::: "memory")
; #define PG8_BAR __builtin_amdgcn_s_barrier()
; #define PG8_SCHED __builtin_amdgcn_sched_barrier(0)
; template <class Epi, class Sched, bool ALIGN_EPI = false, bool SP2 = false>
; __device__ __forceinline__ void gemm_phase(PG8_LAS unsigned char* lds, const Gemm g, const Sched& S, const Epi& E, int tid_in) {
;     ...
;             PG8_LDB(B0, 0, 0); PG8_LDB(B1, 0, 1); PG8_SCHED; PG8_LDA(At, 0, 0); PG8_STAGE(PG8_SA(1, 1), a1 + hstep, voffA);
;             PG8_WAIT_V(8); PG8_WAIT_L(0); PG8_BAR; PG8_MMA(0, 0, At, B0); PG8_MMA(0, 1, At, B1); PG8_BAR; PG8_SCHED;
;             PG8_LDA(At, 0, 1); PG8_STAGE(PG8_SB(0, 0), b2, voffB); PG8_STAGE(PG8_SB(0, 1), b2 + hstep, voffB); PG8_STAGE(PG8_SA(0, 0), a2, voffA);
;             PG8_WAIT_V(8); PG8_WAIT_L(0); PG8_BAR; PG8_MMA(1, 0, At, B0); PG8_MMA(1, 1, At, B1); PG8_BAR; PG8_SCHED;
.Lpk14:
	s_or_b64 s[98:99], s[8:9], 1
	v_lshl_add_u64 v[184:185], s[40:41], 0, v[162:163]
	s_add_i32 m0, s12, 0xc000
	ds_read_b128 v[176:179], v191
	ds_read_b128 v[180:183], v191 offset:1024
	ds_read_b128 v[192:195], v191 offset:2048
	ds_read_b128 v[196:199], v191 offset:3072
	ds_read_b128 v[202:205], v191 offset:4096
	ds_read_b128 v[206:209], v191 offset:5120
	ds_read_b128 v[210:213], v191 offset:6144
	ds_read_b128 v[214:217], v191 offset:7168
	global_load_lds_dwordx4 v[184:185], off
	v_lshl_add_u64 v[184:185], s[40:41], 0, v[160:161]
	s_add_i32 m0, s12, 0xe000
	s_nop 0
	global_load_lds_dwordx4 v[184:185], off
	s_waitcnt vmcnt(8)
	s_waitcnt lgkmcnt(0)
	s_barrier
	s_setprio 1
	s_waitcnt lgkmcnt(0)
	v_mfma_f32_16x16x32_bf16 v[124:127], v[128:131], v[176:179], v[124:127]
	v_mfma_f32_16x16x32_bf16 v[120:123], v[136:139], v[176:179], v[120:123]
	v_mfma_f32_16x16x32_bf16 v[108:111], v[128:131], v[192:195], v[108:111]
	v_mfma_f32_16x16x32_bf16 v[104:107], v[136:139], v[192:195], v[104:107]
	v_mfma_f32_16x16x32_bf16 v[92:95], v[128:131], v[202:205], v[92:95]
	v_mfma_f32_16x16x32_bf16 v[88:91], v[136:139], v[202:205], v[88:91]
	v_mfma_f32_16x16x32_bf16 v[76:79], v[128:131], v[210:213], v[76:79]
	v_mfma_f32_16x16x32_bf16 v[72:75], v[136:139], v[210:213], v[72:75]
	v_mfma_f32_16x16x32_bf16 v[124:127], v[132:135], v[180:183], v[124:127]
	v_mfma_f32_16x16x32_bf16 v[120:123], v[140:143], v[180:183], v[120:123]
	v_mfma_f32_16x16x32_bf16 v[108:111], v[132:135], v[196:199], v[108:111]
	v_mfma_f32_16x16x32_bf16 v[104:107], v[140:143], v[196:199], v[104:107]
	v_mfma_f32_16x16x32_bf16 v[92:95], v[132:135], v[206:209], v[92:95]
	v_mfma_f32_16x16x32_bf16 v[88:91], v[140:143], v[206:209], v[88:91]
	v_mfma_f32_16x16x32_bf16 v[76:79], v[132:135], v[214:217], v[76:79]
	v_mfma_f32_16x16x32_bf16 v[72:75], v[140:143], v[214:217], v[72:75]
	s_setprio 0
	s_setprio 1
	v_mfma_f32_16x16x32_bf16 v[116:119], v[144:147], v[176:179], v[116:119]
	v_mfma_f32_16x16x32_bf16 v[112:115], v[168:171], v[176:179], v[112:115]
	v_mfma_f32_16x16x32_bf16 v[100:103], v[144:147], v[192:195], v[100:103]
	v_mfma_f32_16x16x32_bf16 v[96:99], v[168:171], v[192:195], v[96:99]
	v_mfma_f32_16x16x32_bf16 v[84:87], v[144:147], v[202:205], v[84:87]
	v_mfma_f32_16x16x32_bf16 v[80:83], v[168:171], v[202:205], v[80:83]
	v_mfma_f32_16x16x32_bf16 v[68:71], v[144:147], v[210:213], v[68:71]
	v_mfma_f32_16x16x32_bf16 v[64:67], v[168:171], v[210:213], v[64:67]
	v_mfma_f32_16x16x32_bf16 v[116:119], v[148:151], v[180:183], v[116:119]
	v_mfma_f32_16x16x32_bf16 v[112:115], v[172:175], v[180:183], v[112:115]
	v_mfma_f32_16x16x32_bf16 v[100:103], v[148:151], v[196:199], v[100:103]
	v_mfma_f32_16x16x32_bf16 v[96:99], v[172:175], v[196:199], v[96:99]
	v_mfma_f32_16x16x32_bf16 v[84:87], v[148:151], v[206:209], v[84:87]
	v_mfma_f32_16x16x32_bf16 v[80:83], v[172:175], v[206:209], v[80:83]
	v_mfma_f32_16x16x32_bf16 v[68:71], v[148:151], v[214:217], v[68:71]
	v_mfma_f32_16x16x32_bf16 v[64:67], v[172:175], v[214:217], v[64:67]
	s_setprio 0
	s_barrier
	s_add_i32 s58, s51, s5
	v_lshl_add_u64 v[184:185], s[42:43], 0, v[154:155]
	s_mov_b32 m0, s58
	ds_read_b128 v[176:179], v191 offset:16384
	ds_read_b128 v[180:183], v191 offset:17408
	ds_read_b128 v[192:195], v191 offset:18432
	ds_read_b128 v[196:199], v191 offset:19456
	ds_read_b128 v[202:205], v191 offset:20480
	ds_read_b128 v[206:209], v191 offset:21504
	ds_read_b128 v[210:213], v191 offset:22528
	ds_read_b128 v[214:217], v191 offset:23552
	s_mov_b64 exec, s[98:99]
	global_load_lds_dwordx4 v[184:185], off
	s_mov_b64 exec, -1
	s_add_i32 m0, s58, 0x2000
	s_add_u32 s58, s42, 0x40000
	v_lshl_add_u64 v[218:219], s[42:43], 0, v[158:159]
	s_addc_u32 s59, s43, 0
	s_add_i32 s60, s52, s5
	s_mov_b64 exec, s[98:99]
	global_load_lds_dwordx4 v[218:219], off
	s_mov_b64 exec, -1
	v_lshl_add_u64 v[220:221], s[58:59], 0, v[154:155]
	s_mov_b32 m0, s60
	v_lshl_add_u64 v[222:223], s[44:45], 0, v[156:157]
	s_mov_b64 exec, s[98:99]
	global_load_lds_dwordx4 v[220:221], off
	s_mov_b64 exec, -1
	v_lshl_add_u64 v[220:221], s[58:59], 0, v[158:159]
	s_add_i32 m0, s60, 0x2000
	s_nop 0
	s_mov_b64 exec, s[98:99]
	global_load_lds_dwordx4 v[220:221], off
	s_mov_b64 exec, -1
	v_lshl_add_u64 v[220:221], s[44:45], 0, v[152:153]
	s_mov_b32 m0, s12
	s_nop 0
	s_mov_b64 exec, s[98:99]
	global_load_lds_dwordx4 v[220:221], off
	s_mov_b64 exec, -1
	s_mov_b32 m0, s13
	s_nop 0
	s_mov_b64 exec, s[98:99]
	global_load_lds_dwordx4 v[222:223], off
	s_mov_b64 exec, -1
	s_waitcnt vmcnt(8)
	s_waitcnt lgkmcnt(0)
	s_barrier
; #define PG8_STAGE(bufoff, gbase, voff) do { _Pragma("unroll") for (int _i = 0; _i < 2; ++_i) \
;         __builtin_amdgcn_global_load_lds((const unsigned*)((const char*)(gbase) + (voff)[_i]), (PG8_LAS unsigned*)(lds + (bufoff) + ldsw + _i * 8192), 16, 0, 0); } while (0)
; #define PG8_LDA(dst, b, h) do { _Pragma("unroll") for (int m = 0; m < 4; ++m) _Pragma("unroll") for (int k = 0; k < 2; ++k) dst[m][k] = *(const PG8_LAS bf16x8*)(lds + PG8_SA(b, h) + aoff + m * 2048 + k * 1024); } while (0)
; #define PG8_LDB(dst, b, h) do { _Pragma("unroll") for (int n = 0; n < 2; ++n) _Pragma("unroll") for (int k = 0; k < 2; ++k) dst[n][k] = *(const PG8_LAS bf16x8*)(lds + PG8_SB(b, h) + boff + n * 2048 + k * 1024); } while (0)
; #define PG8_MMA(ai, bj, At, Bt) do { __builtin_amdgcn_s_setprio(1); _Pragma("unroll") for (int m = 0; m < 4; ++m) _Pragma("unroll") for (int n = 0; n < 2; ++n) _Pragma("unroll") for (int k = 0; k < 2; ++k) \
;         acc[ai][bj][m][n] = __builtin_amdgcn_mfma_f32_16x16x32_bf16(Bt[n][k], At[m][k], acc[ai][bj][m][n], 0, 0, 0); __builtin_amdgcn_s_setprio(0); } while (0)
; #define PG8_WAIT_V(n) asm volatile("s_waitcnt vmcnt(" #n ")" ::: "memory")
; #define PG8_WAIT_L(n) asm volatile("s_waitcnt lgkmcnt(" #n ")" ::: "memory")
; #define PG8_BAR __builtin_amdgcn_s_barrier()
; #define PG8_SCHED __builtin_amdgcn_sched_barrier(0)
; template <class Epi, class Sched, bool ALIGN_EPI = false, bool SP2 = false>
; __device__ __forceinline__ void gemm_phase(PG8_LAS unsigned char* lds, const Gemm g, const Sched& S, const Epi& E, int tid_in) {
;     ...
;             PG8_WAIT_V(8); PG8_WAIT_L(0); PG8_BAR; PG8_MMA(1, 0, At, B0); PG8_MMA(1, 1, At, B1); PG8_BAR; PG8_SCHED;
;             PG8_LDB(B0, 1, 0); PG8_LDB(B1, 1, 1); PG8_SCHED; PG8_LDA(At, 1, 0); PG8_STAGE(PG8_SA(0, 1), a2 + hstep, voffA);
;             PG8_WAIT_V(8); PG8_WAIT_L(0); PG8_BAR; PG8_MMA(0, 0, At, B0); PG8_MMA(0, 1, At, B1); PG8_BAR; PG8_SCHED;
	s_setprio 1
	s_waitcnt lgkmcnt(0)
	v_mfma_f32_16x16x32_bf16 v[60:63], v[128:131], v[176:179], v[60:63]
	v_mfma_f32_16x16x32_bf16 v[56:59], v[136:139], v[176:179], v[56:59]
	v_mfma_f32_16x16x32_bf16 v[44:47], v[128:131], v[192:195], v[44:47]
	v_mfma_f32_16x16x32_bf16 v[40:43], v[136:139], v[192:195], v[40:43]
	v_mfma_f32_16x16x32_bf16 v[28:31], v[128:131], v[202:205], v[28:31]
	v_mfma_f32_16x16x32_bf16 v[24:27], v[136:139], v[202:205], v[24:27]
	v_mfma_f32_16x16x32_bf16 v[12:15], v[128:131], v[210:213], v[12:15]
	v_mfma_f32_16x16x32_bf16 v[8:11], v[136:139], v[210:213], v[8:11]
	v_mfma_f32_16x16x32_bf16 v[60:63], v[132:135], v[180:183], v[60:63]
	v_mfma_f32_16x16x32_bf16 v[56:59], v[140:143], v[180:183], v[56:59]
	v_mfma_f32_16x16x32_bf16 v[44:47], v[132:135], v[196:199], v[44:47]
	v_mfma_f32_16x16x32_bf16 v[40:43], v[140:143], v[196:199], v[40:43]
	v_mfma_f32_16x16x32_bf16 v[28:31], v[132:135], v[206:209], v[28:31]
	v_mfma_f32_16x16x32_bf16 v[24:27], v[140:143], v[206:209], v[24:27]
	v_mfma_f32_16x16x32_bf16 v[12:15], v[132:135], v[214:217], v[12:15]
	v_mfma_f32_16x16x32_bf16 v[8:11], v[140:143], v[214:217], v[8:11]
	s_setprio 0
	s_setprio 1
	v_mfma_f32_16x16x32_bf16 v[52:55], v[144:147], v[176:179], v[52:55]
	v_mfma_f32_16x16x32_bf16 v[48:51], v[168:171], v[176:179], v[48:51]
	v_mfma_f32_16x16x32_bf16 v[36:39], v[144:147], v[192:195], v[36:39]
	v_mfma_f32_16x16x32_bf16 v[32:35], v[168:171], v[192:195], v[32:35]
	v_mfma_f32_16x16x32_bf16 v[20:23], v[144:147], v[202:205], v[20:23]
	v_mfma_f32_16x16x32_bf16 v[16:19], v[168:171], v[202:205], v[16:19]
	v_mfma_f32_16x16x32_bf16 v[4:7], v[144:147], v[210:213], v[4:7]
	v_mfma_f32_16x16x32_bf16 v[0:3], v[168:171], v[210:213], v[0:3]
	v_mfma_f32_16x16x32_bf16 v[52:55], v[148:151], v[180:183], v[52:55]
	v_mfma_f32_16x16x32_bf16 v[48:51], v[172:175], v[180:183], v[48:51]
	v_mfma_f32_16x16x32_bf16 v[36:39], v[148:151], v[196:199], v[36:39]
	v_mfma_f32_16x16x32_bf16 v[32:35], v[172:175], v[196:199], v[32:35]
	v_mfma_f32_16x16x32_bf16 v[20:23], v[148:151], v[206:209], v[20:23]
	v_mfma_f32_16x16x32_bf16 v[16:19], v[172:175], v[206:209], v[16:19]
	v_mfma_f32_16x16x32_bf16 v[4:7], v[148:151], v[214:217], v[4:7]
	v_mfma_f32_16x16x32_bf16 v[0:3], v[172:175], v[214:217], v[0:3]
	s_setprio 0
	s_barrier
	s_add_i32 s58, 0, 0x18000
	s_add_i32 s59, 0, 0x1c000
	v_add_u32_e32 v140, s58, v187
	v_add_u32_e32 v172, s59, v187
	ds_read_b128 v[128:131], v140
	ds_read_b128 v[132:135], v140 offset:1024
	ds_read_b128 v[136:139], v140 offset:2048
	ds_read_b128 v[140:143], v140 offset:3072
	ds_read_b128 v[144:147], v172
	ds_read_b128 v[148:151], v172 offset:1024
	ds_read_b128 v[168:171], v172 offset:2048
	ds_read_b128 v[172:175], v172 offset:3072
	s_add_u32 s44, s44, 0x40000
	s_addc_u32 s45, s45, 0
	s_mov_b32 m0, s30
	v_lshl_add_u64 v[224:225], s[44:45], 0, v[152:153]
	ds_read_b128 v[176:179], v191 offset:32768
	ds_read_b128 v[180:183], v191 offset:33792
	ds_read_b128 v[192:195], v191 offset:34816
	ds_read_b128 v[196:199], v191 offset:35840
	ds_read_b128 v[202:205], v191 offset:36864
	ds_read_b128 v[206:209], v191 offset:37888
	ds_read_b128 v[210:213], v191 offset:38912
	ds_read_b128 v[214:217], v191 offset:39936
	s_mov_b64 exec, s[98:99]
	global_load_lds_dwordx4 v[224:225], off
	s_mov_b64 exec, -1
	v_lshl_add_u64 v[224:225], s[44:45], 0, v[156:157]
	s_mov_b32 m0, s31
	s_nop 0
	s_mov_b64 exec, s[98:99]
	global_load_lds_dwordx4 v[224:225], off
	s_mov_b64 exec, -1
	s_waitcnt vmcnt(8)
	s_waitcnt lgkmcnt(0)
	s_barrier
	s_setprio 1
	s_waitcnt lgkmcnt(0)
	v_mfma_f32_16x16x32_bf16 v[124:127], v[128:131], v[176:179], v[124:127]
	v_mfma_f32_16x16x32_bf16 v[120:123], v[136:139], v[176:179], v[120:123]
	v_mfma_f32_16x16x32_bf16 v[108:111], v[128:131], v[192:195], v[108:111]
	v_mfma_f32_16x16x32_bf16 v[104:107], v[136:139], v[192:195], v[104:107]
	v_mfma_f32_16x16x32_bf16 v[92:95], v[128:131], v[202:205], v[92:95]
	v_mfma_f32_16x16x32_bf16 v[88:91], v[136:139], v[202:205], v[88:91]
	v_mfma_f32_16x16x32_bf16 v[76:79], v[128:131], v[210:213], v[76:79]
	v_mfma_f32_16x16x32_bf16 v[72:75], v[136:139], v[210:213], v[72:75]
	v_mfma_f32_16x16x32_bf16 v[124:127], v[132:135], v[180:183], v[124:127]
	v_mfma_f32_16x16x32_bf16 v[120:123], v[140:143], v[180:183], v[120:123]
	v_mfma_f32_16x16x32_bf16 v[108:111], v[132:135], v[196:199], v[108:111]
	v_mfma_f32_16x16x32_bf16 v[104:107], v[140:143], v[196:199], v[104:107]
	v_mfma_f32_16x16x32_bf16 v[92:95], v[132:135], v[206:209], v[92:95]
	v_mfma_f32_16x16x32_bf16 v[88:91], v[140:143], v[206:209], v[88:91]
	v_mfma_f32_16x16x32_bf16 v[76:79], v[132:135], v[214:217], v[76:79]
	v_mfma_f32_16x16x32_bf16 v[72:75], v[140:143], v[214:217], v[72:75]
	s_setprio 0
	s_setprio 1
	v_mfma_f32_16x16x32_bf16 v[116:119], v[144:147], v[176:179], v[116:119]
	v_mfma_f32_16x16x32_bf16 v[112:115], v[168:171], v[176:179], v[112:115]
	v_mfma_f32_16x16x32_bf16 v[100:103], v[144:147], v[192:195], v[100:103]
	v_mfma_f32_16x16x32_bf16 v[96:99], v[168:171], v[192:195], v[96:99]
	v_mfma_f32_16x16x32_bf16 v[84:87], v[144:147], v[202:205], v[84:87]
	v_mfma_f32_16x16x32_bf16 v[80:83], v[168:171], v[202:205], v[80:83]
	v_mfma_f32_16x16x32_bf16 v[68:71], v[144:147], v[210:213], v[68:71]
	v_mfma_f32_16x16x32_bf16 v[64:67], v[168:171], v[210:213], v[64:67]
	v_mfma_f32_16x16x32_bf16 v[116:119], v[148:151], v[180:183], v[116:119]
	v_mfma_f32_16x16x32_bf16 v[112:115], v[172:175], v[180:183], v[112:115]
	v_mfma_f32_16x16x32_bf16 v[100:103], v[148:151], v[196:199], v[100:103]
	v_mfma_f32_16x16x32_bf16 v[96:99], v[172:175], v[196:199], v[96:99]
	v_mfma_f32_16x16x32_bf16 v[84:87], v[148:151], v[206:209], v[84:87]
	v_mfma_f32_16x16x32_bf16 v[80:83], v[172:175], v[206:209], v[80:83]
	v_mfma_f32_16x16x32_bf16 v[68:71], v[148:151], v[214:217], v[68:71]
	v_mfma_f32_16x16x32_bf16 v[64:67], v[172:175], v[214:217], v[64:67]
	s_setprio 0
	s_barrier
; #define PG8_STAGE(bufoff, gbase, voff) do { _Pragma("unroll") for (int _i = 0; _i < 2; ++_i) \
;         __builtin_amdgcn_global_load_lds((const unsigned*)((const char*)(gbase) + (voff)[_i]), (PG8_LAS unsigned*)(lds + (bufoff) + ldsw + _i * 8192), 16, 0, 0); } while (0)
; #define PG8_LDA(dst, b, h) do { _Pragma("unroll") for (int m = 0; m < 4; ++m) _Pragma("unroll") for (int k = 0; k < 2; ++k) dst[m][k] = *(const PG8_LAS bf16x8*)(lds + PG8_SA(b, h) + aoff + m * 2048 + k * 1024); } while (0)
; #define PG8_MMA(ai, bj, At, Bt) do { __builtin_amdgcn_s_setprio(1); _Pragma("unroll") for (int m = 0; m < 4; ++m) _Pragma("unroll") for (int n = 0; n < 2; ++n) _Pragma("unroll") for (int k = 0; k < 2; ++k) \
;         acc[ai][bj][m][n] = __builtin_amdgcn_mfma_f32_16x16x32_bf16(Bt[n][k], At[m][k], acc[ai][bj][m][n], 0, 0, 0); __builtin_amdgcn_s_setprio(0); } while (0)
; #define PG8_WAIT_V(n) asm volatile("s_waitcnt vmcnt(" #n ")" ::: "memory")
; #define PG8_WAIT_L(n) asm volatile("s_waitcnt lgkmcnt(" #n ")" ::: "memory")
; #define PG8_BAR __builtin_amdgcn_s_barrier()
; #define PG8_SCHED __builtin_amdgcn_sched_barrier(0)
; template <class Epi, class Sched, bool ALIGN_EPI = false, bool SP2 = false>
; __device__ __forceinline__ void gemm_phase(PG8_LAS unsigned char* lds, const Gemm g, const Sched& S, const Epi& E, int tid_in) {
;     ...
;             PG8_LDA(At, 1, 1); PG8_STAGE(PG8_SB(1, 0), b3, voffB); PG8_STAGE(PG8_SB(1, 1), b3 + hstep, voffB); PG8_STAGE(PG8_SA(1, 0), a3, voffA);
;             PG8_WAIT_V(8); PG8_WAIT_L(0); PG8_BAR; PG8_MMA(1, 0, At, B0); PG8_MMA(1, 1, At, B1); PG8_BAR; PG8_SCHED;
	s_add_i32 s44, s58, s5
	v_lshl_add_u64 v[184:185], v[184:185], 0, s[20:21]
	s_mov_b32 m0, s44
	ds_read_b128 v[176:179], v191 offset:49152
	ds_read_b128 v[180:183], v191 offset:50176
	ds_read_b128 v[192:195], v191 offset:51200
	ds_read_b128 v[196:199], v191 offset:52224
	ds_read_b128 v[202:205], v191 offset:53248
	ds_read_b128 v[206:209], v191 offset:54272
	ds_read_b128 v[210:213], v191 offset:55296
	ds_read_b128 v[214:217], v191 offset:56320
	s_mov_b64 exec, s[98:99]
	global_load_lds_dwordx4 v[184:185], off
	s_mov_b64 exec, -1
	s_add_i32 m0, s44, 0x2000
	s_add_u32 s42, s42, 0x40080
	v_lshl_add_u64 v[184:185], v[218:219], 0, s[20:21]
	s_addc_u32 s43, s43, 0
	s_add_i32 s44, s59, s5
	s_mov_b64 exec, s[98:99]
	global_load_lds_dwordx4 v[184:185], off
	s_mov_b64 exec, -1
	v_lshl_add_u64 v[184:185], s[42:43], 0, v[154:155]
	s_mov_b32 m0, s44
	s_nop 0
	s_mov_b64 exec, s[98:99]
	global_load_lds_dwordx4 v[184:185], off
	s_mov_b64 exec, -1
	v_lshl_add_u64 v[184:185], s[42:43], 0, v[158:159]
	s_add_i32 m0, s44, 0x2000
	s_nop 0
	s_mov_b64 exec, s[98:99]
	global_load_lds_dwordx4 v[184:185], off
	s_mov_b64 exec, -1
	v_lshl_add_u64 v[184:185], v[220:221], 0, s[20:21]
	s_mov_b32 m0, s46
	s_nop 0
	s_mov_b64 exec, s[98:99]
	global_load_lds_dwordx4 v[184:185], off
	s_mov_b64 exec, -1
	v_lshl_add_u64 v[184:185], v[222:223], 0, s[20:21]
	s_mov_b32 m0, s47
	s_nop 0
	s_mov_b64 exec, s[98:99]
	global_load_lds_dwordx4 v[184:185], off
	s_mov_b64 exec, -1
	s_waitcnt vmcnt(8)
	s_waitcnt lgkmcnt(0)
	s_barrier
	s_setprio 1
	s_waitcnt lgkmcnt(0)
	v_mfma_f32_16x16x32_bf16 v[60:63], v[128:131], v[176:179], v[60:63]
	v_mfma_f32_16x16x32_bf16 v[56:59], v[136:139], v[176:179], v[56:59]
	v_mfma_f32_16x16x32_bf16 v[44:47], v[128:131], v[192:195], v[44:47]
	v_mfma_f32_16x16x32_bf16 v[40:43], v[136:139], v[192:195], v[40:43]
	v_mfma_f32_16x16x32_bf16 v[28:31], v[128:131], v[202:205], v[28:31]
	v_mfma_f32_16x16x32_bf16 v[24:27], v[136:139], v[202:205], v[24:27]
	v_mfma_f32_16x16x32_bf16 v[12:15], v[128:131], v[210:213], v[12:15]
	v_mfma_f32_16x16x32_bf16 v[8:11], v[136:139], v[210:213], v[8:11]
	v_mfma_f32_16x16x32_bf16 v[60:63], v[132:135], v[180:183], v[60:63]
	v_mfma_f32_16x16x32_bf16 v[56:59], v[140:143], v[180:183], v[56:59]
	v_mfma_f32_16x16x32_bf16 v[44:47], v[132:135], v[196:199], v[44:47]
	v_mfma_f32_16x16x32_bf16 v[40:43], v[140:143], v[196:199], v[40:43]
	v_mfma_f32_16x16x32_bf16 v[28:31], v[132:135], v[206:209], v[28:31]
	v_mfma_f32_16x16x32_bf16 v[24:27], v[140:143], v[206:209], v[24:27]
	v_mfma_f32_16x16x32_bf16 v[12:15], v[132:135], v[214:217], v[12:15]
	v_mfma_f32_16x16x32_bf16 v[8:11], v[140:143], v[214:217], v[8:11]
	s_setprio 0
	s_setprio 1
	v_mfma_f32_16x16x32_bf16 v[52:55], v[144:147], v[176:179], v[52:55]
	v_mfma_f32_16x16x32_bf16 v[48:51], v[168:171], v[176:179], v[48:51]
	v_mfma_f32_16x16x32_bf16 v[36:39], v[144:147], v[192:195], v[36:39]
	v_mfma_f32_16x16x32_bf16 v[32:35], v[168:171], v[192:195], v[32:35]
	v_mfma_f32_16x16x32_bf16 v[20:23], v[144:147], v[202:205], v[20:23]
	v_mfma_f32_16x16x32_bf16 v[16:19], v[168:171], v[202:205], v[16:19]
	v_mfma_f32_16x16x32_bf16 v[4:7], v[144:147], v[210:213], v[4:7]
	v_mfma_f32_16x16x32_bf16 v[0:3], v[168:171], v[210:213], v[0:3]
	v_mfma_f32_16x16x32_bf16 v[52:55], v[148:151], v[180:183], v[52:55]
	v_mfma_f32_16x16x32_bf16 v[48:51], v[172:175], v[180:183], v[48:51]
	v_mfma_f32_16x16x32_bf16 v[36:39], v[148:151], v[196:199], v[36:39]
	v_mfma_f32_16x16x32_bf16 v[32:35], v[172:175], v[196:199], v[32:35]
	v_mfma_f32_16x16x32_bf16 v[20:23], v[148:151], v[206:209], v[20:23]
	v_mfma_f32_16x16x32_bf16 v[16:19], v[172:175], v[206:209], v[16:19]
	v_mfma_f32_16x16x32_bf16 v[4:7], v[148:151], v[214:217], v[4:7]
	v_mfma_f32_16x16x32_bf16 v[0:3], v[172:175], v[214:217], v[0:3]
	s_setprio 0
	s_barrier
	s_add_i32 s57, s57, 2
	s_add_u32 s55, s55, 0x100
	s_addc_u32 s56, s56, 0
	s_add_u32 s40, s40, 0x100
	s_addc_u32 s41, s41, 0
	s_cmp_gt_u32 s57, 13
	s_branch .Lpost14

; #define PG8_STAGE(bufoff, gbase, voff) do { _Pragma("unroll") for (int _i = 0; _i < 2; ++_i) \
;         __builtin_amdgcn_global_load_lds((const unsigned*)((const char*)(gbase) + (voff)[_i]), (PG8_LAS unsigned*)(lds + (bufoff) + ldsw + _i * 8192), 16, 0, 0); } while (0)
; #define PG8_LDA(dst, b, h) do { _Pragma("unroll") for (int m = 0; m < 4; ++m) _Pragma("unroll") for (int k = 0; k < 2; ++k) dst[m][k] = *(const PG8_LAS bf16x8*)(lds + PG8_SA(b, h) + aoff + m * 2048 + k * 1024); } while (0)
; #define PG8_LDB(dst, b, h) do { _Pragma("unroll") for (int n = 0; n < 2; ++n) _Pragma("unroll") for (int k = 0; k < 2; ++k) dst[n][k] = *(const PG8_LAS bf16x8*)(lds + PG8_SB(b, h) + boff + n * 2048 + k * 1024); } while (0)
; #define PG8_MMA(ai, bj, At, Bt) do { __builtin_amdgcn_s_setprio(1); _Pragma("unroll") for (int m = 0; m < 4; ++m) _Pragma("unroll") for (int n = 0; n < 2; ++n) _Pragma("unroll") for (int k = 0; k < 2; ++k) \
;         acc[ai][bj][m][n] = __builtin_amdgcn_mfma_f32_16x16x32_bf16(Bt[n][k], At[m][k], acc[ai][bj][m][n], 0, 0, 0); __builtin_amdgcn_s_setprio(0); } while (0)
; #define PG8_WAIT_V(n) asm volatile("s_waitcnt vmcnt(" #n ")" ::: "memory")
; #define PG8_BAR __builtin_amdgcn_s_barrier()
; template <class Epi, class Sched, bool ALIGN_EPI = false, bool SP2 = false>
; __device__ __forceinline__ void gemm_phase(PG8_LAS unsigned char* lds, const Gemm g, const Sched& S, const Epi& E, int tid_in) {
;     ...
;         for (int t = 0; t < nt; t += 2) {
;             const bool last = (t == nt - 2);
;             const char* a1 = cA + (size_t)(t + 1) * kstep;
;             const char* a2 = last ? nA : cA + (size_t)(t + 2) * kstep; const char* b2 = last ? nB : cB + (size_t)(t + 2) * kstep;
;             const char* a3 = a2 + kstep; const char* b3 = b2 + kstep;
;             if (last && has_next) S.a_ready(nxt);
;             if constexpr (SP2) {
;             PG8_LDB(B0, 0, 0); PG8_LDB(B1, 0, 1); PG8_SCHED; PG8_LDA(At, 0, 0); PG8_STAGE(PG8_SA(1, 1), a1 + hstep, voffA);
;             PG8_WAIT_V(8); PG8_WAIT_L(0); PG8_BAR; PG8_MMA(0, 0, At, B0); PG8_MMA(0, 1, At, B1); PG8_BAR; PG8_SCHED;
;             PG8_LDA(At, 0, 1); PG8_STAGE(PG8_SB(0, 0), b2, voffB); PG8_STAGE(PG8_SB(0, 1), b2 + hstep, voffB); PG8_STAGE(PG8_SA(0, 0), a2, voffA);
;             PG8_WAIT_V(8); PG8_WAIT_L(0); PG8_BAR; PG8_MMA(1, 0, At, B0); PG8_MMA(1, 1, At, B1); PG8_BAR; PG8_SCHED;
.LBB0_2040:
	ds_read_b128 v[146:149], v165
	ds_read_b128 v[176:179], v165 offset:1024
	ds_read_b128 v[180:183], v165 offset:2048
	ds_read_b128 v[184:187], v165 offset:3072
	ds_read_b128 v[188:191], v169
	ds_read_b128 v[192:195], v169 offset:1024
	ds_read_b128 v[196:199], v169 offset:2048
	ds_read_b128 v[202:205], v169 offset:3072
	s_add_u32 s34, s26, 0xfffc0080
	s_addc_u32 s35, s27, -1
	s_cmp_eq_u32 s53, 12
	s_cselect_b32 s37, s19, s35
	s_cselect_b32 s36, s49, s34
	s_cselect_b32 s35, s17, s52
	s_cselect_b32 s34, s50, s51
	s_cbranch_scc1 .Lpk15
	v_lshl_add_u64 v[150:151], s[26:27], 0, v[140:141]
	s_add_i32 m0, s25, 0xc000
	ds_read_b128 v[206:209], v173
	ds_read_b128 v[210:213], v173 offset:1024
	ds_read_b128 v[214:217], v173 offset:2048
	ds_read_b128 v[218:221], v173 offset:3072
	ds_read_b128 v[222:225], v173 offset:4096
	ds_read_b128 v[226:229], v173 offset:5120
	ds_read_b128 v[230:233], v173 offset:6144
	ds_read_b128 v[234:237], v173 offset:7168
	global_load_lds_dwordx4 v[150:151], off
	v_lshl_add_u64 v[150:151], s[26:27], 0, v[138:139]
	s_add_i32 m0, s25, 0xe000
	s_nop 0
	global_load_lds_dwordx4 v[150:151], off
	s_waitcnt vmcnt(8)
	s_waitcnt lgkmcnt(0)
	s_barrier
	s_setprio 1
	s_waitcnt lgkmcnt(0)
	v_mfma_f32_16x16x32_bf16 v[124:127], v[146:149], v[206:209], v[124:127]
	v_mfma_f32_16x16x32_bf16 v[120:123], v[180:183], v[206:209], v[120:123]
	v_mfma_f32_16x16x32_bf16 v[108:111], v[146:149], v[214:217], v[108:111]
	v_mfma_f32_16x16x32_bf16 v[104:107], v[180:183], v[214:217], v[104:107]
	v_mfma_f32_16x16x32_bf16 v[92:95], v[146:149], v[222:225], v[92:95]
	v_mfma_f32_16x16x32_bf16 v[88:91], v[180:183], v[222:225], v[88:91]
	v_mfma_f32_16x16x32_bf16 v[76:79], v[146:149], v[230:233], v[76:79]
	v_mfma_f32_16x16x32_bf16 v[72:75], v[180:183], v[230:233], v[72:75]
	v_mfma_f32_16x16x32_bf16 v[124:127], v[176:179], v[210:213], v[124:127]
	v_mfma_f32_16x16x32_bf16 v[120:123], v[184:187], v[210:213], v[120:123]
	v_mfma_f32_16x16x32_bf16 v[108:111], v[176:179], v[218:221], v[108:111]
	v_mfma_f32_16x16x32_bf16 v[104:107], v[184:187], v[218:221], v[104:107]
	v_mfma_f32_16x16x32_bf16 v[92:95], v[176:179], v[226:229], v[92:95]
	v_mfma_f32_16x16x32_bf16 v[88:91], v[184:187], v[226:229], v[88:91]
	v_mfma_f32_16x16x32_bf16 v[76:79], v[176:179], v[234:237], v[76:79]
	v_mfma_f32_16x16x32_bf16 v[72:75], v[184:187], v[234:237], v[72:75]
	s_setprio 0
	s_setprio 1
	v_mfma_f32_16x16x32_bf16 v[116:119], v[188:191], v[206:209], v[116:119]
	v_mfma_f32_16x16x32_bf16 v[112:115], v[196:199], v[206:209], v[112:115]
	v_mfma_f32_16x16x32_bf16 v[100:103], v[188:191], v[214:217], v[100:103]
	v_mfma_f32_16x16x32_bf16 v[96:99], v[196:199], v[214:217], v[96:99]
	v_mfma_f32_16x16x32_bf16 v[84:87], v[188:191], v[222:225], v[84:87]
	v_mfma_f32_16x16x32_bf16 v[80:83], v[196:199], v[222:225], v[80:83]
	v_mfma_f32_16x16x32_bf16 v[68:71], v[188:191], v[230:233], v[68:71]
	v_mfma_f32_16x16x32_bf16 v[64:67], v[196:199], v[230:233], v[64:67]
	v_mfma_f32_16x16x32_bf16 v[116:119], v[192:195], v[210:213], v[116:119]
	v_mfma_f32_16x16x32_bf16 v[112:115], v[202:205], v[210:213], v[112:115]
	v_mfma_f32_16x16x32_bf16 v[100:103], v[192:195], v[218:221], v[100:103]
	v_mfma_f32_16x16x32_bf16 v[96:99], v[202:205], v[218:221], v[96:99]
	v_mfma_f32_16x16x32_bf16 v[84:87], v[192:195], v[226:229], v[84:87]
	v_mfma_f32_16x16x32_bf16 v[80:83], v[202:205], v[226:229], v[80:83]
	v_mfma_f32_16x16x32_bf16 v[68:71], v[192:195], v[234:237], v[68:71]
	v_mfma_f32_16x16x32_bf16 v[64:67], v[202:205], v[234:237], v[64:67]
	s_setprio 0
	s_barrier
	s_add_i32 s54, s45, s5
	v_lshl_add_u64 v[150:151], s[34:35], 0, v[132:133]
	s_mov_b32 m0, s54
	ds_read_b128 v[206:209], v173 offset:16384
	ds_read_b128 v[210:213], v173 offset:17408
	ds_read_b128 v[214:217], v173 offset:18432
	ds_read_b128 v[218:221], v173 offset:19456
	ds_read_b128 v[222:225], v173 offset:20480
	ds_read_b128 v[226:229], v173 offset:21504
	ds_read_b128 v[230:233], v173 offset:22528
	ds_read_b128 v[234:237], v173 offset:23552
	global_load_lds_dwordx4 v[150:151], off
	s_add_i32 m0, s54, 0x2000
	s_add_u32 s54, s34, 0x40000
	v_lshl_add_u64 v[154:155], s[34:35], 0, v[128:129]
	s_addc_u32 s55, s35, 0
	s_add_i32 s56, s46, s5
	global_load_lds_dwordx4 v[154:155], off
	v_lshl_add_u64 v[158:159], s[54:55], 0, v[132:133]
	s_mov_b32 m0, s56
	v_lshl_add_u64 v[162:163], s[36:37], 0, v[130:131]
	global_load_lds_dwordx4 v[158:159], off
	v_lshl_add_u64 v[158:159], s[54:55], 0, v[128:129]
	s_add_i32 m0, s56, 0x2000
	s_nop 0
	global_load_lds_dwordx4 v[158:159], off
	v_lshl_add_u64 v[158:159], s[36:37], 0, v[134:135]
	s_mov_b32 m0, s25
	s_nop 0
	global_load_lds_dwordx4 v[158:159], off
	s_mov_b32 m0, s33
	s_nop 0
	global_load_lds_dwordx4 v[162:163], off
	s_waitcnt vmcnt(8)
	s_waitcnt lgkmcnt(0)
	s_barrier
; #define PG8_STAGE(bufoff, gbase, voff) do { _Pragma("unroll") for (int _i = 0; _i < 2; ++_i) \
;         __builtin_amdgcn_global_load_lds((const unsigned*)((const char*)(gbase) + (voff)[_i]), (PG8_LAS unsigned*)(lds + (bufoff) + ldsw + _i * 8192), 16, 0, 0); } while (0)
; #define PG8_LDA(dst, b, h) do { _Pragma("unroll") for (int m = 0; m < 4; ++m) _Pragma("unroll") for (int k = 0; k < 2; ++k) dst[m][k] = *(const PG8_LAS bf16x8*)(lds + PG8_SA(b, h) + aoff + m * 2048 + k * 1024); } while (0)
; #define PG8_LDB(dst, b, h) do { _Pragma("unroll") for (int n = 0; n < 2; ++n) _Pragma("unroll") for (int k = 0; k < 2; ++k) dst[n][k] = *(const PG8_LAS bf16x8*)(lds + PG8_SB(b, h) + boff + n * 2048 + k * 1024); } while (0)
; #define PG8_MMA(ai, bj, At, Bt) do { __builtin_amdgcn_s_setprio(1); _Pragma("unroll") for (int m = 0; m < 4; ++m) _Pragma("unroll") for (int n = 0; n < 2; ++n) _Pragma("unroll") for (int k = 0; k < 2; ++k) \
;         acc[ai][bj][m][n] = __builtin_amdgcn_mfma_f32_16x16x32_bf16(Bt[n][k], At[m][k], acc[ai][bj][m][n], 0, 0, 0); __builtin_amdgcn_s_setprio(0); } while (0)
; #define PG8_WAIT_V(n) asm volatile("s_waitcnt vmcnt(" #n ")" ::: "memory")
; #define PG8_WAIT_L(n) asm volatile("s_waitcnt lgkmcnt(" #n ")" ::: "memory")
; #define PG8_BAR __builtin_amdgcn_s_barrier()
; #define PG8_SCHED __builtin_amdgcn_sched_barrier(0)
; template <class Epi, class Sched, bool ALIGN_EPI = false, bool SP2 = false>
; __device__ __forceinline__ void gemm_phase(PG8_LAS unsigned char* lds, const Gemm g, const Sched& S, const Epi& E, int tid_in) {
;     ...
;             PG8_WAIT_V(8); PG8_WAIT_L(0); PG8_BAR; PG8_MMA(1, 0, At, B0); PG8_MMA(1, 1, At, B1); PG8_BAR; PG8_SCHED;
;             PG8_LDB(B0, 1, 0); PG8_LDB(B1, 1, 1); PG8_SCHED; PG8_LDA(At, 1, 0); PG8_STAGE(PG8_SA(0, 1), a2 + hstep, voffA);
;             PG8_WAIT_V(8); PG8_WAIT_L(0); PG8_BAR; PG8_MMA(0, 0, At, B0); PG8_MMA(0, 1, At, B1); PG8_BAR; PG8_SCHED;
	s_setprio 1
	s_waitcnt lgkmcnt(0)
	v_mfma_f32_16x16x32_bf16 v[60:63], v[146:149], v[206:209], v[60:63]
	v_mfma_f32_16x16x32_bf16 v[56:59], v[180:183], v[206:209], v[56:59]
	v_mfma_f32_16x16x32_bf16 v[44:47], v[146:149], v[214:217], v[44:47]
	v_mfma_f32_16x16x32_bf16 v[40:43], v[180:183], v[214:217], v[40:43]
	v_mfma_f32_16x16x32_bf16 v[28:31], v[146:149], v[222:225], v[28:31]
	v_mfma_f32_16x16x32_bf16 v[24:27], v[180:183], v[222:225], v[24:27]
	v_mfma_f32_16x16x32_bf16 v[12:15], v[146:149], v[230:233], v[12:15]
	v_mfma_f32_16x16x32_bf16 v[8:11], v[180:183], v[230:233], v[8:11]
	v_mfma_f32_16x16x32_bf16 v[60:63], v[176:179], v[210:213], v[60:63]
	v_mfma_f32_16x16x32_bf16 v[56:59], v[184:187], v[210:213], v[56:59]
	v_mfma_f32_16x16x32_bf16 v[44:47], v[176:179], v[218:221], v[44:47]
	v_mfma_f32_16x16x32_bf16 v[40:43], v[184:187], v[218:221], v[40:43]
	v_mfma_f32_16x16x32_bf16 v[28:31], v[176:179], v[226:229], v[28:31]
	v_mfma_f32_16x16x32_bf16 v[24:27], v[184:187], v[226:229], v[24:27]
	v_mfma_f32_16x16x32_bf16 v[12:15], v[176:179], v[234:237], v[12:15]
	v_mfma_f32_16x16x32_bf16 v[8:11], v[184:187], v[234:237], v[8:11]
	s_setprio 0
	s_setprio 1
	v_mfma_f32_16x16x32_bf16 v[52:55], v[188:191], v[206:209], v[52:55]
	v_mfma_f32_16x16x32_bf16 v[48:51], v[196:199], v[206:209], v[48:51]
	v_mfma_f32_16x16x32_bf16 v[36:39], v[188:191], v[214:217], v[36:39]
	v_mfma_f32_16x16x32_bf16 v[32:35], v[196:199], v[214:217], v[32:35]
	v_mfma_f32_16x16x32_bf16 v[20:23], v[188:191], v[222:225], v[20:23]
	v_mfma_f32_16x16x32_bf16 v[16:19], v[196:199], v[222:225], v[16:19]
	v_mfma_f32_16x16x32_bf16 v[4:7], v[188:191], v[230:233], v[4:7]
	v_mfma_f32_16x16x32_bf16 v[0:3], v[196:199], v[230:233], v[0:3]
	v_mfma_f32_16x16x32_bf16 v[52:55], v[192:195], v[210:213], v[52:55]
	v_mfma_f32_16x16x32_bf16 v[48:51], v[202:205], v[210:213], v[48:51]
	v_mfma_f32_16x16x32_bf16 v[36:39], v[192:195], v[218:221], v[36:39]
	v_mfma_f32_16x16x32_bf16 v[32:35], v[202:205], v[218:221], v[32:35]
	v_mfma_f32_16x16x32_bf16 v[20:23], v[192:195], v[226:229], v[20:23]
	v_mfma_f32_16x16x32_bf16 v[16:19], v[202:205], v[226:229], v[16:19]
	v_mfma_f32_16x16x32_bf16 v[4:7], v[192:195], v[234:237], v[4:7]
	v_mfma_f32_16x16x32_bf16 v[0:3], v[202:205], v[234:237], v[0:3]
	s_setprio 0
	s_barrier
	s_add_i32 s54, 0, 0x18000
	v_add_u32_e32 v152, s54, v157
	s_add_i32 s55, 0, 0x1c000
	ds_read_b128 v[146:149], v152
	ds_read_b128 v[176:179], v152 offset:1024
	ds_read_b128 v[180:183], v152 offset:2048
	ds_read_b128 v[184:187], v152 offset:3072
	v_add_u32_e32 v152, s55, v157
	ds_read_b128 v[188:191], v152
	ds_read_b128 v[192:195], v152 offset:1024
	ds_read_b128 v[196:199], v152 offset:2048
	ds_read_b128 v[202:205], v152 offset:3072
	s_add_u32 s36, s36, 0x40000
	s_addc_u32 s37, s37, 0
	s_mov_b32 m0, s38
	v_lshl_add_u64 v[166:167], s[36:37], 0, v[134:135]
	ds_read_b128 v[206:209], v173 offset:32768
	ds_read_b128 v[210:213], v173 offset:33792
	ds_read_b128 v[214:217], v173 offset:34816
	ds_read_b128 v[218:221], v173 offset:35840
	ds_read_b128 v[222:225], v173 offset:36864
	ds_read_b128 v[226:229], v173 offset:37888
	ds_read_b128 v[230:233], v173 offset:38912
	ds_read_b128 v[234:237], v173 offset:39936
	global_load_lds_dwordx4 v[166:167], off
	v_lshl_add_u64 v[166:167], s[36:37], 0, v[130:131]
	s_mov_b32 m0, s39
	s_nop 0
	global_load_lds_dwordx4 v[166:167], off
	s_waitcnt vmcnt(8)
	s_waitcnt lgkmcnt(0)
	s_barrier
	s_setprio 1
	s_waitcnt lgkmcnt(0)
	v_mfma_f32_16x16x32_bf16 v[124:127], v[146:149], v[206:209], v[124:127]
	v_mfma_f32_16x16x32_bf16 v[120:123], v[180:183], v[206:209], v[120:123]
	v_mfma_f32_16x16x32_bf16 v[108:111], v[146:149], v[214:217], v[108:111]
	v_mfma_f32_16x16x32_bf16 v[104:107], v[180:183], v[214:217], v[104:107]
	v_mfma_f32_16x16x32_bf16 v[92:95], v[146:149], v[222:225], v[92:95]
	v_mfma_f32_16x16x32_bf16 v[88:91], v[180:183], v[222:225], v[88:91]
	v_mfma_f32_16x16x32_bf16 v[76:79], v[146:149], v[230:233], v[76:79]
	v_mfma_f32_16x16x32_bf16 v[72:75], v[180:183], v[230:233], v[72:75]
	v_mfma_f32_16x16x32_bf16 v[124:127], v[176:179], v[210:213], v[124:127]
	v_mfma_f32_16x16x32_bf16 v[120:123], v[184:187], v[210:213], v[120:123]
	v_mfma_f32_16x16x32_bf16 v[108:111], v[176:179], v[218:221], v[108:111]
	v_mfma_f32_16x16x32_bf16 v[104:107], v[184:187], v[218:221], v[104:107]
	v_mfma_f32_16x16x32_bf16 v[92:95], v[176:179], v[226:229], v[92:95]
	v_mfma_f32_16x16x32_bf16 v[88:91], v[184:187], v[226:229], v[88:91]
	v_mfma_f32_16x16x32_bf16 v[76:79], v[176:179], v[234:237], v[76:79]
	v_mfma_f32_16x16x32_bf16 v[72:75], v[184:187], v[234:237], v[72:75]
	s_setprio 0
	s_setprio 1
	v_mfma_f32_16x16x32_bf16 v[116:119], v[188:191], v[206:209], v[116:119]
	v_mfma_f32_16x16x32_bf16 v[112:115], v[196:199], v[206:209], v[112:115]
	v_mfma_f32_16x16x32_bf16 v[100:103], v[188:191], v[214:217], v[100:103]
	v_mfma_f32_16x16x32_bf16 v[96:99], v[196:199], v[214:217], v[96:99]
	v_mfma_f32_16x16x32_bf16 v[84:87], v[188:191], v[222:225], v[84:87]
	v_mfma_f32_16x16x32_bf16 v[80:83], v[196:199], v[222:225], v[80:83]
	v_mfma_f32_16x16x32_bf16 v[68:71], v[188:191], v[230:233], v[68:71]
	v_mfma_f32_16x16x32_bf16 v[64:67], v[196:199], v[230:233], v[64:67]
	v_mfma_f32_16x16x32_bf16 v[116:119], v[192:195], v[210:213], v[116:119]
	v_mfma_f32_16x16x32_bf16 v[112:115], v[202:205], v[210:213], v[112:115]
	v_mfma_f32_16x16x32_bf16 v[100:103], v[192:195], v[218:221], v[100:103]
	v_mfma_f32_16x16x32_bf16 v[96:99], v[202:205], v[218:221], v[96:99]
	v_mfma_f32_16x16x32_bf16 v[84:87], v[192:195], v[226:229], v[84:87]
	v_mfma_f32_16x16x32_bf16 v[80:83], v[202:205], v[226:229], v[80:83]
	v_mfma_f32_16x16x32_bf16 v[68:71], v[192:195], v[234:237], v[68:71]
	v_mfma_f32_16x16x32_bf16 v[64:67], v[202:205], v[234:237], v[64:67]
	s_setprio 0
	s_barrier
; #define PG8_STAGE(bufoff, gbase, voff) do { _Pragma("unroll") for (int _i = 0; _i < 2; ++_i) \
;         __builtin_amdgcn_global_load_lds((const unsigned*)((const char*)(gbase) + (voff)[_i]), (PG8_LAS unsigned*)(lds + (bufoff) + ldsw + _i * 8192), 16, 0, 0); } while (0)
; #define PG8_LDA(dst, b, h) do { _Pragma("unroll") for (int m = 0; m < 4; ++m) _Pragma("unroll") for (int k = 0; k < 2; ++k) dst[m][k] = *(const PG8_LAS bf16x8*)(lds + PG8_SA(b, h) + aoff + m * 2048 + k * 1024); } while (0)
; #define PG8_MMA(ai, bj, At, Bt) do { __builtin_amdgcn_s_setprio(1); _Pragma("unroll") for (int m = 0; m < 4; ++m) _Pragma("unroll") for (int n = 0; n < 2; ++n) _Pragma("unroll") for (int k = 0; k < 2; ++k) \
;         acc[ai][bj][m][n] = __builtin_amdgcn_mfma_f32_16x16x32_bf16(Bt[n][k], At[m][k], acc[ai][bj][m][n], 0, 0, 0); __builtin_amdgcn_s_setprio(0); } while (0)
; #define PG8_WAIT_V(n) asm volatile("s_waitcnt vmcnt(" #n ")" ::: "memory")
; #define PG8_WAIT_L(n) asm volatile("s_waitcnt lgkmcnt(" #n ")" ::: "memory")
; #define PG8_BAR __builtin_amdgcn_s_barrier()
; #define PG8_SCHED __builtin_amdgcn_sched_barrier(0)
; template <class Epi, class Sched, bool ALIGN_EPI = false, bool SP2 = false>
; __device__ __forceinline__ void gemm_phase(PG8_LAS unsigned char* lds, const Gemm g, const Sched& S, const Epi& E, int tid_in) {
;     ...
;             PG8_LDA(At, 1, 1); PG8_STAGE(PG8_SB(1, 0), b3, voffB); PG8_STAGE(PG8_SB(1, 1), b3 + hstep, voffB); PG8_STAGE(PG8_SA(1, 0), a3, voffA);
;             PG8_WAIT_V(8); PG8_WAIT_L(0); PG8_BAR; PG8_MMA(1, 0, At, B0); PG8_MMA(1, 1, At, B1); PG8_BAR; PG8_SCHED;
;     ...
;         if constexpr (ALIGN_EPI) { if (wr == 0) PG8_BAR; }
	s_add_i32 s36, s54, s5
	v_lshl_add_u64 v[150:151], v[150:151], 0, s[12:13]
	s_mov_b32 m0, s36
	ds_read_b128 v[206:209], v173 offset:49152
	ds_read_b128 v[210:213], v173 offset:50176
	ds_read_b128 v[214:217], v173 offset:51200
	ds_read_b128 v[218:221], v173 offset:52224
	ds_read_b128 v[222:225], v173 offset:53248
	ds_read_b128 v[226:229], v173 offset:54272
	ds_read_b128 v[230:233], v173 offset:55296
	ds_read_b128 v[234:237], v173 offset:56320
	global_load_lds_dwordx4 v[150:151], off
	s_add_i32 m0, s36, 0x2000
	s_add_u32 s34, s34, 0x40080
	v_lshl_add_u64 v[150:151], v[154:155], 0, s[12:13]
	s_addc_u32 s35, s35, 0
	s_add_i32 s36, s55, s5
	global_load_lds_dwordx4 v[150:151], off
	v_lshl_add_u64 v[150:151], s[34:35], 0, v[132:133]
	s_mov_b32 m0, s36
	s_nop 0
	global_load_lds_dwordx4 v[150:151], off
	v_lshl_add_u64 v[150:151], s[34:35], 0, v[128:129]
	s_add_i32 m0, s36, 0x2000
	s_nop 0
	global_load_lds_dwordx4 v[150:151], off
	v_lshl_add_u64 v[150:151], v[158:159], 0, s[12:13]
	s_mov_b32 m0, s41
	s_nop 0
	global_load_lds_dwordx4 v[150:151], off
	v_lshl_add_u64 v[150:151], v[162:163], 0, s[12:13]
	s_mov_b32 m0, s42
	s_nop 0
	global_load_lds_dwordx4 v[150:151], off
	s_waitcnt vmcnt(8)
	s_waitcnt lgkmcnt(0)
	s_barrier
	s_setprio 1
	s_waitcnt lgkmcnt(0)
	v_mfma_f32_16x16x32_bf16 v[60:63], v[146:149], v[206:209], v[60:63]
	v_mfma_f32_16x16x32_bf16 v[56:59], v[180:183], v[206:209], v[56:59]
	v_mfma_f32_16x16x32_bf16 v[44:47], v[146:149], v[214:217], v[44:47]
	v_mfma_f32_16x16x32_bf16 v[40:43], v[180:183], v[214:217], v[40:43]
	v_mfma_f32_16x16x32_bf16 v[28:31], v[146:149], v[222:225], v[28:31]
	v_mfma_f32_16x16x32_bf16 v[24:27], v[180:183], v[222:225], v[24:27]
	v_mfma_f32_16x16x32_bf16 v[12:15], v[146:149], v[230:233], v[12:15]
	v_mfma_f32_16x16x32_bf16 v[8:11], v[180:183], v[230:233], v[8:11]
	v_mfma_f32_16x16x32_bf16 v[60:63], v[176:179], v[210:213], v[60:63]
	v_mfma_f32_16x16x32_bf16 v[56:59], v[184:187], v[210:213], v[56:59]
	v_mfma_f32_16x16x32_bf16 v[44:47], v[176:179], v[218:221], v[44:47]
	v_mfma_f32_16x16x32_bf16 v[40:43], v[184:187], v[218:221], v[40:43]
	v_mfma_f32_16x16x32_bf16 v[28:31], v[176:179], v[226:229], v[28:31]
	v_mfma_f32_16x16x32_bf16 v[24:27], v[184:187], v[226:229], v[24:27]
	v_mfma_f32_16x16x32_bf16 v[12:15], v[176:179], v[234:237], v[12:15]
	v_mfma_f32_16x16x32_bf16 v[8:11], v[184:187], v[234:237], v[8:11]
	s_setprio 0
	s_setprio 1
	v_mfma_f32_16x16x32_bf16 v[52:55], v[188:191], v[206:209], v[52:55]
	v_mfma_f32_16x16x32_bf16 v[48:51], v[196:199], v[206:209], v[48:51]
	v_mfma_f32_16x16x32_bf16 v[36:39], v[188:191], v[214:217], v[36:39]
	v_mfma_f32_16x16x32_bf16 v[32:35], v[196:199], v[214:217], v[32:35]
	v_mfma_f32_16x16x32_bf16 v[20:23], v[188:191], v[222:225], v[20:23]
	v_mfma_f32_16x16x32_bf16 v[16:19], v[196:199], v[222:225], v[16:19]
	v_mfma_f32_16x16x32_bf16 v[4:7], v[188:191], v[230:233], v[4:7]
	v_mfma_f32_16x16x32_bf16 v[0:3], v[196:199], v[230:233], v[0:3]
	v_mfma_f32_16x16x32_bf16 v[52:55], v[192:195], v[210:213], v[52:55]
	v_mfma_f32_16x16x32_bf16 v[48:51], v[202:205], v[210:213], v[48:51]
	v_mfma_f32_16x16x32_bf16 v[36:39], v[192:195], v[218:221], v[36:39]
	v_mfma_f32_16x16x32_bf16 v[32:35], v[202:205], v[218:221], v[32:35]
	v_mfma_f32_16x16x32_bf16 v[20:23], v[192:195], v[226:229], v[20:23]
	v_mfma_f32_16x16x32_bf16 v[16:19], v[202:205], v[226:229], v[16:19]
	v_mfma_f32_16x16x32_bf16 v[4:7], v[192:195], v[234:237], v[4:7]
	v_mfma_f32_16x16x32_bf16 v[0:3], v[202:205], v[234:237], v[0:3]
	s_setprio 0
	s_barrier
	s_add_i32 s53, s53, 2
	s_add_u32 s51, s51, 0x100
	s_addc_u32 s52, s52, 0
	s_add_u32 s26, s26, 0x100
	s_addc_u32 s27, s27, 0
	s_cmp_gt_u32 s53, 13
	s_cbranch_scc0 .LBB0_2040
.Lpost15:
	s_and_b64 vcc, exec, s[14:15]
	s_cbranch_vccz .LBB0_2043
	s_barrier

; #define PG8_STAGE(bufoff, gbase, voff) do { _Pragma("unroll") for (int _i = 0; _i < 2; ++_i) \
;         __builtin_amdgcn_global_load_lds((const unsigned*)((const char*)(gbase) + (voff)[_i]), (PG8_LAS unsigned*)(lds + (bufoff) + ldsw + _i * 8192), 16, 0, 0); } while (0)
; #define PG8_LDA(dst, b, h) do { _Pragma("unroll") for (int m = 0; m < 4; ++m) _Pragma("unroll") for (int k = 0; k < 2; ++k) dst[m][k] = *(const PG8_LAS bf16x8*)(lds + PG8_SA(b, h) + aoff + m * 2048 + k * 1024); } while (0)
; #define PG8_LDB(dst, b, h) do { _Pragma("unroll") for (int n = 0; n < 2; ++n) _Pragma("unroll") for (int k = 0; k < 2; ++k) dst[n][k] = *(const PG8_LAS bf16x8*)(lds + PG8_SB(b, h) + boff + n * 2048 + k * 1024); } while (0)
; #define PG8_MMA(ai, bj, At, Bt) do { __builtin_amdgcn_s_setprio(1); _Pragma("unroll") for (int m = 0; m < 4; ++m) _Pragma("unroll") for (int n = 0; n < 2; ++n) _Pragma("unroll") for (int k = 0; k < 2; ++k) \
;         acc[ai][bj][m][n] = __builtin_amdgcn_mfma_f32_16x16x32_bf16(Bt[n][k], At[m][k], acc[ai][bj][m][n], 0, 0, 0); __builtin_amdgcn_s_setprio(0); } while (0)
; #define PG8_WAIT_V(n) asm volatile("s_waitcnt vmcnt(" #n ")" ::: "memory")
; #define PG8_WAIT_L(n) asm volatile("s_waitcnt lgkmcnt(" #n ")" ::: "memory")
; #define PG8_BAR __builtin_amdgcn_s_barrier()
; #define PG8_SCHED __builtin_amdgcn_sched_barrier(0)
; template <class Epi, class Sched, bool ALIGN_EPI = false, bool SP2 = false>
; __device__ __forceinline__ void gemm_phase(PG8_LAS unsigned char* lds, const Gemm g, const Sched& S, const Epi& E, int tid_in) {
;     ...
;             PG8_LDB(B0, 0, 0); PG8_LDB(B1, 0, 1); PG8_SCHED; PG8_LDA(At, 0, 0); PG8_STAGE(PG8_SA(1, 1), a1 + hstep, voffA);
;             PG8_WAIT_V(8); PG8_WAIT_L(0); PG8_BAR; PG8_MMA(0, 0, At, B0); PG8_MMA(0, 1, At, B1); PG8_BAR; PG8_SCHED;
;             PG8_LDA(At, 0, 1); PG8_STAGE(PG8_SB(0, 0), b2, voffB); PG8_STAGE(PG8_SB(0, 1), b2 + hstep, voffB); PG8_STAGE(PG8_SA(0, 0), a2, voffA);
;             PG8_WAIT_V(8); PG8_WAIT_L(0); PG8_BAR; PG8_MMA(1, 0, At, B0); PG8_MMA(1, 1, At, B1); PG8_BAR; PG8_SCHED;
.Lpk15:
	s_or_b64 s[98:99], s[6:7], 1
	v_lshl_add_u64 v[150:151], s[26:27], 0, v[140:141]
	s_add_i32 m0, s25, 0xc000
	ds_read_b128 v[206:209], v173
	ds_read_b128 v[210:213], v173 offset:1024
	ds_read_b128 v[214:217], v173 offset:2048
	ds_read_b128 v[218:221], v173 offset:3072
	ds_read_b128 v[222:225], v173 offset:4096
	ds_read_b128 v[226:229], v173 offset:5120
	ds_read_b128 v[230:233], v173 offset:6144
	ds_read_b128 v[234:237], v173 offset:7168
	global_load_lds_dwordx4 v[150:151], off
	v_lshl_add_u64 v[150:151], s[26:27], 0, v[138:139]
	s_add_i32 m0, s25, 0xe000
	s_nop 0
	global_load_lds_dwordx4 v[150:151], off
	s_waitcnt vmcnt(8)
	s_waitcnt lgkmcnt(0)
	s_barrier
	s_setprio 1
	s_waitcnt lgkmcnt(0)
	v_mfma_f32_16x16x32_bf16 v[124:127], v[146:149], v[206:209], v[124:127]
	v_mfma_f32_16x16x32_bf16 v[120:123], v[180:183], v[206:209], v[120:123]
	v_mfma_f32_16x16x32_bf16 v[108:111], v[146:149], v[214:217], v[108:111]
	v_mfma_f32_16x16x32_bf16 v[104:107], v[180:183], v[214:217], v[104:107]
	v_mfma_f32_16x16x32_bf16 v[92:95], v[146:149], v[222:225], v[92:95]
	v_mfma_f32_16x16x32_bf16 v[88:91], v[180:183], v[222:225], v[88:91]
	v_mfma_f32_16x16x32_bf16 v[76:79], v[146:149], v[230:233], v[76:79]
	v_mfma_f32_16x16x32_bf16 v[72:75], v[180:183], v[230:233], v[72:75]
	v_mfma_f32_16x16x32_bf16 v[124:127], v[176:179], v[210:213], v[124:127]
	v_mfma_f32_16x16x32_bf16 v[120:123], v[184:187], v[210:213], v[120:123]
	v_mfma_f32_16x16x32_bf16 v[108:111], v[176:179], v[218:221], v[108:111]
	v_mfma_f32_16x16x32_bf16 v[104:107], v[184:187], v[218:221], v[104:107]
	v_mfma_f32_16x16x32_bf16 v[92:95], v[176:179], v[226:229], v[92:95]
	v_mfma_f32_16x16x32_bf16 v[88:91], v[184:187], v[226:229], v[88:91]
	v_mfma_f32_16x16x32_bf16 v[76:79], v[176:179], v[234:237], v[76:79]
	v_mfma_f32_16x16x32_bf16 v[72:75], v[184:187], v[234:237], v[72:75]
	s_setprio 0
	s_setprio 1
	v_mfma_f32_16x16x32_bf16 v[116:119], v[188:191], v[206:209], v[116:119]
	v_mfma_f32_16x16x32_bf16 v[112:115], v[196:199], v[206:209], v[112:115]
	v_mfma_f32_16x16x32_bf16 v[100:103], v[188:191], v[214:217], v[100:103]
	v_mfma_f32_16x16x32_bf16 v[96:99], v[196:199], v[214:217], v[96:99]
	v_mfma_f32_16x16x32_bf16 v[84:87], v[188:191], v[222:225], v[84:87]
	v_mfma_f32_16x16x32_bf16 v[80:83], v[196:199], v[222:225], v[80:83]
	v_mfma_f32_16x16x32_bf16 v[68:71], v[188:191], v[230:233], v[68:71]
	v_mfma_f32_16x16x32_bf16 v[64:67], v[196:199], v[230:233], v[64:67]
	v_mfma_f32_16x16x32_bf16 v[116:119], v[192:195], v[210:213], v[116:119]
	v_mfma_f32_16x16x32_bf16 v[112:115], v[202:205], v[210:213], v[112:115]
	v_mfma_f32_16x16x32_bf16 v[100:103], v[192:195], v[218:221], v[100:103]
	v_mfma_f32_16x16x32_bf16 v[96:99], v[202:205], v[218:221], v[96:99]
	v_mfma_f32_16x16x32_bf16 v[84:87], v[192:195], v[226:229], v[84:87]
	v_mfma_f32_16x16x32_bf16 v[80:83], v[202:205], v[226:229], v[80:83]
	v_mfma_f32_16x16x32_bf16 v[68:71], v[192:195], v[234:237], v[68:71]
	v_mfma_f32_16x16x32_bf16 v[64:67], v[202:205], v[234:237], v[64:67]
	s_setprio 0
	s_barrier
	s_add_i32 s54, s45, s5
	v_lshl_add_u64 v[150:151], s[34:35], 0, v[132:133]
	s_mov_b32 m0, s54
	ds_read_b128 v[206:209], v173 offset:16384
	ds_read_b128 v[210:213], v173 offset:17408
	ds_read_b128 v[214:217], v173 offset:18432
	ds_read_b128 v[218:221], v173 offset:19456
	ds_read_b128 v[222:225], v173 offset:20480
	ds_read_b128 v[226:229], v173 offset:21504
	ds_read_b128 v[230:233], v173 offset:22528
	ds_read_b128 v[234:237], v173 offset:23552
	s_mov_b64 exec, s[98:99]
	global_load_lds_dwordx4 v[150:151], off
	s_mov_b64 exec, -1
	s_add_i32 m0, s54, 0x2000
	s_add_u32 s54, s34, 0x40000
	v_lshl_add_u64 v[154:155], s[34:35], 0, v[128:129]
	s_addc_u32 s55, s35, 0
	s_add_i32 s56, s46, s5
	s_mov_b64 exec, s[98:99]
	global_load_lds_dwordx4 v[154:155], off
	s_mov_b64 exec, -1
	v_lshl_add_u64 v[158:159], s[54:55], 0, v[132:133]
	s_mov_b32 m0, s56
	v_lshl_add_u64 v[162:163], s[36:37], 0, v[130:131]
	s_mov_b64 exec, s[98:99]
	global_load_lds_dwordx4 v[158:159], off
	s_mov_b64 exec, -1
	v_lshl_add_u64 v[158:159], s[54:55], 0, v[128:129]
	s_add_i32 m0, s56, 0x2000
	s_nop 0
	s_mov_b64 exec, s[98:99]
	global_load_lds_dwordx4 v[158:159], off
	s_mov_b64 exec, -1
	v_lshl_add_u64 v[158:159], s[36:37], 0, v[134:135]
	s_mov_b32 m0, s25
	s_nop 0
	s_mov_b64 exec, s[98:99]
	global_load_lds_dwordx4 v[158:159], off
	s_mov_b64 exec, -1
	s_mov_b32 m0, s33
	s_nop 0
	s_mov_b64 exec, s[98:99]
	global_load_lds_dwordx4 v[162:163], off
	s_mov_b64 exec, -1
	s_waitcnt vmcnt(8)
	s_waitcnt lgkmcnt(0)
	s_barrier
; #define PG8_STAGE(bufoff, gbase, voff) do { _Pragma("unroll") for (int _i = 0; _i < 2; ++_i) \
;         __builtin_amdgcn_global_load_lds((const unsigned*)((const char*)(gbase) + (voff)[_i]), (PG8_LAS unsigned*)(lds + (bufoff) + ldsw + _i * 8192), 16, 0, 0); } while (0)
; #define PG8_LDA(dst, b, h) do { _Pragma("unroll") for (int m = 0; m < 4; ++m) _Pragma("unroll") for (int k = 0; k < 2; ++k) dst[m][k] = *(const PG8_LAS bf16x8*)(lds + PG8_SA(b, h) + aoff + m * 2048 + k * 1024); } while (0)
; #define PG8_LDB(dst, b, h) do { _Pragma("unroll") for (int n = 0; n < 2; ++n) _Pragma("unroll") for (int k = 0; k < 2; ++k) dst[n][k] = *(const PG8_LAS bf16x8*)(lds + PG8_SB(b, h) + boff + n * 2048 + k * 1024); } while (0)
; #define PG8_MMA(ai, bj, At, Bt) do { __builtin_amdgcn_s_setprio(1); _Pragma("unroll") for (int m = 0; m < 4; ++m) _Pragma("unroll") for (int n = 0; n < 2; ++n) _Pragma("unroll") for (int k = 0; k < 2; ++k) \
;         acc[ai][bj][m][n] = __builtin_amdgcn_mfma_f32_16x16x32_bf16(Bt[n][k], At[m][k], acc[ai][bj][m][n], 0, 0, 0); __builtin_amdgcn_s_setprio(0); } while (0)
; #define PG8_WAIT_V(n) asm volatile("s_waitcnt vmcnt(" #n ")" ::: "memory")
; #define PG8_WAIT_L(n) asm volatile("s_waitcnt lgkmcnt(" #n ")" ::: "memory")
; #define PG8_BAR __builtin_amdgcn_s_barrier()
; #define PG8_SCHED __builtin_amdgcn_sched_barrier(0)
; template <class Epi, class Sched, bool ALIGN_EPI = false, bool SP2 = false>
; __device__ __forceinline__ void gemm_phase(PG8_LAS unsigned char* lds, const Gemm g, const Sched& S, const Epi& E, int tid_in) {
;     ...
;             PG8_WAIT_V(8); PG8_WAIT_L(0); PG8_BAR; PG8_MMA(1, 0, At, B0); PG8_MMA(1, 1, At, B1); PG8_BAR; PG8_SCHED;
;             PG8_LDB(B0, 1, 0); PG8_LDB(B1, 1, 1); PG8_SCHED; PG8_LDA(At, 1, 0); PG8_STAGE(PG8_SA(0, 1), a2 + hstep, voffA);
;             PG8_WAIT_V(8); PG8_WAIT_L(0); PG8_BAR; PG8_MMA(0, 0, At, B0); PG8_MMA(0, 1, At, B1); PG8_BAR; PG8_SCHED;
	s_setprio 1
	s_waitcnt lgkmcnt(0)
	v_mfma_f32_16x16x32_bf16 v[60:63], v[146:149], v[206:209], v[60:63]
	v_mfma_f32_16x16x32_bf16 v[56:59], v[180:183], v[206:209], v[56:59]
	v_mfma_f32_16x16x32_bf16 v[44:47], v[146:149], v[214:217], v[44:47]
	v_mfma_f32_16x16x32_bf16 v[40:43], v[180:183], v[214:217], v[40:43]
	v_mfma_f32_16x16x32_bf16 v[28:31], v[146:149], v[222:225], v[28:31]
	v_mfma_f32_16x16x32_bf16 v[24:27], v[180:183], v[222:225], v[24:27]
	v_mfma_f32_16x16x32_bf16 v[12:15], v[146:149], v[230:233], v[12:15]
	v_mfma_f32_16x16x32_bf16 v[8:11], v[180:183], v[230:233], v[8:11]
	v_mfma_f32_16x16x32_bf16 v[60:63], v[176:179], v[210:213], v[60:63]
	v_mfma_f32_16x16x32_bf16 v[56:59], v[184:187], v[210:213], v[56:59]
	v_mfma_f32_16x16x32_bf16 v[44:47], v[176:179], v[218:221], v[44:47]
	v_mfma_f32_16x16x32_bf16 v[40:43], v[184:187], v[218:221], v[40:43]
	v_mfma_f32_16x16x32_bf16 v[28:31], v[176:179], v[226:229], v[28:31]
	v_mfma_f32_16x16x32_bf16 v[24:27], v[184:187], v[226:229], v[24:27]
	v_mfma_f32_16x16x32_bf16 v[12:15], v[176:179], v[234:237], v[12:15]
	v_mfma_f32_16x16x32_bf16 v[8:11], v[184:187], v[234:237], v[8:11]
	s_setprio 0
	s_setprio 1
	v_mfma_f32_16x16x32_bf16 v[52:55], v[188:191], v[206:209], v[52:55]
	v_mfma_f32_16x16x32_bf16 v[48:51], v[196:199], v[206:209], v[48:51]
	v_mfma_f32_16x16x32_bf16 v[36:39], v[188:191], v[214:217], v[36:39]
	v_mfma_f32_16x16x32_bf16 v[32:35], v[196:199], v[214:217], v[32:35]
	v_mfma_f32_16x16x32_bf16 v[20:23], v[188:191], v[222:225], v[20:23]
	v_mfma_f32_16x16x32_bf16 v[16:19], v[196:199], v[222:225], v[16:19]
	v_mfma_f32_16x16x32_bf16 v[4:7], v[188:191], v[230:233], v[4:7]
	v_mfma_f32_16x16x32_bf16 v[0:3], v[196:199], v[230:233], v[0:3]
	v_mfma_f32_16x16x32_bf16 v[52:55], v[192:195], v[210:213], v[52:55]
	v_mfma_f32_16x16x32_bf16 v[48:51], v[202:205], v[210:213], v[48:51]
	v_mfma_f32_16x16x32_bf16 v[36:39], v[192:195], v[218:221], v[36:39]
	v_mfma_f32_16x16x32_bf16 v[32:35], v[202:205], v[218:221], v[32:35]
	v_mfma_f32_16x16x32_bf16 v[20:23], v[192:195], v[226:229], v[20:23]
	v_mfma_f32_16x16x32_bf16 v[16:19], v[202:205], v[226:229], v[16:19]
	v_mfma_f32_16x16x32_bf16 v[4:7], v[192:195], v[234:237], v[4:7]
	v_mfma_f32_16x16x32_bf16 v[0:3], v[202:205], v[234:237], v[0:3]
	s_setprio 0
	s_barrier
	s_add_i32 s54, 0, 0x18000
	v_add_u32_e32 v152, s54, v157
	s_add_i32 s55, 0, 0x1c000
	ds_read_b128 v[146:149], v152
	ds_read_b128 v[176:179], v152 offset:1024
	ds_read_b128 v[180:183], v152 offset:2048
	ds_read_b128 v[184:187], v152 offset:3072
	v_add_u32_e32 v152, s55, v157
	ds_read_b128 v[188:191], v152
	ds_read_b128 v[192:195], v152 offset:1024
	ds_read_b128 v[196:199], v152 offset:2048
	ds_read_b128 v[202:205], v152 offset:3072
	s_add_u32 s36, s36, 0x40000
	s_addc_u32 s37, s37, 0
	s_mov_b32 m0, s38
	v_lshl_add_u64 v[166:167], s[36:37], 0, v[134:135]
	ds_read_b128 v[206:209], v173 offset:32768
	ds_read_b128 v[210:213], v173 offset:33792
	ds_read_b128 v[214:217], v173 offset:34816
	ds_read_b128 v[218:221], v173 offset:35840
	ds_read_b128 v[222:225], v173 offset:36864
	ds_read_b128 v[226:229], v173 offset:37888
	ds_read_b128 v[230:233], v173 offset:38912
	ds_read_b128 v[234:237], v173 offset:39936
	s_mov_b64 exec, s[98:99]
	global_load_lds_dwordx4 v[166:167], off
	s_mov_b64 exec, -1
	v_lshl_add_u64 v[166:167], s[36:37], 0, v[130:131]
	s_mov_b32 m0, s39
	s_nop 0
	s_mov_b64 exec, s[98:99]
	global_load_lds_dwordx4 v[166:167], off
	s_mov_b64 exec, -1
	s_waitcnt vmcnt(8)
	s_waitcnt lgkmcnt(0)
	s_barrier
	s_setprio 1
	s_waitcnt lgkmcnt(0)
	v_mfma_f32_16x16x32_bf16 v[124:127], v[146:149], v[206:209], v[124:127]
	v_mfma_f32_16x16x32_bf16 v[120:123], v[180:183], v[206:209], v[120:123]
	v_mfma_f32_16x16x32_bf16 v[108:111], v[146:149], v[214:217], v[108:111]
	v_mfma_f32_16x16x32_bf16 v[104:107], v[180:183], v[214:217], v[104:107]
	v_mfma_f32_16x16x32_bf16 v[92:95], v[146:149], v[222:225], v[92:95]
	v_mfma_f32_16x16x32_bf16 v[88:91], v[180:183], v[222:225], v[88:91]
	v_mfma_f32_16x16x32_bf16 v[76:79], v[146:149], v[230:233], v[76:79]
	v_mfma_f32_16x16x32_bf16 v[72:75], v[180:183], v[230:233], v[72:75]
	v_mfma_f32_16x16x32_bf16 v[124:127], v[176:179], v[210:213], v[124:127]
	v_mfma_f32_16x16x32_bf16 v[120:123], v[184:187], v[210:213], v[120:123]
	v_mfma_f32_16x16x32_bf16 v[108:111], v[176:179], v[218:221], v[108:111]
	v_mfma_f32_16x16x32_bf16 v[104:107], v[184:187], v[218:221], v[104:107]
	v_mfma_f32_16x16x32_bf16 v[92:95], v[176:179], v[226:229], v[92:95]
	v_mfma_f32_16x16x32_bf16 v[88:91], v[184:187], v[226:229], v[88:91]
	v_mfma_f32_16x16x32_bf16 v[76:79], v[176:179], v[234:237], v[76:79]
	v_mfma_f32_16x16x32_bf16 v[72:75], v[184:187], v[234:237], v[72:75]
	s_setprio 0
	s_setprio 1
	v_mfma_f32_16x16x32_bf16 v[116:119], v[188:191], v[206:209], v[116:119]
	v_mfma_f32_16x16x32_bf16 v[112:115], v[196:199], v[206:209], v[112:115]
	v_mfma_f32_16x16x32_bf16 v[100:103], v[188:191], v[214:217], v[100:103]
	v_mfma_f32_16x16x32_bf16 v[96:99], v[196:199], v[214:217], v[96:99]
	v_mfma_f32_16x16x32_bf16 v[84:87], v[188:191], v[222:225], v[84:87]
	v_mfma_f32_16x16x32_bf16 v[80:83], v[196:199], v[222:225], v[80:83]
	v_mfma_f32_16x16x32_bf16 v[68:71], v[188:191], v[230:233], v[68:71]
	v_mfma_f32_16x16x32_bf16 v[64:67], v[196:199], v[230:233], v[64:67]
	v_mfma_f32_16x16x32_bf16 v[116:119], v[192:195], v[210:213], v[116:119]
	v_mfma_f32_16x16x32_bf16 v[112:115], v[202:205], v[210:213], v[112:115]
	v_mfma_f32_16x16x32_bf16 v[100:103], v[192:195], v[218:221], v[100:103]
	v_mfma_f32_16x16x32_bf16 v[96:99], v[202:205], v[218:221], v[96:99]
	v_mfma_f32_16x16x32_bf16 v[84:87], v[192:195], v[226:229], v[84:87]
	v_mfma_f32_16x16x32_bf16 v[80:83], v[202:205], v[226:229], v[80:83]
	v_mfma_f32_16x16x32_bf16 v[68:71], v[192:195], v[234:237], v[68:71]
	v_mfma_f32_16x16x32_bf16 v[64:67], v[202:205], v[234:237], v[64:67]
	s_setprio 0
	s_barrier
; #define PG8_STAGE(bufoff, gbase, voff) do { _Pragma("unroll") for (int _i = 0; _i < 2; ++_i) \
;         __builtin_amdgcn_global_load_lds((const unsigned*)((const char*)(gbase) + (voff)[_i]), (PG8_LAS unsigned*)(lds + (bufoff) + ldsw + _i * 8192), 16, 0, 0); } while (0)
; #define PG8_LDA(dst, b, h) do { _Pragma("unroll") for (int m = 0; m < 4; ++m) _Pragma("unroll") for (int k = 0; k < 2; ++k) dst[m][k] = *(const PG8_LAS bf16x8*)(lds + PG8_SA(b, h) + aoff + m * 2048 + k * 1024); } while (0)
; #define PG8_MMA(ai, bj, At, Bt) do { __builtin_amdgcn_s_setprio(1); _Pragma("unroll") for (int m = 0; m < 4; ++m) _Pragma("unroll") for (int n = 0; n < 2; ++n) _Pragma("unroll") for (int k = 0; k < 2; ++k) \
;         acc[ai][bj][m][n] = __builtin_amdgcn_mfma_f32_16x16x32_bf16(Bt[n][k], At[m][k], acc[ai][bj][m][n], 0, 0, 0); __builtin_amdgcn_s_setprio(0); } while (0)
; #define PG8_WAIT_V(n) asm volatile("s_waitcnt vmcnt(" #n ")" ::: "memory")
; #define PG8_WAIT_L(n) asm volatile("s_waitcnt lgkmcnt(" #n ")" ::: "memory")
; #define PG8_BAR __builtin_amdgcn_s_barrier()
; #define PG8_SCHED __builtin_amdgcn_sched_barrier(0)
; template <class Epi, class Sched, bool ALIGN_EPI = false, bool SP2 = false>
; __device__ __forceinline__ void gemm_phase(PG8_LAS unsigned char* lds, const Gemm g, const Sched& S, const Epi& E, int tid_in) {
;     ...
;             PG8_LDA(At, 1, 1); PG8_STAGE(PG8_SB(1, 0), b3, voffB); PG8_STAGE(PG8_SB(1, 1), b3 + hstep, voffB); PG8_STAGE(PG8_SA(1, 0), a3, voffA);
;             PG8_WAIT_V(8); PG8_WAIT_L(0); PG8_BAR; PG8_MMA(1, 0, At, B0); PG8_MMA(1, 1, At, B1); PG8_BAR; PG8_SCHED;
	s_add_i32 s36, s54, s5
	v_lshl_add_u64 v[150:151], v[150:151], 0, s[12:13]
	s_mov_b32 m0, s36
	ds_read_b128 v[206:209], v173 offset:49152
	ds_read_b128 v[210:213], v173 offset:50176
	ds_read_b128 v[214:217], v173 offset:51200
	ds_read_b128 v[218:221], v173 offset:52224
	ds_read_b128 v[222:225], v173 offset:53248
	ds_read_b128 v[226:229], v173 offset:54272
	ds_read_b128 v[230:233], v173 offset:55296
	ds_read_b128 v[234:237], v173 offset:56320
	s_mov_b64 exec, s[98:99]
	global_load_lds_dwordx4 v[150:151], off
	s_mov_b64 exec, -1
	s_add_i32 m0, s36, 0x2000
	s_add_u32 s34, s34, 0x40080
	v_lshl_add_u64 v[150:151], v[154:155], 0, s[12:13]
	s_addc_u32 s35, s35, 0
	s_add_i32 s36, s55, s5
	s_mov_b64 exec, s[98:99]
	global_load_lds_dwordx4 v[150:151], off
	s_mov_b64 exec, -1
	v_lshl_add_u64 v[150:151], s[34:35], 0, v[132:133]
	s_mov_b32 m0, s36
	s_nop 0
	s_mov_b64 exec, s[98:99]
	global_load_lds_dwordx4 v[150:151], off
	s_mov_b64 exec, -1
	v_lshl_add_u64 v[150:151], s[34:35], 0, v[128:129]
	s_add_i32 m0, s36, 0x2000
	s_nop 0
	s_mov_b64 exec, s[98:99]
	global_load_lds_dwordx4 v[150:151], off
	s_mov_b64 exec, -1
	v_lshl_add_u64 v[150:151], v[158:159], 0, s[12:13]
	s_mov_b32 m0, s41
	s_nop 0
	s_mov_b64 exec, s[98:99]
	global_load_lds_dwordx4 v[150:151], off
	s_mov_b64 exec, -1
	v_lshl_add_u64 v[150:151], v[162:163], 0, s[12:13]
	s_mov_b32 m0, s42
	s_nop 0
	s_mov_b64 exec, s[98:99]
	global_load_lds_dwordx4 v[150:151], off
	s_mov_b64 exec, -1
	s_waitcnt vmcnt(8)
	s_waitcnt lgkmcnt(0)
	s_barrier
	s_setprio 1
	s_waitcnt lgkmcnt(0)
	v_mfma_f32_16x16x32_bf16 v[60:63], v[146:149], v[206:209], v[60:63]
	v_mfma_f32_16x16x32_bf16 v[56:59], v[180:183], v[206:209], v[56:59]
	v_mfma_f32_16x16x32_bf16 v[44:47], v[146:149], v[214:217], v[44:47]
	v_mfma_f32_16x16x32_bf16 v[40:43], v[180:183], v[214:217], v[40:43]
	v_mfma_f32_16x16x32_bf16 v[28:31], v[146:149], v[222:225], v[28:31]
	v_mfma_f32_16x16x32_bf16 v[24:27], v[180:183], v[222:225], v[24:27]
	v_mfma_f32_16x16x32_bf16 v[12:15], v[146:149], v[230:233], v[12:15]
	v_mfma_f32_16x16x32_bf16 v[8:11], v[180:183], v[230:233], v[8:11]
	v_mfma_f32_16x16x32_bf16 v[60:63], v[176:179], v[210:213], v[60:63]
	v_mfma_f32_16x16x32_bf16 v[56:59], v[184:187], v[210:213], v[56:59]
	v_mfma_f32_16x16x32_bf16 v[44:47], v[176:179], v[218:221], v[44:47]
	v_mfma_f32_16x16x32_bf16 v[40:43], v[184:187], v[218:221], v[40:43]
	v_mfma_f32_16x16x32_bf16 v[28:31], v[176:179], v[226:229], v[28:31]
	v_mfma_f32_16x16x32_bf16 v[24:27], v[184:187], v[226:229], v[24:27]
	v_mfma_f32_16x16x32_bf16 v[12:15], v[176:179], v[234:237], v[12:15]
	v_mfma_f32_16x16x32_bf16 v[8:11], v[184:187], v[234:237], v[8:11]
	s_setprio 0
	s_setprio 1
	v_mfma_f32_16x16x32_bf16 v[52:55], v[188:191], v[206:209], v[52:55]
	v_mfma_f32_16x16x32_bf16 v[48:51], v[196:199], v[206:209], v[48:51]
	v_mfma_f32_16x16x32_bf16 v[36:39], v[188:191], v[214:217], v[36:39]
	v_mfma_f32_16x16x32_bf16 v[32:35], v[196:199], v[214:217], v[32:35]
	v_mfma_f32_16x16x32_bf16 v[20:23], v[188:191], v[222:225], v[20:23]
	v_mfma_f32_16x16x32_bf16 v[16:19], v[196:199], v[222:225], v[16:19]
	v_mfma_f32_16x16x32_bf16 v[4:7], v[188:191], v[230:233], v[4:7]
	v_mfma_f32_16x16x32_bf16 v[0:3], v[196:199], v[230:233], v[0:3]
	v_mfma_f32_16x16x32_bf16 v[52:55], v[192:195], v[210:213], v[52:55]
	v_mfma_f32_16x16x32_bf16 v[48:51], v[202:205], v[210:213], v[48:51]
	v_mfma_f32_16x16x32_bf16 v[36:39], v[192:195], v[218:221], v[36:39]
	v_mfma_f32_16x16x32_bf16 v[32:35], v[202:205], v[218:221], v[32:35]
	v_mfma_f32_16x16x32_bf16 v[20:23], v[192:195], v[226:229], v[20:23]
	v_mfma_f32_16x16x32_bf16 v[16:19], v[202:205], v[226:229], v[16:19]
	v_mfma_f32_16x16x32_bf16 v[4:7], v[192:195], v[234:237], v[4:7]
	v_mfma_f32_16x16x32_bf16 v[0:3], v[202:205], v[234:237], v[0:3]
	s_setprio 0
	s_barrier
	s_add_i32 s53, s53, 2
	s_add_u32 s51, s51, 0x100
	s_addc_u32 s52, s52, 0
	s_add_u32 s26, s26, 0x100
	s_addc_u32 s27, s27, 0
	s_cmp_gt_u32 s53, 13
	s_branch .Lpost15

; #define PG8_STAGE(bufoff, gbase, voff) do { _Pragma("unroll") for (int _i = 0; _i < 2; ++_i) \
;         __builtin_amdgcn_global_load_lds((const unsigned*)((const char*)(gbase) + (voff)[_i]), (PG8_LAS unsigned*)(lds + (bufoff) + ldsw + _i * 8192), 16, 0, 0); } while (0)
; #define PG8_LDA(dst, b, h) do { _Pragma("unroll") for (int m = 0; m < 4; ++m) _Pragma("unroll") for (int k = 0; k < 2; ++k) dst[m][k] = *(const PG8_LAS bf16x8*)(lds + PG8_SA(b, h) + aoff + m * 2048 + k * 1024); } while (0)
; #define PG8_LDB(dst, b, h) do { _Pragma("unroll") for (int n = 0; n < 2; ++n) _Pragma("unroll") for (int k = 0; k < 2; ++k) dst[n][k] = *(const PG8_LAS bf16x8*)(lds + PG8_SB(b, h) + boff + n * 2048 + k * 1024); } while (0)
; #define PG8_MMA(ai, bj, At, Bt) do { __builtin_amdgcn_s_setprio(1); _Pragma("unroll") for (int m = 0; m < 4; ++m) _Pragma("unroll") for (int n = 0; n < 2; ++n) _Pragma("unroll") for (int k = 0; k < 2; ++k) \
;         acc[ai][bj][m][n] = __builtin_amdgcn_mfma_f32_16x16x32_bf16(Bt[n][k], At[m][k], acc[ai][bj][m][n], 0, 0, 0); __builtin_amdgcn_s_setprio(0); } while (0)
; #define PG8_WAIT_V(n) asm volatile("s_waitcnt vmcnt(" #n ")" ::: "memory")
; #define PG8_BAR __builtin_amdgcn_s_barrier()
; template <class Epi, class Sched, bool ALIGN_EPI = false, bool SP2 = false>
; __device__ __forceinline__ void gemm_phase(PG8_LAS unsigned char* lds, const Gemm g, const Sched& S, const Epi& E, int tid_in) {
;     ...
;         for (int t = 0; t < nt; t += 2) {
;             const bool last = (t == nt - 2);
;             const char* a1 = cA + (size_t)(t + 1) * kstep;
;             const char* a2 = last ? nA : cA + (size_t)(t + 2) * kstep; const char* b2 = last ? nB : cB + (size_t)(t + 2) * kstep;
;             const char* a3 = a2 + kstep; const char* b3 = b2 + kstep;
;             if (last && has_next) S.a_ready(nxt);
;             if constexpr (SP2) {
;             PG8_LDB(B0, 0, 0); PG8_LDB(B1, 0, 1); PG8_SCHED; PG8_LDA(At, 0, 0); PG8_STAGE(PG8_SA(1, 1), a1 + hstep, voffA);
;             PG8_WAIT_V(8); PG8_WAIT_L(0); PG8_BAR; PG8_MMA(0, 0, At, B0); PG8_MMA(0, 1, At, B1); PG8_BAR; PG8_SCHED;
;             PG8_LDA(At, 0, 1); PG8_STAGE(PG8_SB(0, 0), b2, voffB); PG8_STAGE(PG8_SB(0, 1), b2 + hstep, voffB); PG8_STAGE(PG8_SA(0, 0), a2, voffA);
;             PG8_WAIT_V(8); PG8_WAIT_L(0); PG8_BAR; PG8_MMA(1, 0, At, B0); PG8_MMA(1, 1, At, B1); PG8_BAR; PG8_SCHED;
.LBB0_2120:
	ds_read_b128 v[144:147], v155
	ds_read_b128 v[148:151], v155 offset:1024
	ds_read_b128 v[158:161], v155 offset:2048
	ds_read_b128 v[162:165], v155 offset:3072
	ds_read_b128 v[166:169], v156
	ds_read_b128 v[170:173], v156 offset:1024
	ds_read_b128 v[174:177], v156 offset:2048
	ds_read_b128 v[178:181], v156 offset:3072
	s_add_u32 s20, s18, 0x100
	s_addc_u32 s21, s19, 0
	s_cmp_eq_u32 s49, 40
	s_cselect_b32 s25, s5, s21
	s_cselect_b32 s24, s4, s20
	s_cselect_b32 s23, s17, s48
	s_cselect_b32 s22, s16, s47
	s_cbranch_scc1 .Lpk16
	v_lshl_add_u64 v[214:215], s[18:19], 0, v[138:139]
	s_add_i32 m0, s33, 0xc000
	ds_read_b128 v[182:185], v157
	ds_read_b128 v[186:189], v157 offset:1024
	ds_read_b128 v[190:193], v157 offset:2048
	ds_read_b128 v[194:197], v157 offset:3072
	ds_read_b128 v[198:201], v157 offset:4096
	ds_read_b128 v[202:205], v157 offset:5120
	ds_read_b128 v[206:209], v157 offset:6144
	ds_read_b128 v[210:213], v157 offset:7168
	global_load_lds_dwordx4 v[214:215], off
	v_lshl_add_u64 v[214:215], s[18:19], 0, v[136:137]
	s_add_i32 m0, s33, 0xe000
	s_nop 0
	global_load_lds_dwordx4 v[214:215], off
	s_waitcnt vmcnt(8)
	s_waitcnt lgkmcnt(0)
	s_barrier
	s_setprio 1
	s_waitcnt lgkmcnt(0)
	v_mfma_f32_16x16x32_bf16 v[124:127], v[144:147], v[182:185], v[124:127]
	v_mfma_f32_16x16x32_bf16 v[120:123], v[158:161], v[182:185], v[120:123]
	v_mfma_f32_16x16x32_bf16 v[108:111], v[144:147], v[190:193], v[108:111]
	v_mfma_f32_16x16x32_bf16 v[104:107], v[158:161], v[190:193], v[104:107]
	v_mfma_f32_16x16x32_bf16 v[96:99], v[144:147], v[198:201], v[96:99]
	v_mfma_f32_16x16x32_bf16 v[88:91], v[158:161], v[198:201], v[88:91]
	v_mfma_f32_16x16x32_bf16 v[80:83], v[144:147], v[206:209], v[80:83]
	v_mfma_f32_16x16x32_bf16 v[72:75], v[158:161], v[206:209], v[72:75]
	v_mfma_f32_16x16x32_bf16 v[124:127], v[148:151], v[186:189], v[124:127]
	v_mfma_f32_16x16x32_bf16 v[120:123], v[162:165], v[186:189], v[120:123]
	v_mfma_f32_16x16x32_bf16 v[108:111], v[148:151], v[194:197], v[108:111]
	v_mfma_f32_16x16x32_bf16 v[104:107], v[162:165], v[194:197], v[104:107]
	v_mfma_f32_16x16x32_bf16 v[96:99], v[148:151], v[202:205], v[96:99]
	v_mfma_f32_16x16x32_bf16 v[88:91], v[162:165], v[202:205], v[88:91]
	v_mfma_f32_16x16x32_bf16 v[80:83], v[148:151], v[210:213], v[80:83]
	v_mfma_f32_16x16x32_bf16 v[72:75], v[162:165], v[210:213], v[72:75]
	s_setprio 0
	s_setprio 1
	v_mfma_f32_16x16x32_bf16 v[116:119], v[166:169], v[182:185], v[116:119]
	v_mfma_f32_16x16x32_bf16 v[112:115], v[174:177], v[182:185], v[112:115]
	v_mfma_f32_16x16x32_bf16 v[100:103], v[166:169], v[190:193], v[100:103]
	v_mfma_f32_16x16x32_bf16 v[92:95], v[174:177], v[190:193], v[92:95]
	v_mfma_f32_16x16x32_bf16 v[84:87], v[166:169], v[198:201], v[84:87]
	v_mfma_f32_16x16x32_bf16 v[76:79], v[174:177], v[198:201], v[76:79]
	v_mfma_f32_16x16x32_bf16 v[68:71], v[166:169], v[206:209], v[68:71]
	v_mfma_f32_16x16x32_bf16 v[64:67], v[174:177], v[206:209], v[64:67]
	v_mfma_f32_16x16x32_bf16 v[116:119], v[170:173], v[186:189], v[116:119]
	v_mfma_f32_16x16x32_bf16 v[112:115], v[178:181], v[186:189], v[112:115]
	v_mfma_f32_16x16x32_bf16 v[100:103], v[170:173], v[194:197], v[100:103]
	v_mfma_f32_16x16x32_bf16 v[92:95], v[178:181], v[194:197], v[92:95]
	v_mfma_f32_16x16x32_bf16 v[84:87], v[170:173], v[202:205], v[84:87]
	v_mfma_f32_16x16x32_bf16 v[76:79], v[178:181], v[202:205], v[76:79]
	v_mfma_f32_16x16x32_bf16 v[68:71], v[170:173], v[210:213], v[68:71]
	v_mfma_f32_16x16x32_bf16 v[64:67], v[178:181], v[210:213], v[64:67]
	s_setprio 0
	s_barrier
	s_add_i32 s18, s41, s31
	v_lshl_add_u64 v[214:215], s[22:23], 0, v[130:131]
	s_mov_b32 m0, s18
	ds_read_b128 v[182:185], v157 offset:16384
	ds_read_b128 v[186:189], v157 offset:17408
	ds_read_b128 v[190:193], v157 offset:18432
	ds_read_b128 v[194:197], v157 offset:19456
	ds_read_b128 v[198:201], v157 offset:20480
	ds_read_b128 v[202:205], v157 offset:21504
	ds_read_b128 v[206:209], v157 offset:22528
	ds_read_b128 v[210:213], v157 offset:23552
	global_load_lds_dwordx4 v[214:215], off
	s_add_i32 m0, s18, 0x2000
	s_add_u32 s18, s22, 0xb0000
	v_lshl_add_u64 v[216:217], s[22:23], 0, v[134:135]
	s_addc_u32 s19, s23, 0
	s_add_i32 s50, s42, s31
	global_load_lds_dwordx4 v[216:217], off
	v_lshl_add_u64 v[218:219], s[18:19], 0, v[130:131]
	s_mov_b32 m0, s50
	v_lshl_add_u64 v[220:221], s[24:25], 0, v[132:133]
	global_load_lds_dwordx4 v[218:219], off
	v_lshl_add_u64 v[218:219], s[18:19], 0, v[134:135]
	s_add_i32 m0, s50, 0x2000
	s_nop 0
	global_load_lds_dwordx4 v[218:219], off
	v_lshl_add_u64 v[218:219], s[24:25], 0, v[128:129]
	s_mov_b32 m0, s33
	s_nop 0
	global_load_lds_dwordx4 v[218:219], off
	s_mov_b32 m0, s34
	s_nop 0
	global_load_lds_dwordx4 v[220:221], off
	s_waitcnt vmcnt(8)
	s_waitcnt lgkmcnt(0)
	s_barrier
; #define PG8_STAGE(bufoff, gbase, voff) do { _Pragma("unroll") for (int _i = 0; _i < 2; ++_i) \
;         __builtin_amdgcn_global_load_lds((const unsigned*)((const char*)(gbase) + (voff)[_i]), (PG8_LAS unsigned*)(lds + (bufoff) + ldsw + _i * 8192), 16, 0, 0); } while (0)
; #define PG8_LDA(dst, b, h) do { _Pragma("unroll") for (int m = 0; m < 4; ++m) _Pragma("unroll") for (int k = 0; k < 2; ++k) dst[m][k] = *(const PG8_LAS bf16x8*)(lds + PG8_SA(b, h) + aoff + m * 2048 + k * 1024); } while (0)
; #define PG8_LDB(dst, b, h) do { _Pragma("unroll") for (int n = 0; n < 2; ++n) _Pragma("unroll") for (int k = 0; k < 2; ++k) dst[n][k] = *(const PG8_LAS bf16x8*)(lds + PG8_SB(b, h) + boff + n * 2048 + k * 1024); } while (0)
; #define PG8_MMA(ai, bj, At, Bt) do { __builtin_amdgcn_s_setprio(1); _Pragma("unroll") for (int m = 0; m < 4; ++m) _Pragma("unroll") for (int n = 0; n < 2; ++n) _Pragma("unroll") for (int k = 0; k < 2; ++k) \
;         acc[ai][bj][m][n] = __builtin_amdgcn_mfma_f32_16x16x32_bf16(Bt[n][k], At[m][k], acc[ai][bj][m][n], 0, 0, 0); __builtin_amdgcn_s_setprio(0); } while (0)
; #define PG8_WAIT_V(n) asm volatile("s_waitcnt vmcnt(" #n ")" ::: "memory")
; #define PG8_WAIT_L(n) asm volatile("s_waitcnt lgkmcnt(" #n ")" ::: "memory")
; #define PG8_BAR __builtin_amdgcn_s_barrier()
; #define PG8_SCHED __builtin_amdgcn_sched_barrier(0)
; template <class Epi, class Sched, bool ALIGN_EPI = false, bool SP2 = false>
; __device__ __forceinline__ void gemm_phase(PG8_LAS unsigned char* lds, const Gemm g, const Sched& S, const Epi& E, int tid_in) {
;     ...
;             PG8_WAIT_V(8); PG8_WAIT_L(0); PG8_BAR; PG8_MMA(1, 0, At, B0); PG8_MMA(1, 1, At, B1); PG8_BAR; PG8_SCHED;
;             PG8_LDB(B0, 1, 0); PG8_LDB(B1, 1, 1); PG8_SCHED; PG8_LDA(At, 1, 0); PG8_STAGE(PG8_SA(0, 1), a2 + hstep, voffA);
;             PG8_WAIT_V(8); PG8_WAIT_L(0); PG8_BAR; PG8_MMA(0, 0, At, B0); PG8_MMA(0, 1, At, B1); PG8_BAR; PG8_SCHED;
	s_setprio 1
	s_waitcnt lgkmcnt(0)
	v_mfma_f32_16x16x32_bf16 v[60:63], v[144:147], v[182:185], v[60:63]
	v_mfma_f32_16x16x32_bf16 v[56:59], v[158:161], v[182:185], v[56:59]
	v_mfma_f32_16x16x32_bf16 v[48:51], v[144:147], v[190:193], v[48:51]
	v_mfma_f32_16x16x32_bf16 v[40:43], v[158:161], v[190:193], v[40:43]
	v_mfma_f32_16x16x32_bf16 v[32:35], v[144:147], v[198:201], v[32:35]
	v_mfma_f32_16x16x32_bf16 v[24:27], v[158:161], v[198:201], v[24:27]
	v_mfma_f32_16x16x32_bf16 v[16:19], v[144:147], v[206:209], v[16:19]
	v_mfma_f32_16x16x32_bf16 v[8:11], v[158:161], v[206:209], v[8:11]
	v_mfma_f32_16x16x32_bf16 v[60:63], v[148:151], v[186:189], v[60:63]
	v_mfma_f32_16x16x32_bf16 v[56:59], v[162:165], v[186:189], v[56:59]
	v_mfma_f32_16x16x32_bf16 v[48:51], v[148:151], v[194:197], v[48:51]
	v_mfma_f32_16x16x32_bf16 v[40:43], v[162:165], v[194:197], v[40:43]
	v_mfma_f32_16x16x32_bf16 v[32:35], v[148:151], v[202:205], v[32:35]
	v_mfma_f32_16x16x32_bf16 v[24:27], v[162:165], v[202:205], v[24:27]
	v_mfma_f32_16x16x32_bf16 v[16:19], v[148:151], v[210:213], v[16:19]
	v_mfma_f32_16x16x32_bf16 v[8:11], v[162:165], v[210:213], v[8:11]
	s_setprio 0
	s_setprio 1
	v_mfma_f32_16x16x32_bf16 v[52:55], v[166:169], v[182:185], v[52:55]
	v_mfma_f32_16x16x32_bf16 v[44:47], v[174:177], v[182:185], v[44:47]
	v_mfma_f32_16x16x32_bf16 v[36:39], v[166:169], v[190:193], v[36:39]
	v_mfma_f32_16x16x32_bf16 v[28:31], v[174:177], v[190:193], v[28:31]
	v_mfma_f32_16x16x32_bf16 v[20:23], v[166:169], v[198:201], v[20:23]
	v_mfma_f32_16x16x32_bf16 v[12:15], v[174:177], v[198:201], v[12:15]
	v_mfma_f32_16x16x32_bf16 v[4:7], v[166:169], v[206:209], v[4:7]
	v_mfma_f32_16x16x32_bf16 v[0:3], v[174:177], v[206:209], v[0:3]
	v_mfma_f32_16x16x32_bf16 v[52:55], v[170:173], v[186:189], v[52:55]
	v_mfma_f32_16x16x32_bf16 v[44:47], v[178:181], v[186:189], v[44:47]
	v_mfma_f32_16x16x32_bf16 v[36:39], v[170:173], v[194:197], v[36:39]
	v_mfma_f32_16x16x32_bf16 v[28:31], v[178:181], v[194:197], v[28:31]
	v_mfma_f32_16x16x32_bf16 v[20:23], v[170:173], v[202:205], v[20:23]
	v_mfma_f32_16x16x32_bf16 v[12:15], v[178:181], v[202:205], v[12:15]
	v_mfma_f32_16x16x32_bf16 v[4:7], v[170:173], v[210:213], v[4:7]
	v_mfma_f32_16x16x32_bf16 v[0:3], v[178:181], v[210:213], v[0:3]
	s_setprio 0
	s_barrier
	s_add_i32 s50, 0, 0x18000
	s_add_i32 s51, 0, 0x1c000
	v_add_u32_e32 v162, s50, v153
	v_add_u32_e32 v178, s51, v153
	ds_read_b128 v[144:147], v162
	ds_read_b128 v[148:151], v162 offset:1024
	ds_read_b128 v[158:161], v162 offset:2048
	ds_read_b128 v[162:165], v162 offset:3072
	ds_read_b128 v[166:169], v178
	ds_read_b128 v[170:173], v178 offset:1024
	ds_read_b128 v[174:177], v178 offset:2048
	ds_read_b128 v[178:181], v178 offset:3072
	s_add_u32 s18, s24, 0xb0000
	s_addc_u32 s19, s25, 0
	s_mov_b32 m0, s35
	v_lshl_add_u64 v[222:223], s[18:19], 0, v[128:129]
	ds_read_b128 v[182:185], v157 offset:32768
	ds_read_b128 v[186:189], v157 offset:33792
	ds_read_b128 v[190:193], v157 offset:34816
	ds_read_b128 v[194:197], v157 offset:35840
	ds_read_b128 v[198:201], v157 offset:36864
	ds_read_b128 v[202:205], v157 offset:37888
	ds_read_b128 v[206:209], v157 offset:38912
	ds_read_b128 v[210:213], v157 offset:39936
	global_load_lds_dwordx4 v[222:223], off
	v_lshl_add_u64 v[222:223], s[18:19], 0, v[132:133]
	s_mov_b32 m0, s36
	s_nop 0
	global_load_lds_dwordx4 v[222:223], off
	s_waitcnt vmcnt(8)
	s_waitcnt lgkmcnt(0)
	s_barrier
	s_setprio 1
	s_waitcnt lgkmcnt(0)
	v_mfma_f32_16x16x32_bf16 v[124:127], v[144:147], v[182:185], v[124:127]
	v_mfma_f32_16x16x32_bf16 v[120:123], v[158:161], v[182:185], v[120:123]
	v_mfma_f32_16x16x32_bf16 v[108:111], v[144:147], v[190:193], v[108:111]
	v_mfma_f32_16x16x32_bf16 v[104:107], v[158:161], v[190:193], v[104:107]
	v_mfma_f32_16x16x32_bf16 v[96:99], v[144:147], v[198:201], v[96:99]
	v_mfma_f32_16x16x32_bf16 v[88:91], v[158:161], v[198:201], v[88:91]
	v_mfma_f32_16x16x32_bf16 v[80:83], v[144:147], v[206:209], v[80:83]
	v_mfma_f32_16x16x32_bf16 v[72:75], v[158:161], v[206:209], v[72:75]
	v_mfma_f32_16x16x32_bf16 v[124:127], v[148:151], v[186:189], v[124:127]
	v_mfma_f32_16x16x32_bf16 v[120:123], v[162:165], v[186:189], v[120:123]
	v_mfma_f32_16x16x32_bf16 v[108:111], v[148:151], v[194:197], v[108:111]
	v_mfma_f32_16x16x32_bf16 v[104:107], v[162:165], v[194:197], v[104:107]
	v_mfma_f32_16x16x32_bf16 v[96:99], v[148:151], v[202:205], v[96:99]
	v_mfma_f32_16x16x32_bf16 v[88:91], v[162:165], v[202:205], v[88:91]
	v_mfma_f32_16x16x32_bf16 v[80:83], v[148:151], v[210:213], v[80:83]
	v_mfma_f32_16x16x32_bf16 v[72:75], v[162:165], v[210:213], v[72:75]
	s_setprio 0
	s_setprio 1
	v_mfma_f32_16x16x32_bf16 v[116:119], v[166:169], v[182:185], v[116:119]
	v_mfma_f32_16x16x32_bf16 v[112:115], v[174:177], v[182:185], v[112:115]
	v_mfma_f32_16x16x32_bf16 v[100:103], v[166:169], v[190:193], v[100:103]
	v_mfma_f32_16x16x32_bf16 v[92:95], v[174:177], v[190:193], v[92:95]
	v_mfma_f32_16x16x32_bf16 v[84:87], v[166:169], v[198:201], v[84:87]
	v_mfma_f32_16x16x32_bf16 v[76:79], v[174:177], v[198:201], v[76:79]
	v_mfma_f32_16x16x32_bf16 v[68:71], v[166:169], v[206:209], v[68:71]
	v_mfma_f32_16x16x32_bf16 v[64:67], v[174:177], v[206:209], v[64:67]
	v_mfma_f32_16x16x32_bf16 v[116:119], v[170:173], v[186:189], v[116:119]
	v_mfma_f32_16x16x32_bf16 v[112:115], v[178:181], v[186:189], v[112:115]
	v_mfma_f32_16x16x32_bf16 v[100:103], v[170:173], v[194:197], v[100:103]
	v_mfma_f32_16x16x32_bf16 v[92:95], v[178:181], v[194:197], v[92:95]
	v_mfma_f32_16x16x32_bf16 v[84:87], v[170:173], v[202:205], v[84:87]
	v_mfma_f32_16x16x32_bf16 v[76:79], v[178:181], v[202:205], v[76:79]
	v_mfma_f32_16x16x32_bf16 v[68:71], v[170:173], v[210:213], v[68:71]
	v_mfma_f32_16x16x32_bf16 v[64:67], v[178:181], v[210:213], v[64:67]
	s_setprio 0
	s_barrier
; #define PG8_STAGE(bufoff, gbase, voff) do { _Pragma("unroll") for (int _i = 0; _i < 2; ++_i) \
;         __builtin_amdgcn_global_load_lds((const unsigned*)((const char*)(gbase) + (voff)[_i]), (PG8_LAS unsigned*)(lds + (bufoff) + ldsw + _i * 8192), 16, 0, 0); } while (0)
; #define PG8_LDA(dst, b, h) do { _Pragma("unroll") for (int m = 0; m < 4; ++m) _Pragma("unroll") for (int k = 0; k < 2; ++k) dst[m][k] = *(const PG8_LAS bf16x8*)(lds + PG8_SA(b, h) + aoff + m * 2048 + k * 1024); } while (0)
; #define PG8_MMA(ai, bj, At, Bt) do { __builtin_amdgcn_s_setprio(1); _Pragma("unroll") for (int m = 0; m < 4; ++m) _Pragma("unroll") for (int n = 0; n < 2; ++n) _Pragma("unroll") for (int k = 0; k < 2; ++k) \
;         acc[ai][bj][m][n] = __builtin_amdgcn_mfma_f32_16x16x32_bf16(Bt[n][k], At[m][k], acc[ai][bj][m][n], 0, 0, 0); __builtin_amdgcn_s_setprio(0); } while (0)
; #define PG8_WAIT_V(n) asm volatile("s_waitcnt vmcnt(" #n ")" ::: "memory")
; #define PG8_WAIT_L(n) asm volatile("s_waitcnt lgkmcnt(" #n ")" ::: "memory")
; #define PG8_BAR __builtin_amdgcn_s_barrier()
; #define PG8_SCHED __builtin_amdgcn_sched_barrier(0)
; template <class Epi, class Sched, bool ALIGN_EPI = false, bool SP2 = false>
; __device__ __forceinline__ void gemm_phase(PG8_LAS unsigned char* lds, const Gemm g, const Sched& S, const Epi& E, int tid_in) {
;     ...
;         for (int t = 0; t < nt; t += 2) {
;             const bool last = (t == nt - 2);
;             const char* a1 = cA + (size_t)(t + 1) * kstep;
;             const char* a2 = last ? nA : cA + (size_t)(t + 2) * kstep; const char* b2 = last ? nB : cB + (size_t)(t + 2) * kstep;
;     ...
;             PG8_LDA(At, 1, 1); PG8_STAGE(PG8_SB(1, 0), b3, voffB); PG8_STAGE(PG8_SB(1, 1), b3 + hstep, voffB); PG8_STAGE(PG8_SA(1, 0), a3, voffA);
;             PG8_WAIT_V(8); PG8_WAIT_L(0); PG8_BAR; PG8_MMA(1, 0, At, B0); PG8_MMA(1, 1, At, B1); PG8_BAR; PG8_SCHED;
	s_add_i32 s18, s50, s31
	v_lshl_add_u64 v[214:215], v[214:215], 0, s[12:13]
	s_mov_b32 m0, s18
	ds_read_b128 v[182:185], v157 offset:49152
	ds_read_b128 v[186:189], v157 offset:50176
	ds_read_b128 v[190:193], v157 offset:51200
	ds_read_b128 v[194:197], v157 offset:52224
	ds_read_b128 v[198:201], v157 offset:53248
	ds_read_b128 v[202:205], v157 offset:54272
	ds_read_b128 v[206:209], v157 offset:55296
	ds_read_b128 v[210:213], v157 offset:56320
	global_load_lds_dwordx4 v[214:215], off
	s_add_i32 m0, s18, 0x2000
	s_add_u32 s18, s22, 0xb0080
	v_lshl_add_u64 v[214:215], v[216:217], 0, s[12:13]
	s_addc_u32 s19, s23, 0
	s_add_i32 s22, s51, s31
	global_load_lds_dwordx4 v[214:215], off
	v_lshl_add_u64 v[214:215], s[18:19], 0, v[130:131]
	s_mov_b32 m0, s22
	s_nop 0
	global_load_lds_dwordx4 v[214:215], off
	v_lshl_add_u64 v[214:215], s[18:19], 0, v[134:135]
	s_add_i32 m0, s22, 0x2000
	s_nop 0
	global_load_lds_dwordx4 v[214:215], off
	v_lshl_add_u64 v[214:215], v[218:219], 0, s[12:13]
	s_mov_b32 m0, s38
	s_nop 0
	global_load_lds_dwordx4 v[214:215], off
	v_lshl_add_u64 v[214:215], v[220:221], 0, s[12:13]
	s_mov_b32 m0, s39
	s_nop 0
	global_load_lds_dwordx4 v[214:215], off
	s_waitcnt vmcnt(8)
	s_waitcnt lgkmcnt(0)
	s_barrier
	s_setprio 1
	s_waitcnt lgkmcnt(0)
	v_mfma_f32_16x16x32_bf16 v[60:63], v[144:147], v[182:185], v[60:63]
	v_mfma_f32_16x16x32_bf16 v[56:59], v[158:161], v[182:185], v[56:59]
	v_mfma_f32_16x16x32_bf16 v[48:51], v[144:147], v[190:193], v[48:51]
	v_mfma_f32_16x16x32_bf16 v[40:43], v[158:161], v[190:193], v[40:43]
	v_mfma_f32_16x16x32_bf16 v[32:35], v[144:147], v[198:201], v[32:35]
	v_mfma_f32_16x16x32_bf16 v[24:27], v[158:161], v[198:201], v[24:27]
	v_mfma_f32_16x16x32_bf16 v[16:19], v[144:147], v[206:209], v[16:19]
	v_mfma_f32_16x16x32_bf16 v[8:11], v[158:161], v[206:209], v[8:11]
	v_mfma_f32_16x16x32_bf16 v[60:63], v[148:151], v[186:189], v[60:63]
	v_mfma_f32_16x16x32_bf16 v[56:59], v[162:165], v[186:189], v[56:59]
	v_mfma_f32_16x16x32_bf16 v[48:51], v[148:151], v[194:197], v[48:51]
	v_mfma_f32_16x16x32_bf16 v[40:43], v[162:165], v[194:197], v[40:43]
	v_mfma_f32_16x16x32_bf16 v[32:35], v[148:151], v[202:205], v[32:35]
	v_mfma_f32_16x16x32_bf16 v[24:27], v[162:165], v[202:205], v[24:27]
	v_mfma_f32_16x16x32_bf16 v[16:19], v[148:151], v[210:213], v[16:19]
	v_mfma_f32_16x16x32_bf16 v[8:11], v[162:165], v[210:213], v[8:11]
	s_setprio 0
	s_setprio 1
	v_mfma_f32_16x16x32_bf16 v[52:55], v[166:169], v[182:185], v[52:55]
	v_mfma_f32_16x16x32_bf16 v[44:47], v[174:177], v[182:185], v[44:47]
	v_mfma_f32_16x16x32_bf16 v[36:39], v[166:169], v[190:193], v[36:39]
	v_mfma_f32_16x16x32_bf16 v[28:31], v[174:177], v[190:193], v[28:31]
	v_mfma_f32_16x16x32_bf16 v[20:23], v[166:169], v[198:201], v[20:23]
	v_mfma_f32_16x16x32_bf16 v[12:15], v[174:177], v[198:201], v[12:15]
	v_mfma_f32_16x16x32_bf16 v[4:7], v[166:169], v[206:209], v[4:7]
	v_mfma_f32_16x16x32_bf16 v[0:3], v[174:177], v[206:209], v[0:3]
	v_mfma_f32_16x16x32_bf16 v[52:55], v[170:173], v[186:189], v[52:55]
	v_mfma_f32_16x16x32_bf16 v[44:47], v[178:181], v[186:189], v[44:47]
	v_mfma_f32_16x16x32_bf16 v[36:39], v[170:173], v[194:197], v[36:39]
	v_mfma_f32_16x16x32_bf16 v[28:31], v[178:181], v[194:197], v[28:31]
	v_mfma_f32_16x16x32_bf16 v[20:23], v[170:173], v[202:205], v[20:23]
	v_mfma_f32_16x16x32_bf16 v[12:15], v[178:181], v[202:205], v[12:15]
	v_mfma_f32_16x16x32_bf16 v[4:7], v[170:173], v[210:213], v[4:7]
	v_mfma_f32_16x16x32_bf16 v[0:3], v[178:181], v[210:213], v[0:3]
	s_setprio 0
	s_barrier
	s_add_i32 s49, s49, 2
	s_add_u32 s47, s47, 0x100
	s_addc_u32 s48, s48, 0
	s_cmp_gt_u32 s49, 41
	s_mov_b64 s[18:19], s[20:21]
	s_cbranch_scc0 .LBB0_2120

; #define PG8_STAGE(bufoff, gbase, voff) do { _Pragma("unroll") for (int _i = 0; _i < 2; ++_i) \
;         __builtin_amdgcn_global_load_lds((const unsigned*)((const char*)(gbase) + (voff)[_i]), (PG8_LAS unsigned*)(lds + (bufoff) + ldsw + _i * 8192), 16, 0, 0); } while (0)
; #define PG8_LDA(dst, b, h) do { _Pragma("unroll") for (int m = 0; m < 4; ++m) _Pragma("unroll") for (int k = 0; k < 2; ++k) dst[m][k] = *(const PG8_LAS bf16x8*)(lds + PG8_SA(b, h) + aoff + m * 2048 + k * 1024); } while (0)
; #define PG8_LDB(dst, b, h) do { _Pragma("unroll") for (int n = 0; n < 2; ++n) _Pragma("unroll") for (int k = 0; k < 2; ++k) dst[n][k] = *(const PG8_LAS bf16x8*)(lds + PG8_SB(b, h) + boff + n * 2048 + k * 1024); } while (0)
; #define PG8_MMA(ai, bj, At, Bt) do { __builtin_amdgcn_s_setprio(1); _Pragma("unroll") for (int m = 0; m < 4; ++m) _Pragma("unroll") for (int n = 0; n < 2; ++n) _Pragma("unroll") for (int k = 0; k < 2; ++k) \
;         acc[ai][bj][m][n] = __builtin_amdgcn_mfma_f32_16x16x32_bf16(Bt[n][k], At[m][k], acc[ai][bj][m][n], 0, 0, 0); __builtin_amdgcn_s_setprio(0); } while (0)
; #define PG8_WAIT_V(n) asm volatile("s_waitcnt vmcnt(" #n ")" ::: "memory")
; #define PG8_WAIT_L(n) asm volatile("s_waitcnt lgkmcnt(" #n ")" ::: "memory")
; #define PG8_BAR __builtin_amdgcn_s_barrier()
; #define PG8_SCHED __builtin_amdgcn_sched_barrier(0)
; template <class Epi, class Sched, bool ALIGN_EPI = false, bool SP2 = false>
; __device__ __forceinline__ void gemm_phase(PG8_LAS unsigned char* lds, const Gemm g, const Sched& S, const Epi& E, int tid_in) {
;     ...
;             PG8_LDB(B0, 0, 0); PG8_LDB(B1, 0, 1); PG8_SCHED; PG8_LDA(At, 0, 0); PG8_STAGE(PG8_SA(1, 1), a1 + hstep, voffA);
;             PG8_WAIT_V(8); PG8_WAIT_L(0); PG8_BAR; PG8_MMA(0, 0, At, B0); PG8_MMA(0, 1, At, B1); PG8_BAR; PG8_SCHED;
;             PG8_LDA(At, 0, 1); PG8_STAGE(PG8_SB(0, 0), b2, voffB); PG8_STAGE(PG8_SB(0, 1), b2 + hstep, voffB); PG8_STAGE(PG8_SA(0, 0), a2, voffA);
;             PG8_WAIT_V(8); PG8_WAIT_L(0); PG8_BAR; PG8_MMA(1, 0, At, B0); PG8_MMA(1, 1, At, B1); PG8_BAR; PG8_SCHED;
.Lpk16:
	s_mov_b64 s[98:99], 1
	v_lshl_add_u64 v[214:215], s[18:19], 0, v[138:139]
	s_add_i32 m0, s33, 0xc000
	ds_read_b128 v[182:185], v157
	ds_read_b128 v[186:189], v157 offset:1024
	ds_read_b128 v[190:193], v157 offset:2048
	ds_read_b128 v[194:197], v157 offset:3072
	ds_read_b128 v[198:201], v157 offset:4096
	ds_read_b128 v[202:205], v157 offset:5120
	ds_read_b128 v[206:209], v157 offset:6144
	ds_read_b128 v[210:213], v157 offset:7168
	global_load_lds_dwordx4 v[214:215], off
	v_lshl_add_u64 v[214:215], s[18:19], 0, v[136:137]
	s_add_i32 m0, s33, 0xe000
	s_nop 0
	global_load_lds_dwordx4 v[214:215], off
	s_waitcnt vmcnt(8)
	s_waitcnt lgkmcnt(0)
	s_barrier
	s_setprio 1
	s_waitcnt lgkmcnt(0)
	v_mfma_f32_16x16x32_bf16 v[124:127], v[144:147], v[182:185], v[124:127]
	v_mfma_f32_16x16x32_bf16 v[120:123], v[158:161], v[182:185], v[120:123]
	v_mfma_f32_16x16x32_bf16 v[108:111], v[144:147], v[190:193], v[108:111]
	v_mfma_f32_16x16x32_bf16 v[104:107], v[158:161], v[190:193], v[104:107]
	v_mfma_f32_16x16x32_bf16 v[96:99], v[144:147], v[198:201], v[96:99]
	v_mfma_f32_16x16x32_bf16 v[88:91], v[158:161], v[198:201], v[88:91]
	v_mfma_f32_16x16x32_bf16 v[80:83], v[144:147], v[206:209], v[80:83]
	v_mfma_f32_16x16x32_bf16 v[72:75], v[158:161], v[206:209], v[72:75]
	v_mfma_f32_16x16x32_bf16 v[124:127], v[148:151], v[186:189], v[124:127]
	v_mfma_f32_16x16x32_bf16 v[120:123], v[162:165], v[186:189], v[120:123]
	v_mfma_f32_16x16x32_bf16 v[108:111], v[148:151], v[194:197], v[108:111]
	v_mfma_f32_16x16x32_bf16 v[104:107], v[162:165], v[194:197], v[104:107]
	v_mfma_f32_16x16x32_bf16 v[96:99], v[148:151], v[202:205], v[96:99]
	v_mfma_f32_16x16x32_bf16 v[88:91], v[162:165], v[202:205], v[88:91]
	v_mfma_f32_16x16x32_bf16 v[80:83], v[148:151], v[210:213], v[80:83]
	v_mfma_f32_16x16x32_bf16 v[72:75], v[162:165], v[210:213], v[72:75]
	s_setprio 0
	s_setprio 1
	v_mfma_f32_16x16x32_bf16 v[116:119], v[166:169], v[182:185], v[116:119]
	v_mfma_f32_16x16x32_bf16 v[112:115], v[174:177], v[182:185], v[112:115]
	v_mfma_f32_16x16x32_bf16 v[100:103], v[166:169], v[190:193], v[100:103]
	v_mfma_f32_16x16x32_bf16 v[92:95], v[174:177], v[190:193], v[92:95]
	v_mfma_f32_16x16x32_bf16 v[84:87], v[166:169], v[198:201], v[84:87]
	v_mfma_f32_16x16x32_bf16 v[76:79], v[174:177], v[198:201], v[76:79]
	v_mfma_f32_16x16x32_bf16 v[68:71], v[166:169], v[206:209], v[68:71]
	v_mfma_f32_16x16x32_bf16 v[64:67], v[174:177], v[206:209], v[64:67]
	v_mfma_f32_16x16x32_bf16 v[116:119], v[170:173], v[186:189], v[116:119]
	v_mfma_f32_16x16x32_bf16 v[112:115], v[178:181], v[186:189], v[112:115]
	v_mfma_f32_16x16x32_bf16 v[100:103], v[170:173], v[194:197], v[100:103]
	v_mfma_f32_16x16x32_bf16 v[92:95], v[178:181], v[194:197], v[92:95]
	v_mfma_f32_16x16x32_bf16 v[84:87], v[170:173], v[202:205], v[84:87]
	v_mfma_f32_16x16x32_bf16 v[76:79], v[178:181], v[202:205], v[76:79]
	v_mfma_f32_16x16x32_bf16 v[68:71], v[170:173], v[210:213], v[68:71]
	v_mfma_f32_16x16x32_bf16 v[64:67], v[178:181], v[210:213], v[64:67]
	s_setprio 0
	s_barrier
	s_add_i32 s18, s41, s31
	v_lshl_add_u64 v[214:215], s[22:23], 0, v[130:131]
	s_mov_b32 m0, s18
	ds_read_b128 v[182:185], v157 offset:16384
	ds_read_b128 v[186:189], v157 offset:17408
	ds_read_b128 v[190:193], v157 offset:18432
	ds_read_b128 v[194:197], v157 offset:19456
	ds_read_b128 v[198:201], v157 offset:20480
	ds_read_b128 v[202:205], v157 offset:21504
	ds_read_b128 v[206:209], v157 offset:22528
	ds_read_b128 v[210:213], v157 offset:23552
	s_mov_b64 exec, s[98:99]
	global_load_lds_dwordx4 v[214:215], off
	s_mov_b64 exec, -1
	s_add_i32 m0, s18, 0x2000
	s_add_u32 s18, s22, 0xb0000
	v_lshl_add_u64 v[216:217], s[22:23], 0, v[134:135]
	s_addc_u32 s19, s23, 0
	s_add_i32 s50, s42, s31
	s_mov_b64 exec, s[98:99]
	global_load_lds_dwordx4 v[216:217], off
	s_mov_b64 exec, -1
	v_lshl_add_u64 v[218:219], s[18:19], 0, v[130:131]
	s_mov_b32 m0, s50
	v_lshl_add_u64 v[220:221], s[24:25], 0, v[132:133]
	s_mov_b64 exec, s[98:99]
	global_load_lds_dwordx4 v[218:219], off
	s_mov_b64 exec, -1
	v_lshl_add_u64 v[218:219], s[18:19], 0, v[134:135]
	s_add_i32 m0, s50, 0x2000
	s_nop 0
	s_mov_b64 exec, s[98:99]
	global_load_lds_dwordx4 v[218:219], off
	s_mov_b64 exec, -1
	v_lshl_add_u64 v[218:219], s[24:25], 0, v[128:129]
	s_mov_b32 m0, s33
	s_nop 0
	s_mov_b64 exec, s[98:99]
	global_load_lds_dwordx4 v[218:219], off
	s_mov_b64 exec, -1
	s_mov_b32 m0, s34
	s_nop 0
	s_mov_b64 exec, s[98:99]
	global_load_lds_dwordx4 v[220:221], off
	s_mov_b64 exec, -1
	s_waitcnt vmcnt(8)
	s_waitcnt lgkmcnt(0)
	s_barrier
; #define PG8_STAGE(bufoff, gbase, voff) do { _Pragma("unroll") for (int _i = 0; _i < 2; ++_i) \
;         __builtin_amdgcn_global_load_lds((const unsigned*)((const char*)(gbase) + (voff)[_i]), (PG8_LAS unsigned*)(lds + (bufoff) + ldsw + _i * 8192), 16, 0, 0); } while (0)
; #define PG8_LDA(dst, b, h) do { _Pragma("unroll") for (int m = 0; m < 4; ++m) _Pragma("unroll") for (int k = 0; k < 2; ++k) dst[m][k] = *(const PG8_LAS bf16x8*)(lds + PG8_SA(b, h) + aoff + m * 2048 + k * 1024); } while (0)
; #define PG8_LDB(dst, b, h) do { _Pragma("unroll") for (int n = 0; n < 2; ++n) _Pragma("unroll") for (int k = 0; k < 2; ++k) dst[n][k] = *(const PG8_LAS bf16x8*)(lds + PG8_SB(b, h) + boff + n * 2048 + k * 1024); } while (0)
; #define PG8_MMA(ai, bj, At, Bt) do { __builtin_amdgcn_s_setprio(1); _Pragma("unroll") for (int m = 0; m < 4; ++m) _Pragma("unroll") for (int n = 0; n < 2; ++n) _Pragma("unroll") for (int k = 0; k < 2; ++k) \
;         acc[ai][bj][m][n] = __builtin_amdgcn_mfma_f32_16x16x32_bf16(Bt[n][k], At[m][k], acc[ai][bj][m][n], 0, 0, 0); __builtin_amdgcn_s_setprio(0); } while (0)
; #define PG8_WAIT_V(n) asm volatile("s_waitcnt vmcnt(" #n ")" ::: "memory")
; #define PG8_WAIT_L(n) asm volatile("s_waitcnt lgkmcnt(" #n ")" ::: "memory")
; #define PG8_BAR __builtin_amdgcn_s_barrier()
; #define PG8_SCHED __builtin_amdgcn_sched_barrier(0)
; template <class Epi, class Sched, bool ALIGN_EPI = false, bool SP2 = false>
; __device__ __forceinline__ void gemm_phase(PG8_LAS unsigned char* lds, const Gemm g, const Sched& S, const Epi& E, int tid_in) {
;     ...
;             PG8_WAIT_V(8); PG8_WAIT_L(0); PG8_BAR; PG8_MMA(1, 0, At, B0); PG8_MMA(1, 1, At, B1); PG8_BAR; PG8_SCHED;
;             PG8_LDB(B0, 1, 0); PG8_LDB(B1, 1, 1); PG8_SCHED; PG8_LDA(At, 1, 0); PG8_STAGE(PG8_SA(0, 1), a2 + hstep, voffA);
;             PG8_WAIT_V(8); PG8_WAIT_L(0); PG8_BAR; PG8_MMA(0, 0, At, B0); PG8_MMA(0, 1, At, B1); PG8_BAR; PG8_SCHED;
	s_setprio 1
	s_waitcnt lgkmcnt(0)
	v_mfma_f32_16x16x32_bf16 v[60:63], v[144:147], v[182:185], v[60:63]
	v_mfma_f32_16x16x32_bf16 v[56:59], v[158:161], v[182:185], v[56:59]
	v_mfma_f32_16x16x32_bf16 v[48:51], v[144:147], v[190:193], v[48:51]
	v_mfma_f32_16x16x32_bf16 v[40:43], v[158:161], v[190:193], v[40:43]
	v_mfma_f32_16x16x32_bf16 v[32:35], v[144:147], v[198:201], v[32:35]
	v_mfma_f32_16x16x32_bf16 v[24:27], v[158:161], v[198:201], v[24:27]
	v_mfma_f32_16x16x32_bf16 v[16:19], v[144:147], v[206:209], v[16:19]
	v_mfma_f32_16x16x32_bf16 v[8:11], v[158:161], v[206:209], v[8:11]
	v_mfma_f32_16x16x32_bf16 v[60:63], v[148:151], v[186:189], v[60:63]
	v_mfma_f32_16x16x32_bf16 v[56:59], v[162:165], v[186:189], v[56:59]
	v_mfma_f32_16x16x32_bf16 v[48:51], v[148:151], v[194:197], v[48:51]
	v_mfma_f32_16x16x32_bf16 v[40:43], v[162:165], v[194:197], v[40:43]
	v_mfma_f32_16x16x32_bf16 v[32:35], v[148:151], v[202:205], v[32:35]
	v_mfma_f32_16x16x32_bf16 v[24:27], v[162:165], v[202:205], v[24:27]
	v_mfma_f32_16x16x32_bf16 v[16:19], v[148:151], v[210:213], v[16:19]
	v_mfma_f32_16x16x32_bf16 v[8:11], v[162:165], v[210:213], v[8:11]
	s_setprio 0
	s_setprio 1
	v_mfma_f32_16x16x32_bf16 v[52:55], v[166:169], v[182:185], v[52:55]
	v_mfma_f32_16x16x32_bf16 v[44:47], v[174:177], v[182:185], v[44:47]
	v_mfma_f32_16x16x32_bf16 v[36:39], v[166:169], v[190:193], v[36:39]
	v_mfma_f32_16x16x32_bf16 v[28:31], v[174:177], v[190:193], v[28:31]
	v_mfma_f32_16x16x32_bf16 v[20:23], v[166:169], v[198:201], v[20:23]
	v_mfma_f32_16x16x32_bf16 v[12:15], v[174:177], v[198:201], v[12:15]
	v_mfma_f32_16x16x32_bf16 v[4:7], v[166:169], v[206:209], v[4:7]
	v_mfma_f32_16x16x32_bf16 v[0:3], v[174:177], v[206:209], v[0:3]
	v_mfma_f32_16x16x32_bf16 v[52:55], v[170:173], v[186:189], v[52:55]
	v_mfma_f32_16x16x32_bf16 v[44:47], v[178:181], v[186:189], v[44:47]
	v_mfma_f32_16x16x32_bf16 v[36:39], v[170:173], v[194:197], v[36:39]
	v_mfma_f32_16x16x32_bf16 v[28:31], v[178:181], v[194:197], v[28:31]
	v_mfma_f32_16x16x32_bf16 v[20:23], v[170:173], v[202:205], v[20:23]
	v_mfma_f32_16x16x32_bf16 v[12:15], v[178:181], v[202:205], v[12:15]
	v_mfma_f32_16x16x32_bf16 v[4:7], v[170:173], v[210:213], v[4:7]
	v_mfma_f32_16x16x32_bf16 v[0:3], v[178:181], v[210:213], v[0:3]
	s_setprio 0
	s_barrier
	s_add_i32 s50, 0, 0x18000
	s_add_i32 s51, 0, 0x1c000
	v_add_u32_e32 v162, s50, v153
	v_add_u32_e32 v178, s51, v153
	ds_read_b128 v[144:147], v162
	ds_read_b128 v[148:151], v162 offset:1024
	ds_read_b128 v[158:161], v162 offset:2048
	ds_read_b128 v[162:165], v162 offset:3072
	ds_read_b128 v[166:169], v178
	ds_read_b128 v[170:173], v178 offset:1024
	ds_read_b128 v[174:177], v178 offset:2048
	ds_read_b128 v[178:181], v178 offset:3072
	s_add_u32 s18, s24, 0xb0000
	s_addc_u32 s19, s25, 0
	s_mov_b32 m0, s35
	v_lshl_add_u64 v[222:223], s[18:19], 0, v[128:129]
	ds_read_b128 v[182:185], v157 offset:32768
	ds_read_b128 v[186:189], v157 offset:33792
	ds_read_b128 v[190:193], v157 offset:34816
	ds_read_b128 v[194:197], v157 offset:35840
	ds_read_b128 v[198:201], v157 offset:36864
	ds_read_b128 v[202:205], v157 offset:37888
	ds_read_b128 v[206:209], v157 offset:38912
	ds_read_b128 v[210:213], v157 offset:39936
	s_mov_b64 exec, s[98:99]
	global_load_lds_dwordx4 v[222:223], off
	s_mov_b64 exec, -1
	v_lshl_add_u64 v[222:223], s[18:19], 0, v[132:133]
	s_mov_b32 m0, s36
	s_nop 0
	s_mov_b64 exec, s[98:99]
	global_load_lds_dwordx4 v[222:223], off
	s_mov_b64 exec, -1
	s_waitcnt vmcnt(8)
	s_waitcnt lgkmcnt(0)
	s_barrier
	s_setprio 1
	s_waitcnt lgkmcnt(0)
	v_mfma_f32_16x16x32_bf16 v[124:127], v[144:147], v[182:185], v[124:127]
	v_mfma_f32_16x16x32_bf16 v[120:123], v[158:161], v[182:185], v[120:123]
	v_mfma_f32_16x16x32_bf16 v[108:111], v[144:147], v[190:193], v[108:111]
	v_mfma_f32_16x16x32_bf16 v[104:107], v[158:161], v[190:193], v[104:107]
	v_mfma_f32_16x16x32_bf16 v[96:99], v[144:147], v[198:201], v[96:99]
	v_mfma_f32_16x16x32_bf16 v[88:91], v[158:161], v[198:201], v[88:91]
	v_mfma_f32_16x16x32_bf16 v[80:83], v[144:147], v[206:209], v[80:83]
	v_mfma_f32_16x16x32_bf16 v[72:75], v[158:161], v[206:209], v[72:75]
	v_mfma_f32_16x16x32_bf16 v[124:127], v[148:151], v[186:189], v[124:127]
	v_mfma_f32_16x16x32_bf16 v[120:123], v[162:165], v[186:189], v[120:123]
	v_mfma_f32_16x16x32_bf16 v[108:111], v[148:151], v[194:197], v[108:111]
	v_mfma_f32_16x16x32_bf16 v[104:107], v[162:165], v[194:197], v[104:107]
	v_mfma_f32_16x16x32_bf16 v[96:99], v[148:151], v[202:205], v[96:99]
	v_mfma_f32_16x16x32_bf16 v[88:91], v[162:165], v[202:205], v[88:91]
	v_mfma_f32_16x16x32_bf16 v[80:83], v[148:151], v[210:213], v[80:83]
	v_mfma_f32_16x16x32_bf16 v[72:75], v[162:165], v[210:213], v[72:75]
	s_setprio 0
	s_setprio 1
	v_mfma_f32_16x16x32_bf16 v[116:119], v[166:169], v[182:185], v[116:119]
	v_mfma_f32_16x16x32_bf16 v[112:115], v[174:177], v[182:185], v[112:115]
	v_mfma_f32_16x16x32_bf16 v[100:103], v[166:169], v[190:193], v[100:103]
	v_mfma_f32_16x16x32_bf16 v[92:95], v[174:177], v[190:193], v[92:95]
	v_mfma_f32_16x16x32_bf16 v[84:87], v[166:169], v[198:201], v[84:87]
	v_mfma_f32_16x16x32_bf16 v[76:79], v[174:177], v[198:201], v[76:79]
	v_mfma_f32_16x16x32_bf16 v[68:71], v[166:169], v[206:209], v[68:71]
	v_mfma_f32_16x16x32_bf16 v[64:67], v[174:177], v[206:209], v[64:67]
	v_mfma_f32_16x16x32_bf16 v[116:119], v[170:173], v[186:189], v[116:119]
	v_mfma_f32_16x16x32_bf16 v[112:115], v[178:181], v[186:189], v[112:115]
	v_mfma_f32_16x16x32_bf16 v[100:103], v[170:173], v[194:197], v[100:103]
	v_mfma_f32_16x16x32_bf16 v[92:95], v[178:181], v[194:197], v[92:95]
	v_mfma_f32_16x16x32_bf16 v[84:87], v[170:173], v[202:205], v[84:87]
	v_mfma_f32_16x16x32_bf16 v[76:79], v[178:181], v[202:205], v[76:79]
	v_mfma_f32_16x16x32_bf16 v[68:71], v[170:173], v[210:213], v[68:71]
	v_mfma_f32_16x16x32_bf16 v[64:67], v[178:181], v[210:213], v[64:67]
	s_setprio 0
	s_barrier
; #define PG8_STAGE(bufoff, gbase, voff) do { _Pragma("unroll") for (int _i = 0; _i < 2; ++_i) \
;         __builtin_amdgcn_global_load_lds((const unsigned*)((const char*)(gbase) + (voff)[_i]), (PG8_LAS unsigned*)(lds + (bufoff) + ldsw + _i * 8192), 16, 0, 0); } while (0)
; #define PG8_LDA(dst, b, h) do { _Pragma("unroll") for (int m = 0; m < 4; ++m) _Pragma("unroll") for (int k = 0; k < 2; ++k) dst[m][k] = *(const PG8_LAS bf16x8*)(lds + PG8_SA(b, h) + aoff + m * 2048 + k * 1024); } while (0)
; #define PG8_MMA(ai, bj, At, Bt) do { __builtin_amdgcn_s_setprio(1); _Pragma("unroll") for (int m = 0; m < 4; ++m) _Pragma("unroll") for (int n = 0; n < 2; ++n) _Pragma("unroll") for (int k = 0; k < 2; ++k) \
;         acc[ai][bj][m][n] = __builtin_amdgcn_mfma_f32_16x16x32_bf16(Bt[n][k], At[m][k], acc[ai][bj][m][n], 0, 0, 0); __builtin_amdgcn_s_setprio(0); } while (0)
; #define PG8_WAIT_V(n) asm volatile("s_waitcnt vmcnt(" #n ")" ::: "memory")
; #define PG8_WAIT_L(n) asm volatile("s_waitcnt lgkmcnt(" #n ")" ::: "memory")
; #define PG8_BAR __builtin_amdgcn_s_barrier()
; #define PG8_SCHED __builtin_amdgcn_sched_barrier(0)
; template <class Epi, class Sched, bool ALIGN_EPI = false, bool SP2 = false>
; __device__ __forceinline__ void gemm_phase(PG8_LAS unsigned char* lds, const Gemm g, const Sched& S, const Epi& E, int tid_in) {
;     ...
;             PG8_LDA(At, 1, 1); PG8_STAGE(PG8_SB(1, 0), b3, voffB); PG8_STAGE(PG8_SB(1, 1), b3 + hstep, voffB); PG8_STAGE(PG8_SA(1, 0), a3, voffA);
;             PG8_WAIT_V(8); PG8_WAIT_L(0); PG8_BAR; PG8_MMA(1, 0, At, B0); PG8_MMA(1, 1, At, B1); PG8_BAR; PG8_SCHED;
	s_add_i32 s18, s50, s31
	v_lshl_add_u64 v[214:215], v[214:215], 0, s[12:13]
	s_mov_b32 m0, s18
	ds_read_b128 v[182:185], v157 offset:49152
	ds_read_b128 v[186:189], v157 offset:50176
	ds_read_b128 v[190:193], v157 offset:51200
	ds_read_b128 v[194:197], v157 offset:52224
	ds_read_b128 v[198:201], v157 offset:53248
	ds_read_b128 v[202:205], v157 offset:54272
	ds_read_b128 v[206:209], v157 offset:55296
	ds_read_b128 v[210:213], v157 offset:56320
	s_mov_b64 exec, s[98:99]
	global_load_lds_dwordx4 v[214:215], off
	s_mov_b64 exec, -1
	s_add_i32 m0, s18, 0x2000
	s_add_u32 s18, s22, 0xb0080
	v_lshl_add_u64 v[214:215], v[216:217], 0, s[12:13]
	s_addc_u32 s19, s23, 0
	s_add_i32 s22, s51, s31
	s_mov_b64 exec, s[98:99]
	global_load_lds_dwordx4 v[214:215], off
	s_mov_b64 exec, -1
	v_lshl_add_u64 v[214:215], s[18:19], 0, v[130:131]
	s_mov_b32 m0, s22
	s_nop 0
	s_mov_b64 exec, s[98:99]
	global_load_lds_dwordx4 v[214:215], off
	s_mov_b64 exec, -1
	v_lshl_add_u64 v[214:215], s[18:19], 0, v[134:135]
	s_add_i32 m0, s22, 0x2000
	s_nop 0
	s_mov_b64 exec, s[98:99]
	global_load_lds_dwordx4 v[214:215], off
	s_mov_b64 exec, -1
	v_lshl_add_u64 v[214:215], v[218:219], 0, s[12:13]
	s_mov_b32 m0, s38
	s_nop 0
	s_mov_b64 exec, s[98:99]
	global_load_lds_dwordx4 v[214:215], off
	s_mov_b64 exec, -1
	v_lshl_add_u64 v[214:215], v[220:221], 0, s[12:13]
	s_mov_b32 m0, s39
	s_nop 0
	s_mov_b64 exec, s[98:99]
	global_load_lds_dwordx4 v[214:215], off
	s_mov_b64 exec, -1
	s_waitcnt vmcnt(8)
	s_waitcnt lgkmcnt(0)
	s_barrier
	s_setprio 1
	s_waitcnt lgkmcnt(0)
	v_mfma_f32_16x16x32_bf16 v[60:63], v[144:147], v[182:185], v[60:63]
	v_mfma_f32_16x16x32_bf16 v[56:59], v[158:161], v[182:185], v[56:59]
	v_mfma_f32_16x16x32_bf16 v[48:51], v[144:147], v[190:193], v[48:51]
	v_mfma_f32_16x16x32_bf16 v[40:43], v[158:161], v[190:193], v[40:43]
	v_mfma_f32_16x16x32_bf16 v[32:35], v[144:147], v[198:201], v[32:35]
	v_mfma_f32_16x16x32_bf16 v[24:27], v[158:161], v[198:201], v[24:27]
	v_mfma_f32_16x16x32_bf16 v[16:19], v[144:147], v[206:209], v[16:19]
	v_mfma_f32_16x16x32_bf16 v[8:11], v[158:161], v[206:209], v[8:11]
	v_mfma_f32_16x16x32_bf16 v[60:63], v[148:151], v[186:189], v[60:63]
	v_mfma_f32_16x16x32_bf16 v[56:59], v[162:165], v[186:189], v[56:59]
	v_mfma_f32_16x16x32_bf16 v[48:51], v[148:151], v[194:197], v[48:51]
	v_mfma_f32_16x16x32_bf16 v[40:43], v[162:165], v[194:197], v[40:43]
	v_mfma_f32_16x16x32_bf16 v[32:35], v[148:151], v[202:205], v[32:35]
	v_mfma_f32_16x16x32_bf16 v[24:27], v[162:165], v[202:205], v[24:27]
	v_mfma_f32_16x16x32_bf16 v[16:19], v[148:151], v[210:213], v[16:19]
	v_mfma_f32_16x16x32_bf16 v[8:11], v[162:165], v[210:213], v[8:11]
	s_setprio 0
	s_setprio 1
	v_mfma_f32_16x16x32_bf16 v[52:55], v[166:169], v[182:185], v[52:55]
	v_mfma_f32_16x16x32_bf16 v[44:47], v[174:177], v[182:185], v[44:47]
	v_mfma_f32_16x16x32_bf16 v[36:39], v[166:169], v[190:193], v[36:39]
	v_mfma_f32_16x16x32_bf16 v[28:31], v[174:177], v[190:193], v[28:31]
	v_mfma_f32_16x16x32_bf16 v[20:23], v[166:169], v[198:201], v[20:23]
	v_mfma_f32_16x16x32_bf16 v[12:15], v[174:177], v[198:201], v[12:15]
	v_mfma_f32_16x16x32_bf16 v[4:7], v[166:169], v[206:209], v[4:7]
	v_mfma_f32_16x16x32_bf16 v[0:3], v[174:177], v[206:209], v[0:3]
	v_mfma_f32_16x16x32_bf16 v[52:55], v[170:173], v[186:189], v[52:55]
	v_mfma_f32_16x16x32_bf16 v[44:47], v[178:181], v[186:189], v[44:47]
	v_mfma_f32_16x16x32_bf16 v[36:39], v[170:173], v[194:197], v[36:39]
	v_mfma_f32_16x16x32_bf16 v[28:31], v[178:181], v[194:197], v[28:31]
	v_mfma_f32_16x16x32_bf16 v[20:23], v[170:173], v[202:205], v[20:23]
	v_mfma_f32_16x16x32_bf16 v[12:15], v[178:181], v[202:205], v[12:15]
	v_mfma_f32_16x16x32_bf16 v[4:7], v[170:173], v[210:213], v[4:7]
	v_mfma_f32_16x16x32_bf16 v[0:3], v[178:181], v[210:213], v[0:3]
	s_setprio 0
	s_barrier
	s_add_i32 s49, s49, 2
	s_add_u32 s47, s47, 0x100
	s_addc_u32 s48, s48, 0
	s_cmp_gt_u32 s49, 41
	s_mov_b64 s[18:19], s[20:21]
	s_branch .Lpost16
